# speedup vs baseline: 1.0508x; 1.0283x over previous
; DI void topk_phase(const bf16_t* PROJ, const unsigned char* K8, const unsigned char* V8, const unsigned short* SC, bf16_t* ODSA, int c, char* smem, int bid, int nb) {
;     ...
;       unsigned T = 0u;
;       for (int b = 15; b >= 0; --b) {
;         const unsigned cand = T | (1u << b);
;         int cc = 0;
; #pragma unroll
;         for (int i = 0; i < 64; ++i) if ((i >> 2) * 1024 < n) cc += key[i] >= cand ? 1 : 0;
;         if (block_count(cc, b & 1, red) >= 256) T = cand;
;       }
;       int cg_ = 0, ce_ = 0;
; #pragma unroll
;       for (int i = 0; i < 64; ++i) if ((i >> 2) * 1024 < n) { cg_ += key[i] > T ? 1 : 0; ce_ += key[i] == T ? 1 : 0; }
;       if (tid == 0) cnts[0] = 0;
;       const int cgt = block_count(cg_, 2, red);
;       const int ceq = block_count(ce_, 3, red);
;       const int need = 256 - cgt;
;       int X = 0x7fffffff;
;       if (ceq != need) {
;         X = 0;
;         for (int b = 13; b >= 0; --b) {
;           const int cand = X | (1 << b);
;           int cc = 0;
; #pragma unroll
;           for (int i = 0; i < 64; ++i) if ((i >> 2) * 1024 < n) cc += (key[i] == T && ((i >> 2) * 256 + tid) * 4 + (i & 3) < cand) ? 1 : 0;
;           if (block_count(cc, b & 1, red) < need) X = cand;
;         }
;       }
; #pragma unroll
;       for (int i = 0; i < 64; ++i)
;         if ((i >> 2) * 1024 < n) {
;           const int idx = ((i >> 2) * 256 + tid) * 4 + (i & 3);
;           if (key[i] > T || (key[i] == T && idx <= X)) { const int ps = atomicAdd(&cnts[0], 1); sel[ps] = idx; }
;         }
.LBB0_611:
	s_or_b64 exec, exec, s[20:21]
	v_max3_u32 v8, v166, v165, v164
	v_max3_u32 v8, v8, v163, v162
	v_max3_u32 v8, v8, v161, v160
	v_max3_u32 v8, v8, v158, v159
	v_max3_u32 v8, v8, v157, v156
	v_max3_u32 v8, v8, v155, v154
	v_max3_u32 v8, v8, v153, v152
	v_max3_u32 v8, v8, v150, v151
	v_max3_u32 v8, v8, v149, v148
	v_max3_u32 v8, v8, v147, v146
	v_max3_u32 v8, v8, v145, v144
	v_max3_u32 v8, v8, v142, v143
	v_max3_u32 v8, v8, v141, v140
	v_max3_u32 v8, v8, v139, v138
	v_max3_u32 v8, v8, v137, v136
	v_max3_u32 v8, v8, v81, v135
	v_max3_u32 v8, v8, v80, v79
	v_max3_u32 v8, v8, v78, v77
	v_max3_u32 v8, v8, v76, v75
	v_max3_u32 v8, v8, v73, v74
	v_max3_u32 v8, v8, v72, v70
	v_max3_u32 v8, v8, v69, v68
	v_max3_u32 v8, v8, v67, v66
	v_max3_u32 v8, v8, v64, v65
	v_max3_u32 v8, v8, v63, v62
	v_max3_u32 v8, v8, v61, v59
	v_max3_u32 v8, v8, v60, v58
	v_max3_u32 v8, v8, v57, v56
	v_max3_u32 v8, v8, v55, v54
	v_max3_u32 v8, v8, v53, v15
	v_max3_u32 v8, v8, v52, v14
	v_max_u32_e32 v8, v8, v12
	v_not_b32_e32 v8, v8
	s_nop 1
	v_max_u32_dpp v8, v8, v8 row_shr:1 row_mask:0xf bank_mask:0xf bound_ctrl:1
	s_nop 1
	v_max_u32_dpp v8, v8, v8 row_shr:2 row_mask:0xf bank_mask:0xf bound_ctrl:1
	s_nop 1
	v_max_u32_dpp v8, v8, v8 row_shr:4 row_mask:0xf bank_mask:0xf bound_ctrl:1
	s_nop 1
	v_max_u32_dpp v8, v8, v8 row_shr:8 row_mask:0xf bank_mask:0xf bound_ctrl:1
	s_nop 1
	v_readlane_b32 s0, v8, 15
	v_readlane_b32 s1, v8, 31
	v_readlane_b32 s22, v8, 47
	v_readlane_b32 s23, v8, 63
	s_max_u32 s0, s0, s1
	s_max_u32 s22, s22, s23
	s_max_u32 s0, s0, s22
	v_lshrrev_b32_e32 v10, 6, v214
	v_lshlrev_b32_e32 v10, 2, v10
	v_mov_b32_e32 v9, s0
	ds_write_b32 v10, v9 offset:1024
	s_waitcnt lgkmcnt(0)
	s_barrier
	ds_read_b128 v[168:171], v185 offset:1024
	s_waitcnt lgkmcnt(0)
	v_max3_u32 v9, v168, v169, v170
	v_max_u32_e32 v9, v9, v171
	v_not_b32_e32 v9, v9
	s_nop 1
	v_readfirstlane_b32 s0, v9
	s_nop 1
	s_cmp_eq_u32 s0, 0
	s_cbranch_scc1 .Lsel_fb_A
	s_mov_b32 s1, 0
	v_cmp_le_u32_e64 s[22:23], s0, v166
	v_cmp_le_u32_e64 s[24:25], s0, v165
	s_bcnt1_i32_b64 s26, s[22:23]
	s_add_i32 s1, s1, s26
	v_cmp_le_u32_e64 s[22:23], s0, v164
	s_bcnt1_i32_b64 s26, s[24:25]
	s_add_i32 s1, s1, s26
	v_cmp_le_u32_e64 s[24:25], s0, v163
	s_bcnt1_i32_b64 s26, s[22:23]
	s_add_i32 s1, s1, s26
	v_cmp_le_u32_e64 s[22:23], s0, v162
	s_bcnt1_i32_b64 s26, s[24:25]
	s_add_i32 s1, s1, s26
	v_cmp_le_u32_e64 s[24:25], s0, v161
	s_bcnt1_i32_b64 s26, s[22:23]
	s_add_i32 s1, s1, s26
	v_cmp_le_u32_e64 s[22:23], s0, v160
	s_bcnt1_i32_b64 s26, s[24:25]
	s_add_i32 s1, s1, s26
	v_cmp_le_u32_e64 s[24:25], s0, v158
	s_bcnt1_i32_b64 s26, s[22:23]
	s_add_i32 s1, s1, s26
	v_cmp_le_u32_e64 s[22:23], s0, v159
	s_bcnt1_i32_b64 s26, s[24:25]
	s_add_i32 s1, s1, s26
	v_cmp_le_u32_e64 s[24:25], s0, v157
	s_bcnt1_i32_b64 s26, s[22:23]
	s_add_i32 s1, s1, s26
	v_cmp_le_u32_e64 s[22:23], s0, v156
	s_bcnt1_i32_b64 s26, s[24:25]
	s_add_i32 s1, s1, s26
	v_cmp_le_u32_e64 s[24:25], s0, v155
	s_bcnt1_i32_b64 s26, s[22:23]
	s_add_i32 s1, s1, s26
	v_cmp_le_u32_e64 s[22:23], s0, v154
	s_bcnt1_i32_b64 s26, s[24:25]
	s_add_i32 s1, s1, s26
	v_cmp_le_u32_e64 s[24:25], s0, v153
	s_bcnt1_i32_b64 s26, s[22:23]
	s_add_i32 s1, s1, s26
	v_cmp_le_u32_e64 s[22:23], s0, v152
	s_bcnt1_i32_b64 s26, s[24:25]
	s_add_i32 s1, s1, s26
	v_cmp_le_u32_e64 s[24:25], s0, v150
	s_bcnt1_i32_b64 s26, s[22:23]
	s_add_i32 s1, s1, s26
	v_cmp_le_u32_e64 s[22:23], s0, v151
	s_bcnt1_i32_b64 s26, s[24:25]
	s_add_i32 s1, s1, s26
	v_cmp_le_u32_e64 s[24:25], s0, v149
	s_bcnt1_i32_b64 s26, s[22:23]
	s_add_i32 s1, s1, s26
	v_cmp_le_u32_e64 s[22:23], s0, v148
	s_bcnt1_i32_b64 s26, s[24:25]
	s_add_i32 s1, s1, s26
	v_cmp_le_u32_e64 s[24:25], s0, v147
	s_bcnt1_i32_b64 s26, s[22:23]
	s_add_i32 s1, s1, s26
	v_cmp_le_u32_e64 s[22:23], s0, v146
	s_bcnt1_i32_b64 s26, s[24:25]
	s_add_i32 s1, s1, s26
	v_cmp_le_u32_e64 s[24:25], s0, v145
	s_bcnt1_i32_b64 s26, s[22:23]
	s_add_i32 s1, s1, s26
	v_cmp_le_u32_e64 s[22:23], s0, v144
	s_bcnt1_i32_b64 s26, s[24:25]
	s_add_i32 s1, s1, s26
	v_cmp_le_u32_e64 s[24:25], s0, v142
	s_bcnt1_i32_b64 s26, s[22:23]
	s_add_i32 s1, s1, s26
	v_cmp_le_u32_e64 s[22:23], s0, v143
	s_bcnt1_i32_b64 s26, s[24:25]
	s_add_i32 s1, s1, s26
	v_cmp_le_u32_e64 s[24:25], s0, v141
	s_bcnt1_i32_b64 s26, s[22:23]
	s_add_i32 s1, s1, s26
	v_cmp_le_u32_e64 s[22:23], s0, v140
	s_bcnt1_i32_b64 s26, s[24:25]
	s_add_i32 s1, s1, s26
	v_cmp_le_u32_e64 s[24:25], s0, v139
	s_bcnt1_i32_b64 s26, s[22:23]
	s_add_i32 s1, s1, s26
	v_cmp_le_u32_e64 s[22:23], s0, v138
	s_bcnt1_i32_b64 s26, s[24:25]
	s_add_i32 s1, s1, s26
	v_cmp_le_u32_e64 s[24:25], s0, v137
	s_bcnt1_i32_b64 s26, s[22:23]
	s_add_i32 s1, s1, s26
	v_cmp_le_u32_e64 s[22:23], s0, v136
	s_bcnt1_i32_b64 s26, s[24:25]
	s_add_i32 s1, s1, s26
	v_cmp_le_u32_e64 s[24:25], s0, v81
	s_bcnt1_i32_b64 s26, s[22:23]
	s_add_i32 s1, s1, s26
	v_cmp_le_u32_e64 s[22:23], s0, v135
	s_bcnt1_i32_b64 s26, s[24:25]
	s_add_i32 s1, s1, s26
	v_cmp_le_u32_e64 s[24:25], s0, v80
	s_bcnt1_i32_b64 s26, s[22:23]
	s_add_i32 s1, s1, s26
	v_cmp_le_u32_e64 s[22:23], s0, v79
	s_bcnt1_i32_b64 s26, s[24:25]
	s_add_i32 s1, s1, s26
	v_cmp_le_u32_e64 s[24:25], s0, v78
	s_bcnt1_i32_b64 s26, s[22:23]
	s_add_i32 s1, s1, s26
	v_cmp_le_u32_e64 s[22:23], s0, v77
	s_bcnt1_i32_b64 s26, s[24:25]
	s_add_i32 s1, s1, s26
	v_cmp_le_u32_e64 s[24:25], s0, v76
	s_bcnt1_i32_b64 s26, s[22:23]
	s_add_i32 s1, s1, s26
	v_cmp_le_u32_e64 s[22:23], s0, v75
	s_bcnt1_i32_b64 s26, s[24:25]
	s_add_i32 s1, s1, s26
	v_cmp_le_u32_e64 s[24:25], s0, v73
	s_bcnt1_i32_b64 s26, s[22:23]
	s_add_i32 s1, s1, s26
	v_cmp_le_u32_e64 s[22:23], s0, v74
	s_bcnt1_i32_b64 s26, s[24:25]
	s_add_i32 s1, s1, s26
; DI void topk_phase(const bf16_t* PROJ, const unsigned char* K8, const unsigned char* V8, const unsigned short* SC, bf16_t* ODSA, int c, char* smem, int bid, int nb) {
;     ...
;       unsigned T = 0u;
;       for (int b = 15; b >= 0; --b) {
;         const unsigned cand = T | (1u << b);
;         int cc = 0;
; #pragma unroll
;         for (int i = 0; i < 64; ++i) if ((i >> 2) * 1024 < n) cc += key[i] >= cand ? 1 : 0;
;         if (block_count(cc, b & 1, red) >= 256) T = cand;
;       }
;       int cg_ = 0, ce_ = 0;
; #pragma unroll
;       for (int i = 0; i < 64; ++i) if ((i >> 2) * 1024 < n) { cg_ += key[i] > T ? 1 : 0; ce_ += key[i] == T ? 1 : 0; }
;       if (tid == 0) cnts[0] = 0;
;       const int cgt = block_count(cg_, 2, red);
;       const int ceq = block_count(ce_, 3, red);
;       const int need = 256 - cgt;
;       int X = 0x7fffffff;
;       if (ceq != need) {
;         X = 0;
;         for (int b = 13; b >= 0; --b) {
;           const int cand = X | (1 << b);
;           int cc = 0;
; #pragma unroll
;           for (int i = 0; i < 64; ++i) if ((i >> 2) * 1024 < n) cc += (key[i] == T && ((i >> 2) * 256 + tid) * 4 + (i & 3) < cand) ? 1 : 0;
;           if (block_count(cc, b & 1, red) < need) X = cand;
;         }
;       }
; #pragma unroll
;       for (int i = 0; i < 64; ++i)
;         if ((i >> 2) * 1024 < n) {
;           const int idx = ((i >> 2) * 256 + tid) * 4 + (i & 3);
;           if (key[i] > T || (key[i] == T && idx <= X)) { const int ps = atomicAdd(&cnts[0], 1); sel[ps] = idx; }
;         }
	v_cmp_le_u32_e64 s[24:25], s0, v72
	s_bcnt1_i32_b64 s26, s[22:23]
	s_add_i32 s1, s1, s26
	v_cmp_le_u32_e64 s[22:23], s0, v70
	s_bcnt1_i32_b64 s26, s[24:25]
	s_add_i32 s1, s1, s26
	v_cmp_le_u32_e64 s[24:25], s0, v69
	s_bcnt1_i32_b64 s26, s[22:23]
	s_add_i32 s1, s1, s26
	v_cmp_le_u32_e64 s[22:23], s0, v68
	s_bcnt1_i32_b64 s26, s[24:25]
	s_add_i32 s1, s1, s26
	v_cmp_le_u32_e64 s[24:25], s0, v67
	s_bcnt1_i32_b64 s26, s[22:23]
	s_add_i32 s1, s1, s26
	v_cmp_le_u32_e64 s[22:23], s0, v66
	s_bcnt1_i32_b64 s26, s[24:25]
	s_add_i32 s1, s1, s26
	v_cmp_le_u32_e64 s[24:25], s0, v64
	s_bcnt1_i32_b64 s26, s[22:23]
	s_add_i32 s1, s1, s26
	v_cmp_le_u32_e64 s[22:23], s0, v65
	s_bcnt1_i32_b64 s26, s[24:25]
	s_add_i32 s1, s1, s26
	v_cmp_le_u32_e64 s[24:25], s0, v63
	s_bcnt1_i32_b64 s26, s[22:23]
	s_add_i32 s1, s1, s26
	v_cmp_le_u32_e64 s[22:23], s0, v62
	s_bcnt1_i32_b64 s26, s[24:25]
	s_add_i32 s1, s1, s26
	v_cmp_le_u32_e64 s[24:25], s0, v61
	s_bcnt1_i32_b64 s26, s[22:23]
	s_add_i32 s1, s1, s26
	v_cmp_le_u32_e64 s[22:23], s0, v59
	s_bcnt1_i32_b64 s26, s[24:25]
	s_add_i32 s1, s1, s26
	v_cmp_le_u32_e64 s[24:25], s0, v60
	s_bcnt1_i32_b64 s26, s[22:23]
	s_add_i32 s1, s1, s26
	v_cmp_le_u32_e64 s[22:23], s0, v58
	s_bcnt1_i32_b64 s26, s[24:25]
	s_add_i32 s1, s1, s26
	v_cmp_le_u32_e64 s[24:25], s0, v57
	s_bcnt1_i32_b64 s26, s[22:23]
	s_add_i32 s1, s1, s26
	v_cmp_le_u32_e64 s[22:23], s0, v56
	s_bcnt1_i32_b64 s26, s[24:25]
	s_add_i32 s1, s1, s26
	v_cmp_le_u32_e64 s[24:25], s0, v55
	s_bcnt1_i32_b64 s26, s[22:23]
	s_add_i32 s1, s1, s26
	v_cmp_le_u32_e64 s[22:23], s0, v54
	s_bcnt1_i32_b64 s26, s[24:25]
	s_add_i32 s1, s1, s26
	v_cmp_le_u32_e64 s[24:25], s0, v53
	s_bcnt1_i32_b64 s26, s[22:23]
	s_add_i32 s1, s1, s26
	v_cmp_le_u32_e64 s[22:23], s0, v15
	s_bcnt1_i32_b64 s26, s[24:25]
	s_add_i32 s1, s1, s26
	v_cmp_le_u32_e64 s[24:25], s0, v52
	s_bcnt1_i32_b64 s26, s[22:23]
	s_add_i32 s1, s1, s26
	v_cmp_le_u32_e64 s[22:23], s0, v14
	s_bcnt1_i32_b64 s26, s[24:25]
	s_add_i32 s1, s1, s26
	v_cmp_le_u32_e64 s[24:25], s0, v12
	s_bcnt1_i32_b64 s26, s[22:23]
	s_add_i32 s1, s1, s26
	s_bcnt1_i32_b64 s26, s[24:25]
	s_add_i32 s1, s1, s26
	v_mov_b32_e32 v9, s1
	ds_write_b32 v10, v9 offset:1040
	s_waitcnt lgkmcnt(0)
	s_barrier
	ds_read_b128 v[168:171], v185 offset:1040
	s_waitcnt lgkmcnt(0)
	v_readfirstlane_b32 s24, v168
	v_readfirstlane_b32 s25, v169
	v_readfirstlane_b32 s26, v170
	v_readfirstlane_b32 s27, v171
	s_add_i32 s28, s24, s25
	s_add_i32 s28, s28, s26
	s_add_i32 s28, s28, s27
	s_cmp_gt_u32 s28, 0x800
	s_cbranch_scc1 .Lsel_fb_A
	v_readfirstlane_b32 s29, v10
	s_mov_b32 s31, s28
	s_mov_b32 s1, 0
	s_cmp_ge_u32 s29, 4
	s_cselect_b32 s30, s24, 0
	s_add_i32 s1, s1, s30
	s_cmp_ge_u32 s29, 8
	s_cselect_b32 s30, s25, 0
	s_add_i32 s1, s1, s30
	s_cmp_ge_u32 s29, 12
	s_cselect_b32 s30, s26, 0
	s_add_i32 s1, s1, s30
	v_cmp_le_u32_e64 s[22:23], s0, v166
	v_cmp_le_u32_e64 s[24:25], s0, v165
	s_nop 0
	v_mbcnt_lo_u32_b32 v9, s22, 0
	v_mbcnt_hi_u32_b32 v9, s23, v9
	v_add_lshl_u32 v11, v9, s1, 2
	s_bcnt1_i32_b64 s26, s[22:23]
	s_add_i32 s1, s1, s26
	s_mov_b64 exec, s[22:23]
	ds_write2st64_b32 v11, v166, v18 offset0:36 offset1:68
	s_mov_b64 exec, -1
	v_cmp_le_u32_e64 s[22:23], s0, v164
	v_mbcnt_lo_u32_b32 v9, s24, 0
	v_mbcnt_hi_u32_b32 v9, s25, v9
	v_add_lshl_u32 v11, v9, s1, 2
	s_bcnt1_i32_b64 s26, s[24:25]
	s_add_i32 s1, s1, s26
	s_mov_b64 exec, s[24:25]
	ds_write2st64_b32 v11, v165, v118 offset0:36 offset1:68
	s_mov_b64 exec, -1
	v_cmp_le_u32_e64 s[24:25], s0, v163
	v_mbcnt_lo_u32_b32 v9, s22, 0
	v_mbcnt_hi_u32_b32 v9, s23, v9
	v_add_lshl_u32 v11, v9, s1, 2
	s_bcnt1_i32_b64 s26, s[22:23]
	s_add_i32 s1, s1, s26
	s_mov_b64 exec, s[22:23]
	ds_write2st64_b32 v11, v164, v85 offset0:36 offset1:68
	s_mov_b64 exec, -1
	v_cmp_le_u32_e64 s[22:23], s0, v162
	v_mbcnt_lo_u32_b32 v9, s24, 0
	v_mbcnt_hi_u32_b32 v9, s25, v9
	v_add_lshl_u32 v11, v9, s1, 2
	s_bcnt1_i32_b64 s26, s[24:25]
	s_add_i32 s1, s1, s26
	s_mov_b64 exec, s[24:25]
	ds_write2st64_b32 v11, v163, v86 offset0:36 offset1:68
	s_mov_b64 exec, -1
	v_cmp_le_u32_e64 s[24:25], s0, v161
	v_mbcnt_lo_u32_b32 v9, s22, 0
	v_mbcnt_hi_u32_b32 v9, s23, v9
	v_add_lshl_u32 v11, v9, s1, 2
	s_bcnt1_i32_b64 s26, s[22:23]
	s_add_i32 s1, s1, s26
	s_mov_b64 exec, s[22:23]
	ds_write2st64_b32 v11, v162, v87 offset0:36 offset1:68
	s_mov_b64 exec, -1
	v_cmp_le_u32_e64 s[22:23], s0, v160
	v_mbcnt_lo_u32_b32 v9, s24, 0
	v_mbcnt_hi_u32_b32 v9, s25, v9
	v_add_lshl_u32 v11, v9, s1, 2
	s_bcnt1_i32_b64 s26, s[24:25]
	s_add_i32 s1, s1, s26
	s_mov_b64 exec, s[24:25]
	ds_write2st64_b32 v11, v161, v119 offset0:36 offset1:68
	s_mov_b64 exec, -1
	v_cmp_le_u32_e64 s[24:25], s0, v158
	v_mbcnt_lo_u32_b32 v9, s22, 0
	v_mbcnt_hi_u32_b32 v9, s23, v9
	v_add_lshl_u32 v11, v9, s1, 2
	s_bcnt1_i32_b64 s26, s[22:23]
	s_add_i32 s1, s1, s26
	s_mov_b64 exec, s[22:23]
	ds_write2st64_b32 v11, v160, v88 offset0:36 offset1:68
	s_mov_b64 exec, -1
	v_cmp_le_u32_e64 s[22:23], s0, v159
	v_mbcnt_lo_u32_b32 v9, s24, 0
	v_mbcnt_hi_u32_b32 v9, s25, v9
	v_add_lshl_u32 v11, v9, s1, 2
	s_bcnt1_i32_b64 s26, s[24:25]
	s_add_i32 s1, s1, s26
	s_mov_b64 exec, s[24:25]
	ds_write2st64_b32 v11, v158, v89 offset0:36 offset1:68
	s_mov_b64 exec, -1
	v_cmp_le_u32_e64 s[24:25], s0, v157
	v_mbcnt_lo_u32_b32 v9, s22, 0
	v_mbcnt_hi_u32_b32 v9, s23, v9
	v_add_lshl_u32 v11, v9, s1, 2
	s_bcnt1_i32_b64 s26, s[22:23]
	s_add_i32 s1, s1, s26
	s_mov_b64 exec, s[22:23]
	ds_write2st64_b32 v11, v159, v22 offset0:36 offset1:68
	s_mov_b64 exec, -1
	v_cmp_le_u32_e64 s[22:23], s0, v156
	v_mbcnt_lo_u32_b32 v9, s24, 0
	v_mbcnt_hi_u32_b32 v9, s25, v9
	v_add_lshl_u32 v11, v9, s1, 2
	s_bcnt1_i32_b64 s26, s[24:25]
	s_add_i32 s1, s1, s26
	s_mov_b64 exec, s[24:25]
; DI void topk_phase(const bf16_t* PROJ, const unsigned char* K8, const unsigned char* V8, const unsigned short* SC, bf16_t* ODSA, int c, char* smem, int bid, int nb) {
;     ...
;       for (int i = 0; i < 64; ++i)
;         if ((i >> 2) * 1024 < n) {
;           const int idx = ((i >> 2) * 256 + tid) * 4 + (i & 3);
;           if (key[i] > T || (key[i] == T && idx <= X)) { const int ps = atomicAdd(&cnts[0], 1); sel[ps] = idx; }
;         }
	ds_write2st64_b32 v11, v157, v120 offset0:36 offset1:68
	s_mov_b64 exec, -1
	v_cmp_le_u32_e64 s[24:25], s0, v155
	v_mbcnt_lo_u32_b32 v9, s22, 0
	v_mbcnt_hi_u32_b32 v9, s23, v9
	v_add_lshl_u32 v11, v9, s1, 2
	s_bcnt1_i32_b64 s26, s[22:23]
	s_add_i32 s1, s1, s26
	s_mov_b64 exec, s[22:23]
	ds_write2st64_b32 v11, v156, v90 offset0:36 offset1:68
	s_mov_b64 exec, -1
	v_cmp_le_u32_e64 s[22:23], s0, v154
	v_mbcnt_lo_u32_b32 v9, s24, 0
	v_mbcnt_hi_u32_b32 v9, s25, v9
	v_add_lshl_u32 v11, v9, s1, 2
	s_bcnt1_i32_b64 s26, s[24:25]
	s_add_i32 s1, s1, s26
	s_mov_b64 exec, s[24:25]
	ds_write2st64_b32 v11, v155, v91 offset0:36 offset1:68
	s_mov_b64 exec, -1
	v_cmp_le_u32_e64 s[24:25], s0, v153
	v_mbcnt_lo_u32_b32 v9, s22, 0
	v_mbcnt_hi_u32_b32 v9, s23, v9
	v_add_lshl_u32 v11, v9, s1, 2
	s_bcnt1_i32_b64 s26, s[22:23]
	s_add_i32 s1, s1, s26
	s_mov_b64 exec, s[22:23]
	ds_write2st64_b32 v11, v154, v24 offset0:36 offset1:68
	s_mov_b64 exec, -1
	v_cmp_le_u32_e64 s[22:23], s0, v152
	v_mbcnt_lo_u32_b32 v9, s24, 0
	v_mbcnt_hi_u32_b32 v9, s25, v9
	v_add_lshl_u32 v11, v9, s1, 2
	s_bcnt1_i32_b64 s26, s[24:25]
	s_add_i32 s1, s1, s26
	s_mov_b64 exec, s[24:25]
	ds_write2st64_b32 v11, v153, v121 offset0:36 offset1:68
	s_mov_b64 exec, -1
	v_cmp_le_u32_e64 s[24:25], s0, v150
	v_mbcnt_lo_u32_b32 v9, s22, 0
	v_mbcnt_hi_u32_b32 v9, s23, v9
	v_add_lshl_u32 v11, v9, s1, 2
	s_bcnt1_i32_b64 s26, s[22:23]
	s_add_i32 s1, s1, s26
	s_mov_b64 exec, s[22:23]
	ds_write2st64_b32 v11, v152, v92 offset0:36 offset1:68
	s_mov_b64 exec, -1
	v_cmp_le_u32_e64 s[22:23], s0, v151
	v_mbcnt_lo_u32_b32 v9, s24, 0
	v_mbcnt_hi_u32_b32 v9, s25, v9
	v_add_lshl_u32 v11, v9, s1, 2
	s_bcnt1_i32_b64 s26, s[24:25]
	s_add_i32 s1, s1, s26
	s_mov_b64 exec, s[24:25]
	ds_write2st64_b32 v11, v150, v93 offset0:36 offset1:68
	s_mov_b64 exec, -1
	v_cmp_le_u32_e64 s[24:25], s0, v149
	v_mbcnt_lo_u32_b32 v9, s22, 0
	v_mbcnt_hi_u32_b32 v9, s23, v9
	v_add_lshl_u32 v11, v9, s1, 2
	s_bcnt1_i32_b64 s26, s[22:23]
	s_add_i32 s1, s1, s26
	s_mov_b64 exec, s[22:23]
	ds_write2st64_b32 v11, v151, v26 offset0:36 offset1:68
	s_mov_b64 exec, -1
	v_cmp_le_u32_e64 s[22:23], s0, v148
	v_mbcnt_lo_u32_b32 v9, s24, 0
	v_mbcnt_hi_u32_b32 v9, s25, v9
	v_add_lshl_u32 v11, v9, s1, 2
	s_bcnt1_i32_b64 s26, s[24:25]
	s_add_i32 s1, s1, s26
	s_mov_b64 exec, s[24:25]
	ds_write2st64_b32 v11, v149, v122 offset0:36 offset1:68
	s_mov_b64 exec, -1
	v_cmp_le_u32_e64 s[24:25], s0, v147
	v_mbcnt_lo_u32_b32 v9, s22, 0
	v_mbcnt_hi_u32_b32 v9, s23, v9
	v_add_lshl_u32 v11, v9, s1, 2
	s_bcnt1_i32_b64 s26, s[22:23]
	s_add_i32 s1, s1, s26
	s_mov_b64 exec, s[22:23]
	ds_write2st64_b32 v11, v148, v94 offset0:36 offset1:68
	s_mov_b64 exec, -1
	v_cmp_le_u32_e64 s[22:23], s0, v146
	v_mbcnt_lo_u32_b32 v9, s24, 0
	v_mbcnt_hi_u32_b32 v9, s25, v9
	v_add_lshl_u32 v11, v9, s1, 2
	s_bcnt1_i32_b64 s26, s[24:25]
	s_add_i32 s1, s1, s26
	s_mov_b64 exec, s[24:25]
	ds_write2st64_b32 v11, v147, v95 offset0:36 offset1:68
	s_mov_b64 exec, -1
	v_cmp_le_u32_e64 s[24:25], s0, v145
	v_mbcnt_lo_u32_b32 v9, s22, 0
	v_mbcnt_hi_u32_b32 v9, s23, v9
	v_add_lshl_u32 v11, v9, s1, 2
	s_bcnt1_i32_b64 s26, s[22:23]
	s_add_i32 s1, s1, s26
	s_mov_b64 exec, s[22:23]
	ds_write2st64_b32 v11, v146, v28 offset0:36 offset1:68
	s_mov_b64 exec, -1
	v_cmp_le_u32_e64 s[22:23], s0, v144
	v_mbcnt_lo_u32_b32 v9, s24, 0
	v_mbcnt_hi_u32_b32 v9, s25, v9
	v_add_lshl_u32 v11, v9, s1, 2
	s_bcnt1_i32_b64 s26, s[24:25]
	s_add_i32 s1, s1, s26
	s_mov_b64 exec, s[24:25]
	ds_write2st64_b32 v11, v145, v123 offset0:36 offset1:68
	s_mov_b64 exec, -1
	v_cmp_le_u32_e64 s[24:25], s0, v142
	v_mbcnt_lo_u32_b32 v9, s22, 0
	v_mbcnt_hi_u32_b32 v9, s23, v9
	v_add_lshl_u32 v11, v9, s1, 2
	s_bcnt1_i32_b64 s26, s[22:23]
	s_add_i32 s1, s1, s26
	s_mov_b64 exec, s[22:23]
	ds_write2st64_b32 v11, v144, v96 offset0:36 offset1:68
	s_mov_b64 exec, -1
	v_cmp_le_u32_e64 s[22:23], s0, v143
	v_mbcnt_lo_u32_b32 v9, s24, 0
	v_mbcnt_hi_u32_b32 v9, s25, v9
	v_add_lshl_u32 v11, v9, s1, 2
	s_bcnt1_i32_b64 s26, s[24:25]
	s_add_i32 s1, s1, s26
	s_mov_b64 exec, s[24:25]
	ds_write2st64_b32 v11, v142, v97 offset0:36 offset1:68
	s_mov_b64 exec, -1
	v_cmp_le_u32_e64 s[24:25], s0, v141
	v_mbcnt_lo_u32_b32 v9, s22, 0
	v_mbcnt_hi_u32_b32 v9, s23, v9
	v_add_lshl_u32 v11, v9, s1, 2
	s_bcnt1_i32_b64 s26, s[22:23]
	s_add_i32 s1, s1, s26
	s_mov_b64 exec, s[22:23]
	ds_write2st64_b32 v11, v143, v30 offset0:36 offset1:68
	s_mov_b64 exec, -1
	v_cmp_le_u32_e64 s[22:23], s0, v140
	v_mbcnt_lo_u32_b32 v9, s24, 0
	v_mbcnt_hi_u32_b32 v9, s25, v9
	v_add_lshl_u32 v11, v9, s1, 2
	s_bcnt1_i32_b64 s26, s[24:25]
	s_add_i32 s1, s1, s26
	s_mov_b64 exec, s[24:25]
	ds_write2st64_b32 v11, v141, v124 offset0:36 offset1:68
	s_mov_b64 exec, -1
	v_cmp_le_u32_e64 s[24:25], s0, v139
	v_mbcnt_lo_u32_b32 v9, s22, 0
	v_mbcnt_hi_u32_b32 v9, s23, v9
	v_add_lshl_u32 v11, v9, s1, 2
	s_bcnt1_i32_b64 s26, s[22:23]
	s_add_i32 s1, s1, s26
	s_mov_b64 exec, s[22:23]
	ds_write2st64_b32 v11, v140, v98 offset0:36 offset1:68
	s_mov_b64 exec, -1
	v_cmp_le_u32_e64 s[22:23], s0, v138
	v_mbcnt_lo_u32_b32 v9, s24, 0
	v_mbcnt_hi_u32_b32 v9, s25, v9
	v_add_lshl_u32 v11, v9, s1, 2
	s_bcnt1_i32_b64 s26, s[24:25]
	s_add_i32 s1, s1, s26
	s_mov_b64 exec, s[24:25]
	ds_write2st64_b32 v11, v139, v99 offset0:36 offset1:68
	s_mov_b64 exec, -1
	v_cmp_le_u32_e64 s[24:25], s0, v137
	v_mbcnt_lo_u32_b32 v9, s22, 0
	v_mbcnt_hi_u32_b32 v9, s23, v9
	v_add_lshl_u32 v11, v9, s1, 2
	s_bcnt1_i32_b64 s26, s[22:23]
	s_add_i32 s1, s1, s26
	s_mov_b64 exec, s[22:23]
	ds_write2st64_b32 v11, v138, v32 offset0:36 offset1:68
	s_mov_b64 exec, -1
	v_cmp_le_u32_e64 s[22:23], s0, v136
	v_mbcnt_lo_u32_b32 v9, s24, 0
	v_mbcnt_hi_u32_b32 v9, s25, v9
; DI void topk_phase(const bf16_t* PROJ, const unsigned char* K8, const unsigned char* V8, const unsigned short* SC, bf16_t* ODSA, int c, char* smem, int bid, int nb) {
;     ...
;       for (int i = 0; i < 64; ++i)
;         if ((i >> 2) * 1024 < n) {
;           const int idx = ((i >> 2) * 256 + tid) * 4 + (i & 3);
;           if (key[i] > T || (key[i] == T && idx <= X)) { const int ps = atomicAdd(&cnts[0], 1); sel[ps] = idx; }
;         }
	v_add_lshl_u32 v11, v9, s1, 2
	s_bcnt1_i32_b64 s26, s[24:25]
	s_add_i32 s1, s1, s26
	s_mov_b64 exec, s[24:25]
	ds_write2st64_b32 v11, v137, v125 offset0:36 offset1:68
	s_mov_b64 exec, -1
	v_cmp_le_u32_e64 s[24:25], s0, v81
	v_mbcnt_lo_u32_b32 v9, s22, 0
	v_mbcnt_hi_u32_b32 v9, s23, v9
	v_add_lshl_u32 v11, v9, s1, 2
	s_bcnt1_i32_b64 s26, s[22:23]
	s_add_i32 s1, s1, s26
	s_mov_b64 exec, s[22:23]
	ds_write2st64_b32 v11, v136, v100 offset0:36 offset1:68
	s_mov_b64 exec, -1
	v_cmp_le_u32_e64 s[22:23], s0, v135
	v_mbcnt_lo_u32_b32 v9, s24, 0
	v_mbcnt_hi_u32_b32 v9, s25, v9
	v_add_lshl_u32 v11, v9, s1, 2
	s_bcnt1_i32_b64 s26, s[24:25]
	s_add_i32 s1, s1, s26
	s_mov_b64 exec, s[24:25]
	ds_write2st64_b32 v11, v81, v101 offset0:36 offset1:68
	s_mov_b64 exec, -1
	v_cmp_le_u32_e64 s[24:25], s0, v80
	v_mbcnt_lo_u32_b32 v9, s22, 0
	v_mbcnt_hi_u32_b32 v9, s23, v9
	v_add_lshl_u32 v11, v9, s1, 2
	s_bcnt1_i32_b64 s26, s[22:23]
	s_add_i32 s1, s1, s26
	s_mov_b64 exec, s[22:23]
	ds_write2st64_b32 v11, v135, v34 offset0:36 offset1:68
	s_mov_b64 exec, -1
	v_cmp_le_u32_e64 s[22:23], s0, v79
	v_mbcnt_lo_u32_b32 v9, s24, 0
	v_mbcnt_hi_u32_b32 v9, s25, v9
	v_add_lshl_u32 v11, v9, s1, 2
	s_bcnt1_i32_b64 s26, s[24:25]
	s_add_i32 s1, s1, s26
	s_mov_b64 exec, s[24:25]
	ds_write2st64_b32 v11, v80, v126 offset0:36 offset1:68
	s_mov_b64 exec, -1
	v_cmp_le_u32_e64 s[24:25], s0, v78
	v_mbcnt_lo_u32_b32 v9, s22, 0
	v_mbcnt_hi_u32_b32 v9, s23, v9
	v_add_lshl_u32 v11, v9, s1, 2
	s_bcnt1_i32_b64 s26, s[22:23]
	s_add_i32 s1, s1, s26
	s_mov_b64 exec, s[22:23]
	ds_write2st64_b32 v11, v79, v102 offset0:36 offset1:68
	s_mov_b64 exec, -1
	v_cmp_le_u32_e64 s[22:23], s0, v77
	v_mbcnt_lo_u32_b32 v9, s24, 0
	v_mbcnt_hi_u32_b32 v9, s25, v9
	v_add_lshl_u32 v11, v9, s1, 2
	s_bcnt1_i32_b64 s26, s[24:25]
	s_add_i32 s1, s1, s26
	s_mov_b64 exec, s[24:25]
	ds_write2st64_b32 v11, v78, v103 offset0:36 offset1:68
	s_mov_b64 exec, -1
	v_cmp_le_u32_e64 s[24:25], s0, v76
	v_mbcnt_lo_u32_b32 v9, s22, 0
	v_mbcnt_hi_u32_b32 v9, s23, v9
	v_add_lshl_u32 v11, v9, s1, 2
	s_bcnt1_i32_b64 s26, s[22:23]
	s_add_i32 s1, s1, s26
	s_mov_b64 exec, s[22:23]
	ds_write2st64_b32 v11, v77, v36 offset0:36 offset1:68
	s_mov_b64 exec, -1
	v_cmp_le_u32_e64 s[22:23], s0, v75
	v_mbcnt_lo_u32_b32 v9, s24, 0
	v_mbcnt_hi_u32_b32 v9, s25, v9
	v_add_lshl_u32 v11, v9, s1, 2
	s_bcnt1_i32_b64 s26, s[24:25]
	s_add_i32 s1, s1, s26
	s_mov_b64 exec, s[24:25]
	ds_write2st64_b32 v11, v76, v127 offset0:36 offset1:68
	s_mov_b64 exec, -1
	v_cmp_le_u32_e64 s[24:25], s0, v73
	v_mbcnt_lo_u32_b32 v9, s22, 0
	v_mbcnt_hi_u32_b32 v9, s23, v9
	v_add_lshl_u32 v11, v9, s1, 2
	s_bcnt1_i32_b64 s26, s[22:23]
	s_add_i32 s1, s1, s26
	s_mov_b64 exec, s[22:23]
	ds_write2st64_b32 v11, v75, v104 offset0:36 offset1:68
	s_mov_b64 exec, -1
	v_cmp_le_u32_e64 s[22:23], s0, v74
	v_mbcnt_lo_u32_b32 v9, s24, 0
	v_mbcnt_hi_u32_b32 v9, s25, v9
	v_add_lshl_u32 v11, v9, s1, 2
	s_bcnt1_i32_b64 s26, s[24:25]
	s_add_i32 s1, s1, s26
	s_mov_b64 exec, s[24:25]
	ds_write2st64_b32 v11, v73, v105 offset0:36 offset1:68
	s_mov_b64 exec, -1
	v_cmp_le_u32_e64 s[24:25], s0, v72
	v_mbcnt_lo_u32_b32 v9, s22, 0
	v_mbcnt_hi_u32_b32 v9, s23, v9
	v_add_lshl_u32 v11, v9, s1, 2
	s_bcnt1_i32_b64 s26, s[22:23]
	s_add_i32 s1, s1, s26
	s_mov_b64 exec, s[22:23]
	ds_write2st64_b32 v11, v74, v38 offset0:36 offset1:68
	s_mov_b64 exec, -1
	v_cmp_le_u32_e64 s[22:23], s0, v70
	v_mbcnt_lo_u32_b32 v9, s24, 0
	v_mbcnt_hi_u32_b32 v9, s25, v9
	v_add_lshl_u32 v11, v9, s1, 2
	s_bcnt1_i32_b64 s26, s[24:25]
	s_add_i32 s1, s1, s26
	s_mov_b64 exec, s[24:25]
	ds_write2st64_b32 v11, v72, v128 offset0:36 offset1:68
	s_mov_b64 exec, -1
	v_cmp_le_u32_e64 s[24:25], s0, v69
	v_mbcnt_lo_u32_b32 v9, s22, 0
	v_mbcnt_hi_u32_b32 v9, s23, v9
	v_add_lshl_u32 v11, v9, s1, 2
	s_bcnt1_i32_b64 s26, s[22:23]
	s_add_i32 s1, s1, s26
	s_mov_b64 exec, s[22:23]
	ds_write2st64_b32 v11, v70, v106 offset0:36 offset1:68
	s_mov_b64 exec, -1
	v_cmp_le_u32_e64 s[22:23], s0, v68
	v_mbcnt_lo_u32_b32 v9, s24, 0
	v_mbcnt_hi_u32_b32 v9, s25, v9
	v_add_lshl_u32 v11, v9, s1, 2
	s_bcnt1_i32_b64 s26, s[24:25]
	s_add_i32 s1, s1, s26
	s_mov_b64 exec, s[24:25]
	ds_write2st64_b32 v11, v69, v107 offset0:36 offset1:68
	s_mov_b64 exec, -1
	v_cmp_le_u32_e64 s[24:25], s0, v67
	v_mbcnt_lo_u32_b32 v9, s22, 0
	v_mbcnt_hi_u32_b32 v9, s23, v9
	v_add_lshl_u32 v11, v9, s1, 2
	s_bcnt1_i32_b64 s26, s[22:23]
	s_add_i32 s1, s1, s26
	s_mov_b64 exec, s[22:23]
	ds_write2st64_b32 v11, v68, v40 offset0:36 offset1:68
	s_mov_b64 exec, -1
	v_cmp_le_u32_e64 s[22:23], s0, v66
	v_mbcnt_lo_u32_b32 v9, s24, 0
	v_mbcnt_hi_u32_b32 v9, s25, v9
	v_add_lshl_u32 v11, v9, s1, 2
	s_bcnt1_i32_b64 s26, s[24:25]
	s_add_i32 s1, s1, s26
	s_mov_b64 exec, s[24:25]
	ds_write2st64_b32 v11, v67, v129 offset0:36 offset1:68
	s_mov_b64 exec, -1
	v_cmp_le_u32_e64 s[24:25], s0, v64
	v_mbcnt_lo_u32_b32 v9, s22, 0
	v_mbcnt_hi_u32_b32 v9, s23, v9
	v_add_lshl_u32 v11, v9, s1, 2
	s_bcnt1_i32_b64 s26, s[22:23]
	s_add_i32 s1, s1, s26
	s_mov_b64 exec, s[22:23]
	ds_write2st64_b32 v11, v66, v108 offset0:36 offset1:68
	s_mov_b64 exec, -1
	v_cmp_le_u32_e64 s[22:23], s0, v65
	v_mbcnt_lo_u32_b32 v9, s24, 0
	v_mbcnt_hi_u32_b32 v9, s25, v9
	v_add_lshl_u32 v11, v9, s1, 2
	s_bcnt1_i32_b64 s26, s[24:25]
	s_add_i32 s1, s1, s26
	s_mov_b64 exec, s[24:25]
	ds_write2st64_b32 v11, v64, v109 offset0:36 offset1:68
	s_mov_b64 exec, -1
	v_cmp_le_u32_e64 s[24:25], s0, v63
	v_mbcnt_lo_u32_b32 v9, s22, 0
	v_mbcnt_hi_u32_b32 v9, s23, v9
	v_add_lshl_u32 v11, v9, s1, 2
	s_bcnt1_i32_b64 s26, s[22:23]
	s_add_i32 s1, s1, s26
	s_mov_b64 exec, s[22:23]
	ds_write2st64_b32 v11, v65, v42 offset0:36 offset1:68
	s_mov_b64 exec, -1
	v_cmp_le_u32_e64 s[22:23], s0, v62
; DI void topk_phase(const bf16_t* PROJ, const unsigned char* K8, const unsigned char* V8, const unsigned short* SC, bf16_t* ODSA, int c, char* smem, int bid, int nb) {
;     ...
;       for (int i = 0; i < 64; ++i)
;         if ((i >> 2) * 1024 < n) {
;           const int idx = ((i >> 2) * 256 + tid) * 4 + (i & 3);
;           if (key[i] > T || (key[i] == T && idx <= X)) { const int ps = atomicAdd(&cnts[0], 1); sel[ps] = idx; }
;         }
	v_mbcnt_lo_u32_b32 v9, s24, 0
	v_mbcnt_hi_u32_b32 v9, s25, v9
	v_add_lshl_u32 v11, v9, s1, 2
	s_bcnt1_i32_b64 s26, s[24:25]
	s_add_i32 s1, s1, s26
	s_mov_b64 exec, s[24:25]
	ds_write2st64_b32 v11, v63, v130 offset0:36 offset1:68
	s_mov_b64 exec, -1
	v_cmp_le_u32_e64 s[24:25], s0, v61
	v_mbcnt_lo_u32_b32 v9, s22, 0
	v_mbcnt_hi_u32_b32 v9, s23, v9
	v_add_lshl_u32 v11, v9, s1, 2
	s_bcnt1_i32_b64 s26, s[22:23]
	s_add_i32 s1, s1, s26
	s_mov_b64 exec, s[22:23]
	ds_write2st64_b32 v11, v62, v110 offset0:36 offset1:68
	s_mov_b64 exec, -1
	v_cmp_le_u32_e64 s[22:23], s0, v59
	v_mbcnt_lo_u32_b32 v9, s24, 0
	v_mbcnt_hi_u32_b32 v9, s25, v9
	v_add_lshl_u32 v11, v9, s1, 2
	s_bcnt1_i32_b64 s26, s[24:25]
	s_add_i32 s1, s1, s26
	s_mov_b64 exec, s[24:25]
	ds_write2st64_b32 v11, v61, v111 offset0:36 offset1:68
	s_mov_b64 exec, -1
	v_cmp_le_u32_e64 s[24:25], s0, v60
	v_mbcnt_lo_u32_b32 v9, s22, 0
	v_mbcnt_hi_u32_b32 v9, s23, v9
	v_add_lshl_u32 v11, v9, s1, 2
	s_bcnt1_i32_b64 s26, s[22:23]
	s_add_i32 s1, s1, s26
	s_mov_b64 exec, s[22:23]
	ds_write2st64_b32 v11, v59, v44 offset0:36 offset1:68
	s_mov_b64 exec, -1
	v_cmp_le_u32_e64 s[22:23], s0, v58
	v_mbcnt_lo_u32_b32 v9, s24, 0
	v_mbcnt_hi_u32_b32 v9, s25, v9
	v_add_lshl_u32 v11, v9, s1, 2
	s_bcnt1_i32_b64 s26, s[24:25]
	s_add_i32 s1, s1, s26
	s_mov_b64 exec, s[24:25]
	ds_write2st64_b32 v11, v60, v131 offset0:36 offset1:68
	s_mov_b64 exec, -1
	v_cmp_le_u32_e64 s[24:25], s0, v57
	v_mbcnt_lo_u32_b32 v9, s22, 0
	v_mbcnt_hi_u32_b32 v9, s23, v9
	v_add_lshl_u32 v11, v9, s1, 2
	s_bcnt1_i32_b64 s26, s[22:23]
	s_add_i32 s1, s1, s26
	s_mov_b64 exec, s[22:23]
	ds_write2st64_b32 v11, v58, v112 offset0:36 offset1:68
	s_mov_b64 exec, -1
	v_cmp_le_u32_e64 s[22:23], s0, v56
	v_mbcnt_lo_u32_b32 v9, s24, 0
	v_mbcnt_hi_u32_b32 v9, s25, v9
	v_add_lshl_u32 v11, v9, s1, 2
	s_bcnt1_i32_b64 s26, s[24:25]
	s_add_i32 s1, s1, s26
	s_mov_b64 exec, s[24:25]
	ds_write2st64_b32 v11, v57, v113 offset0:36 offset1:68
	s_mov_b64 exec, -1
	v_cmp_le_u32_e64 s[24:25], s0, v55
	v_mbcnt_lo_u32_b32 v9, s22, 0
	v_mbcnt_hi_u32_b32 v9, s23, v9
	v_add_lshl_u32 v11, v9, s1, 2
	s_bcnt1_i32_b64 s26, s[22:23]
	s_add_i32 s1, s1, s26
	s_mov_b64 exec, s[22:23]
	ds_write2st64_b32 v11, v56, v46 offset0:36 offset1:68
	s_mov_b64 exec, -1
	v_cmp_le_u32_e64 s[22:23], s0, v54
	v_mbcnt_lo_u32_b32 v9, s24, 0
	v_mbcnt_hi_u32_b32 v9, s25, v9
	v_add_lshl_u32 v11, v9, s1, 2
	s_bcnt1_i32_b64 s26, s[24:25]
	s_add_i32 s1, s1, s26
	s_mov_b64 exec, s[24:25]
	ds_write2st64_b32 v11, v55, v132 offset0:36 offset1:68
	s_mov_b64 exec, -1
	v_cmp_le_u32_e64 s[24:25], s0, v53
	v_mbcnt_lo_u32_b32 v9, s22, 0
	v_mbcnt_hi_u32_b32 v9, s23, v9
	v_add_lshl_u32 v11, v9, s1, 2
	s_bcnt1_i32_b64 s26, s[22:23]
	s_add_i32 s1, s1, s26
	s_mov_b64 exec, s[22:23]
	ds_write2st64_b32 v11, v54, v114 offset0:36 offset1:68
	s_mov_b64 exec, -1
	v_cmp_le_u32_e64 s[22:23], s0, v15
	v_mbcnt_lo_u32_b32 v9, s24, 0
	v_mbcnt_hi_u32_b32 v9, s25, v9
	v_add_lshl_u32 v11, v9, s1, 2
	s_bcnt1_i32_b64 s26, s[24:25]
	s_add_i32 s1, s1, s26
	s_mov_b64 exec, s[24:25]
	ds_write2st64_b32 v11, v53, v115 offset0:36 offset1:68
	s_mov_b64 exec, -1
	v_cmp_le_u32_e64 s[24:25], s0, v52
	v_mbcnt_lo_u32_b32 v9, s22, 0
	v_mbcnt_hi_u32_b32 v9, s23, v9
	v_add_lshl_u32 v11, v9, s1, 2
	s_bcnt1_i32_b64 s26, s[22:23]
	s_add_i32 s1, s1, s26
	s_mov_b64 exec, s[22:23]
	ds_write2st64_b32 v11, v15, v48 offset0:36 offset1:68
	s_mov_b64 exec, -1
	v_cmp_le_u32_e64 s[22:23], s0, v14
	v_mbcnt_lo_u32_b32 v9, s24, 0
	v_mbcnt_hi_u32_b32 v9, s25, v9
	v_add_lshl_u32 v11, v9, s1, 2
	s_bcnt1_i32_b64 s26, s[24:25]
	s_add_i32 s1, s1, s26
	s_mov_b64 exec, s[24:25]
	ds_write2st64_b32 v11, v52, v133 offset0:36 offset1:68
	s_mov_b64 exec, -1
	v_cmp_le_u32_e64 s[24:25], s0, v12
	v_mbcnt_lo_u32_b32 v9, s22, 0
	v_mbcnt_hi_u32_b32 v9, s23, v9
	v_add_lshl_u32 v11, v9, s1, 2
	s_bcnt1_i32_b64 s26, s[22:23]
	s_add_i32 s1, s1, s26
	s_mov_b64 exec, s[22:23]
	ds_write2st64_b32 v11, v14, v116 offset0:36 offset1:68
	s_mov_b64 exec, -1
	v_mbcnt_lo_u32_b32 v9, s24, 0
	v_mbcnt_hi_u32_b32 v9, s25, v9
	v_add_lshl_u32 v11, v9, s1, 2
	s_bcnt1_i32_b64 s26, s[24:25]
	s_add_i32 s1, s1, s26
	s_mov_b64 exec, s[24:25]
	ds_write2st64_b32 v11, v12, v117 offset0:36 offset1:68
	s_mov_b64 exec, -1
	s_waitcnt lgkmcnt(0)
	s_barrier
	s_cmp_lg_u32 s29, 0
	s_cbranch_scc1 .LBB0_1044
; DI void topk_phase(const bf16_t* PROJ, const unsigned char* K8, const unsigned char* V8, const unsigned short* SC, bf16_t* ODSA, int c, char* smem, int bid, int nb) {
;     ...
;       unsigned T = 0u;
;       for (int b = 15; b >= 0; --b) {
;         const unsigned cand = T | (1u << b);
;         int cc = 0;
; #pragma unroll
;         for (int i = 0; i < 64; ++i) if ((i >> 2) * 1024 < n) cc += key[i] >= cand ? 1 : 0;
;         if (block_count(cc, b & 1, red) >= 256) T = cand;
;       }
	v_and_b32_e32 v10, 63, v214
	v_lshlrev_b32_e32 v11, 2, v10
	ds_read_b32 v186, v11 offset:9216
	ds_read_b32 v172, v11 offset:17408
	ds_read_b32 v187, v11 offset:9472
	ds_read_b32 v173, v11 offset:17664
	ds_read_b32 v188, v11 offset:9728
	ds_read_b32 v174, v11 offset:17920
	ds_read_b32 v189, v11 offset:9984
	ds_read_b32 v175, v11 offset:18176
	s_waitcnt lgkmcnt(0)
	ds_read_b32 v190, v11 offset:10240
	ds_read_b32 v176, v11 offset:18432
	ds_read_b32 v191, v11 offset:10496
	ds_read_b32 v177, v11 offset:18688
	ds_read_b32 v192, v11 offset:10752
	ds_read_b32 v178, v11 offset:18944
	ds_read_b32 v193, v11 offset:11008
	ds_read_b32 v179, v11 offset:19200
	s_waitcnt lgkmcnt(0)
	ds_read_b32 v194, v11 offset:11264
	ds_read_b32 v180, v11 offset:19456
	ds_read_b32 v195, v11 offset:11520
	ds_read_b32 v181, v11 offset:19712
	ds_read_b32 v196, v11 offset:11776
	ds_read_b32 v182, v11 offset:19968
	ds_read_b32 v197, v11 offset:12032
	ds_read_b32 v183, v11 offset:20224
	s_waitcnt lgkmcnt(0)
	ds_read_b32 v198, v11 offset:12288
	ds_read_b32 v184, v11 offset:20480
	ds_read_b32 v199, v11 offset:12544
	ds_read_b32 v230, v11 offset:20736
	ds_read_b32 v200, v11 offset:12800
	ds_read_b32 v231, v11 offset:20992
	ds_read_b32 v201, v11 offset:13056
	ds_read_b32 v232, v11 offset:21248
	s_waitcnt lgkmcnt(0)
	ds_read_b32 v202, v11 offset:13312
	ds_read_b32 v233, v11 offset:21504
	ds_read_b32 v203, v11 offset:13568
	ds_read_b32 v235, v11 offset:21760
	ds_read_b32 v204, v11 offset:13824
	ds_read_b32 v236, v11 offset:22016
	ds_read_b32 v205, v11 offset:14080
	ds_read_b32 v237, v11 offset:22272
	s_waitcnt lgkmcnt(0)
	ds_read_b32 v206, v11 offset:14336
	ds_read_b32 v238, v11 offset:22528
	ds_read_b32 v207, v11 offset:14592
	ds_read_b32 v239, v11 offset:22784
	ds_read_b32 v208, v11 offset:14848
	ds_read_b32 v240, v11 offset:23040
	ds_read_b32 v209, v11 offset:15104
	ds_read_b32 v241, v11 offset:23296
	s_waitcnt lgkmcnt(0)
	ds_read_b32 v210, v11 offset:15360
	ds_read_b32 v242, v11 offset:23552
	ds_read_b32 v211, v11 offset:15616
	ds_read_b32 v243, v11 offset:23808
	ds_read_b32 v212, v11 offset:15872
	ds_read_b32 v244, v11 offset:24064
	ds_read_b32 v213, v11 offset:16128
	ds_read_b32 v245, v11 offset:24320
	s_waitcnt lgkmcnt(0)
	ds_read_b32 v226, v11 offset:16384
	ds_read_b32 v215, v11 offset:24576
	ds_read_b32 v227, v11 offset:16640
	ds_read_b32 v216, v11 offset:24832
	ds_read_b32 v228, v11 offset:16896
	ds_read_b32 v221, v11 offset:25088
	ds_read_b32 v229, v11 offset:17152
	ds_read_b32 v224, v11 offset:25344
	s_waitcnt lgkmcnt(0)
	s_sub_i32 s26, s31, 0
	v_cmp_gt_i32_e64 s[22:23], s26, v10
	s_sub_i32 s27, s31, 64
	v_cmp_gt_i32_e64 s[24:25], s27, v10
	s_nop 0
	v_cndmask_b32_e64 v186, 0, v186, s[22:23]
	s_sub_i32 s26, s31, 128
	v_cmp_gt_i32_e64 s[22:23], s26, v10
	v_cndmask_b32_e64 v187, 0, v187, s[24:25]
	s_sub_i32 s27, s31, 192
	v_cmp_gt_i32_e64 s[24:25], s27, v10
	v_cndmask_b32_e64 v188, 0, v188, s[22:23]
	s_sub_i32 s26, s31, 256
	v_cmp_gt_i32_e64 s[22:23], s26, v10
	v_cndmask_b32_e64 v189, 0, v189, s[24:25]
	s_sub_i32 s27, s31, 320
	v_cmp_gt_i32_e64 s[24:25], s27, v10
	v_cndmask_b32_e64 v190, 0, v190, s[22:23]
	s_sub_i32 s26, s31, 384
	v_cmp_gt_i32_e64 s[22:23], s26, v10
	v_cndmask_b32_e64 v191, 0, v191, s[24:25]
	s_sub_i32 s27, s31, 448
	v_cmp_gt_i32_e64 s[24:25], s27, v10
	v_cndmask_b32_e64 v192, 0, v192, s[22:23]
	s_sub_i32 s26, s31, 512
	v_cmp_gt_i32_e64 s[22:23], s26, v10
	v_cndmask_b32_e64 v193, 0, v193, s[24:25]
	s_sub_i32 s27, s31, 576
	v_cmp_gt_i32_e64 s[24:25], s27, v10
	v_cndmask_b32_e64 v194, 0, v194, s[22:23]
	s_sub_i32 s26, s31, 640
	v_cmp_gt_i32_e64 s[22:23], s26, v10
	v_cndmask_b32_e64 v195, 0, v195, s[24:25]
	s_sub_i32 s27, s31, 704
	v_cmp_gt_i32_e64 s[24:25], s27, v10
	v_cndmask_b32_e64 v196, 0, v196, s[22:23]
	s_sub_i32 s26, s31, 768
	v_cmp_gt_i32_e64 s[22:23], s26, v10
	v_cndmask_b32_e64 v197, 0, v197, s[24:25]
	s_sub_i32 s27, s31, 832
	v_cmp_gt_i32_e64 s[24:25], s27, v10
	v_cndmask_b32_e64 v198, 0, v198, s[22:23]
	s_sub_i32 s26, s31, 896
	v_cmp_gt_i32_e64 s[22:23], s26, v10
	v_cndmask_b32_e64 v199, 0, v199, s[24:25]
	s_sub_i32 s27, s31, 960
	v_cmp_gt_i32_e64 s[24:25], s27, v10
	v_cndmask_b32_e64 v200, 0, v200, s[22:23]
	s_sub_i32 s26, s31, 1024
	v_cmp_gt_i32_e64 s[22:23], s26, v10
	v_cndmask_b32_e64 v201, 0, v201, s[24:25]
	s_sub_i32 s27, s31, 1088
	v_cmp_gt_i32_e64 s[24:25], s27, v10
	v_cndmask_b32_e64 v202, 0, v202, s[22:23]
	s_sub_i32 s26, s31, 1152
	v_cmp_gt_i32_e64 s[22:23], s26, v10
	v_cndmask_b32_e64 v203, 0, v203, s[24:25]
	s_sub_i32 s27, s31, 1216
	v_cmp_gt_i32_e64 s[24:25], s27, v10
	v_cndmask_b32_e64 v204, 0, v204, s[22:23]
	s_sub_i32 s26, s31, 1280
	v_cmp_gt_i32_e64 s[22:23], s26, v10
	v_cndmask_b32_e64 v205, 0, v205, s[24:25]
	s_sub_i32 s27, s31, 1344
	v_cmp_gt_i32_e64 s[24:25], s27, v10
	v_cndmask_b32_e64 v206, 0, v206, s[22:23]
	s_sub_i32 s26, s31, 1408
	v_cmp_gt_i32_e64 s[22:23], s26, v10
	v_cndmask_b32_e64 v207, 0, v207, s[24:25]
	s_sub_i32 s27, s31, 1472
	v_cmp_gt_i32_e64 s[24:25], s27, v10
	v_cndmask_b32_e64 v208, 0, v208, s[22:23]
	s_sub_i32 s26, s31, 1536
	v_cmp_gt_i32_e64 s[22:23], s26, v10
	v_cndmask_b32_e64 v209, 0, v209, s[24:25]
	s_sub_i32 s27, s31, 1600
	v_cmp_gt_i32_e64 s[24:25], s27, v10
	v_cndmask_b32_e64 v210, 0, v210, s[22:23]
	s_sub_i32 s26, s31, 1664
	v_cmp_gt_i32_e64 s[22:23], s26, v10
	v_cndmask_b32_e64 v211, 0, v211, s[24:25]
	s_sub_i32 s27, s31, 1728
	v_cmp_gt_i32_e64 s[24:25], s27, v10
	v_cndmask_b32_e64 v212, 0, v212, s[22:23]
	s_sub_i32 s26, s31, 1792
	v_cmp_gt_i32_e64 s[22:23], s26, v10
	v_cndmask_b32_e64 v213, 0, v213, s[24:25]
	s_sub_i32 s27, s31, 1856
	v_cmp_gt_i32_e64 s[24:25], s27, v10
	v_cndmask_b32_e64 v226, 0, v226, s[22:23]
	s_sub_i32 s26, s31, 1920
	v_cmp_gt_i32_e64 s[22:23], s26, v10
	v_cndmask_b32_e64 v227, 0, v227, s[24:25]
	s_sub_i32 s27, s31, 1984
	v_cmp_gt_i32_e64 s[24:25], s27, v10
	v_cndmask_b32_e64 v228, 0, v228, s[22:23]
	v_cndmask_b32_e64 v229, 0, v229, s[24:25]
	s_mov_b32 s1, 0
	s_mov_b32 s2, 15
; DI void topk_phase(const bf16_t* PROJ, const unsigned char* K8, const unsigned char* V8, const unsigned short* SC, bf16_t* ODSA, int c, char* smem, int bid, int nb) {
;     ...
;       unsigned T = 0u;
;       for (int b = 15; b >= 0; --b) {
;         const unsigned cand = T | (1u << b);
;         int cc = 0;
; #pragma unroll
;         for (int i = 0; i < 64; ++i) if ((i >> 2) * 1024 < n) cc += key[i] >= cand ? 1 : 0;
;         if (block_count(cc, b & 1, red) >= 256) T = cand;
;       }
;       int cg_ = 0, ce_ = 0;
; #pragma unroll
;       for (int i = 0; i < 64; ++i) if ((i >> 2) * 1024 < n) { cg_ += key[i] > T ? 1 : 0; ce_ += key[i] == T ? 1 : 0; }
.Lsel_bis_A:
	s_lshl_b32 s0, 1, s2
	s_or_b32 s0, s0, s1
	s_mov_b32 s27, 0
	v_cmp_le_u32_e64 s[22:23], s0, v186
	v_cmp_le_u32_e64 s[24:25], s0, v187
	s_bcnt1_i32_b64 s26, s[22:23]
	s_add_i32 s27, s27, s26
	v_cmp_le_u32_e64 s[22:23], s0, v188
	s_bcnt1_i32_b64 s26, s[24:25]
	s_add_i32 s27, s27, s26
	v_cmp_le_u32_e64 s[24:25], s0, v189
	s_bcnt1_i32_b64 s26, s[22:23]
	s_add_i32 s27, s27, s26
	v_cmp_le_u32_e64 s[22:23], s0, v190
	s_bcnt1_i32_b64 s26, s[24:25]
	s_add_i32 s27, s27, s26
	v_cmp_le_u32_e64 s[24:25], s0, v191
	s_bcnt1_i32_b64 s26, s[22:23]
	s_add_i32 s27, s27, s26
	v_cmp_le_u32_e64 s[22:23], s0, v192
	s_bcnt1_i32_b64 s26, s[24:25]
	s_add_i32 s27, s27, s26
	v_cmp_le_u32_e64 s[24:25], s0, v193
	s_bcnt1_i32_b64 s26, s[22:23]
	s_add_i32 s27, s27, s26
	v_cmp_le_u32_e64 s[22:23], s0, v194
	s_bcnt1_i32_b64 s26, s[24:25]
	s_add_i32 s27, s27, s26
	v_cmp_le_u32_e64 s[24:25], s0, v195
	s_bcnt1_i32_b64 s26, s[22:23]
	s_add_i32 s27, s27, s26
	v_cmp_le_u32_e64 s[22:23], s0, v196
	s_bcnt1_i32_b64 s26, s[24:25]
	s_add_i32 s27, s27, s26
	v_cmp_le_u32_e64 s[24:25], s0, v197
	s_bcnt1_i32_b64 s26, s[22:23]
	s_add_i32 s27, s27, s26
	v_cmp_le_u32_e64 s[22:23], s0, v198
	s_bcnt1_i32_b64 s26, s[24:25]
	s_add_i32 s27, s27, s26
	v_cmp_le_u32_e64 s[24:25], s0, v199
	s_bcnt1_i32_b64 s26, s[22:23]
	s_add_i32 s27, s27, s26
	v_cmp_le_u32_e64 s[22:23], s0, v200
	s_bcnt1_i32_b64 s26, s[24:25]
	s_add_i32 s27, s27, s26
	v_cmp_le_u32_e64 s[24:25], s0, v201
	s_bcnt1_i32_b64 s26, s[22:23]
	s_add_i32 s27, s27, s26
	v_cmp_le_u32_e64 s[22:23], s0, v202
	s_bcnt1_i32_b64 s26, s[24:25]
	s_add_i32 s27, s27, s26
	v_cmp_le_u32_e64 s[24:25], s0, v203
	s_bcnt1_i32_b64 s26, s[22:23]
	s_add_i32 s27, s27, s26
	v_cmp_le_u32_e64 s[22:23], s0, v204
	s_bcnt1_i32_b64 s26, s[24:25]
	s_add_i32 s27, s27, s26
	v_cmp_le_u32_e64 s[24:25], s0, v205
	s_bcnt1_i32_b64 s26, s[22:23]
	s_add_i32 s27, s27, s26
	v_cmp_le_u32_e64 s[22:23], s0, v206
	s_bcnt1_i32_b64 s26, s[24:25]
	s_add_i32 s27, s27, s26
	v_cmp_le_u32_e64 s[24:25], s0, v207
	s_bcnt1_i32_b64 s26, s[22:23]
	s_add_i32 s27, s27, s26
	v_cmp_le_u32_e64 s[22:23], s0, v208
	s_bcnt1_i32_b64 s26, s[24:25]
	s_add_i32 s27, s27, s26
	v_cmp_le_u32_e64 s[24:25], s0, v209
	s_bcnt1_i32_b64 s26, s[22:23]
	s_add_i32 s27, s27, s26
	v_cmp_le_u32_e64 s[22:23], s0, v210
	s_bcnt1_i32_b64 s26, s[24:25]
	s_add_i32 s27, s27, s26
	v_cmp_le_u32_e64 s[24:25], s0, v211
	s_bcnt1_i32_b64 s26, s[22:23]
	s_add_i32 s27, s27, s26
	v_cmp_le_u32_e64 s[22:23], s0, v212
	s_bcnt1_i32_b64 s26, s[24:25]
	s_add_i32 s27, s27, s26
	v_cmp_le_u32_e64 s[24:25], s0, v213
	s_bcnt1_i32_b64 s26, s[22:23]
	s_add_i32 s27, s27, s26
	v_cmp_le_u32_e64 s[22:23], s0, v226
	s_bcnt1_i32_b64 s26, s[24:25]
	s_add_i32 s27, s27, s26
	v_cmp_le_u32_e64 s[24:25], s0, v227
	s_bcnt1_i32_b64 s26, s[22:23]
	s_add_i32 s27, s27, s26
	v_cmp_le_u32_e64 s[22:23], s0, v228
	s_bcnt1_i32_b64 s26, s[24:25]
	s_add_i32 s27, s27, s26
	v_cmp_le_u32_e64 s[24:25], s0, v229
	s_bcnt1_i32_b64 s26, s[22:23]
	s_add_i32 s27, s27, s26
	s_bcnt1_i32_b64 s26, s[24:25]
	s_add_i32 s27, s27, s26
	s_cmp_ge_u32 s27, 0x100
	s_cselect_b32 s1, s0, s1
	s_add_i32 s2, s2, -1
	s_cmp_lg_u32 s2, -1
	s_cbranch_scc1 .Lsel_bis_A
	s_mov_b32 s27, 0
	s_mov_b32 s28, 0
	v_add_u32_e32 v8, 1, v172
	v_cmp_eq_u32_e64 s[22:23], s1, v186
	v_cmp_lt_u32_e64 s[24:25], s1, v186
	s_bcnt1_i32_b64 s26, s[22:23]
	s_add_i32 s28, s28, s26
	s_bcnt1_i32_b64 s26, s[24:25]
	s_add_i32 s27, s27, s26
	v_cndmask_b32_e64 v8, -1, v8, s[22:23]
	v_cndmask_b32_e64 v186, v8, 0, s[24:25]
	v_add_u32_e32 v9, 1, v173
	v_cmp_eq_u32_e64 s[22:23], s1, v187
	v_cmp_lt_u32_e64 s[24:25], s1, v187
	s_bcnt1_i32_b64 s26, s[22:23]
	s_add_i32 s28, s28, s26
	s_bcnt1_i32_b64 s26, s[24:25]
	s_add_i32 s27, s27, s26
	v_cndmask_b32_e64 v9, -1, v9, s[22:23]
	v_cndmask_b32_e64 v187, v9, 0, s[24:25]
	v_add_u32_e32 v13, 1, v174
	v_cmp_eq_u32_e64 s[22:23], s1, v188
	v_cmp_lt_u32_e64 s[24:25], s1, v188
	s_bcnt1_i32_b64 s26, s[22:23]
	s_add_i32 s28, s28, s26
	s_bcnt1_i32_b64 s26, s[24:25]
	s_add_i32 s27, s27, s26
	v_cndmask_b32_e64 v13, -1, v13, s[22:23]
	v_cndmask_b32_e64 v188, v13, 0, s[24:25]
	v_add_u32_e32 v167, 1, v175
	v_cmp_eq_u32_e64 s[22:23], s1, v189
	v_cmp_lt_u32_e64 s[24:25], s1, v189
	s_bcnt1_i32_b64 s26, s[22:23]
	s_add_i32 s28, s28, s26
	s_bcnt1_i32_b64 s26, s[24:25]
	s_add_i32 s27, s27, s26
	v_cndmask_b32_e64 v167, -1, v167, s[22:23]
	v_cndmask_b32_e64 v189, v167, 0, s[24:25]
	v_add_u32_e32 v8, 1, v176
	v_cmp_eq_u32_e64 s[22:23], s1, v190
	v_cmp_lt_u32_e64 s[24:25], s1, v190
	s_bcnt1_i32_b64 s26, s[22:23]
	s_add_i32 s28, s28, s26
	s_bcnt1_i32_b64 s26, s[24:25]
	s_add_i32 s27, s27, s26
	v_cndmask_b32_e64 v8, -1, v8, s[22:23]
	v_cndmask_b32_e64 v190, v8, 0, s[24:25]
	v_add_u32_e32 v9, 1, v177
	v_cmp_eq_u32_e64 s[22:23], s1, v191
	v_cmp_lt_u32_e64 s[24:25], s1, v191
	s_bcnt1_i32_b64 s26, s[22:23]
	s_add_i32 s28, s28, s26
	s_bcnt1_i32_b64 s26, s[24:25]
	s_add_i32 s27, s27, s26
	v_cndmask_b32_e64 v9, -1, v9, s[22:23]
	v_cndmask_b32_e64 v191, v9, 0, s[24:25]
	v_add_u32_e32 v13, 1, v178
	v_cmp_eq_u32_e64 s[22:23], s1, v192
	v_cmp_lt_u32_e64 s[24:25], s1, v192
	s_bcnt1_i32_b64 s26, s[22:23]
	s_add_i32 s28, s28, s26
	s_bcnt1_i32_b64 s26, s[24:25]
	s_add_i32 s27, s27, s26
	v_cndmask_b32_e64 v13, -1, v13, s[22:23]
	v_cndmask_b32_e64 v192, v13, 0, s[24:25]
	v_add_u32_e32 v167, 1, v179
	v_cmp_eq_u32_e64 s[22:23], s1, v193
	v_cmp_lt_u32_e64 s[24:25], s1, v193
	s_bcnt1_i32_b64 s26, s[22:23]
	s_add_i32 s28, s28, s26
	s_bcnt1_i32_b64 s26, s[24:25]
	s_add_i32 s27, s27, s26
	v_cndmask_b32_e64 v167, -1, v167, s[22:23]
	v_cndmask_b32_e64 v193, v167, 0, s[24:25]
	v_add_u32_e32 v8, 1, v180
	v_cmp_eq_u32_e64 s[22:23], s1, v194
; DI void topk_phase(const bf16_t* PROJ, const unsigned char* K8, const unsigned char* V8, const unsigned short* SC, bf16_t* ODSA, int c, char* smem, int bid, int nb) {
;     ...
;       int cg_ = 0, ce_ = 0;
; #pragma unroll
;       for (int i = 0; i < 64; ++i) if ((i >> 2) * 1024 < n) { cg_ += key[i] > T ? 1 : 0; ce_ += key[i] == T ? 1 : 0; }
	v_cmp_lt_u32_e64 s[24:25], s1, v194
	s_bcnt1_i32_b64 s26, s[22:23]
	s_add_i32 s28, s28, s26
	s_bcnt1_i32_b64 s26, s[24:25]
	s_add_i32 s27, s27, s26
	v_cndmask_b32_e64 v8, -1, v8, s[22:23]
	v_cndmask_b32_e64 v194, v8, 0, s[24:25]
	v_add_u32_e32 v9, 1, v181
	v_cmp_eq_u32_e64 s[22:23], s1, v195
	v_cmp_lt_u32_e64 s[24:25], s1, v195
	s_bcnt1_i32_b64 s26, s[22:23]
	s_add_i32 s28, s28, s26
	s_bcnt1_i32_b64 s26, s[24:25]
	s_add_i32 s27, s27, s26
	v_cndmask_b32_e64 v9, -1, v9, s[22:23]
	v_cndmask_b32_e64 v195, v9, 0, s[24:25]
	v_add_u32_e32 v13, 1, v182
	v_cmp_eq_u32_e64 s[22:23], s1, v196
	v_cmp_lt_u32_e64 s[24:25], s1, v196
	s_bcnt1_i32_b64 s26, s[22:23]
	s_add_i32 s28, s28, s26
	s_bcnt1_i32_b64 s26, s[24:25]
	s_add_i32 s27, s27, s26
	v_cndmask_b32_e64 v13, -1, v13, s[22:23]
	v_cndmask_b32_e64 v196, v13, 0, s[24:25]
	v_add_u32_e32 v167, 1, v183
	v_cmp_eq_u32_e64 s[22:23], s1, v197
	v_cmp_lt_u32_e64 s[24:25], s1, v197
	s_bcnt1_i32_b64 s26, s[22:23]
	s_add_i32 s28, s28, s26
	s_bcnt1_i32_b64 s26, s[24:25]
	s_add_i32 s27, s27, s26
	v_cndmask_b32_e64 v167, -1, v167, s[22:23]
	v_cndmask_b32_e64 v197, v167, 0, s[24:25]
	v_add_u32_e32 v8, 1, v184
	v_cmp_eq_u32_e64 s[22:23], s1, v198
	v_cmp_lt_u32_e64 s[24:25], s1, v198
	s_bcnt1_i32_b64 s26, s[22:23]
	s_add_i32 s28, s28, s26
	s_bcnt1_i32_b64 s26, s[24:25]
	s_add_i32 s27, s27, s26
	v_cndmask_b32_e64 v8, -1, v8, s[22:23]
	v_cndmask_b32_e64 v198, v8, 0, s[24:25]
	v_add_u32_e32 v9, 1, v230
	v_cmp_eq_u32_e64 s[22:23], s1, v199
	v_cmp_lt_u32_e64 s[24:25], s1, v199
	s_bcnt1_i32_b64 s26, s[22:23]
	s_add_i32 s28, s28, s26
	s_bcnt1_i32_b64 s26, s[24:25]
	s_add_i32 s27, s27, s26
	v_cndmask_b32_e64 v9, -1, v9, s[22:23]
	v_cndmask_b32_e64 v199, v9, 0, s[24:25]
	v_add_u32_e32 v13, 1, v231
	v_cmp_eq_u32_e64 s[22:23], s1, v200
	v_cmp_lt_u32_e64 s[24:25], s1, v200
	s_bcnt1_i32_b64 s26, s[22:23]
	s_add_i32 s28, s28, s26
	s_bcnt1_i32_b64 s26, s[24:25]
	s_add_i32 s27, s27, s26
	v_cndmask_b32_e64 v13, -1, v13, s[22:23]
	v_cndmask_b32_e64 v200, v13, 0, s[24:25]
	v_add_u32_e32 v167, 1, v232
	v_cmp_eq_u32_e64 s[22:23], s1, v201
	v_cmp_lt_u32_e64 s[24:25], s1, v201
	s_bcnt1_i32_b64 s26, s[22:23]
	s_add_i32 s28, s28, s26
	s_bcnt1_i32_b64 s26, s[24:25]
	s_add_i32 s27, s27, s26
	v_cndmask_b32_e64 v167, -1, v167, s[22:23]
	v_cndmask_b32_e64 v201, v167, 0, s[24:25]
	v_add_u32_e32 v8, 1, v233
	v_cmp_eq_u32_e64 s[22:23], s1, v202
	v_cmp_lt_u32_e64 s[24:25], s1, v202
	s_bcnt1_i32_b64 s26, s[22:23]
	s_add_i32 s28, s28, s26
	s_bcnt1_i32_b64 s26, s[24:25]
	s_add_i32 s27, s27, s26
	v_cndmask_b32_e64 v8, -1, v8, s[22:23]
	v_cndmask_b32_e64 v202, v8, 0, s[24:25]
	v_add_u32_e32 v9, 1, v235
	v_cmp_eq_u32_e64 s[22:23], s1, v203
	v_cmp_lt_u32_e64 s[24:25], s1, v203
	s_bcnt1_i32_b64 s26, s[22:23]
	s_add_i32 s28, s28, s26
	s_bcnt1_i32_b64 s26, s[24:25]
	s_add_i32 s27, s27, s26
	v_cndmask_b32_e64 v9, -1, v9, s[22:23]
	v_cndmask_b32_e64 v203, v9, 0, s[24:25]
	v_add_u32_e32 v13, 1, v236
	v_cmp_eq_u32_e64 s[22:23], s1, v204
	v_cmp_lt_u32_e64 s[24:25], s1, v204
	s_bcnt1_i32_b64 s26, s[22:23]
	s_add_i32 s28, s28, s26
	s_bcnt1_i32_b64 s26, s[24:25]
	s_add_i32 s27, s27, s26
	v_cndmask_b32_e64 v13, -1, v13, s[22:23]
	v_cndmask_b32_e64 v204, v13, 0, s[24:25]
	v_add_u32_e32 v167, 1, v237
	v_cmp_eq_u32_e64 s[22:23], s1, v205
	v_cmp_lt_u32_e64 s[24:25], s1, v205
	s_bcnt1_i32_b64 s26, s[22:23]
	s_add_i32 s28, s28, s26
	s_bcnt1_i32_b64 s26, s[24:25]
	s_add_i32 s27, s27, s26
	v_cndmask_b32_e64 v167, -1, v167, s[22:23]
	v_cndmask_b32_e64 v205, v167, 0, s[24:25]
	v_add_u32_e32 v8, 1, v238
	v_cmp_eq_u32_e64 s[22:23], s1, v206
	v_cmp_lt_u32_e64 s[24:25], s1, v206
	s_bcnt1_i32_b64 s26, s[22:23]
	s_add_i32 s28, s28, s26
	s_bcnt1_i32_b64 s26, s[24:25]
	s_add_i32 s27, s27, s26
	v_cndmask_b32_e64 v8, -1, v8, s[22:23]
	v_cndmask_b32_e64 v206, v8, 0, s[24:25]
	v_add_u32_e32 v9, 1, v239
	v_cmp_eq_u32_e64 s[22:23], s1, v207
	v_cmp_lt_u32_e64 s[24:25], s1, v207
	s_bcnt1_i32_b64 s26, s[22:23]
	s_add_i32 s28, s28, s26
	s_bcnt1_i32_b64 s26, s[24:25]
	s_add_i32 s27, s27, s26
	v_cndmask_b32_e64 v9, -1, v9, s[22:23]
	v_cndmask_b32_e64 v207, v9, 0, s[24:25]
	v_add_u32_e32 v13, 1, v240
	v_cmp_eq_u32_e64 s[22:23], s1, v208
	v_cmp_lt_u32_e64 s[24:25], s1, v208
	s_bcnt1_i32_b64 s26, s[22:23]
	s_add_i32 s28, s28, s26
	s_bcnt1_i32_b64 s26, s[24:25]
	s_add_i32 s27, s27, s26
	v_cndmask_b32_e64 v13, -1, v13, s[22:23]
	v_cndmask_b32_e64 v208, v13, 0, s[24:25]
	v_add_u32_e32 v167, 1, v241
	v_cmp_eq_u32_e64 s[22:23], s1, v209
	v_cmp_lt_u32_e64 s[24:25], s1, v209
	s_bcnt1_i32_b64 s26, s[22:23]
	s_add_i32 s28, s28, s26
	s_bcnt1_i32_b64 s26, s[24:25]
	s_add_i32 s27, s27, s26
	v_cndmask_b32_e64 v167, -1, v167, s[22:23]
	v_cndmask_b32_e64 v209, v167, 0, s[24:25]
	v_add_u32_e32 v8, 1, v242
	v_cmp_eq_u32_e64 s[22:23], s1, v210
	v_cmp_lt_u32_e64 s[24:25], s1, v210
	s_bcnt1_i32_b64 s26, s[22:23]
	s_add_i32 s28, s28, s26
	s_bcnt1_i32_b64 s26, s[24:25]
	s_add_i32 s27, s27, s26
	v_cndmask_b32_e64 v8, -1, v8, s[22:23]
	v_cndmask_b32_e64 v210, v8, 0, s[24:25]
	v_add_u32_e32 v9, 1, v243
	v_cmp_eq_u32_e64 s[22:23], s1, v211
	v_cmp_lt_u32_e64 s[24:25], s1, v211
	s_bcnt1_i32_b64 s26, s[22:23]
	s_add_i32 s28, s28, s26
	s_bcnt1_i32_b64 s26, s[24:25]
	s_add_i32 s27, s27, s26
	v_cndmask_b32_e64 v9, -1, v9, s[22:23]
	v_cndmask_b32_e64 v211, v9, 0, s[24:25]
	v_add_u32_e32 v13, 1, v244
	v_cmp_eq_u32_e64 s[22:23], s1, v212
	v_cmp_lt_u32_e64 s[24:25], s1, v212
	s_bcnt1_i32_b64 s26, s[22:23]
	s_add_i32 s28, s28, s26
	s_bcnt1_i32_b64 s26, s[24:25]
	s_add_i32 s27, s27, s26
	v_cndmask_b32_e64 v13, -1, v13, s[22:23]
	v_cndmask_b32_e64 v212, v13, 0, s[24:25]
	v_add_u32_e32 v167, 1, v245
	v_cmp_eq_u32_e64 s[22:23], s1, v213
; DI void topk_phase(const bf16_t* PROJ, const unsigned char* K8, const unsigned char* V8, const unsigned short* SC, bf16_t* ODSA, int c, char* smem, int bid, int nb) {
;     ...
;       const int need = 256 - cgt;
;       int X = 0x7fffffff;
;       if (ceq != need) {
;         X = 0;
;         for (int b = 13; b >= 0; --b) {
;           const int cand = X | (1 << b);
;           int cc = 0;
; #pragma unroll
;           for (int i = 0; i < 64; ++i) if ((i >> 2) * 1024 < n) cc += (key[i] == T && ((i >> 2) * 256 + tid) * 4 + (i & 3) < cand) ? 1 : 0;
;           if (block_count(cc, b & 1, red) < need) X = cand;
;         }
;       }
	v_cmp_lt_u32_e64 s[24:25], s1, v213
	s_bcnt1_i32_b64 s26, s[22:23]
	s_add_i32 s28, s28, s26
	s_bcnt1_i32_b64 s26, s[24:25]
	s_add_i32 s27, s27, s26
	v_cndmask_b32_e64 v167, -1, v167, s[22:23]
	v_cndmask_b32_e64 v213, v167, 0, s[24:25]
	v_add_u32_e32 v8, 1, v215
	v_cmp_eq_u32_e64 s[22:23], s1, v226
	v_cmp_lt_u32_e64 s[24:25], s1, v226
	s_bcnt1_i32_b64 s26, s[22:23]
	s_add_i32 s28, s28, s26
	s_bcnt1_i32_b64 s26, s[24:25]
	s_add_i32 s27, s27, s26
	v_cndmask_b32_e64 v8, -1, v8, s[22:23]
	v_cndmask_b32_e64 v226, v8, 0, s[24:25]
	v_add_u32_e32 v9, 1, v216
	v_cmp_eq_u32_e64 s[22:23], s1, v227
	v_cmp_lt_u32_e64 s[24:25], s1, v227
	s_bcnt1_i32_b64 s26, s[22:23]
	s_add_i32 s28, s28, s26
	s_bcnt1_i32_b64 s26, s[24:25]
	s_add_i32 s27, s27, s26
	v_cndmask_b32_e64 v9, -1, v9, s[22:23]
	v_cndmask_b32_e64 v227, v9, 0, s[24:25]
	v_add_u32_e32 v13, 1, v221
	v_cmp_eq_u32_e64 s[22:23], s1, v228
	v_cmp_lt_u32_e64 s[24:25], s1, v228
	s_bcnt1_i32_b64 s26, s[22:23]
	s_add_i32 s28, s28, s26
	s_bcnt1_i32_b64 s26, s[24:25]
	s_add_i32 s27, s27, s26
	v_cndmask_b32_e64 v13, -1, v13, s[22:23]
	v_cndmask_b32_e64 v228, v13, 0, s[24:25]
	v_add_u32_e32 v167, 1, v224
	v_cmp_eq_u32_e64 s[22:23], s1, v229
	v_cmp_lt_u32_e64 s[24:25], s1, v229
	s_bcnt1_i32_b64 s26, s[22:23]
	s_add_i32 s28, s28, s26
	s_bcnt1_i32_b64 s26, s[24:25]
	s_add_i32 s27, s27, s26
	v_cndmask_b32_e64 v167, -1, v167, s[22:23]
	v_cndmask_b32_e64 v229, v167, 0, s[24:25]
	s_sub_i32 s29, 0x100, s27
	s_mov_b32 s30, 0x80000000
	s_cmp_eq_u32 s28, s29
	s_cbranch_scc1 .Lsel_fin_A
	s_mov_b32 s30, 0
	s_mov_b32 s2, 13
.Lsel_tie_A:
	s_lshl_b32 s0, 1, s2
	s_or_b32 s0, s0, s30
	s_mov_b32 s33, 0
	v_cmp_ge_u32_e64 s[22:23], s0, v186
	v_cmp_ge_u32_e64 s[24:25], s0, v187
	s_bcnt1_i32_b64 s26, s[22:23]
	s_add_i32 s33, s33, s26
	v_cmp_ge_u32_e64 s[22:23], s0, v188
	s_bcnt1_i32_b64 s26, s[24:25]
	s_add_i32 s33, s33, s26
	v_cmp_ge_u32_e64 s[24:25], s0, v189
	s_bcnt1_i32_b64 s26, s[22:23]
	s_add_i32 s33, s33, s26
	v_cmp_ge_u32_e64 s[22:23], s0, v190
	s_bcnt1_i32_b64 s26, s[24:25]
	s_add_i32 s33, s33, s26
	v_cmp_ge_u32_e64 s[24:25], s0, v191
	s_bcnt1_i32_b64 s26, s[22:23]
	s_add_i32 s33, s33, s26
	v_cmp_ge_u32_e64 s[22:23], s0, v192
	s_bcnt1_i32_b64 s26, s[24:25]
	s_add_i32 s33, s33, s26
	v_cmp_ge_u32_e64 s[24:25], s0, v193
	s_bcnt1_i32_b64 s26, s[22:23]
	s_add_i32 s33, s33, s26
	v_cmp_ge_u32_e64 s[22:23], s0, v194
	s_bcnt1_i32_b64 s26, s[24:25]
	s_add_i32 s33, s33, s26
	v_cmp_ge_u32_e64 s[24:25], s0, v195
	s_bcnt1_i32_b64 s26, s[22:23]
	s_add_i32 s33, s33, s26
	v_cmp_ge_u32_e64 s[22:23], s0, v196
	s_bcnt1_i32_b64 s26, s[24:25]
	s_add_i32 s33, s33, s26
	v_cmp_ge_u32_e64 s[24:25], s0, v197
	s_bcnt1_i32_b64 s26, s[22:23]
	s_add_i32 s33, s33, s26
	v_cmp_ge_u32_e64 s[22:23], s0, v198
	s_bcnt1_i32_b64 s26, s[24:25]
	s_add_i32 s33, s33, s26
	v_cmp_ge_u32_e64 s[24:25], s0, v199
	s_bcnt1_i32_b64 s26, s[22:23]
	s_add_i32 s33, s33, s26
	v_cmp_ge_u32_e64 s[22:23], s0, v200
	s_bcnt1_i32_b64 s26, s[24:25]
	s_add_i32 s33, s33, s26
	v_cmp_ge_u32_e64 s[24:25], s0, v201
	s_bcnt1_i32_b64 s26, s[22:23]
	s_add_i32 s33, s33, s26
	v_cmp_ge_u32_e64 s[22:23], s0, v202
	s_bcnt1_i32_b64 s26, s[24:25]
	s_add_i32 s33, s33, s26
	v_cmp_ge_u32_e64 s[24:25], s0, v203
	s_bcnt1_i32_b64 s26, s[22:23]
	s_add_i32 s33, s33, s26
	v_cmp_ge_u32_e64 s[22:23], s0, v204
	s_bcnt1_i32_b64 s26, s[24:25]
	s_add_i32 s33, s33, s26
	v_cmp_ge_u32_e64 s[24:25], s0, v205
	s_bcnt1_i32_b64 s26, s[22:23]
	s_add_i32 s33, s33, s26
	v_cmp_ge_u32_e64 s[22:23], s0, v206
	s_bcnt1_i32_b64 s26, s[24:25]
	s_add_i32 s33, s33, s26
	v_cmp_ge_u32_e64 s[24:25], s0, v207
	s_bcnt1_i32_b64 s26, s[22:23]
	s_add_i32 s33, s33, s26
	v_cmp_ge_u32_e64 s[22:23], s0, v208
	s_bcnt1_i32_b64 s26, s[24:25]
	s_add_i32 s33, s33, s26
	v_cmp_ge_u32_e64 s[24:25], s0, v209
	s_bcnt1_i32_b64 s26, s[22:23]
	s_add_i32 s33, s33, s26
	v_cmp_ge_u32_e64 s[22:23], s0, v210
	s_bcnt1_i32_b64 s26, s[24:25]
	s_add_i32 s33, s33, s26
	v_cmp_ge_u32_e64 s[24:25], s0, v211
	s_bcnt1_i32_b64 s26, s[22:23]
	s_add_i32 s33, s33, s26
	v_cmp_ge_u32_e64 s[22:23], s0, v212
	s_bcnt1_i32_b64 s26, s[24:25]
	s_add_i32 s33, s33, s26
	v_cmp_ge_u32_e64 s[24:25], s0, v213
	s_bcnt1_i32_b64 s26, s[22:23]
	s_add_i32 s33, s33, s26
	v_cmp_ge_u32_e64 s[22:23], s0, v226
	s_bcnt1_i32_b64 s26, s[24:25]
	s_add_i32 s33, s33, s26
	v_cmp_ge_u32_e64 s[24:25], s0, v227
	s_bcnt1_i32_b64 s26, s[22:23]
	s_add_i32 s33, s33, s26
	v_cmp_ge_u32_e64 s[22:23], s0, v228
	s_bcnt1_i32_b64 s26, s[24:25]
	s_add_i32 s33, s33, s26
	v_cmp_ge_u32_e64 s[24:25], s0, v229
	s_bcnt1_i32_b64 s26, s[22:23]
	s_add_i32 s33, s33, s26
	s_bcnt1_i32_b64 s26, s[24:25]
	s_add_i32 s33, s33, s26
	s_sub_i32 s33, s33, s27
	s_cmp_lt_u32 s33, s29
	s_cselect_b32 s30, s0, s30
	s_add_i32 s2, s2, -1
	s_cmp_lg_u32 s2, -1
	s_cbranch_scc1 .Lsel_tie_A
	s_add_i32 s30, s30, 1
; DI void topk_phase(const bf16_t* PROJ, const unsigned char* K8, const unsigned char* V8, const unsigned short* SC, bf16_t* ODSA, int c, char* smem, int bid, int nb) {
;     ...
; #pragma unroll
;       for (int i = 0; i < 64; ++i)
;         if ((i >> 2) * 1024 < n) {
;           const int idx = ((i >> 2) * 256 + tid) * 4 + (i & 3);
;           if (key[i] > T || (key[i] == T && idx <= X)) { const int ps = atomicAdd(&cnts[0], 1); sel[ps] = idx; }
;         }
.Lsel_fin_A:
	s_mov_b32 s33, 0
	v_cmp_ge_u32_e64 s[22:23], s30, v186
	v_cmp_ge_u32_e64 s[24:25], s30, v187
	s_nop 0
	v_mbcnt_lo_u32_b32 v9, s22, 0
	v_mbcnt_hi_u32_b32 v9, s23, v9
	v_add_lshl_u32 v8, v9, s33, 2
	s_bcnt1_i32_b64 s26, s[22:23]
	s_add_i32 s33, s33, s26
	s_mov_b64 exec, s[22:23]
	ds_write_b32 v8, v172
	s_mov_b64 exec, -1
	v_cmp_ge_u32_e64 s[22:23], s30, v188
	v_mbcnt_lo_u32_b32 v9, s24, 0
	v_mbcnt_hi_u32_b32 v9, s25, v9
	v_add_lshl_u32 v8, v9, s33, 2
	s_bcnt1_i32_b64 s26, s[24:25]
	s_add_i32 s33, s33, s26
	s_mov_b64 exec, s[24:25]
	ds_write_b32 v8, v173
	s_mov_b64 exec, -1
	v_cmp_ge_u32_e64 s[24:25], s30, v189
	v_mbcnt_lo_u32_b32 v9, s22, 0
	v_mbcnt_hi_u32_b32 v9, s23, v9
	v_add_lshl_u32 v8, v9, s33, 2
	s_bcnt1_i32_b64 s26, s[22:23]
	s_add_i32 s33, s33, s26
	s_mov_b64 exec, s[22:23]
	ds_write_b32 v8, v174
	s_mov_b64 exec, -1
	v_cmp_ge_u32_e64 s[22:23], s30, v190
	v_mbcnt_lo_u32_b32 v9, s24, 0
	v_mbcnt_hi_u32_b32 v9, s25, v9
	v_add_lshl_u32 v8, v9, s33, 2
	s_bcnt1_i32_b64 s26, s[24:25]
	s_add_i32 s33, s33, s26
	s_mov_b64 exec, s[24:25]
	ds_write_b32 v8, v175
	s_mov_b64 exec, -1
	v_cmp_ge_u32_e64 s[24:25], s30, v191
	v_mbcnt_lo_u32_b32 v9, s22, 0
	v_mbcnt_hi_u32_b32 v9, s23, v9
	v_add_lshl_u32 v8, v9, s33, 2
	s_bcnt1_i32_b64 s26, s[22:23]
	s_add_i32 s33, s33, s26
	s_mov_b64 exec, s[22:23]
	ds_write_b32 v8, v176
	s_mov_b64 exec, -1
	v_cmp_ge_u32_e64 s[22:23], s30, v192
	v_mbcnt_lo_u32_b32 v9, s24, 0
	v_mbcnt_hi_u32_b32 v9, s25, v9
	v_add_lshl_u32 v8, v9, s33, 2
	s_bcnt1_i32_b64 s26, s[24:25]
	s_add_i32 s33, s33, s26
	s_mov_b64 exec, s[24:25]
	ds_write_b32 v8, v177
	s_mov_b64 exec, -1
	v_cmp_ge_u32_e64 s[24:25], s30, v193
	v_mbcnt_lo_u32_b32 v9, s22, 0
	v_mbcnt_hi_u32_b32 v9, s23, v9
	v_add_lshl_u32 v8, v9, s33, 2
	s_bcnt1_i32_b64 s26, s[22:23]
	s_add_i32 s33, s33, s26
	s_mov_b64 exec, s[22:23]
	ds_write_b32 v8, v178
	s_mov_b64 exec, -1
	v_cmp_ge_u32_e64 s[22:23], s30, v194
	v_mbcnt_lo_u32_b32 v9, s24, 0
	v_mbcnt_hi_u32_b32 v9, s25, v9
	v_add_lshl_u32 v8, v9, s33, 2
	s_bcnt1_i32_b64 s26, s[24:25]
	s_add_i32 s33, s33, s26
	s_mov_b64 exec, s[24:25]
	ds_write_b32 v8, v179
	s_mov_b64 exec, -1
	v_cmp_ge_u32_e64 s[24:25], s30, v195
	v_mbcnt_lo_u32_b32 v9, s22, 0
	v_mbcnt_hi_u32_b32 v9, s23, v9
	v_add_lshl_u32 v8, v9, s33, 2
	s_bcnt1_i32_b64 s26, s[22:23]
	s_add_i32 s33, s33, s26
	s_mov_b64 exec, s[22:23]
	ds_write_b32 v8, v180
	s_mov_b64 exec, -1
	v_cmp_ge_u32_e64 s[22:23], s30, v196
	v_mbcnt_lo_u32_b32 v9, s24, 0
	v_mbcnt_hi_u32_b32 v9, s25, v9
	v_add_lshl_u32 v8, v9, s33, 2
	s_bcnt1_i32_b64 s26, s[24:25]
	s_add_i32 s33, s33, s26
	s_mov_b64 exec, s[24:25]
	ds_write_b32 v8, v181
	s_mov_b64 exec, -1
	v_cmp_ge_u32_e64 s[24:25], s30, v197
	v_mbcnt_lo_u32_b32 v9, s22, 0
	v_mbcnt_hi_u32_b32 v9, s23, v9
	v_add_lshl_u32 v8, v9, s33, 2
	s_bcnt1_i32_b64 s26, s[22:23]
	s_add_i32 s33, s33, s26
	s_mov_b64 exec, s[22:23]
	ds_write_b32 v8, v182
	s_mov_b64 exec, -1
	v_cmp_ge_u32_e64 s[22:23], s30, v198
	v_mbcnt_lo_u32_b32 v9, s24, 0
	v_mbcnt_hi_u32_b32 v9, s25, v9
	v_add_lshl_u32 v8, v9, s33, 2
	s_bcnt1_i32_b64 s26, s[24:25]
	s_add_i32 s33, s33, s26
	s_mov_b64 exec, s[24:25]
	ds_write_b32 v8, v183
	s_mov_b64 exec, -1
	v_cmp_ge_u32_e64 s[24:25], s30, v199
	v_mbcnt_lo_u32_b32 v9, s22, 0
	v_mbcnt_hi_u32_b32 v9, s23, v9
	v_add_lshl_u32 v8, v9, s33, 2
	s_bcnt1_i32_b64 s26, s[22:23]
	s_add_i32 s33, s33, s26
	s_mov_b64 exec, s[22:23]
	ds_write_b32 v8, v184
	s_mov_b64 exec, -1
	v_cmp_ge_u32_e64 s[22:23], s30, v200
	v_mbcnt_lo_u32_b32 v9, s24, 0
	v_mbcnt_hi_u32_b32 v9, s25, v9
	v_add_lshl_u32 v8, v9, s33, 2
	s_bcnt1_i32_b64 s26, s[24:25]
	s_add_i32 s33, s33, s26
	s_mov_b64 exec, s[24:25]
	ds_write_b32 v8, v230
	s_mov_b64 exec, -1
	v_cmp_ge_u32_e64 s[24:25], s30, v201
	v_mbcnt_lo_u32_b32 v9, s22, 0
	v_mbcnt_hi_u32_b32 v9, s23, v9
	v_add_lshl_u32 v8, v9, s33, 2
	s_bcnt1_i32_b64 s26, s[22:23]
	s_add_i32 s33, s33, s26
	s_mov_b64 exec, s[22:23]
	ds_write_b32 v8, v231
	s_mov_b64 exec, -1
	v_cmp_ge_u32_e64 s[22:23], s30, v202
	v_mbcnt_lo_u32_b32 v9, s24, 0
	v_mbcnt_hi_u32_b32 v9, s25, v9
	v_add_lshl_u32 v8, v9, s33, 2
	s_bcnt1_i32_b64 s26, s[24:25]
	s_add_i32 s33, s33, s26
	s_mov_b64 exec, s[24:25]
	ds_write_b32 v8, v232
	s_mov_b64 exec, -1
	v_cmp_ge_u32_e64 s[24:25], s30, v203
	v_mbcnt_lo_u32_b32 v9, s22, 0
	v_mbcnt_hi_u32_b32 v9, s23, v9
	v_add_lshl_u32 v8, v9, s33, 2
	s_bcnt1_i32_b64 s26, s[22:23]
	s_add_i32 s33, s33, s26
	s_mov_b64 exec, s[22:23]
	ds_write_b32 v8, v233
; DI void topk_phase(const bf16_t* PROJ, const unsigned char* K8, const unsigned char* V8, const unsigned short* SC, bf16_t* ODSA, int c, char* smem, int bid, int nb) {
;     ...
;       unsigned T = 0u;
;       for (int b = 15; b >= 0; --b) {
;         const unsigned cand = T | (1u << b);
;         int cc = 0;
; #pragma unroll
;         for (int i = 0; i < 64; ++i) if ((i >> 2) * 1024 < n) cc += key[i] >= cand ? 1 : 0;
;         if (block_count(cc, b & 1, red) >= 256) T = cand;
;     ...
;       for (int i = 0; i < 64; ++i)
;         if ((i >> 2) * 1024 < n) {
;           const int idx = ((i >> 2) * 256 + tid) * 4 + (i & 3);
;           if (key[i] > T || (key[i] == T && idx <= X)) { const int ps = atomicAdd(&cnts[0], 1); sel[ps] = idx; }
;         }
	s_mov_b64 exec, -1
	v_cmp_ge_u32_e64 s[22:23], s30, v204
	v_mbcnt_lo_u32_b32 v9, s24, 0
	v_mbcnt_hi_u32_b32 v9, s25, v9
	v_add_lshl_u32 v8, v9, s33, 2
	s_bcnt1_i32_b64 s26, s[24:25]
	s_add_i32 s33, s33, s26
	s_mov_b64 exec, s[24:25]
	ds_write_b32 v8, v235
	s_mov_b64 exec, -1
	v_cmp_ge_u32_e64 s[24:25], s30, v205
	v_mbcnt_lo_u32_b32 v9, s22, 0
	v_mbcnt_hi_u32_b32 v9, s23, v9
	v_add_lshl_u32 v8, v9, s33, 2
	s_bcnt1_i32_b64 s26, s[22:23]
	s_add_i32 s33, s33, s26
	s_mov_b64 exec, s[22:23]
	ds_write_b32 v8, v236
	s_mov_b64 exec, -1
	v_cmp_ge_u32_e64 s[22:23], s30, v206
	v_mbcnt_lo_u32_b32 v9, s24, 0
	v_mbcnt_hi_u32_b32 v9, s25, v9
	v_add_lshl_u32 v8, v9, s33, 2
	s_bcnt1_i32_b64 s26, s[24:25]
	s_add_i32 s33, s33, s26
	s_mov_b64 exec, s[24:25]
	ds_write_b32 v8, v237
	s_mov_b64 exec, -1
	v_cmp_ge_u32_e64 s[24:25], s30, v207
	v_mbcnt_lo_u32_b32 v9, s22, 0
	v_mbcnt_hi_u32_b32 v9, s23, v9
	v_add_lshl_u32 v8, v9, s33, 2
	s_bcnt1_i32_b64 s26, s[22:23]
	s_add_i32 s33, s33, s26
	s_mov_b64 exec, s[22:23]
	ds_write_b32 v8, v238
	s_mov_b64 exec, -1
	v_cmp_ge_u32_e64 s[22:23], s30, v208
	v_mbcnt_lo_u32_b32 v9, s24, 0
	v_mbcnt_hi_u32_b32 v9, s25, v9
	v_add_lshl_u32 v8, v9, s33, 2
	s_bcnt1_i32_b64 s26, s[24:25]
	s_add_i32 s33, s33, s26
	s_mov_b64 exec, s[24:25]
	ds_write_b32 v8, v239
	s_mov_b64 exec, -1
	v_cmp_ge_u32_e64 s[24:25], s30, v209
	v_mbcnt_lo_u32_b32 v9, s22, 0
	v_mbcnt_hi_u32_b32 v9, s23, v9
	v_add_lshl_u32 v8, v9, s33, 2
	s_bcnt1_i32_b64 s26, s[22:23]
	s_add_i32 s33, s33, s26
	s_mov_b64 exec, s[22:23]
	ds_write_b32 v8, v240
	s_mov_b64 exec, -1
	v_cmp_ge_u32_e64 s[22:23], s30, v210
	v_mbcnt_lo_u32_b32 v9, s24, 0
	v_mbcnt_hi_u32_b32 v9, s25, v9
	v_add_lshl_u32 v8, v9, s33, 2
	s_bcnt1_i32_b64 s26, s[24:25]
	s_add_i32 s33, s33, s26
	s_mov_b64 exec, s[24:25]
	ds_write_b32 v8, v241
	s_mov_b64 exec, -1
	v_cmp_ge_u32_e64 s[24:25], s30, v211
	v_mbcnt_lo_u32_b32 v9, s22, 0
	v_mbcnt_hi_u32_b32 v9, s23, v9
	v_add_lshl_u32 v8, v9, s33, 2
	s_bcnt1_i32_b64 s26, s[22:23]
	s_add_i32 s33, s33, s26
	s_mov_b64 exec, s[22:23]
	ds_write_b32 v8, v242
	s_mov_b64 exec, -1
	v_cmp_ge_u32_e64 s[22:23], s30, v212
	v_mbcnt_lo_u32_b32 v9, s24, 0
	v_mbcnt_hi_u32_b32 v9, s25, v9
	v_add_lshl_u32 v8, v9, s33, 2
	s_bcnt1_i32_b64 s26, s[24:25]
	s_add_i32 s33, s33, s26
	s_mov_b64 exec, s[24:25]
	ds_write_b32 v8, v243
	s_mov_b64 exec, -1
	v_cmp_ge_u32_e64 s[24:25], s30, v213
	v_mbcnt_lo_u32_b32 v9, s22, 0
	v_mbcnt_hi_u32_b32 v9, s23, v9
	v_add_lshl_u32 v8, v9, s33, 2
	s_bcnt1_i32_b64 s26, s[22:23]
	s_add_i32 s33, s33, s26
	s_mov_b64 exec, s[22:23]
	ds_write_b32 v8, v244
	s_mov_b64 exec, -1
	v_cmp_ge_u32_e64 s[22:23], s30, v226
	v_mbcnt_lo_u32_b32 v9, s24, 0
	v_mbcnt_hi_u32_b32 v9, s25, v9
	v_add_lshl_u32 v8, v9, s33, 2
	s_bcnt1_i32_b64 s26, s[24:25]
	s_add_i32 s33, s33, s26
	s_mov_b64 exec, s[24:25]
	ds_write_b32 v8, v245
	s_mov_b64 exec, -1
	v_cmp_ge_u32_e64 s[24:25], s30, v227
	v_mbcnt_lo_u32_b32 v9, s22, 0
	v_mbcnt_hi_u32_b32 v9, s23, v9
	v_add_lshl_u32 v8, v9, s33, 2
	s_bcnt1_i32_b64 s26, s[22:23]
	s_add_i32 s33, s33, s26
	s_mov_b64 exec, s[22:23]
	ds_write_b32 v8, v215
	s_mov_b64 exec, -1
	v_cmp_ge_u32_e64 s[22:23], s30, v228
	v_mbcnt_lo_u32_b32 v9, s24, 0
	v_mbcnt_hi_u32_b32 v9, s25, v9
	v_add_lshl_u32 v8, v9, s33, 2
	s_bcnt1_i32_b64 s26, s[24:25]
	s_add_i32 s33, s33, s26
	s_mov_b64 exec, s[24:25]
	ds_write_b32 v8, v216
	s_mov_b64 exec, -1
	v_cmp_ge_u32_e64 s[24:25], s30, v229
	v_mbcnt_lo_u32_b32 v9, s22, 0
	v_mbcnt_hi_u32_b32 v9, s23, v9
	v_add_lshl_u32 v8, v9, s33, 2
	s_bcnt1_i32_b64 s26, s[22:23]
	s_add_i32 s33, s33, s26
	s_mov_b64 exec, s[22:23]
	ds_write_b32 v8, v221
	s_mov_b64 exec, -1
	v_mbcnt_lo_u32_b32 v9, s24, 0
	v_mbcnt_hi_u32_b32 v9, s25, v9
	v_add_lshl_u32 v8, v9, s33, 2
	s_bcnt1_i32_b64 s26, s[24:25]
	s_add_i32 s33, s33, s26
	s_mov_b64 exec, s[24:25]
	ds_write_b32 v8, v224
	s_mov_b64 exec, -1
	s_branch .LBB0_1044
.Lsel_fb_A:
	s_xor_b64 s[72:73], s[8:9], -1
	s_xor_b64 s[28:29], s[10:11], -1
	s_xor_b64 s[26:27], s[12:13], -1
	s_xor_b64 s[70:71], s[14:15], -1
	s_xor_b64 s[24:25], s[4:5], -1
	s_xor_b64 s[68:69], s[2:3], -1
	s_xor_b64 s[22:23], s[6:7], -1
	s_xor_b64 s[20:21], s[16:17], -1
	s_xor_b64 s[66:67], s[18:19], -1
	s_xor_b64 s[18:19], s[30:31], -1
	s_xor_b64 s[16:17], s[34:35], -1
	s_xor_b64 s[80:81], s[36:37], -1
	s_xor_b64 s[78:79], s[38:39], -1
	s_xor_b64 s[76:77], s[40:41], -1
	s_xor_b64 s[74:75], s[42:43], -1
	s_mov_b32 s2, 15
	v_mov_b32_e32 v13, 0
	s_branch .LBB0_613

; DI float sum8(float v) { v += DPPF(v, 0xB1); v += DPPF(v, 0x4E); v += DPPF(v, 0x141); return v; }
; DI void topk_phase(const bf16_t* PROJ, const unsigned char* K8, const unsigned char* V8, const unsigned short* SC, bf16_t* ODSA, int c, char* smem, int bid, int nb) {
;     ...
;     const int mysel = sel[wid * 64 + lane];
; #pragma unroll 4
;     for (int jj = 0; jj < 64; ++jj) {
;       const int j = wid * 64 + jj;
;       {
;         const size_t ro = (size_t)__builtin_amdgcn_readlane(mysel, jj) * 1024 + lane * 16;
;         const uint4 a = *(const uint4*)(K8 + ro), vv = *(const uint4*)(V8 + ro);
;         const unsigned w[4] = {a.x, a.y, a.z, a.w}, u[4] = {vv.x, vv.y, vv.z, vv.w};
;         float da = 0.f;
; #pragma unroll
;         for (int i = 0; i < 4; ++i) {
;           const f32x2v lo = __builtin_amdgcn_cvt_pk_f32_fp8((int)w[i], false), hi = __builtin_amdgcn_cvt_pk_f32_fp8((int)w[i], true);
;           da += qv[4 * i] * lo[0] + qv[4 * i + 1] * lo[1] + qv[4 * i + 2] * hi[0] + qv[4 * i + 3] * hi[1];
;         }
;         da = sum8(da);
;         da = j < count ? da : -3e30f;
;         const float mn = fmaxf(m_run, da), al = __builtin_amdgcn_exp2f(m_run - mn), pp = __builtin_amdgcn_exp2f(da - mn);
;         m_run = mn; l_run = l_run * al + pp;
; #pragma unroll
;         for (int i = 0; i < 4; ++i) {
;           const f32x2v lo = __builtin_amdgcn_cvt_pk_f32_fp8((int)u[i], false), hi = __builtin_amdgcn_cvt_pk_f32_fp8((int)u[i], true);
;           ov[4 * i] = ov[4 * i] * al + pp * lo[0]; ov[4 * i + 1] = ov[4 * i + 1] * al + pp * lo[1];
;           ov[4 * i + 2] = ov[4 * i + 2] * al + pp * hi[0]; ov[4 * i + 3] = ov[4 * i + 3] * al + pp * hi[1];
;         }
;       }
;     }
.LBB0_1048:
	s_waitcnt lgkmcnt(0)
	v_readfirstlane_b32 s1, v71
	v_readlane_b32 s0, v135, 0
	s_lshl_b32 s0, s0, 10
	s_add_u32 s4, s6, s0
	s_addc_u32 s5, s7, 0
	global_load_dwordx4 v[136:139], v16, s[4:5]
	v_readlane_b32 s0, v135, 1
	s_lshl_b32 s0, s0, 10
	s_add_u32 s4, s6, s0
	s_addc_u32 s5, s7, 0
	global_load_dwordx4 v[140:143], v16, s[4:5]
	v_readlane_b32 s0, v135, 2
	s_lshl_b32 s0, s0, 10
	s_add_u32 s4, s6, s0
	s_addc_u32 s5, s7, 0
	global_load_dwordx4 v[144:147], v16, s[4:5]
	v_readlane_b32 s0, v135, 3
	s_lshl_b32 s0, s0, 10
	s_add_u32 s4, s6, s0
	s_addc_u32 s5, s7, 0
	global_load_dwordx4 v[148:151], v16, s[4:5]
	v_readlane_b32 s0, v135, 4
	s_lshl_b32 s0, s0, 10
	s_add_u32 s4, s6, s0
	s_addc_u32 s5, s7, 0
	global_load_dwordx4 v[152:155], v16, s[4:5]
	v_readlane_b32 s0, v135, 5
	s_lshl_b32 s0, s0, 10
	s_add_u32 s4, s6, s0
	s_addc_u32 s5, s7, 0
	global_load_dwordx4 v[156:159], v16, s[4:5]
	v_readlane_b32 s0, v135, 6
	s_lshl_b32 s0, s0, 10
	s_add_u32 s4, s6, s0
	s_addc_u32 s5, s7, 0
	global_load_dwordx4 v[160:163], v16, s[4:5]
	v_readlane_b32 s0, v135, 7
	s_lshl_b32 s0, s0, 10
	s_add_u32 s4, s6, s0
	s_addc_u32 s5, s7, 0
	global_load_dwordx4 v[164:167], v16, s[4:5]
	v_readlane_b32 s0, v135, 8
	s_lshl_b32 s0, s0, 10
	s_add_u32 s4, s6, s0
	s_addc_u32 s5, s7, 0
	global_load_dwordx4 v[168:171], v16, s[4:5]
	v_readlane_b32 s0, v135, 9
	s_lshl_b32 s0, s0, 10
	s_add_u32 s4, s6, s0
	s_addc_u32 s5, s7, 0
	global_load_dwordx4 v[172:175], v16, s[4:5]
	v_readlane_b32 s0, v135, 10
	s_lshl_b32 s0, s0, 10
	s_add_u32 s4, s6, s0
	s_addc_u32 s5, s7, 0
	global_load_dwordx4 v[176:179], v16, s[4:5]
	v_readlane_b32 s0, v135, 11
	s_lshl_b32 s0, s0, 10
	s_add_u32 s4, s6, s0
	s_addc_u32 s5, s7, 0
	global_load_dwordx4 v[180:183], v16, s[4:5]
	v_readlane_b32 s0, v135, 12
	s_lshl_b32 s0, s0, 10
	s_add_u32 s4, s6, s0
	s_addc_u32 s5, s7, 0
	global_load_dwordx4 v[186:189], v16, s[4:5]
	v_readlane_b32 s0, v135, 13
	s_lshl_b32 s0, s0, 10
	s_add_u32 s4, s6, s0
	s_addc_u32 s5, s7, 0
	global_load_dwordx4 v[190:193], v16, s[4:5]
	v_readlane_b32 s0, v135, 14
	s_lshl_b32 s0, s0, 10
	s_add_u32 s4, s6, s0
	s_addc_u32 s5, s7, 0
	global_load_dwordx4 v[194:197], v16, s[4:5]
	v_readlane_b32 s0, v135, 15
	s_lshl_b32 s0, s0, 10
	s_add_u32 s4, s6, s0
	s_addc_u32 s5, s7, 0
	global_load_dwordx4 v[198:201], v16, s[4:5]
	v_mov_b32_e32 v240, v53
	v_mov_b32_e32 v241, v55
	v_mov_b32_e32 v53, v54
	v_mov_b32_e32 v55, v58
	v_mov_b32_e32 v54, v56
	v_mov_b32_e32 v58, v57
	v_mov_b32_e32 v56, v240
	v_mov_b32_e32 v57, v241
	v_mov_b32_e32 v240, v61
	v_mov_b32_e32 v241, v63
	v_mov_b32_e32 v61, v62
	v_mov_b32_e32 v63, v66
	v_mov_b32_e32 v62, v64
	v_mov_b32_e32 v66, v65
	v_mov_b32_e32 v64, v240
	v_mov_b32_e32 v65, v241
	v_mov_b32_e32 v0, 0
	v_mov_b32_e32 v1, 0
	v_mov_b32_e32 v2, 0
	v_mov_b32_e32 v3, 0
	v_mov_b32_e32 v4, 0
	v_mov_b32_e32 v5, 0
	v_mov_b32_e32 v6, 0
	v_mov_b32_e32 v7, 0
	v_mov_b32_e32 v8, 0
	v_mov_b32_e32 v9, 0
	v_mov_b32_e32 v10, 0
	v_mov_b32_e32 v11, 0
	v_mov_b32_e32 v12, 0
	v_mov_b32_e32 v13, 0
	v_mov_b32_e32 v14, 0
	v_mov_b32_e32 v15, 0
	v_mov_b32_e32 v215, 0
	v_mov_b32_e32 v216, 0xf149f2ca
	s_waitcnt vmcnt(15)
	v_cvt_pk_f32_fp8_e32 v[240:241], v136
	v_cvt_pk_f32_fp8_sdwa v[242:243], v136 src0_sel:WORD_1
	v_cvt_pk_f32_fp8_e32 v[244:245], v137
	v_cvt_pk_f32_fp8_sdwa v[202:203], v137 src0_sel:WORD_1
	v_pk_mul_f32 v[204:205], v[240:241], v[52:53]
	v_pk_mul_f32 v[206:207], v[242:243], v[54:55]
	v_cvt_pk_f32_fp8_e32 v[240:241], v138
	v_cvt_pk_f32_fp8_sdwa v[242:243], v138 src0_sel:WORD_1
	v_pk_fma_f32 v[204:205], v[244:245], v[56:57], v[204:205]
	v_pk_fma_f32 v[206:207], v[202:203], v[58:59], v[206:207]
	v_cvt_pk_f32_fp8_e32 v[244:245], v139
	v_cvt_pk_f32_fp8_sdwa v[202:203], v139 src0_sel:WORD_1
	v_pk_fma_f32 v[204:205], v[240:241], v[60:61], v[204:205]
	v_pk_fma_f32 v[206:207], v[242:243], v[62:63], v[206:207]
	v_pk_fma_f32 v[204:205], v[244:245], v[64:65], v[204:205]
	v_pk_fma_f32 v[206:207], v[202:203], v[66:67], v[206:207]
	v_readlane_b32 s0, v135, 0
	s_lshl_b32 s0, s0, 10
	s_add_u32 s4, s8, s0
	s_addc_u32 s5, s9, 0
	global_load_dwordx4 v[136:139], v16, s[4:5]
	v_pk_add_f32 v[204:205], v[204:205], v[206:207]
	s_nop 0
	v_add_f32_e32 v235, v204, v205
	s_waitcnt vmcnt(15)
	v_cvt_pk_f32_fp8_e32 v[240:241], v140
	v_cvt_pk_f32_fp8_sdwa v[242:243], v140 src0_sel:WORD_1
	v_cvt_pk_f32_fp8_e32 v[244:245], v141
	v_cvt_pk_f32_fp8_sdwa v[202:203], v141 src0_sel:WORD_1
	v_add_f32_dpp v235, v235, v235 quad_perm:[1,0,3,2] row_mask:0xf bank_mask:0xf bound_ctrl:1
	v_pk_mul_f32 v[204:205], v[240:241], v[52:53]
	v_pk_mul_f32 v[206:207], v[242:243], v[54:55]
	v_add_f32_dpp v235, v235, v235 quad_perm:[2,3,0,1] row_mask:0xf bank_mask:0xf bound_ctrl:1
	v_cvt_pk_f32_fp8_e32 v[240:241], v142
	v_cvt_pk_f32_fp8_sdwa v[242:243], v142 src0_sel:WORD_1
	v_add_f32_dpp v235, v235, v235 row_half_mirror row_mask:0xf bank_mask:0xf bound_ctrl:1
	v_pk_fma_f32 v[204:205], v[244:245], v[56:57], v[204:205]
	v_pk_fma_f32 v[206:207], v[202:203], v[58:59], v[206:207]
	s_add_i32 s0, s1, 0
	s_cmp_lt_i32 s0, s2
	s_cselect_b64 vcc, -1, 0
	v_cvt_pk_f32_fp8_e32 v[244:245], v143
	v_cvt_pk_f32_fp8_sdwa v[202:203], v143 src0_sel:WORD_1
	v_cndmask_b32_e32 v210, v220, v235, vcc
	v_pk_fma_f32 v[204:205], v[240:241], v[60:61], v[204:205]
	v_pk_fma_f32 v[206:207], v[242:243], v[62:63], v[206:207]
	v_pk_fma_f32 v[204:205], v[244:245], v[64:65], v[204:205]
	v_pk_fma_f32 v[206:207], v[202:203], v[66:67], v[206:207]
	v_readlane_b32 s0, v135, 1
	s_lshl_b32 s0, s0, 10
	s_add_u32 s4, s8, s0
	s_addc_u32 s5, s9, 0
	global_load_dwordx4 v[140:143], v16, s[4:5]
	v_pk_add_f32 v[204:205], v[204:205], v[206:207]
	s_nop 0
	v_add_f32_e32 v221, v204, v205
	s_waitcnt vmcnt(15)
; DI float sum8(float v) { v += DPPF(v, 0xB1); v += DPPF(v, 0x4E); v += DPPF(v, 0x141); return v; }
; DI void topk_phase(const bf16_t* PROJ, const unsigned char* K8, const unsigned char* V8, const unsigned short* SC, bf16_t* ODSA, int c, char* smem, int bid, int nb) {
;     ...
;       {
;         const size_t ro = (size_t)__builtin_amdgcn_readlane(mysel, jj) * 1024 + lane * 16;
;         const uint4 a = *(const uint4*)(K8 + ro), vv = *(const uint4*)(V8 + ro);
;         const unsigned w[4] = {a.x, a.y, a.z, a.w}, u[4] = {vv.x, vv.y, vv.z, vv.w};
;         float da = 0.f;
; #pragma unroll
;         for (int i = 0; i < 4; ++i) {
;           const f32x2v lo = __builtin_amdgcn_cvt_pk_f32_fp8((int)w[i], false), hi = __builtin_amdgcn_cvt_pk_f32_fp8((int)w[i], true);
;           da += qv[4 * i] * lo[0] + qv[4 * i + 1] * lo[1] + qv[4 * i + 2] * hi[0] + qv[4 * i + 3] * hi[1];
;         }
;         da = sum8(da);
;         da = j < count ? da : -3e30f;
	v_cvt_pk_f32_fp8_e32 v[240:241], v144
	v_cvt_pk_f32_fp8_sdwa v[242:243], v144 src0_sel:WORD_1
	v_cvt_pk_f32_fp8_e32 v[244:245], v145
	v_cvt_pk_f32_fp8_sdwa v[202:203], v145 src0_sel:WORD_1
	v_add_f32_dpp v221, v221, v221 quad_perm:[1,0,3,2] row_mask:0xf bank_mask:0xf bound_ctrl:1
	v_pk_mul_f32 v[204:205], v[240:241], v[52:53]
	v_pk_mul_f32 v[206:207], v[242:243], v[54:55]
	v_add_f32_dpp v221, v221, v221 quad_perm:[2,3,0,1] row_mask:0xf bank_mask:0xf bound_ctrl:1
	v_cvt_pk_f32_fp8_e32 v[240:241], v146
	v_cvt_pk_f32_fp8_sdwa v[242:243], v146 src0_sel:WORD_1
	v_add_f32_dpp v221, v221, v221 row_half_mirror row_mask:0xf bank_mask:0xf bound_ctrl:1
	v_pk_fma_f32 v[204:205], v[244:245], v[56:57], v[204:205]
	v_pk_fma_f32 v[206:207], v[202:203], v[58:59], v[206:207]
	s_add_i32 s0, s1, 1
	s_cmp_lt_i32 s0, s2
	s_cselect_b64 vcc, -1, 0
	v_cvt_pk_f32_fp8_e32 v[244:245], v147
	v_cvt_pk_f32_fp8_sdwa v[202:203], v147 src0_sel:WORD_1
	v_cndmask_b32_e32 v211, v220, v221, vcc
	v_pk_fma_f32 v[204:205], v[240:241], v[60:61], v[204:205]
	v_pk_fma_f32 v[206:207], v[242:243], v[62:63], v[206:207]
	v_pk_fma_f32 v[204:205], v[244:245], v[64:65], v[204:205]
	v_pk_fma_f32 v[206:207], v[202:203], v[66:67], v[206:207]
	v_readlane_b32 s0, v135, 2
	s_lshl_b32 s0, s0, 10
	s_add_u32 s4, s8, s0
	s_addc_u32 s5, s9, 0
	global_load_dwordx4 v[144:147], v16, s[4:5]
	v_pk_add_f32 v[204:205], v[204:205], v[206:207]
	s_nop 0
	v_add_f32_e32 v235, v204, v205
	s_waitcnt vmcnt(15)
	v_cvt_pk_f32_fp8_e32 v[240:241], v148
	v_cvt_pk_f32_fp8_sdwa v[242:243], v148 src0_sel:WORD_1
	v_cvt_pk_f32_fp8_e32 v[244:245], v149
	v_cvt_pk_f32_fp8_sdwa v[202:203], v149 src0_sel:WORD_1
	v_add_f32_dpp v235, v235, v235 quad_perm:[1,0,3,2] row_mask:0xf bank_mask:0xf bound_ctrl:1
	v_pk_mul_f32 v[204:205], v[240:241], v[52:53]
	v_pk_mul_f32 v[206:207], v[242:243], v[54:55]
	v_add_f32_dpp v235, v235, v235 quad_perm:[2,3,0,1] row_mask:0xf bank_mask:0xf bound_ctrl:1
	v_cvt_pk_f32_fp8_e32 v[240:241], v150
	v_cvt_pk_f32_fp8_sdwa v[242:243], v150 src0_sel:WORD_1
	v_add_f32_dpp v235, v235, v235 row_half_mirror row_mask:0xf bank_mask:0xf bound_ctrl:1
	v_pk_fma_f32 v[204:205], v[244:245], v[56:57], v[204:205]
	v_pk_fma_f32 v[206:207], v[202:203], v[58:59], v[206:207]
	s_add_i32 s0, s1, 2
	s_cmp_lt_i32 s0, s2
	s_cselect_b64 vcc, -1, 0
	v_cvt_pk_f32_fp8_e32 v[244:245], v151
	v_cvt_pk_f32_fp8_sdwa v[202:203], v151 src0_sel:WORD_1
	v_cndmask_b32_e32 v212, v220, v235, vcc
	v_pk_fma_f32 v[204:205], v[240:241], v[60:61], v[204:205]
	v_pk_fma_f32 v[206:207], v[242:243], v[62:63], v[206:207]
	v_pk_fma_f32 v[204:205], v[244:245], v[64:65], v[204:205]
	v_pk_fma_f32 v[206:207], v[202:203], v[66:67], v[206:207]
	v_readlane_b32 s0, v135, 3
	s_lshl_b32 s0, s0, 10
	s_add_u32 s4, s8, s0
	s_addc_u32 s5, s9, 0
	global_load_dwordx4 v[148:151], v16, s[4:5]
	v_pk_add_f32 v[204:205], v[204:205], v[206:207]
	s_nop 0
	v_add_f32_e32 v221, v204, v205
	s_waitcnt vmcnt(15)
	v_cvt_pk_f32_fp8_e32 v[240:241], v152
	v_cvt_pk_f32_fp8_sdwa v[242:243], v152 src0_sel:WORD_1
	v_cvt_pk_f32_fp8_e32 v[244:245], v153
	v_cvt_pk_f32_fp8_sdwa v[202:203], v153 src0_sel:WORD_1
	v_add_f32_dpp v221, v221, v221 quad_perm:[1,0,3,2] row_mask:0xf bank_mask:0xf bound_ctrl:1
	v_pk_mul_f32 v[204:205], v[240:241], v[52:53]
	v_pk_mul_f32 v[206:207], v[242:243], v[54:55]
	v_add_f32_dpp v221, v221, v221 quad_perm:[2,3,0,1] row_mask:0xf bank_mask:0xf bound_ctrl:1
	v_cvt_pk_f32_fp8_e32 v[240:241], v154
	v_cvt_pk_f32_fp8_sdwa v[242:243], v154 src0_sel:WORD_1
	v_add_f32_dpp v221, v221, v221 row_half_mirror row_mask:0xf bank_mask:0xf bound_ctrl:1
	v_pk_fma_f32 v[204:205], v[244:245], v[56:57], v[204:205]
	v_pk_fma_f32 v[206:207], v[202:203], v[58:59], v[206:207]
	s_add_i32 s0, s1, 3
	s_cmp_lt_i32 s0, s2
	s_cselect_b64 vcc, -1, 0
	v_cvt_pk_f32_fp8_e32 v[244:245], v155
	v_cvt_pk_f32_fp8_sdwa v[202:203], v155 src0_sel:WORD_1
	v_cndmask_b32_e32 v213, v220, v221, vcc
	v_pk_fma_f32 v[204:205], v[240:241], v[60:61], v[204:205]
	v_pk_fma_f32 v[206:207], v[242:243], v[62:63], v[206:207]
	v_pk_fma_f32 v[204:205], v[244:245], v[64:65], v[204:205]
	v_pk_fma_f32 v[206:207], v[202:203], v[66:67], v[206:207]
	v_readlane_b32 s0, v135, 4
	s_lshl_b32 s0, s0, 10
	s_add_u32 s4, s8, s0
	s_addc_u32 s5, s9, 0
	global_load_dwordx4 v[152:155], v16, s[4:5]
	v_pk_add_f32 v[204:205], v[204:205], v[206:207]
	s_nop 0
	v_add_f32_e32 v235, v204, v205
	s_waitcnt vmcnt(15)
	v_cvt_pk_f32_fp8_e32 v[240:241], v156
	v_cvt_pk_f32_fp8_sdwa v[242:243], v156 src0_sel:WORD_1
	v_cvt_pk_f32_fp8_e32 v[244:245], v157
	v_cvt_pk_f32_fp8_sdwa v[202:203], v157 src0_sel:WORD_1
	v_add_f32_dpp v235, v235, v235 quad_perm:[1,0,3,2] row_mask:0xf bank_mask:0xf bound_ctrl:1
	v_pk_mul_f32 v[204:205], v[240:241], v[52:53]
	v_pk_mul_f32 v[206:207], v[242:243], v[54:55]
	v_add_f32_dpp v235, v235, v235 quad_perm:[2,3,0,1] row_mask:0xf bank_mask:0xf bound_ctrl:1
	v_cvt_pk_f32_fp8_e32 v[240:241], v158
	v_cvt_pk_f32_fp8_sdwa v[242:243], v158 src0_sel:WORD_1
	v_add_f32_dpp v235, v235, v235 row_half_mirror row_mask:0xf bank_mask:0xf bound_ctrl:1
	v_pk_fma_f32 v[204:205], v[244:245], v[56:57], v[204:205]
	v_pk_fma_f32 v[206:207], v[202:203], v[58:59], v[206:207]
	s_add_i32 s0, s1, 4
	s_cmp_lt_i32 s0, s2
	s_cselect_b64 vcc, -1, 0
	v_cvt_pk_f32_fp8_e32 v[244:245], v159
	v_cvt_pk_f32_fp8_sdwa v[202:203], v159 src0_sel:WORD_1
	v_cndmask_b32_e32 v226, v220, v235, vcc
	v_pk_fma_f32 v[204:205], v[240:241], v[60:61], v[204:205]
	v_pk_fma_f32 v[206:207], v[242:243], v[62:63], v[206:207]
	v_pk_fma_f32 v[204:205], v[244:245], v[64:65], v[204:205]
	v_pk_fma_f32 v[206:207], v[202:203], v[66:67], v[206:207]
	v_readlane_b32 s0, v135, 5
	s_lshl_b32 s0, s0, 10
	s_add_u32 s4, s8, s0
	s_addc_u32 s5, s9, 0
	global_load_dwordx4 v[156:159], v16, s[4:5]
	v_pk_add_f32 v[204:205], v[204:205], v[206:207]
	s_nop 0
	v_add_f32_e32 v221, v204, v205
	s_waitcnt vmcnt(15)
; DI float sum8(float v) { v += DPPF(v, 0xB1); v += DPPF(v, 0x4E); v += DPPF(v, 0x141); return v; }
; DI void topk_phase(const bf16_t* PROJ, const unsigned char* K8, const unsigned char* V8, const unsigned short* SC, bf16_t* ODSA, int c, char* smem, int bid, int nb) {
;     ...
;     const int mysel = sel[wid * 64 + lane];
; #pragma unroll 4
;     for (int jj = 0; jj < 64; ++jj) {
;       const int j = wid * 64 + jj;
;       {
;         const size_t ro = (size_t)__builtin_amdgcn_readlane(mysel, jj) * 1024 + lane * 16;
;         const uint4 a = *(const uint4*)(K8 + ro), vv = *(const uint4*)(V8 + ro);
;         const unsigned w[4] = {a.x, a.y, a.z, a.w}, u[4] = {vv.x, vv.y, vv.z, vv.w};
;         float da = 0.f;
; #pragma unroll
;         for (int i = 0; i < 4; ++i) {
;           const f32x2v lo = __builtin_amdgcn_cvt_pk_f32_fp8((int)w[i], false), hi = __builtin_amdgcn_cvt_pk_f32_fp8((int)w[i], true);
;           da += qv[4 * i] * lo[0] + qv[4 * i + 1] * lo[1] + qv[4 * i + 2] * hi[0] + qv[4 * i + 3] * hi[1];
;         }
;         da = sum8(da);
;         da = j < count ? da : -3e30f;
;         const float mn = fmaxf(m_run, da), al = __builtin_amdgcn_exp2f(m_run - mn), pp = __builtin_amdgcn_exp2f(da - mn);
;         m_run = mn; l_run = l_run * al + pp;
	v_cvt_pk_f32_fp8_e32 v[240:241], v160
	v_cvt_pk_f32_fp8_sdwa v[242:243], v160 src0_sel:WORD_1
	v_cvt_pk_f32_fp8_e32 v[244:245], v161
	v_cvt_pk_f32_fp8_sdwa v[202:203], v161 src0_sel:WORD_1
	v_add_f32_dpp v221, v221, v221 quad_perm:[1,0,3,2] row_mask:0xf bank_mask:0xf bound_ctrl:1
	v_pk_mul_f32 v[204:205], v[240:241], v[52:53]
	v_pk_mul_f32 v[206:207], v[242:243], v[54:55]
	v_add_f32_dpp v221, v221, v221 quad_perm:[2,3,0,1] row_mask:0xf bank_mask:0xf bound_ctrl:1
	v_cvt_pk_f32_fp8_e32 v[240:241], v162
	v_cvt_pk_f32_fp8_sdwa v[242:243], v162 src0_sel:WORD_1
	v_add_f32_dpp v221, v221, v221 row_half_mirror row_mask:0xf bank_mask:0xf bound_ctrl:1
	v_pk_fma_f32 v[204:205], v[244:245], v[56:57], v[204:205]
	v_pk_fma_f32 v[206:207], v[202:203], v[58:59], v[206:207]
	s_add_i32 s0, s1, 5
	s_cmp_lt_i32 s0, s2
	s_cselect_b64 vcc, -1, 0
	v_cvt_pk_f32_fp8_e32 v[244:245], v163
	v_cvt_pk_f32_fp8_sdwa v[202:203], v163 src0_sel:WORD_1
	v_cndmask_b32_e32 v227, v220, v221, vcc
	v_pk_fma_f32 v[204:205], v[240:241], v[60:61], v[204:205]
	v_pk_fma_f32 v[206:207], v[242:243], v[62:63], v[206:207]
	v_pk_fma_f32 v[204:205], v[244:245], v[64:65], v[204:205]
	v_pk_fma_f32 v[206:207], v[202:203], v[66:67], v[206:207]
	v_readlane_b32 s0, v135, 6
	s_lshl_b32 s0, s0, 10
	s_add_u32 s4, s8, s0
	s_addc_u32 s5, s9, 0
	global_load_dwordx4 v[160:163], v16, s[4:5]
	v_pk_add_f32 v[204:205], v[204:205], v[206:207]
	s_nop 0
	v_add_f32_e32 v235, v204, v205
	s_waitcnt vmcnt(15)
	v_cvt_pk_f32_fp8_e32 v[240:241], v164
	v_cvt_pk_f32_fp8_sdwa v[242:243], v164 src0_sel:WORD_1
	v_cvt_pk_f32_fp8_e32 v[244:245], v165
	v_cvt_pk_f32_fp8_sdwa v[202:203], v165 src0_sel:WORD_1
	v_add_f32_dpp v235, v235, v235 quad_perm:[1,0,3,2] row_mask:0xf bank_mask:0xf bound_ctrl:1
	v_pk_mul_f32 v[204:205], v[240:241], v[52:53]
	v_pk_mul_f32 v[206:207], v[242:243], v[54:55]
	v_add_f32_dpp v235, v235, v235 quad_perm:[2,3,0,1] row_mask:0xf bank_mask:0xf bound_ctrl:1
	v_cvt_pk_f32_fp8_e32 v[240:241], v166
	v_cvt_pk_f32_fp8_sdwa v[242:243], v166 src0_sel:WORD_1
	v_add_f32_dpp v235, v235, v235 row_half_mirror row_mask:0xf bank_mask:0xf bound_ctrl:1
	v_pk_fma_f32 v[204:205], v[244:245], v[56:57], v[204:205]
	v_pk_fma_f32 v[206:207], v[202:203], v[58:59], v[206:207]
	s_add_i32 s0, s1, 6
	s_cmp_lt_i32 s0, s2
	s_cselect_b64 vcc, -1, 0
	v_cvt_pk_f32_fp8_e32 v[244:245], v167
	v_cvt_pk_f32_fp8_sdwa v[202:203], v167 src0_sel:WORD_1
	v_cndmask_b32_e32 v228, v220, v235, vcc
	v_pk_fma_f32 v[204:205], v[240:241], v[60:61], v[204:205]
	v_pk_fma_f32 v[206:207], v[242:243], v[62:63], v[206:207]
	v_pk_fma_f32 v[204:205], v[244:245], v[64:65], v[204:205]
	v_pk_fma_f32 v[206:207], v[202:203], v[66:67], v[206:207]
	v_readlane_b32 s0, v135, 7
	s_lshl_b32 s0, s0, 10
	s_add_u32 s4, s8, s0
	s_addc_u32 s5, s9, 0
	global_load_dwordx4 v[164:167], v16, s[4:5]
	v_pk_add_f32 v[204:205], v[204:205], v[206:207]
	s_nop 0
	v_add_f32_e32 v221, v204, v205
	s_waitcnt vmcnt(15)
	v_cvt_pk_f32_fp8_e32 v[240:241], v168
	v_cvt_pk_f32_fp8_sdwa v[242:243], v168 src0_sel:WORD_1
	v_cvt_pk_f32_fp8_e32 v[244:245], v169
	v_cvt_pk_f32_fp8_sdwa v[202:203], v169 src0_sel:WORD_1
	v_add_f32_dpp v221, v221, v221 quad_perm:[1,0,3,2] row_mask:0xf bank_mask:0xf bound_ctrl:1
	v_pk_mul_f32 v[204:205], v[240:241], v[52:53]
	v_pk_mul_f32 v[206:207], v[242:243], v[54:55]
	v_add_f32_dpp v221, v221, v221 quad_perm:[2,3,0,1] row_mask:0xf bank_mask:0xf bound_ctrl:1
	v_cvt_pk_f32_fp8_e32 v[240:241], v170
	v_cvt_pk_f32_fp8_sdwa v[242:243], v170 src0_sel:WORD_1
	v_add_f32_dpp v221, v221, v221 row_half_mirror row_mask:0xf bank_mask:0xf bound_ctrl:1
	v_pk_fma_f32 v[204:205], v[244:245], v[56:57], v[204:205]
	v_pk_fma_f32 v[206:207], v[202:203], v[58:59], v[206:207]
	s_add_i32 s0, s1, 7
	s_cmp_lt_i32 s0, s2
	s_cselect_b64 vcc, -1, 0
	v_cvt_pk_f32_fp8_e32 v[244:245], v171
	v_cvt_pk_f32_fp8_sdwa v[202:203], v171 src0_sel:WORD_1
	v_cndmask_b32_e32 v229, v220, v221, vcc
	v_pk_fma_f32 v[204:205], v[240:241], v[60:61], v[204:205]
	v_pk_fma_f32 v[206:207], v[242:243], v[62:63], v[206:207]
	v_pk_fma_f32 v[204:205], v[244:245], v[64:65], v[204:205]
	v_pk_fma_f32 v[206:207], v[202:203], v[66:67], v[206:207]
	v_readlane_b32 s0, v135, 8
	s_lshl_b32 s0, s0, 10
	s_add_u32 s4, s8, s0
	s_addc_u32 s5, s9, 0
	global_load_dwordx4 v[168:171], v16, s[4:5]
	v_pk_add_f32 v[204:205], v[204:205], v[206:207]
	s_nop 0
	v_add_f32_e32 v235, v204, v205
	s_waitcnt vmcnt(15)
	v_cvt_pk_f32_fp8_e32 v[240:241], v172
	v_cvt_pk_f32_fp8_sdwa v[242:243], v172 src0_sel:WORD_1
	v_cvt_pk_f32_fp8_e32 v[244:245], v173
	v_cvt_pk_f32_fp8_sdwa v[202:203], v173 src0_sel:WORD_1
	v_add_f32_dpp v235, v235, v235 quad_perm:[1,0,3,2] row_mask:0xf bank_mask:0xf bound_ctrl:1
	v_pk_mul_f32 v[204:205], v[240:241], v[52:53]
	v_pk_mul_f32 v[206:207], v[242:243], v[54:55]
	v_add_f32_dpp v235, v235, v235 quad_perm:[2,3,0,1] row_mask:0xf bank_mask:0xf bound_ctrl:1
	v_cvt_pk_f32_fp8_e32 v[240:241], v174
	v_cvt_pk_f32_fp8_sdwa v[242:243], v174 src0_sel:WORD_1
	v_add_f32_dpp v235, v235, v235 row_half_mirror row_mask:0xf bank_mask:0xf bound_ctrl:1
	v_pk_fma_f32 v[204:205], v[244:245], v[56:57], v[204:205]
	v_pk_fma_f32 v[206:207], v[202:203], v[58:59], v[206:207]
	s_add_i32 s0, s1, 8
	s_cmp_lt_i32 s0, s2
	s_cselect_b64 vcc, -1, 0
	v_cvt_pk_f32_fp8_e32 v[244:245], v175
	v_cvt_pk_f32_fp8_sdwa v[202:203], v175 src0_sel:WORD_1
	v_cndmask_b32_e32 v230, v220, v235, vcc
	v_pk_fma_f32 v[204:205], v[240:241], v[60:61], v[204:205]
	v_pk_fma_f32 v[206:207], v[242:243], v[62:63], v[206:207]
	v_pk_fma_f32 v[204:205], v[244:245], v[64:65], v[204:205]
	v_pk_fma_f32 v[206:207], v[202:203], v[66:67], v[206:207]
	v_readlane_b32 s0, v135, 9
	s_lshl_b32 s0, s0, 10
	s_add_u32 s4, s8, s0
	s_addc_u32 s5, s9, 0
	global_load_dwordx4 v[172:175], v16, s[4:5]
	v_pk_add_f32 v[204:205], v[204:205], v[206:207]
	s_nop 0
	v_add_f32_e32 v221, v204, v205
	s_waitcnt vmcnt(15)
; DI float sum8(float v) { v += DPPF(v, 0xB1); v += DPPF(v, 0x4E); v += DPPF(v, 0x141); return v; }
; DI void topk_phase(const bf16_t* PROJ, const unsigned char* K8, const unsigned char* V8, const unsigned short* SC, bf16_t* ODSA, int c, char* smem, int bid, int nb) {
;     ...
;     const int mysel = sel[wid * 64 + lane];
; #pragma unroll 4
;     for (int jj = 0; jj < 64; ++jj) {
;       const int j = wid * 64 + jj;
;       {
;         const size_t ro = (size_t)__builtin_amdgcn_readlane(mysel, jj) * 1024 + lane * 16;
;         const uint4 a = *(const uint4*)(K8 + ro), vv = *(const uint4*)(V8 + ro);
;         const unsigned w[4] = {a.x, a.y, a.z, a.w}, u[4] = {vv.x, vv.y, vv.z, vv.w};
;         float da = 0.f;
; #pragma unroll
;         for (int i = 0; i < 4; ++i) {
;           const f32x2v lo = __builtin_amdgcn_cvt_pk_f32_fp8((int)w[i], false), hi = __builtin_amdgcn_cvt_pk_f32_fp8((int)w[i], true);
;           da += qv[4 * i] * lo[0] + qv[4 * i + 1] * lo[1] + qv[4 * i + 2] * hi[0] + qv[4 * i + 3] * hi[1];
;         }
;         da = sum8(da);
;         da = j < count ? da : -3e30f;
;         const float mn = fmaxf(m_run, da), al = __builtin_amdgcn_exp2f(m_run - mn), pp = __builtin_amdgcn_exp2f(da - mn);
;         m_run = mn; l_run = l_run * al + pp;
	v_cvt_pk_f32_fp8_e32 v[240:241], v176
	v_cvt_pk_f32_fp8_sdwa v[242:243], v176 src0_sel:WORD_1
	v_cvt_pk_f32_fp8_e32 v[244:245], v177
	v_cvt_pk_f32_fp8_sdwa v[202:203], v177 src0_sel:WORD_1
	v_add_f32_dpp v221, v221, v221 quad_perm:[1,0,3,2] row_mask:0xf bank_mask:0xf bound_ctrl:1
	v_pk_mul_f32 v[204:205], v[240:241], v[52:53]
	v_pk_mul_f32 v[206:207], v[242:243], v[54:55]
	v_add_f32_dpp v221, v221, v221 quad_perm:[2,3,0,1] row_mask:0xf bank_mask:0xf bound_ctrl:1
	v_cvt_pk_f32_fp8_e32 v[240:241], v178
	v_cvt_pk_f32_fp8_sdwa v[242:243], v178 src0_sel:WORD_1
	v_add_f32_dpp v221, v221, v221 row_half_mirror row_mask:0xf bank_mask:0xf bound_ctrl:1
	v_pk_fma_f32 v[204:205], v[244:245], v[56:57], v[204:205]
	v_pk_fma_f32 v[206:207], v[202:203], v[58:59], v[206:207]
	s_add_i32 s0, s1, 9
	s_cmp_lt_i32 s0, s2
	s_cselect_b64 vcc, -1, 0
	v_cvt_pk_f32_fp8_e32 v[244:245], v179
	v_cvt_pk_f32_fp8_sdwa v[202:203], v179 src0_sel:WORD_1
	v_cndmask_b32_e32 v231, v220, v221, vcc
	v_pk_fma_f32 v[204:205], v[240:241], v[60:61], v[204:205]
	v_pk_fma_f32 v[206:207], v[242:243], v[62:63], v[206:207]
	v_pk_fma_f32 v[204:205], v[244:245], v[64:65], v[204:205]
	v_pk_fma_f32 v[206:207], v[202:203], v[66:67], v[206:207]
	v_readlane_b32 s0, v135, 10
	s_lshl_b32 s0, s0, 10
	s_add_u32 s4, s8, s0
	s_addc_u32 s5, s9, 0
	global_load_dwordx4 v[176:179], v16, s[4:5]
	v_pk_add_f32 v[204:205], v[204:205], v[206:207]
	s_nop 0
	v_add_f32_e32 v235, v204, v205
	s_waitcnt vmcnt(15)
	v_cvt_pk_f32_fp8_e32 v[240:241], v180
	v_cvt_pk_f32_fp8_sdwa v[242:243], v180 src0_sel:WORD_1
	v_cvt_pk_f32_fp8_e32 v[244:245], v181
	v_cvt_pk_f32_fp8_sdwa v[202:203], v181 src0_sel:WORD_1
	v_add_f32_dpp v235, v235, v235 quad_perm:[1,0,3,2] row_mask:0xf bank_mask:0xf bound_ctrl:1
	v_pk_mul_f32 v[204:205], v[240:241], v[52:53]
	v_pk_mul_f32 v[206:207], v[242:243], v[54:55]
	v_add_f32_dpp v235, v235, v235 quad_perm:[2,3,0,1] row_mask:0xf bank_mask:0xf bound_ctrl:1
	v_cvt_pk_f32_fp8_e32 v[240:241], v182
	v_cvt_pk_f32_fp8_sdwa v[242:243], v182 src0_sel:WORD_1
	v_add_f32_dpp v235, v235, v235 row_half_mirror row_mask:0xf bank_mask:0xf bound_ctrl:1
	v_pk_fma_f32 v[204:205], v[244:245], v[56:57], v[204:205]
	v_pk_fma_f32 v[206:207], v[202:203], v[58:59], v[206:207]
	s_add_i32 s0, s1, 10
	s_cmp_lt_i32 s0, s2
	s_cselect_b64 vcc, -1, 0
	v_cvt_pk_f32_fp8_e32 v[244:245], v183
	v_cvt_pk_f32_fp8_sdwa v[202:203], v183 src0_sel:WORD_1
	v_cndmask_b32_e32 v232, v220, v235, vcc
	v_pk_fma_f32 v[204:205], v[240:241], v[60:61], v[204:205]
	v_pk_fma_f32 v[206:207], v[242:243], v[62:63], v[206:207]
	v_pk_fma_f32 v[204:205], v[244:245], v[64:65], v[204:205]
	v_pk_fma_f32 v[206:207], v[202:203], v[66:67], v[206:207]
	v_readlane_b32 s0, v135, 11
	s_lshl_b32 s0, s0, 10
	s_add_u32 s4, s8, s0
	s_addc_u32 s5, s9, 0
	global_load_dwordx4 v[180:183], v16, s[4:5]
	v_pk_add_f32 v[204:205], v[204:205], v[206:207]
	s_nop 0
	v_add_f32_e32 v221, v204, v205
	s_waitcnt vmcnt(15)
	v_cvt_pk_f32_fp8_e32 v[240:241], v186
	v_cvt_pk_f32_fp8_sdwa v[242:243], v186 src0_sel:WORD_1
	v_cvt_pk_f32_fp8_e32 v[244:245], v187
	v_cvt_pk_f32_fp8_sdwa v[202:203], v187 src0_sel:WORD_1
	v_add_f32_dpp v221, v221, v221 quad_perm:[1,0,3,2] row_mask:0xf bank_mask:0xf bound_ctrl:1
	v_pk_mul_f32 v[204:205], v[240:241], v[52:53]
	v_pk_mul_f32 v[206:207], v[242:243], v[54:55]
	v_add_f32_dpp v221, v221, v221 quad_perm:[2,3,0,1] row_mask:0xf bank_mask:0xf bound_ctrl:1
	v_cvt_pk_f32_fp8_e32 v[240:241], v188
	v_cvt_pk_f32_fp8_sdwa v[242:243], v188 src0_sel:WORD_1
	v_add_f32_dpp v221, v221, v221 row_half_mirror row_mask:0xf bank_mask:0xf bound_ctrl:1
	v_pk_fma_f32 v[204:205], v[244:245], v[56:57], v[204:205]
	v_pk_fma_f32 v[206:207], v[202:203], v[58:59], v[206:207]
	s_add_i32 s0, s1, 11
	s_cmp_lt_i32 s0, s2
	s_cselect_b64 vcc, -1, 0
	v_cvt_pk_f32_fp8_e32 v[244:245], v189
	v_cvt_pk_f32_fp8_sdwa v[202:203], v189 src0_sel:WORD_1
	v_cndmask_b32_e32 v233, v220, v221, vcc
	v_pk_fma_f32 v[204:205], v[240:241], v[60:61], v[204:205]
	v_pk_fma_f32 v[206:207], v[242:243], v[62:63], v[206:207]
	v_pk_fma_f32 v[204:205], v[244:245], v[64:65], v[204:205]
	v_pk_fma_f32 v[206:207], v[202:203], v[66:67], v[206:207]
	v_readlane_b32 s0, v135, 12
	s_lshl_b32 s0, s0, 10
	s_add_u32 s4, s8, s0
	s_addc_u32 s5, s9, 0
	global_load_dwordx4 v[186:189], v16, s[4:5]
	v_pk_add_f32 v[204:205], v[204:205], v[206:207]
	s_nop 0
	v_add_f32_e32 v235, v204, v205
	s_waitcnt vmcnt(15)
	v_cvt_pk_f32_fp8_e32 v[240:241], v190
	v_cvt_pk_f32_fp8_sdwa v[242:243], v190 src0_sel:WORD_1
	v_cvt_pk_f32_fp8_e32 v[244:245], v191
	v_cvt_pk_f32_fp8_sdwa v[202:203], v191 src0_sel:WORD_1
	v_add_f32_dpp v235, v235, v235 quad_perm:[1,0,3,2] row_mask:0xf bank_mask:0xf bound_ctrl:1
	v_pk_mul_f32 v[204:205], v[240:241], v[52:53]
	v_pk_mul_f32 v[206:207], v[242:243], v[54:55]
	v_add_f32_dpp v235, v235, v235 quad_perm:[2,3,0,1] row_mask:0xf bank_mask:0xf bound_ctrl:1
	v_cvt_pk_f32_fp8_e32 v[240:241], v192
	v_cvt_pk_f32_fp8_sdwa v[242:243], v192 src0_sel:WORD_1
	v_add_f32_dpp v235, v235, v235 row_half_mirror row_mask:0xf bank_mask:0xf bound_ctrl:1
	v_pk_fma_f32 v[204:205], v[244:245], v[56:57], v[204:205]
	v_pk_fma_f32 v[206:207], v[202:203], v[58:59], v[206:207]
	s_add_i32 s0, s1, 12
	s_cmp_lt_i32 s0, s2
	s_cselect_b64 vcc, -1, 0
	v_cvt_pk_f32_fp8_e32 v[244:245], v193
	v_cvt_pk_f32_fp8_sdwa v[202:203], v193 src0_sel:WORD_1
	v_cndmask_b32_e32 v236, v220, v235, vcc
	v_pk_fma_f32 v[204:205], v[240:241], v[60:61], v[204:205]
	v_pk_fma_f32 v[206:207], v[242:243], v[62:63], v[206:207]
	v_pk_fma_f32 v[204:205], v[244:245], v[64:65], v[204:205]
	v_pk_fma_f32 v[206:207], v[202:203], v[66:67], v[206:207]
	v_readlane_b32 s0, v135, 13
	s_lshl_b32 s0, s0, 10
	s_add_u32 s4, s8, s0
	s_addc_u32 s5, s9, 0
	global_load_dwordx4 v[190:193], v16, s[4:5]
	v_pk_add_f32 v[204:205], v[204:205], v[206:207]
	s_nop 0
	v_add_f32_e32 v221, v204, v205
	s_waitcnt vmcnt(15)
; DI float sum8(float v) { v += DPPF(v, 0xB1); v += DPPF(v, 0x4E); v += DPPF(v, 0x141); return v; }
; DI void topk_phase(const bf16_t* PROJ, const unsigned char* K8, const unsigned char* V8, const unsigned short* SC, bf16_t* ODSA, int c, char* smem, int bid, int nb) {
;     ...
;     const int mysel = sel[wid * 64 + lane];
; #pragma unroll 4
;     for (int jj = 0; jj < 64; ++jj) {
;       const int j = wid * 64 + jj;
;       {
;         const size_t ro = (size_t)__builtin_amdgcn_readlane(mysel, jj) * 1024 + lane * 16;
;         const uint4 a = *(const uint4*)(K8 + ro), vv = *(const uint4*)(V8 + ro);
;         const unsigned w[4] = {a.x, a.y, a.z, a.w}, u[4] = {vv.x, vv.y, vv.z, vv.w};
;         float da = 0.f;
; #pragma unroll
;         for (int i = 0; i < 4; ++i) {
;           const f32x2v lo = __builtin_amdgcn_cvt_pk_f32_fp8((int)w[i], false), hi = __builtin_amdgcn_cvt_pk_f32_fp8((int)w[i], true);
;           da += qv[4 * i] * lo[0] + qv[4 * i + 1] * lo[1] + qv[4 * i + 2] * hi[0] + qv[4 * i + 3] * hi[1];
;         }
;         da = sum8(da);
;         da = j < count ? da : -3e30f;
;         const float mn = fmaxf(m_run, da), al = __builtin_amdgcn_exp2f(m_run - mn), pp = __builtin_amdgcn_exp2f(da - mn);
;         m_run = mn; l_run = l_run * al + pp;
; #pragma unroll
;         for (int i = 0; i < 4; ++i) {
;           const f32x2v lo = __builtin_amdgcn_cvt_pk_f32_fp8((int)u[i], false), hi = __builtin_amdgcn_cvt_pk_f32_fp8((int)u[i], true);
;           ov[4 * i] = ov[4 * i] * al + pp * lo[0]; ov[4 * i + 1] = ov[4 * i + 1] * al + pp * lo[1];
;           ov[4 * i + 2] = ov[4 * i + 2] * al + pp * hi[0]; ov[4 * i + 3] = ov[4 * i + 3] * al + pp * hi[1];
;         }
	v_cvt_pk_f32_fp8_e32 v[240:241], v194
	v_cvt_pk_f32_fp8_sdwa v[242:243], v194 src0_sel:WORD_1
	v_cvt_pk_f32_fp8_e32 v[244:245], v195
	v_cvt_pk_f32_fp8_sdwa v[202:203], v195 src0_sel:WORD_1
	v_add_f32_dpp v221, v221, v221 quad_perm:[1,0,3,2] row_mask:0xf bank_mask:0xf bound_ctrl:1
	v_pk_mul_f32 v[204:205], v[240:241], v[52:53]
	v_pk_mul_f32 v[206:207], v[242:243], v[54:55]
	v_add_f32_dpp v221, v221, v221 quad_perm:[2,3,0,1] row_mask:0xf bank_mask:0xf bound_ctrl:1
	v_cvt_pk_f32_fp8_e32 v[240:241], v196
	v_cvt_pk_f32_fp8_sdwa v[242:243], v196 src0_sel:WORD_1
	v_add_f32_dpp v221, v221, v221 row_half_mirror row_mask:0xf bank_mask:0xf bound_ctrl:1
	v_pk_fma_f32 v[204:205], v[244:245], v[56:57], v[204:205]
	v_pk_fma_f32 v[206:207], v[202:203], v[58:59], v[206:207]
	s_add_i32 s0, s1, 13
	s_cmp_lt_i32 s0, s2
	s_cselect_b64 vcc, -1, 0
	v_cvt_pk_f32_fp8_e32 v[244:245], v197
	v_cvt_pk_f32_fp8_sdwa v[202:203], v197 src0_sel:WORD_1
	v_cndmask_b32_e32 v237, v220, v221, vcc
	v_pk_fma_f32 v[204:205], v[240:241], v[60:61], v[204:205]
	v_pk_fma_f32 v[206:207], v[242:243], v[62:63], v[206:207]
	v_pk_fma_f32 v[204:205], v[244:245], v[64:65], v[204:205]
	v_pk_fma_f32 v[206:207], v[202:203], v[66:67], v[206:207]
	v_readlane_b32 s0, v135, 14
	s_lshl_b32 s0, s0, 10
	s_add_u32 s4, s8, s0
	s_addc_u32 s5, s9, 0
	global_load_dwordx4 v[194:197], v16, s[4:5]
	v_pk_add_f32 v[204:205], v[204:205], v[206:207]
	s_nop 0
	v_add_f32_e32 v235, v204, v205
	s_waitcnt vmcnt(15)
	v_cvt_pk_f32_fp8_e32 v[240:241], v198
	v_cvt_pk_f32_fp8_sdwa v[242:243], v198 src0_sel:WORD_1
	v_cvt_pk_f32_fp8_e32 v[244:245], v199
	v_cvt_pk_f32_fp8_sdwa v[202:203], v199 src0_sel:WORD_1
	v_add_f32_dpp v235, v235, v235 quad_perm:[1,0,3,2] row_mask:0xf bank_mask:0xf bound_ctrl:1
	v_pk_mul_f32 v[204:205], v[240:241], v[52:53]
	v_pk_mul_f32 v[206:207], v[242:243], v[54:55]
	v_add_f32_dpp v235, v235, v235 quad_perm:[2,3,0,1] row_mask:0xf bank_mask:0xf bound_ctrl:1
	v_cvt_pk_f32_fp8_e32 v[240:241], v200
	v_cvt_pk_f32_fp8_sdwa v[242:243], v200 src0_sel:WORD_1
	v_add_f32_dpp v235, v235, v235 row_half_mirror row_mask:0xf bank_mask:0xf bound_ctrl:1
	v_pk_fma_f32 v[204:205], v[244:245], v[56:57], v[204:205]
	v_pk_fma_f32 v[206:207], v[202:203], v[58:59], v[206:207]
	s_add_i32 s0, s1, 14
	s_cmp_lt_i32 s0, s2
	s_cselect_b64 vcc, -1, 0
	v_cvt_pk_f32_fp8_e32 v[244:245], v201
	v_cvt_pk_f32_fp8_sdwa v[202:203], v201 src0_sel:WORD_1
	v_cndmask_b32_e32 v238, v220, v235, vcc
	v_pk_fma_f32 v[204:205], v[240:241], v[60:61], v[204:205]
	v_pk_fma_f32 v[206:207], v[242:243], v[62:63], v[206:207]
	v_pk_fma_f32 v[204:205], v[244:245], v[64:65], v[204:205]
	v_pk_fma_f32 v[206:207], v[202:203], v[66:67], v[206:207]
	v_readlane_b32 s0, v135, 15
	s_lshl_b32 s0, s0, 10
	s_add_u32 s4, s8, s0
	s_addc_u32 s5, s9, 0
	global_load_dwordx4 v[198:201], v16, s[4:5]
	v_pk_add_f32 v[204:205], v[204:205], v[206:207]
	s_nop 0
	v_add_f32_e32 v221, v204, v205
	s_nop 1
	v_add_f32_dpp v221, v221, v221 quad_perm:[1,0,3,2] row_mask:0xf bank_mask:0xf bound_ctrl:1
	s_nop 1
	v_add_f32_dpp v221, v221, v221 quad_perm:[2,3,0,1] row_mask:0xf bank_mask:0xf bound_ctrl:1
	s_nop 1
	v_add_f32_dpp v221, v221, v221 row_half_mirror row_mask:0xf bank_mask:0xf bound_ctrl:1
	s_add_i32 s0, s1, 15
	s_cmp_lt_i32 s0, s2
	s_cselect_b64 vcc, -1, 0
	s_nop 1
	v_cndmask_b32_e32 v239, v220, v221, vcc
	v_max3_f32 v224, v210, v211, v212
	v_max3_f32 v224, v224, v213, v226
	v_max3_f32 v224, v224, v227, v228
	v_max3_f32 v224, v224, v229, v230
	v_max3_f32 v224, v224, v231, v232
	v_max3_f32 v224, v224, v233, v236
	v_max3_f32 v224, v224, v237, v238
	v_max_f32_e32 v224, v224, v239
	v_max_f32_e32 v216, v216, v224
	v_sub_f32_e32 v210, v210, v216
	v_exp_f32_e32 v210, v210
	s_waitcnt vmcnt(15)
	v_cvt_pk_f32_fp8_e32 v[240:241], v136
	v_cvt_pk_f32_fp8_sdwa v[242:243], v136 src0_sel:WORD_1
	v_cvt_pk_f32_fp8_e32 v[244:245], v137
	v_pk_fma_f32 v[12:13], v[240:241], v[210:211], v[12:13] op_sel_hi:[1,0,1]
	v_cvt_pk_f32_fp8_sdwa v[240:241], v137 src0_sel:WORD_1
	v_pk_fma_f32 v[14:15], v[242:243], v[210:211], v[14:15] op_sel_hi:[1,0,1]
	v_cvt_pk_f32_fp8_e32 v[242:243], v138
	v_sub_f32_e32 v211, v211, v216
	v_pk_fma_f32 v[8:9], v[244:245], v[210:211], v[8:9] op_sel_hi:[1,0,1]
	v_cvt_pk_f32_fp8_sdwa v[244:245], v138 src0_sel:WORD_1
	v_pk_fma_f32 v[10:11], v[240:241], v[210:211], v[10:11] op_sel_hi:[1,0,1]
	v_cvt_pk_f32_fp8_e32 v[240:241], v139
	v_exp_f32_e32 v211, v211
	v_pk_fma_f32 v[4:5], v[242:243], v[210:211], v[4:5] op_sel_hi:[1,0,1]
	v_cvt_pk_f32_fp8_sdwa v[242:243], v139 src0_sel:WORD_1
	v_pk_fma_f32 v[6:7], v[244:245], v[210:211], v[6:7] op_sel_hi:[1,0,1]
	v_add_f32_e32 v215, v215, v210
	v_pk_fma_f32 v[0:1], v[240:241], v[210:211], v[0:1] op_sel_hi:[1,0,1]
	v_pk_fma_f32 v[2:3], v[242:243], v[210:211], v[2:3] op_sel_hi:[1,0,1]
	v_readlane_b32 s0, v135, 16
	s_lshl_b32 s0, s0, 10
	s_add_u32 s4, s6, s0
	s_addc_u32 s5, s7, 0
	global_load_dwordx4 v[136:139], v16, s[4:5]
	s_waitcnt vmcnt(15)
	v_cvt_pk_f32_fp8_e32 v[240:241], v140
	v_cvt_pk_f32_fp8_sdwa v[242:243], v140 src0_sel:WORD_1
	v_cvt_pk_f32_fp8_e32 v[244:245], v141
	v_pk_fma_f32 v[12:13], v[240:241], v[210:211], v[12:13] op_sel:[0,1,0]
	v_cvt_pk_f32_fp8_sdwa v[240:241], v141 src0_sel:WORD_1
	v_pk_fma_f32 v[14:15], v[242:243], v[210:211], v[14:15] op_sel:[0,1,0]
	v_cvt_pk_f32_fp8_e32 v[242:243], v142
	v_sub_f32_e32 v212, v212, v216
	v_pk_fma_f32 v[8:9], v[244:245], v[210:211], v[8:9] op_sel:[0,1,0]
	v_cvt_pk_f32_fp8_sdwa v[244:245], v142 src0_sel:WORD_1
	v_pk_fma_f32 v[10:11], v[240:241], v[210:211], v[10:11] op_sel:[0,1,0]
	v_cvt_pk_f32_fp8_e32 v[240:241], v143
	v_exp_f32_e32 v212, v212
	v_pk_fma_f32 v[4:5], v[242:243], v[210:211], v[4:5] op_sel:[0,1,0]
	v_cvt_pk_f32_fp8_sdwa v[242:243], v143 src0_sel:WORD_1
	v_pk_fma_f32 v[6:7], v[244:245], v[210:211], v[6:7] op_sel:[0,1,0]
	v_add_f32_e32 v215, v215, v211
	v_pk_fma_f32 v[0:1], v[240:241], v[210:211], v[0:1] op_sel:[0,1,0]
	v_pk_fma_f32 v[2:3], v[242:243], v[210:211], v[2:3] op_sel:[0,1,0]
	v_readlane_b32 s0, v135, 17
	s_lshl_b32 s0, s0, 10
	s_add_u32 s4, s6, s0
	s_addc_u32 s5, s7, 0
	global_load_dwordx4 v[140:143], v16, s[4:5]
	s_waitcnt vmcnt(15)
; DI void topk_phase(const bf16_t* PROJ, const unsigned char* K8, const unsigned char* V8, const unsigned short* SC, bf16_t* ODSA, int c, char* smem, int bid, int nb) {
;     ...
;         const float mn = fmaxf(m_run, da), al = __builtin_amdgcn_exp2f(m_run - mn), pp = __builtin_amdgcn_exp2f(da - mn);
;         m_run = mn; l_run = l_run * al + pp;
; #pragma unroll
;         for (int i = 0; i < 4; ++i) {
;           const f32x2v lo = __builtin_amdgcn_cvt_pk_f32_fp8((int)u[i], false), hi = __builtin_amdgcn_cvt_pk_f32_fp8((int)u[i], true);
;           ov[4 * i] = ov[4 * i] * al + pp * lo[0]; ov[4 * i + 1] = ov[4 * i + 1] * al + pp * lo[1];
;           ov[4 * i + 2] = ov[4 * i + 2] * al + pp * hi[0]; ov[4 * i + 3] = ov[4 * i + 3] * al + pp * hi[1];
;         }
	v_cvt_pk_f32_fp8_e32 v[240:241], v144
	v_cvt_pk_f32_fp8_sdwa v[242:243], v144 src0_sel:WORD_1
	v_cvt_pk_f32_fp8_e32 v[244:245], v145
	v_pk_fma_f32 v[12:13], v[240:241], v[212:213], v[12:13] op_sel_hi:[1,0,1]
	v_cvt_pk_f32_fp8_sdwa v[240:241], v145 src0_sel:WORD_1
	v_pk_fma_f32 v[14:15], v[242:243], v[212:213], v[14:15] op_sel_hi:[1,0,1]
	v_cvt_pk_f32_fp8_e32 v[242:243], v146
	v_sub_f32_e32 v213, v213, v216
	v_pk_fma_f32 v[8:9], v[244:245], v[212:213], v[8:9] op_sel_hi:[1,0,1]
	v_cvt_pk_f32_fp8_sdwa v[244:245], v146 src0_sel:WORD_1
	v_pk_fma_f32 v[10:11], v[240:241], v[212:213], v[10:11] op_sel_hi:[1,0,1]
	v_cvt_pk_f32_fp8_e32 v[240:241], v147
	v_exp_f32_e32 v213, v213
	v_pk_fma_f32 v[4:5], v[242:243], v[212:213], v[4:5] op_sel_hi:[1,0,1]
	v_cvt_pk_f32_fp8_sdwa v[242:243], v147 src0_sel:WORD_1
	v_pk_fma_f32 v[6:7], v[244:245], v[212:213], v[6:7] op_sel_hi:[1,0,1]
	v_add_f32_e32 v215, v215, v212
	v_pk_fma_f32 v[0:1], v[240:241], v[212:213], v[0:1] op_sel_hi:[1,0,1]
	v_pk_fma_f32 v[2:3], v[242:243], v[212:213], v[2:3] op_sel_hi:[1,0,1]
	v_readlane_b32 s0, v135, 18
	s_lshl_b32 s0, s0, 10
	s_add_u32 s4, s6, s0
	s_addc_u32 s5, s7, 0
	global_load_dwordx4 v[144:147], v16, s[4:5]
	s_waitcnt vmcnt(15)
	v_cvt_pk_f32_fp8_e32 v[240:241], v148
	v_cvt_pk_f32_fp8_sdwa v[242:243], v148 src0_sel:WORD_1
	v_cvt_pk_f32_fp8_e32 v[244:245], v149
	v_pk_fma_f32 v[12:13], v[240:241], v[212:213], v[12:13] op_sel:[0,1,0]
	v_cvt_pk_f32_fp8_sdwa v[240:241], v149 src0_sel:WORD_1
	v_pk_fma_f32 v[14:15], v[242:243], v[212:213], v[14:15] op_sel:[0,1,0]
	v_cvt_pk_f32_fp8_e32 v[242:243], v150
	v_sub_f32_e32 v226, v226, v216
	v_pk_fma_f32 v[8:9], v[244:245], v[212:213], v[8:9] op_sel:[0,1,0]
	v_cvt_pk_f32_fp8_sdwa v[244:245], v150 src0_sel:WORD_1
	v_pk_fma_f32 v[10:11], v[240:241], v[212:213], v[10:11] op_sel:[0,1,0]
	v_cvt_pk_f32_fp8_e32 v[240:241], v151
	v_exp_f32_e32 v226, v226
	v_pk_fma_f32 v[4:5], v[242:243], v[212:213], v[4:5] op_sel:[0,1,0]
	v_cvt_pk_f32_fp8_sdwa v[242:243], v151 src0_sel:WORD_1
	v_pk_fma_f32 v[6:7], v[244:245], v[212:213], v[6:7] op_sel:[0,1,0]
	v_add_f32_e32 v215, v215, v213
	v_pk_fma_f32 v[0:1], v[240:241], v[212:213], v[0:1] op_sel:[0,1,0]
	v_pk_fma_f32 v[2:3], v[242:243], v[212:213], v[2:3] op_sel:[0,1,0]
	v_readlane_b32 s0, v135, 19
	s_lshl_b32 s0, s0, 10
	s_add_u32 s4, s6, s0
	s_addc_u32 s5, s7, 0
	global_load_dwordx4 v[148:151], v16, s[4:5]
	s_waitcnt vmcnt(15)
	v_cvt_pk_f32_fp8_e32 v[240:241], v152
	v_cvt_pk_f32_fp8_sdwa v[242:243], v152 src0_sel:WORD_1
	v_cvt_pk_f32_fp8_e32 v[244:245], v153
	v_pk_fma_f32 v[12:13], v[240:241], v[226:227], v[12:13] op_sel_hi:[1,0,1]
	v_cvt_pk_f32_fp8_sdwa v[240:241], v153 src0_sel:WORD_1
	v_pk_fma_f32 v[14:15], v[242:243], v[226:227], v[14:15] op_sel_hi:[1,0,1]
	v_cvt_pk_f32_fp8_e32 v[242:243], v154
	v_sub_f32_e32 v227, v227, v216
	v_pk_fma_f32 v[8:9], v[244:245], v[226:227], v[8:9] op_sel_hi:[1,0,1]
	v_cvt_pk_f32_fp8_sdwa v[244:245], v154 src0_sel:WORD_1
	v_pk_fma_f32 v[10:11], v[240:241], v[226:227], v[10:11] op_sel_hi:[1,0,1]
	v_cvt_pk_f32_fp8_e32 v[240:241], v155
	v_exp_f32_e32 v227, v227
	v_pk_fma_f32 v[4:5], v[242:243], v[226:227], v[4:5] op_sel_hi:[1,0,1]
	v_cvt_pk_f32_fp8_sdwa v[242:243], v155 src0_sel:WORD_1
	v_pk_fma_f32 v[6:7], v[244:245], v[226:227], v[6:7] op_sel_hi:[1,0,1]
	v_add_f32_e32 v215, v215, v226
	v_pk_fma_f32 v[0:1], v[240:241], v[226:227], v[0:1] op_sel_hi:[1,0,1]
	v_pk_fma_f32 v[2:3], v[242:243], v[226:227], v[2:3] op_sel_hi:[1,0,1]
	v_readlane_b32 s0, v135, 20
	s_lshl_b32 s0, s0, 10
	s_add_u32 s4, s6, s0
	s_addc_u32 s5, s7, 0
	global_load_dwordx4 v[152:155], v16, s[4:5]
	s_waitcnt vmcnt(15)
	v_cvt_pk_f32_fp8_e32 v[240:241], v156
	v_cvt_pk_f32_fp8_sdwa v[242:243], v156 src0_sel:WORD_1
	v_cvt_pk_f32_fp8_e32 v[244:245], v157
	v_pk_fma_f32 v[12:13], v[240:241], v[226:227], v[12:13] op_sel:[0,1,0]
	v_cvt_pk_f32_fp8_sdwa v[240:241], v157 src0_sel:WORD_1
	v_pk_fma_f32 v[14:15], v[242:243], v[226:227], v[14:15] op_sel:[0,1,0]
	v_cvt_pk_f32_fp8_e32 v[242:243], v158
	v_sub_f32_e32 v228, v228, v216
	v_pk_fma_f32 v[8:9], v[244:245], v[226:227], v[8:9] op_sel:[0,1,0]
	v_cvt_pk_f32_fp8_sdwa v[244:245], v158 src0_sel:WORD_1
	v_pk_fma_f32 v[10:11], v[240:241], v[226:227], v[10:11] op_sel:[0,1,0]
	v_cvt_pk_f32_fp8_e32 v[240:241], v159
	v_exp_f32_e32 v228, v228
	v_pk_fma_f32 v[4:5], v[242:243], v[226:227], v[4:5] op_sel:[0,1,0]
	v_cvt_pk_f32_fp8_sdwa v[242:243], v159 src0_sel:WORD_1
	v_pk_fma_f32 v[6:7], v[244:245], v[226:227], v[6:7] op_sel:[0,1,0]
	v_add_f32_e32 v215, v215, v227
	v_pk_fma_f32 v[0:1], v[240:241], v[226:227], v[0:1] op_sel:[0,1,0]
	v_pk_fma_f32 v[2:3], v[242:243], v[226:227], v[2:3] op_sel:[0,1,0]
	v_readlane_b32 s0, v135, 21
	s_lshl_b32 s0, s0, 10
	s_add_u32 s4, s6, s0
	s_addc_u32 s5, s7, 0
	global_load_dwordx4 v[156:159], v16, s[4:5]
	s_waitcnt vmcnt(15)
	v_cvt_pk_f32_fp8_e32 v[240:241], v160
	v_cvt_pk_f32_fp8_sdwa v[242:243], v160 src0_sel:WORD_1
	v_cvt_pk_f32_fp8_e32 v[244:245], v161
	v_pk_fma_f32 v[12:13], v[240:241], v[228:229], v[12:13] op_sel_hi:[1,0,1]
	v_cvt_pk_f32_fp8_sdwa v[240:241], v161 src0_sel:WORD_1
	v_pk_fma_f32 v[14:15], v[242:243], v[228:229], v[14:15] op_sel_hi:[1,0,1]
	v_cvt_pk_f32_fp8_e32 v[242:243], v162
	v_sub_f32_e32 v229, v229, v216
	v_pk_fma_f32 v[8:9], v[244:245], v[228:229], v[8:9] op_sel_hi:[1,0,1]
	v_cvt_pk_f32_fp8_sdwa v[244:245], v162 src0_sel:WORD_1
	v_pk_fma_f32 v[10:11], v[240:241], v[228:229], v[10:11] op_sel_hi:[1,0,1]
	v_cvt_pk_f32_fp8_e32 v[240:241], v163
	v_exp_f32_e32 v229, v229
	v_pk_fma_f32 v[4:5], v[242:243], v[228:229], v[4:5] op_sel_hi:[1,0,1]
	v_cvt_pk_f32_fp8_sdwa v[242:243], v163 src0_sel:WORD_1
	v_pk_fma_f32 v[6:7], v[244:245], v[228:229], v[6:7] op_sel_hi:[1,0,1]
	v_add_f32_e32 v215, v215, v228
	v_pk_fma_f32 v[0:1], v[240:241], v[228:229], v[0:1] op_sel_hi:[1,0,1]
	v_pk_fma_f32 v[2:3], v[242:243], v[228:229], v[2:3] op_sel_hi:[1,0,1]
	v_readlane_b32 s0, v135, 22
	s_lshl_b32 s0, s0, 10
	s_add_u32 s4, s6, s0
	s_addc_u32 s5, s7, 0
	global_load_dwordx4 v[160:163], v16, s[4:5]
	s_waitcnt vmcnt(15)
; DI void topk_phase(const bf16_t* PROJ, const unsigned char* K8, const unsigned char* V8, const unsigned short* SC, bf16_t* ODSA, int c, char* smem, int bid, int nb) {
;     ...
;         const float mn = fmaxf(m_run, da), al = __builtin_amdgcn_exp2f(m_run - mn), pp = __builtin_amdgcn_exp2f(da - mn);
;         m_run = mn; l_run = l_run * al + pp;
; #pragma unroll
;         for (int i = 0; i < 4; ++i) {
;           const f32x2v lo = __builtin_amdgcn_cvt_pk_f32_fp8((int)u[i], false), hi = __builtin_amdgcn_cvt_pk_f32_fp8((int)u[i], true);
;           ov[4 * i] = ov[4 * i] * al + pp * lo[0]; ov[4 * i + 1] = ov[4 * i + 1] * al + pp * lo[1];
;           ov[4 * i + 2] = ov[4 * i + 2] * al + pp * hi[0]; ov[4 * i + 3] = ov[4 * i + 3] * al + pp * hi[1];
;         }
	v_cvt_pk_f32_fp8_e32 v[240:241], v164
	v_cvt_pk_f32_fp8_sdwa v[242:243], v164 src0_sel:WORD_1
	v_cvt_pk_f32_fp8_e32 v[244:245], v165
	v_pk_fma_f32 v[12:13], v[240:241], v[228:229], v[12:13] op_sel:[0,1,0]
	v_cvt_pk_f32_fp8_sdwa v[240:241], v165 src0_sel:WORD_1
	v_pk_fma_f32 v[14:15], v[242:243], v[228:229], v[14:15] op_sel:[0,1,0]
	v_cvt_pk_f32_fp8_e32 v[242:243], v166
	v_sub_f32_e32 v230, v230, v216
	v_pk_fma_f32 v[8:9], v[244:245], v[228:229], v[8:9] op_sel:[0,1,0]
	v_cvt_pk_f32_fp8_sdwa v[244:245], v166 src0_sel:WORD_1
	v_pk_fma_f32 v[10:11], v[240:241], v[228:229], v[10:11] op_sel:[0,1,0]
	v_cvt_pk_f32_fp8_e32 v[240:241], v167
	v_exp_f32_e32 v230, v230
	v_pk_fma_f32 v[4:5], v[242:243], v[228:229], v[4:5] op_sel:[0,1,0]
	v_cvt_pk_f32_fp8_sdwa v[242:243], v167 src0_sel:WORD_1
	v_pk_fma_f32 v[6:7], v[244:245], v[228:229], v[6:7] op_sel:[0,1,0]
	v_add_f32_e32 v215, v215, v229
	v_pk_fma_f32 v[0:1], v[240:241], v[228:229], v[0:1] op_sel:[0,1,0]
	v_pk_fma_f32 v[2:3], v[242:243], v[228:229], v[2:3] op_sel:[0,1,0]
	v_readlane_b32 s0, v135, 23
	s_lshl_b32 s0, s0, 10
	s_add_u32 s4, s6, s0
	s_addc_u32 s5, s7, 0
	global_load_dwordx4 v[164:167], v16, s[4:5]
	s_waitcnt vmcnt(15)
	v_cvt_pk_f32_fp8_e32 v[240:241], v168
	v_cvt_pk_f32_fp8_sdwa v[242:243], v168 src0_sel:WORD_1
	v_cvt_pk_f32_fp8_e32 v[244:245], v169
	v_pk_fma_f32 v[12:13], v[240:241], v[230:231], v[12:13] op_sel_hi:[1,0,1]
	v_cvt_pk_f32_fp8_sdwa v[240:241], v169 src0_sel:WORD_1
	v_pk_fma_f32 v[14:15], v[242:243], v[230:231], v[14:15] op_sel_hi:[1,0,1]
	v_cvt_pk_f32_fp8_e32 v[242:243], v170
	v_sub_f32_e32 v231, v231, v216
	v_pk_fma_f32 v[8:9], v[244:245], v[230:231], v[8:9] op_sel_hi:[1,0,1]
	v_cvt_pk_f32_fp8_sdwa v[244:245], v170 src0_sel:WORD_1
	v_pk_fma_f32 v[10:11], v[240:241], v[230:231], v[10:11] op_sel_hi:[1,0,1]
	v_cvt_pk_f32_fp8_e32 v[240:241], v171
	v_exp_f32_e32 v231, v231
	v_pk_fma_f32 v[4:5], v[242:243], v[230:231], v[4:5] op_sel_hi:[1,0,1]
	v_cvt_pk_f32_fp8_sdwa v[242:243], v171 src0_sel:WORD_1
	v_pk_fma_f32 v[6:7], v[244:245], v[230:231], v[6:7] op_sel_hi:[1,0,1]
	v_add_f32_e32 v215, v215, v230
	v_pk_fma_f32 v[0:1], v[240:241], v[230:231], v[0:1] op_sel_hi:[1,0,1]
	v_pk_fma_f32 v[2:3], v[242:243], v[230:231], v[2:3] op_sel_hi:[1,0,1]
	v_readlane_b32 s0, v135, 24
	s_lshl_b32 s0, s0, 10
	s_add_u32 s4, s6, s0
	s_addc_u32 s5, s7, 0
	global_load_dwordx4 v[168:171], v16, s[4:5]
	s_waitcnt vmcnt(15)
	v_cvt_pk_f32_fp8_e32 v[240:241], v172
	v_cvt_pk_f32_fp8_sdwa v[242:243], v172 src0_sel:WORD_1
	v_cvt_pk_f32_fp8_e32 v[244:245], v173
	v_pk_fma_f32 v[12:13], v[240:241], v[230:231], v[12:13] op_sel:[0,1,0]
	v_cvt_pk_f32_fp8_sdwa v[240:241], v173 src0_sel:WORD_1
	v_pk_fma_f32 v[14:15], v[242:243], v[230:231], v[14:15] op_sel:[0,1,0]
	v_cvt_pk_f32_fp8_e32 v[242:243], v174
	v_sub_f32_e32 v232, v232, v216
	v_pk_fma_f32 v[8:9], v[244:245], v[230:231], v[8:9] op_sel:[0,1,0]
	v_cvt_pk_f32_fp8_sdwa v[244:245], v174 src0_sel:WORD_1
	v_pk_fma_f32 v[10:11], v[240:241], v[230:231], v[10:11] op_sel:[0,1,0]
	v_cvt_pk_f32_fp8_e32 v[240:241], v175
	v_exp_f32_e32 v232, v232
	v_pk_fma_f32 v[4:5], v[242:243], v[230:231], v[4:5] op_sel:[0,1,0]
	v_cvt_pk_f32_fp8_sdwa v[242:243], v175 src0_sel:WORD_1
	v_pk_fma_f32 v[6:7], v[244:245], v[230:231], v[6:7] op_sel:[0,1,0]
	v_add_f32_e32 v215, v215, v231
	v_pk_fma_f32 v[0:1], v[240:241], v[230:231], v[0:1] op_sel:[0,1,0]
	v_pk_fma_f32 v[2:3], v[242:243], v[230:231], v[2:3] op_sel:[0,1,0]
	v_readlane_b32 s0, v135, 25
	s_lshl_b32 s0, s0, 10
	s_add_u32 s4, s6, s0
	s_addc_u32 s5, s7, 0
	global_load_dwordx4 v[172:175], v16, s[4:5]
	s_waitcnt vmcnt(15)
	v_cvt_pk_f32_fp8_e32 v[240:241], v176
	v_cvt_pk_f32_fp8_sdwa v[242:243], v176 src0_sel:WORD_1
	v_cvt_pk_f32_fp8_e32 v[244:245], v177
	v_pk_fma_f32 v[12:13], v[240:241], v[232:233], v[12:13] op_sel_hi:[1,0,1]
	v_cvt_pk_f32_fp8_sdwa v[240:241], v177 src0_sel:WORD_1
	v_pk_fma_f32 v[14:15], v[242:243], v[232:233], v[14:15] op_sel_hi:[1,0,1]
	v_cvt_pk_f32_fp8_e32 v[242:243], v178
	v_sub_f32_e32 v233, v233, v216
	v_pk_fma_f32 v[8:9], v[244:245], v[232:233], v[8:9] op_sel_hi:[1,0,1]
	v_cvt_pk_f32_fp8_sdwa v[244:245], v178 src0_sel:WORD_1
	v_pk_fma_f32 v[10:11], v[240:241], v[232:233], v[10:11] op_sel_hi:[1,0,1]
	v_cvt_pk_f32_fp8_e32 v[240:241], v179
	v_exp_f32_e32 v233, v233
	v_pk_fma_f32 v[4:5], v[242:243], v[232:233], v[4:5] op_sel_hi:[1,0,1]
	v_cvt_pk_f32_fp8_sdwa v[242:243], v179 src0_sel:WORD_1
	v_pk_fma_f32 v[6:7], v[244:245], v[232:233], v[6:7] op_sel_hi:[1,0,1]
	v_add_f32_e32 v215, v215, v232
	v_pk_fma_f32 v[0:1], v[240:241], v[232:233], v[0:1] op_sel_hi:[1,0,1]
	v_pk_fma_f32 v[2:3], v[242:243], v[232:233], v[2:3] op_sel_hi:[1,0,1]
	v_readlane_b32 s0, v135, 26
	s_lshl_b32 s0, s0, 10
	s_add_u32 s4, s6, s0
	s_addc_u32 s5, s7, 0
	global_load_dwordx4 v[176:179], v16, s[4:5]
	s_waitcnt vmcnt(15)
	v_cvt_pk_f32_fp8_e32 v[240:241], v180
	v_cvt_pk_f32_fp8_sdwa v[242:243], v180 src0_sel:WORD_1
	v_cvt_pk_f32_fp8_e32 v[244:245], v181
	v_pk_fma_f32 v[12:13], v[240:241], v[232:233], v[12:13] op_sel:[0,1,0]
	v_cvt_pk_f32_fp8_sdwa v[240:241], v181 src0_sel:WORD_1
	v_pk_fma_f32 v[14:15], v[242:243], v[232:233], v[14:15] op_sel:[0,1,0]
	v_cvt_pk_f32_fp8_e32 v[242:243], v182
	v_sub_f32_e32 v236, v236, v216
	v_pk_fma_f32 v[8:9], v[244:245], v[232:233], v[8:9] op_sel:[0,1,0]
	v_cvt_pk_f32_fp8_sdwa v[244:245], v182 src0_sel:WORD_1
	v_pk_fma_f32 v[10:11], v[240:241], v[232:233], v[10:11] op_sel:[0,1,0]
	v_cvt_pk_f32_fp8_e32 v[240:241], v183
	v_exp_f32_e32 v236, v236
	v_pk_fma_f32 v[4:5], v[242:243], v[232:233], v[4:5] op_sel:[0,1,0]
	v_cvt_pk_f32_fp8_sdwa v[242:243], v183 src0_sel:WORD_1
	v_pk_fma_f32 v[6:7], v[244:245], v[232:233], v[6:7] op_sel:[0,1,0]
	v_add_f32_e32 v215, v215, v233
	v_pk_fma_f32 v[0:1], v[240:241], v[232:233], v[0:1] op_sel:[0,1,0]
	v_pk_fma_f32 v[2:3], v[242:243], v[232:233], v[2:3] op_sel:[0,1,0]
	v_readlane_b32 s0, v135, 27
	s_lshl_b32 s0, s0, 10
	s_add_u32 s4, s6, s0
	s_addc_u32 s5, s7, 0
	global_load_dwordx4 v[180:183], v16, s[4:5]
	s_waitcnt vmcnt(15)
; DI float sum8(float v) { v += DPPF(v, 0xB1); v += DPPF(v, 0x4E); v += DPPF(v, 0x141); return v; }
; DI void topk_phase(const bf16_t* PROJ, const unsigned char* K8, const unsigned char* V8, const unsigned short* SC, bf16_t* ODSA, int c, char* smem, int bid, int nb) {
;     ...
;         const size_t ro = (size_t)__builtin_amdgcn_readlane(mysel, jj) * 1024 + lane * 16;
;         const uint4 a = *(const uint4*)(K8 + ro), vv = *(const uint4*)(V8 + ro);
;         const unsigned w[4] = {a.x, a.y, a.z, a.w}, u[4] = {vv.x, vv.y, vv.z, vv.w};
;         float da = 0.f;
; #pragma unroll
;         for (int i = 0; i < 4; ++i) {
;           const f32x2v lo = __builtin_amdgcn_cvt_pk_f32_fp8((int)w[i], false), hi = __builtin_amdgcn_cvt_pk_f32_fp8((int)w[i], true);
;           da += qv[4 * i] * lo[0] + qv[4 * i + 1] * lo[1] + qv[4 * i + 2] * hi[0] + qv[4 * i + 3] * hi[1];
;         }
;         da = sum8(da);
;     ...
;         const float mn = fmaxf(m_run, da), al = __builtin_amdgcn_exp2f(m_run - mn), pp = __builtin_amdgcn_exp2f(da - mn);
;         m_run = mn; l_run = l_run * al + pp;
; #pragma unroll
;         for (int i = 0; i < 4; ++i) {
;           const f32x2v lo = __builtin_amdgcn_cvt_pk_f32_fp8((int)u[i], false), hi = __builtin_amdgcn_cvt_pk_f32_fp8((int)u[i], true);
;           ov[4 * i] = ov[4 * i] * al + pp * lo[0]; ov[4 * i + 1] = ov[4 * i + 1] * al + pp * lo[1];
;           ov[4 * i + 2] = ov[4 * i + 2] * al + pp * hi[0]; ov[4 * i + 3] = ov[4 * i + 3] * al + pp * hi[1];
;         }
	v_cvt_pk_f32_fp8_e32 v[240:241], v186
	v_cvt_pk_f32_fp8_sdwa v[242:243], v186 src0_sel:WORD_1
	v_cvt_pk_f32_fp8_e32 v[244:245], v187
	v_pk_fma_f32 v[12:13], v[240:241], v[236:237], v[12:13] op_sel_hi:[1,0,1]
	v_cvt_pk_f32_fp8_sdwa v[240:241], v187 src0_sel:WORD_1
	v_pk_fma_f32 v[14:15], v[242:243], v[236:237], v[14:15] op_sel_hi:[1,0,1]
	v_cvt_pk_f32_fp8_e32 v[242:243], v188
	v_sub_f32_e32 v237, v237, v216
	v_pk_fma_f32 v[8:9], v[244:245], v[236:237], v[8:9] op_sel_hi:[1,0,1]
	v_cvt_pk_f32_fp8_sdwa v[244:245], v188 src0_sel:WORD_1
	v_pk_fma_f32 v[10:11], v[240:241], v[236:237], v[10:11] op_sel_hi:[1,0,1]
	v_cvt_pk_f32_fp8_e32 v[240:241], v189
	v_exp_f32_e32 v237, v237
	v_pk_fma_f32 v[4:5], v[242:243], v[236:237], v[4:5] op_sel_hi:[1,0,1]
	v_cvt_pk_f32_fp8_sdwa v[242:243], v189 src0_sel:WORD_1
	v_pk_fma_f32 v[6:7], v[244:245], v[236:237], v[6:7] op_sel_hi:[1,0,1]
	v_add_f32_e32 v215, v215, v236
	v_pk_fma_f32 v[0:1], v[240:241], v[236:237], v[0:1] op_sel_hi:[1,0,1]
	v_pk_fma_f32 v[2:3], v[242:243], v[236:237], v[2:3] op_sel_hi:[1,0,1]
	v_readlane_b32 s0, v135, 28
	s_lshl_b32 s0, s0, 10
	s_add_u32 s4, s6, s0
	s_addc_u32 s5, s7, 0
	global_load_dwordx4 v[186:189], v16, s[4:5]
	s_waitcnt vmcnt(15)
	v_cvt_pk_f32_fp8_e32 v[240:241], v190
	v_cvt_pk_f32_fp8_sdwa v[242:243], v190 src0_sel:WORD_1
	v_cvt_pk_f32_fp8_e32 v[244:245], v191
	v_pk_fma_f32 v[12:13], v[240:241], v[236:237], v[12:13] op_sel:[0,1,0]
	v_cvt_pk_f32_fp8_sdwa v[240:241], v191 src0_sel:WORD_1
	v_pk_fma_f32 v[14:15], v[242:243], v[236:237], v[14:15] op_sel:[0,1,0]
	v_cvt_pk_f32_fp8_e32 v[242:243], v192
	v_sub_f32_e32 v238, v238, v216
	v_pk_fma_f32 v[8:9], v[244:245], v[236:237], v[8:9] op_sel:[0,1,0]
	v_cvt_pk_f32_fp8_sdwa v[244:245], v192 src0_sel:WORD_1
	v_pk_fma_f32 v[10:11], v[240:241], v[236:237], v[10:11] op_sel:[0,1,0]
	v_cvt_pk_f32_fp8_e32 v[240:241], v193
	v_exp_f32_e32 v238, v238
	v_pk_fma_f32 v[4:5], v[242:243], v[236:237], v[4:5] op_sel:[0,1,0]
	v_cvt_pk_f32_fp8_sdwa v[242:243], v193 src0_sel:WORD_1
	v_pk_fma_f32 v[6:7], v[244:245], v[236:237], v[6:7] op_sel:[0,1,0]
	v_add_f32_e32 v215, v215, v237
	v_pk_fma_f32 v[0:1], v[240:241], v[236:237], v[0:1] op_sel:[0,1,0]
	v_pk_fma_f32 v[2:3], v[242:243], v[236:237], v[2:3] op_sel:[0,1,0]
	v_readlane_b32 s0, v135, 29
	s_lshl_b32 s0, s0, 10
	s_add_u32 s4, s6, s0
	s_addc_u32 s5, s7, 0
	global_load_dwordx4 v[190:193], v16, s[4:5]
	s_waitcnt vmcnt(15)
	v_cvt_pk_f32_fp8_e32 v[240:241], v194
	v_cvt_pk_f32_fp8_sdwa v[242:243], v194 src0_sel:WORD_1
	v_cvt_pk_f32_fp8_e32 v[244:245], v195
	v_pk_fma_f32 v[12:13], v[240:241], v[238:239], v[12:13] op_sel_hi:[1,0,1]
	v_cvt_pk_f32_fp8_sdwa v[240:241], v195 src0_sel:WORD_1
	v_pk_fma_f32 v[14:15], v[242:243], v[238:239], v[14:15] op_sel_hi:[1,0,1]
	v_cvt_pk_f32_fp8_e32 v[242:243], v196
	v_sub_f32_e32 v239, v239, v216
	v_pk_fma_f32 v[8:9], v[244:245], v[238:239], v[8:9] op_sel_hi:[1,0,1]
	v_cvt_pk_f32_fp8_sdwa v[244:245], v196 src0_sel:WORD_1
	v_pk_fma_f32 v[10:11], v[240:241], v[238:239], v[10:11] op_sel_hi:[1,0,1]
	v_cvt_pk_f32_fp8_e32 v[240:241], v197
	v_exp_f32_e32 v239, v239
	v_pk_fma_f32 v[4:5], v[242:243], v[238:239], v[4:5] op_sel_hi:[1,0,1]
	v_cvt_pk_f32_fp8_sdwa v[242:243], v197 src0_sel:WORD_1
	v_pk_fma_f32 v[6:7], v[244:245], v[238:239], v[6:7] op_sel_hi:[1,0,1]
	v_add_f32_e32 v215, v215, v238
	v_pk_fma_f32 v[0:1], v[240:241], v[238:239], v[0:1] op_sel_hi:[1,0,1]
	v_pk_fma_f32 v[2:3], v[242:243], v[238:239], v[2:3] op_sel_hi:[1,0,1]
	v_readlane_b32 s0, v135, 30
	s_lshl_b32 s0, s0, 10
	s_add_u32 s4, s6, s0
	s_addc_u32 s5, s7, 0
	global_load_dwordx4 v[194:197], v16, s[4:5]
	s_waitcnt vmcnt(15)
	v_cvt_pk_f32_fp8_e32 v[240:241], v198
	v_cvt_pk_f32_fp8_sdwa v[242:243], v198 src0_sel:WORD_1
	v_cvt_pk_f32_fp8_e32 v[244:245], v199
	v_pk_fma_f32 v[12:13], v[240:241], v[238:239], v[12:13] op_sel:[0,1,0]
	v_cvt_pk_f32_fp8_sdwa v[240:241], v199 src0_sel:WORD_1
	v_pk_fma_f32 v[14:15], v[242:243], v[238:239], v[14:15] op_sel:[0,1,0]
	v_cvt_pk_f32_fp8_e32 v[242:243], v200
	v_add_f32_e32 v215, v215, v239
	v_pk_fma_f32 v[8:9], v[244:245], v[238:239], v[8:9] op_sel:[0,1,0]
	v_cvt_pk_f32_fp8_sdwa v[244:245], v200 src0_sel:WORD_1
	v_pk_fma_f32 v[10:11], v[240:241], v[238:239], v[10:11] op_sel:[0,1,0]
	v_cvt_pk_f32_fp8_e32 v[240:241], v201
	v_pk_fma_f32 v[4:5], v[242:243], v[238:239], v[4:5] op_sel:[0,1,0]
	v_cvt_pk_f32_fp8_sdwa v[242:243], v201 src0_sel:WORD_1
	v_pk_fma_f32 v[6:7], v[244:245], v[238:239], v[6:7] op_sel:[0,1,0]
	v_pk_fma_f32 v[0:1], v[240:241], v[238:239], v[0:1] op_sel:[0,1,0]
	v_pk_fma_f32 v[2:3], v[242:243], v[238:239], v[2:3] op_sel:[0,1,0]
	v_readlane_b32 s0, v135, 31
	s_lshl_b32 s0, s0, 10
	s_add_u32 s4, s6, s0
	s_addc_u32 s5, s7, 0
	global_load_dwordx4 v[198:201], v16, s[4:5]
	s_waitcnt vmcnt(15)
	v_cvt_pk_f32_fp8_e32 v[240:241], v136
	v_cvt_pk_f32_fp8_sdwa v[242:243], v136 src0_sel:WORD_1
	v_cvt_pk_f32_fp8_e32 v[244:245], v137
	v_cvt_pk_f32_fp8_sdwa v[202:203], v137 src0_sel:WORD_1
	v_pk_mul_f32 v[204:205], v[240:241], v[52:53]
	v_pk_mul_f32 v[206:207], v[242:243], v[54:55]
	v_cvt_pk_f32_fp8_e32 v[240:241], v138
	v_cvt_pk_f32_fp8_sdwa v[242:243], v138 src0_sel:WORD_1
	v_pk_fma_f32 v[204:205], v[244:245], v[56:57], v[204:205]
	v_pk_fma_f32 v[206:207], v[202:203], v[58:59], v[206:207]
	v_cvt_pk_f32_fp8_e32 v[244:245], v139
	v_cvt_pk_f32_fp8_sdwa v[202:203], v139 src0_sel:WORD_1
	v_pk_fma_f32 v[204:205], v[240:241], v[60:61], v[204:205]
	v_pk_fma_f32 v[206:207], v[242:243], v[62:63], v[206:207]
	v_pk_fma_f32 v[204:205], v[244:245], v[64:65], v[204:205]
	v_pk_fma_f32 v[206:207], v[202:203], v[66:67], v[206:207]
	v_readlane_b32 s0, v135, 16
	s_lshl_b32 s0, s0, 10
	s_add_u32 s4, s8, s0
	s_addc_u32 s5, s9, 0
	global_load_dwordx4 v[136:139], v16, s[4:5]
	v_pk_add_f32 v[204:205], v[204:205], v[206:207]
	s_nop 0
	v_add_f32_e32 v235, v204, v205
	s_waitcnt vmcnt(15)
; DI float sum8(float v) { v += DPPF(v, 0xB1); v += DPPF(v, 0x4E); v += DPPF(v, 0x141); return v; }
; DI void topk_phase(const bf16_t* PROJ, const unsigned char* K8, const unsigned char* V8, const unsigned short* SC, bf16_t* ODSA, int c, char* smem, int bid, int nb) {
;     ...
;         const size_t ro = (size_t)__builtin_amdgcn_readlane(mysel, jj) * 1024 + lane * 16;
;         const uint4 a = *(const uint4*)(K8 + ro), vv = *(const uint4*)(V8 + ro);
;         const unsigned w[4] = {a.x, a.y, a.z, a.w}, u[4] = {vv.x, vv.y, vv.z, vv.w};
;         float da = 0.f;
; #pragma unroll
;         for (int i = 0; i < 4; ++i) {
;           const f32x2v lo = __builtin_amdgcn_cvt_pk_f32_fp8((int)w[i], false), hi = __builtin_amdgcn_cvt_pk_f32_fp8((int)w[i], true);
;           da += qv[4 * i] * lo[0] + qv[4 * i + 1] * lo[1] + qv[4 * i + 2] * hi[0] + qv[4 * i + 3] * hi[1];
;         }
;         da = sum8(da);
;         da = j < count ? da : -3e30f;
;         const float mn = fmaxf(m_run, da), al = __builtin_amdgcn_exp2f(m_run - mn), pp = __builtin_amdgcn_exp2f(da - mn);
;         m_run = mn; l_run = l_run * al + pp;
	v_cvt_pk_f32_fp8_e32 v[240:241], v140
	v_cvt_pk_f32_fp8_sdwa v[242:243], v140 src0_sel:WORD_1
	v_cvt_pk_f32_fp8_e32 v[244:245], v141
	v_cvt_pk_f32_fp8_sdwa v[202:203], v141 src0_sel:WORD_1
	v_add_f32_dpp v235, v235, v235 quad_perm:[1,0,3,2] row_mask:0xf bank_mask:0xf bound_ctrl:1
	v_pk_mul_f32 v[204:205], v[240:241], v[52:53]
	v_pk_mul_f32 v[206:207], v[242:243], v[54:55]
	v_add_f32_dpp v235, v235, v235 quad_perm:[2,3,0,1] row_mask:0xf bank_mask:0xf bound_ctrl:1
	v_cvt_pk_f32_fp8_e32 v[240:241], v142
	v_cvt_pk_f32_fp8_sdwa v[242:243], v142 src0_sel:WORD_1
	v_add_f32_dpp v235, v235, v235 row_half_mirror row_mask:0xf bank_mask:0xf bound_ctrl:1
	v_pk_fma_f32 v[204:205], v[244:245], v[56:57], v[204:205]
	v_pk_fma_f32 v[206:207], v[202:203], v[58:59], v[206:207]
	s_add_i32 s0, s1, 16
	s_cmp_lt_i32 s0, s2
	s_cselect_b64 vcc, -1, 0
	v_cvt_pk_f32_fp8_e32 v[244:245], v143
	v_cvt_pk_f32_fp8_sdwa v[202:203], v143 src0_sel:WORD_1
	v_cndmask_b32_e32 v210, v220, v235, vcc
	v_pk_fma_f32 v[204:205], v[240:241], v[60:61], v[204:205]
	v_pk_fma_f32 v[206:207], v[242:243], v[62:63], v[206:207]
	v_pk_fma_f32 v[204:205], v[244:245], v[64:65], v[204:205]
	v_pk_fma_f32 v[206:207], v[202:203], v[66:67], v[206:207]
	v_readlane_b32 s0, v135, 17
	s_lshl_b32 s0, s0, 10
	s_add_u32 s4, s8, s0
	s_addc_u32 s5, s9, 0
	global_load_dwordx4 v[140:143], v16, s[4:5]
	v_pk_add_f32 v[204:205], v[204:205], v[206:207]
	s_nop 0
	v_add_f32_e32 v221, v204, v205
	s_waitcnt vmcnt(15)
	v_cvt_pk_f32_fp8_e32 v[240:241], v144
	v_cvt_pk_f32_fp8_sdwa v[242:243], v144 src0_sel:WORD_1
	v_cvt_pk_f32_fp8_e32 v[244:245], v145
	v_cvt_pk_f32_fp8_sdwa v[202:203], v145 src0_sel:WORD_1
	v_add_f32_dpp v221, v221, v221 quad_perm:[1,0,3,2] row_mask:0xf bank_mask:0xf bound_ctrl:1
	v_pk_mul_f32 v[204:205], v[240:241], v[52:53]
	v_pk_mul_f32 v[206:207], v[242:243], v[54:55]
	v_add_f32_dpp v221, v221, v221 quad_perm:[2,3,0,1] row_mask:0xf bank_mask:0xf bound_ctrl:1
	v_cvt_pk_f32_fp8_e32 v[240:241], v146
	v_cvt_pk_f32_fp8_sdwa v[242:243], v146 src0_sel:WORD_1
	v_add_f32_dpp v221, v221, v221 row_half_mirror row_mask:0xf bank_mask:0xf bound_ctrl:1
	v_pk_fma_f32 v[204:205], v[244:245], v[56:57], v[204:205]
	v_pk_fma_f32 v[206:207], v[202:203], v[58:59], v[206:207]
	s_add_i32 s0, s1, 17
	s_cmp_lt_i32 s0, s2
	s_cselect_b64 vcc, -1, 0
	v_cvt_pk_f32_fp8_e32 v[244:245], v147
	v_cvt_pk_f32_fp8_sdwa v[202:203], v147 src0_sel:WORD_1
	v_cndmask_b32_e32 v211, v220, v221, vcc
	v_pk_fma_f32 v[204:205], v[240:241], v[60:61], v[204:205]
	v_pk_fma_f32 v[206:207], v[242:243], v[62:63], v[206:207]
	v_pk_fma_f32 v[204:205], v[244:245], v[64:65], v[204:205]
	v_pk_fma_f32 v[206:207], v[202:203], v[66:67], v[206:207]
	v_readlane_b32 s0, v135, 18
	s_lshl_b32 s0, s0, 10
	s_add_u32 s4, s8, s0
	s_addc_u32 s5, s9, 0
	global_load_dwordx4 v[144:147], v16, s[4:5]
	v_pk_add_f32 v[204:205], v[204:205], v[206:207]
	s_nop 0
	v_add_f32_e32 v235, v204, v205
	s_waitcnt vmcnt(15)
	v_cvt_pk_f32_fp8_e32 v[240:241], v148
	v_cvt_pk_f32_fp8_sdwa v[242:243], v148 src0_sel:WORD_1
	v_cvt_pk_f32_fp8_e32 v[244:245], v149
	v_cvt_pk_f32_fp8_sdwa v[202:203], v149 src0_sel:WORD_1
	v_add_f32_dpp v235, v235, v235 quad_perm:[1,0,3,2] row_mask:0xf bank_mask:0xf bound_ctrl:1
	v_pk_mul_f32 v[204:205], v[240:241], v[52:53]
	v_pk_mul_f32 v[206:207], v[242:243], v[54:55]
	v_add_f32_dpp v235, v235, v235 quad_perm:[2,3,0,1] row_mask:0xf bank_mask:0xf bound_ctrl:1
	v_cvt_pk_f32_fp8_e32 v[240:241], v150
	v_cvt_pk_f32_fp8_sdwa v[242:243], v150 src0_sel:WORD_1
	v_add_f32_dpp v235, v235, v235 row_half_mirror row_mask:0xf bank_mask:0xf bound_ctrl:1
	v_pk_fma_f32 v[204:205], v[244:245], v[56:57], v[204:205]
	v_pk_fma_f32 v[206:207], v[202:203], v[58:59], v[206:207]
	s_add_i32 s0, s1, 18
	s_cmp_lt_i32 s0, s2
	s_cselect_b64 vcc, -1, 0
	v_cvt_pk_f32_fp8_e32 v[244:245], v151
	v_cvt_pk_f32_fp8_sdwa v[202:203], v151 src0_sel:WORD_1
	v_cndmask_b32_e32 v212, v220, v235, vcc
	v_pk_fma_f32 v[204:205], v[240:241], v[60:61], v[204:205]
	v_pk_fma_f32 v[206:207], v[242:243], v[62:63], v[206:207]
	v_pk_fma_f32 v[204:205], v[244:245], v[64:65], v[204:205]
	v_pk_fma_f32 v[206:207], v[202:203], v[66:67], v[206:207]
	v_readlane_b32 s0, v135, 19
	s_lshl_b32 s0, s0, 10
	s_add_u32 s4, s8, s0
	s_addc_u32 s5, s9, 0
	global_load_dwordx4 v[148:151], v16, s[4:5]
	v_pk_add_f32 v[204:205], v[204:205], v[206:207]
	s_nop 0
	v_add_f32_e32 v221, v204, v205
	s_waitcnt vmcnt(15)
	v_cvt_pk_f32_fp8_e32 v[240:241], v152
	v_cvt_pk_f32_fp8_sdwa v[242:243], v152 src0_sel:WORD_1
	v_cvt_pk_f32_fp8_e32 v[244:245], v153
	v_cvt_pk_f32_fp8_sdwa v[202:203], v153 src0_sel:WORD_1
	v_add_f32_dpp v221, v221, v221 quad_perm:[1,0,3,2] row_mask:0xf bank_mask:0xf bound_ctrl:1
	v_pk_mul_f32 v[204:205], v[240:241], v[52:53]
	v_pk_mul_f32 v[206:207], v[242:243], v[54:55]
	v_add_f32_dpp v221, v221, v221 quad_perm:[2,3,0,1] row_mask:0xf bank_mask:0xf bound_ctrl:1
	v_cvt_pk_f32_fp8_e32 v[240:241], v154
	v_cvt_pk_f32_fp8_sdwa v[242:243], v154 src0_sel:WORD_1
	v_add_f32_dpp v221, v221, v221 row_half_mirror row_mask:0xf bank_mask:0xf bound_ctrl:1
	v_pk_fma_f32 v[204:205], v[244:245], v[56:57], v[204:205]
	v_pk_fma_f32 v[206:207], v[202:203], v[58:59], v[206:207]
	s_add_i32 s0, s1, 19
	s_cmp_lt_i32 s0, s2
	s_cselect_b64 vcc, -1, 0
	v_cvt_pk_f32_fp8_e32 v[244:245], v155
	v_cvt_pk_f32_fp8_sdwa v[202:203], v155 src0_sel:WORD_1
	v_cndmask_b32_e32 v213, v220, v221, vcc
	v_pk_fma_f32 v[204:205], v[240:241], v[60:61], v[204:205]
	v_pk_fma_f32 v[206:207], v[242:243], v[62:63], v[206:207]
	v_pk_fma_f32 v[204:205], v[244:245], v[64:65], v[204:205]
	v_pk_fma_f32 v[206:207], v[202:203], v[66:67], v[206:207]
	v_readlane_b32 s0, v135, 20
	s_lshl_b32 s0, s0, 10
	s_add_u32 s4, s8, s0
	s_addc_u32 s5, s9, 0
	global_load_dwordx4 v[152:155], v16, s[4:5]
	v_pk_add_f32 v[204:205], v[204:205], v[206:207]
	s_nop 0
	v_add_f32_e32 v235, v204, v205
	s_waitcnt vmcnt(15)
; DI float sum8(float v) { v += DPPF(v, 0xB1); v += DPPF(v, 0x4E); v += DPPF(v, 0x141); return v; }
; DI void topk_phase(const bf16_t* PROJ, const unsigned char* K8, const unsigned char* V8, const unsigned short* SC, bf16_t* ODSA, int c, char* smem, int bid, int nb) {
;     ...
;         const size_t ro = (size_t)__builtin_amdgcn_readlane(mysel, jj) * 1024 + lane * 16;
;         const uint4 a = *(const uint4*)(K8 + ro), vv = *(const uint4*)(V8 + ro);
;         const unsigned w[4] = {a.x, a.y, a.z, a.w}, u[4] = {vv.x, vv.y, vv.z, vv.w};
;         float da = 0.f;
; #pragma unroll
;         for (int i = 0; i < 4; ++i) {
;           const f32x2v lo = __builtin_amdgcn_cvt_pk_f32_fp8((int)w[i], false), hi = __builtin_amdgcn_cvt_pk_f32_fp8((int)w[i], true);
;           da += qv[4 * i] * lo[0] + qv[4 * i + 1] * lo[1] + qv[4 * i + 2] * hi[0] + qv[4 * i + 3] * hi[1];
;         }
;         da = sum8(da);
;         da = j < count ? da : -3e30f;
;         const float mn = fmaxf(m_run, da), al = __builtin_amdgcn_exp2f(m_run - mn), pp = __builtin_amdgcn_exp2f(da - mn);
;         m_run = mn; l_run = l_run * al + pp;
	v_cvt_pk_f32_fp8_e32 v[240:241], v156
	v_cvt_pk_f32_fp8_sdwa v[242:243], v156 src0_sel:WORD_1
	v_cvt_pk_f32_fp8_e32 v[244:245], v157
	v_cvt_pk_f32_fp8_sdwa v[202:203], v157 src0_sel:WORD_1
	v_add_f32_dpp v235, v235, v235 quad_perm:[1,0,3,2] row_mask:0xf bank_mask:0xf bound_ctrl:1
	v_pk_mul_f32 v[204:205], v[240:241], v[52:53]
	v_pk_mul_f32 v[206:207], v[242:243], v[54:55]
	v_add_f32_dpp v235, v235, v235 quad_perm:[2,3,0,1] row_mask:0xf bank_mask:0xf bound_ctrl:1
	v_cvt_pk_f32_fp8_e32 v[240:241], v158
	v_cvt_pk_f32_fp8_sdwa v[242:243], v158 src0_sel:WORD_1
	v_add_f32_dpp v235, v235, v235 row_half_mirror row_mask:0xf bank_mask:0xf bound_ctrl:1
	v_pk_fma_f32 v[204:205], v[244:245], v[56:57], v[204:205]
	v_pk_fma_f32 v[206:207], v[202:203], v[58:59], v[206:207]
	s_add_i32 s0, s1, 20
	s_cmp_lt_i32 s0, s2
	s_cselect_b64 vcc, -1, 0
	v_cvt_pk_f32_fp8_e32 v[244:245], v159
	v_cvt_pk_f32_fp8_sdwa v[202:203], v159 src0_sel:WORD_1
	v_cndmask_b32_e32 v226, v220, v235, vcc
	v_pk_fma_f32 v[204:205], v[240:241], v[60:61], v[204:205]
	v_pk_fma_f32 v[206:207], v[242:243], v[62:63], v[206:207]
	v_pk_fma_f32 v[204:205], v[244:245], v[64:65], v[204:205]
	v_pk_fma_f32 v[206:207], v[202:203], v[66:67], v[206:207]
	v_readlane_b32 s0, v135, 21
	s_lshl_b32 s0, s0, 10
	s_add_u32 s4, s8, s0
	s_addc_u32 s5, s9, 0
	global_load_dwordx4 v[156:159], v16, s[4:5]
	v_pk_add_f32 v[204:205], v[204:205], v[206:207]
	s_nop 0
	v_add_f32_e32 v221, v204, v205
	s_waitcnt vmcnt(15)
	v_cvt_pk_f32_fp8_e32 v[240:241], v160
	v_cvt_pk_f32_fp8_sdwa v[242:243], v160 src0_sel:WORD_1
	v_cvt_pk_f32_fp8_e32 v[244:245], v161
	v_cvt_pk_f32_fp8_sdwa v[202:203], v161 src0_sel:WORD_1
	v_add_f32_dpp v221, v221, v221 quad_perm:[1,0,3,2] row_mask:0xf bank_mask:0xf bound_ctrl:1
	v_pk_mul_f32 v[204:205], v[240:241], v[52:53]
	v_pk_mul_f32 v[206:207], v[242:243], v[54:55]
	v_add_f32_dpp v221, v221, v221 quad_perm:[2,3,0,1] row_mask:0xf bank_mask:0xf bound_ctrl:1
	v_cvt_pk_f32_fp8_e32 v[240:241], v162
	v_cvt_pk_f32_fp8_sdwa v[242:243], v162 src0_sel:WORD_1
	v_add_f32_dpp v221, v221, v221 row_half_mirror row_mask:0xf bank_mask:0xf bound_ctrl:1
	v_pk_fma_f32 v[204:205], v[244:245], v[56:57], v[204:205]
	v_pk_fma_f32 v[206:207], v[202:203], v[58:59], v[206:207]
	s_add_i32 s0, s1, 21
	s_cmp_lt_i32 s0, s2
	s_cselect_b64 vcc, -1, 0
	v_cvt_pk_f32_fp8_e32 v[244:245], v163
	v_cvt_pk_f32_fp8_sdwa v[202:203], v163 src0_sel:WORD_1
	v_cndmask_b32_e32 v227, v220, v221, vcc
	v_pk_fma_f32 v[204:205], v[240:241], v[60:61], v[204:205]
	v_pk_fma_f32 v[206:207], v[242:243], v[62:63], v[206:207]
	v_pk_fma_f32 v[204:205], v[244:245], v[64:65], v[204:205]
	v_pk_fma_f32 v[206:207], v[202:203], v[66:67], v[206:207]
	v_readlane_b32 s0, v135, 22
	s_lshl_b32 s0, s0, 10
	s_add_u32 s4, s8, s0
	s_addc_u32 s5, s9, 0
	global_load_dwordx4 v[160:163], v16, s[4:5]
	v_pk_add_f32 v[204:205], v[204:205], v[206:207]
	s_nop 0
	v_add_f32_e32 v235, v204, v205
	s_waitcnt vmcnt(15)
	v_cvt_pk_f32_fp8_e32 v[240:241], v164
	v_cvt_pk_f32_fp8_sdwa v[242:243], v164 src0_sel:WORD_1
	v_cvt_pk_f32_fp8_e32 v[244:245], v165
	v_cvt_pk_f32_fp8_sdwa v[202:203], v165 src0_sel:WORD_1
	v_add_f32_dpp v235, v235, v235 quad_perm:[1,0,3,2] row_mask:0xf bank_mask:0xf bound_ctrl:1
	v_pk_mul_f32 v[204:205], v[240:241], v[52:53]
	v_pk_mul_f32 v[206:207], v[242:243], v[54:55]
	v_add_f32_dpp v235, v235, v235 quad_perm:[2,3,0,1] row_mask:0xf bank_mask:0xf bound_ctrl:1
	v_cvt_pk_f32_fp8_e32 v[240:241], v166
	v_cvt_pk_f32_fp8_sdwa v[242:243], v166 src0_sel:WORD_1
	v_add_f32_dpp v235, v235, v235 row_half_mirror row_mask:0xf bank_mask:0xf bound_ctrl:1
	v_pk_fma_f32 v[204:205], v[244:245], v[56:57], v[204:205]
	v_pk_fma_f32 v[206:207], v[202:203], v[58:59], v[206:207]
	s_add_i32 s0, s1, 22
	s_cmp_lt_i32 s0, s2
	s_cselect_b64 vcc, -1, 0
	v_cvt_pk_f32_fp8_e32 v[244:245], v167
	v_cvt_pk_f32_fp8_sdwa v[202:203], v167 src0_sel:WORD_1
	v_cndmask_b32_e32 v228, v220, v235, vcc
	v_pk_fma_f32 v[204:205], v[240:241], v[60:61], v[204:205]
	v_pk_fma_f32 v[206:207], v[242:243], v[62:63], v[206:207]
	v_pk_fma_f32 v[204:205], v[244:245], v[64:65], v[204:205]
	v_pk_fma_f32 v[206:207], v[202:203], v[66:67], v[206:207]
	v_readlane_b32 s0, v135, 23
	s_lshl_b32 s0, s0, 10
	s_add_u32 s4, s8, s0
	s_addc_u32 s5, s9, 0
	global_load_dwordx4 v[164:167], v16, s[4:5]
	v_pk_add_f32 v[204:205], v[204:205], v[206:207]
	s_nop 0
	v_add_f32_e32 v221, v204, v205
	s_waitcnt vmcnt(15)
	v_cvt_pk_f32_fp8_e32 v[240:241], v168
	v_cvt_pk_f32_fp8_sdwa v[242:243], v168 src0_sel:WORD_1
	v_cvt_pk_f32_fp8_e32 v[244:245], v169
	v_cvt_pk_f32_fp8_sdwa v[202:203], v169 src0_sel:WORD_1
	v_add_f32_dpp v221, v221, v221 quad_perm:[1,0,3,2] row_mask:0xf bank_mask:0xf bound_ctrl:1
	v_pk_mul_f32 v[204:205], v[240:241], v[52:53]
	v_pk_mul_f32 v[206:207], v[242:243], v[54:55]
	v_add_f32_dpp v221, v221, v221 quad_perm:[2,3,0,1] row_mask:0xf bank_mask:0xf bound_ctrl:1
	v_cvt_pk_f32_fp8_e32 v[240:241], v170
	v_cvt_pk_f32_fp8_sdwa v[242:243], v170 src0_sel:WORD_1
	v_add_f32_dpp v221, v221, v221 row_half_mirror row_mask:0xf bank_mask:0xf bound_ctrl:1
	v_pk_fma_f32 v[204:205], v[244:245], v[56:57], v[204:205]
	v_pk_fma_f32 v[206:207], v[202:203], v[58:59], v[206:207]
	s_add_i32 s0, s1, 23
	s_cmp_lt_i32 s0, s2
	s_cselect_b64 vcc, -1, 0
	v_cvt_pk_f32_fp8_e32 v[244:245], v171
	v_cvt_pk_f32_fp8_sdwa v[202:203], v171 src0_sel:WORD_1
	v_cndmask_b32_e32 v229, v220, v221, vcc
	v_pk_fma_f32 v[204:205], v[240:241], v[60:61], v[204:205]
	v_pk_fma_f32 v[206:207], v[242:243], v[62:63], v[206:207]
	v_pk_fma_f32 v[204:205], v[244:245], v[64:65], v[204:205]
	v_pk_fma_f32 v[206:207], v[202:203], v[66:67], v[206:207]
	v_readlane_b32 s0, v135, 24
	s_lshl_b32 s0, s0, 10
	s_add_u32 s4, s8, s0
	s_addc_u32 s5, s9, 0
	global_load_dwordx4 v[168:171], v16, s[4:5]
	v_pk_add_f32 v[204:205], v[204:205], v[206:207]
	s_nop 0
	v_add_f32_e32 v235, v204, v205
	s_waitcnt vmcnt(15)
; DI float sum8(float v) { v += DPPF(v, 0xB1); v += DPPF(v, 0x4E); v += DPPF(v, 0x141); return v; }
; DI void topk_phase(const bf16_t* PROJ, const unsigned char* K8, const unsigned char* V8, const unsigned short* SC, bf16_t* ODSA, int c, char* smem, int bid, int nb) {
;     ...
;         const size_t ro = (size_t)__builtin_amdgcn_readlane(mysel, jj) * 1024 + lane * 16;
;         const uint4 a = *(const uint4*)(K8 + ro), vv = *(const uint4*)(V8 + ro);
;         const unsigned w[4] = {a.x, a.y, a.z, a.w}, u[4] = {vv.x, vv.y, vv.z, vv.w};
;         float da = 0.f;
; #pragma unroll
;         for (int i = 0; i < 4; ++i) {
;           const f32x2v lo = __builtin_amdgcn_cvt_pk_f32_fp8((int)w[i], false), hi = __builtin_amdgcn_cvt_pk_f32_fp8((int)w[i], true);
;           da += qv[4 * i] * lo[0] + qv[4 * i + 1] * lo[1] + qv[4 * i + 2] * hi[0] + qv[4 * i + 3] * hi[1];
;         }
;         da = sum8(da);
;         da = j < count ? da : -3e30f;
;         const float mn = fmaxf(m_run, da), al = __builtin_amdgcn_exp2f(m_run - mn), pp = __builtin_amdgcn_exp2f(da - mn);
;         m_run = mn; l_run = l_run * al + pp;
	v_cvt_pk_f32_fp8_e32 v[240:241], v172
	v_cvt_pk_f32_fp8_sdwa v[242:243], v172 src0_sel:WORD_1
	v_cvt_pk_f32_fp8_e32 v[244:245], v173
	v_cvt_pk_f32_fp8_sdwa v[202:203], v173 src0_sel:WORD_1
	v_add_f32_dpp v235, v235, v235 quad_perm:[1,0,3,2] row_mask:0xf bank_mask:0xf bound_ctrl:1
	v_pk_mul_f32 v[204:205], v[240:241], v[52:53]
	v_pk_mul_f32 v[206:207], v[242:243], v[54:55]
	v_add_f32_dpp v235, v235, v235 quad_perm:[2,3,0,1] row_mask:0xf bank_mask:0xf bound_ctrl:1
	v_cvt_pk_f32_fp8_e32 v[240:241], v174
	v_cvt_pk_f32_fp8_sdwa v[242:243], v174 src0_sel:WORD_1
	v_add_f32_dpp v235, v235, v235 row_half_mirror row_mask:0xf bank_mask:0xf bound_ctrl:1
	v_pk_fma_f32 v[204:205], v[244:245], v[56:57], v[204:205]
	v_pk_fma_f32 v[206:207], v[202:203], v[58:59], v[206:207]
	s_add_i32 s0, s1, 24
	s_cmp_lt_i32 s0, s2
	s_cselect_b64 vcc, -1, 0
	v_cvt_pk_f32_fp8_e32 v[244:245], v175
	v_cvt_pk_f32_fp8_sdwa v[202:203], v175 src0_sel:WORD_1
	v_cndmask_b32_e32 v230, v220, v235, vcc
	v_pk_fma_f32 v[204:205], v[240:241], v[60:61], v[204:205]
	v_pk_fma_f32 v[206:207], v[242:243], v[62:63], v[206:207]
	v_pk_fma_f32 v[204:205], v[244:245], v[64:65], v[204:205]
	v_pk_fma_f32 v[206:207], v[202:203], v[66:67], v[206:207]
	v_readlane_b32 s0, v135, 25
	s_lshl_b32 s0, s0, 10
	s_add_u32 s4, s8, s0
	s_addc_u32 s5, s9, 0
	global_load_dwordx4 v[172:175], v16, s[4:5]
	v_pk_add_f32 v[204:205], v[204:205], v[206:207]
	s_nop 0
	v_add_f32_e32 v221, v204, v205
	s_waitcnt vmcnt(15)
	v_cvt_pk_f32_fp8_e32 v[240:241], v176
	v_cvt_pk_f32_fp8_sdwa v[242:243], v176 src0_sel:WORD_1
	v_cvt_pk_f32_fp8_e32 v[244:245], v177
	v_cvt_pk_f32_fp8_sdwa v[202:203], v177 src0_sel:WORD_1
	v_add_f32_dpp v221, v221, v221 quad_perm:[1,0,3,2] row_mask:0xf bank_mask:0xf bound_ctrl:1
	v_pk_mul_f32 v[204:205], v[240:241], v[52:53]
	v_pk_mul_f32 v[206:207], v[242:243], v[54:55]
	v_add_f32_dpp v221, v221, v221 quad_perm:[2,3,0,1] row_mask:0xf bank_mask:0xf bound_ctrl:1
	v_cvt_pk_f32_fp8_e32 v[240:241], v178
	v_cvt_pk_f32_fp8_sdwa v[242:243], v178 src0_sel:WORD_1
	v_add_f32_dpp v221, v221, v221 row_half_mirror row_mask:0xf bank_mask:0xf bound_ctrl:1
	v_pk_fma_f32 v[204:205], v[244:245], v[56:57], v[204:205]
	v_pk_fma_f32 v[206:207], v[202:203], v[58:59], v[206:207]
	s_add_i32 s0, s1, 25
	s_cmp_lt_i32 s0, s2
	s_cselect_b64 vcc, -1, 0
	v_cvt_pk_f32_fp8_e32 v[244:245], v179
	v_cvt_pk_f32_fp8_sdwa v[202:203], v179 src0_sel:WORD_1
	v_cndmask_b32_e32 v231, v220, v221, vcc
	v_pk_fma_f32 v[204:205], v[240:241], v[60:61], v[204:205]
	v_pk_fma_f32 v[206:207], v[242:243], v[62:63], v[206:207]
	v_pk_fma_f32 v[204:205], v[244:245], v[64:65], v[204:205]
	v_pk_fma_f32 v[206:207], v[202:203], v[66:67], v[206:207]
	v_readlane_b32 s0, v135, 26
	s_lshl_b32 s0, s0, 10
	s_add_u32 s4, s8, s0
	s_addc_u32 s5, s9, 0
	global_load_dwordx4 v[176:179], v16, s[4:5]
	v_pk_add_f32 v[204:205], v[204:205], v[206:207]
	s_nop 0
	v_add_f32_e32 v235, v204, v205
	s_waitcnt vmcnt(15)
	v_cvt_pk_f32_fp8_e32 v[240:241], v180
	v_cvt_pk_f32_fp8_sdwa v[242:243], v180 src0_sel:WORD_1
	v_cvt_pk_f32_fp8_e32 v[244:245], v181
	v_cvt_pk_f32_fp8_sdwa v[202:203], v181 src0_sel:WORD_1
	v_add_f32_dpp v235, v235, v235 quad_perm:[1,0,3,2] row_mask:0xf bank_mask:0xf bound_ctrl:1
	v_pk_mul_f32 v[204:205], v[240:241], v[52:53]
	v_pk_mul_f32 v[206:207], v[242:243], v[54:55]
	v_add_f32_dpp v235, v235, v235 quad_perm:[2,3,0,1] row_mask:0xf bank_mask:0xf bound_ctrl:1
	v_cvt_pk_f32_fp8_e32 v[240:241], v182
	v_cvt_pk_f32_fp8_sdwa v[242:243], v182 src0_sel:WORD_1
	v_add_f32_dpp v235, v235, v235 row_half_mirror row_mask:0xf bank_mask:0xf bound_ctrl:1
	v_pk_fma_f32 v[204:205], v[244:245], v[56:57], v[204:205]
	v_pk_fma_f32 v[206:207], v[202:203], v[58:59], v[206:207]
	s_add_i32 s0, s1, 26
	s_cmp_lt_i32 s0, s2
	s_cselect_b64 vcc, -1, 0
	v_cvt_pk_f32_fp8_e32 v[244:245], v183
	v_cvt_pk_f32_fp8_sdwa v[202:203], v183 src0_sel:WORD_1
	v_cndmask_b32_e32 v232, v220, v235, vcc
	v_pk_fma_f32 v[204:205], v[240:241], v[60:61], v[204:205]
	v_pk_fma_f32 v[206:207], v[242:243], v[62:63], v[206:207]
	v_pk_fma_f32 v[204:205], v[244:245], v[64:65], v[204:205]
	v_pk_fma_f32 v[206:207], v[202:203], v[66:67], v[206:207]
	v_readlane_b32 s0, v135, 27
	s_lshl_b32 s0, s0, 10
	s_add_u32 s4, s8, s0
	s_addc_u32 s5, s9, 0
	global_load_dwordx4 v[180:183], v16, s[4:5]
	v_pk_add_f32 v[204:205], v[204:205], v[206:207]
	s_nop 0
	v_add_f32_e32 v221, v204, v205
	s_waitcnt vmcnt(15)
	v_cvt_pk_f32_fp8_e32 v[240:241], v186
	v_cvt_pk_f32_fp8_sdwa v[242:243], v186 src0_sel:WORD_1
	v_cvt_pk_f32_fp8_e32 v[244:245], v187
	v_cvt_pk_f32_fp8_sdwa v[202:203], v187 src0_sel:WORD_1
	v_add_f32_dpp v221, v221, v221 quad_perm:[1,0,3,2] row_mask:0xf bank_mask:0xf bound_ctrl:1
	v_pk_mul_f32 v[204:205], v[240:241], v[52:53]
	v_pk_mul_f32 v[206:207], v[242:243], v[54:55]
	v_add_f32_dpp v221, v221, v221 quad_perm:[2,3,0,1] row_mask:0xf bank_mask:0xf bound_ctrl:1
	v_cvt_pk_f32_fp8_e32 v[240:241], v188
	v_cvt_pk_f32_fp8_sdwa v[242:243], v188 src0_sel:WORD_1
	v_add_f32_dpp v221, v221, v221 row_half_mirror row_mask:0xf bank_mask:0xf bound_ctrl:1
	v_pk_fma_f32 v[204:205], v[244:245], v[56:57], v[204:205]
	v_pk_fma_f32 v[206:207], v[202:203], v[58:59], v[206:207]
	s_add_i32 s0, s1, 27
	s_cmp_lt_i32 s0, s2
	s_cselect_b64 vcc, -1, 0
	v_cvt_pk_f32_fp8_e32 v[244:245], v189
	v_cvt_pk_f32_fp8_sdwa v[202:203], v189 src0_sel:WORD_1
	v_cndmask_b32_e32 v233, v220, v221, vcc
	v_pk_fma_f32 v[204:205], v[240:241], v[60:61], v[204:205]
	v_pk_fma_f32 v[206:207], v[242:243], v[62:63], v[206:207]
	v_pk_fma_f32 v[204:205], v[244:245], v[64:65], v[204:205]
	v_pk_fma_f32 v[206:207], v[202:203], v[66:67], v[206:207]
	v_readlane_b32 s0, v135, 28
	s_lshl_b32 s0, s0, 10
	s_add_u32 s4, s8, s0
	s_addc_u32 s5, s9, 0
	global_load_dwordx4 v[186:189], v16, s[4:5]
	v_pk_add_f32 v[204:205], v[204:205], v[206:207]
	s_nop 0
	v_add_f32_e32 v235, v204, v205
	s_waitcnt vmcnt(15)
; DI float sum8(float v) { v += DPPF(v, 0xB1); v += DPPF(v, 0x4E); v += DPPF(v, 0x141); return v; }
; DI void topk_phase(const bf16_t* PROJ, const unsigned char* K8, const unsigned char* V8, const unsigned short* SC, bf16_t* ODSA, int c, char* smem, int bid, int nb) {
;     ...
;         const size_t ro = (size_t)__builtin_amdgcn_readlane(mysel, jj) * 1024 + lane * 16;
;         const uint4 a = *(const uint4*)(K8 + ro), vv = *(const uint4*)(V8 + ro);
;         const unsigned w[4] = {a.x, a.y, a.z, a.w}, u[4] = {vv.x, vv.y, vv.z, vv.w};
;         float da = 0.f;
; #pragma unroll
;         for (int i = 0; i < 4; ++i) {
;           const f32x2v lo = __builtin_amdgcn_cvt_pk_f32_fp8((int)w[i], false), hi = __builtin_amdgcn_cvt_pk_f32_fp8((int)w[i], true);
;           da += qv[4 * i] * lo[0] + qv[4 * i + 1] * lo[1] + qv[4 * i + 2] * hi[0] + qv[4 * i + 3] * hi[1];
;         }
;         da = sum8(da);
;         da = j < count ? da : -3e30f;
;         const float mn = fmaxf(m_run, da), al = __builtin_amdgcn_exp2f(m_run - mn), pp = __builtin_amdgcn_exp2f(da - mn);
;         m_run = mn; l_run = l_run * al + pp;
; #pragma unroll
	v_cvt_pk_f32_fp8_e32 v[240:241], v190
	v_cvt_pk_f32_fp8_sdwa v[242:243], v190 src0_sel:WORD_1
	v_cvt_pk_f32_fp8_e32 v[244:245], v191
	v_cvt_pk_f32_fp8_sdwa v[202:203], v191 src0_sel:WORD_1
	v_add_f32_dpp v235, v235, v235 quad_perm:[1,0,3,2] row_mask:0xf bank_mask:0xf bound_ctrl:1
	v_pk_mul_f32 v[204:205], v[240:241], v[52:53]
	v_pk_mul_f32 v[206:207], v[242:243], v[54:55]
	v_add_f32_dpp v235, v235, v235 quad_perm:[2,3,0,1] row_mask:0xf bank_mask:0xf bound_ctrl:1
	v_cvt_pk_f32_fp8_e32 v[240:241], v192
	v_cvt_pk_f32_fp8_sdwa v[242:243], v192 src0_sel:WORD_1
	v_add_f32_dpp v235, v235, v235 row_half_mirror row_mask:0xf bank_mask:0xf bound_ctrl:1
	v_pk_fma_f32 v[204:205], v[244:245], v[56:57], v[204:205]
	v_pk_fma_f32 v[206:207], v[202:203], v[58:59], v[206:207]
	s_add_i32 s0, s1, 28
	s_cmp_lt_i32 s0, s2
	s_cselect_b64 vcc, -1, 0
	v_cvt_pk_f32_fp8_e32 v[244:245], v193
	v_cvt_pk_f32_fp8_sdwa v[202:203], v193 src0_sel:WORD_1
	v_cndmask_b32_e32 v236, v220, v235, vcc
	v_pk_fma_f32 v[204:205], v[240:241], v[60:61], v[204:205]
	v_pk_fma_f32 v[206:207], v[242:243], v[62:63], v[206:207]
	v_pk_fma_f32 v[204:205], v[244:245], v[64:65], v[204:205]
	v_pk_fma_f32 v[206:207], v[202:203], v[66:67], v[206:207]
	v_readlane_b32 s0, v135, 29
	s_lshl_b32 s0, s0, 10
	s_add_u32 s4, s8, s0
	s_addc_u32 s5, s9, 0
	global_load_dwordx4 v[190:193], v16, s[4:5]
	v_pk_add_f32 v[204:205], v[204:205], v[206:207]
	s_nop 0
	v_add_f32_e32 v221, v204, v205
	s_waitcnt vmcnt(15)
	v_cvt_pk_f32_fp8_e32 v[240:241], v194
	v_cvt_pk_f32_fp8_sdwa v[242:243], v194 src0_sel:WORD_1
	v_cvt_pk_f32_fp8_e32 v[244:245], v195
	v_cvt_pk_f32_fp8_sdwa v[202:203], v195 src0_sel:WORD_1
	v_add_f32_dpp v221, v221, v221 quad_perm:[1,0,3,2] row_mask:0xf bank_mask:0xf bound_ctrl:1
	v_pk_mul_f32 v[204:205], v[240:241], v[52:53]
	v_pk_mul_f32 v[206:207], v[242:243], v[54:55]
	v_add_f32_dpp v221, v221, v221 quad_perm:[2,3,0,1] row_mask:0xf bank_mask:0xf bound_ctrl:1
	v_cvt_pk_f32_fp8_e32 v[240:241], v196
	v_cvt_pk_f32_fp8_sdwa v[242:243], v196 src0_sel:WORD_1
	v_add_f32_dpp v221, v221, v221 row_half_mirror row_mask:0xf bank_mask:0xf bound_ctrl:1
	v_pk_fma_f32 v[204:205], v[244:245], v[56:57], v[204:205]
	v_pk_fma_f32 v[206:207], v[202:203], v[58:59], v[206:207]
	s_add_i32 s0, s1, 29
	s_cmp_lt_i32 s0, s2
	s_cselect_b64 vcc, -1, 0
	v_cvt_pk_f32_fp8_e32 v[244:245], v197
	v_cvt_pk_f32_fp8_sdwa v[202:203], v197 src0_sel:WORD_1
	v_cndmask_b32_e32 v237, v220, v221, vcc
	v_pk_fma_f32 v[204:205], v[240:241], v[60:61], v[204:205]
	v_pk_fma_f32 v[206:207], v[242:243], v[62:63], v[206:207]
	v_pk_fma_f32 v[204:205], v[244:245], v[64:65], v[204:205]
	v_pk_fma_f32 v[206:207], v[202:203], v[66:67], v[206:207]
	v_readlane_b32 s0, v135, 30
	s_lshl_b32 s0, s0, 10
	s_add_u32 s4, s8, s0
	s_addc_u32 s5, s9, 0
	global_load_dwordx4 v[194:197], v16, s[4:5]
	v_pk_add_f32 v[204:205], v[204:205], v[206:207]
	s_nop 0
	v_add_f32_e32 v235, v204, v205
	s_waitcnt vmcnt(15)
	v_cvt_pk_f32_fp8_e32 v[240:241], v198
	v_cvt_pk_f32_fp8_sdwa v[242:243], v198 src0_sel:WORD_1
	v_cvt_pk_f32_fp8_e32 v[244:245], v199
	v_cvt_pk_f32_fp8_sdwa v[202:203], v199 src0_sel:WORD_1
	v_add_f32_dpp v235, v235, v235 quad_perm:[1,0,3,2] row_mask:0xf bank_mask:0xf bound_ctrl:1
	v_pk_mul_f32 v[204:205], v[240:241], v[52:53]
	v_pk_mul_f32 v[206:207], v[242:243], v[54:55]
	v_add_f32_dpp v235, v235, v235 quad_perm:[2,3,0,1] row_mask:0xf bank_mask:0xf bound_ctrl:1
	v_cvt_pk_f32_fp8_e32 v[240:241], v200
	v_cvt_pk_f32_fp8_sdwa v[242:243], v200 src0_sel:WORD_1
	v_add_f32_dpp v235, v235, v235 row_half_mirror row_mask:0xf bank_mask:0xf bound_ctrl:1
	v_pk_fma_f32 v[204:205], v[244:245], v[56:57], v[204:205]
	v_pk_fma_f32 v[206:207], v[202:203], v[58:59], v[206:207]
	s_add_i32 s0, s1, 30
	s_cmp_lt_i32 s0, s2
	s_cselect_b64 vcc, -1, 0
	v_cvt_pk_f32_fp8_e32 v[244:245], v201
	v_cvt_pk_f32_fp8_sdwa v[202:203], v201 src0_sel:WORD_1
	v_cndmask_b32_e32 v238, v220, v235, vcc
	v_pk_fma_f32 v[204:205], v[240:241], v[60:61], v[204:205]
	v_pk_fma_f32 v[206:207], v[242:243], v[62:63], v[206:207]
	v_pk_fma_f32 v[204:205], v[244:245], v[64:65], v[204:205]
	v_pk_fma_f32 v[206:207], v[202:203], v[66:67], v[206:207]
	v_readlane_b32 s0, v135, 31
	s_lshl_b32 s0, s0, 10
	s_add_u32 s4, s8, s0
	s_addc_u32 s5, s9, 0
	global_load_dwordx4 v[198:201], v16, s[4:5]
	v_pk_add_f32 v[204:205], v[204:205], v[206:207]
	s_nop 0
	v_add_f32_e32 v221, v204, v205
	s_nop 1
	v_add_f32_dpp v221, v221, v221 quad_perm:[1,0,3,2] row_mask:0xf bank_mask:0xf bound_ctrl:1
	s_nop 1
	v_add_f32_dpp v221, v221, v221 quad_perm:[2,3,0,1] row_mask:0xf bank_mask:0xf bound_ctrl:1
	s_nop 1
	v_add_f32_dpp v221, v221, v221 row_half_mirror row_mask:0xf bank_mask:0xf bound_ctrl:1
	s_add_i32 s0, s1, 31
	s_cmp_lt_i32 s0, s2
	s_cselect_b64 vcc, -1, 0
	s_nop 1
	v_cndmask_b32_e32 v239, v220, v221, vcc
	v_max3_f32 v224, v210, v211, v212
	v_max3_f32 v224, v224, v213, v226
	v_max3_f32 v224, v224, v227, v228
	v_max3_f32 v224, v224, v229, v230
	v_max3_f32 v224, v224, v231, v232
	v_max3_f32 v224, v224, v233, v236
	v_max3_f32 v224, v224, v237, v238
	v_max_f32_e32 v224, v224, v239
	v_max_f32_e32 v221, v216, v224
	v_sub_f32_e32 v184, v216, v221
	v_exp_f32_e32 v184, v184
	v_mov_b32_e32 v216, v221
	s_nop 0
	v_pk_mul_f32 v[12:13], v[12:13], v[184:185] op_sel_hi:[1,0]
	v_pk_mul_f32 v[14:15], v[14:15], v[184:185] op_sel_hi:[1,0]
	v_pk_mul_f32 v[8:9], v[8:9], v[184:185] op_sel_hi:[1,0]
	v_pk_mul_f32 v[10:11], v[10:11], v[184:185] op_sel_hi:[1,0]
	v_pk_mul_f32 v[4:5], v[4:5], v[184:185] op_sel_hi:[1,0]
	v_pk_mul_f32 v[6:7], v[6:7], v[184:185] op_sel_hi:[1,0]
	v_pk_mul_f32 v[0:1], v[0:1], v[184:185] op_sel_hi:[1,0]
	v_pk_mul_f32 v[2:3], v[2:3], v[184:185] op_sel_hi:[1,0]
	v_mul_f32_e32 v215, v215, v184
	v_sub_f32_e32 v210, v210, v216
	v_exp_f32_e32 v210, v210
	s_waitcnt vmcnt(15)
; DI void topk_phase(const bf16_t* PROJ, const unsigned char* K8, const unsigned char* V8, const unsigned short* SC, bf16_t* ODSA, int c, char* smem, int bid, int nb) {
;     ...
;         const float mn = fmaxf(m_run, da), al = __builtin_amdgcn_exp2f(m_run - mn), pp = __builtin_amdgcn_exp2f(da - mn);
;         m_run = mn; l_run = l_run * al + pp;
; #pragma unroll
;         for (int i = 0; i < 4; ++i) {
;           const f32x2v lo = __builtin_amdgcn_cvt_pk_f32_fp8((int)u[i], false), hi = __builtin_amdgcn_cvt_pk_f32_fp8((int)u[i], true);
;           ov[4 * i] = ov[4 * i] * al + pp * lo[0]; ov[4 * i + 1] = ov[4 * i + 1] * al + pp * lo[1];
;           ov[4 * i + 2] = ov[4 * i + 2] * al + pp * hi[0]; ov[4 * i + 3] = ov[4 * i + 3] * al + pp * hi[1];
;         }
	v_cvt_pk_f32_fp8_e32 v[240:241], v136
	v_cvt_pk_f32_fp8_sdwa v[242:243], v136 src0_sel:WORD_1
	v_cvt_pk_f32_fp8_e32 v[244:245], v137
	v_pk_fma_f32 v[12:13], v[240:241], v[210:211], v[12:13] op_sel_hi:[1,0,1]
	v_cvt_pk_f32_fp8_sdwa v[240:241], v137 src0_sel:WORD_1
	v_pk_fma_f32 v[14:15], v[242:243], v[210:211], v[14:15] op_sel_hi:[1,0,1]
	v_cvt_pk_f32_fp8_e32 v[242:243], v138
	v_sub_f32_e32 v211, v211, v216
	v_pk_fma_f32 v[8:9], v[244:245], v[210:211], v[8:9] op_sel_hi:[1,0,1]
	v_cvt_pk_f32_fp8_sdwa v[244:245], v138 src0_sel:WORD_1
	v_pk_fma_f32 v[10:11], v[240:241], v[210:211], v[10:11] op_sel_hi:[1,0,1]
	v_cvt_pk_f32_fp8_e32 v[240:241], v139
	v_exp_f32_e32 v211, v211
	v_pk_fma_f32 v[4:5], v[242:243], v[210:211], v[4:5] op_sel_hi:[1,0,1]
	v_cvt_pk_f32_fp8_sdwa v[242:243], v139 src0_sel:WORD_1
	v_pk_fma_f32 v[6:7], v[244:245], v[210:211], v[6:7] op_sel_hi:[1,0,1]
	v_add_f32_e32 v215, v215, v210
	v_pk_fma_f32 v[0:1], v[240:241], v[210:211], v[0:1] op_sel_hi:[1,0,1]
	v_pk_fma_f32 v[2:3], v[242:243], v[210:211], v[2:3] op_sel_hi:[1,0,1]
	v_readlane_b32 s0, v135, 32
	s_lshl_b32 s0, s0, 10
	s_add_u32 s4, s6, s0
	s_addc_u32 s5, s7, 0
	global_load_dwordx4 v[136:139], v16, s[4:5]
	s_waitcnt vmcnt(15)
	v_cvt_pk_f32_fp8_e32 v[240:241], v140
	v_cvt_pk_f32_fp8_sdwa v[242:243], v140 src0_sel:WORD_1
	v_cvt_pk_f32_fp8_e32 v[244:245], v141
	v_pk_fma_f32 v[12:13], v[240:241], v[210:211], v[12:13] op_sel:[0,1,0]
	v_cvt_pk_f32_fp8_sdwa v[240:241], v141 src0_sel:WORD_1
	v_pk_fma_f32 v[14:15], v[242:243], v[210:211], v[14:15] op_sel:[0,1,0]
	v_cvt_pk_f32_fp8_e32 v[242:243], v142
	v_sub_f32_e32 v212, v212, v216
	v_pk_fma_f32 v[8:9], v[244:245], v[210:211], v[8:9] op_sel:[0,1,0]
	v_cvt_pk_f32_fp8_sdwa v[244:245], v142 src0_sel:WORD_1
	v_pk_fma_f32 v[10:11], v[240:241], v[210:211], v[10:11] op_sel:[0,1,0]
	v_cvt_pk_f32_fp8_e32 v[240:241], v143
	v_exp_f32_e32 v212, v212
	v_pk_fma_f32 v[4:5], v[242:243], v[210:211], v[4:5] op_sel:[0,1,0]
	v_cvt_pk_f32_fp8_sdwa v[242:243], v143 src0_sel:WORD_1
	v_pk_fma_f32 v[6:7], v[244:245], v[210:211], v[6:7] op_sel:[0,1,0]
	v_add_f32_e32 v215, v215, v211
	v_pk_fma_f32 v[0:1], v[240:241], v[210:211], v[0:1] op_sel:[0,1,0]
	v_pk_fma_f32 v[2:3], v[242:243], v[210:211], v[2:3] op_sel:[0,1,0]
	v_readlane_b32 s0, v135, 33
	s_lshl_b32 s0, s0, 10
	s_add_u32 s4, s6, s0
	s_addc_u32 s5, s7, 0
	global_load_dwordx4 v[140:143], v16, s[4:5]
	s_waitcnt vmcnt(15)
	v_cvt_pk_f32_fp8_e32 v[240:241], v144
	v_cvt_pk_f32_fp8_sdwa v[242:243], v144 src0_sel:WORD_1
	v_cvt_pk_f32_fp8_e32 v[244:245], v145
	v_pk_fma_f32 v[12:13], v[240:241], v[212:213], v[12:13] op_sel_hi:[1,0,1]
	v_cvt_pk_f32_fp8_sdwa v[240:241], v145 src0_sel:WORD_1
	v_pk_fma_f32 v[14:15], v[242:243], v[212:213], v[14:15] op_sel_hi:[1,0,1]
	v_cvt_pk_f32_fp8_e32 v[242:243], v146
	v_sub_f32_e32 v213, v213, v216
	v_pk_fma_f32 v[8:9], v[244:245], v[212:213], v[8:9] op_sel_hi:[1,0,1]
	v_cvt_pk_f32_fp8_sdwa v[244:245], v146 src0_sel:WORD_1
	v_pk_fma_f32 v[10:11], v[240:241], v[212:213], v[10:11] op_sel_hi:[1,0,1]
	v_cvt_pk_f32_fp8_e32 v[240:241], v147
	v_exp_f32_e32 v213, v213
	v_pk_fma_f32 v[4:5], v[242:243], v[212:213], v[4:5] op_sel_hi:[1,0,1]
	v_cvt_pk_f32_fp8_sdwa v[242:243], v147 src0_sel:WORD_1
	v_pk_fma_f32 v[6:7], v[244:245], v[212:213], v[6:7] op_sel_hi:[1,0,1]
	v_add_f32_e32 v215, v215, v212
	v_pk_fma_f32 v[0:1], v[240:241], v[212:213], v[0:1] op_sel_hi:[1,0,1]
	v_pk_fma_f32 v[2:3], v[242:243], v[212:213], v[2:3] op_sel_hi:[1,0,1]
	v_readlane_b32 s0, v135, 34
	s_lshl_b32 s0, s0, 10
	s_add_u32 s4, s6, s0
	s_addc_u32 s5, s7, 0
	global_load_dwordx4 v[144:147], v16, s[4:5]
	s_waitcnt vmcnt(15)
	v_cvt_pk_f32_fp8_e32 v[240:241], v148
	v_cvt_pk_f32_fp8_sdwa v[242:243], v148 src0_sel:WORD_1
	v_cvt_pk_f32_fp8_e32 v[244:245], v149
	v_pk_fma_f32 v[12:13], v[240:241], v[212:213], v[12:13] op_sel:[0,1,0]
	v_cvt_pk_f32_fp8_sdwa v[240:241], v149 src0_sel:WORD_1
	v_pk_fma_f32 v[14:15], v[242:243], v[212:213], v[14:15] op_sel:[0,1,0]
	v_cvt_pk_f32_fp8_e32 v[242:243], v150
	v_sub_f32_e32 v226, v226, v216
	v_pk_fma_f32 v[8:9], v[244:245], v[212:213], v[8:9] op_sel:[0,1,0]
	v_cvt_pk_f32_fp8_sdwa v[244:245], v150 src0_sel:WORD_1
	v_pk_fma_f32 v[10:11], v[240:241], v[212:213], v[10:11] op_sel:[0,1,0]
	v_cvt_pk_f32_fp8_e32 v[240:241], v151
	v_exp_f32_e32 v226, v226
	v_pk_fma_f32 v[4:5], v[242:243], v[212:213], v[4:5] op_sel:[0,1,0]
	v_cvt_pk_f32_fp8_sdwa v[242:243], v151 src0_sel:WORD_1
	v_pk_fma_f32 v[6:7], v[244:245], v[212:213], v[6:7] op_sel:[0,1,0]
	v_add_f32_e32 v215, v215, v213
	v_pk_fma_f32 v[0:1], v[240:241], v[212:213], v[0:1] op_sel:[0,1,0]
	v_pk_fma_f32 v[2:3], v[242:243], v[212:213], v[2:3] op_sel:[0,1,0]
	v_readlane_b32 s0, v135, 35
	s_lshl_b32 s0, s0, 10
	s_add_u32 s4, s6, s0
	s_addc_u32 s5, s7, 0
	global_load_dwordx4 v[148:151], v16, s[4:5]
	s_waitcnt vmcnt(15)
	v_cvt_pk_f32_fp8_e32 v[240:241], v152
	v_cvt_pk_f32_fp8_sdwa v[242:243], v152 src0_sel:WORD_1
	v_cvt_pk_f32_fp8_e32 v[244:245], v153
	v_pk_fma_f32 v[12:13], v[240:241], v[226:227], v[12:13] op_sel_hi:[1,0,1]
	v_cvt_pk_f32_fp8_sdwa v[240:241], v153 src0_sel:WORD_1
	v_pk_fma_f32 v[14:15], v[242:243], v[226:227], v[14:15] op_sel_hi:[1,0,1]
	v_cvt_pk_f32_fp8_e32 v[242:243], v154
	v_sub_f32_e32 v227, v227, v216
	v_pk_fma_f32 v[8:9], v[244:245], v[226:227], v[8:9] op_sel_hi:[1,0,1]
	v_cvt_pk_f32_fp8_sdwa v[244:245], v154 src0_sel:WORD_1
	v_pk_fma_f32 v[10:11], v[240:241], v[226:227], v[10:11] op_sel_hi:[1,0,1]
	v_cvt_pk_f32_fp8_e32 v[240:241], v155
	v_exp_f32_e32 v227, v227
	v_pk_fma_f32 v[4:5], v[242:243], v[226:227], v[4:5] op_sel_hi:[1,0,1]
	v_cvt_pk_f32_fp8_sdwa v[242:243], v155 src0_sel:WORD_1
	v_pk_fma_f32 v[6:7], v[244:245], v[226:227], v[6:7] op_sel_hi:[1,0,1]
	v_add_f32_e32 v215, v215, v226
	v_pk_fma_f32 v[0:1], v[240:241], v[226:227], v[0:1] op_sel_hi:[1,0,1]
	v_pk_fma_f32 v[2:3], v[242:243], v[226:227], v[2:3] op_sel_hi:[1,0,1]
	v_readlane_b32 s0, v135, 36
	s_lshl_b32 s0, s0, 10
	s_add_u32 s4, s6, s0
	s_addc_u32 s5, s7, 0
	global_load_dwordx4 v[152:155], v16, s[4:5]
	s_waitcnt vmcnt(15)
; DI void topk_phase(const bf16_t* PROJ, const unsigned char* K8, const unsigned char* V8, const unsigned short* SC, bf16_t* ODSA, int c, char* smem, int bid, int nb) {
;     ...
;         const float mn = fmaxf(m_run, da), al = __builtin_amdgcn_exp2f(m_run - mn), pp = __builtin_amdgcn_exp2f(da - mn);
;         m_run = mn; l_run = l_run * al + pp;
; #pragma unroll
;         for (int i = 0; i < 4; ++i) {
;           const f32x2v lo = __builtin_amdgcn_cvt_pk_f32_fp8((int)u[i], false), hi = __builtin_amdgcn_cvt_pk_f32_fp8((int)u[i], true);
;           ov[4 * i] = ov[4 * i] * al + pp * lo[0]; ov[4 * i + 1] = ov[4 * i + 1] * al + pp * lo[1];
;           ov[4 * i + 2] = ov[4 * i + 2] * al + pp * hi[0]; ov[4 * i + 3] = ov[4 * i + 3] * al + pp * hi[1];
;         }
	v_cvt_pk_f32_fp8_e32 v[240:241], v156
	v_cvt_pk_f32_fp8_sdwa v[242:243], v156 src0_sel:WORD_1
	v_cvt_pk_f32_fp8_e32 v[244:245], v157
	v_pk_fma_f32 v[12:13], v[240:241], v[226:227], v[12:13] op_sel:[0,1,0]
	v_cvt_pk_f32_fp8_sdwa v[240:241], v157 src0_sel:WORD_1
	v_pk_fma_f32 v[14:15], v[242:243], v[226:227], v[14:15] op_sel:[0,1,0]
	v_cvt_pk_f32_fp8_e32 v[242:243], v158
	v_sub_f32_e32 v228, v228, v216
	v_pk_fma_f32 v[8:9], v[244:245], v[226:227], v[8:9] op_sel:[0,1,0]
	v_cvt_pk_f32_fp8_sdwa v[244:245], v158 src0_sel:WORD_1
	v_pk_fma_f32 v[10:11], v[240:241], v[226:227], v[10:11] op_sel:[0,1,0]
	v_cvt_pk_f32_fp8_e32 v[240:241], v159
	v_exp_f32_e32 v228, v228
	v_pk_fma_f32 v[4:5], v[242:243], v[226:227], v[4:5] op_sel:[0,1,0]
	v_cvt_pk_f32_fp8_sdwa v[242:243], v159 src0_sel:WORD_1
	v_pk_fma_f32 v[6:7], v[244:245], v[226:227], v[6:7] op_sel:[0,1,0]
	v_add_f32_e32 v215, v215, v227
	v_pk_fma_f32 v[0:1], v[240:241], v[226:227], v[0:1] op_sel:[0,1,0]
	v_pk_fma_f32 v[2:3], v[242:243], v[226:227], v[2:3] op_sel:[0,1,0]
	v_readlane_b32 s0, v135, 37
	s_lshl_b32 s0, s0, 10
	s_add_u32 s4, s6, s0
	s_addc_u32 s5, s7, 0
	global_load_dwordx4 v[156:159], v16, s[4:5]
	s_waitcnt vmcnt(15)
	v_cvt_pk_f32_fp8_e32 v[240:241], v160
	v_cvt_pk_f32_fp8_sdwa v[242:243], v160 src0_sel:WORD_1
	v_cvt_pk_f32_fp8_e32 v[244:245], v161
	v_pk_fma_f32 v[12:13], v[240:241], v[228:229], v[12:13] op_sel_hi:[1,0,1]
	v_cvt_pk_f32_fp8_sdwa v[240:241], v161 src0_sel:WORD_1
	v_pk_fma_f32 v[14:15], v[242:243], v[228:229], v[14:15] op_sel_hi:[1,0,1]
	v_cvt_pk_f32_fp8_e32 v[242:243], v162
	v_sub_f32_e32 v229, v229, v216
	v_pk_fma_f32 v[8:9], v[244:245], v[228:229], v[8:9] op_sel_hi:[1,0,1]
	v_cvt_pk_f32_fp8_sdwa v[244:245], v162 src0_sel:WORD_1
	v_pk_fma_f32 v[10:11], v[240:241], v[228:229], v[10:11] op_sel_hi:[1,0,1]
	v_cvt_pk_f32_fp8_e32 v[240:241], v163
	v_exp_f32_e32 v229, v229
	v_pk_fma_f32 v[4:5], v[242:243], v[228:229], v[4:5] op_sel_hi:[1,0,1]
	v_cvt_pk_f32_fp8_sdwa v[242:243], v163 src0_sel:WORD_1
	v_pk_fma_f32 v[6:7], v[244:245], v[228:229], v[6:7] op_sel_hi:[1,0,1]
	v_add_f32_e32 v215, v215, v228
	v_pk_fma_f32 v[0:1], v[240:241], v[228:229], v[0:1] op_sel_hi:[1,0,1]
	v_pk_fma_f32 v[2:3], v[242:243], v[228:229], v[2:3] op_sel_hi:[1,0,1]
	v_readlane_b32 s0, v135, 38
	s_lshl_b32 s0, s0, 10
	s_add_u32 s4, s6, s0
	s_addc_u32 s5, s7, 0
	global_load_dwordx4 v[160:163], v16, s[4:5]
	s_waitcnt vmcnt(15)
	v_cvt_pk_f32_fp8_e32 v[240:241], v164
	v_cvt_pk_f32_fp8_sdwa v[242:243], v164 src0_sel:WORD_1
	v_cvt_pk_f32_fp8_e32 v[244:245], v165
	v_pk_fma_f32 v[12:13], v[240:241], v[228:229], v[12:13] op_sel:[0,1,0]
	v_cvt_pk_f32_fp8_sdwa v[240:241], v165 src0_sel:WORD_1
	v_pk_fma_f32 v[14:15], v[242:243], v[228:229], v[14:15] op_sel:[0,1,0]
	v_cvt_pk_f32_fp8_e32 v[242:243], v166
	v_sub_f32_e32 v230, v230, v216
	v_pk_fma_f32 v[8:9], v[244:245], v[228:229], v[8:9] op_sel:[0,1,0]
	v_cvt_pk_f32_fp8_sdwa v[244:245], v166 src0_sel:WORD_1
	v_pk_fma_f32 v[10:11], v[240:241], v[228:229], v[10:11] op_sel:[0,1,0]
	v_cvt_pk_f32_fp8_e32 v[240:241], v167
	v_exp_f32_e32 v230, v230
	v_pk_fma_f32 v[4:5], v[242:243], v[228:229], v[4:5] op_sel:[0,1,0]
	v_cvt_pk_f32_fp8_sdwa v[242:243], v167 src0_sel:WORD_1
	v_pk_fma_f32 v[6:7], v[244:245], v[228:229], v[6:7] op_sel:[0,1,0]
	v_add_f32_e32 v215, v215, v229
	v_pk_fma_f32 v[0:1], v[240:241], v[228:229], v[0:1] op_sel:[0,1,0]
	v_pk_fma_f32 v[2:3], v[242:243], v[228:229], v[2:3] op_sel:[0,1,0]
	v_readlane_b32 s0, v135, 39
	s_lshl_b32 s0, s0, 10
	s_add_u32 s4, s6, s0
	s_addc_u32 s5, s7, 0
	global_load_dwordx4 v[164:167], v16, s[4:5]
	s_waitcnt vmcnt(15)
	v_cvt_pk_f32_fp8_e32 v[240:241], v168
	v_cvt_pk_f32_fp8_sdwa v[242:243], v168 src0_sel:WORD_1
	v_cvt_pk_f32_fp8_e32 v[244:245], v169
	v_pk_fma_f32 v[12:13], v[240:241], v[230:231], v[12:13] op_sel_hi:[1,0,1]
	v_cvt_pk_f32_fp8_sdwa v[240:241], v169 src0_sel:WORD_1
	v_pk_fma_f32 v[14:15], v[242:243], v[230:231], v[14:15] op_sel_hi:[1,0,1]
	v_cvt_pk_f32_fp8_e32 v[242:243], v170
	v_sub_f32_e32 v231, v231, v216
	v_pk_fma_f32 v[8:9], v[244:245], v[230:231], v[8:9] op_sel_hi:[1,0,1]
	v_cvt_pk_f32_fp8_sdwa v[244:245], v170 src0_sel:WORD_1
	v_pk_fma_f32 v[10:11], v[240:241], v[230:231], v[10:11] op_sel_hi:[1,0,1]
	v_cvt_pk_f32_fp8_e32 v[240:241], v171
	v_exp_f32_e32 v231, v231
	v_pk_fma_f32 v[4:5], v[242:243], v[230:231], v[4:5] op_sel_hi:[1,0,1]
	v_cvt_pk_f32_fp8_sdwa v[242:243], v171 src0_sel:WORD_1
	v_pk_fma_f32 v[6:7], v[244:245], v[230:231], v[6:7] op_sel_hi:[1,0,1]
	v_add_f32_e32 v215, v215, v230
	v_pk_fma_f32 v[0:1], v[240:241], v[230:231], v[0:1] op_sel_hi:[1,0,1]
	v_pk_fma_f32 v[2:3], v[242:243], v[230:231], v[2:3] op_sel_hi:[1,0,1]
	v_readlane_b32 s0, v135, 40
	s_lshl_b32 s0, s0, 10
	s_add_u32 s4, s6, s0
	s_addc_u32 s5, s7, 0
	global_load_dwordx4 v[168:171], v16, s[4:5]
	s_waitcnt vmcnt(15)
	v_cvt_pk_f32_fp8_e32 v[240:241], v172
	v_cvt_pk_f32_fp8_sdwa v[242:243], v172 src0_sel:WORD_1
	v_cvt_pk_f32_fp8_e32 v[244:245], v173
	v_pk_fma_f32 v[12:13], v[240:241], v[230:231], v[12:13] op_sel:[0,1,0]
	v_cvt_pk_f32_fp8_sdwa v[240:241], v173 src0_sel:WORD_1
	v_pk_fma_f32 v[14:15], v[242:243], v[230:231], v[14:15] op_sel:[0,1,0]
	v_cvt_pk_f32_fp8_e32 v[242:243], v174
	v_sub_f32_e32 v232, v232, v216
	v_pk_fma_f32 v[8:9], v[244:245], v[230:231], v[8:9] op_sel:[0,1,0]
	v_cvt_pk_f32_fp8_sdwa v[244:245], v174 src0_sel:WORD_1
	v_pk_fma_f32 v[10:11], v[240:241], v[230:231], v[10:11] op_sel:[0,1,0]
	v_cvt_pk_f32_fp8_e32 v[240:241], v175
	v_exp_f32_e32 v232, v232
	v_pk_fma_f32 v[4:5], v[242:243], v[230:231], v[4:5] op_sel:[0,1,0]
	v_cvt_pk_f32_fp8_sdwa v[242:243], v175 src0_sel:WORD_1
	v_pk_fma_f32 v[6:7], v[244:245], v[230:231], v[6:7] op_sel:[0,1,0]
	v_add_f32_e32 v215, v215, v231
	v_pk_fma_f32 v[0:1], v[240:241], v[230:231], v[0:1] op_sel:[0,1,0]
	v_pk_fma_f32 v[2:3], v[242:243], v[230:231], v[2:3] op_sel:[0,1,0]
	v_readlane_b32 s0, v135, 41
	s_lshl_b32 s0, s0, 10
	s_add_u32 s4, s6, s0
	s_addc_u32 s5, s7, 0
	global_load_dwordx4 v[172:175], v16, s[4:5]
	s_waitcnt vmcnt(15)
; DI void topk_phase(const bf16_t* PROJ, const unsigned char* K8, const unsigned char* V8, const unsigned short* SC, bf16_t* ODSA, int c, char* smem, int bid, int nb) {
;     ...
;         const float mn = fmaxf(m_run, da), al = __builtin_amdgcn_exp2f(m_run - mn), pp = __builtin_amdgcn_exp2f(da - mn);
;         m_run = mn; l_run = l_run * al + pp;
; #pragma unroll
;         for (int i = 0; i < 4; ++i) {
;           const f32x2v lo = __builtin_amdgcn_cvt_pk_f32_fp8((int)u[i], false), hi = __builtin_amdgcn_cvt_pk_f32_fp8((int)u[i], true);
;           ov[4 * i] = ov[4 * i] * al + pp * lo[0]; ov[4 * i + 1] = ov[4 * i + 1] * al + pp * lo[1];
;           ov[4 * i + 2] = ov[4 * i + 2] * al + pp * hi[0]; ov[4 * i + 3] = ov[4 * i + 3] * al + pp * hi[1];
;         }
	v_cvt_pk_f32_fp8_e32 v[240:241], v176
	v_cvt_pk_f32_fp8_sdwa v[242:243], v176 src0_sel:WORD_1
	v_cvt_pk_f32_fp8_e32 v[244:245], v177
	v_pk_fma_f32 v[12:13], v[240:241], v[232:233], v[12:13] op_sel_hi:[1,0,1]
	v_cvt_pk_f32_fp8_sdwa v[240:241], v177 src0_sel:WORD_1
	v_pk_fma_f32 v[14:15], v[242:243], v[232:233], v[14:15] op_sel_hi:[1,0,1]
	v_cvt_pk_f32_fp8_e32 v[242:243], v178
	v_sub_f32_e32 v233, v233, v216
	v_pk_fma_f32 v[8:9], v[244:245], v[232:233], v[8:9] op_sel_hi:[1,0,1]
	v_cvt_pk_f32_fp8_sdwa v[244:245], v178 src0_sel:WORD_1
	v_pk_fma_f32 v[10:11], v[240:241], v[232:233], v[10:11] op_sel_hi:[1,0,1]
	v_cvt_pk_f32_fp8_e32 v[240:241], v179
	v_exp_f32_e32 v233, v233
	v_pk_fma_f32 v[4:5], v[242:243], v[232:233], v[4:5] op_sel_hi:[1,0,1]
	v_cvt_pk_f32_fp8_sdwa v[242:243], v179 src0_sel:WORD_1
	v_pk_fma_f32 v[6:7], v[244:245], v[232:233], v[6:7] op_sel_hi:[1,0,1]
	v_add_f32_e32 v215, v215, v232
	v_pk_fma_f32 v[0:1], v[240:241], v[232:233], v[0:1] op_sel_hi:[1,0,1]
	v_pk_fma_f32 v[2:3], v[242:243], v[232:233], v[2:3] op_sel_hi:[1,0,1]
	v_readlane_b32 s0, v135, 42
	s_lshl_b32 s0, s0, 10
	s_add_u32 s4, s6, s0
	s_addc_u32 s5, s7, 0
	global_load_dwordx4 v[176:179], v16, s[4:5]
	s_waitcnt vmcnt(15)
	v_cvt_pk_f32_fp8_e32 v[240:241], v180
	v_cvt_pk_f32_fp8_sdwa v[242:243], v180 src0_sel:WORD_1
	v_cvt_pk_f32_fp8_e32 v[244:245], v181
	v_pk_fma_f32 v[12:13], v[240:241], v[232:233], v[12:13] op_sel:[0,1,0]
	v_cvt_pk_f32_fp8_sdwa v[240:241], v181 src0_sel:WORD_1
	v_pk_fma_f32 v[14:15], v[242:243], v[232:233], v[14:15] op_sel:[0,1,0]
	v_cvt_pk_f32_fp8_e32 v[242:243], v182
	v_sub_f32_e32 v236, v236, v216
	v_pk_fma_f32 v[8:9], v[244:245], v[232:233], v[8:9] op_sel:[0,1,0]
	v_cvt_pk_f32_fp8_sdwa v[244:245], v182 src0_sel:WORD_1
	v_pk_fma_f32 v[10:11], v[240:241], v[232:233], v[10:11] op_sel:[0,1,0]
	v_cvt_pk_f32_fp8_e32 v[240:241], v183
	v_exp_f32_e32 v236, v236
	v_pk_fma_f32 v[4:5], v[242:243], v[232:233], v[4:5] op_sel:[0,1,0]
	v_cvt_pk_f32_fp8_sdwa v[242:243], v183 src0_sel:WORD_1
	v_pk_fma_f32 v[6:7], v[244:245], v[232:233], v[6:7] op_sel:[0,1,0]
	v_add_f32_e32 v215, v215, v233
	v_pk_fma_f32 v[0:1], v[240:241], v[232:233], v[0:1] op_sel:[0,1,0]
	v_pk_fma_f32 v[2:3], v[242:243], v[232:233], v[2:3] op_sel:[0,1,0]
	v_readlane_b32 s0, v135, 43
	s_lshl_b32 s0, s0, 10
	s_add_u32 s4, s6, s0
	s_addc_u32 s5, s7, 0
	global_load_dwordx4 v[180:183], v16, s[4:5]
	s_waitcnt vmcnt(15)
	v_cvt_pk_f32_fp8_e32 v[240:241], v186
	v_cvt_pk_f32_fp8_sdwa v[242:243], v186 src0_sel:WORD_1
	v_cvt_pk_f32_fp8_e32 v[244:245], v187
	v_pk_fma_f32 v[12:13], v[240:241], v[236:237], v[12:13] op_sel_hi:[1,0,1]
	v_cvt_pk_f32_fp8_sdwa v[240:241], v187 src0_sel:WORD_1
	v_pk_fma_f32 v[14:15], v[242:243], v[236:237], v[14:15] op_sel_hi:[1,0,1]
	v_cvt_pk_f32_fp8_e32 v[242:243], v188
	v_sub_f32_e32 v237, v237, v216
	v_pk_fma_f32 v[8:9], v[244:245], v[236:237], v[8:9] op_sel_hi:[1,0,1]
	v_cvt_pk_f32_fp8_sdwa v[244:245], v188 src0_sel:WORD_1
	v_pk_fma_f32 v[10:11], v[240:241], v[236:237], v[10:11] op_sel_hi:[1,0,1]
	v_cvt_pk_f32_fp8_e32 v[240:241], v189
	v_exp_f32_e32 v237, v237
	v_pk_fma_f32 v[4:5], v[242:243], v[236:237], v[4:5] op_sel_hi:[1,0,1]
	v_cvt_pk_f32_fp8_sdwa v[242:243], v189 src0_sel:WORD_1
	v_pk_fma_f32 v[6:7], v[244:245], v[236:237], v[6:7] op_sel_hi:[1,0,1]
	v_add_f32_e32 v215, v215, v236
	v_pk_fma_f32 v[0:1], v[240:241], v[236:237], v[0:1] op_sel_hi:[1,0,1]
	v_pk_fma_f32 v[2:3], v[242:243], v[236:237], v[2:3] op_sel_hi:[1,0,1]
	v_readlane_b32 s0, v135, 44
	s_lshl_b32 s0, s0, 10
	s_add_u32 s4, s6, s0
	s_addc_u32 s5, s7, 0
	global_load_dwordx4 v[186:189], v16, s[4:5]
	s_waitcnt vmcnt(15)
	v_cvt_pk_f32_fp8_e32 v[240:241], v190
	v_cvt_pk_f32_fp8_sdwa v[242:243], v190 src0_sel:WORD_1
	v_cvt_pk_f32_fp8_e32 v[244:245], v191
	v_pk_fma_f32 v[12:13], v[240:241], v[236:237], v[12:13] op_sel:[0,1,0]
	v_cvt_pk_f32_fp8_sdwa v[240:241], v191 src0_sel:WORD_1
	v_pk_fma_f32 v[14:15], v[242:243], v[236:237], v[14:15] op_sel:[0,1,0]
	v_cvt_pk_f32_fp8_e32 v[242:243], v192
	v_sub_f32_e32 v238, v238, v216
	v_pk_fma_f32 v[8:9], v[244:245], v[236:237], v[8:9] op_sel:[0,1,0]
	v_cvt_pk_f32_fp8_sdwa v[244:245], v192 src0_sel:WORD_1
	v_pk_fma_f32 v[10:11], v[240:241], v[236:237], v[10:11] op_sel:[0,1,0]
	v_cvt_pk_f32_fp8_e32 v[240:241], v193
	v_exp_f32_e32 v238, v238
	v_pk_fma_f32 v[4:5], v[242:243], v[236:237], v[4:5] op_sel:[0,1,0]
	v_cvt_pk_f32_fp8_sdwa v[242:243], v193 src0_sel:WORD_1
	v_pk_fma_f32 v[6:7], v[244:245], v[236:237], v[6:7] op_sel:[0,1,0]
	v_add_f32_e32 v215, v215, v237
	v_pk_fma_f32 v[0:1], v[240:241], v[236:237], v[0:1] op_sel:[0,1,0]
	v_pk_fma_f32 v[2:3], v[242:243], v[236:237], v[2:3] op_sel:[0,1,0]
	v_readlane_b32 s0, v135, 45
	s_lshl_b32 s0, s0, 10
	s_add_u32 s4, s6, s0
	s_addc_u32 s5, s7, 0
	global_load_dwordx4 v[190:193], v16, s[4:5]
	s_waitcnt vmcnt(15)
	v_cvt_pk_f32_fp8_e32 v[240:241], v194
	v_cvt_pk_f32_fp8_sdwa v[242:243], v194 src0_sel:WORD_1
	v_cvt_pk_f32_fp8_e32 v[244:245], v195
	v_pk_fma_f32 v[12:13], v[240:241], v[238:239], v[12:13] op_sel_hi:[1,0,1]
	v_cvt_pk_f32_fp8_sdwa v[240:241], v195 src0_sel:WORD_1
	v_pk_fma_f32 v[14:15], v[242:243], v[238:239], v[14:15] op_sel_hi:[1,0,1]
	v_cvt_pk_f32_fp8_e32 v[242:243], v196
	v_sub_f32_e32 v239, v239, v216
	v_pk_fma_f32 v[8:9], v[244:245], v[238:239], v[8:9] op_sel_hi:[1,0,1]
	v_cvt_pk_f32_fp8_sdwa v[244:245], v196 src0_sel:WORD_1
	v_pk_fma_f32 v[10:11], v[240:241], v[238:239], v[10:11] op_sel_hi:[1,0,1]
	v_cvt_pk_f32_fp8_e32 v[240:241], v197
	v_exp_f32_e32 v239, v239
	v_pk_fma_f32 v[4:5], v[242:243], v[238:239], v[4:5] op_sel_hi:[1,0,1]
	v_cvt_pk_f32_fp8_sdwa v[242:243], v197 src0_sel:WORD_1
	v_pk_fma_f32 v[6:7], v[244:245], v[238:239], v[6:7] op_sel_hi:[1,0,1]
	v_add_f32_e32 v215, v215, v238
	v_pk_fma_f32 v[0:1], v[240:241], v[238:239], v[0:1] op_sel_hi:[1,0,1]
	v_pk_fma_f32 v[2:3], v[242:243], v[238:239], v[2:3] op_sel_hi:[1,0,1]
	v_readlane_b32 s0, v135, 46
	s_lshl_b32 s0, s0, 10
	s_add_u32 s4, s6, s0
	s_addc_u32 s5, s7, 0
	global_load_dwordx4 v[194:197], v16, s[4:5]
	s_waitcnt vmcnt(15)
; DI float sum8(float v) { v += DPPF(v, 0xB1); v += DPPF(v, 0x4E); v += DPPF(v, 0x141); return v; }
; DI void topk_phase(const bf16_t* PROJ, const unsigned char* K8, const unsigned char* V8, const unsigned short* SC, bf16_t* ODSA, int c, char* smem, int bid, int nb) {
;     ...
;         const size_t ro = (size_t)__builtin_amdgcn_readlane(mysel, jj) * 1024 + lane * 16;
;         const uint4 a = *(const uint4*)(K8 + ro), vv = *(const uint4*)(V8 + ro);
;         const unsigned w[4] = {a.x, a.y, a.z, a.w}, u[4] = {vv.x, vv.y, vv.z, vv.w};
;         float da = 0.f;
; #pragma unroll
;         for (int i = 0; i < 4; ++i) {
;           const f32x2v lo = __builtin_amdgcn_cvt_pk_f32_fp8((int)w[i], false), hi = __builtin_amdgcn_cvt_pk_f32_fp8((int)w[i], true);
;           da += qv[4 * i] * lo[0] + qv[4 * i + 1] * lo[1] + qv[4 * i + 2] * hi[0] + qv[4 * i + 3] * hi[1];
;         }
;         da = sum8(da);
;         da = j < count ? da : -3e30f;
;         const float mn = fmaxf(m_run, da), al = __builtin_amdgcn_exp2f(m_run - mn), pp = __builtin_amdgcn_exp2f(da - mn);
;         m_run = mn; l_run = l_run * al + pp;
; #pragma unroll
;         for (int i = 0; i < 4; ++i) {
;           const f32x2v lo = __builtin_amdgcn_cvt_pk_f32_fp8((int)u[i], false), hi = __builtin_amdgcn_cvt_pk_f32_fp8((int)u[i], true);
;           ov[4 * i] = ov[4 * i] * al + pp * lo[0]; ov[4 * i + 1] = ov[4 * i + 1] * al + pp * lo[1];
;           ov[4 * i + 2] = ov[4 * i + 2] * al + pp * hi[0]; ov[4 * i + 3] = ov[4 * i + 3] * al + pp * hi[1];
;         }
	v_cvt_pk_f32_fp8_e32 v[240:241], v198
	v_cvt_pk_f32_fp8_sdwa v[242:243], v198 src0_sel:WORD_1
	v_cvt_pk_f32_fp8_e32 v[244:245], v199
	v_pk_fma_f32 v[12:13], v[240:241], v[238:239], v[12:13] op_sel:[0,1,0]
	v_cvt_pk_f32_fp8_sdwa v[240:241], v199 src0_sel:WORD_1
	v_pk_fma_f32 v[14:15], v[242:243], v[238:239], v[14:15] op_sel:[0,1,0]
	v_cvt_pk_f32_fp8_e32 v[242:243], v200
	v_add_f32_e32 v215, v215, v239
	v_pk_fma_f32 v[8:9], v[244:245], v[238:239], v[8:9] op_sel:[0,1,0]
	v_cvt_pk_f32_fp8_sdwa v[244:245], v200 src0_sel:WORD_1
	v_pk_fma_f32 v[10:11], v[240:241], v[238:239], v[10:11] op_sel:[0,1,0]
	v_cvt_pk_f32_fp8_e32 v[240:241], v201
	v_pk_fma_f32 v[4:5], v[242:243], v[238:239], v[4:5] op_sel:[0,1,0]
	v_cvt_pk_f32_fp8_sdwa v[242:243], v201 src0_sel:WORD_1
	v_pk_fma_f32 v[6:7], v[244:245], v[238:239], v[6:7] op_sel:[0,1,0]
	v_pk_fma_f32 v[0:1], v[240:241], v[238:239], v[0:1] op_sel:[0,1,0]
	v_pk_fma_f32 v[2:3], v[242:243], v[238:239], v[2:3] op_sel:[0,1,0]
	v_readlane_b32 s0, v135, 47
	s_lshl_b32 s0, s0, 10
	s_add_u32 s4, s6, s0
	s_addc_u32 s5, s7, 0
	global_load_dwordx4 v[198:201], v16, s[4:5]
	s_waitcnt vmcnt(15)
	v_cvt_pk_f32_fp8_e32 v[240:241], v136
	v_cvt_pk_f32_fp8_sdwa v[242:243], v136 src0_sel:WORD_1
	v_cvt_pk_f32_fp8_e32 v[244:245], v137
	v_cvt_pk_f32_fp8_sdwa v[202:203], v137 src0_sel:WORD_1
	v_pk_mul_f32 v[204:205], v[240:241], v[52:53]
	v_pk_mul_f32 v[206:207], v[242:243], v[54:55]
	v_cvt_pk_f32_fp8_e32 v[240:241], v138
	v_cvt_pk_f32_fp8_sdwa v[242:243], v138 src0_sel:WORD_1
	v_pk_fma_f32 v[204:205], v[244:245], v[56:57], v[204:205]
	v_pk_fma_f32 v[206:207], v[202:203], v[58:59], v[206:207]
	v_cvt_pk_f32_fp8_e32 v[244:245], v139
	v_cvt_pk_f32_fp8_sdwa v[202:203], v139 src0_sel:WORD_1
	v_pk_fma_f32 v[204:205], v[240:241], v[60:61], v[204:205]
	v_pk_fma_f32 v[206:207], v[242:243], v[62:63], v[206:207]
	v_pk_fma_f32 v[204:205], v[244:245], v[64:65], v[204:205]
	v_pk_fma_f32 v[206:207], v[202:203], v[66:67], v[206:207]
	v_readlane_b32 s0, v135, 32
	s_lshl_b32 s0, s0, 10
	s_add_u32 s4, s8, s0
	s_addc_u32 s5, s9, 0
	global_load_dwordx4 v[136:139], v16, s[4:5]
	v_pk_add_f32 v[204:205], v[204:205], v[206:207]
	s_nop 0
	v_add_f32_e32 v235, v204, v205
	s_waitcnt vmcnt(15)
	v_cvt_pk_f32_fp8_e32 v[240:241], v140
	v_cvt_pk_f32_fp8_sdwa v[242:243], v140 src0_sel:WORD_1
	v_cvt_pk_f32_fp8_e32 v[244:245], v141
	v_cvt_pk_f32_fp8_sdwa v[202:203], v141 src0_sel:WORD_1
	v_add_f32_dpp v235, v235, v235 quad_perm:[1,0,3,2] row_mask:0xf bank_mask:0xf bound_ctrl:1
	v_pk_mul_f32 v[204:205], v[240:241], v[52:53]
	v_pk_mul_f32 v[206:207], v[242:243], v[54:55]
	v_add_f32_dpp v235, v235, v235 quad_perm:[2,3,0,1] row_mask:0xf bank_mask:0xf bound_ctrl:1
	v_cvt_pk_f32_fp8_e32 v[240:241], v142
	v_cvt_pk_f32_fp8_sdwa v[242:243], v142 src0_sel:WORD_1
	v_add_f32_dpp v235, v235, v235 row_half_mirror row_mask:0xf bank_mask:0xf bound_ctrl:1
	v_pk_fma_f32 v[204:205], v[244:245], v[56:57], v[204:205]
	v_pk_fma_f32 v[206:207], v[202:203], v[58:59], v[206:207]
	s_add_i32 s0, s1, 32
	s_cmp_lt_i32 s0, s2
	s_cselect_b64 vcc, -1, 0
	v_cvt_pk_f32_fp8_e32 v[244:245], v143
	v_cvt_pk_f32_fp8_sdwa v[202:203], v143 src0_sel:WORD_1
	v_cndmask_b32_e32 v210, v220, v235, vcc
	v_pk_fma_f32 v[204:205], v[240:241], v[60:61], v[204:205]
	v_pk_fma_f32 v[206:207], v[242:243], v[62:63], v[206:207]
	v_pk_fma_f32 v[204:205], v[244:245], v[64:65], v[204:205]
	v_pk_fma_f32 v[206:207], v[202:203], v[66:67], v[206:207]
	v_readlane_b32 s0, v135, 33
	s_lshl_b32 s0, s0, 10
	s_add_u32 s4, s8, s0
	s_addc_u32 s5, s9, 0
	global_load_dwordx4 v[140:143], v16, s[4:5]
	v_pk_add_f32 v[204:205], v[204:205], v[206:207]
	s_nop 0
	v_add_f32_e32 v221, v204, v205
	s_waitcnt vmcnt(15)
	v_cvt_pk_f32_fp8_e32 v[240:241], v144
	v_cvt_pk_f32_fp8_sdwa v[242:243], v144 src0_sel:WORD_1
	v_cvt_pk_f32_fp8_e32 v[244:245], v145
	v_cvt_pk_f32_fp8_sdwa v[202:203], v145 src0_sel:WORD_1
	v_add_f32_dpp v221, v221, v221 quad_perm:[1,0,3,2] row_mask:0xf bank_mask:0xf bound_ctrl:1
	v_pk_mul_f32 v[204:205], v[240:241], v[52:53]
	v_pk_mul_f32 v[206:207], v[242:243], v[54:55]
	v_add_f32_dpp v221, v221, v221 quad_perm:[2,3,0,1] row_mask:0xf bank_mask:0xf bound_ctrl:1
	v_cvt_pk_f32_fp8_e32 v[240:241], v146
	v_cvt_pk_f32_fp8_sdwa v[242:243], v146 src0_sel:WORD_1
	v_add_f32_dpp v221, v221, v221 row_half_mirror row_mask:0xf bank_mask:0xf bound_ctrl:1
	v_pk_fma_f32 v[204:205], v[244:245], v[56:57], v[204:205]
	v_pk_fma_f32 v[206:207], v[202:203], v[58:59], v[206:207]
	s_add_i32 s0, s1, 33
	s_cmp_lt_i32 s0, s2
	s_cselect_b64 vcc, -1, 0
	v_cvt_pk_f32_fp8_e32 v[244:245], v147
	v_cvt_pk_f32_fp8_sdwa v[202:203], v147 src0_sel:WORD_1
	v_cndmask_b32_e32 v211, v220, v221, vcc
	v_pk_fma_f32 v[204:205], v[240:241], v[60:61], v[204:205]
	v_pk_fma_f32 v[206:207], v[242:243], v[62:63], v[206:207]
	v_pk_fma_f32 v[204:205], v[244:245], v[64:65], v[204:205]
	v_pk_fma_f32 v[206:207], v[202:203], v[66:67], v[206:207]
	v_readlane_b32 s0, v135, 34
	s_lshl_b32 s0, s0, 10
	s_add_u32 s4, s8, s0
	s_addc_u32 s5, s9, 0
	global_load_dwordx4 v[144:147], v16, s[4:5]
	v_pk_add_f32 v[204:205], v[204:205], v[206:207]
	s_nop 0
	v_add_f32_e32 v235, v204, v205
	s_waitcnt vmcnt(15)
; DI float sum8(float v) { v += DPPF(v, 0xB1); v += DPPF(v, 0x4E); v += DPPF(v, 0x141); return v; }
; DI void topk_phase(const bf16_t* PROJ, const unsigned char* K8, const unsigned char* V8, const unsigned short* SC, bf16_t* ODSA, int c, char* smem, int bid, int nb) {
;     ...
;         const size_t ro = (size_t)__builtin_amdgcn_readlane(mysel, jj) * 1024 + lane * 16;
;         const uint4 a = *(const uint4*)(K8 + ro), vv = *(const uint4*)(V8 + ro);
;         const unsigned w[4] = {a.x, a.y, a.z, a.w}, u[4] = {vv.x, vv.y, vv.z, vv.w};
;         float da = 0.f;
; #pragma unroll
;         for (int i = 0; i < 4; ++i) {
;           const f32x2v lo = __builtin_amdgcn_cvt_pk_f32_fp8((int)w[i], false), hi = __builtin_amdgcn_cvt_pk_f32_fp8((int)w[i], true);
;           da += qv[4 * i] * lo[0] + qv[4 * i + 1] * lo[1] + qv[4 * i + 2] * hi[0] + qv[4 * i + 3] * hi[1];
;         }
;         da = sum8(da);
;         da = j < count ? da : -3e30f;
;         const float mn = fmaxf(m_run, da), al = __builtin_amdgcn_exp2f(m_run - mn), pp = __builtin_amdgcn_exp2f(da - mn);
;         m_run = mn; l_run = l_run * al + pp;
	v_cvt_pk_f32_fp8_e32 v[240:241], v148
	v_cvt_pk_f32_fp8_sdwa v[242:243], v148 src0_sel:WORD_1
	v_cvt_pk_f32_fp8_e32 v[244:245], v149
	v_cvt_pk_f32_fp8_sdwa v[202:203], v149 src0_sel:WORD_1
	v_add_f32_dpp v235, v235, v235 quad_perm:[1,0,3,2] row_mask:0xf bank_mask:0xf bound_ctrl:1
	v_pk_mul_f32 v[204:205], v[240:241], v[52:53]
	v_pk_mul_f32 v[206:207], v[242:243], v[54:55]
	v_add_f32_dpp v235, v235, v235 quad_perm:[2,3,0,1] row_mask:0xf bank_mask:0xf bound_ctrl:1
	v_cvt_pk_f32_fp8_e32 v[240:241], v150
	v_cvt_pk_f32_fp8_sdwa v[242:243], v150 src0_sel:WORD_1
	v_add_f32_dpp v235, v235, v235 row_half_mirror row_mask:0xf bank_mask:0xf bound_ctrl:1
	v_pk_fma_f32 v[204:205], v[244:245], v[56:57], v[204:205]
	v_pk_fma_f32 v[206:207], v[202:203], v[58:59], v[206:207]
	s_add_i32 s0, s1, 34
	s_cmp_lt_i32 s0, s2
	s_cselect_b64 vcc, -1, 0
	v_cvt_pk_f32_fp8_e32 v[244:245], v151
	v_cvt_pk_f32_fp8_sdwa v[202:203], v151 src0_sel:WORD_1
	v_cndmask_b32_e32 v212, v220, v235, vcc
	v_pk_fma_f32 v[204:205], v[240:241], v[60:61], v[204:205]
	v_pk_fma_f32 v[206:207], v[242:243], v[62:63], v[206:207]
	v_pk_fma_f32 v[204:205], v[244:245], v[64:65], v[204:205]
	v_pk_fma_f32 v[206:207], v[202:203], v[66:67], v[206:207]
	v_readlane_b32 s0, v135, 35
	s_lshl_b32 s0, s0, 10
	s_add_u32 s4, s8, s0
	s_addc_u32 s5, s9, 0
	global_load_dwordx4 v[148:151], v16, s[4:5]
	v_pk_add_f32 v[204:205], v[204:205], v[206:207]
	s_nop 0
	v_add_f32_e32 v221, v204, v205
	s_waitcnt vmcnt(15)
	v_cvt_pk_f32_fp8_e32 v[240:241], v152
	v_cvt_pk_f32_fp8_sdwa v[242:243], v152 src0_sel:WORD_1
	v_cvt_pk_f32_fp8_e32 v[244:245], v153
	v_cvt_pk_f32_fp8_sdwa v[202:203], v153 src0_sel:WORD_1
	v_add_f32_dpp v221, v221, v221 quad_perm:[1,0,3,2] row_mask:0xf bank_mask:0xf bound_ctrl:1
	v_pk_mul_f32 v[204:205], v[240:241], v[52:53]
	v_pk_mul_f32 v[206:207], v[242:243], v[54:55]
	v_add_f32_dpp v221, v221, v221 quad_perm:[2,3,0,1] row_mask:0xf bank_mask:0xf bound_ctrl:1
	v_cvt_pk_f32_fp8_e32 v[240:241], v154
	v_cvt_pk_f32_fp8_sdwa v[242:243], v154 src0_sel:WORD_1
	v_add_f32_dpp v221, v221, v221 row_half_mirror row_mask:0xf bank_mask:0xf bound_ctrl:1
	v_pk_fma_f32 v[204:205], v[244:245], v[56:57], v[204:205]
	v_pk_fma_f32 v[206:207], v[202:203], v[58:59], v[206:207]
	s_add_i32 s0, s1, 35
	s_cmp_lt_i32 s0, s2
	s_cselect_b64 vcc, -1, 0
	v_cvt_pk_f32_fp8_e32 v[244:245], v155
	v_cvt_pk_f32_fp8_sdwa v[202:203], v155 src0_sel:WORD_1
	v_cndmask_b32_e32 v213, v220, v221, vcc
	v_pk_fma_f32 v[204:205], v[240:241], v[60:61], v[204:205]
	v_pk_fma_f32 v[206:207], v[242:243], v[62:63], v[206:207]
	v_pk_fma_f32 v[204:205], v[244:245], v[64:65], v[204:205]
	v_pk_fma_f32 v[206:207], v[202:203], v[66:67], v[206:207]
	v_readlane_b32 s0, v135, 36
	s_lshl_b32 s0, s0, 10
	s_add_u32 s4, s8, s0
	s_addc_u32 s5, s9, 0
	global_load_dwordx4 v[152:155], v16, s[4:5]
	v_pk_add_f32 v[204:205], v[204:205], v[206:207]
	s_nop 0
	v_add_f32_e32 v235, v204, v205
	s_waitcnt vmcnt(15)
	v_cvt_pk_f32_fp8_e32 v[240:241], v156
	v_cvt_pk_f32_fp8_sdwa v[242:243], v156 src0_sel:WORD_1
	v_cvt_pk_f32_fp8_e32 v[244:245], v157
	v_cvt_pk_f32_fp8_sdwa v[202:203], v157 src0_sel:WORD_1
	v_add_f32_dpp v235, v235, v235 quad_perm:[1,0,3,2] row_mask:0xf bank_mask:0xf bound_ctrl:1
	v_pk_mul_f32 v[204:205], v[240:241], v[52:53]
	v_pk_mul_f32 v[206:207], v[242:243], v[54:55]
	v_add_f32_dpp v235, v235, v235 quad_perm:[2,3,0,1] row_mask:0xf bank_mask:0xf bound_ctrl:1
	v_cvt_pk_f32_fp8_e32 v[240:241], v158
	v_cvt_pk_f32_fp8_sdwa v[242:243], v158 src0_sel:WORD_1
	v_add_f32_dpp v235, v235, v235 row_half_mirror row_mask:0xf bank_mask:0xf bound_ctrl:1
	v_pk_fma_f32 v[204:205], v[244:245], v[56:57], v[204:205]
	v_pk_fma_f32 v[206:207], v[202:203], v[58:59], v[206:207]
	s_add_i32 s0, s1, 36
	s_cmp_lt_i32 s0, s2
	s_cselect_b64 vcc, -1, 0
	v_cvt_pk_f32_fp8_e32 v[244:245], v159
	v_cvt_pk_f32_fp8_sdwa v[202:203], v159 src0_sel:WORD_1
	v_cndmask_b32_e32 v226, v220, v235, vcc
	v_pk_fma_f32 v[204:205], v[240:241], v[60:61], v[204:205]
	v_pk_fma_f32 v[206:207], v[242:243], v[62:63], v[206:207]
	v_pk_fma_f32 v[204:205], v[244:245], v[64:65], v[204:205]
	v_pk_fma_f32 v[206:207], v[202:203], v[66:67], v[206:207]
	v_readlane_b32 s0, v135, 37
	s_lshl_b32 s0, s0, 10
	s_add_u32 s4, s8, s0
	s_addc_u32 s5, s9, 0
	global_load_dwordx4 v[156:159], v16, s[4:5]
	v_pk_add_f32 v[204:205], v[204:205], v[206:207]
	s_nop 0
	v_add_f32_e32 v221, v204, v205
	s_waitcnt vmcnt(15)
	v_cvt_pk_f32_fp8_e32 v[240:241], v160
	v_cvt_pk_f32_fp8_sdwa v[242:243], v160 src0_sel:WORD_1
	v_cvt_pk_f32_fp8_e32 v[244:245], v161
	v_cvt_pk_f32_fp8_sdwa v[202:203], v161 src0_sel:WORD_1
	v_add_f32_dpp v221, v221, v221 quad_perm:[1,0,3,2] row_mask:0xf bank_mask:0xf bound_ctrl:1
	v_pk_mul_f32 v[204:205], v[240:241], v[52:53]
	v_pk_mul_f32 v[206:207], v[242:243], v[54:55]
	v_add_f32_dpp v221, v221, v221 quad_perm:[2,3,0,1] row_mask:0xf bank_mask:0xf bound_ctrl:1
	v_cvt_pk_f32_fp8_e32 v[240:241], v162
	v_cvt_pk_f32_fp8_sdwa v[242:243], v162 src0_sel:WORD_1
	v_add_f32_dpp v221, v221, v221 row_half_mirror row_mask:0xf bank_mask:0xf bound_ctrl:1
	v_pk_fma_f32 v[204:205], v[244:245], v[56:57], v[204:205]
	v_pk_fma_f32 v[206:207], v[202:203], v[58:59], v[206:207]
	s_add_i32 s0, s1, 37
	s_cmp_lt_i32 s0, s2
	s_cselect_b64 vcc, -1, 0
	v_cvt_pk_f32_fp8_e32 v[244:245], v163
	v_cvt_pk_f32_fp8_sdwa v[202:203], v163 src0_sel:WORD_1
	v_cndmask_b32_e32 v227, v220, v221, vcc
	v_pk_fma_f32 v[204:205], v[240:241], v[60:61], v[204:205]
	v_pk_fma_f32 v[206:207], v[242:243], v[62:63], v[206:207]
	v_pk_fma_f32 v[204:205], v[244:245], v[64:65], v[204:205]
	v_pk_fma_f32 v[206:207], v[202:203], v[66:67], v[206:207]
	v_readlane_b32 s0, v135, 38
	s_lshl_b32 s0, s0, 10
	s_add_u32 s4, s8, s0
	s_addc_u32 s5, s9, 0
	global_load_dwordx4 v[160:163], v16, s[4:5]
	v_pk_add_f32 v[204:205], v[204:205], v[206:207]
	s_nop 0
	v_add_f32_e32 v235, v204, v205
	s_waitcnt vmcnt(15)
; DI float sum8(float v) { v += DPPF(v, 0xB1); v += DPPF(v, 0x4E); v += DPPF(v, 0x141); return v; }
; DI void topk_phase(const bf16_t* PROJ, const unsigned char* K8, const unsigned char* V8, const unsigned short* SC, bf16_t* ODSA, int c, char* smem, int bid, int nb) {
;     ...
; #pragma unroll 4
;     for (int jj = 0; jj < 64; ++jj) {
;       const int j = wid * 64 + jj;
;       {
;         const size_t ro = (size_t)__builtin_amdgcn_readlane(mysel, jj) * 1024 + lane * 16;
;         const uint4 a = *(const uint4*)(K8 + ro), vv = *(const uint4*)(V8 + ro);
;         const unsigned w[4] = {a.x, a.y, a.z, a.w}, u[4] = {vv.x, vv.y, vv.z, vv.w};
;         float da = 0.f;
; #pragma unroll
;         for (int i = 0; i < 4; ++i) {
;           const f32x2v lo = __builtin_amdgcn_cvt_pk_f32_fp8((int)w[i], false), hi = __builtin_amdgcn_cvt_pk_f32_fp8((int)w[i], true);
;           da += qv[4 * i] * lo[0] + qv[4 * i + 1] * lo[1] + qv[4 * i + 2] * hi[0] + qv[4 * i + 3] * hi[1];
;         }
;         da = sum8(da);
;         da = j < count ? da : -3e30f;
;         const float mn = fmaxf(m_run, da), al = __builtin_amdgcn_exp2f(m_run - mn), pp = __builtin_amdgcn_exp2f(da - mn);
;         m_run = mn; l_run = l_run * al + pp;
; #pragma unroll
;         for (int i = 0; i < 4; ++i) {
;           const f32x2v lo = __builtin_amdgcn_cvt_pk_f32_fp8((int)u[i], false), hi = __builtin_amdgcn_cvt_pk_f32_fp8((int)u[i], true);
;           ov[4 * i] = ov[4 * i] * al + pp * lo[0]; ov[4 * i + 1] = ov[4 * i + 1] * al + pp * lo[1];
;           ov[4 * i + 2] = ov[4 * i + 2] * al + pp * hi[0]; ov[4 * i + 3] = ov[4 * i + 3] * al + pp * hi[1];
;         }
	v_cvt_pk_f32_fp8_e32 v[240:241], v164
	v_cvt_pk_f32_fp8_sdwa v[242:243], v164 src0_sel:WORD_1
	v_cvt_pk_f32_fp8_e32 v[244:245], v165
	v_cvt_pk_f32_fp8_sdwa v[202:203], v165 src0_sel:WORD_1
	v_add_f32_dpp v235, v235, v235 quad_perm:[1,0,3,2] row_mask:0xf bank_mask:0xf bound_ctrl:1
	v_pk_mul_f32 v[204:205], v[240:241], v[52:53]
	v_pk_mul_f32 v[206:207], v[242:243], v[54:55]
	v_add_f32_dpp v235, v235, v235 quad_perm:[2,3,0,1] row_mask:0xf bank_mask:0xf bound_ctrl:1
	v_cvt_pk_f32_fp8_e32 v[240:241], v166
	v_cvt_pk_f32_fp8_sdwa v[242:243], v166 src0_sel:WORD_1
	v_add_f32_dpp v235, v235, v235 row_half_mirror row_mask:0xf bank_mask:0xf bound_ctrl:1
	v_pk_fma_f32 v[204:205], v[244:245], v[56:57], v[204:205]
	v_pk_fma_f32 v[206:207], v[202:203], v[58:59], v[206:207]
	s_add_i32 s0, s1, 38
	s_cmp_lt_i32 s0, s2
	s_cselect_b64 vcc, -1, 0
	v_cvt_pk_f32_fp8_e32 v[244:245], v167
	v_cvt_pk_f32_fp8_sdwa v[202:203], v167 src0_sel:WORD_1
	v_cndmask_b32_e32 v228, v220, v235, vcc
	v_pk_fma_f32 v[204:205], v[240:241], v[60:61], v[204:205]
	v_pk_fma_f32 v[206:207], v[242:243], v[62:63], v[206:207]
	v_pk_fma_f32 v[204:205], v[244:245], v[64:65], v[204:205]
	v_pk_fma_f32 v[206:207], v[202:203], v[66:67], v[206:207]
	v_readlane_b32 s0, v135, 39
	s_lshl_b32 s0, s0, 10
	s_add_u32 s4, s8, s0
	s_addc_u32 s5, s9, 0
	global_load_dwordx4 v[164:167], v16, s[4:5]
	v_pk_add_f32 v[204:205], v[204:205], v[206:207]
	s_nop 0
	v_add_f32_e32 v221, v204, v205
	s_waitcnt vmcnt(15)
	v_cvt_pk_f32_fp8_e32 v[240:241], v168
	v_cvt_pk_f32_fp8_sdwa v[242:243], v168 src0_sel:WORD_1
	v_cvt_pk_f32_fp8_e32 v[244:245], v169
	v_cvt_pk_f32_fp8_sdwa v[202:203], v169 src0_sel:WORD_1
	v_add_f32_dpp v221, v221, v221 quad_perm:[1,0,3,2] row_mask:0xf bank_mask:0xf bound_ctrl:1
	v_pk_mul_f32 v[204:205], v[240:241], v[52:53]
	v_pk_mul_f32 v[206:207], v[242:243], v[54:55]
	v_add_f32_dpp v221, v221, v221 quad_perm:[2,3,0,1] row_mask:0xf bank_mask:0xf bound_ctrl:1
	v_cvt_pk_f32_fp8_e32 v[240:241], v170
	v_cvt_pk_f32_fp8_sdwa v[242:243], v170 src0_sel:WORD_1
	v_add_f32_dpp v221, v221, v221 row_half_mirror row_mask:0xf bank_mask:0xf bound_ctrl:1
	v_pk_fma_f32 v[204:205], v[244:245], v[56:57], v[204:205]
	v_pk_fma_f32 v[206:207], v[202:203], v[58:59], v[206:207]
	s_add_i32 s0, s1, 39
	s_cmp_lt_i32 s0, s2
	s_cselect_b64 vcc, -1, 0
	v_cvt_pk_f32_fp8_e32 v[244:245], v171
	v_cvt_pk_f32_fp8_sdwa v[202:203], v171 src0_sel:WORD_1
	v_cndmask_b32_e32 v229, v220, v221, vcc
	v_pk_fma_f32 v[204:205], v[240:241], v[60:61], v[204:205]
	v_pk_fma_f32 v[206:207], v[242:243], v[62:63], v[206:207]
	v_pk_fma_f32 v[204:205], v[244:245], v[64:65], v[204:205]
	v_pk_fma_f32 v[206:207], v[202:203], v[66:67], v[206:207]
	v_readlane_b32 s0, v135, 40
	s_lshl_b32 s0, s0, 10
	s_add_u32 s4, s8, s0
	s_addc_u32 s5, s9, 0
	global_load_dwordx4 v[168:171], v16, s[4:5]
	v_pk_add_f32 v[204:205], v[204:205], v[206:207]
	s_nop 0
	v_add_f32_e32 v235, v204, v205
	s_waitcnt vmcnt(15)
	v_cvt_pk_f32_fp8_e32 v[240:241], v172
	v_cvt_pk_f32_fp8_sdwa v[242:243], v172 src0_sel:WORD_1
	v_cvt_pk_f32_fp8_e32 v[244:245], v173
	v_cvt_pk_f32_fp8_sdwa v[202:203], v173 src0_sel:WORD_1
	v_add_f32_dpp v235, v235, v235 quad_perm:[1,0,3,2] row_mask:0xf bank_mask:0xf bound_ctrl:1
	v_pk_mul_f32 v[204:205], v[240:241], v[52:53]
	v_pk_mul_f32 v[206:207], v[242:243], v[54:55]
	v_add_f32_dpp v235, v235, v235 quad_perm:[2,3,0,1] row_mask:0xf bank_mask:0xf bound_ctrl:1
	v_cvt_pk_f32_fp8_e32 v[240:241], v174
	v_cvt_pk_f32_fp8_sdwa v[242:243], v174 src0_sel:WORD_1
	v_add_f32_dpp v235, v235, v235 row_half_mirror row_mask:0xf bank_mask:0xf bound_ctrl:1
	v_pk_fma_f32 v[204:205], v[244:245], v[56:57], v[204:205]
	v_pk_fma_f32 v[206:207], v[202:203], v[58:59], v[206:207]
	s_add_i32 s0, s1, 40
	s_cmp_lt_i32 s0, s2
	s_cselect_b64 vcc, -1, 0
	v_cvt_pk_f32_fp8_e32 v[244:245], v175
	v_cvt_pk_f32_fp8_sdwa v[202:203], v175 src0_sel:WORD_1
	v_cndmask_b32_e32 v230, v220, v235, vcc
	v_pk_fma_f32 v[204:205], v[240:241], v[60:61], v[204:205]
	v_pk_fma_f32 v[206:207], v[242:243], v[62:63], v[206:207]
	v_pk_fma_f32 v[204:205], v[244:245], v[64:65], v[204:205]
	v_pk_fma_f32 v[206:207], v[202:203], v[66:67], v[206:207]
	v_readlane_b32 s0, v135, 41
	s_lshl_b32 s0, s0, 10
	s_add_u32 s4, s8, s0
	s_addc_u32 s5, s9, 0
	global_load_dwordx4 v[172:175], v16, s[4:5]
	v_pk_add_f32 v[204:205], v[204:205], v[206:207]
	s_nop 0
	v_add_f32_e32 v221, v204, v205
	s_waitcnt vmcnt(15)
	v_cvt_pk_f32_fp8_e32 v[240:241], v176
	v_cvt_pk_f32_fp8_sdwa v[242:243], v176 src0_sel:WORD_1
	v_cvt_pk_f32_fp8_e32 v[244:245], v177
	v_cvt_pk_f32_fp8_sdwa v[202:203], v177 src0_sel:WORD_1
	v_add_f32_dpp v221, v221, v221 quad_perm:[1,0,3,2] row_mask:0xf bank_mask:0xf bound_ctrl:1
	v_pk_mul_f32 v[204:205], v[240:241], v[52:53]
	v_pk_mul_f32 v[206:207], v[242:243], v[54:55]
	v_add_f32_dpp v221, v221, v221 quad_perm:[2,3,0,1] row_mask:0xf bank_mask:0xf bound_ctrl:1
	v_cvt_pk_f32_fp8_e32 v[240:241], v178
	v_cvt_pk_f32_fp8_sdwa v[242:243], v178 src0_sel:WORD_1
	v_add_f32_dpp v221, v221, v221 row_half_mirror row_mask:0xf bank_mask:0xf bound_ctrl:1
	v_pk_fma_f32 v[204:205], v[244:245], v[56:57], v[204:205]
	v_pk_fma_f32 v[206:207], v[202:203], v[58:59], v[206:207]
	s_add_i32 s0, s1, 41
	s_cmp_lt_i32 s0, s2
	s_cselect_b64 vcc, -1, 0
	v_cvt_pk_f32_fp8_e32 v[244:245], v179
	v_cvt_pk_f32_fp8_sdwa v[202:203], v179 src0_sel:WORD_1
	v_cndmask_b32_e32 v231, v220, v221, vcc
	v_pk_fma_f32 v[204:205], v[240:241], v[60:61], v[204:205]
	v_pk_fma_f32 v[206:207], v[242:243], v[62:63], v[206:207]
	v_pk_fma_f32 v[204:205], v[244:245], v[64:65], v[204:205]
	v_pk_fma_f32 v[206:207], v[202:203], v[66:67], v[206:207]
	v_readlane_b32 s0, v135, 42
	s_lshl_b32 s0, s0, 10
	s_add_u32 s4, s8, s0
	s_addc_u32 s5, s9, 0
	global_load_dwordx4 v[176:179], v16, s[4:5]
	v_pk_add_f32 v[204:205], v[204:205], v[206:207]
	s_nop 0
	v_add_f32_e32 v235, v204, v205
	s_waitcnt vmcnt(15)
; DI float sum8(float v) { v += DPPF(v, 0xB1); v += DPPF(v, 0x4E); v += DPPF(v, 0x141); return v; }
; DI void topk_phase(const bf16_t* PROJ, const unsigned char* K8, const unsigned char* V8, const unsigned short* SC, bf16_t* ODSA, int c, char* smem, int bid, int nb) {
;     ...
;         const size_t ro = (size_t)__builtin_amdgcn_readlane(mysel, jj) * 1024 + lane * 16;
;         const uint4 a = *(const uint4*)(K8 + ro), vv = *(const uint4*)(V8 + ro);
;         const unsigned w[4] = {a.x, a.y, a.z, a.w}, u[4] = {vv.x, vv.y, vv.z, vv.w};
;         float da = 0.f;
; #pragma unroll
;         for (int i = 0; i < 4; ++i) {
;           const f32x2v lo = __builtin_amdgcn_cvt_pk_f32_fp8((int)w[i], false), hi = __builtin_amdgcn_cvt_pk_f32_fp8((int)w[i], true);
;           da += qv[4 * i] * lo[0] + qv[4 * i + 1] * lo[1] + qv[4 * i + 2] * hi[0] + qv[4 * i + 3] * hi[1];
;         }
;         da = sum8(da);
;         da = j < count ? da : -3e30f;
	v_cvt_pk_f32_fp8_e32 v[240:241], v180
	v_cvt_pk_f32_fp8_sdwa v[242:243], v180 src0_sel:WORD_1
	v_cvt_pk_f32_fp8_e32 v[244:245], v181
	v_cvt_pk_f32_fp8_sdwa v[202:203], v181 src0_sel:WORD_1
	v_add_f32_dpp v235, v235, v235 quad_perm:[1,0,3,2] row_mask:0xf bank_mask:0xf bound_ctrl:1
	v_pk_mul_f32 v[204:205], v[240:241], v[52:53]
	v_pk_mul_f32 v[206:207], v[242:243], v[54:55]
	v_add_f32_dpp v235, v235, v235 quad_perm:[2,3,0,1] row_mask:0xf bank_mask:0xf bound_ctrl:1
	v_cvt_pk_f32_fp8_e32 v[240:241], v182
	v_cvt_pk_f32_fp8_sdwa v[242:243], v182 src0_sel:WORD_1
	v_add_f32_dpp v235, v235, v235 row_half_mirror row_mask:0xf bank_mask:0xf bound_ctrl:1
	v_pk_fma_f32 v[204:205], v[244:245], v[56:57], v[204:205]
	v_pk_fma_f32 v[206:207], v[202:203], v[58:59], v[206:207]
	s_add_i32 s0, s1, 42
	s_cmp_lt_i32 s0, s2
	s_cselect_b64 vcc, -1, 0
	v_cvt_pk_f32_fp8_e32 v[244:245], v183
	v_cvt_pk_f32_fp8_sdwa v[202:203], v183 src0_sel:WORD_1
	v_cndmask_b32_e32 v232, v220, v235, vcc
	v_pk_fma_f32 v[204:205], v[240:241], v[60:61], v[204:205]
	v_pk_fma_f32 v[206:207], v[242:243], v[62:63], v[206:207]
	v_pk_fma_f32 v[204:205], v[244:245], v[64:65], v[204:205]
	v_pk_fma_f32 v[206:207], v[202:203], v[66:67], v[206:207]
	v_readlane_b32 s0, v135, 43
	s_lshl_b32 s0, s0, 10
	s_add_u32 s4, s8, s0
	s_addc_u32 s5, s9, 0
	global_load_dwordx4 v[180:183], v16, s[4:5]
	v_pk_add_f32 v[204:205], v[204:205], v[206:207]
	s_nop 0
	v_add_f32_e32 v221, v204, v205
	s_waitcnt vmcnt(15)
	v_cvt_pk_f32_fp8_e32 v[240:241], v186
	v_cvt_pk_f32_fp8_sdwa v[242:243], v186 src0_sel:WORD_1
	v_cvt_pk_f32_fp8_e32 v[244:245], v187
	v_cvt_pk_f32_fp8_sdwa v[202:203], v187 src0_sel:WORD_1
	v_add_f32_dpp v221, v221, v221 quad_perm:[1,0,3,2] row_mask:0xf bank_mask:0xf bound_ctrl:1
	v_pk_mul_f32 v[204:205], v[240:241], v[52:53]
	v_pk_mul_f32 v[206:207], v[242:243], v[54:55]
	v_add_f32_dpp v221, v221, v221 quad_perm:[2,3,0,1] row_mask:0xf bank_mask:0xf bound_ctrl:1
	v_cvt_pk_f32_fp8_e32 v[240:241], v188
	v_cvt_pk_f32_fp8_sdwa v[242:243], v188 src0_sel:WORD_1
	v_add_f32_dpp v221, v221, v221 row_half_mirror row_mask:0xf bank_mask:0xf bound_ctrl:1
	v_pk_fma_f32 v[204:205], v[244:245], v[56:57], v[204:205]
	v_pk_fma_f32 v[206:207], v[202:203], v[58:59], v[206:207]
	s_add_i32 s0, s1, 43
	s_cmp_lt_i32 s0, s2
	s_cselect_b64 vcc, -1, 0
	v_cvt_pk_f32_fp8_e32 v[244:245], v189
	v_cvt_pk_f32_fp8_sdwa v[202:203], v189 src0_sel:WORD_1
	v_cndmask_b32_e32 v233, v220, v221, vcc
	v_pk_fma_f32 v[204:205], v[240:241], v[60:61], v[204:205]
	v_pk_fma_f32 v[206:207], v[242:243], v[62:63], v[206:207]
	v_pk_fma_f32 v[204:205], v[244:245], v[64:65], v[204:205]
	v_pk_fma_f32 v[206:207], v[202:203], v[66:67], v[206:207]
	v_readlane_b32 s0, v135, 44
	s_lshl_b32 s0, s0, 10
	s_add_u32 s4, s8, s0
	s_addc_u32 s5, s9, 0
	global_load_dwordx4 v[186:189], v16, s[4:5]
	v_pk_add_f32 v[204:205], v[204:205], v[206:207]
	s_nop 0
	v_add_f32_e32 v235, v204, v205
	s_waitcnt vmcnt(15)
	v_cvt_pk_f32_fp8_e32 v[240:241], v190
	v_cvt_pk_f32_fp8_sdwa v[242:243], v190 src0_sel:WORD_1
	v_cvt_pk_f32_fp8_e32 v[244:245], v191
	v_cvt_pk_f32_fp8_sdwa v[202:203], v191 src0_sel:WORD_1
	v_add_f32_dpp v235, v235, v235 quad_perm:[1,0,3,2] row_mask:0xf bank_mask:0xf bound_ctrl:1
	v_pk_mul_f32 v[204:205], v[240:241], v[52:53]
	v_pk_mul_f32 v[206:207], v[242:243], v[54:55]
	v_add_f32_dpp v235, v235, v235 quad_perm:[2,3,0,1] row_mask:0xf bank_mask:0xf bound_ctrl:1
	v_cvt_pk_f32_fp8_e32 v[240:241], v192
	v_cvt_pk_f32_fp8_sdwa v[242:243], v192 src0_sel:WORD_1
	v_add_f32_dpp v235, v235, v235 row_half_mirror row_mask:0xf bank_mask:0xf bound_ctrl:1
	v_pk_fma_f32 v[204:205], v[244:245], v[56:57], v[204:205]
	v_pk_fma_f32 v[206:207], v[202:203], v[58:59], v[206:207]
	s_add_i32 s0, s1, 44
	s_cmp_lt_i32 s0, s2
	s_cselect_b64 vcc, -1, 0
	v_cvt_pk_f32_fp8_e32 v[244:245], v193
	v_cvt_pk_f32_fp8_sdwa v[202:203], v193 src0_sel:WORD_1
	v_cndmask_b32_e32 v236, v220, v235, vcc
	v_pk_fma_f32 v[204:205], v[240:241], v[60:61], v[204:205]
	v_pk_fma_f32 v[206:207], v[242:243], v[62:63], v[206:207]
	v_pk_fma_f32 v[204:205], v[244:245], v[64:65], v[204:205]
	v_pk_fma_f32 v[206:207], v[202:203], v[66:67], v[206:207]
	v_readlane_b32 s0, v135, 45
	s_lshl_b32 s0, s0, 10
	s_add_u32 s4, s8, s0
	s_addc_u32 s5, s9, 0
	global_load_dwordx4 v[190:193], v16, s[4:5]
	v_pk_add_f32 v[204:205], v[204:205], v[206:207]
	s_nop 0
	v_add_f32_e32 v221, v204, v205
	s_waitcnt vmcnt(15)
	v_cvt_pk_f32_fp8_e32 v[240:241], v194
	v_cvt_pk_f32_fp8_sdwa v[242:243], v194 src0_sel:WORD_1
	v_cvt_pk_f32_fp8_e32 v[244:245], v195
	v_cvt_pk_f32_fp8_sdwa v[202:203], v195 src0_sel:WORD_1
	v_add_f32_dpp v221, v221, v221 quad_perm:[1,0,3,2] row_mask:0xf bank_mask:0xf bound_ctrl:1
	v_pk_mul_f32 v[204:205], v[240:241], v[52:53]
	v_pk_mul_f32 v[206:207], v[242:243], v[54:55]
	v_add_f32_dpp v221, v221, v221 quad_perm:[2,3,0,1] row_mask:0xf bank_mask:0xf bound_ctrl:1
	v_cvt_pk_f32_fp8_e32 v[240:241], v196
	v_cvt_pk_f32_fp8_sdwa v[242:243], v196 src0_sel:WORD_1
	v_add_f32_dpp v221, v221, v221 row_half_mirror row_mask:0xf bank_mask:0xf bound_ctrl:1
	v_pk_fma_f32 v[204:205], v[244:245], v[56:57], v[204:205]
	v_pk_fma_f32 v[206:207], v[202:203], v[58:59], v[206:207]
	s_add_i32 s0, s1, 45
	s_cmp_lt_i32 s0, s2
	s_cselect_b64 vcc, -1, 0
	v_cvt_pk_f32_fp8_e32 v[244:245], v197
	v_cvt_pk_f32_fp8_sdwa v[202:203], v197 src0_sel:WORD_1
	v_cndmask_b32_e32 v237, v220, v221, vcc
	v_pk_fma_f32 v[204:205], v[240:241], v[60:61], v[204:205]
	v_pk_fma_f32 v[206:207], v[242:243], v[62:63], v[206:207]
	v_pk_fma_f32 v[204:205], v[244:245], v[64:65], v[204:205]
	v_pk_fma_f32 v[206:207], v[202:203], v[66:67], v[206:207]
	v_readlane_b32 s0, v135, 46
	s_lshl_b32 s0, s0, 10
	s_add_u32 s4, s8, s0
	s_addc_u32 s5, s9, 0
	global_load_dwordx4 v[194:197], v16, s[4:5]
	v_pk_add_f32 v[204:205], v[204:205], v[206:207]
	s_nop 0
	v_add_f32_e32 v235, v204, v205
	s_waitcnt vmcnt(15)
; DI float sum8(float v) { v += DPPF(v, 0xB1); v += DPPF(v, 0x4E); v += DPPF(v, 0x141); return v; }
; DI void topk_phase(const bf16_t* PROJ, const unsigned char* K8, const unsigned char* V8, const unsigned short* SC, bf16_t* ODSA, int c, char* smem, int bid, int nb) {
;     ...
;           const f32x2v lo = __builtin_amdgcn_cvt_pk_f32_fp8((int)w[i], false), hi = __builtin_amdgcn_cvt_pk_f32_fp8((int)w[i], true);
;           da += qv[4 * i] * lo[0] + qv[4 * i + 1] * lo[1] + qv[4 * i + 2] * hi[0] + qv[4 * i + 3] * hi[1];
;         }
;         da = sum8(da);
;         da = j < count ? da : -3e30f;
;         const float mn = fmaxf(m_run, da), al = __builtin_amdgcn_exp2f(m_run - mn), pp = __builtin_amdgcn_exp2f(da - mn);
;         m_run = mn; l_run = l_run * al + pp;
; #pragma unroll
;         for (int i = 0; i < 4; ++i) {
;           const f32x2v lo = __builtin_amdgcn_cvt_pk_f32_fp8((int)u[i], false), hi = __builtin_amdgcn_cvt_pk_f32_fp8((int)u[i], true);
;           ov[4 * i] = ov[4 * i] * al + pp * lo[0]; ov[4 * i + 1] = ov[4 * i + 1] * al + pp * lo[1];
;           ov[4 * i + 2] = ov[4 * i + 2] * al + pp * hi[0]; ov[4 * i + 3] = ov[4 * i + 3] * al + pp * hi[1];
;         }
	v_cvt_pk_f32_fp8_e32 v[240:241], v198
	v_cvt_pk_f32_fp8_sdwa v[242:243], v198 src0_sel:WORD_1
	v_cvt_pk_f32_fp8_e32 v[244:245], v199
	v_cvt_pk_f32_fp8_sdwa v[202:203], v199 src0_sel:WORD_1
	v_add_f32_dpp v235, v235, v235 quad_perm:[1,0,3,2] row_mask:0xf bank_mask:0xf bound_ctrl:1
	v_pk_mul_f32 v[204:205], v[240:241], v[52:53]
	v_pk_mul_f32 v[206:207], v[242:243], v[54:55]
	v_add_f32_dpp v235, v235, v235 quad_perm:[2,3,0,1] row_mask:0xf bank_mask:0xf bound_ctrl:1
	v_cvt_pk_f32_fp8_e32 v[240:241], v200
	v_cvt_pk_f32_fp8_sdwa v[242:243], v200 src0_sel:WORD_1
	v_add_f32_dpp v235, v235, v235 row_half_mirror row_mask:0xf bank_mask:0xf bound_ctrl:1
	v_pk_fma_f32 v[204:205], v[244:245], v[56:57], v[204:205]
	v_pk_fma_f32 v[206:207], v[202:203], v[58:59], v[206:207]
	s_add_i32 s0, s1, 46
	s_cmp_lt_i32 s0, s2
	s_cselect_b64 vcc, -1, 0
	v_cvt_pk_f32_fp8_e32 v[244:245], v201
	v_cvt_pk_f32_fp8_sdwa v[202:203], v201 src0_sel:WORD_1
	v_cndmask_b32_e32 v238, v220, v235, vcc
	v_pk_fma_f32 v[204:205], v[240:241], v[60:61], v[204:205]
	v_pk_fma_f32 v[206:207], v[242:243], v[62:63], v[206:207]
	v_pk_fma_f32 v[204:205], v[244:245], v[64:65], v[204:205]
	v_pk_fma_f32 v[206:207], v[202:203], v[66:67], v[206:207]
	v_readlane_b32 s0, v135, 47
	s_lshl_b32 s0, s0, 10
	s_add_u32 s4, s8, s0
	s_addc_u32 s5, s9, 0
	global_load_dwordx4 v[198:201], v16, s[4:5]
	v_pk_add_f32 v[204:205], v[204:205], v[206:207]
	s_nop 0
	v_add_f32_e32 v221, v204, v205
	s_nop 1
	v_add_f32_dpp v221, v221, v221 quad_perm:[1,0,3,2] row_mask:0xf bank_mask:0xf bound_ctrl:1
	s_nop 1
	v_add_f32_dpp v221, v221, v221 quad_perm:[2,3,0,1] row_mask:0xf bank_mask:0xf bound_ctrl:1
	s_nop 1
	v_add_f32_dpp v221, v221, v221 row_half_mirror row_mask:0xf bank_mask:0xf bound_ctrl:1
	s_add_i32 s0, s1, 47
	s_cmp_lt_i32 s0, s2
	s_cselect_b64 vcc, -1, 0
	s_nop 1
	v_cndmask_b32_e32 v239, v220, v221, vcc
	v_max3_f32 v224, v210, v211, v212
	v_max3_f32 v224, v224, v213, v226
	v_max3_f32 v224, v224, v227, v228
	v_max3_f32 v224, v224, v229, v230
	v_max3_f32 v224, v224, v231, v232
	v_max3_f32 v224, v224, v233, v236
	v_max3_f32 v224, v224, v237, v238
	v_max_f32_e32 v224, v224, v239
	v_max_f32_e32 v221, v216, v224
	v_sub_f32_e32 v184, v216, v221
	v_exp_f32_e32 v184, v184
	v_mov_b32_e32 v216, v221
	s_nop 0
	v_pk_mul_f32 v[12:13], v[12:13], v[184:185] op_sel_hi:[1,0]
	v_pk_mul_f32 v[14:15], v[14:15], v[184:185] op_sel_hi:[1,0]
	v_pk_mul_f32 v[8:9], v[8:9], v[184:185] op_sel_hi:[1,0]
	v_pk_mul_f32 v[10:11], v[10:11], v[184:185] op_sel_hi:[1,0]
	v_pk_mul_f32 v[4:5], v[4:5], v[184:185] op_sel_hi:[1,0]
	v_pk_mul_f32 v[6:7], v[6:7], v[184:185] op_sel_hi:[1,0]
	v_pk_mul_f32 v[0:1], v[0:1], v[184:185] op_sel_hi:[1,0]
	v_pk_mul_f32 v[2:3], v[2:3], v[184:185] op_sel_hi:[1,0]
	v_mul_f32_e32 v215, v215, v184
	v_sub_f32_e32 v210, v210, v216
	v_exp_f32_e32 v210, v210
	s_waitcnt vmcnt(15)
	v_cvt_pk_f32_fp8_e32 v[240:241], v136
	v_cvt_pk_f32_fp8_sdwa v[242:243], v136 src0_sel:WORD_1
	v_cvt_pk_f32_fp8_e32 v[244:245], v137
	v_pk_fma_f32 v[12:13], v[240:241], v[210:211], v[12:13] op_sel_hi:[1,0,1]
	v_cvt_pk_f32_fp8_sdwa v[240:241], v137 src0_sel:WORD_1
	v_pk_fma_f32 v[14:15], v[242:243], v[210:211], v[14:15] op_sel_hi:[1,0,1]
	v_cvt_pk_f32_fp8_e32 v[242:243], v138
	v_sub_f32_e32 v211, v211, v216
	v_pk_fma_f32 v[8:9], v[244:245], v[210:211], v[8:9] op_sel_hi:[1,0,1]
	v_cvt_pk_f32_fp8_sdwa v[244:245], v138 src0_sel:WORD_1
	v_pk_fma_f32 v[10:11], v[240:241], v[210:211], v[10:11] op_sel_hi:[1,0,1]
	v_cvt_pk_f32_fp8_e32 v[240:241], v139
	v_exp_f32_e32 v211, v211
	v_pk_fma_f32 v[4:5], v[242:243], v[210:211], v[4:5] op_sel_hi:[1,0,1]
	v_cvt_pk_f32_fp8_sdwa v[242:243], v139 src0_sel:WORD_1
	v_pk_fma_f32 v[6:7], v[244:245], v[210:211], v[6:7] op_sel_hi:[1,0,1]
	v_add_f32_e32 v215, v215, v210
	v_pk_fma_f32 v[0:1], v[240:241], v[210:211], v[0:1] op_sel_hi:[1,0,1]
	v_pk_fma_f32 v[2:3], v[242:243], v[210:211], v[2:3] op_sel_hi:[1,0,1]
	v_readlane_b32 s0, v135, 48
	s_lshl_b32 s0, s0, 10
	s_add_u32 s4, s6, s0
	s_addc_u32 s5, s7, 0
	global_load_dwordx4 v[136:139], v16, s[4:5]
	s_waitcnt vmcnt(15)
	v_cvt_pk_f32_fp8_e32 v[240:241], v140
	v_cvt_pk_f32_fp8_sdwa v[242:243], v140 src0_sel:WORD_1
	v_cvt_pk_f32_fp8_e32 v[244:245], v141
	v_pk_fma_f32 v[12:13], v[240:241], v[210:211], v[12:13] op_sel:[0,1,0]
	v_cvt_pk_f32_fp8_sdwa v[240:241], v141 src0_sel:WORD_1
	v_pk_fma_f32 v[14:15], v[242:243], v[210:211], v[14:15] op_sel:[0,1,0]
	v_cvt_pk_f32_fp8_e32 v[242:243], v142
	v_sub_f32_e32 v212, v212, v216
	v_pk_fma_f32 v[8:9], v[244:245], v[210:211], v[8:9] op_sel:[0,1,0]
	v_cvt_pk_f32_fp8_sdwa v[244:245], v142 src0_sel:WORD_1
	v_pk_fma_f32 v[10:11], v[240:241], v[210:211], v[10:11] op_sel:[0,1,0]
	v_cvt_pk_f32_fp8_e32 v[240:241], v143
	v_exp_f32_e32 v212, v212
	v_pk_fma_f32 v[4:5], v[242:243], v[210:211], v[4:5] op_sel:[0,1,0]
	v_cvt_pk_f32_fp8_sdwa v[242:243], v143 src0_sel:WORD_1
	v_pk_fma_f32 v[6:7], v[244:245], v[210:211], v[6:7] op_sel:[0,1,0]
	v_add_f32_e32 v215, v215, v211
	v_pk_fma_f32 v[0:1], v[240:241], v[210:211], v[0:1] op_sel:[0,1,0]
	v_pk_fma_f32 v[2:3], v[242:243], v[210:211], v[2:3] op_sel:[0,1,0]
	v_readlane_b32 s0, v135, 49
	s_lshl_b32 s0, s0, 10
	s_add_u32 s4, s6, s0
	s_addc_u32 s5, s7, 0
	global_load_dwordx4 v[140:143], v16, s[4:5]
	s_waitcnt vmcnt(15)
; DI void topk_phase(const bf16_t* PROJ, const unsigned char* K8, const unsigned char* V8, const unsigned short* SC, bf16_t* ODSA, int c, char* smem, int bid, int nb) {
;     ...
;         const float mn = fmaxf(m_run, da), al = __builtin_amdgcn_exp2f(m_run - mn), pp = __builtin_amdgcn_exp2f(da - mn);
;         m_run = mn; l_run = l_run * al + pp;
; #pragma unroll
;         for (int i = 0; i < 4; ++i) {
;           const f32x2v lo = __builtin_amdgcn_cvt_pk_f32_fp8((int)u[i], false), hi = __builtin_amdgcn_cvt_pk_f32_fp8((int)u[i], true);
;           ov[4 * i] = ov[4 * i] * al + pp * lo[0]; ov[4 * i + 1] = ov[4 * i + 1] * al + pp * lo[1];
;           ov[4 * i + 2] = ov[4 * i + 2] * al + pp * hi[0]; ov[4 * i + 3] = ov[4 * i + 3] * al + pp * hi[1];
;         }
	v_cvt_pk_f32_fp8_e32 v[240:241], v144
	v_cvt_pk_f32_fp8_sdwa v[242:243], v144 src0_sel:WORD_1
	v_cvt_pk_f32_fp8_e32 v[244:245], v145
	v_pk_fma_f32 v[12:13], v[240:241], v[212:213], v[12:13] op_sel_hi:[1,0,1]
	v_cvt_pk_f32_fp8_sdwa v[240:241], v145 src0_sel:WORD_1
	v_pk_fma_f32 v[14:15], v[242:243], v[212:213], v[14:15] op_sel_hi:[1,0,1]
	v_cvt_pk_f32_fp8_e32 v[242:243], v146
	v_sub_f32_e32 v213, v213, v216
	v_pk_fma_f32 v[8:9], v[244:245], v[212:213], v[8:9] op_sel_hi:[1,0,1]
	v_cvt_pk_f32_fp8_sdwa v[244:245], v146 src0_sel:WORD_1
	v_pk_fma_f32 v[10:11], v[240:241], v[212:213], v[10:11] op_sel_hi:[1,0,1]
	v_cvt_pk_f32_fp8_e32 v[240:241], v147
	v_exp_f32_e32 v213, v213
	v_pk_fma_f32 v[4:5], v[242:243], v[212:213], v[4:5] op_sel_hi:[1,0,1]
	v_cvt_pk_f32_fp8_sdwa v[242:243], v147 src0_sel:WORD_1
	v_pk_fma_f32 v[6:7], v[244:245], v[212:213], v[6:7] op_sel_hi:[1,0,1]
	v_add_f32_e32 v215, v215, v212
	v_pk_fma_f32 v[0:1], v[240:241], v[212:213], v[0:1] op_sel_hi:[1,0,1]
	v_pk_fma_f32 v[2:3], v[242:243], v[212:213], v[2:3] op_sel_hi:[1,0,1]
	v_readlane_b32 s0, v135, 50
	s_lshl_b32 s0, s0, 10
	s_add_u32 s4, s6, s0
	s_addc_u32 s5, s7, 0
	global_load_dwordx4 v[144:147], v16, s[4:5]
	s_waitcnt vmcnt(15)
	v_cvt_pk_f32_fp8_e32 v[240:241], v148
	v_cvt_pk_f32_fp8_sdwa v[242:243], v148 src0_sel:WORD_1
	v_cvt_pk_f32_fp8_e32 v[244:245], v149
	v_pk_fma_f32 v[12:13], v[240:241], v[212:213], v[12:13] op_sel:[0,1,0]
	v_cvt_pk_f32_fp8_sdwa v[240:241], v149 src0_sel:WORD_1
	v_pk_fma_f32 v[14:15], v[242:243], v[212:213], v[14:15] op_sel:[0,1,0]
	v_cvt_pk_f32_fp8_e32 v[242:243], v150
	v_sub_f32_e32 v226, v226, v216
	v_pk_fma_f32 v[8:9], v[244:245], v[212:213], v[8:9] op_sel:[0,1,0]
	v_cvt_pk_f32_fp8_sdwa v[244:245], v150 src0_sel:WORD_1
	v_pk_fma_f32 v[10:11], v[240:241], v[212:213], v[10:11] op_sel:[0,1,0]
	v_cvt_pk_f32_fp8_e32 v[240:241], v151
	v_exp_f32_e32 v226, v226
	v_pk_fma_f32 v[4:5], v[242:243], v[212:213], v[4:5] op_sel:[0,1,0]
	v_cvt_pk_f32_fp8_sdwa v[242:243], v151 src0_sel:WORD_1
	v_pk_fma_f32 v[6:7], v[244:245], v[212:213], v[6:7] op_sel:[0,1,0]
	v_add_f32_e32 v215, v215, v213
	v_pk_fma_f32 v[0:1], v[240:241], v[212:213], v[0:1] op_sel:[0,1,0]
	v_pk_fma_f32 v[2:3], v[242:243], v[212:213], v[2:3] op_sel:[0,1,0]
	v_readlane_b32 s0, v135, 51
	s_lshl_b32 s0, s0, 10
	s_add_u32 s4, s6, s0
	s_addc_u32 s5, s7, 0
	global_load_dwordx4 v[148:151], v16, s[4:5]
	s_waitcnt vmcnt(15)
	v_cvt_pk_f32_fp8_e32 v[240:241], v152
	v_cvt_pk_f32_fp8_sdwa v[242:243], v152 src0_sel:WORD_1
	v_cvt_pk_f32_fp8_e32 v[244:245], v153
	v_pk_fma_f32 v[12:13], v[240:241], v[226:227], v[12:13] op_sel_hi:[1,0,1]
	v_cvt_pk_f32_fp8_sdwa v[240:241], v153 src0_sel:WORD_1
	v_pk_fma_f32 v[14:15], v[242:243], v[226:227], v[14:15] op_sel_hi:[1,0,1]
	v_cvt_pk_f32_fp8_e32 v[242:243], v154
	v_sub_f32_e32 v227, v227, v216
	v_pk_fma_f32 v[8:9], v[244:245], v[226:227], v[8:9] op_sel_hi:[1,0,1]
	v_cvt_pk_f32_fp8_sdwa v[244:245], v154 src0_sel:WORD_1
	v_pk_fma_f32 v[10:11], v[240:241], v[226:227], v[10:11] op_sel_hi:[1,0,1]
	v_cvt_pk_f32_fp8_e32 v[240:241], v155
	v_exp_f32_e32 v227, v227
	v_pk_fma_f32 v[4:5], v[242:243], v[226:227], v[4:5] op_sel_hi:[1,0,1]
	v_cvt_pk_f32_fp8_sdwa v[242:243], v155 src0_sel:WORD_1
	v_pk_fma_f32 v[6:7], v[244:245], v[226:227], v[6:7] op_sel_hi:[1,0,1]
	v_add_f32_e32 v215, v215, v226
	v_pk_fma_f32 v[0:1], v[240:241], v[226:227], v[0:1] op_sel_hi:[1,0,1]
	v_pk_fma_f32 v[2:3], v[242:243], v[226:227], v[2:3] op_sel_hi:[1,0,1]
	v_readlane_b32 s0, v135, 52
	s_lshl_b32 s0, s0, 10
	s_add_u32 s4, s6, s0
	s_addc_u32 s5, s7, 0
	global_load_dwordx4 v[152:155], v16, s[4:5]
	s_waitcnt vmcnt(15)
	v_cvt_pk_f32_fp8_e32 v[240:241], v156
	v_cvt_pk_f32_fp8_sdwa v[242:243], v156 src0_sel:WORD_1
	v_cvt_pk_f32_fp8_e32 v[244:245], v157
	v_pk_fma_f32 v[12:13], v[240:241], v[226:227], v[12:13] op_sel:[0,1,0]
	v_cvt_pk_f32_fp8_sdwa v[240:241], v157 src0_sel:WORD_1
	v_pk_fma_f32 v[14:15], v[242:243], v[226:227], v[14:15] op_sel:[0,1,0]
	v_cvt_pk_f32_fp8_e32 v[242:243], v158
	v_sub_f32_e32 v228, v228, v216
	v_pk_fma_f32 v[8:9], v[244:245], v[226:227], v[8:9] op_sel:[0,1,0]
	v_cvt_pk_f32_fp8_sdwa v[244:245], v158 src0_sel:WORD_1
	v_pk_fma_f32 v[10:11], v[240:241], v[226:227], v[10:11] op_sel:[0,1,0]
	v_cvt_pk_f32_fp8_e32 v[240:241], v159
	v_exp_f32_e32 v228, v228
	v_pk_fma_f32 v[4:5], v[242:243], v[226:227], v[4:5] op_sel:[0,1,0]
	v_cvt_pk_f32_fp8_sdwa v[242:243], v159 src0_sel:WORD_1
	v_pk_fma_f32 v[6:7], v[244:245], v[226:227], v[6:7] op_sel:[0,1,0]
	v_add_f32_e32 v215, v215, v227
	v_pk_fma_f32 v[0:1], v[240:241], v[226:227], v[0:1] op_sel:[0,1,0]
	v_pk_fma_f32 v[2:3], v[242:243], v[226:227], v[2:3] op_sel:[0,1,0]
	v_readlane_b32 s0, v135, 53
	s_lshl_b32 s0, s0, 10
	s_add_u32 s4, s6, s0
	s_addc_u32 s5, s7, 0
	global_load_dwordx4 v[156:159], v16, s[4:5]
	s_waitcnt vmcnt(15)
	v_cvt_pk_f32_fp8_e32 v[240:241], v160
	v_cvt_pk_f32_fp8_sdwa v[242:243], v160 src0_sel:WORD_1
	v_cvt_pk_f32_fp8_e32 v[244:245], v161
	v_pk_fma_f32 v[12:13], v[240:241], v[228:229], v[12:13] op_sel_hi:[1,0,1]
	v_cvt_pk_f32_fp8_sdwa v[240:241], v161 src0_sel:WORD_1
	v_pk_fma_f32 v[14:15], v[242:243], v[228:229], v[14:15] op_sel_hi:[1,0,1]
	v_cvt_pk_f32_fp8_e32 v[242:243], v162
	v_sub_f32_e32 v229, v229, v216
	v_pk_fma_f32 v[8:9], v[244:245], v[228:229], v[8:9] op_sel_hi:[1,0,1]
	v_cvt_pk_f32_fp8_sdwa v[244:245], v162 src0_sel:WORD_1
	v_pk_fma_f32 v[10:11], v[240:241], v[228:229], v[10:11] op_sel_hi:[1,0,1]
	v_cvt_pk_f32_fp8_e32 v[240:241], v163
	v_exp_f32_e32 v229, v229
	v_pk_fma_f32 v[4:5], v[242:243], v[228:229], v[4:5] op_sel_hi:[1,0,1]
	v_cvt_pk_f32_fp8_sdwa v[242:243], v163 src0_sel:WORD_1
	v_pk_fma_f32 v[6:7], v[244:245], v[228:229], v[6:7] op_sel_hi:[1,0,1]
	v_add_f32_e32 v215, v215, v228
	v_pk_fma_f32 v[0:1], v[240:241], v[228:229], v[0:1] op_sel_hi:[1,0,1]
	v_pk_fma_f32 v[2:3], v[242:243], v[228:229], v[2:3] op_sel_hi:[1,0,1]
	v_readlane_b32 s0, v135, 54
	s_lshl_b32 s0, s0, 10
	s_add_u32 s4, s6, s0
	s_addc_u32 s5, s7, 0
	global_load_dwordx4 v[160:163], v16, s[4:5]
	s_waitcnt vmcnt(15)
; DI void topk_phase(const bf16_t* PROJ, const unsigned char* K8, const unsigned char* V8, const unsigned short* SC, bf16_t* ODSA, int c, char* smem, int bid, int nb) {
;     ...
;         const float mn = fmaxf(m_run, da), al = __builtin_amdgcn_exp2f(m_run - mn), pp = __builtin_amdgcn_exp2f(da - mn);
;         m_run = mn; l_run = l_run * al + pp;
; #pragma unroll
;         for (int i = 0; i < 4; ++i) {
;           const f32x2v lo = __builtin_amdgcn_cvt_pk_f32_fp8((int)u[i], false), hi = __builtin_amdgcn_cvt_pk_f32_fp8((int)u[i], true);
;           ov[4 * i] = ov[4 * i] * al + pp * lo[0]; ov[4 * i + 1] = ov[4 * i + 1] * al + pp * lo[1];
;           ov[4 * i + 2] = ov[4 * i + 2] * al + pp * hi[0]; ov[4 * i + 3] = ov[4 * i + 3] * al + pp * hi[1];
;         }
	v_cvt_pk_f32_fp8_e32 v[240:241], v164
	v_cvt_pk_f32_fp8_sdwa v[242:243], v164 src0_sel:WORD_1
	v_cvt_pk_f32_fp8_e32 v[244:245], v165
	v_pk_fma_f32 v[12:13], v[240:241], v[228:229], v[12:13] op_sel:[0,1,0]
	v_cvt_pk_f32_fp8_sdwa v[240:241], v165 src0_sel:WORD_1
	v_pk_fma_f32 v[14:15], v[242:243], v[228:229], v[14:15] op_sel:[0,1,0]
	v_cvt_pk_f32_fp8_e32 v[242:243], v166
	v_sub_f32_e32 v230, v230, v216
	v_pk_fma_f32 v[8:9], v[244:245], v[228:229], v[8:9] op_sel:[0,1,0]
	v_cvt_pk_f32_fp8_sdwa v[244:245], v166 src0_sel:WORD_1
	v_pk_fma_f32 v[10:11], v[240:241], v[228:229], v[10:11] op_sel:[0,1,0]
	v_cvt_pk_f32_fp8_e32 v[240:241], v167
	v_exp_f32_e32 v230, v230
	v_pk_fma_f32 v[4:5], v[242:243], v[228:229], v[4:5] op_sel:[0,1,0]
	v_cvt_pk_f32_fp8_sdwa v[242:243], v167 src0_sel:WORD_1
	v_pk_fma_f32 v[6:7], v[244:245], v[228:229], v[6:7] op_sel:[0,1,0]
	v_add_f32_e32 v215, v215, v229
	v_pk_fma_f32 v[0:1], v[240:241], v[228:229], v[0:1] op_sel:[0,1,0]
	v_pk_fma_f32 v[2:3], v[242:243], v[228:229], v[2:3] op_sel:[0,1,0]
	v_readlane_b32 s0, v135, 55
	s_lshl_b32 s0, s0, 10
	s_add_u32 s4, s6, s0
	s_addc_u32 s5, s7, 0
	global_load_dwordx4 v[164:167], v16, s[4:5]
	s_waitcnt vmcnt(15)
	v_cvt_pk_f32_fp8_e32 v[240:241], v168
	v_cvt_pk_f32_fp8_sdwa v[242:243], v168 src0_sel:WORD_1
	v_cvt_pk_f32_fp8_e32 v[244:245], v169
	v_pk_fma_f32 v[12:13], v[240:241], v[230:231], v[12:13] op_sel_hi:[1,0,1]
	v_cvt_pk_f32_fp8_sdwa v[240:241], v169 src0_sel:WORD_1
	v_pk_fma_f32 v[14:15], v[242:243], v[230:231], v[14:15] op_sel_hi:[1,0,1]
	v_cvt_pk_f32_fp8_e32 v[242:243], v170
	v_sub_f32_e32 v231, v231, v216
	v_pk_fma_f32 v[8:9], v[244:245], v[230:231], v[8:9] op_sel_hi:[1,0,1]
	v_cvt_pk_f32_fp8_sdwa v[244:245], v170 src0_sel:WORD_1
	v_pk_fma_f32 v[10:11], v[240:241], v[230:231], v[10:11] op_sel_hi:[1,0,1]
	v_cvt_pk_f32_fp8_e32 v[240:241], v171
	v_exp_f32_e32 v231, v231
	v_pk_fma_f32 v[4:5], v[242:243], v[230:231], v[4:5] op_sel_hi:[1,0,1]
	v_cvt_pk_f32_fp8_sdwa v[242:243], v171 src0_sel:WORD_1
	v_pk_fma_f32 v[6:7], v[244:245], v[230:231], v[6:7] op_sel_hi:[1,0,1]
	v_add_f32_e32 v215, v215, v230
	v_pk_fma_f32 v[0:1], v[240:241], v[230:231], v[0:1] op_sel_hi:[1,0,1]
	v_pk_fma_f32 v[2:3], v[242:243], v[230:231], v[2:3] op_sel_hi:[1,0,1]
	v_readlane_b32 s0, v135, 56
	s_lshl_b32 s0, s0, 10
	s_add_u32 s4, s6, s0
	s_addc_u32 s5, s7, 0
	global_load_dwordx4 v[168:171], v16, s[4:5]
	s_waitcnt vmcnt(15)
	v_cvt_pk_f32_fp8_e32 v[240:241], v172
	v_cvt_pk_f32_fp8_sdwa v[242:243], v172 src0_sel:WORD_1
	v_cvt_pk_f32_fp8_e32 v[244:245], v173
	v_pk_fma_f32 v[12:13], v[240:241], v[230:231], v[12:13] op_sel:[0,1,0]
	v_cvt_pk_f32_fp8_sdwa v[240:241], v173 src0_sel:WORD_1
	v_pk_fma_f32 v[14:15], v[242:243], v[230:231], v[14:15] op_sel:[0,1,0]
	v_cvt_pk_f32_fp8_e32 v[242:243], v174
	v_sub_f32_e32 v232, v232, v216
	v_pk_fma_f32 v[8:9], v[244:245], v[230:231], v[8:9] op_sel:[0,1,0]
	v_cvt_pk_f32_fp8_sdwa v[244:245], v174 src0_sel:WORD_1
	v_pk_fma_f32 v[10:11], v[240:241], v[230:231], v[10:11] op_sel:[0,1,0]
	v_cvt_pk_f32_fp8_e32 v[240:241], v175
	v_exp_f32_e32 v232, v232
	v_pk_fma_f32 v[4:5], v[242:243], v[230:231], v[4:5] op_sel:[0,1,0]
	v_cvt_pk_f32_fp8_sdwa v[242:243], v175 src0_sel:WORD_1
	v_pk_fma_f32 v[6:7], v[244:245], v[230:231], v[6:7] op_sel:[0,1,0]
	v_add_f32_e32 v215, v215, v231
	v_pk_fma_f32 v[0:1], v[240:241], v[230:231], v[0:1] op_sel:[0,1,0]
	v_pk_fma_f32 v[2:3], v[242:243], v[230:231], v[2:3] op_sel:[0,1,0]
	v_readlane_b32 s0, v135, 57
	s_lshl_b32 s0, s0, 10
	s_add_u32 s4, s6, s0
	s_addc_u32 s5, s7, 0
	global_load_dwordx4 v[172:175], v16, s[4:5]
	s_waitcnt vmcnt(15)
	v_cvt_pk_f32_fp8_e32 v[240:241], v176
	v_cvt_pk_f32_fp8_sdwa v[242:243], v176 src0_sel:WORD_1
	v_cvt_pk_f32_fp8_e32 v[244:245], v177
	v_pk_fma_f32 v[12:13], v[240:241], v[232:233], v[12:13] op_sel_hi:[1,0,1]
	v_cvt_pk_f32_fp8_sdwa v[240:241], v177 src0_sel:WORD_1
	v_pk_fma_f32 v[14:15], v[242:243], v[232:233], v[14:15] op_sel_hi:[1,0,1]
	v_cvt_pk_f32_fp8_e32 v[242:243], v178
	v_sub_f32_e32 v233, v233, v216
	v_pk_fma_f32 v[8:9], v[244:245], v[232:233], v[8:9] op_sel_hi:[1,0,1]
	v_cvt_pk_f32_fp8_sdwa v[244:245], v178 src0_sel:WORD_1
	v_pk_fma_f32 v[10:11], v[240:241], v[232:233], v[10:11] op_sel_hi:[1,0,1]
	v_cvt_pk_f32_fp8_e32 v[240:241], v179
	v_exp_f32_e32 v233, v233
	v_pk_fma_f32 v[4:5], v[242:243], v[232:233], v[4:5] op_sel_hi:[1,0,1]
	v_cvt_pk_f32_fp8_sdwa v[242:243], v179 src0_sel:WORD_1
	v_pk_fma_f32 v[6:7], v[244:245], v[232:233], v[6:7] op_sel_hi:[1,0,1]
	v_add_f32_e32 v215, v215, v232
	v_pk_fma_f32 v[0:1], v[240:241], v[232:233], v[0:1] op_sel_hi:[1,0,1]
	v_pk_fma_f32 v[2:3], v[242:243], v[232:233], v[2:3] op_sel_hi:[1,0,1]
	v_readlane_b32 s0, v135, 58
	s_lshl_b32 s0, s0, 10
	s_add_u32 s4, s6, s0
	s_addc_u32 s5, s7, 0
	global_load_dwordx4 v[176:179], v16, s[4:5]
	s_waitcnt vmcnt(15)
	v_cvt_pk_f32_fp8_e32 v[240:241], v180
	v_cvt_pk_f32_fp8_sdwa v[242:243], v180 src0_sel:WORD_1
	v_cvt_pk_f32_fp8_e32 v[244:245], v181
	v_pk_fma_f32 v[12:13], v[240:241], v[232:233], v[12:13] op_sel:[0,1,0]
	v_cvt_pk_f32_fp8_sdwa v[240:241], v181 src0_sel:WORD_1
	v_pk_fma_f32 v[14:15], v[242:243], v[232:233], v[14:15] op_sel:[0,1,0]
	v_cvt_pk_f32_fp8_e32 v[242:243], v182
	v_sub_f32_e32 v236, v236, v216
	v_pk_fma_f32 v[8:9], v[244:245], v[232:233], v[8:9] op_sel:[0,1,0]
	v_cvt_pk_f32_fp8_sdwa v[244:245], v182 src0_sel:WORD_1
	v_pk_fma_f32 v[10:11], v[240:241], v[232:233], v[10:11] op_sel:[0,1,0]
	v_cvt_pk_f32_fp8_e32 v[240:241], v183
	v_exp_f32_e32 v236, v236
	v_pk_fma_f32 v[4:5], v[242:243], v[232:233], v[4:5] op_sel:[0,1,0]
	v_cvt_pk_f32_fp8_sdwa v[242:243], v183 src0_sel:WORD_1
	v_pk_fma_f32 v[6:7], v[244:245], v[232:233], v[6:7] op_sel:[0,1,0]
	v_add_f32_e32 v215, v215, v233
	v_pk_fma_f32 v[0:1], v[240:241], v[232:233], v[0:1] op_sel:[0,1,0]
	v_pk_fma_f32 v[2:3], v[242:243], v[232:233], v[2:3] op_sel:[0,1,0]
	v_readlane_b32 s0, v135, 59
	s_lshl_b32 s0, s0, 10
	s_add_u32 s4, s6, s0
	s_addc_u32 s5, s7, 0
	global_load_dwordx4 v[180:183], v16, s[4:5]
	s_waitcnt vmcnt(15)
; DI float sum8(float v) { v += DPPF(v, 0xB1); v += DPPF(v, 0x4E); v += DPPF(v, 0x141); return v; }
; DI void topk_phase(const bf16_t* PROJ, const unsigned char* K8, const unsigned char* V8, const unsigned short* SC, bf16_t* ODSA, int c, char* smem, int bid, int nb) {
;     ...
;         const size_t ro = (size_t)__builtin_amdgcn_readlane(mysel, jj) * 1024 + lane * 16;
;         const uint4 a = *(const uint4*)(K8 + ro), vv = *(const uint4*)(V8 + ro);
;         const unsigned w[4] = {a.x, a.y, a.z, a.w}, u[4] = {vv.x, vv.y, vv.z, vv.w};
;         float da = 0.f;
; #pragma unroll
;         for (int i = 0; i < 4; ++i) {
;           const f32x2v lo = __builtin_amdgcn_cvt_pk_f32_fp8((int)w[i], false), hi = __builtin_amdgcn_cvt_pk_f32_fp8((int)w[i], true);
;           da += qv[4 * i] * lo[0] + qv[4 * i + 1] * lo[1] + qv[4 * i + 2] * hi[0] + qv[4 * i + 3] * hi[1];
;         }
;         da = sum8(da);
;         da = j < count ? da : -3e30f;
;         const float mn = fmaxf(m_run, da), al = __builtin_amdgcn_exp2f(m_run - mn), pp = __builtin_amdgcn_exp2f(da - mn);
;         m_run = mn; l_run = l_run * al + pp;
; #pragma unroll
;         for (int i = 0; i < 4; ++i) {
;           const f32x2v lo = __builtin_amdgcn_cvt_pk_f32_fp8((int)u[i], false), hi = __builtin_amdgcn_cvt_pk_f32_fp8((int)u[i], true);
;           ov[4 * i] = ov[4 * i] * al + pp * lo[0]; ov[4 * i + 1] = ov[4 * i + 1] * al + pp * lo[1];
;           ov[4 * i + 2] = ov[4 * i + 2] * al + pp * hi[0]; ov[4 * i + 3] = ov[4 * i + 3] * al + pp * hi[1];
;         }
	v_cvt_pk_f32_fp8_e32 v[240:241], v186
	v_cvt_pk_f32_fp8_sdwa v[242:243], v186 src0_sel:WORD_1
	v_cvt_pk_f32_fp8_e32 v[244:245], v187
	v_pk_fma_f32 v[12:13], v[240:241], v[236:237], v[12:13] op_sel_hi:[1,0,1]
	v_cvt_pk_f32_fp8_sdwa v[240:241], v187 src0_sel:WORD_1
	v_pk_fma_f32 v[14:15], v[242:243], v[236:237], v[14:15] op_sel_hi:[1,0,1]
	v_cvt_pk_f32_fp8_e32 v[242:243], v188
	v_sub_f32_e32 v237, v237, v216
	v_pk_fma_f32 v[8:9], v[244:245], v[236:237], v[8:9] op_sel_hi:[1,0,1]
	v_cvt_pk_f32_fp8_sdwa v[244:245], v188 src0_sel:WORD_1
	v_pk_fma_f32 v[10:11], v[240:241], v[236:237], v[10:11] op_sel_hi:[1,0,1]
	v_cvt_pk_f32_fp8_e32 v[240:241], v189
	v_exp_f32_e32 v237, v237
	v_pk_fma_f32 v[4:5], v[242:243], v[236:237], v[4:5] op_sel_hi:[1,0,1]
	v_cvt_pk_f32_fp8_sdwa v[242:243], v189 src0_sel:WORD_1
	v_pk_fma_f32 v[6:7], v[244:245], v[236:237], v[6:7] op_sel_hi:[1,0,1]
	v_add_f32_e32 v215, v215, v236
	v_pk_fma_f32 v[0:1], v[240:241], v[236:237], v[0:1] op_sel_hi:[1,0,1]
	v_pk_fma_f32 v[2:3], v[242:243], v[236:237], v[2:3] op_sel_hi:[1,0,1]
	v_readlane_b32 s0, v135, 60
	s_lshl_b32 s0, s0, 10
	s_add_u32 s4, s6, s0
	s_addc_u32 s5, s7, 0
	global_load_dwordx4 v[186:189], v16, s[4:5]
	s_waitcnt vmcnt(15)
	v_cvt_pk_f32_fp8_e32 v[240:241], v190
	v_cvt_pk_f32_fp8_sdwa v[242:243], v190 src0_sel:WORD_1
	v_cvt_pk_f32_fp8_e32 v[244:245], v191
	v_pk_fma_f32 v[12:13], v[240:241], v[236:237], v[12:13] op_sel:[0,1,0]
	v_cvt_pk_f32_fp8_sdwa v[240:241], v191 src0_sel:WORD_1
	v_pk_fma_f32 v[14:15], v[242:243], v[236:237], v[14:15] op_sel:[0,1,0]
	v_cvt_pk_f32_fp8_e32 v[242:243], v192
	v_sub_f32_e32 v238, v238, v216
	v_pk_fma_f32 v[8:9], v[244:245], v[236:237], v[8:9] op_sel:[0,1,0]
	v_cvt_pk_f32_fp8_sdwa v[244:245], v192 src0_sel:WORD_1
	v_pk_fma_f32 v[10:11], v[240:241], v[236:237], v[10:11] op_sel:[0,1,0]
	v_cvt_pk_f32_fp8_e32 v[240:241], v193
	v_exp_f32_e32 v238, v238
	v_pk_fma_f32 v[4:5], v[242:243], v[236:237], v[4:5] op_sel:[0,1,0]
	v_cvt_pk_f32_fp8_sdwa v[242:243], v193 src0_sel:WORD_1
	v_pk_fma_f32 v[6:7], v[244:245], v[236:237], v[6:7] op_sel:[0,1,0]
	v_add_f32_e32 v215, v215, v237
	v_pk_fma_f32 v[0:1], v[240:241], v[236:237], v[0:1] op_sel:[0,1,0]
	v_pk_fma_f32 v[2:3], v[242:243], v[236:237], v[2:3] op_sel:[0,1,0]
	v_readlane_b32 s0, v135, 61
	s_lshl_b32 s0, s0, 10
	s_add_u32 s4, s6, s0
	s_addc_u32 s5, s7, 0
	global_load_dwordx4 v[190:193], v16, s[4:5]
	s_waitcnt vmcnt(15)
	v_cvt_pk_f32_fp8_e32 v[240:241], v194
	v_cvt_pk_f32_fp8_sdwa v[242:243], v194 src0_sel:WORD_1
	v_cvt_pk_f32_fp8_e32 v[244:245], v195
	v_pk_fma_f32 v[12:13], v[240:241], v[238:239], v[12:13] op_sel_hi:[1,0,1]
	v_cvt_pk_f32_fp8_sdwa v[240:241], v195 src0_sel:WORD_1
	v_pk_fma_f32 v[14:15], v[242:243], v[238:239], v[14:15] op_sel_hi:[1,0,1]
	v_cvt_pk_f32_fp8_e32 v[242:243], v196
	v_sub_f32_e32 v239, v239, v216
	v_pk_fma_f32 v[8:9], v[244:245], v[238:239], v[8:9] op_sel_hi:[1,0,1]
	v_cvt_pk_f32_fp8_sdwa v[244:245], v196 src0_sel:WORD_1
	v_pk_fma_f32 v[10:11], v[240:241], v[238:239], v[10:11] op_sel_hi:[1,0,1]
	v_cvt_pk_f32_fp8_e32 v[240:241], v197
	v_exp_f32_e32 v239, v239
	v_pk_fma_f32 v[4:5], v[242:243], v[238:239], v[4:5] op_sel_hi:[1,0,1]
	v_cvt_pk_f32_fp8_sdwa v[242:243], v197 src0_sel:WORD_1
	v_pk_fma_f32 v[6:7], v[244:245], v[238:239], v[6:7] op_sel_hi:[1,0,1]
	v_add_f32_e32 v215, v215, v238
	v_pk_fma_f32 v[0:1], v[240:241], v[238:239], v[0:1] op_sel_hi:[1,0,1]
	v_pk_fma_f32 v[2:3], v[242:243], v[238:239], v[2:3] op_sel_hi:[1,0,1]
	v_readlane_b32 s0, v135, 62
	s_lshl_b32 s0, s0, 10
	s_add_u32 s4, s6, s0
	s_addc_u32 s5, s7, 0
	global_load_dwordx4 v[194:197], v16, s[4:5]
	s_waitcnt vmcnt(15)
	v_cvt_pk_f32_fp8_e32 v[240:241], v198
	v_cvt_pk_f32_fp8_sdwa v[242:243], v198 src0_sel:WORD_1
	v_cvt_pk_f32_fp8_e32 v[244:245], v199
	v_pk_fma_f32 v[12:13], v[240:241], v[238:239], v[12:13] op_sel:[0,1,0]
	v_cvt_pk_f32_fp8_sdwa v[240:241], v199 src0_sel:WORD_1
	v_pk_fma_f32 v[14:15], v[242:243], v[238:239], v[14:15] op_sel:[0,1,0]
	v_cvt_pk_f32_fp8_e32 v[242:243], v200
	v_add_f32_e32 v215, v215, v239
	v_pk_fma_f32 v[8:9], v[244:245], v[238:239], v[8:9] op_sel:[0,1,0]
	v_cvt_pk_f32_fp8_sdwa v[244:245], v200 src0_sel:WORD_1
	v_pk_fma_f32 v[10:11], v[240:241], v[238:239], v[10:11] op_sel:[0,1,0]
	v_cvt_pk_f32_fp8_e32 v[240:241], v201
	v_pk_fma_f32 v[4:5], v[242:243], v[238:239], v[4:5] op_sel:[0,1,0]
	v_cvt_pk_f32_fp8_sdwa v[242:243], v201 src0_sel:WORD_1
	v_pk_fma_f32 v[6:7], v[244:245], v[238:239], v[6:7] op_sel:[0,1,0]
	v_pk_fma_f32 v[0:1], v[240:241], v[238:239], v[0:1] op_sel:[0,1,0]
	v_pk_fma_f32 v[2:3], v[242:243], v[238:239], v[2:3] op_sel:[0,1,0]
	v_readlane_b32 s0, v135, 63
	s_lshl_b32 s0, s0, 10
	s_add_u32 s4, s6, s0
	s_addc_u32 s5, s7, 0
	global_load_dwordx4 v[198:201], v16, s[4:5]
	s_waitcnt vmcnt(15)
	v_cvt_pk_f32_fp8_e32 v[240:241], v136
	v_cvt_pk_f32_fp8_sdwa v[242:243], v136 src0_sel:WORD_1
	v_cvt_pk_f32_fp8_e32 v[244:245], v137
	v_cvt_pk_f32_fp8_sdwa v[202:203], v137 src0_sel:WORD_1
	v_pk_mul_f32 v[204:205], v[240:241], v[52:53]
	v_pk_mul_f32 v[206:207], v[242:243], v[54:55]
	v_cvt_pk_f32_fp8_e32 v[240:241], v138
	v_cvt_pk_f32_fp8_sdwa v[242:243], v138 src0_sel:WORD_1
	v_pk_fma_f32 v[204:205], v[244:245], v[56:57], v[204:205]
	v_pk_fma_f32 v[206:207], v[202:203], v[58:59], v[206:207]
	v_cvt_pk_f32_fp8_e32 v[244:245], v139
	v_cvt_pk_f32_fp8_sdwa v[202:203], v139 src0_sel:WORD_1
	v_pk_fma_f32 v[204:205], v[240:241], v[60:61], v[204:205]
	v_pk_fma_f32 v[206:207], v[242:243], v[62:63], v[206:207]
	v_pk_fma_f32 v[204:205], v[244:245], v[64:65], v[204:205]
	v_pk_fma_f32 v[206:207], v[202:203], v[66:67], v[206:207]
	v_readlane_b32 s0, v135, 48
	s_lshl_b32 s0, s0, 10
	s_add_u32 s4, s8, s0
	s_addc_u32 s5, s9, 0
	global_load_dwordx4 v[136:139], v16, s[4:5]
	v_pk_add_f32 v[204:205], v[204:205], v[206:207]
	s_nop 0
	v_add_f32_e32 v235, v204, v205
	s_waitcnt vmcnt(15)
; DI float sum8(float v) { v += DPPF(v, 0xB1); v += DPPF(v, 0x4E); v += DPPF(v, 0x141); return v; }
; DI void topk_phase(const bf16_t* PROJ, const unsigned char* K8, const unsigned char* V8, const unsigned short* SC, bf16_t* ODSA, int c, char* smem, int bid, int nb) {
;     ...
;         const size_t ro = (size_t)__builtin_amdgcn_readlane(mysel, jj) * 1024 + lane * 16;
;         const uint4 a = *(const uint4*)(K8 + ro), vv = *(const uint4*)(V8 + ro);
;         const unsigned w[4] = {a.x, a.y, a.z, a.w}, u[4] = {vv.x, vv.y, vv.z, vv.w};
;         float da = 0.f;
; #pragma unroll
;         for (int i = 0; i < 4; ++i) {
;           const f32x2v lo = __builtin_amdgcn_cvt_pk_f32_fp8((int)w[i], false), hi = __builtin_amdgcn_cvt_pk_f32_fp8((int)w[i], true);
;           da += qv[4 * i] * lo[0] + qv[4 * i + 1] * lo[1] + qv[4 * i + 2] * hi[0] + qv[4 * i + 3] * hi[1];
;         }
;         da = sum8(da);
;         da = j < count ? da : -3e30f;
	v_cvt_pk_f32_fp8_e32 v[240:241], v140
	v_cvt_pk_f32_fp8_sdwa v[242:243], v140 src0_sel:WORD_1
	v_cvt_pk_f32_fp8_e32 v[244:245], v141
	v_cvt_pk_f32_fp8_sdwa v[202:203], v141 src0_sel:WORD_1
	v_add_f32_dpp v235, v235, v235 quad_perm:[1,0,3,2] row_mask:0xf bank_mask:0xf bound_ctrl:1
	v_pk_mul_f32 v[204:205], v[240:241], v[52:53]
	v_pk_mul_f32 v[206:207], v[242:243], v[54:55]
	v_add_f32_dpp v235, v235, v235 quad_perm:[2,3,0,1] row_mask:0xf bank_mask:0xf bound_ctrl:1
	v_cvt_pk_f32_fp8_e32 v[240:241], v142
	v_cvt_pk_f32_fp8_sdwa v[242:243], v142 src0_sel:WORD_1
	v_add_f32_dpp v235, v235, v235 row_half_mirror row_mask:0xf bank_mask:0xf bound_ctrl:1
	v_pk_fma_f32 v[204:205], v[244:245], v[56:57], v[204:205]
	v_pk_fma_f32 v[206:207], v[202:203], v[58:59], v[206:207]
	s_add_i32 s0, s1, 48
	s_cmp_lt_i32 s0, s2
	s_cselect_b64 vcc, -1, 0
	v_cvt_pk_f32_fp8_e32 v[244:245], v143
	v_cvt_pk_f32_fp8_sdwa v[202:203], v143 src0_sel:WORD_1
	v_cndmask_b32_e32 v210, v220, v235, vcc
	v_pk_fma_f32 v[204:205], v[240:241], v[60:61], v[204:205]
	v_pk_fma_f32 v[206:207], v[242:243], v[62:63], v[206:207]
	v_pk_fma_f32 v[204:205], v[244:245], v[64:65], v[204:205]
	v_pk_fma_f32 v[206:207], v[202:203], v[66:67], v[206:207]
	v_readlane_b32 s0, v135, 49
	s_lshl_b32 s0, s0, 10
	s_add_u32 s4, s8, s0
	s_addc_u32 s5, s9, 0
	global_load_dwordx4 v[140:143], v16, s[4:5]
	v_pk_add_f32 v[204:205], v[204:205], v[206:207]
	s_nop 0
	v_add_f32_e32 v221, v204, v205
	s_waitcnt vmcnt(15)
	v_cvt_pk_f32_fp8_e32 v[240:241], v144
	v_cvt_pk_f32_fp8_sdwa v[242:243], v144 src0_sel:WORD_1
	v_cvt_pk_f32_fp8_e32 v[244:245], v145
	v_cvt_pk_f32_fp8_sdwa v[202:203], v145 src0_sel:WORD_1
	v_add_f32_dpp v221, v221, v221 quad_perm:[1,0,3,2] row_mask:0xf bank_mask:0xf bound_ctrl:1
	v_pk_mul_f32 v[204:205], v[240:241], v[52:53]
	v_pk_mul_f32 v[206:207], v[242:243], v[54:55]
	v_add_f32_dpp v221, v221, v221 quad_perm:[2,3,0,1] row_mask:0xf bank_mask:0xf bound_ctrl:1
	v_cvt_pk_f32_fp8_e32 v[240:241], v146
	v_cvt_pk_f32_fp8_sdwa v[242:243], v146 src0_sel:WORD_1
	v_add_f32_dpp v221, v221, v221 row_half_mirror row_mask:0xf bank_mask:0xf bound_ctrl:1
	v_pk_fma_f32 v[204:205], v[244:245], v[56:57], v[204:205]
	v_pk_fma_f32 v[206:207], v[202:203], v[58:59], v[206:207]
	s_add_i32 s0, s1, 49
	s_cmp_lt_i32 s0, s2
	s_cselect_b64 vcc, -1, 0
	v_cvt_pk_f32_fp8_e32 v[244:245], v147
	v_cvt_pk_f32_fp8_sdwa v[202:203], v147 src0_sel:WORD_1
	v_cndmask_b32_e32 v211, v220, v221, vcc
	v_pk_fma_f32 v[204:205], v[240:241], v[60:61], v[204:205]
	v_pk_fma_f32 v[206:207], v[242:243], v[62:63], v[206:207]
	v_pk_fma_f32 v[204:205], v[244:245], v[64:65], v[204:205]
	v_pk_fma_f32 v[206:207], v[202:203], v[66:67], v[206:207]
	v_readlane_b32 s0, v135, 50
	s_lshl_b32 s0, s0, 10
	s_add_u32 s4, s8, s0
	s_addc_u32 s5, s9, 0
	global_load_dwordx4 v[144:147], v16, s[4:5]
	v_pk_add_f32 v[204:205], v[204:205], v[206:207]
	s_nop 0
	v_add_f32_e32 v235, v204, v205
	s_waitcnt vmcnt(15)
	v_cvt_pk_f32_fp8_e32 v[240:241], v148
	v_cvt_pk_f32_fp8_sdwa v[242:243], v148 src0_sel:WORD_1
	v_cvt_pk_f32_fp8_e32 v[244:245], v149
	v_cvt_pk_f32_fp8_sdwa v[202:203], v149 src0_sel:WORD_1
	v_add_f32_dpp v235, v235, v235 quad_perm:[1,0,3,2] row_mask:0xf bank_mask:0xf bound_ctrl:1
	v_pk_mul_f32 v[204:205], v[240:241], v[52:53]
	v_pk_mul_f32 v[206:207], v[242:243], v[54:55]
	v_add_f32_dpp v235, v235, v235 quad_perm:[2,3,0,1] row_mask:0xf bank_mask:0xf bound_ctrl:1
	v_cvt_pk_f32_fp8_e32 v[240:241], v150
	v_cvt_pk_f32_fp8_sdwa v[242:243], v150 src0_sel:WORD_1
	v_add_f32_dpp v235, v235, v235 row_half_mirror row_mask:0xf bank_mask:0xf bound_ctrl:1
	v_pk_fma_f32 v[204:205], v[244:245], v[56:57], v[204:205]
	v_pk_fma_f32 v[206:207], v[202:203], v[58:59], v[206:207]
	s_add_i32 s0, s1, 50
	s_cmp_lt_i32 s0, s2
	s_cselect_b64 vcc, -1, 0
	v_cvt_pk_f32_fp8_e32 v[244:245], v151
	v_cvt_pk_f32_fp8_sdwa v[202:203], v151 src0_sel:WORD_1
	v_cndmask_b32_e32 v212, v220, v235, vcc
	v_pk_fma_f32 v[204:205], v[240:241], v[60:61], v[204:205]
	v_pk_fma_f32 v[206:207], v[242:243], v[62:63], v[206:207]
	v_pk_fma_f32 v[204:205], v[244:245], v[64:65], v[204:205]
	v_pk_fma_f32 v[206:207], v[202:203], v[66:67], v[206:207]
	v_readlane_b32 s0, v135, 51
	s_lshl_b32 s0, s0, 10
	s_add_u32 s4, s8, s0
	s_addc_u32 s5, s9, 0
	global_load_dwordx4 v[148:151], v16, s[4:5]
	v_pk_add_f32 v[204:205], v[204:205], v[206:207]
	s_nop 0
	v_add_f32_e32 v221, v204, v205
	s_waitcnt vmcnt(15)
	v_cvt_pk_f32_fp8_e32 v[240:241], v152
	v_cvt_pk_f32_fp8_sdwa v[242:243], v152 src0_sel:WORD_1
	v_cvt_pk_f32_fp8_e32 v[244:245], v153
	v_cvt_pk_f32_fp8_sdwa v[202:203], v153 src0_sel:WORD_1
	v_add_f32_dpp v221, v221, v221 quad_perm:[1,0,3,2] row_mask:0xf bank_mask:0xf bound_ctrl:1
	v_pk_mul_f32 v[204:205], v[240:241], v[52:53]
	v_pk_mul_f32 v[206:207], v[242:243], v[54:55]
	v_add_f32_dpp v221, v221, v221 quad_perm:[2,3,0,1] row_mask:0xf bank_mask:0xf bound_ctrl:1
	v_cvt_pk_f32_fp8_e32 v[240:241], v154
	v_cvt_pk_f32_fp8_sdwa v[242:243], v154 src0_sel:WORD_1
	v_add_f32_dpp v221, v221, v221 row_half_mirror row_mask:0xf bank_mask:0xf bound_ctrl:1
	v_pk_fma_f32 v[204:205], v[244:245], v[56:57], v[204:205]
	v_pk_fma_f32 v[206:207], v[202:203], v[58:59], v[206:207]
	s_add_i32 s0, s1, 51
	s_cmp_lt_i32 s0, s2
	s_cselect_b64 vcc, -1, 0
	v_cvt_pk_f32_fp8_e32 v[244:245], v155
	v_cvt_pk_f32_fp8_sdwa v[202:203], v155 src0_sel:WORD_1
	v_cndmask_b32_e32 v213, v220, v221, vcc
	v_pk_fma_f32 v[204:205], v[240:241], v[60:61], v[204:205]
	v_pk_fma_f32 v[206:207], v[242:243], v[62:63], v[206:207]
	v_pk_fma_f32 v[204:205], v[244:245], v[64:65], v[204:205]
	v_pk_fma_f32 v[206:207], v[202:203], v[66:67], v[206:207]
	v_readlane_b32 s0, v135, 52
	s_lshl_b32 s0, s0, 10
	s_add_u32 s4, s8, s0
	s_addc_u32 s5, s9, 0
	global_load_dwordx4 v[152:155], v16, s[4:5]
	v_pk_add_f32 v[204:205], v[204:205], v[206:207]
	s_nop 0
	v_add_f32_e32 v235, v204, v205
	s_waitcnt vmcnt(15)
; DI float sum8(float v) { v += DPPF(v, 0xB1); v += DPPF(v, 0x4E); v += DPPF(v, 0x141); return v; }
; DI void topk_phase(const bf16_t* PROJ, const unsigned char* K8, const unsigned char* V8, const unsigned short* SC, bf16_t* ODSA, int c, char* smem, int bid, int nb) {
;     ...
;         const size_t ro = (size_t)__builtin_amdgcn_readlane(mysel, jj) * 1024 + lane * 16;
;         const uint4 a = *(const uint4*)(K8 + ro), vv = *(const uint4*)(V8 + ro);
;         const unsigned w[4] = {a.x, a.y, a.z, a.w}, u[4] = {vv.x, vv.y, vv.z, vv.w};
;         float da = 0.f;
; #pragma unroll
;         for (int i = 0; i < 4; ++i) {
;           const f32x2v lo = __builtin_amdgcn_cvt_pk_f32_fp8((int)w[i], false), hi = __builtin_amdgcn_cvt_pk_f32_fp8((int)w[i], true);
;           da += qv[4 * i] * lo[0] + qv[4 * i + 1] * lo[1] + qv[4 * i + 2] * hi[0] + qv[4 * i + 3] * hi[1];
;         }
;         da = sum8(da);
;         da = j < count ? da : -3e30f;
	v_cvt_pk_f32_fp8_e32 v[240:241], v156
	v_cvt_pk_f32_fp8_sdwa v[242:243], v156 src0_sel:WORD_1
	v_cvt_pk_f32_fp8_e32 v[244:245], v157
	v_cvt_pk_f32_fp8_sdwa v[202:203], v157 src0_sel:WORD_1
	v_add_f32_dpp v235, v235, v235 quad_perm:[1,0,3,2] row_mask:0xf bank_mask:0xf bound_ctrl:1
	v_pk_mul_f32 v[204:205], v[240:241], v[52:53]
	v_pk_mul_f32 v[206:207], v[242:243], v[54:55]
	v_add_f32_dpp v235, v235, v235 quad_perm:[2,3,0,1] row_mask:0xf bank_mask:0xf bound_ctrl:1
	v_cvt_pk_f32_fp8_e32 v[240:241], v158
	v_cvt_pk_f32_fp8_sdwa v[242:243], v158 src0_sel:WORD_1
	v_add_f32_dpp v235, v235, v235 row_half_mirror row_mask:0xf bank_mask:0xf bound_ctrl:1
	v_pk_fma_f32 v[204:205], v[244:245], v[56:57], v[204:205]
	v_pk_fma_f32 v[206:207], v[202:203], v[58:59], v[206:207]
	s_add_i32 s0, s1, 52
	s_cmp_lt_i32 s0, s2
	s_cselect_b64 vcc, -1, 0
	v_cvt_pk_f32_fp8_e32 v[244:245], v159
	v_cvt_pk_f32_fp8_sdwa v[202:203], v159 src0_sel:WORD_1
	v_cndmask_b32_e32 v226, v220, v235, vcc
	v_pk_fma_f32 v[204:205], v[240:241], v[60:61], v[204:205]
	v_pk_fma_f32 v[206:207], v[242:243], v[62:63], v[206:207]
	v_pk_fma_f32 v[204:205], v[244:245], v[64:65], v[204:205]
	v_pk_fma_f32 v[206:207], v[202:203], v[66:67], v[206:207]
	v_readlane_b32 s0, v135, 53
	s_lshl_b32 s0, s0, 10
	s_add_u32 s4, s8, s0
	s_addc_u32 s5, s9, 0
	global_load_dwordx4 v[156:159], v16, s[4:5]
	v_pk_add_f32 v[204:205], v[204:205], v[206:207]
	s_nop 0
	v_add_f32_e32 v221, v204, v205
	s_waitcnt vmcnt(15)
	v_cvt_pk_f32_fp8_e32 v[240:241], v160
	v_cvt_pk_f32_fp8_sdwa v[242:243], v160 src0_sel:WORD_1
	v_cvt_pk_f32_fp8_e32 v[244:245], v161
	v_cvt_pk_f32_fp8_sdwa v[202:203], v161 src0_sel:WORD_1
	v_add_f32_dpp v221, v221, v221 quad_perm:[1,0,3,2] row_mask:0xf bank_mask:0xf bound_ctrl:1
	v_pk_mul_f32 v[204:205], v[240:241], v[52:53]
	v_pk_mul_f32 v[206:207], v[242:243], v[54:55]
	v_add_f32_dpp v221, v221, v221 quad_perm:[2,3,0,1] row_mask:0xf bank_mask:0xf bound_ctrl:1
	v_cvt_pk_f32_fp8_e32 v[240:241], v162
	v_cvt_pk_f32_fp8_sdwa v[242:243], v162 src0_sel:WORD_1
	v_add_f32_dpp v221, v221, v221 row_half_mirror row_mask:0xf bank_mask:0xf bound_ctrl:1
	v_pk_fma_f32 v[204:205], v[244:245], v[56:57], v[204:205]
	v_pk_fma_f32 v[206:207], v[202:203], v[58:59], v[206:207]
	s_add_i32 s0, s1, 53
	s_cmp_lt_i32 s0, s2
	s_cselect_b64 vcc, -1, 0
	v_cvt_pk_f32_fp8_e32 v[244:245], v163
	v_cvt_pk_f32_fp8_sdwa v[202:203], v163 src0_sel:WORD_1
	v_cndmask_b32_e32 v227, v220, v221, vcc
	v_pk_fma_f32 v[204:205], v[240:241], v[60:61], v[204:205]
	v_pk_fma_f32 v[206:207], v[242:243], v[62:63], v[206:207]
	v_pk_fma_f32 v[204:205], v[244:245], v[64:65], v[204:205]
	v_pk_fma_f32 v[206:207], v[202:203], v[66:67], v[206:207]
	v_readlane_b32 s0, v135, 54
	s_lshl_b32 s0, s0, 10
	s_add_u32 s4, s8, s0
	s_addc_u32 s5, s9, 0
	global_load_dwordx4 v[160:163], v16, s[4:5]
	v_pk_add_f32 v[204:205], v[204:205], v[206:207]
	s_nop 0
	v_add_f32_e32 v235, v204, v205
	s_waitcnt vmcnt(15)
	v_cvt_pk_f32_fp8_e32 v[240:241], v164
	v_cvt_pk_f32_fp8_sdwa v[242:243], v164 src0_sel:WORD_1
	v_cvt_pk_f32_fp8_e32 v[244:245], v165
	v_cvt_pk_f32_fp8_sdwa v[202:203], v165 src0_sel:WORD_1
	v_add_f32_dpp v235, v235, v235 quad_perm:[1,0,3,2] row_mask:0xf bank_mask:0xf bound_ctrl:1
	v_pk_mul_f32 v[204:205], v[240:241], v[52:53]
	v_pk_mul_f32 v[206:207], v[242:243], v[54:55]
	v_add_f32_dpp v235, v235, v235 quad_perm:[2,3,0,1] row_mask:0xf bank_mask:0xf bound_ctrl:1
	v_cvt_pk_f32_fp8_e32 v[240:241], v166
	v_cvt_pk_f32_fp8_sdwa v[242:243], v166 src0_sel:WORD_1
	v_add_f32_dpp v235, v235, v235 row_half_mirror row_mask:0xf bank_mask:0xf bound_ctrl:1
	v_pk_fma_f32 v[204:205], v[244:245], v[56:57], v[204:205]
	v_pk_fma_f32 v[206:207], v[202:203], v[58:59], v[206:207]
	s_add_i32 s0, s1, 54
	s_cmp_lt_i32 s0, s2
	s_cselect_b64 vcc, -1, 0
	v_cvt_pk_f32_fp8_e32 v[244:245], v167
	v_cvt_pk_f32_fp8_sdwa v[202:203], v167 src0_sel:WORD_1
	v_cndmask_b32_e32 v228, v220, v235, vcc
	v_pk_fma_f32 v[204:205], v[240:241], v[60:61], v[204:205]
	v_pk_fma_f32 v[206:207], v[242:243], v[62:63], v[206:207]
	v_pk_fma_f32 v[204:205], v[244:245], v[64:65], v[204:205]
	v_pk_fma_f32 v[206:207], v[202:203], v[66:67], v[206:207]
	v_readlane_b32 s0, v135, 55
	s_lshl_b32 s0, s0, 10
	s_add_u32 s4, s8, s0
	s_addc_u32 s5, s9, 0
	global_load_dwordx4 v[164:167], v16, s[4:5]
	v_pk_add_f32 v[204:205], v[204:205], v[206:207]
	s_nop 0
	v_add_f32_e32 v221, v204, v205
	s_waitcnt vmcnt(15)
	v_cvt_pk_f32_fp8_e32 v[240:241], v168
	v_cvt_pk_f32_fp8_sdwa v[242:243], v168 src0_sel:WORD_1
	v_cvt_pk_f32_fp8_e32 v[244:245], v169
	v_cvt_pk_f32_fp8_sdwa v[202:203], v169 src0_sel:WORD_1
	v_add_f32_dpp v221, v221, v221 quad_perm:[1,0,3,2] row_mask:0xf bank_mask:0xf bound_ctrl:1
	v_pk_mul_f32 v[204:205], v[240:241], v[52:53]
	v_pk_mul_f32 v[206:207], v[242:243], v[54:55]
	v_add_f32_dpp v221, v221, v221 quad_perm:[2,3,0,1] row_mask:0xf bank_mask:0xf bound_ctrl:1
	v_cvt_pk_f32_fp8_e32 v[240:241], v170
	v_cvt_pk_f32_fp8_sdwa v[242:243], v170 src0_sel:WORD_1
	v_add_f32_dpp v221, v221, v221 row_half_mirror row_mask:0xf bank_mask:0xf bound_ctrl:1
	v_pk_fma_f32 v[204:205], v[244:245], v[56:57], v[204:205]
	v_pk_fma_f32 v[206:207], v[202:203], v[58:59], v[206:207]
	s_add_i32 s0, s1, 55
	s_cmp_lt_i32 s0, s2
	s_cselect_b64 vcc, -1, 0
	v_cvt_pk_f32_fp8_e32 v[244:245], v171
	v_cvt_pk_f32_fp8_sdwa v[202:203], v171 src0_sel:WORD_1
	v_cndmask_b32_e32 v229, v220, v221, vcc
	v_pk_fma_f32 v[204:205], v[240:241], v[60:61], v[204:205]
	v_pk_fma_f32 v[206:207], v[242:243], v[62:63], v[206:207]
	v_pk_fma_f32 v[204:205], v[244:245], v[64:65], v[204:205]
	v_pk_fma_f32 v[206:207], v[202:203], v[66:67], v[206:207]
	v_readlane_b32 s0, v135, 56
	s_lshl_b32 s0, s0, 10
	s_add_u32 s4, s8, s0
	s_addc_u32 s5, s9, 0
	global_load_dwordx4 v[168:171], v16, s[4:5]
	v_pk_add_f32 v[204:205], v[204:205], v[206:207]
	s_nop 0
	v_add_f32_e32 v235, v204, v205
	s_waitcnt vmcnt(15)
; DI float sum8(float v) { v += DPPF(v, 0xB1); v += DPPF(v, 0x4E); v += DPPF(v, 0x141); return v; }
; DI void topk_phase(const bf16_t* PROJ, const unsigned char* K8, const unsigned char* V8, const unsigned short* SC, bf16_t* ODSA, int c, char* smem, int bid, int nb) {
;     ...
;         const size_t ro = (size_t)__builtin_amdgcn_readlane(mysel, jj) * 1024 + lane * 16;
;         const uint4 a = *(const uint4*)(K8 + ro), vv = *(const uint4*)(V8 + ro);
;         const unsigned w[4] = {a.x, a.y, a.z, a.w}, u[4] = {vv.x, vv.y, vv.z, vv.w};
;         float da = 0.f;
; #pragma unroll
;         for (int i = 0; i < 4; ++i) {
;           const f32x2v lo = __builtin_amdgcn_cvt_pk_f32_fp8((int)w[i], false), hi = __builtin_amdgcn_cvt_pk_f32_fp8((int)w[i], true);
;           da += qv[4 * i] * lo[0] + qv[4 * i + 1] * lo[1] + qv[4 * i + 2] * hi[0] + qv[4 * i + 3] * hi[1];
;         }
;         da = sum8(da);
;         da = j < count ? da : -3e30f;
	v_cvt_pk_f32_fp8_e32 v[240:241], v172
	v_cvt_pk_f32_fp8_sdwa v[242:243], v172 src0_sel:WORD_1
	v_cvt_pk_f32_fp8_e32 v[244:245], v173
	v_cvt_pk_f32_fp8_sdwa v[202:203], v173 src0_sel:WORD_1
	v_add_f32_dpp v235, v235, v235 quad_perm:[1,0,3,2] row_mask:0xf bank_mask:0xf bound_ctrl:1
	v_pk_mul_f32 v[204:205], v[240:241], v[52:53]
	v_pk_mul_f32 v[206:207], v[242:243], v[54:55]
	v_add_f32_dpp v235, v235, v235 quad_perm:[2,3,0,1] row_mask:0xf bank_mask:0xf bound_ctrl:1
	v_cvt_pk_f32_fp8_e32 v[240:241], v174
	v_cvt_pk_f32_fp8_sdwa v[242:243], v174 src0_sel:WORD_1
	v_add_f32_dpp v235, v235, v235 row_half_mirror row_mask:0xf bank_mask:0xf bound_ctrl:1
	v_pk_fma_f32 v[204:205], v[244:245], v[56:57], v[204:205]
	v_pk_fma_f32 v[206:207], v[202:203], v[58:59], v[206:207]
	s_add_i32 s0, s1, 56
	s_cmp_lt_i32 s0, s2
	s_cselect_b64 vcc, -1, 0
	v_cvt_pk_f32_fp8_e32 v[244:245], v175
	v_cvt_pk_f32_fp8_sdwa v[202:203], v175 src0_sel:WORD_1
	v_cndmask_b32_e32 v230, v220, v235, vcc
	v_pk_fma_f32 v[204:205], v[240:241], v[60:61], v[204:205]
	v_pk_fma_f32 v[206:207], v[242:243], v[62:63], v[206:207]
	v_pk_fma_f32 v[204:205], v[244:245], v[64:65], v[204:205]
	v_pk_fma_f32 v[206:207], v[202:203], v[66:67], v[206:207]
	v_readlane_b32 s0, v135, 57
	s_lshl_b32 s0, s0, 10
	s_add_u32 s4, s8, s0
	s_addc_u32 s5, s9, 0
	global_load_dwordx4 v[172:175], v16, s[4:5]
	v_pk_add_f32 v[204:205], v[204:205], v[206:207]
	s_nop 0
	v_add_f32_e32 v221, v204, v205
	s_waitcnt vmcnt(15)
	v_cvt_pk_f32_fp8_e32 v[240:241], v176
	v_cvt_pk_f32_fp8_sdwa v[242:243], v176 src0_sel:WORD_1
	v_cvt_pk_f32_fp8_e32 v[244:245], v177
	v_cvt_pk_f32_fp8_sdwa v[202:203], v177 src0_sel:WORD_1
	v_add_f32_dpp v221, v221, v221 quad_perm:[1,0,3,2] row_mask:0xf bank_mask:0xf bound_ctrl:1
	v_pk_mul_f32 v[204:205], v[240:241], v[52:53]
	v_pk_mul_f32 v[206:207], v[242:243], v[54:55]
	v_add_f32_dpp v221, v221, v221 quad_perm:[2,3,0,1] row_mask:0xf bank_mask:0xf bound_ctrl:1
	v_cvt_pk_f32_fp8_e32 v[240:241], v178
	v_cvt_pk_f32_fp8_sdwa v[242:243], v178 src0_sel:WORD_1
	v_add_f32_dpp v221, v221, v221 row_half_mirror row_mask:0xf bank_mask:0xf bound_ctrl:1
	v_pk_fma_f32 v[204:205], v[244:245], v[56:57], v[204:205]
	v_pk_fma_f32 v[206:207], v[202:203], v[58:59], v[206:207]
	s_add_i32 s0, s1, 57
	s_cmp_lt_i32 s0, s2
	s_cselect_b64 vcc, -1, 0
	v_cvt_pk_f32_fp8_e32 v[244:245], v179
	v_cvt_pk_f32_fp8_sdwa v[202:203], v179 src0_sel:WORD_1
	v_cndmask_b32_e32 v231, v220, v221, vcc
	v_pk_fma_f32 v[204:205], v[240:241], v[60:61], v[204:205]
	v_pk_fma_f32 v[206:207], v[242:243], v[62:63], v[206:207]
	v_pk_fma_f32 v[204:205], v[244:245], v[64:65], v[204:205]
	v_pk_fma_f32 v[206:207], v[202:203], v[66:67], v[206:207]
	v_readlane_b32 s0, v135, 58
	s_lshl_b32 s0, s0, 10
	s_add_u32 s4, s8, s0
	s_addc_u32 s5, s9, 0
	global_load_dwordx4 v[176:179], v16, s[4:5]
	v_pk_add_f32 v[204:205], v[204:205], v[206:207]
	s_nop 0
	v_add_f32_e32 v235, v204, v205
	s_waitcnt vmcnt(15)
	v_cvt_pk_f32_fp8_e32 v[240:241], v180
	v_cvt_pk_f32_fp8_sdwa v[242:243], v180 src0_sel:WORD_1
	v_cvt_pk_f32_fp8_e32 v[244:245], v181
	v_cvt_pk_f32_fp8_sdwa v[202:203], v181 src0_sel:WORD_1
	v_add_f32_dpp v235, v235, v235 quad_perm:[1,0,3,2] row_mask:0xf bank_mask:0xf bound_ctrl:1
	v_pk_mul_f32 v[204:205], v[240:241], v[52:53]
	v_pk_mul_f32 v[206:207], v[242:243], v[54:55]
	v_add_f32_dpp v235, v235, v235 quad_perm:[2,3,0,1] row_mask:0xf bank_mask:0xf bound_ctrl:1
	v_cvt_pk_f32_fp8_e32 v[240:241], v182
	v_cvt_pk_f32_fp8_sdwa v[242:243], v182 src0_sel:WORD_1
	v_add_f32_dpp v235, v235, v235 row_half_mirror row_mask:0xf bank_mask:0xf bound_ctrl:1
	v_pk_fma_f32 v[204:205], v[244:245], v[56:57], v[204:205]
	v_pk_fma_f32 v[206:207], v[202:203], v[58:59], v[206:207]
	s_add_i32 s0, s1, 58
	s_cmp_lt_i32 s0, s2
	s_cselect_b64 vcc, -1, 0
	v_cvt_pk_f32_fp8_e32 v[244:245], v183
	v_cvt_pk_f32_fp8_sdwa v[202:203], v183 src0_sel:WORD_1
	v_cndmask_b32_e32 v232, v220, v235, vcc
	v_pk_fma_f32 v[204:205], v[240:241], v[60:61], v[204:205]
	v_pk_fma_f32 v[206:207], v[242:243], v[62:63], v[206:207]
	v_pk_fma_f32 v[204:205], v[244:245], v[64:65], v[204:205]
	v_pk_fma_f32 v[206:207], v[202:203], v[66:67], v[206:207]
	v_readlane_b32 s0, v135, 59
	s_lshl_b32 s0, s0, 10
	s_add_u32 s4, s8, s0
	s_addc_u32 s5, s9, 0
	global_load_dwordx4 v[180:183], v16, s[4:5]
	v_pk_add_f32 v[204:205], v[204:205], v[206:207]
	s_nop 0
	v_add_f32_e32 v221, v204, v205
	s_waitcnt vmcnt(15)
	v_cvt_pk_f32_fp8_e32 v[240:241], v186
	v_cvt_pk_f32_fp8_sdwa v[242:243], v186 src0_sel:WORD_1
	v_cvt_pk_f32_fp8_e32 v[244:245], v187
	v_cvt_pk_f32_fp8_sdwa v[202:203], v187 src0_sel:WORD_1
	v_add_f32_dpp v221, v221, v221 quad_perm:[1,0,3,2] row_mask:0xf bank_mask:0xf bound_ctrl:1
	v_pk_mul_f32 v[204:205], v[240:241], v[52:53]
	v_pk_mul_f32 v[206:207], v[242:243], v[54:55]
	v_add_f32_dpp v221, v221, v221 quad_perm:[2,3,0,1] row_mask:0xf bank_mask:0xf bound_ctrl:1
	v_cvt_pk_f32_fp8_e32 v[240:241], v188
	v_cvt_pk_f32_fp8_sdwa v[242:243], v188 src0_sel:WORD_1
	v_add_f32_dpp v221, v221, v221 row_half_mirror row_mask:0xf bank_mask:0xf bound_ctrl:1
	v_pk_fma_f32 v[204:205], v[244:245], v[56:57], v[204:205]
	v_pk_fma_f32 v[206:207], v[202:203], v[58:59], v[206:207]
	s_add_i32 s0, s1, 59
	s_cmp_lt_i32 s0, s2
	s_cselect_b64 vcc, -1, 0
	v_cvt_pk_f32_fp8_e32 v[244:245], v189
	v_cvt_pk_f32_fp8_sdwa v[202:203], v189 src0_sel:WORD_1
	v_cndmask_b32_e32 v233, v220, v221, vcc
	v_pk_fma_f32 v[204:205], v[240:241], v[60:61], v[204:205]
	v_pk_fma_f32 v[206:207], v[242:243], v[62:63], v[206:207]
	v_pk_fma_f32 v[204:205], v[244:245], v[64:65], v[204:205]
	v_pk_fma_f32 v[206:207], v[202:203], v[66:67], v[206:207]
	v_readlane_b32 s0, v135, 60
	s_lshl_b32 s0, s0, 10
	s_add_u32 s4, s8, s0
	s_addc_u32 s5, s9, 0
	global_load_dwordx4 v[186:189], v16, s[4:5]
	v_pk_add_f32 v[204:205], v[204:205], v[206:207]
	s_nop 0
	v_add_f32_e32 v235, v204, v205
	s_waitcnt vmcnt(15)
; DI float sum8(float v) { v += DPPF(v, 0xB1); v += DPPF(v, 0x4E); v += DPPF(v, 0x141); return v; }
; DI void topk_phase(const bf16_t* PROJ, const unsigned char* K8, const unsigned char* V8, const unsigned short* SC, bf16_t* ODSA, int c, char* smem, int bid, int nb) {
;     ...
;         const size_t ro = (size_t)__builtin_amdgcn_readlane(mysel, jj) * 1024 + lane * 16;
;         const uint4 a = *(const uint4*)(K8 + ro), vv = *(const uint4*)(V8 + ro);
;         const unsigned w[4] = {a.x, a.y, a.z, a.w}, u[4] = {vv.x, vv.y, vv.z, vv.w};
;         float da = 0.f;
; #pragma unroll
;         for (int i = 0; i < 4; ++i) {
;           const f32x2v lo = __builtin_amdgcn_cvt_pk_f32_fp8((int)w[i], false), hi = __builtin_amdgcn_cvt_pk_f32_fp8((int)w[i], true);
;           da += qv[4 * i] * lo[0] + qv[4 * i + 1] * lo[1] + qv[4 * i + 2] * hi[0] + qv[4 * i + 3] * hi[1];
;         }
;         da = sum8(da);
;         da = j < count ? da : -3e30f;
;         const float mn = fmaxf(m_run, da), al = __builtin_amdgcn_exp2f(m_run - mn), pp = __builtin_amdgcn_exp2f(da - mn);
;         m_run = mn; l_run = l_run * al + pp;
; #pragma unroll
	v_cvt_pk_f32_fp8_e32 v[240:241], v190
	v_cvt_pk_f32_fp8_sdwa v[242:243], v190 src0_sel:WORD_1
	v_cvt_pk_f32_fp8_e32 v[244:245], v191
	v_cvt_pk_f32_fp8_sdwa v[202:203], v191 src0_sel:WORD_1
	v_add_f32_dpp v235, v235, v235 quad_perm:[1,0,3,2] row_mask:0xf bank_mask:0xf bound_ctrl:1
	v_pk_mul_f32 v[204:205], v[240:241], v[52:53]
	v_pk_mul_f32 v[206:207], v[242:243], v[54:55]
	v_add_f32_dpp v235, v235, v235 quad_perm:[2,3,0,1] row_mask:0xf bank_mask:0xf bound_ctrl:1
	v_cvt_pk_f32_fp8_e32 v[240:241], v192
	v_cvt_pk_f32_fp8_sdwa v[242:243], v192 src0_sel:WORD_1
	v_add_f32_dpp v235, v235, v235 row_half_mirror row_mask:0xf bank_mask:0xf bound_ctrl:1
	v_pk_fma_f32 v[204:205], v[244:245], v[56:57], v[204:205]
	v_pk_fma_f32 v[206:207], v[202:203], v[58:59], v[206:207]
	s_add_i32 s0, s1, 60
	s_cmp_lt_i32 s0, s2
	s_cselect_b64 vcc, -1, 0
	v_cvt_pk_f32_fp8_e32 v[244:245], v193
	v_cvt_pk_f32_fp8_sdwa v[202:203], v193 src0_sel:WORD_1
	v_cndmask_b32_e32 v236, v220, v235, vcc
	v_pk_fma_f32 v[204:205], v[240:241], v[60:61], v[204:205]
	v_pk_fma_f32 v[206:207], v[242:243], v[62:63], v[206:207]
	v_pk_fma_f32 v[204:205], v[244:245], v[64:65], v[204:205]
	v_pk_fma_f32 v[206:207], v[202:203], v[66:67], v[206:207]
	v_readlane_b32 s0, v135, 61
	s_lshl_b32 s0, s0, 10
	s_add_u32 s4, s8, s0
	s_addc_u32 s5, s9, 0
	global_load_dwordx4 v[190:193], v16, s[4:5]
	v_pk_add_f32 v[204:205], v[204:205], v[206:207]
	s_nop 0
	v_add_f32_e32 v221, v204, v205
	s_waitcnt vmcnt(15)
	v_cvt_pk_f32_fp8_e32 v[240:241], v194
	v_cvt_pk_f32_fp8_sdwa v[242:243], v194 src0_sel:WORD_1
	v_cvt_pk_f32_fp8_e32 v[244:245], v195
	v_cvt_pk_f32_fp8_sdwa v[202:203], v195 src0_sel:WORD_1
	v_add_f32_dpp v221, v221, v221 quad_perm:[1,0,3,2] row_mask:0xf bank_mask:0xf bound_ctrl:1
	v_pk_mul_f32 v[204:205], v[240:241], v[52:53]
	v_pk_mul_f32 v[206:207], v[242:243], v[54:55]
	v_add_f32_dpp v221, v221, v221 quad_perm:[2,3,0,1] row_mask:0xf bank_mask:0xf bound_ctrl:1
	v_cvt_pk_f32_fp8_e32 v[240:241], v196
	v_cvt_pk_f32_fp8_sdwa v[242:243], v196 src0_sel:WORD_1
	v_add_f32_dpp v221, v221, v221 row_half_mirror row_mask:0xf bank_mask:0xf bound_ctrl:1
	v_pk_fma_f32 v[204:205], v[244:245], v[56:57], v[204:205]
	v_pk_fma_f32 v[206:207], v[202:203], v[58:59], v[206:207]
	s_add_i32 s0, s1, 61
	s_cmp_lt_i32 s0, s2
	s_cselect_b64 vcc, -1, 0
	v_cvt_pk_f32_fp8_e32 v[244:245], v197
	v_cvt_pk_f32_fp8_sdwa v[202:203], v197 src0_sel:WORD_1
	v_cndmask_b32_e32 v237, v220, v221, vcc
	v_pk_fma_f32 v[204:205], v[240:241], v[60:61], v[204:205]
	v_pk_fma_f32 v[206:207], v[242:243], v[62:63], v[206:207]
	v_pk_fma_f32 v[204:205], v[244:245], v[64:65], v[204:205]
	v_pk_fma_f32 v[206:207], v[202:203], v[66:67], v[206:207]
	v_readlane_b32 s0, v135, 62
	s_lshl_b32 s0, s0, 10
	s_add_u32 s4, s8, s0
	s_addc_u32 s5, s9, 0
	global_load_dwordx4 v[194:197], v16, s[4:5]
	v_pk_add_f32 v[204:205], v[204:205], v[206:207]
	s_nop 0
	v_add_f32_e32 v235, v204, v205
	s_waitcnt vmcnt(15)
	v_cvt_pk_f32_fp8_e32 v[240:241], v198
	v_cvt_pk_f32_fp8_sdwa v[242:243], v198 src0_sel:WORD_1
	v_cvt_pk_f32_fp8_e32 v[244:245], v199
	v_cvt_pk_f32_fp8_sdwa v[202:203], v199 src0_sel:WORD_1
	v_add_f32_dpp v235, v235, v235 quad_perm:[1,0,3,2] row_mask:0xf bank_mask:0xf bound_ctrl:1
	v_pk_mul_f32 v[204:205], v[240:241], v[52:53]
	v_pk_mul_f32 v[206:207], v[242:243], v[54:55]
	v_add_f32_dpp v235, v235, v235 quad_perm:[2,3,0,1] row_mask:0xf bank_mask:0xf bound_ctrl:1
	v_cvt_pk_f32_fp8_e32 v[240:241], v200
	v_cvt_pk_f32_fp8_sdwa v[242:243], v200 src0_sel:WORD_1
	v_add_f32_dpp v235, v235, v235 row_half_mirror row_mask:0xf bank_mask:0xf bound_ctrl:1
	v_pk_fma_f32 v[204:205], v[244:245], v[56:57], v[204:205]
	v_pk_fma_f32 v[206:207], v[202:203], v[58:59], v[206:207]
	s_add_i32 s0, s1, 62
	s_cmp_lt_i32 s0, s2
	s_cselect_b64 vcc, -1, 0
	v_cvt_pk_f32_fp8_e32 v[244:245], v201
	v_cvt_pk_f32_fp8_sdwa v[202:203], v201 src0_sel:WORD_1
	v_cndmask_b32_e32 v238, v220, v235, vcc
	v_pk_fma_f32 v[204:205], v[240:241], v[60:61], v[204:205]
	v_pk_fma_f32 v[206:207], v[242:243], v[62:63], v[206:207]
	v_pk_fma_f32 v[204:205], v[244:245], v[64:65], v[204:205]
	v_pk_fma_f32 v[206:207], v[202:203], v[66:67], v[206:207]
	v_readlane_b32 s0, v135, 63
	s_lshl_b32 s0, s0, 10
	s_add_u32 s4, s8, s0
	s_addc_u32 s5, s9, 0
	global_load_dwordx4 v[198:201], v16, s[4:5]
	v_pk_add_f32 v[204:205], v[204:205], v[206:207]
	s_nop 0
	v_add_f32_e32 v221, v204, v205
	s_nop 1
	v_add_f32_dpp v221, v221, v221 quad_perm:[1,0,3,2] row_mask:0xf bank_mask:0xf bound_ctrl:1
	s_nop 1
	v_add_f32_dpp v221, v221, v221 quad_perm:[2,3,0,1] row_mask:0xf bank_mask:0xf bound_ctrl:1
	s_nop 1
	v_add_f32_dpp v221, v221, v221 row_half_mirror row_mask:0xf bank_mask:0xf bound_ctrl:1
	s_add_i32 s0, s1, 63
	s_cmp_lt_i32 s0, s2
	s_cselect_b64 vcc, -1, 0
	s_nop 1
	v_cndmask_b32_e32 v239, v220, v221, vcc
	v_max3_f32 v224, v210, v211, v212
	v_max3_f32 v224, v224, v213, v226
	v_max3_f32 v224, v224, v227, v228
	v_max3_f32 v224, v224, v229, v230
	v_max3_f32 v224, v224, v231, v232
	v_max3_f32 v224, v224, v233, v236
	v_max3_f32 v224, v224, v237, v238
	v_max_f32_e32 v224, v224, v239
	v_max_f32_e32 v221, v216, v224
	v_sub_f32_e32 v184, v216, v221
	v_exp_f32_e32 v184, v184
	v_mov_b32_e32 v216, v221
	s_nop 0
	v_pk_mul_f32 v[12:13], v[12:13], v[184:185] op_sel_hi:[1,0]
	v_pk_mul_f32 v[14:15], v[14:15], v[184:185] op_sel_hi:[1,0]
	v_pk_mul_f32 v[8:9], v[8:9], v[184:185] op_sel_hi:[1,0]
	v_pk_mul_f32 v[10:11], v[10:11], v[184:185] op_sel_hi:[1,0]
	v_pk_mul_f32 v[4:5], v[4:5], v[184:185] op_sel_hi:[1,0]
	v_pk_mul_f32 v[6:7], v[6:7], v[184:185] op_sel_hi:[1,0]
	v_pk_mul_f32 v[0:1], v[0:1], v[184:185] op_sel_hi:[1,0]
	v_pk_mul_f32 v[2:3], v[2:3], v[184:185] op_sel_hi:[1,0]
	v_mul_f32_e32 v215, v215, v184
	v_sub_f32_e32 v210, v210, v216
	v_exp_f32_e32 v210, v210
	s_waitcnt vmcnt(15)
; DI void topk_phase(const bf16_t* PROJ, const unsigned char* K8, const unsigned char* V8, const unsigned short* SC, bf16_t* ODSA, int c, char* smem, int bid, int nb) {
;     ...
;         const float mn = fmaxf(m_run, da), al = __builtin_amdgcn_exp2f(m_run - mn), pp = __builtin_amdgcn_exp2f(da - mn);
;         m_run = mn; l_run = l_run * al + pp;
; #pragma unroll
;         for (int i = 0; i < 4; ++i) {
;           const f32x2v lo = __builtin_amdgcn_cvt_pk_f32_fp8((int)u[i], false), hi = __builtin_amdgcn_cvt_pk_f32_fp8((int)u[i], true);
;           ov[4 * i] = ov[4 * i] * al + pp * lo[0]; ov[4 * i + 1] = ov[4 * i + 1] * al + pp * lo[1];
;           ov[4 * i + 2] = ov[4 * i + 2] * al + pp * hi[0]; ov[4 * i + 3] = ov[4 * i + 3] * al + pp * hi[1];
;         }
	v_cvt_pk_f32_fp8_e32 v[240:241], v136
	v_cvt_pk_f32_fp8_sdwa v[242:243], v136 src0_sel:WORD_1
	v_cvt_pk_f32_fp8_e32 v[244:245], v137
	v_pk_fma_f32 v[12:13], v[240:241], v[210:211], v[12:13] op_sel_hi:[1,0,1]
	v_cvt_pk_f32_fp8_sdwa v[240:241], v137 src0_sel:WORD_1
	v_pk_fma_f32 v[14:15], v[242:243], v[210:211], v[14:15] op_sel_hi:[1,0,1]
	v_cvt_pk_f32_fp8_e32 v[242:243], v138
	v_sub_f32_e32 v211, v211, v216
	v_pk_fma_f32 v[8:9], v[244:245], v[210:211], v[8:9] op_sel_hi:[1,0,1]
	v_cvt_pk_f32_fp8_sdwa v[244:245], v138 src0_sel:WORD_1
	v_pk_fma_f32 v[10:11], v[240:241], v[210:211], v[10:11] op_sel_hi:[1,0,1]
	v_cvt_pk_f32_fp8_e32 v[240:241], v139
	v_exp_f32_e32 v211, v211
	v_pk_fma_f32 v[4:5], v[242:243], v[210:211], v[4:5] op_sel_hi:[1,0,1]
	v_cvt_pk_f32_fp8_sdwa v[242:243], v139 src0_sel:WORD_1
	v_pk_fma_f32 v[6:7], v[244:245], v[210:211], v[6:7] op_sel_hi:[1,0,1]
	v_add_f32_e32 v215, v215, v210
	v_pk_fma_f32 v[0:1], v[240:241], v[210:211], v[0:1] op_sel_hi:[1,0,1]
	v_pk_fma_f32 v[2:3], v[242:243], v[210:211], v[2:3] op_sel_hi:[1,0,1]
	s_waitcnt vmcnt(14)
	v_cvt_pk_f32_fp8_e32 v[240:241], v140
	v_cvt_pk_f32_fp8_sdwa v[242:243], v140 src0_sel:WORD_1
	v_cvt_pk_f32_fp8_e32 v[244:245], v141
	v_pk_fma_f32 v[12:13], v[240:241], v[210:211], v[12:13] op_sel:[0,1,0]
	v_cvt_pk_f32_fp8_sdwa v[240:241], v141 src0_sel:WORD_1
	v_pk_fma_f32 v[14:15], v[242:243], v[210:211], v[14:15] op_sel:[0,1,0]
	v_cvt_pk_f32_fp8_e32 v[242:243], v142
	v_sub_f32_e32 v212, v212, v216
	v_pk_fma_f32 v[8:9], v[244:245], v[210:211], v[8:9] op_sel:[0,1,0]
	v_cvt_pk_f32_fp8_sdwa v[244:245], v142 src0_sel:WORD_1
	v_pk_fma_f32 v[10:11], v[240:241], v[210:211], v[10:11] op_sel:[0,1,0]
	v_cvt_pk_f32_fp8_e32 v[240:241], v143
	v_exp_f32_e32 v212, v212
	v_pk_fma_f32 v[4:5], v[242:243], v[210:211], v[4:5] op_sel:[0,1,0]
	v_cvt_pk_f32_fp8_sdwa v[242:243], v143 src0_sel:WORD_1
	v_pk_fma_f32 v[6:7], v[244:245], v[210:211], v[6:7] op_sel:[0,1,0]
	v_add_f32_e32 v215, v215, v211
	v_pk_fma_f32 v[0:1], v[240:241], v[210:211], v[0:1] op_sel:[0,1,0]
	v_pk_fma_f32 v[2:3], v[242:243], v[210:211], v[2:3] op_sel:[0,1,0]
	s_waitcnt vmcnt(13)
	v_cvt_pk_f32_fp8_e32 v[240:241], v144
	v_cvt_pk_f32_fp8_sdwa v[242:243], v144 src0_sel:WORD_1
	v_cvt_pk_f32_fp8_e32 v[244:245], v145
	v_pk_fma_f32 v[12:13], v[240:241], v[212:213], v[12:13] op_sel_hi:[1,0,1]
	v_cvt_pk_f32_fp8_sdwa v[240:241], v145 src0_sel:WORD_1
	v_pk_fma_f32 v[14:15], v[242:243], v[212:213], v[14:15] op_sel_hi:[1,0,1]
	v_cvt_pk_f32_fp8_e32 v[242:243], v146
	v_sub_f32_e32 v213, v213, v216
	v_pk_fma_f32 v[8:9], v[244:245], v[212:213], v[8:9] op_sel_hi:[1,0,1]
	v_cvt_pk_f32_fp8_sdwa v[244:245], v146 src0_sel:WORD_1
	v_pk_fma_f32 v[10:11], v[240:241], v[212:213], v[10:11] op_sel_hi:[1,0,1]
	v_cvt_pk_f32_fp8_e32 v[240:241], v147
	v_exp_f32_e32 v213, v213
	v_pk_fma_f32 v[4:5], v[242:243], v[212:213], v[4:5] op_sel_hi:[1,0,1]
	v_cvt_pk_f32_fp8_sdwa v[242:243], v147 src0_sel:WORD_1
	v_pk_fma_f32 v[6:7], v[244:245], v[212:213], v[6:7] op_sel_hi:[1,0,1]
	v_add_f32_e32 v215, v215, v212
	v_pk_fma_f32 v[0:1], v[240:241], v[212:213], v[0:1] op_sel_hi:[1,0,1]
	v_pk_fma_f32 v[2:3], v[242:243], v[212:213], v[2:3] op_sel_hi:[1,0,1]
	s_waitcnt vmcnt(12)
	v_cvt_pk_f32_fp8_e32 v[240:241], v148
	v_cvt_pk_f32_fp8_sdwa v[242:243], v148 src0_sel:WORD_1
	v_cvt_pk_f32_fp8_e32 v[244:245], v149
	v_pk_fma_f32 v[12:13], v[240:241], v[212:213], v[12:13] op_sel:[0,1,0]
	v_cvt_pk_f32_fp8_sdwa v[240:241], v149 src0_sel:WORD_1
	v_pk_fma_f32 v[14:15], v[242:243], v[212:213], v[14:15] op_sel:[0,1,0]
	v_cvt_pk_f32_fp8_e32 v[242:243], v150
	v_sub_f32_e32 v226, v226, v216
	v_pk_fma_f32 v[8:9], v[244:245], v[212:213], v[8:9] op_sel:[0,1,0]
	v_cvt_pk_f32_fp8_sdwa v[244:245], v150 src0_sel:WORD_1
	v_pk_fma_f32 v[10:11], v[240:241], v[212:213], v[10:11] op_sel:[0,1,0]
	v_cvt_pk_f32_fp8_e32 v[240:241], v151
	v_exp_f32_e32 v226, v226
	v_pk_fma_f32 v[4:5], v[242:243], v[212:213], v[4:5] op_sel:[0,1,0]
	v_cvt_pk_f32_fp8_sdwa v[242:243], v151 src0_sel:WORD_1
	v_pk_fma_f32 v[6:7], v[244:245], v[212:213], v[6:7] op_sel:[0,1,0]
	v_add_f32_e32 v215, v215, v213
	v_pk_fma_f32 v[0:1], v[240:241], v[212:213], v[0:1] op_sel:[0,1,0]
	v_pk_fma_f32 v[2:3], v[242:243], v[212:213], v[2:3] op_sel:[0,1,0]
	s_waitcnt vmcnt(11)
	v_cvt_pk_f32_fp8_e32 v[240:241], v152
	v_cvt_pk_f32_fp8_sdwa v[242:243], v152 src0_sel:WORD_1
	v_cvt_pk_f32_fp8_e32 v[244:245], v153
	v_pk_fma_f32 v[12:13], v[240:241], v[226:227], v[12:13] op_sel_hi:[1,0,1]
	v_cvt_pk_f32_fp8_sdwa v[240:241], v153 src0_sel:WORD_1
	v_pk_fma_f32 v[14:15], v[242:243], v[226:227], v[14:15] op_sel_hi:[1,0,1]
	v_cvt_pk_f32_fp8_e32 v[242:243], v154
	v_sub_f32_e32 v227, v227, v216
	v_pk_fma_f32 v[8:9], v[244:245], v[226:227], v[8:9] op_sel_hi:[1,0,1]
	v_cvt_pk_f32_fp8_sdwa v[244:245], v154 src0_sel:WORD_1
	v_pk_fma_f32 v[10:11], v[240:241], v[226:227], v[10:11] op_sel_hi:[1,0,1]
	v_cvt_pk_f32_fp8_e32 v[240:241], v155
	v_exp_f32_e32 v227, v227
	v_pk_fma_f32 v[4:5], v[242:243], v[226:227], v[4:5] op_sel_hi:[1,0,1]
	v_cvt_pk_f32_fp8_sdwa v[242:243], v155 src0_sel:WORD_1
	v_pk_fma_f32 v[6:7], v[244:245], v[226:227], v[6:7] op_sel_hi:[1,0,1]
	v_add_f32_e32 v215, v215, v226
	v_pk_fma_f32 v[0:1], v[240:241], v[226:227], v[0:1] op_sel_hi:[1,0,1]
	v_pk_fma_f32 v[2:3], v[242:243], v[226:227], v[2:3] op_sel_hi:[1,0,1]
	s_waitcnt vmcnt(10)
; DI void topk_phase(const bf16_t* PROJ, const unsigned char* K8, const unsigned char* V8, const unsigned short* SC, bf16_t* ODSA, int c, char* smem, int bid, int nb) {
;     ...
;         const float mn = fmaxf(m_run, da), al = __builtin_amdgcn_exp2f(m_run - mn), pp = __builtin_amdgcn_exp2f(da - mn);
;         m_run = mn; l_run = l_run * al + pp;
; #pragma unroll
;         for (int i = 0; i < 4; ++i) {
;           const f32x2v lo = __builtin_amdgcn_cvt_pk_f32_fp8((int)u[i], false), hi = __builtin_amdgcn_cvt_pk_f32_fp8((int)u[i], true);
;           ov[4 * i] = ov[4 * i] * al + pp * lo[0]; ov[4 * i + 1] = ov[4 * i + 1] * al + pp * lo[1];
;           ov[4 * i + 2] = ov[4 * i + 2] * al + pp * hi[0]; ov[4 * i + 3] = ov[4 * i + 3] * al + pp * hi[1];
;         }
	v_cvt_pk_f32_fp8_e32 v[240:241], v156
	v_cvt_pk_f32_fp8_sdwa v[242:243], v156 src0_sel:WORD_1
	v_cvt_pk_f32_fp8_e32 v[244:245], v157
	v_pk_fma_f32 v[12:13], v[240:241], v[226:227], v[12:13] op_sel:[0,1,0]
	v_cvt_pk_f32_fp8_sdwa v[240:241], v157 src0_sel:WORD_1
	v_pk_fma_f32 v[14:15], v[242:243], v[226:227], v[14:15] op_sel:[0,1,0]
	v_cvt_pk_f32_fp8_e32 v[242:243], v158
	v_sub_f32_e32 v228, v228, v216
	v_pk_fma_f32 v[8:9], v[244:245], v[226:227], v[8:9] op_sel:[0,1,0]
	v_cvt_pk_f32_fp8_sdwa v[244:245], v158 src0_sel:WORD_1
	v_pk_fma_f32 v[10:11], v[240:241], v[226:227], v[10:11] op_sel:[0,1,0]
	v_cvt_pk_f32_fp8_e32 v[240:241], v159
	v_exp_f32_e32 v228, v228
	v_pk_fma_f32 v[4:5], v[242:243], v[226:227], v[4:5] op_sel:[0,1,0]
	v_cvt_pk_f32_fp8_sdwa v[242:243], v159 src0_sel:WORD_1
	v_pk_fma_f32 v[6:7], v[244:245], v[226:227], v[6:7] op_sel:[0,1,0]
	v_add_f32_e32 v215, v215, v227
	v_pk_fma_f32 v[0:1], v[240:241], v[226:227], v[0:1] op_sel:[0,1,0]
	v_pk_fma_f32 v[2:3], v[242:243], v[226:227], v[2:3] op_sel:[0,1,0]
	s_waitcnt vmcnt(9)
	v_cvt_pk_f32_fp8_e32 v[240:241], v160
	v_cvt_pk_f32_fp8_sdwa v[242:243], v160 src0_sel:WORD_1
	v_cvt_pk_f32_fp8_e32 v[244:245], v161
	v_pk_fma_f32 v[12:13], v[240:241], v[228:229], v[12:13] op_sel_hi:[1,0,1]
	v_cvt_pk_f32_fp8_sdwa v[240:241], v161 src0_sel:WORD_1
	v_pk_fma_f32 v[14:15], v[242:243], v[228:229], v[14:15] op_sel_hi:[1,0,1]
	v_cvt_pk_f32_fp8_e32 v[242:243], v162
	v_sub_f32_e32 v229, v229, v216
	v_pk_fma_f32 v[8:9], v[244:245], v[228:229], v[8:9] op_sel_hi:[1,0,1]
	v_cvt_pk_f32_fp8_sdwa v[244:245], v162 src0_sel:WORD_1
	v_pk_fma_f32 v[10:11], v[240:241], v[228:229], v[10:11] op_sel_hi:[1,0,1]
	v_cvt_pk_f32_fp8_e32 v[240:241], v163
	v_exp_f32_e32 v229, v229
	v_pk_fma_f32 v[4:5], v[242:243], v[228:229], v[4:5] op_sel_hi:[1,0,1]
	v_cvt_pk_f32_fp8_sdwa v[242:243], v163 src0_sel:WORD_1
	v_pk_fma_f32 v[6:7], v[244:245], v[228:229], v[6:7] op_sel_hi:[1,0,1]
	v_add_f32_e32 v215, v215, v228
	v_pk_fma_f32 v[0:1], v[240:241], v[228:229], v[0:1] op_sel_hi:[1,0,1]
	v_pk_fma_f32 v[2:3], v[242:243], v[228:229], v[2:3] op_sel_hi:[1,0,1]
	s_waitcnt vmcnt(8)
	v_cvt_pk_f32_fp8_e32 v[240:241], v164
	v_cvt_pk_f32_fp8_sdwa v[242:243], v164 src0_sel:WORD_1
	v_cvt_pk_f32_fp8_e32 v[244:245], v165
	v_pk_fma_f32 v[12:13], v[240:241], v[228:229], v[12:13] op_sel:[0,1,0]
	v_cvt_pk_f32_fp8_sdwa v[240:241], v165 src0_sel:WORD_1
	v_pk_fma_f32 v[14:15], v[242:243], v[228:229], v[14:15] op_sel:[0,1,0]
	v_cvt_pk_f32_fp8_e32 v[242:243], v166
	v_sub_f32_e32 v230, v230, v216
	v_pk_fma_f32 v[8:9], v[244:245], v[228:229], v[8:9] op_sel:[0,1,0]
	v_cvt_pk_f32_fp8_sdwa v[244:245], v166 src0_sel:WORD_1
	v_pk_fma_f32 v[10:11], v[240:241], v[228:229], v[10:11] op_sel:[0,1,0]
	v_cvt_pk_f32_fp8_e32 v[240:241], v167
	v_exp_f32_e32 v230, v230
	v_pk_fma_f32 v[4:5], v[242:243], v[228:229], v[4:5] op_sel:[0,1,0]
	v_cvt_pk_f32_fp8_sdwa v[242:243], v167 src0_sel:WORD_1
	v_pk_fma_f32 v[6:7], v[244:245], v[228:229], v[6:7] op_sel:[0,1,0]
	v_add_f32_e32 v215, v215, v229
	v_pk_fma_f32 v[0:1], v[240:241], v[228:229], v[0:1] op_sel:[0,1,0]
	v_pk_fma_f32 v[2:3], v[242:243], v[228:229], v[2:3] op_sel:[0,1,0]
	s_waitcnt vmcnt(7)
	v_cvt_pk_f32_fp8_e32 v[240:241], v168
	v_cvt_pk_f32_fp8_sdwa v[242:243], v168 src0_sel:WORD_1
	v_cvt_pk_f32_fp8_e32 v[244:245], v169
	v_pk_fma_f32 v[12:13], v[240:241], v[230:231], v[12:13] op_sel_hi:[1,0,1]
	v_cvt_pk_f32_fp8_sdwa v[240:241], v169 src0_sel:WORD_1
	v_pk_fma_f32 v[14:15], v[242:243], v[230:231], v[14:15] op_sel_hi:[1,0,1]
	v_cvt_pk_f32_fp8_e32 v[242:243], v170
	v_sub_f32_e32 v231, v231, v216
	v_pk_fma_f32 v[8:9], v[244:245], v[230:231], v[8:9] op_sel_hi:[1,0,1]
	v_cvt_pk_f32_fp8_sdwa v[244:245], v170 src0_sel:WORD_1
	v_pk_fma_f32 v[10:11], v[240:241], v[230:231], v[10:11] op_sel_hi:[1,0,1]
	v_cvt_pk_f32_fp8_e32 v[240:241], v171
	v_exp_f32_e32 v231, v231
	v_pk_fma_f32 v[4:5], v[242:243], v[230:231], v[4:5] op_sel_hi:[1,0,1]
	v_cvt_pk_f32_fp8_sdwa v[242:243], v171 src0_sel:WORD_1
	v_pk_fma_f32 v[6:7], v[244:245], v[230:231], v[6:7] op_sel_hi:[1,0,1]
	v_add_f32_e32 v215, v215, v230
	v_pk_fma_f32 v[0:1], v[240:241], v[230:231], v[0:1] op_sel_hi:[1,0,1]
	v_pk_fma_f32 v[2:3], v[242:243], v[230:231], v[2:3] op_sel_hi:[1,0,1]
	s_waitcnt vmcnt(6)
	v_cvt_pk_f32_fp8_e32 v[240:241], v172
	v_cvt_pk_f32_fp8_sdwa v[242:243], v172 src0_sel:WORD_1
	v_cvt_pk_f32_fp8_e32 v[244:245], v173
	v_pk_fma_f32 v[12:13], v[240:241], v[230:231], v[12:13] op_sel:[0,1,0]
	v_cvt_pk_f32_fp8_sdwa v[240:241], v173 src0_sel:WORD_1
	v_pk_fma_f32 v[14:15], v[242:243], v[230:231], v[14:15] op_sel:[0,1,0]
	v_cvt_pk_f32_fp8_e32 v[242:243], v174
	v_sub_f32_e32 v232, v232, v216
	v_pk_fma_f32 v[8:9], v[244:245], v[230:231], v[8:9] op_sel:[0,1,0]
	v_cvt_pk_f32_fp8_sdwa v[244:245], v174 src0_sel:WORD_1
	v_pk_fma_f32 v[10:11], v[240:241], v[230:231], v[10:11] op_sel:[0,1,0]
	v_cvt_pk_f32_fp8_e32 v[240:241], v175
	v_exp_f32_e32 v232, v232
	v_pk_fma_f32 v[4:5], v[242:243], v[230:231], v[4:5] op_sel:[0,1,0]
	v_cvt_pk_f32_fp8_sdwa v[242:243], v175 src0_sel:WORD_1
	v_pk_fma_f32 v[6:7], v[244:245], v[230:231], v[6:7] op_sel:[0,1,0]
	v_add_f32_e32 v215, v215, v231
	v_pk_fma_f32 v[0:1], v[240:241], v[230:231], v[0:1] op_sel:[0,1,0]
	v_pk_fma_f32 v[2:3], v[242:243], v[230:231], v[2:3] op_sel:[0,1,0]
	s_waitcnt vmcnt(5)
; DI void topk_phase(const bf16_t* PROJ, const unsigned char* K8, const unsigned char* V8, const unsigned short* SC, bf16_t* ODSA, int c, char* smem, int bid, int nb) {
;     ...
;         const float mn = fmaxf(m_run, da), al = __builtin_amdgcn_exp2f(m_run - mn), pp = __builtin_amdgcn_exp2f(da - mn);
;         m_run = mn; l_run = l_run * al + pp;
; #pragma unroll
;         for (int i = 0; i < 4; ++i) {
;           const f32x2v lo = __builtin_amdgcn_cvt_pk_f32_fp8((int)u[i], false), hi = __builtin_amdgcn_cvt_pk_f32_fp8((int)u[i], true);
;           ov[4 * i] = ov[4 * i] * al + pp * lo[0]; ov[4 * i + 1] = ov[4 * i + 1] * al + pp * lo[1];
;           ov[4 * i + 2] = ov[4 * i + 2] * al + pp * hi[0]; ov[4 * i + 3] = ov[4 * i + 3] * al + pp * hi[1];
;         }
;       }
;     }
;     if ((lane & 7) == 0) { sS[wid * 8 + hd] = m_run; sS[32 + wid * 8 + hd] = l_run; }
	v_cvt_pk_f32_fp8_e32 v[240:241], v176
	v_cvt_pk_f32_fp8_sdwa v[242:243], v176 src0_sel:WORD_1
	v_cvt_pk_f32_fp8_e32 v[244:245], v177
	v_pk_fma_f32 v[12:13], v[240:241], v[232:233], v[12:13] op_sel_hi:[1,0,1]
	v_cvt_pk_f32_fp8_sdwa v[240:241], v177 src0_sel:WORD_1
	v_pk_fma_f32 v[14:15], v[242:243], v[232:233], v[14:15] op_sel_hi:[1,0,1]
	v_cvt_pk_f32_fp8_e32 v[242:243], v178
	v_sub_f32_e32 v233, v233, v216
	v_pk_fma_f32 v[8:9], v[244:245], v[232:233], v[8:9] op_sel_hi:[1,0,1]
	v_cvt_pk_f32_fp8_sdwa v[244:245], v178 src0_sel:WORD_1
	v_pk_fma_f32 v[10:11], v[240:241], v[232:233], v[10:11] op_sel_hi:[1,0,1]
	v_cvt_pk_f32_fp8_e32 v[240:241], v179
	v_exp_f32_e32 v233, v233
	v_pk_fma_f32 v[4:5], v[242:243], v[232:233], v[4:5] op_sel_hi:[1,0,1]
	v_cvt_pk_f32_fp8_sdwa v[242:243], v179 src0_sel:WORD_1
	v_pk_fma_f32 v[6:7], v[244:245], v[232:233], v[6:7] op_sel_hi:[1,0,1]
	v_add_f32_e32 v215, v215, v232
	v_pk_fma_f32 v[0:1], v[240:241], v[232:233], v[0:1] op_sel_hi:[1,0,1]
	v_pk_fma_f32 v[2:3], v[242:243], v[232:233], v[2:3] op_sel_hi:[1,0,1]
	s_waitcnt vmcnt(4)
	v_cvt_pk_f32_fp8_e32 v[240:241], v180
	v_cvt_pk_f32_fp8_sdwa v[242:243], v180 src0_sel:WORD_1
	v_cvt_pk_f32_fp8_e32 v[244:245], v181
	v_pk_fma_f32 v[12:13], v[240:241], v[232:233], v[12:13] op_sel:[0,1,0]
	v_cvt_pk_f32_fp8_sdwa v[240:241], v181 src0_sel:WORD_1
	v_pk_fma_f32 v[14:15], v[242:243], v[232:233], v[14:15] op_sel:[0,1,0]
	v_cvt_pk_f32_fp8_e32 v[242:243], v182
	v_sub_f32_e32 v236, v236, v216
	v_pk_fma_f32 v[8:9], v[244:245], v[232:233], v[8:9] op_sel:[0,1,0]
	v_cvt_pk_f32_fp8_sdwa v[244:245], v182 src0_sel:WORD_1
	v_pk_fma_f32 v[10:11], v[240:241], v[232:233], v[10:11] op_sel:[0,1,0]
	v_cvt_pk_f32_fp8_e32 v[240:241], v183
	v_exp_f32_e32 v236, v236
	v_pk_fma_f32 v[4:5], v[242:243], v[232:233], v[4:5] op_sel:[0,1,0]
	v_cvt_pk_f32_fp8_sdwa v[242:243], v183 src0_sel:WORD_1
	v_pk_fma_f32 v[6:7], v[244:245], v[232:233], v[6:7] op_sel:[0,1,0]
	v_add_f32_e32 v215, v215, v233
	v_pk_fma_f32 v[0:1], v[240:241], v[232:233], v[0:1] op_sel:[0,1,0]
	v_pk_fma_f32 v[2:3], v[242:243], v[232:233], v[2:3] op_sel:[0,1,0]
	s_waitcnt vmcnt(3)
	v_cvt_pk_f32_fp8_e32 v[240:241], v186
	v_cvt_pk_f32_fp8_sdwa v[242:243], v186 src0_sel:WORD_1
	v_cvt_pk_f32_fp8_e32 v[244:245], v187
	v_pk_fma_f32 v[12:13], v[240:241], v[236:237], v[12:13] op_sel_hi:[1,0,1]
	v_cvt_pk_f32_fp8_sdwa v[240:241], v187 src0_sel:WORD_1
	v_pk_fma_f32 v[14:15], v[242:243], v[236:237], v[14:15] op_sel_hi:[1,0,1]
	v_cvt_pk_f32_fp8_e32 v[242:243], v188
	v_sub_f32_e32 v237, v237, v216
	v_pk_fma_f32 v[8:9], v[244:245], v[236:237], v[8:9] op_sel_hi:[1,0,1]
	v_cvt_pk_f32_fp8_sdwa v[244:245], v188 src0_sel:WORD_1
	v_pk_fma_f32 v[10:11], v[240:241], v[236:237], v[10:11] op_sel_hi:[1,0,1]
	v_cvt_pk_f32_fp8_e32 v[240:241], v189
	v_exp_f32_e32 v237, v237
	v_pk_fma_f32 v[4:5], v[242:243], v[236:237], v[4:5] op_sel_hi:[1,0,1]
	v_cvt_pk_f32_fp8_sdwa v[242:243], v189 src0_sel:WORD_1
	v_pk_fma_f32 v[6:7], v[244:245], v[236:237], v[6:7] op_sel_hi:[1,0,1]
	v_add_f32_e32 v215, v215, v236
	v_pk_fma_f32 v[0:1], v[240:241], v[236:237], v[0:1] op_sel_hi:[1,0,1]
	v_pk_fma_f32 v[2:3], v[242:243], v[236:237], v[2:3] op_sel_hi:[1,0,1]
	s_waitcnt vmcnt(2)
	v_cvt_pk_f32_fp8_e32 v[240:241], v190
	v_cvt_pk_f32_fp8_sdwa v[242:243], v190 src0_sel:WORD_1
	v_cvt_pk_f32_fp8_e32 v[244:245], v191
	v_pk_fma_f32 v[12:13], v[240:241], v[236:237], v[12:13] op_sel:[0,1,0]
	v_cvt_pk_f32_fp8_sdwa v[240:241], v191 src0_sel:WORD_1
	v_pk_fma_f32 v[14:15], v[242:243], v[236:237], v[14:15] op_sel:[0,1,0]
	v_cvt_pk_f32_fp8_e32 v[242:243], v192
	v_sub_f32_e32 v238, v238, v216
	v_pk_fma_f32 v[8:9], v[244:245], v[236:237], v[8:9] op_sel:[0,1,0]
	v_cvt_pk_f32_fp8_sdwa v[244:245], v192 src0_sel:WORD_1
	v_pk_fma_f32 v[10:11], v[240:241], v[236:237], v[10:11] op_sel:[0,1,0]
	v_cvt_pk_f32_fp8_e32 v[240:241], v193
	v_exp_f32_e32 v238, v238
	v_pk_fma_f32 v[4:5], v[242:243], v[236:237], v[4:5] op_sel:[0,1,0]
	v_cvt_pk_f32_fp8_sdwa v[242:243], v193 src0_sel:WORD_1
	v_pk_fma_f32 v[6:7], v[244:245], v[236:237], v[6:7] op_sel:[0,1,0]
	v_add_f32_e32 v215, v215, v237
	v_pk_fma_f32 v[0:1], v[240:241], v[236:237], v[0:1] op_sel:[0,1,0]
	v_pk_fma_f32 v[2:3], v[242:243], v[236:237], v[2:3] op_sel:[0,1,0]
	s_waitcnt vmcnt(1)
	v_cvt_pk_f32_fp8_e32 v[240:241], v194
	v_cvt_pk_f32_fp8_sdwa v[242:243], v194 src0_sel:WORD_1
	v_cvt_pk_f32_fp8_e32 v[244:245], v195
	v_pk_fma_f32 v[12:13], v[240:241], v[238:239], v[12:13] op_sel_hi:[1,0,1]
	v_cvt_pk_f32_fp8_sdwa v[240:241], v195 src0_sel:WORD_1
	v_pk_fma_f32 v[14:15], v[242:243], v[238:239], v[14:15] op_sel_hi:[1,0,1]
	v_cvt_pk_f32_fp8_e32 v[242:243], v196
	v_sub_f32_e32 v239, v239, v216
	v_pk_fma_f32 v[8:9], v[244:245], v[238:239], v[8:9] op_sel_hi:[1,0,1]
	v_cvt_pk_f32_fp8_sdwa v[244:245], v196 src0_sel:WORD_1
	v_pk_fma_f32 v[10:11], v[240:241], v[238:239], v[10:11] op_sel_hi:[1,0,1]
	v_cvt_pk_f32_fp8_e32 v[240:241], v197
	v_exp_f32_e32 v239, v239
	v_pk_fma_f32 v[4:5], v[242:243], v[238:239], v[4:5] op_sel_hi:[1,0,1]
	v_cvt_pk_f32_fp8_sdwa v[242:243], v197 src0_sel:WORD_1
	v_pk_fma_f32 v[6:7], v[244:245], v[238:239], v[6:7] op_sel_hi:[1,0,1]
	v_add_f32_e32 v215, v215, v238
	v_pk_fma_f32 v[0:1], v[240:241], v[238:239], v[0:1] op_sel_hi:[1,0,1]
	v_pk_fma_f32 v[2:3], v[242:243], v[238:239], v[2:3] op_sel_hi:[1,0,1]
	s_waitcnt vmcnt(0)
	v_cvt_pk_f32_fp8_e32 v[240:241], v198
	v_cvt_pk_f32_fp8_sdwa v[242:243], v198 src0_sel:WORD_1
	v_cvt_pk_f32_fp8_e32 v[244:245], v199
	v_pk_fma_f32 v[12:13], v[240:241], v[238:239], v[12:13] op_sel:[0,1,0]
	v_cvt_pk_f32_fp8_sdwa v[240:241], v199 src0_sel:WORD_1
	v_pk_fma_f32 v[14:15], v[242:243], v[238:239], v[14:15] op_sel:[0,1,0]
	v_cvt_pk_f32_fp8_e32 v[242:243], v200
	v_add_f32_e32 v215, v215, v239
	v_pk_fma_f32 v[8:9], v[244:245], v[238:239], v[8:9] op_sel:[0,1,0]
	v_cvt_pk_f32_fp8_sdwa v[244:245], v200 src0_sel:WORD_1
	v_pk_fma_f32 v[10:11], v[240:241], v[238:239], v[10:11] op_sel:[0,1,0]
	v_cvt_pk_f32_fp8_e32 v[240:241], v201
	v_pk_fma_f32 v[4:5], v[242:243], v[238:239], v[4:5] op_sel:[0,1,0]
	v_cvt_pk_f32_fp8_sdwa v[242:243], v201 src0_sel:WORD_1
	v_pk_fma_f32 v[6:7], v[244:245], v[238:239], v[6:7] op_sel:[0,1,0]
	v_pk_fma_f32 v[0:1], v[240:241], v[238:239], v[0:1] op_sel:[0,1,0]
	v_pk_fma_f32 v[2:3], v[242:243], v[238:239], v[2:3] op_sel:[0,1,0]
	v_mov_b32_e32 v68, v215
	v_mov_b32_e32 v69, v216
	s_mov_b64 s[0:1], exec
	v_readlane_b32 s2, v251, 23
	v_readlane_b32 s3, v251, 24
	s_and_b64 s[2:3], s[0:1], s[2:3]
	s_mov_b64 exec, s[2:3]
	s_cbranch_execz .LBB0_577
	ds_write2_b32 v134, v69, v68 offset1:32
	s_branch .LBB0_577

; DI void topk_phase(const bf16_t* PROJ, const unsigned char* K8, const unsigned char* V8, const unsigned short* SC, bf16_t* ODSA, int c, char* smem, int bid, int nb) {
;     ...
;       unsigned T = 0u;
;       for (int b = 15; b >= 0; --b) {
;         const unsigned cand = T | (1u << b);
;         int cc = 0;
; #pragma unroll
;         for (int i = 0; i < 64; ++i) if ((i >> 2) * 1024 < n) cc += key[i] >= cand ? 1 : 0;
;         if (block_count(cc, b & 1, red) >= 256) T = cand;
;       }
;       int cg_ = 0, ce_ = 0;
; #pragma unroll
;       for (int i = 0; i < 64; ++i) if ((i >> 2) * 1024 < n) { cg_ += key[i] > T ? 1 : 0; ce_ += key[i] == T ? 1 : 0; }
;       if (tid == 0) cnts[0] = 0;
;       const int cgt = block_count(cg_, 2, red);
;       const int ceq = block_count(ce_, 3, red);
;       const int need = 256 - cgt;
.LBB0_1084:
	s_or_b64 exec, exec, s[16:17]
	v_max3_u32 v8, v65, v64, v63
	v_max3_u32 v8, v8, v62, v61
	v_max3_u32 v8, v8, v60, v59
	v_max3_u32 v8, v8, v57, v58
	v_max3_u32 v8, v8, v56, v54
	v_max3_u32 v8, v8, v53, v52
	v_max3_u32 v8, v8, v51, v50
	v_max3_u32 v8, v8, v48, v49
	v_max3_u32 v8, v8, v47, v46
	v_max3_u32 v8, v8, v45, v44
	v_max3_u32 v8, v8, v43, v42
	v_max3_u32 v8, v8, v40, v41
	v_max3_u32 v8, v8, v39, v38
	v_max3_u32 v8, v8, v37, v36
	v_max3_u32 v8, v8, v15, v14
	v_max_u32_e32 v8, v8, v12
	v_not_b32_e32 v8, v8
	s_nop 1
	v_max_u32_dpp v8, v8, v8 row_shr:1 row_mask:0xf bank_mask:0xf bound_ctrl:1
	s_nop 1
	v_max_u32_dpp v8, v8, v8 row_shr:2 row_mask:0xf bank_mask:0xf bound_ctrl:1
	s_nop 1
	v_max_u32_dpp v8, v8, v8 row_shr:4 row_mask:0xf bank_mask:0xf bound_ctrl:1
	s_nop 1
	v_max_u32_dpp v8, v8, v8 row_shr:8 row_mask:0xf bank_mask:0xf bound_ctrl:1
	s_nop 1
	v_readlane_b32 s0, v8, 15
	v_readlane_b32 s1, v8, 31
	v_readlane_b32 s22, v8, 47
	v_readlane_b32 s23, v8, 63
	s_max_u32 s0, s0, s1
	s_max_u32 s22, s22, s23
	s_max_u32 s0, s0, s22
	v_lshrrev_b32_e32 v10, 6, v214
	v_lshlrev_b32_e32 v10, 2, v10
	v_mov_b32_e32 v9, s0
	ds_write_b32 v10, v9 offset:1024
	s_waitcnt lgkmcnt(0)
	s_barrier
	ds_read_b128 v[168:171], v185 offset:1024
	s_waitcnt lgkmcnt(0)
	v_max3_u32 v9, v168, v169, v170
	v_max_u32_e32 v9, v9, v171
	v_not_b32_e32 v9, v9
	s_nop 1
	v_readfirstlane_b32 s0, v9
	s_nop 1
	s_cmp_eq_u32 s0, 0
	s_cbranch_scc1 .Lsel_fb_B
	s_mov_b32 s1, 0
	v_cmp_le_u32_e64 s[22:23], s0, v65
	v_cmp_le_u32_e64 s[24:25], s0, v64
	s_bcnt1_i32_b64 s26, s[22:23]
	s_add_i32 s1, s1, s26
	v_cmp_le_u32_e64 s[22:23], s0, v63
	s_bcnt1_i32_b64 s26, s[24:25]
	s_add_i32 s1, s1, s26
	v_cmp_le_u32_e64 s[24:25], s0, v62
	s_bcnt1_i32_b64 s26, s[22:23]
	s_add_i32 s1, s1, s26
	v_cmp_le_u32_e64 s[22:23], s0, v61
	s_bcnt1_i32_b64 s26, s[24:25]
	s_add_i32 s1, s1, s26
	v_cmp_le_u32_e64 s[24:25], s0, v60
	s_bcnt1_i32_b64 s26, s[22:23]
	s_add_i32 s1, s1, s26
	v_cmp_le_u32_e64 s[22:23], s0, v59
	s_bcnt1_i32_b64 s26, s[24:25]
	s_add_i32 s1, s1, s26
	v_cmp_le_u32_e64 s[24:25], s0, v57
	s_bcnt1_i32_b64 s26, s[22:23]
	s_add_i32 s1, s1, s26
	v_cmp_le_u32_e64 s[22:23], s0, v58
	s_bcnt1_i32_b64 s26, s[24:25]
	s_add_i32 s1, s1, s26
	v_cmp_le_u32_e64 s[24:25], s0, v56
	s_bcnt1_i32_b64 s26, s[22:23]
	s_add_i32 s1, s1, s26
	v_cmp_le_u32_e64 s[22:23], s0, v54
	s_bcnt1_i32_b64 s26, s[24:25]
	s_add_i32 s1, s1, s26
	v_cmp_le_u32_e64 s[24:25], s0, v53
	s_bcnt1_i32_b64 s26, s[22:23]
	s_add_i32 s1, s1, s26
	v_cmp_le_u32_e64 s[22:23], s0, v52
	s_bcnt1_i32_b64 s26, s[24:25]
	s_add_i32 s1, s1, s26
	v_cmp_le_u32_e64 s[24:25], s0, v51
	s_bcnt1_i32_b64 s26, s[22:23]
	s_add_i32 s1, s1, s26
	v_cmp_le_u32_e64 s[22:23], s0, v50
	s_bcnt1_i32_b64 s26, s[24:25]
	s_add_i32 s1, s1, s26
	v_cmp_le_u32_e64 s[24:25], s0, v48
	s_bcnt1_i32_b64 s26, s[22:23]
	s_add_i32 s1, s1, s26
	v_cmp_le_u32_e64 s[22:23], s0, v49
	s_bcnt1_i32_b64 s26, s[24:25]
	s_add_i32 s1, s1, s26
	v_cmp_le_u32_e64 s[24:25], s0, v47
	s_bcnt1_i32_b64 s26, s[22:23]
	s_add_i32 s1, s1, s26
	v_cmp_le_u32_e64 s[22:23], s0, v46
	s_bcnt1_i32_b64 s26, s[24:25]
	s_add_i32 s1, s1, s26
	v_cmp_le_u32_e64 s[24:25], s0, v45
	s_bcnt1_i32_b64 s26, s[22:23]
	s_add_i32 s1, s1, s26
	v_cmp_le_u32_e64 s[22:23], s0, v44
	s_bcnt1_i32_b64 s26, s[24:25]
	s_add_i32 s1, s1, s26
	v_cmp_le_u32_e64 s[24:25], s0, v43
	s_bcnt1_i32_b64 s26, s[22:23]
	s_add_i32 s1, s1, s26
	v_cmp_le_u32_e64 s[22:23], s0, v42
	s_bcnt1_i32_b64 s26, s[24:25]
	s_add_i32 s1, s1, s26
	v_cmp_le_u32_e64 s[24:25], s0, v40
	s_bcnt1_i32_b64 s26, s[22:23]
	s_add_i32 s1, s1, s26
	v_cmp_le_u32_e64 s[22:23], s0, v41
	s_bcnt1_i32_b64 s26, s[24:25]
	s_add_i32 s1, s1, s26
	v_cmp_le_u32_e64 s[24:25], s0, v39
	s_bcnt1_i32_b64 s26, s[22:23]
	s_add_i32 s1, s1, s26
	v_cmp_le_u32_e64 s[22:23], s0, v38
	s_bcnt1_i32_b64 s26, s[24:25]
	s_add_i32 s1, s1, s26
	v_cmp_le_u32_e64 s[24:25], s0, v37
	s_bcnt1_i32_b64 s26, s[22:23]
	s_add_i32 s1, s1, s26
	v_cmp_le_u32_e64 s[22:23], s0, v36
	s_bcnt1_i32_b64 s26, s[24:25]
	s_add_i32 s1, s1, s26
	v_cmp_le_u32_e64 s[24:25], s0, v15
	s_bcnt1_i32_b64 s26, s[22:23]
	s_add_i32 s1, s1, s26
	v_cmp_le_u32_e64 s[22:23], s0, v14
	s_bcnt1_i32_b64 s26, s[24:25]
	s_add_i32 s1, s1, s26
	v_cmp_le_u32_e64 s[24:25], s0, v12
	s_bcnt1_i32_b64 s26, s[22:23]
	s_add_i32 s1, s1, s26
	s_bcnt1_i32_b64 s26, s[24:25]
	s_add_i32 s1, s1, s26
	v_mov_b32_e32 v9, s1
	ds_write_b32 v10, v9 offset:1040
	s_waitcnt lgkmcnt(0)
	s_barrier
	ds_read_b128 v[168:171], v185 offset:1040
	s_waitcnt lgkmcnt(0)
	v_readfirstlane_b32 s24, v168
	v_readfirstlane_b32 s25, v169
	v_readfirstlane_b32 s26, v170
	v_readfirstlane_b32 s27, v171
	s_add_i32 s28, s24, s25
	s_add_i32 s28, s28, s26
	s_add_i32 s28, s28, s27
	s_cmp_gt_u32 s28, 0x800
	s_cbranch_scc1 .Lsel_fb_B
; DI void topk_phase(const bf16_t* PROJ, const unsigned char* K8, const unsigned char* V8, const unsigned short* SC, bf16_t* ODSA, int c, char* smem, int bid, int nb) {
;     ...
; #pragma unroll
;       for (int i = 0; i < 64; ++i)
;         if ((i >> 2) * 1024 < n) {
;           const int idx = ((i >> 2) * 256 + tid) * 4 + (i & 3);
;           if (key[i] > T || (key[i] == T && idx <= X)) { const int ps = atomicAdd(&cnts[0], 1); sel[ps] = idx; }
;         }
	v_readfirstlane_b32 s29, v10
	s_mov_b32 s31, s28
	s_mov_b32 s1, 0
	s_cmp_ge_u32 s29, 4
	s_cselect_b32 s30, s24, 0
	s_add_i32 s1, s1, s30
	s_cmp_ge_u32 s29, 8
	s_cselect_b32 s30, s25, 0
	s_add_i32 s1, s1, s30
	s_cmp_ge_u32 s29, 12
	s_cselect_b32 s30, s26, 0
	s_add_i32 s1, s1, s30
	v_cmp_le_u32_e64 s[22:23], s0, v65
	v_cmp_le_u32_e64 s[24:25], s0, v64
	s_nop 0
	v_mbcnt_lo_u32_b32 v9, s22, 0
	v_mbcnt_hi_u32_b32 v9, s23, v9
	v_add_lshl_u32 v11, v9, s1, 2
	s_bcnt1_i32_b64 s26, s[22:23]
	s_add_i32 s1, s1, s26
	s_mov_b64 exec, s[22:23]
	ds_write2st64_b32 v11, v65, v18 offset0:36 offset1:68
	s_mov_b64 exec, -1
	v_cmp_le_u32_e64 s[22:23], s0, v63
	v_mbcnt_lo_u32_b32 v9, s24, 0
	v_mbcnt_hi_u32_b32 v9, s25, v9
	v_add_lshl_u32 v11, v9, s1, 2
	s_bcnt1_i32_b64 s26, s[24:25]
	s_add_i32 s1, s1, s26
	s_mov_b64 exec, s[24:25]
	ds_write2st64_b32 v11, v64, v72 offset0:36 offset1:68
	s_mov_b64 exec, -1
	v_cmp_le_u32_e64 s[24:25], s0, v62
	v_mbcnt_lo_u32_b32 v9, s22, 0
	v_mbcnt_hi_u32_b32 v9, s23, v9
	v_add_lshl_u32 v11, v9, s1, 2
	s_bcnt1_i32_b64 s26, s[22:23]
	s_add_i32 s1, s1, s26
	s_mov_b64 exec, s[22:23]
	ds_write2st64_b32 v11, v63, v69 offset0:36 offset1:68
	s_mov_b64 exec, -1
	v_cmp_le_u32_e64 s[22:23], s0, v61
	v_mbcnt_lo_u32_b32 v9, s24, 0
	v_mbcnt_hi_u32_b32 v9, s25, v9
	v_add_lshl_u32 v11, v9, s1, 2
	s_bcnt1_i32_b64 s26, s[24:25]
	s_add_i32 s1, s1, s26
	s_mov_b64 exec, s[24:25]
	ds_write2st64_b32 v11, v62, v70 offset0:36 offset1:68
	s_mov_b64 exec, -1
	v_cmp_le_u32_e64 s[24:25], s0, v60
	v_mbcnt_lo_u32_b32 v9, s22, 0
	v_mbcnt_hi_u32_b32 v9, s23, v9
	v_add_lshl_u32 v11, v9, s1, 2
	s_bcnt1_i32_b64 s26, s[22:23]
	s_add_i32 s1, s1, s26
	s_mov_b64 exec, s[22:23]
	ds_write2st64_b32 v11, v61, v71 offset0:36 offset1:68
	s_mov_b64 exec, -1
	v_cmp_le_u32_e64 s[22:23], s0, v59
	v_mbcnt_lo_u32_b32 v9, s24, 0
	v_mbcnt_hi_u32_b32 v9, s25, v9
	v_add_lshl_u32 v11, v9, s1, 2
	s_bcnt1_i32_b64 s26, s[24:25]
	s_add_i32 s1, s1, s26
	s_mov_b64 exec, s[24:25]
	ds_write2st64_b32 v11, v60, v73 offset0:36 offset1:68
	s_mov_b64 exec, -1
	v_cmp_le_u32_e64 s[24:25], s0, v57
	v_mbcnt_lo_u32_b32 v9, s22, 0
	v_mbcnt_hi_u32_b32 v9, s23, v9
	v_add_lshl_u32 v11, v9, s1, 2
	s_bcnt1_i32_b64 s26, s[22:23]
	s_add_i32 s1, s1, s26
	s_mov_b64 exec, s[22:23]
	ds_write2st64_b32 v11, v59, v74 offset0:36 offset1:68
	s_mov_b64 exec, -1
	v_cmp_le_u32_e64 s[22:23], s0, v58
	v_mbcnt_lo_u32_b32 v9, s24, 0
	v_mbcnt_hi_u32_b32 v9, s25, v9
	v_add_lshl_u32 v11, v9, s1, 2
	s_bcnt1_i32_b64 s26, s[24:25]
	s_add_i32 s1, s1, s26
	s_mov_b64 exec, s[24:25]
	ds_write2st64_b32 v11, v57, v75 offset0:36 offset1:68
	s_mov_b64 exec, -1
	v_cmp_le_u32_e64 s[24:25], s0, v56
	v_mbcnt_lo_u32_b32 v9, s22, 0
	v_mbcnt_hi_u32_b32 v9, s23, v9
	v_add_lshl_u32 v11, v9, s1, 2
	s_bcnt1_i32_b64 s26, s[22:23]
	s_add_i32 s1, s1, s26
	s_mov_b64 exec, s[22:23]
	ds_write2st64_b32 v11, v58, v22 offset0:36 offset1:68
	s_mov_b64 exec, -1
	v_cmp_le_u32_e64 s[22:23], s0, v54
	v_mbcnt_lo_u32_b32 v9, s24, 0
	v_mbcnt_hi_u32_b32 v9, s25, v9
	v_add_lshl_u32 v11, v9, s1, 2
	s_bcnt1_i32_b64 s26, s[24:25]
	s_add_i32 s1, s1, s26
	s_mov_b64 exec, s[24:25]
	ds_write2st64_b32 v11, v56, v76 offset0:36 offset1:68
	s_mov_b64 exec, -1
	v_cmp_le_u32_e64 s[24:25], s0, v53
	v_mbcnt_lo_u32_b32 v9, s22, 0
	v_mbcnt_hi_u32_b32 v9, s23, v9
	v_add_lshl_u32 v11, v9, s1, 2
	s_bcnt1_i32_b64 s26, s[22:23]
	s_add_i32 s1, s1, s26
	s_mov_b64 exec, s[22:23]
	ds_write2st64_b32 v11, v54, v77 offset0:36 offset1:68
	s_mov_b64 exec, -1
	v_cmp_le_u32_e64 s[22:23], s0, v52
	v_mbcnt_lo_u32_b32 v9, s24, 0
	v_mbcnt_hi_u32_b32 v9, s25, v9
	v_add_lshl_u32 v11, v9, s1, 2
	s_bcnt1_i32_b64 s26, s[24:25]
	s_add_i32 s1, s1, s26
	s_mov_b64 exec, s[24:25]
	ds_write2st64_b32 v11, v53, v78 offset0:36 offset1:68
	s_mov_b64 exec, -1
	v_cmp_le_u32_e64 s[24:25], s0, v51
	v_mbcnt_lo_u32_b32 v9, s22, 0
	v_mbcnt_hi_u32_b32 v9, s23, v9
	v_add_lshl_u32 v11, v9, s1, 2
	s_bcnt1_i32_b64 s26, s[22:23]
	s_add_i32 s1, s1, s26
	s_mov_b64 exec, s[22:23]
	ds_write2st64_b32 v11, v52, v24 offset0:36 offset1:68
	s_mov_b64 exec, -1
	v_cmp_le_u32_e64 s[22:23], s0, v50
	v_mbcnt_lo_u32_b32 v9, s24, 0
	v_mbcnt_hi_u32_b32 v9, s25, v9
	v_add_lshl_u32 v11, v9, s1, 2
	s_bcnt1_i32_b64 s26, s[24:25]
	s_add_i32 s1, s1, s26
	s_mov_b64 exec, s[24:25]
	ds_write2st64_b32 v11, v51, v79 offset0:36 offset1:68
	s_mov_b64 exec, -1
	v_cmp_le_u32_e64 s[24:25], s0, v48
	v_mbcnt_lo_u32_b32 v9, s22, 0
	v_mbcnt_hi_u32_b32 v9, s23, v9
	v_add_lshl_u32 v11, v9, s1, 2
	s_bcnt1_i32_b64 s26, s[22:23]
	s_add_i32 s1, s1, s26
	s_mov_b64 exec, s[22:23]
	ds_write2st64_b32 v11, v50, v80 offset0:36 offset1:68
	s_mov_b64 exec, -1
	v_cmp_le_u32_e64 s[22:23], s0, v49
	v_mbcnt_lo_u32_b32 v9, s24, 0
	v_mbcnt_hi_u32_b32 v9, s25, v9
	v_add_lshl_u32 v11, v9, s1, 2
	s_bcnt1_i32_b64 s26, s[24:25]
	s_add_i32 s1, s1, s26
	s_mov_b64 exec, s[24:25]
	ds_write2st64_b32 v11, v48, v81 offset0:36 offset1:68
	s_mov_b64 exec, -1
	v_cmp_le_u32_e64 s[24:25], s0, v47
	v_mbcnt_lo_u32_b32 v9, s22, 0
	v_mbcnt_hi_u32_b32 v9, s23, v9
	v_add_lshl_u32 v11, v9, s1, 2
	s_bcnt1_i32_b64 s26, s[22:23]
	s_add_i32 s1, s1, s26
	s_mov_b64 exec, s[22:23]
	ds_write2st64_b32 v11, v49, v26 offset0:36 offset1:68
	s_mov_b64 exec, -1
	v_cmp_le_u32_e64 s[22:23], s0, v46
	v_mbcnt_lo_u32_b32 v9, s24, 0
	v_mbcnt_hi_u32_b32 v9, s25, v9
	v_add_lshl_u32 v11, v9, s1, 2
	s_bcnt1_i32_b64 s26, s[24:25]
	s_add_i32 s1, s1, s26
	s_mov_b64 exec, s[24:25]
	ds_write2st64_b32 v11, v47, v82 offset0:36 offset1:68
	s_mov_b64 exec, -1
	v_cmp_le_u32_e64 s[24:25], s0, v45
	v_mbcnt_lo_u32_b32 v9, s22, 0
	v_mbcnt_hi_u32_b32 v9, s23, v9
	v_add_lshl_u32 v11, v9, s1, 2
	s_bcnt1_i32_b64 s26, s[22:23]
	s_add_i32 s1, s1, s26
; DI void topk_phase(const bf16_t* PROJ, const unsigned char* K8, const unsigned char* V8, const unsigned short* SC, bf16_t* ODSA, int c, char* smem, int bid, int nb) {
;     ...
; #pragma unroll
;       for (int i = 0; i < 64; ++i)
;         if ((i >> 2) * 1024 < n) {
;           const int idx = ((i >> 2) * 256 + tid) * 4 + (i & 3);
;           if (key[i] > T || (key[i] == T && idx <= X)) { const int ps = atomicAdd(&cnts[0], 1); sel[ps] = idx; }
;         }
	s_mov_b64 exec, s[22:23]
	ds_write2st64_b32 v11, v46, v83 offset0:36 offset1:68
	s_mov_b64 exec, -1
	v_cmp_le_u32_e64 s[22:23], s0, v44
	v_mbcnt_lo_u32_b32 v9, s24, 0
	v_mbcnt_hi_u32_b32 v9, s25, v9
	v_add_lshl_u32 v11, v9, s1, 2
	s_bcnt1_i32_b64 s26, s[24:25]
	s_add_i32 s1, s1, s26
	s_mov_b64 exec, s[24:25]
	ds_write2st64_b32 v11, v45, v84 offset0:36 offset1:68
	s_mov_b64 exec, -1
	v_cmp_le_u32_e64 s[24:25], s0, v43
	v_mbcnt_lo_u32_b32 v9, s22, 0
	v_mbcnt_hi_u32_b32 v9, s23, v9
	v_add_lshl_u32 v11, v9, s1, 2
	s_bcnt1_i32_b64 s26, s[22:23]
	s_add_i32 s1, s1, s26
	s_mov_b64 exec, s[22:23]
	ds_write2st64_b32 v11, v44, v28 offset0:36 offset1:68
	s_mov_b64 exec, -1
	v_cmp_le_u32_e64 s[22:23], s0, v42
	v_mbcnt_lo_u32_b32 v9, s24, 0
	v_mbcnt_hi_u32_b32 v9, s25, v9
	v_add_lshl_u32 v11, v9, s1, 2
	s_bcnt1_i32_b64 s26, s[24:25]
	s_add_i32 s1, s1, s26
	s_mov_b64 exec, s[24:25]
	ds_write2st64_b32 v11, v43, v85 offset0:36 offset1:68
	s_mov_b64 exec, -1
	v_cmp_le_u32_e64 s[24:25], s0, v40
	v_mbcnt_lo_u32_b32 v9, s22, 0
	v_mbcnt_hi_u32_b32 v9, s23, v9
	v_add_lshl_u32 v11, v9, s1, 2
	s_bcnt1_i32_b64 s26, s[22:23]
	s_add_i32 s1, s1, s26
	s_mov_b64 exec, s[22:23]
	ds_write2st64_b32 v11, v42, v86 offset0:36 offset1:68
	s_mov_b64 exec, -1
	v_cmp_le_u32_e64 s[22:23], s0, v41
	v_mbcnt_lo_u32_b32 v9, s24, 0
	v_mbcnt_hi_u32_b32 v9, s25, v9
	v_add_lshl_u32 v11, v9, s1, 2
	s_bcnt1_i32_b64 s26, s[24:25]
	s_add_i32 s1, s1, s26
	s_mov_b64 exec, s[24:25]
	ds_write2st64_b32 v11, v40, v87 offset0:36 offset1:68
	s_mov_b64 exec, -1
	v_cmp_le_u32_e64 s[24:25], s0, v39
	v_mbcnt_lo_u32_b32 v9, s22, 0
	v_mbcnt_hi_u32_b32 v9, s23, v9
	v_add_lshl_u32 v11, v9, s1, 2
	s_bcnt1_i32_b64 s26, s[22:23]
	s_add_i32 s1, s1, s26
	s_mov_b64 exec, s[22:23]
	ds_write2st64_b32 v11, v41, v30 offset0:36 offset1:68
	s_mov_b64 exec, -1
	v_cmp_le_u32_e64 s[22:23], s0, v38
	v_mbcnt_lo_u32_b32 v9, s24, 0
	v_mbcnt_hi_u32_b32 v9, s25, v9
	v_add_lshl_u32 v11, v9, s1, 2
	s_bcnt1_i32_b64 s26, s[24:25]
	s_add_i32 s1, s1, s26
	s_mov_b64 exec, s[24:25]
	ds_write2st64_b32 v11, v39, v88 offset0:36 offset1:68
	s_mov_b64 exec, -1
	v_cmp_le_u32_e64 s[24:25], s0, v37
	v_mbcnt_lo_u32_b32 v9, s22, 0
	v_mbcnt_hi_u32_b32 v9, s23, v9
	v_add_lshl_u32 v11, v9, s1, 2
	s_bcnt1_i32_b64 s26, s[22:23]
	s_add_i32 s1, s1, s26
	s_mov_b64 exec, s[22:23]
	ds_write2st64_b32 v11, v38, v89 offset0:36 offset1:68
	s_mov_b64 exec, -1
	v_cmp_le_u32_e64 s[22:23], s0, v36
	v_mbcnt_lo_u32_b32 v9, s24, 0
	v_mbcnt_hi_u32_b32 v9, s25, v9
	v_add_lshl_u32 v11, v9, s1, 2
	s_bcnt1_i32_b64 s26, s[24:25]
	s_add_i32 s1, s1, s26
	s_mov_b64 exec, s[24:25]
	ds_write2st64_b32 v11, v37, v90 offset0:36 offset1:68
	s_mov_b64 exec, -1
	v_cmp_le_u32_e64 s[24:25], s0, v15
	v_mbcnt_lo_u32_b32 v9, s22, 0
	v_mbcnt_hi_u32_b32 v9, s23, v9
	v_add_lshl_u32 v11, v9, s1, 2
	s_bcnt1_i32_b64 s26, s[22:23]
	s_add_i32 s1, s1, s26
	s_mov_b64 exec, s[22:23]
	ds_write2st64_b32 v11, v36, v32 offset0:36 offset1:68
	s_mov_b64 exec, -1
	v_cmp_le_u32_e64 s[22:23], s0, v14
	v_mbcnt_lo_u32_b32 v9, s24, 0
	v_mbcnt_hi_u32_b32 v9, s25, v9
	v_add_lshl_u32 v11, v9, s1, 2
	s_bcnt1_i32_b64 s26, s[24:25]
	s_add_i32 s1, s1, s26
	s_mov_b64 exec, s[24:25]
	ds_write2st64_b32 v11, v15, v91 offset0:36 offset1:68
	s_mov_b64 exec, -1
	v_cmp_le_u32_e64 s[24:25], s0, v12
	v_mbcnt_lo_u32_b32 v9, s22, 0
	v_mbcnt_hi_u32_b32 v9, s23, v9
	v_add_lshl_u32 v11, v9, s1, 2
	s_bcnt1_i32_b64 s26, s[22:23]
	s_add_i32 s1, s1, s26
	s_mov_b64 exec, s[22:23]
	ds_write2st64_b32 v11, v14, v92 offset0:36 offset1:68
	s_mov_b64 exec, -1
	v_mbcnt_lo_u32_b32 v9, s24, 0
	v_mbcnt_hi_u32_b32 v9, s25, v9
	v_add_lshl_u32 v11, v9, s1, 2
	s_bcnt1_i32_b64 s26, s[24:25]
	s_add_i32 s1, s1, s26
	s_mov_b64 exec, s[24:25]
	ds_write2st64_b32 v11, v12, v93 offset0:36 offset1:68
	s_mov_b64 exec, -1
	s_waitcnt lgkmcnt(0)
	s_barrier
	s_cmp_lg_u32 s29, 0
	s_cbranch_scc1 .LBB0_1309
; DI void topk_phase(const bf16_t* PROJ, const unsigned char* K8, const unsigned char* V8, const unsigned short* SC, bf16_t* ODSA, int c, char* smem, int bid, int nb) {
;     ...
;       const unsigned short* row = SC + (size_t)item * S;
;       unsigned key[64];
; #pragma unroll
;       for (int i = 0; i < 16; ++i) {
;         key[4 * i] = 0u; key[4 * i + 1] = 0u; key[4 * i + 2] = 0u; key[4 * i + 3] = 0u;
;         if (i * 1024 < n) {
;           const int idx = (i * 256 + tid) * 4;
;           if (idx < n) {
;             const uint2 w = *(const uint2*)(row + idx);
;             key[4 * i] = w.x & 0xffffu; key[4 * i + 1] = idx + 1 < n ? w.x >> 16 : 0u; key[4 * i + 2] = idx + 2 < n ? w.y & 0xffffu : 0u; key[4 * i + 3] = idx + 3 < n ? w.y >> 16 : 0u;
;           }
;         }
;       }
;       unsigned T = 0u;
;       for (int b = 15; b >= 0; --b) {
;         const unsigned cand = T | (1u << b);
;         int cc = 0;
; #pragma unroll
;         for (int i = 0; i < 64; ++i) if ((i >> 2) * 1024 < n) cc += key[i] >= cand ? 1 : 0;
;         if (block_count(cc, b & 1, red) >= 256) T = cand;
	v_and_b32_e32 v10, 63, v214
	v_lshlrev_b32_e32 v11, 2, v10
	ds_read_b32 v186, v11 offset:9216
	ds_read_b32 v172, v11 offset:17408
	ds_read_b32 v187, v11 offset:9472
	ds_read_b32 v173, v11 offset:17664
	ds_read_b32 v188, v11 offset:9728
	ds_read_b32 v174, v11 offset:17920
	ds_read_b32 v189, v11 offset:9984
	ds_read_b32 v175, v11 offset:18176
	s_waitcnt lgkmcnt(0)
	ds_read_b32 v190, v11 offset:10240
	ds_read_b32 v176, v11 offset:18432
	ds_read_b32 v191, v11 offset:10496
	ds_read_b32 v177, v11 offset:18688
	ds_read_b32 v192, v11 offset:10752
	ds_read_b32 v178, v11 offset:18944
	ds_read_b32 v193, v11 offset:11008
	ds_read_b32 v179, v11 offset:19200
	s_waitcnt lgkmcnt(0)
	ds_read_b32 v194, v11 offset:11264
	ds_read_b32 v180, v11 offset:19456
	ds_read_b32 v195, v11 offset:11520
	ds_read_b32 v181, v11 offset:19712
	ds_read_b32 v196, v11 offset:11776
	ds_read_b32 v182, v11 offset:19968
	ds_read_b32 v197, v11 offset:12032
	ds_read_b32 v183, v11 offset:20224
	s_waitcnt lgkmcnt(0)
	ds_read_b32 v198, v11 offset:12288
	ds_read_b32 v184, v11 offset:20480
	ds_read_b32 v199, v11 offset:12544
	ds_read_b32 v230, v11 offset:20736
	ds_read_b32 v200, v11 offset:12800
	ds_read_b32 v231, v11 offset:20992
	ds_read_b32 v201, v11 offset:13056
	ds_read_b32 v232, v11 offset:21248
	s_waitcnt lgkmcnt(0)
	ds_read_b32 v202, v11 offset:13312
	ds_read_b32 v233, v11 offset:21504
	ds_read_b32 v203, v11 offset:13568
	ds_read_b32 v235, v11 offset:21760
	ds_read_b32 v204, v11 offset:13824
	ds_read_b32 v236, v11 offset:22016
	ds_read_b32 v205, v11 offset:14080
	ds_read_b32 v237, v11 offset:22272
	s_waitcnt lgkmcnt(0)
	ds_read_b32 v206, v11 offset:14336
	ds_read_b32 v238, v11 offset:22528
	ds_read_b32 v207, v11 offset:14592
	ds_read_b32 v239, v11 offset:22784
	ds_read_b32 v208, v11 offset:14848
	ds_read_b32 v240, v11 offset:23040
	ds_read_b32 v209, v11 offset:15104
	ds_read_b32 v241, v11 offset:23296
	s_waitcnt lgkmcnt(0)
	ds_read_b32 v210, v11 offset:15360
	ds_read_b32 v242, v11 offset:23552
	ds_read_b32 v211, v11 offset:15616
	ds_read_b32 v243, v11 offset:23808
	ds_read_b32 v212, v11 offset:15872
	ds_read_b32 v244, v11 offset:24064
	ds_read_b32 v213, v11 offset:16128
	ds_read_b32 v245, v11 offset:24320
	s_waitcnt lgkmcnt(0)
	ds_read_b32 v226, v11 offset:16384
	ds_read_b32 v215, v11 offset:24576
	ds_read_b32 v227, v11 offset:16640
	ds_read_b32 v216, v11 offset:24832
	ds_read_b32 v228, v11 offset:16896
	ds_read_b32 v221, v11 offset:25088
	ds_read_b32 v229, v11 offset:17152
	ds_read_b32 v224, v11 offset:25344
	s_waitcnt lgkmcnt(0)
	s_sub_i32 s26, s31, 0
	v_cmp_gt_i32_e64 s[22:23], s26, v10
	s_sub_i32 s27, s31, 64
	v_cmp_gt_i32_e64 s[24:25], s27, v10
	s_nop 0
	v_cndmask_b32_e64 v186, 0, v186, s[22:23]
	s_sub_i32 s26, s31, 128
	v_cmp_gt_i32_e64 s[22:23], s26, v10
	v_cndmask_b32_e64 v187, 0, v187, s[24:25]
	s_sub_i32 s27, s31, 192
	v_cmp_gt_i32_e64 s[24:25], s27, v10
	v_cndmask_b32_e64 v188, 0, v188, s[22:23]
	s_sub_i32 s26, s31, 256
	v_cmp_gt_i32_e64 s[22:23], s26, v10
	v_cndmask_b32_e64 v189, 0, v189, s[24:25]
	s_sub_i32 s27, s31, 320
	v_cmp_gt_i32_e64 s[24:25], s27, v10
	v_cndmask_b32_e64 v190, 0, v190, s[22:23]
	s_sub_i32 s26, s31, 384
	v_cmp_gt_i32_e64 s[22:23], s26, v10
	v_cndmask_b32_e64 v191, 0, v191, s[24:25]
	s_sub_i32 s27, s31, 448
	v_cmp_gt_i32_e64 s[24:25], s27, v10
	v_cndmask_b32_e64 v192, 0, v192, s[22:23]
	s_sub_i32 s26, s31, 512
	v_cmp_gt_i32_e64 s[22:23], s26, v10
	v_cndmask_b32_e64 v193, 0, v193, s[24:25]
	s_sub_i32 s27, s31, 576
	v_cmp_gt_i32_e64 s[24:25], s27, v10
	v_cndmask_b32_e64 v194, 0, v194, s[22:23]
	s_sub_i32 s26, s31, 640
	v_cmp_gt_i32_e64 s[22:23], s26, v10
	v_cndmask_b32_e64 v195, 0, v195, s[24:25]
	s_sub_i32 s27, s31, 704
	v_cmp_gt_i32_e64 s[24:25], s27, v10
	v_cndmask_b32_e64 v196, 0, v196, s[22:23]
	s_sub_i32 s26, s31, 768
	v_cmp_gt_i32_e64 s[22:23], s26, v10
	v_cndmask_b32_e64 v197, 0, v197, s[24:25]
	s_sub_i32 s27, s31, 832
	v_cmp_gt_i32_e64 s[24:25], s27, v10
	v_cndmask_b32_e64 v198, 0, v198, s[22:23]
	s_sub_i32 s26, s31, 896
	v_cmp_gt_i32_e64 s[22:23], s26, v10
	v_cndmask_b32_e64 v199, 0, v199, s[24:25]
	s_sub_i32 s27, s31, 960
	v_cmp_gt_i32_e64 s[24:25], s27, v10
	v_cndmask_b32_e64 v200, 0, v200, s[22:23]
	s_sub_i32 s26, s31, 1024
	v_cmp_gt_i32_e64 s[22:23], s26, v10
	v_cndmask_b32_e64 v201, 0, v201, s[24:25]
	s_sub_i32 s27, s31, 1088
	v_cmp_gt_i32_e64 s[24:25], s27, v10
	v_cndmask_b32_e64 v202, 0, v202, s[22:23]
	s_sub_i32 s26, s31, 1152
	v_cmp_gt_i32_e64 s[22:23], s26, v10
	v_cndmask_b32_e64 v203, 0, v203, s[24:25]
	s_sub_i32 s27, s31, 1216
	v_cmp_gt_i32_e64 s[24:25], s27, v10
	v_cndmask_b32_e64 v204, 0, v204, s[22:23]
	s_sub_i32 s26, s31, 1280
	v_cmp_gt_i32_e64 s[22:23], s26, v10
	v_cndmask_b32_e64 v205, 0, v205, s[24:25]
	s_sub_i32 s27, s31, 1344
	v_cmp_gt_i32_e64 s[24:25], s27, v10
	v_cndmask_b32_e64 v206, 0, v206, s[22:23]
	s_sub_i32 s26, s31, 1408
	v_cmp_gt_i32_e64 s[22:23], s26, v10
	v_cndmask_b32_e64 v207, 0, v207, s[24:25]
	s_sub_i32 s27, s31, 1472
	v_cmp_gt_i32_e64 s[24:25], s27, v10
	v_cndmask_b32_e64 v208, 0, v208, s[22:23]
	s_sub_i32 s26, s31, 1536
	v_cmp_gt_i32_e64 s[22:23], s26, v10
	v_cndmask_b32_e64 v209, 0, v209, s[24:25]
	s_sub_i32 s27, s31, 1600
	v_cmp_gt_i32_e64 s[24:25], s27, v10
	v_cndmask_b32_e64 v210, 0, v210, s[22:23]
	s_sub_i32 s26, s31, 1664
	v_cmp_gt_i32_e64 s[22:23], s26, v10
	v_cndmask_b32_e64 v211, 0, v211, s[24:25]
	s_sub_i32 s27, s31, 1728
	v_cmp_gt_i32_e64 s[24:25], s27, v10
	v_cndmask_b32_e64 v212, 0, v212, s[22:23]
	s_sub_i32 s26, s31, 1792
	v_cmp_gt_i32_e64 s[22:23], s26, v10
	v_cndmask_b32_e64 v213, 0, v213, s[24:25]
	s_sub_i32 s27, s31, 1856
	v_cmp_gt_i32_e64 s[24:25], s27, v10
	v_cndmask_b32_e64 v226, 0, v226, s[22:23]
	s_sub_i32 s26, s31, 1920
	v_cmp_gt_i32_e64 s[22:23], s26, v10
	v_cndmask_b32_e64 v227, 0, v227, s[24:25]
	s_sub_i32 s27, s31, 1984
	v_cmp_gt_i32_e64 s[24:25], s27, v10
	v_cndmask_b32_e64 v228, 0, v228, s[22:23]
	v_cndmask_b32_e64 v229, 0, v229, s[24:25]
	s_mov_b32 s1, 0
	s_mov_b32 s2, 15

; DI void topk_phase(const bf16_t* PROJ, const unsigned char* K8, const unsigned char* V8, const unsigned short* SC, bf16_t* ODSA, int c, char* smem, int bid, int nb) {
;     ...
;       unsigned T = 0u;
;       for (int b = 15; b >= 0; --b) {
;         const unsigned cand = T | (1u << b);
;         int cc = 0;
; #pragma unroll
;         for (int i = 0; i < 64; ++i) if ((i >> 2) * 1024 < n) cc += key[i] >= cand ? 1 : 0;
;         if (block_count(cc, b & 1, red) >= 256) T = cand;
.Lsel_fb_B:
	s_xor_b64 s[52:53], s[2:3], -1
	s_xor_b64 s[4:5], s[4:5], -1
	s_xor_b64 s[96:97], s[6:7], -1
	s_xor_b64 s[94:95], s[8:9], -1
	s_xor_b64 s[92:93], s[10:11], -1
	s_xor_b64 s[90:91], s[12:13], -1
	s_xor_b64 s[88:89], s[14:15], -1
	s_mov_b32 s2, 15
	v_mov_b32_e32 v13, 0
	s_branch .LBB0_1086

; DI float sum8(float v) { v += DPPF(v, 0xB1); v += DPPF(v, 0x4E); v += DPPF(v, 0x141); return v; }
; DI void topk_phase(const bf16_t* PROJ, const unsigned char* K8, const unsigned char* V8, const unsigned short* SC, bf16_t* ODSA, int c, char* smem, int bid, int nb) {
;     ...
;     float m_run = -1e30f, l_run = 0.f, ov[16];
; #pragma unroll
;     for (int e = 0; e < 16; ++e) ov[e] = 0.f;
;     const int mysel = sel[wid * 64 + lane];
; #pragma unroll 4
;     for (int jj = 0; jj < 64; ++jj) {
;       const int j = wid * 64 + jj;
;       {
;         const size_t ro = (size_t)__builtin_amdgcn_readlane(mysel, jj) * 1024 + lane * 16;
;         const uint4 a = *(const uint4*)(K8 + ro), vv = *(const uint4*)(V8 + ro);
;         const unsigned w[4] = {a.x, a.y, a.z, a.w}, u[4] = {vv.x, vv.y, vv.z, vv.w};
;         float da = 0.f;
; #pragma unroll
;         for (int i = 0; i < 4; ++i) {
;           const f32x2v lo = __builtin_amdgcn_cvt_pk_f32_fp8((int)w[i], false), hi = __builtin_amdgcn_cvt_pk_f32_fp8((int)w[i], true);
;           da += qv[4 * i] * lo[0] + qv[4 * i + 1] * lo[1] + qv[4 * i + 2] * hi[0] + qv[4 * i + 3] * hi[1];
;         }
;         da = sum8(da);
;         da = j < count ? da : -3e30f;
;         const float mn = fmaxf(m_run, da), al = __builtin_amdgcn_exp2f(m_run - mn), pp = __builtin_amdgcn_exp2f(da - mn);
;         m_run = mn; l_run = l_run * al + pp;
; #pragma unroll
;         for (int i = 0; i < 4; ++i) {
;           const f32x2v lo = __builtin_amdgcn_cvt_pk_f32_fp8((int)u[i], false), hi = __builtin_amdgcn_cvt_pk_f32_fp8((int)u[i], true);
;           ov[4 * i] = ov[4 * i] * al + pp * lo[0]; ov[4 * i + 1] = ov[4 * i + 1] * al + pp * lo[1];
;           ov[4 * i + 2] = ov[4 * i + 2] * al + pp * hi[0]; ov[4 * i + 3] = ov[4 * i + 3] * al + pp * hi[1];
;         }
;       }
;     }
.LBB0_1313:
	s_waitcnt lgkmcnt(0)
	v_readfirstlane_b32 s1, v55
	v_readlane_b32 s0, v95, 0
	s_lshl_b32 s0, s0, 10
	s_add_u32 s4, s6, s0
	s_addc_u32 s5, s7, 0
	global_load_dwordx4 v[136:139], v16, s[4:5]
	v_readlane_b32 s0, v95, 1
	s_lshl_b32 s0, s0, 10
	s_add_u32 s4, s6, s0
	s_addc_u32 s5, s7, 0
	global_load_dwordx4 v[140:143], v16, s[4:5]
	v_readlane_b32 s0, v95, 2
	s_lshl_b32 s0, s0, 10
	s_add_u32 s4, s6, s0
	s_addc_u32 s5, s7, 0
	global_load_dwordx4 v[144:147], v16, s[4:5]
	v_readlane_b32 s0, v95, 3
	s_lshl_b32 s0, s0, 10
	s_add_u32 s4, s6, s0
	s_addc_u32 s5, s7, 0
	global_load_dwordx4 v[148:151], v16, s[4:5]
	v_readlane_b32 s0, v95, 4
	s_lshl_b32 s0, s0, 10
	s_add_u32 s4, s6, s0
	s_addc_u32 s5, s7, 0
	global_load_dwordx4 v[152:155], v16, s[4:5]
	v_readlane_b32 s0, v95, 5
	s_lshl_b32 s0, s0, 10
	s_add_u32 s4, s6, s0
	s_addc_u32 s5, s7, 0
	global_load_dwordx4 v[156:159], v16, s[4:5]
	v_readlane_b32 s0, v95, 6
	s_lshl_b32 s0, s0, 10
	s_add_u32 s4, s6, s0
	s_addc_u32 s5, s7, 0
	global_load_dwordx4 v[160:163], v16, s[4:5]
	v_readlane_b32 s0, v95, 7
	s_lshl_b32 s0, s0, 10
	s_add_u32 s4, s6, s0
	s_addc_u32 s5, s7, 0
	global_load_dwordx4 v[164:167], v16, s[4:5]
	v_readlane_b32 s0, v95, 8
	s_lshl_b32 s0, s0, 10
	s_add_u32 s4, s6, s0
	s_addc_u32 s5, s7, 0
	global_load_dwordx4 v[168:171], v16, s[4:5]
	v_readlane_b32 s0, v95, 9
	s_lshl_b32 s0, s0, 10
	s_add_u32 s4, s6, s0
	s_addc_u32 s5, s7, 0
	global_load_dwordx4 v[172:175], v16, s[4:5]
	v_readlane_b32 s0, v95, 10
	s_lshl_b32 s0, s0, 10
	s_add_u32 s4, s6, s0
	s_addc_u32 s5, s7, 0
	global_load_dwordx4 v[176:179], v16, s[4:5]
	v_readlane_b32 s0, v95, 11
	s_lshl_b32 s0, s0, 10
	s_add_u32 s4, s6, s0
	s_addc_u32 s5, s7, 0
	global_load_dwordx4 v[180:183], v16, s[4:5]
	v_readlane_b32 s0, v95, 12
	s_lshl_b32 s0, s0, 10
	s_add_u32 s4, s6, s0
	s_addc_u32 s5, s7, 0
	global_load_dwordx4 v[186:189], v16, s[4:5]
	v_readlane_b32 s0, v95, 13
	s_lshl_b32 s0, s0, 10
	s_add_u32 s4, s6, s0
	s_addc_u32 s5, s7, 0
	global_load_dwordx4 v[190:193], v16, s[4:5]
	v_readlane_b32 s0, v95, 14
	s_lshl_b32 s0, s0, 10
	s_add_u32 s4, s6, s0
	s_addc_u32 s5, s7, 0
	global_load_dwordx4 v[194:197], v16, s[4:5]
	v_readlane_b32 s0, v95, 15
	s_lshl_b32 s0, s0, 10
	s_add_u32 s4, s6, s0
	s_addc_u32 s5, s7, 0
	global_load_dwordx4 v[198:201], v16, s[4:5]
	v_mov_b32_e32 v240, v37
	v_mov_b32_e32 v241, v39
	v_mov_b32_e32 v37, v38
	v_mov_b32_e32 v39, v42
	v_mov_b32_e32 v38, v40
	v_mov_b32_e32 v42, v41
	v_mov_b32_e32 v40, v240
	v_mov_b32_e32 v41, v241
	v_mov_b32_e32 v240, v45
	v_mov_b32_e32 v241, v47
	v_mov_b32_e32 v45, v46
	v_mov_b32_e32 v47, v50
	v_mov_b32_e32 v46, v48
	v_mov_b32_e32 v50, v49
	v_mov_b32_e32 v48, v240
	v_mov_b32_e32 v49, v241
	v_mov_b32_e32 v0, 0
	v_mov_b32_e32 v1, 0
	v_mov_b32_e32 v2, 0
	v_mov_b32_e32 v3, 0
	v_mov_b32_e32 v4, 0
	v_mov_b32_e32 v5, 0
	v_mov_b32_e32 v6, 0
	v_mov_b32_e32 v7, 0
	v_mov_b32_e32 v8, 0
	v_mov_b32_e32 v9, 0
	v_mov_b32_e32 v10, 0
	v_mov_b32_e32 v11, 0
	v_mov_b32_e32 v12, 0
	v_mov_b32_e32 v13, 0
	v_mov_b32_e32 v14, 0
	v_mov_b32_e32 v15, 0
	v_mov_b32_e32 v215, 0
	v_mov_b32_e32 v216, 0xf149f2ca
	s_waitcnt vmcnt(15)
	v_cvt_pk_f32_fp8_e32 v[240:241], v136
	v_cvt_pk_f32_fp8_sdwa v[242:243], v136 src0_sel:WORD_1
	v_cvt_pk_f32_fp8_e32 v[244:245], v137
	v_cvt_pk_f32_fp8_sdwa v[202:203], v137 src0_sel:WORD_1
	v_pk_mul_f32 v[204:205], v[240:241], v[36:37]
	v_pk_mul_f32 v[206:207], v[242:243], v[38:39]
	v_cvt_pk_f32_fp8_e32 v[240:241], v138
	v_cvt_pk_f32_fp8_sdwa v[242:243], v138 src0_sel:WORD_1
	v_pk_fma_f32 v[204:205], v[244:245], v[40:41], v[204:205]
	v_pk_fma_f32 v[206:207], v[202:203], v[42:43], v[206:207]
	v_cvt_pk_f32_fp8_e32 v[244:245], v139
	v_cvt_pk_f32_fp8_sdwa v[202:203], v139 src0_sel:WORD_1
	v_pk_fma_f32 v[204:205], v[240:241], v[44:45], v[204:205]
	v_pk_fma_f32 v[206:207], v[242:243], v[46:47], v[206:207]
	v_pk_fma_f32 v[204:205], v[244:245], v[48:49], v[204:205]
	v_pk_fma_f32 v[206:207], v[202:203], v[50:51], v[206:207]
	v_readlane_b32 s0, v95, 0
	s_lshl_b32 s0, s0, 10
	s_add_u32 s4, s8, s0
	s_addc_u32 s5, s9, 0
	global_load_dwordx4 v[136:139], v16, s[4:5]
	v_pk_add_f32 v[204:205], v[204:205], v[206:207]
	s_nop 0
	v_add_f32_e32 v235, v204, v205
	s_waitcnt vmcnt(15)
	v_cvt_pk_f32_fp8_e32 v[240:241], v140
	v_cvt_pk_f32_fp8_sdwa v[242:243], v140 src0_sel:WORD_1
	v_cvt_pk_f32_fp8_e32 v[244:245], v141
	v_cvt_pk_f32_fp8_sdwa v[202:203], v141 src0_sel:WORD_1
	v_add_f32_dpp v235, v235, v235 quad_perm:[1,0,3,2] row_mask:0xf bank_mask:0xf bound_ctrl:1
	v_pk_mul_f32 v[204:205], v[240:241], v[36:37]
	v_pk_mul_f32 v[206:207], v[242:243], v[38:39]
	v_add_f32_dpp v235, v235, v235 quad_perm:[2,3,0,1] row_mask:0xf bank_mask:0xf bound_ctrl:1
	v_cvt_pk_f32_fp8_e32 v[240:241], v142
	v_cvt_pk_f32_fp8_sdwa v[242:243], v142 src0_sel:WORD_1
	v_add_f32_dpp v235, v235, v235 row_half_mirror row_mask:0xf bank_mask:0xf bound_ctrl:1
	v_pk_fma_f32 v[204:205], v[244:245], v[40:41], v[204:205]
	v_pk_fma_f32 v[206:207], v[202:203], v[42:43], v[206:207]
	s_add_i32 s0, s1, 0
	s_cmp_lt_i32 s0, s2
	s_cselect_b64 vcc, -1, 0
	v_cvt_pk_f32_fp8_e32 v[244:245], v143
	v_cvt_pk_f32_fp8_sdwa v[202:203], v143 src0_sel:WORD_1
	v_cndmask_b32_e32 v210, v220, v235, vcc
	v_pk_fma_f32 v[204:205], v[240:241], v[44:45], v[204:205]
	v_pk_fma_f32 v[206:207], v[242:243], v[46:47], v[206:207]
	v_pk_fma_f32 v[204:205], v[244:245], v[48:49], v[204:205]
	v_pk_fma_f32 v[206:207], v[202:203], v[50:51], v[206:207]
	v_readlane_b32 s0, v95, 1
	s_lshl_b32 s0, s0, 10
	s_add_u32 s4, s8, s0
	s_addc_u32 s5, s9, 0
	global_load_dwordx4 v[140:143], v16, s[4:5]
	v_pk_add_f32 v[204:205], v[204:205], v[206:207]
	s_nop 0
	v_add_f32_e32 v221, v204, v205
	s_waitcnt vmcnt(15)
; DI float sum8(float v) { v += DPPF(v, 0xB1); v += DPPF(v, 0x4E); v += DPPF(v, 0x141); return v; }
; DI void topk_phase(const bf16_t* PROJ, const unsigned char* K8, const unsigned char* V8, const unsigned short* SC, bf16_t* ODSA, int c, char* smem, int bid, int nb) {
;     ...
;     for (int jj = 0; jj < 64; ++jj) {
;       const int j = wid * 64 + jj;
;       {
;         const size_t ro = (size_t)__builtin_amdgcn_readlane(mysel, jj) * 1024 + lane * 16;
;         const uint4 a = *(const uint4*)(K8 + ro), vv = *(const uint4*)(V8 + ro);
;         const unsigned w[4] = {a.x, a.y, a.z, a.w}, u[4] = {vv.x, vv.y, vv.z, vv.w};
;         float da = 0.f;
; #pragma unroll
;         for (int i = 0; i < 4; ++i) {
;           const f32x2v lo = __builtin_amdgcn_cvt_pk_f32_fp8((int)w[i], false), hi = __builtin_amdgcn_cvt_pk_f32_fp8((int)w[i], true);
;           da += qv[4 * i] * lo[0] + qv[4 * i + 1] * lo[1] + qv[4 * i + 2] * hi[0] + qv[4 * i + 3] * hi[1];
;         }
;         da = sum8(da);
;         da = j < count ? da : -3e30f;
	v_cvt_pk_f32_fp8_e32 v[240:241], v144
	v_cvt_pk_f32_fp8_sdwa v[242:243], v144 src0_sel:WORD_1
	v_cvt_pk_f32_fp8_e32 v[244:245], v145
	v_cvt_pk_f32_fp8_sdwa v[202:203], v145 src0_sel:WORD_1
	v_add_f32_dpp v221, v221, v221 quad_perm:[1,0,3,2] row_mask:0xf bank_mask:0xf bound_ctrl:1
	v_pk_mul_f32 v[204:205], v[240:241], v[36:37]
	v_pk_mul_f32 v[206:207], v[242:243], v[38:39]
	v_add_f32_dpp v221, v221, v221 quad_perm:[2,3,0,1] row_mask:0xf bank_mask:0xf bound_ctrl:1
	v_cvt_pk_f32_fp8_e32 v[240:241], v146
	v_cvt_pk_f32_fp8_sdwa v[242:243], v146 src0_sel:WORD_1
	v_add_f32_dpp v221, v221, v221 row_half_mirror row_mask:0xf bank_mask:0xf bound_ctrl:1
	v_pk_fma_f32 v[204:205], v[244:245], v[40:41], v[204:205]
	v_pk_fma_f32 v[206:207], v[202:203], v[42:43], v[206:207]
	s_add_i32 s0, s1, 1
	s_cmp_lt_i32 s0, s2
	s_cselect_b64 vcc, -1, 0
	v_cvt_pk_f32_fp8_e32 v[244:245], v147
	v_cvt_pk_f32_fp8_sdwa v[202:203], v147 src0_sel:WORD_1
	v_cndmask_b32_e32 v211, v220, v221, vcc
	v_pk_fma_f32 v[204:205], v[240:241], v[44:45], v[204:205]
	v_pk_fma_f32 v[206:207], v[242:243], v[46:47], v[206:207]
	v_pk_fma_f32 v[204:205], v[244:245], v[48:49], v[204:205]
	v_pk_fma_f32 v[206:207], v[202:203], v[50:51], v[206:207]
	v_readlane_b32 s0, v95, 2
	s_lshl_b32 s0, s0, 10
	s_add_u32 s4, s8, s0
	s_addc_u32 s5, s9, 0
	global_load_dwordx4 v[144:147], v16, s[4:5]
	v_pk_add_f32 v[204:205], v[204:205], v[206:207]
	s_nop 0
	v_add_f32_e32 v235, v204, v205
	s_waitcnt vmcnt(15)
	v_cvt_pk_f32_fp8_e32 v[240:241], v148
	v_cvt_pk_f32_fp8_sdwa v[242:243], v148 src0_sel:WORD_1
	v_cvt_pk_f32_fp8_e32 v[244:245], v149
	v_cvt_pk_f32_fp8_sdwa v[202:203], v149 src0_sel:WORD_1
	v_add_f32_dpp v235, v235, v235 quad_perm:[1,0,3,2] row_mask:0xf bank_mask:0xf bound_ctrl:1
	v_pk_mul_f32 v[204:205], v[240:241], v[36:37]
	v_pk_mul_f32 v[206:207], v[242:243], v[38:39]
	v_add_f32_dpp v235, v235, v235 quad_perm:[2,3,0,1] row_mask:0xf bank_mask:0xf bound_ctrl:1
	v_cvt_pk_f32_fp8_e32 v[240:241], v150
	v_cvt_pk_f32_fp8_sdwa v[242:243], v150 src0_sel:WORD_1
	v_add_f32_dpp v235, v235, v235 row_half_mirror row_mask:0xf bank_mask:0xf bound_ctrl:1
	v_pk_fma_f32 v[204:205], v[244:245], v[40:41], v[204:205]
	v_pk_fma_f32 v[206:207], v[202:203], v[42:43], v[206:207]
	s_add_i32 s0, s1, 2
	s_cmp_lt_i32 s0, s2
	s_cselect_b64 vcc, -1, 0
	v_cvt_pk_f32_fp8_e32 v[244:245], v151
	v_cvt_pk_f32_fp8_sdwa v[202:203], v151 src0_sel:WORD_1
	v_cndmask_b32_e32 v212, v220, v235, vcc
	v_pk_fma_f32 v[204:205], v[240:241], v[44:45], v[204:205]
	v_pk_fma_f32 v[206:207], v[242:243], v[46:47], v[206:207]
	v_pk_fma_f32 v[204:205], v[244:245], v[48:49], v[204:205]
	v_pk_fma_f32 v[206:207], v[202:203], v[50:51], v[206:207]
	v_readlane_b32 s0, v95, 3
	s_lshl_b32 s0, s0, 10
	s_add_u32 s4, s8, s0
	s_addc_u32 s5, s9, 0
	global_load_dwordx4 v[148:151], v16, s[4:5]
	v_pk_add_f32 v[204:205], v[204:205], v[206:207]
	s_nop 0
	v_add_f32_e32 v221, v204, v205
	s_waitcnt vmcnt(15)
	v_cvt_pk_f32_fp8_e32 v[240:241], v152
	v_cvt_pk_f32_fp8_sdwa v[242:243], v152 src0_sel:WORD_1
	v_cvt_pk_f32_fp8_e32 v[244:245], v153
	v_cvt_pk_f32_fp8_sdwa v[202:203], v153 src0_sel:WORD_1
	v_add_f32_dpp v221, v221, v221 quad_perm:[1,0,3,2] row_mask:0xf bank_mask:0xf bound_ctrl:1
	v_pk_mul_f32 v[204:205], v[240:241], v[36:37]
	v_pk_mul_f32 v[206:207], v[242:243], v[38:39]
	v_add_f32_dpp v221, v221, v221 quad_perm:[2,3,0,1] row_mask:0xf bank_mask:0xf bound_ctrl:1
	v_cvt_pk_f32_fp8_e32 v[240:241], v154
	v_cvt_pk_f32_fp8_sdwa v[242:243], v154 src0_sel:WORD_1
	v_add_f32_dpp v221, v221, v221 row_half_mirror row_mask:0xf bank_mask:0xf bound_ctrl:1
	v_pk_fma_f32 v[204:205], v[244:245], v[40:41], v[204:205]
	v_pk_fma_f32 v[206:207], v[202:203], v[42:43], v[206:207]
	s_add_i32 s0, s1, 3
	s_cmp_lt_i32 s0, s2
	s_cselect_b64 vcc, -1, 0
	v_cvt_pk_f32_fp8_e32 v[244:245], v155
	v_cvt_pk_f32_fp8_sdwa v[202:203], v155 src0_sel:WORD_1
	v_cndmask_b32_e32 v213, v220, v221, vcc
	v_pk_fma_f32 v[204:205], v[240:241], v[44:45], v[204:205]
	v_pk_fma_f32 v[206:207], v[242:243], v[46:47], v[206:207]
	v_pk_fma_f32 v[204:205], v[244:245], v[48:49], v[204:205]
	v_pk_fma_f32 v[206:207], v[202:203], v[50:51], v[206:207]
	v_readlane_b32 s0, v95, 4
	s_lshl_b32 s0, s0, 10
	s_add_u32 s4, s8, s0
	s_addc_u32 s5, s9, 0
	global_load_dwordx4 v[152:155], v16, s[4:5]
	v_pk_add_f32 v[204:205], v[204:205], v[206:207]
	s_nop 0
	v_add_f32_e32 v235, v204, v205
	s_waitcnt vmcnt(15)
	v_cvt_pk_f32_fp8_e32 v[240:241], v156
	v_cvt_pk_f32_fp8_sdwa v[242:243], v156 src0_sel:WORD_1
	v_cvt_pk_f32_fp8_e32 v[244:245], v157
	v_cvt_pk_f32_fp8_sdwa v[202:203], v157 src0_sel:WORD_1
	v_add_f32_dpp v235, v235, v235 quad_perm:[1,0,3,2] row_mask:0xf bank_mask:0xf bound_ctrl:1
	v_pk_mul_f32 v[204:205], v[240:241], v[36:37]
	v_pk_mul_f32 v[206:207], v[242:243], v[38:39]
	v_add_f32_dpp v235, v235, v235 quad_perm:[2,3,0,1] row_mask:0xf bank_mask:0xf bound_ctrl:1
	v_cvt_pk_f32_fp8_e32 v[240:241], v158
	v_cvt_pk_f32_fp8_sdwa v[242:243], v158 src0_sel:WORD_1
	v_add_f32_dpp v235, v235, v235 row_half_mirror row_mask:0xf bank_mask:0xf bound_ctrl:1
	v_pk_fma_f32 v[204:205], v[244:245], v[40:41], v[204:205]
	v_pk_fma_f32 v[206:207], v[202:203], v[42:43], v[206:207]
	s_add_i32 s0, s1, 4
	s_cmp_lt_i32 s0, s2
	s_cselect_b64 vcc, -1, 0
	v_cvt_pk_f32_fp8_e32 v[244:245], v159
	v_cvt_pk_f32_fp8_sdwa v[202:203], v159 src0_sel:WORD_1
	v_cndmask_b32_e32 v226, v220, v235, vcc
	v_pk_fma_f32 v[204:205], v[240:241], v[44:45], v[204:205]
	v_pk_fma_f32 v[206:207], v[242:243], v[46:47], v[206:207]
	v_pk_fma_f32 v[204:205], v[244:245], v[48:49], v[204:205]
	v_pk_fma_f32 v[206:207], v[202:203], v[50:51], v[206:207]
	v_readlane_b32 s0, v95, 5
	s_lshl_b32 s0, s0, 10
	s_add_u32 s4, s8, s0
	s_addc_u32 s5, s9, 0
	global_load_dwordx4 v[156:159], v16, s[4:5]
	v_pk_add_f32 v[204:205], v[204:205], v[206:207]
	s_nop 0
	v_add_f32_e32 v221, v204, v205
	s_waitcnt vmcnt(15)
; DI float sum8(float v) { v += DPPF(v, 0xB1); v += DPPF(v, 0x4E); v += DPPF(v, 0x141); return v; }
; DI void topk_phase(const bf16_t* PROJ, const unsigned char* K8, const unsigned char* V8, const unsigned short* SC, bf16_t* ODSA, int c, char* smem, int bid, int nb) {
;     ...
;     for (int jj = 0; jj < 64; ++jj) {
;       const int j = wid * 64 + jj;
;       {
;         const size_t ro = (size_t)__builtin_amdgcn_readlane(mysel, jj) * 1024 + lane * 16;
;         const uint4 a = *(const uint4*)(K8 + ro), vv = *(const uint4*)(V8 + ro);
;         const unsigned w[4] = {a.x, a.y, a.z, a.w}, u[4] = {vv.x, vv.y, vv.z, vv.w};
;         float da = 0.f;
; #pragma unroll
;         for (int i = 0; i < 4; ++i) {
;           const f32x2v lo = __builtin_amdgcn_cvt_pk_f32_fp8((int)w[i], false), hi = __builtin_amdgcn_cvt_pk_f32_fp8((int)w[i], true);
;           da += qv[4 * i] * lo[0] + qv[4 * i + 1] * lo[1] + qv[4 * i + 2] * hi[0] + qv[4 * i + 3] * hi[1];
;         }
;         da = sum8(da);
;         da = j < count ? da : -3e30f;
	v_cvt_pk_f32_fp8_e32 v[240:241], v160
	v_cvt_pk_f32_fp8_sdwa v[242:243], v160 src0_sel:WORD_1
	v_cvt_pk_f32_fp8_e32 v[244:245], v161
	v_cvt_pk_f32_fp8_sdwa v[202:203], v161 src0_sel:WORD_1
	v_add_f32_dpp v221, v221, v221 quad_perm:[1,0,3,2] row_mask:0xf bank_mask:0xf bound_ctrl:1
	v_pk_mul_f32 v[204:205], v[240:241], v[36:37]
	v_pk_mul_f32 v[206:207], v[242:243], v[38:39]
	v_add_f32_dpp v221, v221, v221 quad_perm:[2,3,0,1] row_mask:0xf bank_mask:0xf bound_ctrl:1
	v_cvt_pk_f32_fp8_e32 v[240:241], v162
	v_cvt_pk_f32_fp8_sdwa v[242:243], v162 src0_sel:WORD_1
	v_add_f32_dpp v221, v221, v221 row_half_mirror row_mask:0xf bank_mask:0xf bound_ctrl:1
	v_pk_fma_f32 v[204:205], v[244:245], v[40:41], v[204:205]
	v_pk_fma_f32 v[206:207], v[202:203], v[42:43], v[206:207]
	s_add_i32 s0, s1, 5
	s_cmp_lt_i32 s0, s2
	s_cselect_b64 vcc, -1, 0
	v_cvt_pk_f32_fp8_e32 v[244:245], v163
	v_cvt_pk_f32_fp8_sdwa v[202:203], v163 src0_sel:WORD_1
	v_cndmask_b32_e32 v227, v220, v221, vcc
	v_pk_fma_f32 v[204:205], v[240:241], v[44:45], v[204:205]
	v_pk_fma_f32 v[206:207], v[242:243], v[46:47], v[206:207]
	v_pk_fma_f32 v[204:205], v[244:245], v[48:49], v[204:205]
	v_pk_fma_f32 v[206:207], v[202:203], v[50:51], v[206:207]
	v_readlane_b32 s0, v95, 6
	s_lshl_b32 s0, s0, 10
	s_add_u32 s4, s8, s0
	s_addc_u32 s5, s9, 0
	global_load_dwordx4 v[160:163], v16, s[4:5]
	v_pk_add_f32 v[204:205], v[204:205], v[206:207]
	s_nop 0
	v_add_f32_e32 v235, v204, v205
	s_waitcnt vmcnt(15)
	v_cvt_pk_f32_fp8_e32 v[240:241], v164
	v_cvt_pk_f32_fp8_sdwa v[242:243], v164 src0_sel:WORD_1
	v_cvt_pk_f32_fp8_e32 v[244:245], v165
	v_cvt_pk_f32_fp8_sdwa v[202:203], v165 src0_sel:WORD_1
	v_add_f32_dpp v235, v235, v235 quad_perm:[1,0,3,2] row_mask:0xf bank_mask:0xf bound_ctrl:1
	v_pk_mul_f32 v[204:205], v[240:241], v[36:37]
	v_pk_mul_f32 v[206:207], v[242:243], v[38:39]
	v_add_f32_dpp v235, v235, v235 quad_perm:[2,3,0,1] row_mask:0xf bank_mask:0xf bound_ctrl:1
	v_cvt_pk_f32_fp8_e32 v[240:241], v166
	v_cvt_pk_f32_fp8_sdwa v[242:243], v166 src0_sel:WORD_1
	v_add_f32_dpp v235, v235, v235 row_half_mirror row_mask:0xf bank_mask:0xf bound_ctrl:1
	v_pk_fma_f32 v[204:205], v[244:245], v[40:41], v[204:205]
	v_pk_fma_f32 v[206:207], v[202:203], v[42:43], v[206:207]
	s_add_i32 s0, s1, 6
	s_cmp_lt_i32 s0, s2
	s_cselect_b64 vcc, -1, 0
	v_cvt_pk_f32_fp8_e32 v[244:245], v167
	v_cvt_pk_f32_fp8_sdwa v[202:203], v167 src0_sel:WORD_1
	v_cndmask_b32_e32 v228, v220, v235, vcc
	v_pk_fma_f32 v[204:205], v[240:241], v[44:45], v[204:205]
	v_pk_fma_f32 v[206:207], v[242:243], v[46:47], v[206:207]
	v_pk_fma_f32 v[204:205], v[244:245], v[48:49], v[204:205]
	v_pk_fma_f32 v[206:207], v[202:203], v[50:51], v[206:207]
	v_readlane_b32 s0, v95, 7
	s_lshl_b32 s0, s0, 10
	s_add_u32 s4, s8, s0
	s_addc_u32 s5, s9, 0
	global_load_dwordx4 v[164:167], v16, s[4:5]
	v_pk_add_f32 v[204:205], v[204:205], v[206:207]
	s_nop 0
	v_add_f32_e32 v221, v204, v205
	s_waitcnt vmcnt(15)
	v_cvt_pk_f32_fp8_e32 v[240:241], v168
	v_cvt_pk_f32_fp8_sdwa v[242:243], v168 src0_sel:WORD_1
	v_cvt_pk_f32_fp8_e32 v[244:245], v169
	v_cvt_pk_f32_fp8_sdwa v[202:203], v169 src0_sel:WORD_1
	v_add_f32_dpp v221, v221, v221 quad_perm:[1,0,3,2] row_mask:0xf bank_mask:0xf bound_ctrl:1
	v_pk_mul_f32 v[204:205], v[240:241], v[36:37]
	v_pk_mul_f32 v[206:207], v[242:243], v[38:39]
	v_add_f32_dpp v221, v221, v221 quad_perm:[2,3,0,1] row_mask:0xf bank_mask:0xf bound_ctrl:1
	v_cvt_pk_f32_fp8_e32 v[240:241], v170
	v_cvt_pk_f32_fp8_sdwa v[242:243], v170 src0_sel:WORD_1
	v_add_f32_dpp v221, v221, v221 row_half_mirror row_mask:0xf bank_mask:0xf bound_ctrl:1
	v_pk_fma_f32 v[204:205], v[244:245], v[40:41], v[204:205]
	v_pk_fma_f32 v[206:207], v[202:203], v[42:43], v[206:207]
	s_add_i32 s0, s1, 7
	s_cmp_lt_i32 s0, s2
	s_cselect_b64 vcc, -1, 0
	v_cvt_pk_f32_fp8_e32 v[244:245], v171
	v_cvt_pk_f32_fp8_sdwa v[202:203], v171 src0_sel:WORD_1
	v_cndmask_b32_e32 v229, v220, v221, vcc
	v_pk_fma_f32 v[204:205], v[240:241], v[44:45], v[204:205]
	v_pk_fma_f32 v[206:207], v[242:243], v[46:47], v[206:207]
	v_pk_fma_f32 v[204:205], v[244:245], v[48:49], v[204:205]
	v_pk_fma_f32 v[206:207], v[202:203], v[50:51], v[206:207]
	v_readlane_b32 s0, v95, 8
	s_lshl_b32 s0, s0, 10
	s_add_u32 s4, s8, s0
	s_addc_u32 s5, s9, 0
	global_load_dwordx4 v[168:171], v16, s[4:5]
	v_pk_add_f32 v[204:205], v[204:205], v[206:207]
	s_nop 0
	v_add_f32_e32 v235, v204, v205
	s_waitcnt vmcnt(15)
	v_cvt_pk_f32_fp8_e32 v[240:241], v172
	v_cvt_pk_f32_fp8_sdwa v[242:243], v172 src0_sel:WORD_1
	v_cvt_pk_f32_fp8_e32 v[244:245], v173
	v_cvt_pk_f32_fp8_sdwa v[202:203], v173 src0_sel:WORD_1
	v_add_f32_dpp v235, v235, v235 quad_perm:[1,0,3,2] row_mask:0xf bank_mask:0xf bound_ctrl:1
	v_pk_mul_f32 v[204:205], v[240:241], v[36:37]
	v_pk_mul_f32 v[206:207], v[242:243], v[38:39]
	v_add_f32_dpp v235, v235, v235 quad_perm:[2,3,0,1] row_mask:0xf bank_mask:0xf bound_ctrl:1
	v_cvt_pk_f32_fp8_e32 v[240:241], v174
	v_cvt_pk_f32_fp8_sdwa v[242:243], v174 src0_sel:WORD_1
	v_add_f32_dpp v235, v235, v235 row_half_mirror row_mask:0xf bank_mask:0xf bound_ctrl:1
	v_pk_fma_f32 v[204:205], v[244:245], v[40:41], v[204:205]
	v_pk_fma_f32 v[206:207], v[202:203], v[42:43], v[206:207]
	s_add_i32 s0, s1, 8
	s_cmp_lt_i32 s0, s2
	s_cselect_b64 vcc, -1, 0
	v_cvt_pk_f32_fp8_e32 v[244:245], v175
	v_cvt_pk_f32_fp8_sdwa v[202:203], v175 src0_sel:WORD_1
	v_cndmask_b32_e32 v230, v220, v235, vcc
	v_pk_fma_f32 v[204:205], v[240:241], v[44:45], v[204:205]
	v_pk_fma_f32 v[206:207], v[242:243], v[46:47], v[206:207]
	v_pk_fma_f32 v[204:205], v[244:245], v[48:49], v[204:205]
	v_pk_fma_f32 v[206:207], v[202:203], v[50:51], v[206:207]
	v_readlane_b32 s0, v95, 9
	s_lshl_b32 s0, s0, 10
	s_add_u32 s4, s8, s0
	s_addc_u32 s5, s9, 0
	global_load_dwordx4 v[172:175], v16, s[4:5]
	v_pk_add_f32 v[204:205], v[204:205], v[206:207]
	s_nop 0
	v_add_f32_e32 v221, v204, v205
	s_waitcnt vmcnt(15)
; DI float sum8(float v) { v += DPPF(v, 0xB1); v += DPPF(v, 0x4E); v += DPPF(v, 0x141); return v; }
; DI void topk_phase(const bf16_t* PROJ, const unsigned char* K8, const unsigned char* V8, const unsigned short* SC, bf16_t* ODSA, int c, char* smem, int bid, int nb) {
;     ...
;     for (int jj = 0; jj < 64; ++jj) {
;       const int j = wid * 64 + jj;
;       {
;         const size_t ro = (size_t)__builtin_amdgcn_readlane(mysel, jj) * 1024 + lane * 16;
;         const uint4 a = *(const uint4*)(K8 + ro), vv = *(const uint4*)(V8 + ro);
;         const unsigned w[4] = {a.x, a.y, a.z, a.w}, u[4] = {vv.x, vv.y, vv.z, vv.w};
;         float da = 0.f;
; #pragma unroll
;         for (int i = 0; i < 4; ++i) {
;           const f32x2v lo = __builtin_amdgcn_cvt_pk_f32_fp8((int)w[i], false), hi = __builtin_amdgcn_cvt_pk_f32_fp8((int)w[i], true);
;           da += qv[4 * i] * lo[0] + qv[4 * i + 1] * lo[1] + qv[4 * i + 2] * hi[0] + qv[4 * i + 3] * hi[1];
;         }
;         da = sum8(da);
;         da = j < count ? da : -3e30f;
	v_cvt_pk_f32_fp8_e32 v[240:241], v176
	v_cvt_pk_f32_fp8_sdwa v[242:243], v176 src0_sel:WORD_1
	v_cvt_pk_f32_fp8_e32 v[244:245], v177
	v_cvt_pk_f32_fp8_sdwa v[202:203], v177 src0_sel:WORD_1
	v_add_f32_dpp v221, v221, v221 quad_perm:[1,0,3,2] row_mask:0xf bank_mask:0xf bound_ctrl:1
	v_pk_mul_f32 v[204:205], v[240:241], v[36:37]
	v_pk_mul_f32 v[206:207], v[242:243], v[38:39]
	v_add_f32_dpp v221, v221, v221 quad_perm:[2,3,0,1] row_mask:0xf bank_mask:0xf bound_ctrl:1
	v_cvt_pk_f32_fp8_e32 v[240:241], v178
	v_cvt_pk_f32_fp8_sdwa v[242:243], v178 src0_sel:WORD_1
	v_add_f32_dpp v221, v221, v221 row_half_mirror row_mask:0xf bank_mask:0xf bound_ctrl:1
	v_pk_fma_f32 v[204:205], v[244:245], v[40:41], v[204:205]
	v_pk_fma_f32 v[206:207], v[202:203], v[42:43], v[206:207]
	s_add_i32 s0, s1, 9
	s_cmp_lt_i32 s0, s2
	s_cselect_b64 vcc, -1, 0
	v_cvt_pk_f32_fp8_e32 v[244:245], v179
	v_cvt_pk_f32_fp8_sdwa v[202:203], v179 src0_sel:WORD_1
	v_cndmask_b32_e32 v231, v220, v221, vcc
	v_pk_fma_f32 v[204:205], v[240:241], v[44:45], v[204:205]
	v_pk_fma_f32 v[206:207], v[242:243], v[46:47], v[206:207]
	v_pk_fma_f32 v[204:205], v[244:245], v[48:49], v[204:205]
	v_pk_fma_f32 v[206:207], v[202:203], v[50:51], v[206:207]
	v_readlane_b32 s0, v95, 10
	s_lshl_b32 s0, s0, 10
	s_add_u32 s4, s8, s0
	s_addc_u32 s5, s9, 0
	global_load_dwordx4 v[176:179], v16, s[4:5]
	v_pk_add_f32 v[204:205], v[204:205], v[206:207]
	s_nop 0
	v_add_f32_e32 v235, v204, v205
	s_waitcnt vmcnt(15)
	v_cvt_pk_f32_fp8_e32 v[240:241], v180
	v_cvt_pk_f32_fp8_sdwa v[242:243], v180 src0_sel:WORD_1
	v_cvt_pk_f32_fp8_e32 v[244:245], v181
	v_cvt_pk_f32_fp8_sdwa v[202:203], v181 src0_sel:WORD_1
	v_add_f32_dpp v235, v235, v235 quad_perm:[1,0,3,2] row_mask:0xf bank_mask:0xf bound_ctrl:1
	v_pk_mul_f32 v[204:205], v[240:241], v[36:37]
	v_pk_mul_f32 v[206:207], v[242:243], v[38:39]
	v_add_f32_dpp v235, v235, v235 quad_perm:[2,3,0,1] row_mask:0xf bank_mask:0xf bound_ctrl:1
	v_cvt_pk_f32_fp8_e32 v[240:241], v182
	v_cvt_pk_f32_fp8_sdwa v[242:243], v182 src0_sel:WORD_1
	v_add_f32_dpp v235, v235, v235 row_half_mirror row_mask:0xf bank_mask:0xf bound_ctrl:1
	v_pk_fma_f32 v[204:205], v[244:245], v[40:41], v[204:205]
	v_pk_fma_f32 v[206:207], v[202:203], v[42:43], v[206:207]
	s_add_i32 s0, s1, 10
	s_cmp_lt_i32 s0, s2
	s_cselect_b64 vcc, -1, 0
	v_cvt_pk_f32_fp8_e32 v[244:245], v183
	v_cvt_pk_f32_fp8_sdwa v[202:203], v183 src0_sel:WORD_1
	v_cndmask_b32_e32 v232, v220, v235, vcc
	v_pk_fma_f32 v[204:205], v[240:241], v[44:45], v[204:205]
	v_pk_fma_f32 v[206:207], v[242:243], v[46:47], v[206:207]
	v_pk_fma_f32 v[204:205], v[244:245], v[48:49], v[204:205]
	v_pk_fma_f32 v[206:207], v[202:203], v[50:51], v[206:207]
	v_readlane_b32 s0, v95, 11
	s_lshl_b32 s0, s0, 10
	s_add_u32 s4, s8, s0
	s_addc_u32 s5, s9, 0
	global_load_dwordx4 v[180:183], v16, s[4:5]
	v_pk_add_f32 v[204:205], v[204:205], v[206:207]
	s_nop 0
	v_add_f32_e32 v221, v204, v205
	s_waitcnt vmcnt(15)
	v_cvt_pk_f32_fp8_e32 v[240:241], v186
	v_cvt_pk_f32_fp8_sdwa v[242:243], v186 src0_sel:WORD_1
	v_cvt_pk_f32_fp8_e32 v[244:245], v187
	v_cvt_pk_f32_fp8_sdwa v[202:203], v187 src0_sel:WORD_1
	v_add_f32_dpp v221, v221, v221 quad_perm:[1,0,3,2] row_mask:0xf bank_mask:0xf bound_ctrl:1
	v_pk_mul_f32 v[204:205], v[240:241], v[36:37]
	v_pk_mul_f32 v[206:207], v[242:243], v[38:39]
	v_add_f32_dpp v221, v221, v221 quad_perm:[2,3,0,1] row_mask:0xf bank_mask:0xf bound_ctrl:1
	v_cvt_pk_f32_fp8_e32 v[240:241], v188
	v_cvt_pk_f32_fp8_sdwa v[242:243], v188 src0_sel:WORD_1
	v_add_f32_dpp v221, v221, v221 row_half_mirror row_mask:0xf bank_mask:0xf bound_ctrl:1
	v_pk_fma_f32 v[204:205], v[244:245], v[40:41], v[204:205]
	v_pk_fma_f32 v[206:207], v[202:203], v[42:43], v[206:207]
	s_add_i32 s0, s1, 11
	s_cmp_lt_i32 s0, s2
	s_cselect_b64 vcc, -1, 0
	v_cvt_pk_f32_fp8_e32 v[244:245], v189
	v_cvt_pk_f32_fp8_sdwa v[202:203], v189 src0_sel:WORD_1
	v_cndmask_b32_e32 v233, v220, v221, vcc
	v_pk_fma_f32 v[204:205], v[240:241], v[44:45], v[204:205]
	v_pk_fma_f32 v[206:207], v[242:243], v[46:47], v[206:207]
	v_pk_fma_f32 v[204:205], v[244:245], v[48:49], v[204:205]
	v_pk_fma_f32 v[206:207], v[202:203], v[50:51], v[206:207]
	v_readlane_b32 s0, v95, 12
	s_lshl_b32 s0, s0, 10
	s_add_u32 s4, s8, s0
	s_addc_u32 s5, s9, 0
	global_load_dwordx4 v[186:189], v16, s[4:5]
	v_pk_add_f32 v[204:205], v[204:205], v[206:207]
	s_nop 0
	v_add_f32_e32 v235, v204, v205
	s_waitcnt vmcnt(15)
	v_cvt_pk_f32_fp8_e32 v[240:241], v190
	v_cvt_pk_f32_fp8_sdwa v[242:243], v190 src0_sel:WORD_1
	v_cvt_pk_f32_fp8_e32 v[244:245], v191
	v_cvt_pk_f32_fp8_sdwa v[202:203], v191 src0_sel:WORD_1
	v_add_f32_dpp v235, v235, v235 quad_perm:[1,0,3,2] row_mask:0xf bank_mask:0xf bound_ctrl:1
	v_pk_mul_f32 v[204:205], v[240:241], v[36:37]
	v_pk_mul_f32 v[206:207], v[242:243], v[38:39]
	v_add_f32_dpp v235, v235, v235 quad_perm:[2,3,0,1] row_mask:0xf bank_mask:0xf bound_ctrl:1
	v_cvt_pk_f32_fp8_e32 v[240:241], v192
	v_cvt_pk_f32_fp8_sdwa v[242:243], v192 src0_sel:WORD_1
	v_add_f32_dpp v235, v235, v235 row_half_mirror row_mask:0xf bank_mask:0xf bound_ctrl:1
	v_pk_fma_f32 v[204:205], v[244:245], v[40:41], v[204:205]
	v_pk_fma_f32 v[206:207], v[202:203], v[42:43], v[206:207]
	s_add_i32 s0, s1, 12
	s_cmp_lt_i32 s0, s2
	s_cselect_b64 vcc, -1, 0
	v_cvt_pk_f32_fp8_e32 v[244:245], v193
	v_cvt_pk_f32_fp8_sdwa v[202:203], v193 src0_sel:WORD_1
	v_cndmask_b32_e32 v236, v220, v235, vcc
	v_pk_fma_f32 v[204:205], v[240:241], v[44:45], v[204:205]
	v_pk_fma_f32 v[206:207], v[242:243], v[46:47], v[206:207]
	v_pk_fma_f32 v[204:205], v[244:245], v[48:49], v[204:205]
	v_pk_fma_f32 v[206:207], v[202:203], v[50:51], v[206:207]
	v_readlane_b32 s0, v95, 13
	s_lshl_b32 s0, s0, 10
	s_add_u32 s4, s8, s0
	s_addc_u32 s5, s9, 0
	global_load_dwordx4 v[190:193], v16, s[4:5]
	v_pk_add_f32 v[204:205], v[204:205], v[206:207]
	s_nop 0
	v_add_f32_e32 v221, v204, v205
	s_waitcnt vmcnt(15)
; DI float sum8(float v) { v += DPPF(v, 0xB1); v += DPPF(v, 0x4E); v += DPPF(v, 0x141); return v; }
; DI void topk_phase(const bf16_t* PROJ, const unsigned char* K8, const unsigned char* V8, const unsigned short* SC, bf16_t* ODSA, int c, char* smem, int bid, int nb) {
;     ...
;     for (int jj = 0; jj < 64; ++jj) {
;       const int j = wid * 64 + jj;
;       {
;         const size_t ro = (size_t)__builtin_amdgcn_readlane(mysel, jj) * 1024 + lane * 16;
;         const uint4 a = *(const uint4*)(K8 + ro), vv = *(const uint4*)(V8 + ro);
;         const unsigned w[4] = {a.x, a.y, a.z, a.w}, u[4] = {vv.x, vv.y, vv.z, vv.w};
;         float da = 0.f;
; #pragma unroll
;         for (int i = 0; i < 4; ++i) {
;           const f32x2v lo = __builtin_amdgcn_cvt_pk_f32_fp8((int)w[i], false), hi = __builtin_amdgcn_cvt_pk_f32_fp8((int)w[i], true);
;           da += qv[4 * i] * lo[0] + qv[4 * i + 1] * lo[1] + qv[4 * i + 2] * hi[0] + qv[4 * i + 3] * hi[1];
;         }
;         da = sum8(da);
;         da = j < count ? da : -3e30f;
;         const float mn = fmaxf(m_run, da), al = __builtin_amdgcn_exp2f(m_run - mn), pp = __builtin_amdgcn_exp2f(da - mn);
;         m_run = mn; l_run = l_run * al + pp;
; #pragma unroll
;         for (int i = 0; i < 4; ++i) {
;           const f32x2v lo = __builtin_amdgcn_cvt_pk_f32_fp8((int)u[i], false), hi = __builtin_amdgcn_cvt_pk_f32_fp8((int)u[i], true);
;           ov[4 * i] = ov[4 * i] * al + pp * lo[0]; ov[4 * i + 1] = ov[4 * i + 1] * al + pp * lo[1];
;           ov[4 * i + 2] = ov[4 * i + 2] * al + pp * hi[0]; ov[4 * i + 3] = ov[4 * i + 3] * al + pp * hi[1];
;         }
	v_cvt_pk_f32_fp8_e32 v[240:241], v194
	v_cvt_pk_f32_fp8_sdwa v[242:243], v194 src0_sel:WORD_1
	v_cvt_pk_f32_fp8_e32 v[244:245], v195
	v_cvt_pk_f32_fp8_sdwa v[202:203], v195 src0_sel:WORD_1
	v_add_f32_dpp v221, v221, v221 quad_perm:[1,0,3,2] row_mask:0xf bank_mask:0xf bound_ctrl:1
	v_pk_mul_f32 v[204:205], v[240:241], v[36:37]
	v_pk_mul_f32 v[206:207], v[242:243], v[38:39]
	v_add_f32_dpp v221, v221, v221 quad_perm:[2,3,0,1] row_mask:0xf bank_mask:0xf bound_ctrl:1
	v_cvt_pk_f32_fp8_e32 v[240:241], v196
	v_cvt_pk_f32_fp8_sdwa v[242:243], v196 src0_sel:WORD_1
	v_add_f32_dpp v221, v221, v221 row_half_mirror row_mask:0xf bank_mask:0xf bound_ctrl:1
	v_pk_fma_f32 v[204:205], v[244:245], v[40:41], v[204:205]
	v_pk_fma_f32 v[206:207], v[202:203], v[42:43], v[206:207]
	s_add_i32 s0, s1, 13
	s_cmp_lt_i32 s0, s2
	s_cselect_b64 vcc, -1, 0
	v_cvt_pk_f32_fp8_e32 v[244:245], v197
	v_cvt_pk_f32_fp8_sdwa v[202:203], v197 src0_sel:WORD_1
	v_cndmask_b32_e32 v237, v220, v221, vcc
	v_pk_fma_f32 v[204:205], v[240:241], v[44:45], v[204:205]
	v_pk_fma_f32 v[206:207], v[242:243], v[46:47], v[206:207]
	v_pk_fma_f32 v[204:205], v[244:245], v[48:49], v[204:205]
	v_pk_fma_f32 v[206:207], v[202:203], v[50:51], v[206:207]
	v_readlane_b32 s0, v95, 14
	s_lshl_b32 s0, s0, 10
	s_add_u32 s4, s8, s0
	s_addc_u32 s5, s9, 0
	global_load_dwordx4 v[194:197], v16, s[4:5]
	v_pk_add_f32 v[204:205], v[204:205], v[206:207]
	s_nop 0
	v_add_f32_e32 v235, v204, v205
	s_waitcnt vmcnt(15)
	v_cvt_pk_f32_fp8_e32 v[240:241], v198
	v_cvt_pk_f32_fp8_sdwa v[242:243], v198 src0_sel:WORD_1
	v_cvt_pk_f32_fp8_e32 v[244:245], v199
	v_cvt_pk_f32_fp8_sdwa v[202:203], v199 src0_sel:WORD_1
	v_add_f32_dpp v235, v235, v235 quad_perm:[1,0,3,2] row_mask:0xf bank_mask:0xf bound_ctrl:1
	v_pk_mul_f32 v[204:205], v[240:241], v[36:37]
	v_pk_mul_f32 v[206:207], v[242:243], v[38:39]
	v_add_f32_dpp v235, v235, v235 quad_perm:[2,3,0,1] row_mask:0xf bank_mask:0xf bound_ctrl:1
	v_cvt_pk_f32_fp8_e32 v[240:241], v200
	v_cvt_pk_f32_fp8_sdwa v[242:243], v200 src0_sel:WORD_1
	v_add_f32_dpp v235, v235, v235 row_half_mirror row_mask:0xf bank_mask:0xf bound_ctrl:1
	v_pk_fma_f32 v[204:205], v[244:245], v[40:41], v[204:205]
	v_pk_fma_f32 v[206:207], v[202:203], v[42:43], v[206:207]
	s_add_i32 s0, s1, 14
	s_cmp_lt_i32 s0, s2
	s_cselect_b64 vcc, -1, 0
	v_cvt_pk_f32_fp8_e32 v[244:245], v201
	v_cvt_pk_f32_fp8_sdwa v[202:203], v201 src0_sel:WORD_1
	v_cndmask_b32_e32 v238, v220, v235, vcc
	v_pk_fma_f32 v[204:205], v[240:241], v[44:45], v[204:205]
	v_pk_fma_f32 v[206:207], v[242:243], v[46:47], v[206:207]
	v_pk_fma_f32 v[204:205], v[244:245], v[48:49], v[204:205]
	v_pk_fma_f32 v[206:207], v[202:203], v[50:51], v[206:207]
	v_readlane_b32 s0, v95, 15
	s_lshl_b32 s0, s0, 10
	s_add_u32 s4, s8, s0
	s_addc_u32 s5, s9, 0
	global_load_dwordx4 v[198:201], v16, s[4:5]
	v_pk_add_f32 v[204:205], v[204:205], v[206:207]
	s_nop 0
	v_add_f32_e32 v221, v204, v205
	s_nop 1
	v_add_f32_dpp v221, v221, v221 quad_perm:[1,0,3,2] row_mask:0xf bank_mask:0xf bound_ctrl:1
	s_nop 1
	v_add_f32_dpp v221, v221, v221 quad_perm:[2,3,0,1] row_mask:0xf bank_mask:0xf bound_ctrl:1
	s_nop 1
	v_add_f32_dpp v221, v221, v221 row_half_mirror row_mask:0xf bank_mask:0xf bound_ctrl:1
	s_add_i32 s0, s1, 15
	s_cmp_lt_i32 s0, s2
	s_cselect_b64 vcc, -1, 0
	s_nop 1
	v_cndmask_b32_e32 v239, v220, v221, vcc
	v_max3_f32 v224, v210, v211, v212
	v_max3_f32 v224, v224, v213, v226
	v_max3_f32 v224, v224, v227, v228
	v_max3_f32 v224, v224, v229, v230
	v_max3_f32 v224, v224, v231, v232
	v_max3_f32 v224, v224, v233, v236
	v_max3_f32 v224, v224, v237, v238
	v_max_f32_e32 v224, v224, v239
	v_max_f32_e32 v216, v216, v224
	v_sub_f32_e32 v210, v210, v216
	v_exp_f32_e32 v210, v210
	s_waitcnt vmcnt(15)
	v_cvt_pk_f32_fp8_e32 v[240:241], v136
	v_cvt_pk_f32_fp8_sdwa v[242:243], v136 src0_sel:WORD_1
	v_cvt_pk_f32_fp8_e32 v[244:245], v137
	v_pk_fma_f32 v[12:13], v[240:241], v[210:211], v[12:13] op_sel_hi:[1,0,1]
	v_cvt_pk_f32_fp8_sdwa v[240:241], v137 src0_sel:WORD_1
	v_pk_fma_f32 v[14:15], v[242:243], v[210:211], v[14:15] op_sel_hi:[1,0,1]
	v_cvt_pk_f32_fp8_e32 v[242:243], v138
	v_sub_f32_e32 v211, v211, v216
	v_pk_fma_f32 v[8:9], v[244:245], v[210:211], v[8:9] op_sel_hi:[1,0,1]
	v_cvt_pk_f32_fp8_sdwa v[244:245], v138 src0_sel:WORD_1
	v_pk_fma_f32 v[10:11], v[240:241], v[210:211], v[10:11] op_sel_hi:[1,0,1]
	v_cvt_pk_f32_fp8_e32 v[240:241], v139
	v_exp_f32_e32 v211, v211
	v_pk_fma_f32 v[4:5], v[242:243], v[210:211], v[4:5] op_sel_hi:[1,0,1]
	v_cvt_pk_f32_fp8_sdwa v[242:243], v139 src0_sel:WORD_1
	v_pk_fma_f32 v[6:7], v[244:245], v[210:211], v[6:7] op_sel_hi:[1,0,1]
	v_add_f32_e32 v215, v215, v210
	v_pk_fma_f32 v[0:1], v[240:241], v[210:211], v[0:1] op_sel_hi:[1,0,1]
	v_pk_fma_f32 v[2:3], v[242:243], v[210:211], v[2:3] op_sel_hi:[1,0,1]
	v_readlane_b32 s0, v95, 16
	s_lshl_b32 s0, s0, 10
	s_add_u32 s4, s6, s0
	s_addc_u32 s5, s7, 0
	global_load_dwordx4 v[136:139], v16, s[4:5]
	s_waitcnt vmcnt(15)
	v_cvt_pk_f32_fp8_e32 v[240:241], v140
	v_cvt_pk_f32_fp8_sdwa v[242:243], v140 src0_sel:WORD_1
	v_cvt_pk_f32_fp8_e32 v[244:245], v141
	v_pk_fma_f32 v[12:13], v[240:241], v[210:211], v[12:13] op_sel:[0,1,0]
	v_cvt_pk_f32_fp8_sdwa v[240:241], v141 src0_sel:WORD_1
	v_pk_fma_f32 v[14:15], v[242:243], v[210:211], v[14:15] op_sel:[0,1,0]
	v_cvt_pk_f32_fp8_e32 v[242:243], v142
	v_sub_f32_e32 v212, v212, v216
	v_pk_fma_f32 v[8:9], v[244:245], v[210:211], v[8:9] op_sel:[0,1,0]
	v_cvt_pk_f32_fp8_sdwa v[244:245], v142 src0_sel:WORD_1
	v_pk_fma_f32 v[10:11], v[240:241], v[210:211], v[10:11] op_sel:[0,1,0]
	v_cvt_pk_f32_fp8_e32 v[240:241], v143
	v_exp_f32_e32 v212, v212
	v_pk_fma_f32 v[4:5], v[242:243], v[210:211], v[4:5] op_sel:[0,1,0]
	v_cvt_pk_f32_fp8_sdwa v[242:243], v143 src0_sel:WORD_1
	v_pk_fma_f32 v[6:7], v[244:245], v[210:211], v[6:7] op_sel:[0,1,0]
	v_add_f32_e32 v215, v215, v211
	v_pk_fma_f32 v[0:1], v[240:241], v[210:211], v[0:1] op_sel:[0,1,0]
	v_pk_fma_f32 v[2:3], v[242:243], v[210:211], v[2:3] op_sel:[0,1,0]
	v_readlane_b32 s0, v95, 17
	s_lshl_b32 s0, s0, 10
	s_add_u32 s4, s6, s0
	s_addc_u32 s5, s7, 0
	global_load_dwordx4 v[140:143], v16, s[4:5]
	s_waitcnt vmcnt(15)
; DI void topk_phase(const bf16_t* PROJ, const unsigned char* K8, const unsigned char* V8, const unsigned short* SC, bf16_t* ODSA, int c, char* smem, int bid, int nb) {
;     ...
;         const float mn = fmaxf(m_run, da), al = __builtin_amdgcn_exp2f(m_run - mn), pp = __builtin_amdgcn_exp2f(da - mn);
;         m_run = mn; l_run = l_run * al + pp;
; #pragma unroll
;         for (int i = 0; i < 4; ++i) {
;           const f32x2v lo = __builtin_amdgcn_cvt_pk_f32_fp8((int)u[i], false), hi = __builtin_amdgcn_cvt_pk_f32_fp8((int)u[i], true);
;           ov[4 * i] = ov[4 * i] * al + pp * lo[0]; ov[4 * i + 1] = ov[4 * i + 1] * al + pp * lo[1];
;           ov[4 * i + 2] = ov[4 * i + 2] * al + pp * hi[0]; ov[4 * i + 3] = ov[4 * i + 3] * al + pp * hi[1];
;         }
	v_cvt_pk_f32_fp8_e32 v[240:241], v144
	v_cvt_pk_f32_fp8_sdwa v[242:243], v144 src0_sel:WORD_1
	v_cvt_pk_f32_fp8_e32 v[244:245], v145
	v_pk_fma_f32 v[12:13], v[240:241], v[212:213], v[12:13] op_sel_hi:[1,0,1]
	v_cvt_pk_f32_fp8_sdwa v[240:241], v145 src0_sel:WORD_1
	v_pk_fma_f32 v[14:15], v[242:243], v[212:213], v[14:15] op_sel_hi:[1,0,1]
	v_cvt_pk_f32_fp8_e32 v[242:243], v146
	v_sub_f32_e32 v213, v213, v216
	v_pk_fma_f32 v[8:9], v[244:245], v[212:213], v[8:9] op_sel_hi:[1,0,1]
	v_cvt_pk_f32_fp8_sdwa v[244:245], v146 src0_sel:WORD_1
	v_pk_fma_f32 v[10:11], v[240:241], v[212:213], v[10:11] op_sel_hi:[1,0,1]
	v_cvt_pk_f32_fp8_e32 v[240:241], v147
	v_exp_f32_e32 v213, v213
	v_pk_fma_f32 v[4:5], v[242:243], v[212:213], v[4:5] op_sel_hi:[1,0,1]
	v_cvt_pk_f32_fp8_sdwa v[242:243], v147 src0_sel:WORD_1
	v_pk_fma_f32 v[6:7], v[244:245], v[212:213], v[6:7] op_sel_hi:[1,0,1]
	v_add_f32_e32 v215, v215, v212
	v_pk_fma_f32 v[0:1], v[240:241], v[212:213], v[0:1] op_sel_hi:[1,0,1]
	v_pk_fma_f32 v[2:3], v[242:243], v[212:213], v[2:3] op_sel_hi:[1,0,1]
	v_readlane_b32 s0, v95, 18
	s_lshl_b32 s0, s0, 10
	s_add_u32 s4, s6, s0
	s_addc_u32 s5, s7, 0
	global_load_dwordx4 v[144:147], v16, s[4:5]
	s_waitcnt vmcnt(15)
	v_cvt_pk_f32_fp8_e32 v[240:241], v148
	v_cvt_pk_f32_fp8_sdwa v[242:243], v148 src0_sel:WORD_1
	v_cvt_pk_f32_fp8_e32 v[244:245], v149
	v_pk_fma_f32 v[12:13], v[240:241], v[212:213], v[12:13] op_sel:[0,1,0]
	v_cvt_pk_f32_fp8_sdwa v[240:241], v149 src0_sel:WORD_1
	v_pk_fma_f32 v[14:15], v[242:243], v[212:213], v[14:15] op_sel:[0,1,0]
	v_cvt_pk_f32_fp8_e32 v[242:243], v150
	v_sub_f32_e32 v226, v226, v216
	v_pk_fma_f32 v[8:9], v[244:245], v[212:213], v[8:9] op_sel:[0,1,0]
	v_cvt_pk_f32_fp8_sdwa v[244:245], v150 src0_sel:WORD_1
	v_pk_fma_f32 v[10:11], v[240:241], v[212:213], v[10:11] op_sel:[0,1,0]
	v_cvt_pk_f32_fp8_e32 v[240:241], v151
	v_exp_f32_e32 v226, v226
	v_pk_fma_f32 v[4:5], v[242:243], v[212:213], v[4:5] op_sel:[0,1,0]
	v_cvt_pk_f32_fp8_sdwa v[242:243], v151 src0_sel:WORD_1
	v_pk_fma_f32 v[6:7], v[244:245], v[212:213], v[6:7] op_sel:[0,1,0]
	v_add_f32_e32 v215, v215, v213
	v_pk_fma_f32 v[0:1], v[240:241], v[212:213], v[0:1] op_sel:[0,1,0]
	v_pk_fma_f32 v[2:3], v[242:243], v[212:213], v[2:3] op_sel:[0,1,0]
	v_readlane_b32 s0, v95, 19
	s_lshl_b32 s0, s0, 10
	s_add_u32 s4, s6, s0
	s_addc_u32 s5, s7, 0
	global_load_dwordx4 v[148:151], v16, s[4:5]
	s_waitcnt vmcnt(15)
	v_cvt_pk_f32_fp8_e32 v[240:241], v152
	v_cvt_pk_f32_fp8_sdwa v[242:243], v152 src0_sel:WORD_1
	v_cvt_pk_f32_fp8_e32 v[244:245], v153
	v_pk_fma_f32 v[12:13], v[240:241], v[226:227], v[12:13] op_sel_hi:[1,0,1]
	v_cvt_pk_f32_fp8_sdwa v[240:241], v153 src0_sel:WORD_1
	v_pk_fma_f32 v[14:15], v[242:243], v[226:227], v[14:15] op_sel_hi:[1,0,1]
	v_cvt_pk_f32_fp8_e32 v[242:243], v154
	v_sub_f32_e32 v227, v227, v216
	v_pk_fma_f32 v[8:9], v[244:245], v[226:227], v[8:9] op_sel_hi:[1,0,1]
	v_cvt_pk_f32_fp8_sdwa v[244:245], v154 src0_sel:WORD_1
	v_pk_fma_f32 v[10:11], v[240:241], v[226:227], v[10:11] op_sel_hi:[1,0,1]
	v_cvt_pk_f32_fp8_e32 v[240:241], v155
	v_exp_f32_e32 v227, v227
	v_pk_fma_f32 v[4:5], v[242:243], v[226:227], v[4:5] op_sel_hi:[1,0,1]
	v_cvt_pk_f32_fp8_sdwa v[242:243], v155 src0_sel:WORD_1
	v_pk_fma_f32 v[6:7], v[244:245], v[226:227], v[6:7] op_sel_hi:[1,0,1]
	v_add_f32_e32 v215, v215, v226
	v_pk_fma_f32 v[0:1], v[240:241], v[226:227], v[0:1] op_sel_hi:[1,0,1]
	v_pk_fma_f32 v[2:3], v[242:243], v[226:227], v[2:3] op_sel_hi:[1,0,1]
	v_readlane_b32 s0, v95, 20
	s_lshl_b32 s0, s0, 10
	s_add_u32 s4, s6, s0
	s_addc_u32 s5, s7, 0
	global_load_dwordx4 v[152:155], v16, s[4:5]
	s_waitcnt vmcnt(15)
	v_cvt_pk_f32_fp8_e32 v[240:241], v156
	v_cvt_pk_f32_fp8_sdwa v[242:243], v156 src0_sel:WORD_1
	v_cvt_pk_f32_fp8_e32 v[244:245], v157
	v_pk_fma_f32 v[12:13], v[240:241], v[226:227], v[12:13] op_sel:[0,1,0]
	v_cvt_pk_f32_fp8_sdwa v[240:241], v157 src0_sel:WORD_1
	v_pk_fma_f32 v[14:15], v[242:243], v[226:227], v[14:15] op_sel:[0,1,0]
	v_cvt_pk_f32_fp8_e32 v[242:243], v158
	v_sub_f32_e32 v228, v228, v216
	v_pk_fma_f32 v[8:9], v[244:245], v[226:227], v[8:9] op_sel:[0,1,0]
	v_cvt_pk_f32_fp8_sdwa v[244:245], v158 src0_sel:WORD_1
	v_pk_fma_f32 v[10:11], v[240:241], v[226:227], v[10:11] op_sel:[0,1,0]
	v_cvt_pk_f32_fp8_e32 v[240:241], v159
	v_exp_f32_e32 v228, v228
	v_pk_fma_f32 v[4:5], v[242:243], v[226:227], v[4:5] op_sel:[0,1,0]
	v_cvt_pk_f32_fp8_sdwa v[242:243], v159 src0_sel:WORD_1
	v_pk_fma_f32 v[6:7], v[244:245], v[226:227], v[6:7] op_sel:[0,1,0]
	v_add_f32_e32 v215, v215, v227
	v_pk_fma_f32 v[0:1], v[240:241], v[226:227], v[0:1] op_sel:[0,1,0]
	v_pk_fma_f32 v[2:3], v[242:243], v[226:227], v[2:3] op_sel:[0,1,0]
	v_readlane_b32 s0, v95, 21
	s_lshl_b32 s0, s0, 10
	s_add_u32 s4, s6, s0
	s_addc_u32 s5, s7, 0
	global_load_dwordx4 v[156:159], v16, s[4:5]
	s_waitcnt vmcnt(15)
	v_cvt_pk_f32_fp8_e32 v[240:241], v160
	v_cvt_pk_f32_fp8_sdwa v[242:243], v160 src0_sel:WORD_1
	v_cvt_pk_f32_fp8_e32 v[244:245], v161
	v_pk_fma_f32 v[12:13], v[240:241], v[228:229], v[12:13] op_sel_hi:[1,0,1]
	v_cvt_pk_f32_fp8_sdwa v[240:241], v161 src0_sel:WORD_1
	v_pk_fma_f32 v[14:15], v[242:243], v[228:229], v[14:15] op_sel_hi:[1,0,1]
	v_cvt_pk_f32_fp8_e32 v[242:243], v162
	v_sub_f32_e32 v229, v229, v216
	v_pk_fma_f32 v[8:9], v[244:245], v[228:229], v[8:9] op_sel_hi:[1,0,1]
	v_cvt_pk_f32_fp8_sdwa v[244:245], v162 src0_sel:WORD_1
	v_pk_fma_f32 v[10:11], v[240:241], v[228:229], v[10:11] op_sel_hi:[1,0,1]
	v_cvt_pk_f32_fp8_e32 v[240:241], v163
	v_exp_f32_e32 v229, v229
	v_pk_fma_f32 v[4:5], v[242:243], v[228:229], v[4:5] op_sel_hi:[1,0,1]
	v_cvt_pk_f32_fp8_sdwa v[242:243], v163 src0_sel:WORD_1
	v_pk_fma_f32 v[6:7], v[244:245], v[228:229], v[6:7] op_sel_hi:[1,0,1]
	v_add_f32_e32 v215, v215, v228
	v_pk_fma_f32 v[0:1], v[240:241], v[228:229], v[0:1] op_sel_hi:[1,0,1]
	v_pk_fma_f32 v[2:3], v[242:243], v[228:229], v[2:3] op_sel_hi:[1,0,1]
	v_readlane_b32 s0, v95, 22
	s_lshl_b32 s0, s0, 10
	s_add_u32 s4, s6, s0
	s_addc_u32 s5, s7, 0
	global_load_dwordx4 v[160:163], v16, s[4:5]
	s_waitcnt vmcnt(15)
; DI void topk_phase(const bf16_t* PROJ, const unsigned char* K8, const unsigned char* V8, const unsigned short* SC, bf16_t* ODSA, int c, char* smem, int bid, int nb) {
;     ...
;         const float mn = fmaxf(m_run, da), al = __builtin_amdgcn_exp2f(m_run - mn), pp = __builtin_amdgcn_exp2f(da - mn);
;         m_run = mn; l_run = l_run * al + pp;
; #pragma unroll
;         for (int i = 0; i < 4; ++i) {
;           const f32x2v lo = __builtin_amdgcn_cvt_pk_f32_fp8((int)u[i], false), hi = __builtin_amdgcn_cvt_pk_f32_fp8((int)u[i], true);
;           ov[4 * i] = ov[4 * i] * al + pp * lo[0]; ov[4 * i + 1] = ov[4 * i + 1] * al + pp * lo[1];
;           ov[4 * i + 2] = ov[4 * i + 2] * al + pp * hi[0]; ov[4 * i + 3] = ov[4 * i + 3] * al + pp * hi[1];
;         }
	v_cvt_pk_f32_fp8_e32 v[240:241], v164
	v_cvt_pk_f32_fp8_sdwa v[242:243], v164 src0_sel:WORD_1
	v_cvt_pk_f32_fp8_e32 v[244:245], v165
	v_pk_fma_f32 v[12:13], v[240:241], v[228:229], v[12:13] op_sel:[0,1,0]
	v_cvt_pk_f32_fp8_sdwa v[240:241], v165 src0_sel:WORD_1
	v_pk_fma_f32 v[14:15], v[242:243], v[228:229], v[14:15] op_sel:[0,1,0]
	v_cvt_pk_f32_fp8_e32 v[242:243], v166
	v_sub_f32_e32 v230, v230, v216
	v_pk_fma_f32 v[8:9], v[244:245], v[228:229], v[8:9] op_sel:[0,1,0]
	v_cvt_pk_f32_fp8_sdwa v[244:245], v166 src0_sel:WORD_1
	v_pk_fma_f32 v[10:11], v[240:241], v[228:229], v[10:11] op_sel:[0,1,0]
	v_cvt_pk_f32_fp8_e32 v[240:241], v167
	v_exp_f32_e32 v230, v230
	v_pk_fma_f32 v[4:5], v[242:243], v[228:229], v[4:5] op_sel:[0,1,0]
	v_cvt_pk_f32_fp8_sdwa v[242:243], v167 src0_sel:WORD_1
	v_pk_fma_f32 v[6:7], v[244:245], v[228:229], v[6:7] op_sel:[0,1,0]
	v_add_f32_e32 v215, v215, v229
	v_pk_fma_f32 v[0:1], v[240:241], v[228:229], v[0:1] op_sel:[0,1,0]
	v_pk_fma_f32 v[2:3], v[242:243], v[228:229], v[2:3] op_sel:[0,1,0]
	v_readlane_b32 s0, v95, 23
	s_lshl_b32 s0, s0, 10
	s_add_u32 s4, s6, s0
	s_addc_u32 s5, s7, 0
	global_load_dwordx4 v[164:167], v16, s[4:5]
	s_waitcnt vmcnt(15)
	v_cvt_pk_f32_fp8_e32 v[240:241], v168
	v_cvt_pk_f32_fp8_sdwa v[242:243], v168 src0_sel:WORD_1
	v_cvt_pk_f32_fp8_e32 v[244:245], v169
	v_pk_fma_f32 v[12:13], v[240:241], v[230:231], v[12:13] op_sel_hi:[1,0,1]
	v_cvt_pk_f32_fp8_sdwa v[240:241], v169 src0_sel:WORD_1
	v_pk_fma_f32 v[14:15], v[242:243], v[230:231], v[14:15] op_sel_hi:[1,0,1]
	v_cvt_pk_f32_fp8_e32 v[242:243], v170
	v_sub_f32_e32 v231, v231, v216
	v_pk_fma_f32 v[8:9], v[244:245], v[230:231], v[8:9] op_sel_hi:[1,0,1]
	v_cvt_pk_f32_fp8_sdwa v[244:245], v170 src0_sel:WORD_1
	v_pk_fma_f32 v[10:11], v[240:241], v[230:231], v[10:11] op_sel_hi:[1,0,1]
	v_cvt_pk_f32_fp8_e32 v[240:241], v171
	v_exp_f32_e32 v231, v231
	v_pk_fma_f32 v[4:5], v[242:243], v[230:231], v[4:5] op_sel_hi:[1,0,1]
	v_cvt_pk_f32_fp8_sdwa v[242:243], v171 src0_sel:WORD_1
	v_pk_fma_f32 v[6:7], v[244:245], v[230:231], v[6:7] op_sel_hi:[1,0,1]
	v_add_f32_e32 v215, v215, v230
	v_pk_fma_f32 v[0:1], v[240:241], v[230:231], v[0:1] op_sel_hi:[1,0,1]
	v_pk_fma_f32 v[2:3], v[242:243], v[230:231], v[2:3] op_sel_hi:[1,0,1]
	v_readlane_b32 s0, v95, 24
	s_lshl_b32 s0, s0, 10
	s_add_u32 s4, s6, s0
	s_addc_u32 s5, s7, 0
	global_load_dwordx4 v[168:171], v16, s[4:5]
	s_waitcnt vmcnt(15)
	v_cvt_pk_f32_fp8_e32 v[240:241], v172
	v_cvt_pk_f32_fp8_sdwa v[242:243], v172 src0_sel:WORD_1
	v_cvt_pk_f32_fp8_e32 v[244:245], v173
	v_pk_fma_f32 v[12:13], v[240:241], v[230:231], v[12:13] op_sel:[0,1,0]
	v_cvt_pk_f32_fp8_sdwa v[240:241], v173 src0_sel:WORD_1
	v_pk_fma_f32 v[14:15], v[242:243], v[230:231], v[14:15] op_sel:[0,1,0]
	v_cvt_pk_f32_fp8_e32 v[242:243], v174
	v_sub_f32_e32 v232, v232, v216
	v_pk_fma_f32 v[8:9], v[244:245], v[230:231], v[8:9] op_sel:[0,1,0]
	v_cvt_pk_f32_fp8_sdwa v[244:245], v174 src0_sel:WORD_1
	v_pk_fma_f32 v[10:11], v[240:241], v[230:231], v[10:11] op_sel:[0,1,0]
	v_cvt_pk_f32_fp8_e32 v[240:241], v175
	v_exp_f32_e32 v232, v232
	v_pk_fma_f32 v[4:5], v[242:243], v[230:231], v[4:5] op_sel:[0,1,0]
	v_cvt_pk_f32_fp8_sdwa v[242:243], v175 src0_sel:WORD_1
	v_pk_fma_f32 v[6:7], v[244:245], v[230:231], v[6:7] op_sel:[0,1,0]
	v_add_f32_e32 v215, v215, v231
	v_pk_fma_f32 v[0:1], v[240:241], v[230:231], v[0:1] op_sel:[0,1,0]
	v_pk_fma_f32 v[2:3], v[242:243], v[230:231], v[2:3] op_sel:[0,1,0]
	v_readlane_b32 s0, v95, 25
	s_lshl_b32 s0, s0, 10
	s_add_u32 s4, s6, s0
	s_addc_u32 s5, s7, 0
	global_load_dwordx4 v[172:175], v16, s[4:5]
	s_waitcnt vmcnt(15)
	v_cvt_pk_f32_fp8_e32 v[240:241], v176
	v_cvt_pk_f32_fp8_sdwa v[242:243], v176 src0_sel:WORD_1
	v_cvt_pk_f32_fp8_e32 v[244:245], v177
	v_pk_fma_f32 v[12:13], v[240:241], v[232:233], v[12:13] op_sel_hi:[1,0,1]
	v_cvt_pk_f32_fp8_sdwa v[240:241], v177 src0_sel:WORD_1
	v_pk_fma_f32 v[14:15], v[242:243], v[232:233], v[14:15] op_sel_hi:[1,0,1]
	v_cvt_pk_f32_fp8_e32 v[242:243], v178
	v_sub_f32_e32 v233, v233, v216
	v_pk_fma_f32 v[8:9], v[244:245], v[232:233], v[8:9] op_sel_hi:[1,0,1]
	v_cvt_pk_f32_fp8_sdwa v[244:245], v178 src0_sel:WORD_1
	v_pk_fma_f32 v[10:11], v[240:241], v[232:233], v[10:11] op_sel_hi:[1,0,1]
	v_cvt_pk_f32_fp8_e32 v[240:241], v179
	v_exp_f32_e32 v233, v233
	v_pk_fma_f32 v[4:5], v[242:243], v[232:233], v[4:5] op_sel_hi:[1,0,1]
	v_cvt_pk_f32_fp8_sdwa v[242:243], v179 src0_sel:WORD_1
	v_pk_fma_f32 v[6:7], v[244:245], v[232:233], v[6:7] op_sel_hi:[1,0,1]
	v_add_f32_e32 v215, v215, v232
	v_pk_fma_f32 v[0:1], v[240:241], v[232:233], v[0:1] op_sel_hi:[1,0,1]
	v_pk_fma_f32 v[2:3], v[242:243], v[232:233], v[2:3] op_sel_hi:[1,0,1]
	v_readlane_b32 s0, v95, 26
	s_lshl_b32 s0, s0, 10
	s_add_u32 s4, s6, s0
	s_addc_u32 s5, s7, 0
	global_load_dwordx4 v[176:179], v16, s[4:5]
	s_waitcnt vmcnt(15)
	v_cvt_pk_f32_fp8_e32 v[240:241], v180
	v_cvt_pk_f32_fp8_sdwa v[242:243], v180 src0_sel:WORD_1
	v_cvt_pk_f32_fp8_e32 v[244:245], v181
	v_pk_fma_f32 v[12:13], v[240:241], v[232:233], v[12:13] op_sel:[0,1,0]
	v_cvt_pk_f32_fp8_sdwa v[240:241], v181 src0_sel:WORD_1
	v_pk_fma_f32 v[14:15], v[242:243], v[232:233], v[14:15] op_sel:[0,1,0]
	v_cvt_pk_f32_fp8_e32 v[242:243], v182
	v_sub_f32_e32 v236, v236, v216
	v_pk_fma_f32 v[8:9], v[244:245], v[232:233], v[8:9] op_sel:[0,1,0]
	v_cvt_pk_f32_fp8_sdwa v[244:245], v182 src0_sel:WORD_1
	v_pk_fma_f32 v[10:11], v[240:241], v[232:233], v[10:11] op_sel:[0,1,0]
	v_cvt_pk_f32_fp8_e32 v[240:241], v183
	v_exp_f32_e32 v236, v236
	v_pk_fma_f32 v[4:5], v[242:243], v[232:233], v[4:5] op_sel:[0,1,0]
	v_cvt_pk_f32_fp8_sdwa v[242:243], v183 src0_sel:WORD_1
	v_pk_fma_f32 v[6:7], v[244:245], v[232:233], v[6:7] op_sel:[0,1,0]
	v_add_f32_e32 v215, v215, v233
	v_pk_fma_f32 v[0:1], v[240:241], v[232:233], v[0:1] op_sel:[0,1,0]
	v_pk_fma_f32 v[2:3], v[242:243], v[232:233], v[2:3] op_sel:[0,1,0]
	v_readlane_b32 s0, v95, 27
	s_lshl_b32 s0, s0, 10
	s_add_u32 s4, s6, s0
	s_addc_u32 s5, s7, 0
	global_load_dwordx4 v[180:183], v16, s[4:5]
	s_waitcnt vmcnt(15)
; DI float sum8(float v) { v += DPPF(v, 0xB1); v += DPPF(v, 0x4E); v += DPPF(v, 0x141); return v; }
; DI void topk_phase(const bf16_t* PROJ, const unsigned char* K8, const unsigned char* V8, const unsigned short* SC, bf16_t* ODSA, int c, char* smem, int bid, int nb) {
;     ...
;         const size_t ro = (size_t)__builtin_amdgcn_readlane(mysel, jj) * 1024 + lane * 16;
;         const uint4 a = *(const uint4*)(K8 + ro), vv = *(const uint4*)(V8 + ro);
;         const unsigned w[4] = {a.x, a.y, a.z, a.w}, u[4] = {vv.x, vv.y, vv.z, vv.w};
;         float da = 0.f;
; #pragma unroll
;         for (int i = 0; i < 4; ++i) {
;           const f32x2v lo = __builtin_amdgcn_cvt_pk_f32_fp8((int)w[i], false), hi = __builtin_amdgcn_cvt_pk_f32_fp8((int)w[i], true);
;           da += qv[4 * i] * lo[0] + qv[4 * i + 1] * lo[1] + qv[4 * i + 2] * hi[0] + qv[4 * i + 3] * hi[1];
;         }
;         da = sum8(da);
;     ...
;         const float mn = fmaxf(m_run, da), al = __builtin_amdgcn_exp2f(m_run - mn), pp = __builtin_amdgcn_exp2f(da - mn);
;         m_run = mn; l_run = l_run * al + pp;
; #pragma unroll
;         for (int i = 0; i < 4; ++i) {
;           const f32x2v lo = __builtin_amdgcn_cvt_pk_f32_fp8((int)u[i], false), hi = __builtin_amdgcn_cvt_pk_f32_fp8((int)u[i], true);
;           ov[4 * i] = ov[4 * i] * al + pp * lo[0]; ov[4 * i + 1] = ov[4 * i + 1] * al + pp * lo[1];
;           ov[4 * i + 2] = ov[4 * i + 2] * al + pp * hi[0]; ov[4 * i + 3] = ov[4 * i + 3] * al + pp * hi[1];
;         }
	v_cvt_pk_f32_fp8_e32 v[240:241], v186
	v_cvt_pk_f32_fp8_sdwa v[242:243], v186 src0_sel:WORD_1
	v_cvt_pk_f32_fp8_e32 v[244:245], v187
	v_pk_fma_f32 v[12:13], v[240:241], v[236:237], v[12:13] op_sel_hi:[1,0,1]
	v_cvt_pk_f32_fp8_sdwa v[240:241], v187 src0_sel:WORD_1
	v_pk_fma_f32 v[14:15], v[242:243], v[236:237], v[14:15] op_sel_hi:[1,0,1]
	v_cvt_pk_f32_fp8_e32 v[242:243], v188
	v_sub_f32_e32 v237, v237, v216
	v_pk_fma_f32 v[8:9], v[244:245], v[236:237], v[8:9] op_sel_hi:[1,0,1]
	v_cvt_pk_f32_fp8_sdwa v[244:245], v188 src0_sel:WORD_1
	v_pk_fma_f32 v[10:11], v[240:241], v[236:237], v[10:11] op_sel_hi:[1,0,1]
	v_cvt_pk_f32_fp8_e32 v[240:241], v189
	v_exp_f32_e32 v237, v237
	v_pk_fma_f32 v[4:5], v[242:243], v[236:237], v[4:5] op_sel_hi:[1,0,1]
	v_cvt_pk_f32_fp8_sdwa v[242:243], v189 src0_sel:WORD_1
	v_pk_fma_f32 v[6:7], v[244:245], v[236:237], v[6:7] op_sel_hi:[1,0,1]
	v_add_f32_e32 v215, v215, v236
	v_pk_fma_f32 v[0:1], v[240:241], v[236:237], v[0:1] op_sel_hi:[1,0,1]
	v_pk_fma_f32 v[2:3], v[242:243], v[236:237], v[2:3] op_sel_hi:[1,0,1]
	v_readlane_b32 s0, v95, 28
	s_lshl_b32 s0, s0, 10
	s_add_u32 s4, s6, s0
	s_addc_u32 s5, s7, 0
	global_load_dwordx4 v[186:189], v16, s[4:5]
	s_waitcnt vmcnt(15)
	v_cvt_pk_f32_fp8_e32 v[240:241], v190
	v_cvt_pk_f32_fp8_sdwa v[242:243], v190 src0_sel:WORD_1
	v_cvt_pk_f32_fp8_e32 v[244:245], v191
	v_pk_fma_f32 v[12:13], v[240:241], v[236:237], v[12:13] op_sel:[0,1,0]
	v_cvt_pk_f32_fp8_sdwa v[240:241], v191 src0_sel:WORD_1
	v_pk_fma_f32 v[14:15], v[242:243], v[236:237], v[14:15] op_sel:[0,1,0]
	v_cvt_pk_f32_fp8_e32 v[242:243], v192
	v_sub_f32_e32 v238, v238, v216
	v_pk_fma_f32 v[8:9], v[244:245], v[236:237], v[8:9] op_sel:[0,1,0]
	v_cvt_pk_f32_fp8_sdwa v[244:245], v192 src0_sel:WORD_1
	v_pk_fma_f32 v[10:11], v[240:241], v[236:237], v[10:11] op_sel:[0,1,0]
	v_cvt_pk_f32_fp8_e32 v[240:241], v193
	v_exp_f32_e32 v238, v238
	v_pk_fma_f32 v[4:5], v[242:243], v[236:237], v[4:5] op_sel:[0,1,0]
	v_cvt_pk_f32_fp8_sdwa v[242:243], v193 src0_sel:WORD_1
	v_pk_fma_f32 v[6:7], v[244:245], v[236:237], v[6:7] op_sel:[0,1,0]
	v_add_f32_e32 v215, v215, v237
	v_pk_fma_f32 v[0:1], v[240:241], v[236:237], v[0:1] op_sel:[0,1,0]
	v_pk_fma_f32 v[2:3], v[242:243], v[236:237], v[2:3] op_sel:[0,1,0]
	v_readlane_b32 s0, v95, 29
	s_lshl_b32 s0, s0, 10
	s_add_u32 s4, s6, s0
	s_addc_u32 s5, s7, 0
	global_load_dwordx4 v[190:193], v16, s[4:5]
	s_waitcnt vmcnt(15)
	v_cvt_pk_f32_fp8_e32 v[240:241], v194
	v_cvt_pk_f32_fp8_sdwa v[242:243], v194 src0_sel:WORD_1
	v_cvt_pk_f32_fp8_e32 v[244:245], v195
	v_pk_fma_f32 v[12:13], v[240:241], v[238:239], v[12:13] op_sel_hi:[1,0,1]
	v_cvt_pk_f32_fp8_sdwa v[240:241], v195 src0_sel:WORD_1
	v_pk_fma_f32 v[14:15], v[242:243], v[238:239], v[14:15] op_sel_hi:[1,0,1]
	v_cvt_pk_f32_fp8_e32 v[242:243], v196
	v_sub_f32_e32 v239, v239, v216
	v_pk_fma_f32 v[8:9], v[244:245], v[238:239], v[8:9] op_sel_hi:[1,0,1]
	v_cvt_pk_f32_fp8_sdwa v[244:245], v196 src0_sel:WORD_1
	v_pk_fma_f32 v[10:11], v[240:241], v[238:239], v[10:11] op_sel_hi:[1,0,1]
	v_cvt_pk_f32_fp8_e32 v[240:241], v197
	v_exp_f32_e32 v239, v239
	v_pk_fma_f32 v[4:5], v[242:243], v[238:239], v[4:5] op_sel_hi:[1,0,1]
	v_cvt_pk_f32_fp8_sdwa v[242:243], v197 src0_sel:WORD_1
	v_pk_fma_f32 v[6:7], v[244:245], v[238:239], v[6:7] op_sel_hi:[1,0,1]
	v_add_f32_e32 v215, v215, v238
	v_pk_fma_f32 v[0:1], v[240:241], v[238:239], v[0:1] op_sel_hi:[1,0,1]
	v_pk_fma_f32 v[2:3], v[242:243], v[238:239], v[2:3] op_sel_hi:[1,0,1]
	v_readlane_b32 s0, v95, 30
	s_lshl_b32 s0, s0, 10
	s_add_u32 s4, s6, s0
	s_addc_u32 s5, s7, 0
	global_load_dwordx4 v[194:197], v16, s[4:5]
	s_waitcnt vmcnt(15)
	v_cvt_pk_f32_fp8_e32 v[240:241], v198
	v_cvt_pk_f32_fp8_sdwa v[242:243], v198 src0_sel:WORD_1
	v_cvt_pk_f32_fp8_e32 v[244:245], v199
	v_pk_fma_f32 v[12:13], v[240:241], v[238:239], v[12:13] op_sel:[0,1,0]
	v_cvt_pk_f32_fp8_sdwa v[240:241], v199 src0_sel:WORD_1
	v_pk_fma_f32 v[14:15], v[242:243], v[238:239], v[14:15] op_sel:[0,1,0]
	v_cvt_pk_f32_fp8_e32 v[242:243], v200
	v_add_f32_e32 v215, v215, v239
	v_pk_fma_f32 v[8:9], v[244:245], v[238:239], v[8:9] op_sel:[0,1,0]
	v_cvt_pk_f32_fp8_sdwa v[244:245], v200 src0_sel:WORD_1
	v_pk_fma_f32 v[10:11], v[240:241], v[238:239], v[10:11] op_sel:[0,1,0]
	v_cvt_pk_f32_fp8_e32 v[240:241], v201
	v_pk_fma_f32 v[4:5], v[242:243], v[238:239], v[4:5] op_sel:[0,1,0]
	v_cvt_pk_f32_fp8_sdwa v[242:243], v201 src0_sel:WORD_1
	v_pk_fma_f32 v[6:7], v[244:245], v[238:239], v[6:7] op_sel:[0,1,0]
	v_pk_fma_f32 v[0:1], v[240:241], v[238:239], v[0:1] op_sel:[0,1,0]
	v_pk_fma_f32 v[2:3], v[242:243], v[238:239], v[2:3] op_sel:[0,1,0]
	v_readlane_b32 s0, v95, 31
	s_lshl_b32 s0, s0, 10
	s_add_u32 s4, s6, s0
	s_addc_u32 s5, s7, 0
	global_load_dwordx4 v[198:201], v16, s[4:5]
	s_waitcnt vmcnt(15)
	v_cvt_pk_f32_fp8_e32 v[240:241], v136
	v_cvt_pk_f32_fp8_sdwa v[242:243], v136 src0_sel:WORD_1
	v_cvt_pk_f32_fp8_e32 v[244:245], v137
	v_cvt_pk_f32_fp8_sdwa v[202:203], v137 src0_sel:WORD_1
	v_pk_mul_f32 v[204:205], v[240:241], v[36:37]
	v_pk_mul_f32 v[206:207], v[242:243], v[38:39]
	v_cvt_pk_f32_fp8_e32 v[240:241], v138
	v_cvt_pk_f32_fp8_sdwa v[242:243], v138 src0_sel:WORD_1
	v_pk_fma_f32 v[204:205], v[244:245], v[40:41], v[204:205]
	v_pk_fma_f32 v[206:207], v[202:203], v[42:43], v[206:207]
	v_cvt_pk_f32_fp8_e32 v[244:245], v139
	v_cvt_pk_f32_fp8_sdwa v[202:203], v139 src0_sel:WORD_1
	v_pk_fma_f32 v[204:205], v[240:241], v[44:45], v[204:205]
	v_pk_fma_f32 v[206:207], v[242:243], v[46:47], v[206:207]
	v_pk_fma_f32 v[204:205], v[244:245], v[48:49], v[204:205]
	v_pk_fma_f32 v[206:207], v[202:203], v[50:51], v[206:207]
	v_readlane_b32 s0, v95, 16
	s_lshl_b32 s0, s0, 10
	s_add_u32 s4, s8, s0
	s_addc_u32 s5, s9, 0
	global_load_dwordx4 v[136:139], v16, s[4:5]
	v_pk_add_f32 v[204:205], v[204:205], v[206:207]
	s_nop 0
	v_add_f32_e32 v235, v204, v205
	s_waitcnt vmcnt(15)
; DI float sum8(float v) { v += DPPF(v, 0xB1); v += DPPF(v, 0x4E); v += DPPF(v, 0x141); return v; }
; DI void topk_phase(const bf16_t* PROJ, const unsigned char* K8, const unsigned char* V8, const unsigned short* SC, bf16_t* ODSA, int c, char* smem, int bid, int nb) {
;     ...
;         const size_t ro = (size_t)__builtin_amdgcn_readlane(mysel, jj) * 1024 + lane * 16;
;         const uint4 a = *(const uint4*)(K8 + ro), vv = *(const uint4*)(V8 + ro);
;         const unsigned w[4] = {a.x, a.y, a.z, a.w}, u[4] = {vv.x, vv.y, vv.z, vv.w};
;         float da = 0.f;
; #pragma unroll
;         for (int i = 0; i < 4; ++i) {
;           const f32x2v lo = __builtin_amdgcn_cvt_pk_f32_fp8((int)w[i], false), hi = __builtin_amdgcn_cvt_pk_f32_fp8((int)w[i], true);
;           da += qv[4 * i] * lo[0] + qv[4 * i + 1] * lo[1] + qv[4 * i + 2] * hi[0] + qv[4 * i + 3] * hi[1];
;         }
;         da = sum8(da);
;         da = j < count ? da : -3e30f;
	v_cvt_pk_f32_fp8_e32 v[240:241], v140
	v_cvt_pk_f32_fp8_sdwa v[242:243], v140 src0_sel:WORD_1
	v_cvt_pk_f32_fp8_e32 v[244:245], v141
	v_cvt_pk_f32_fp8_sdwa v[202:203], v141 src0_sel:WORD_1
	v_add_f32_dpp v235, v235, v235 quad_perm:[1,0,3,2] row_mask:0xf bank_mask:0xf bound_ctrl:1
	v_pk_mul_f32 v[204:205], v[240:241], v[36:37]
	v_pk_mul_f32 v[206:207], v[242:243], v[38:39]
	v_add_f32_dpp v235, v235, v235 quad_perm:[2,3,0,1] row_mask:0xf bank_mask:0xf bound_ctrl:1
	v_cvt_pk_f32_fp8_e32 v[240:241], v142
	v_cvt_pk_f32_fp8_sdwa v[242:243], v142 src0_sel:WORD_1
	v_add_f32_dpp v235, v235, v235 row_half_mirror row_mask:0xf bank_mask:0xf bound_ctrl:1
	v_pk_fma_f32 v[204:205], v[244:245], v[40:41], v[204:205]
	v_pk_fma_f32 v[206:207], v[202:203], v[42:43], v[206:207]
	s_add_i32 s0, s1, 16
	s_cmp_lt_i32 s0, s2
	s_cselect_b64 vcc, -1, 0
	v_cvt_pk_f32_fp8_e32 v[244:245], v143
	v_cvt_pk_f32_fp8_sdwa v[202:203], v143 src0_sel:WORD_1
	v_cndmask_b32_e32 v210, v220, v235, vcc
	v_pk_fma_f32 v[204:205], v[240:241], v[44:45], v[204:205]
	v_pk_fma_f32 v[206:207], v[242:243], v[46:47], v[206:207]
	v_pk_fma_f32 v[204:205], v[244:245], v[48:49], v[204:205]
	v_pk_fma_f32 v[206:207], v[202:203], v[50:51], v[206:207]
	v_readlane_b32 s0, v95, 17
	s_lshl_b32 s0, s0, 10
	s_add_u32 s4, s8, s0
	s_addc_u32 s5, s9, 0
	global_load_dwordx4 v[140:143], v16, s[4:5]
	v_pk_add_f32 v[204:205], v[204:205], v[206:207]
	s_nop 0
	v_add_f32_e32 v221, v204, v205
	s_waitcnt vmcnt(15)
	v_cvt_pk_f32_fp8_e32 v[240:241], v144
	v_cvt_pk_f32_fp8_sdwa v[242:243], v144 src0_sel:WORD_1
	v_cvt_pk_f32_fp8_e32 v[244:245], v145
	v_cvt_pk_f32_fp8_sdwa v[202:203], v145 src0_sel:WORD_1
	v_add_f32_dpp v221, v221, v221 quad_perm:[1,0,3,2] row_mask:0xf bank_mask:0xf bound_ctrl:1
	v_pk_mul_f32 v[204:205], v[240:241], v[36:37]
	v_pk_mul_f32 v[206:207], v[242:243], v[38:39]
	v_add_f32_dpp v221, v221, v221 quad_perm:[2,3,0,1] row_mask:0xf bank_mask:0xf bound_ctrl:1
	v_cvt_pk_f32_fp8_e32 v[240:241], v146
	v_cvt_pk_f32_fp8_sdwa v[242:243], v146 src0_sel:WORD_1
	v_add_f32_dpp v221, v221, v221 row_half_mirror row_mask:0xf bank_mask:0xf bound_ctrl:1
	v_pk_fma_f32 v[204:205], v[244:245], v[40:41], v[204:205]
	v_pk_fma_f32 v[206:207], v[202:203], v[42:43], v[206:207]
	s_add_i32 s0, s1, 17
	s_cmp_lt_i32 s0, s2
	s_cselect_b64 vcc, -1, 0
	v_cvt_pk_f32_fp8_e32 v[244:245], v147
	v_cvt_pk_f32_fp8_sdwa v[202:203], v147 src0_sel:WORD_1
	v_cndmask_b32_e32 v211, v220, v221, vcc
	v_pk_fma_f32 v[204:205], v[240:241], v[44:45], v[204:205]
	v_pk_fma_f32 v[206:207], v[242:243], v[46:47], v[206:207]
	v_pk_fma_f32 v[204:205], v[244:245], v[48:49], v[204:205]
	v_pk_fma_f32 v[206:207], v[202:203], v[50:51], v[206:207]
	v_readlane_b32 s0, v95, 18
	s_lshl_b32 s0, s0, 10
	s_add_u32 s4, s8, s0
	s_addc_u32 s5, s9, 0
	global_load_dwordx4 v[144:147], v16, s[4:5]
	v_pk_add_f32 v[204:205], v[204:205], v[206:207]
	s_nop 0
	v_add_f32_e32 v235, v204, v205
	s_waitcnt vmcnt(15)
	v_cvt_pk_f32_fp8_e32 v[240:241], v148
	v_cvt_pk_f32_fp8_sdwa v[242:243], v148 src0_sel:WORD_1
	v_cvt_pk_f32_fp8_e32 v[244:245], v149
	v_cvt_pk_f32_fp8_sdwa v[202:203], v149 src0_sel:WORD_1
	v_add_f32_dpp v235, v235, v235 quad_perm:[1,0,3,2] row_mask:0xf bank_mask:0xf bound_ctrl:1
	v_pk_mul_f32 v[204:205], v[240:241], v[36:37]
	v_pk_mul_f32 v[206:207], v[242:243], v[38:39]
	v_add_f32_dpp v235, v235, v235 quad_perm:[2,3,0,1] row_mask:0xf bank_mask:0xf bound_ctrl:1
	v_cvt_pk_f32_fp8_e32 v[240:241], v150
	v_cvt_pk_f32_fp8_sdwa v[242:243], v150 src0_sel:WORD_1
	v_add_f32_dpp v235, v235, v235 row_half_mirror row_mask:0xf bank_mask:0xf bound_ctrl:1
	v_pk_fma_f32 v[204:205], v[244:245], v[40:41], v[204:205]
	v_pk_fma_f32 v[206:207], v[202:203], v[42:43], v[206:207]
	s_add_i32 s0, s1, 18
	s_cmp_lt_i32 s0, s2
	s_cselect_b64 vcc, -1, 0
	v_cvt_pk_f32_fp8_e32 v[244:245], v151
	v_cvt_pk_f32_fp8_sdwa v[202:203], v151 src0_sel:WORD_1
	v_cndmask_b32_e32 v212, v220, v235, vcc
	v_pk_fma_f32 v[204:205], v[240:241], v[44:45], v[204:205]
	v_pk_fma_f32 v[206:207], v[242:243], v[46:47], v[206:207]
	v_pk_fma_f32 v[204:205], v[244:245], v[48:49], v[204:205]
	v_pk_fma_f32 v[206:207], v[202:203], v[50:51], v[206:207]
	v_readlane_b32 s0, v95, 19
	s_lshl_b32 s0, s0, 10
	s_add_u32 s4, s8, s0
	s_addc_u32 s5, s9, 0
	global_load_dwordx4 v[148:151], v16, s[4:5]
	v_pk_add_f32 v[204:205], v[204:205], v[206:207]
	s_nop 0
	v_add_f32_e32 v221, v204, v205
	s_waitcnt vmcnt(15)
	v_cvt_pk_f32_fp8_e32 v[240:241], v152
	v_cvt_pk_f32_fp8_sdwa v[242:243], v152 src0_sel:WORD_1
	v_cvt_pk_f32_fp8_e32 v[244:245], v153
	v_cvt_pk_f32_fp8_sdwa v[202:203], v153 src0_sel:WORD_1
	v_add_f32_dpp v221, v221, v221 quad_perm:[1,0,3,2] row_mask:0xf bank_mask:0xf bound_ctrl:1
	v_pk_mul_f32 v[204:205], v[240:241], v[36:37]
	v_pk_mul_f32 v[206:207], v[242:243], v[38:39]
	v_add_f32_dpp v221, v221, v221 quad_perm:[2,3,0,1] row_mask:0xf bank_mask:0xf bound_ctrl:1
	v_cvt_pk_f32_fp8_e32 v[240:241], v154
	v_cvt_pk_f32_fp8_sdwa v[242:243], v154 src0_sel:WORD_1
	v_add_f32_dpp v221, v221, v221 row_half_mirror row_mask:0xf bank_mask:0xf bound_ctrl:1
	v_pk_fma_f32 v[204:205], v[244:245], v[40:41], v[204:205]
	v_pk_fma_f32 v[206:207], v[202:203], v[42:43], v[206:207]
	s_add_i32 s0, s1, 19
	s_cmp_lt_i32 s0, s2
	s_cselect_b64 vcc, -1, 0
	v_cvt_pk_f32_fp8_e32 v[244:245], v155
	v_cvt_pk_f32_fp8_sdwa v[202:203], v155 src0_sel:WORD_1
	v_cndmask_b32_e32 v213, v220, v221, vcc
	v_pk_fma_f32 v[204:205], v[240:241], v[44:45], v[204:205]
	v_pk_fma_f32 v[206:207], v[242:243], v[46:47], v[206:207]
	v_pk_fma_f32 v[204:205], v[244:245], v[48:49], v[204:205]
	v_pk_fma_f32 v[206:207], v[202:203], v[50:51], v[206:207]
	v_readlane_b32 s0, v95, 20
	s_lshl_b32 s0, s0, 10
	s_add_u32 s4, s8, s0
	s_addc_u32 s5, s9, 0
	global_load_dwordx4 v[152:155], v16, s[4:5]
	v_pk_add_f32 v[204:205], v[204:205], v[206:207]
	s_nop 0
	v_add_f32_e32 v235, v204, v205
	s_waitcnt vmcnt(15)
; DI float sum8(float v) { v += DPPF(v, 0xB1); v += DPPF(v, 0x4E); v += DPPF(v, 0x141); return v; }
; DI void topk_phase(const bf16_t* PROJ, const unsigned char* K8, const unsigned char* V8, const unsigned short* SC, bf16_t* ODSA, int c, char* smem, int bid, int nb) {
;     ...
;         const size_t ro = (size_t)__builtin_amdgcn_readlane(mysel, jj) * 1024 + lane * 16;
;         const uint4 a = *(const uint4*)(K8 + ro), vv = *(const uint4*)(V8 + ro);
;         const unsigned w[4] = {a.x, a.y, a.z, a.w}, u[4] = {vv.x, vv.y, vv.z, vv.w};
;         float da = 0.f;
; #pragma unroll
;         for (int i = 0; i < 4; ++i) {
;           const f32x2v lo = __builtin_amdgcn_cvt_pk_f32_fp8((int)w[i], false), hi = __builtin_amdgcn_cvt_pk_f32_fp8((int)w[i], true);
;           da += qv[4 * i] * lo[0] + qv[4 * i + 1] * lo[1] + qv[4 * i + 2] * hi[0] + qv[4 * i + 3] * hi[1];
;         }
;         da = sum8(da);
;         da = j < count ? da : -3e30f;
	v_cvt_pk_f32_fp8_e32 v[240:241], v156
	v_cvt_pk_f32_fp8_sdwa v[242:243], v156 src0_sel:WORD_1
	v_cvt_pk_f32_fp8_e32 v[244:245], v157
	v_cvt_pk_f32_fp8_sdwa v[202:203], v157 src0_sel:WORD_1
	v_add_f32_dpp v235, v235, v235 quad_perm:[1,0,3,2] row_mask:0xf bank_mask:0xf bound_ctrl:1
	v_pk_mul_f32 v[204:205], v[240:241], v[36:37]
	v_pk_mul_f32 v[206:207], v[242:243], v[38:39]
	v_add_f32_dpp v235, v235, v235 quad_perm:[2,3,0,1] row_mask:0xf bank_mask:0xf bound_ctrl:1
	v_cvt_pk_f32_fp8_e32 v[240:241], v158
	v_cvt_pk_f32_fp8_sdwa v[242:243], v158 src0_sel:WORD_1
	v_add_f32_dpp v235, v235, v235 row_half_mirror row_mask:0xf bank_mask:0xf bound_ctrl:1
	v_pk_fma_f32 v[204:205], v[244:245], v[40:41], v[204:205]
	v_pk_fma_f32 v[206:207], v[202:203], v[42:43], v[206:207]
	s_add_i32 s0, s1, 20
	s_cmp_lt_i32 s0, s2
	s_cselect_b64 vcc, -1, 0
	v_cvt_pk_f32_fp8_e32 v[244:245], v159
	v_cvt_pk_f32_fp8_sdwa v[202:203], v159 src0_sel:WORD_1
	v_cndmask_b32_e32 v226, v220, v235, vcc
	v_pk_fma_f32 v[204:205], v[240:241], v[44:45], v[204:205]
	v_pk_fma_f32 v[206:207], v[242:243], v[46:47], v[206:207]
	v_pk_fma_f32 v[204:205], v[244:245], v[48:49], v[204:205]
	v_pk_fma_f32 v[206:207], v[202:203], v[50:51], v[206:207]
	v_readlane_b32 s0, v95, 21
	s_lshl_b32 s0, s0, 10
	s_add_u32 s4, s8, s0
	s_addc_u32 s5, s9, 0
	global_load_dwordx4 v[156:159], v16, s[4:5]
	v_pk_add_f32 v[204:205], v[204:205], v[206:207]
	s_nop 0
	v_add_f32_e32 v221, v204, v205
	s_waitcnt vmcnt(15)
	v_cvt_pk_f32_fp8_e32 v[240:241], v160
	v_cvt_pk_f32_fp8_sdwa v[242:243], v160 src0_sel:WORD_1
	v_cvt_pk_f32_fp8_e32 v[244:245], v161
	v_cvt_pk_f32_fp8_sdwa v[202:203], v161 src0_sel:WORD_1
	v_add_f32_dpp v221, v221, v221 quad_perm:[1,0,3,2] row_mask:0xf bank_mask:0xf bound_ctrl:1
	v_pk_mul_f32 v[204:205], v[240:241], v[36:37]
	v_pk_mul_f32 v[206:207], v[242:243], v[38:39]
	v_add_f32_dpp v221, v221, v221 quad_perm:[2,3,0,1] row_mask:0xf bank_mask:0xf bound_ctrl:1
	v_cvt_pk_f32_fp8_e32 v[240:241], v162
	v_cvt_pk_f32_fp8_sdwa v[242:243], v162 src0_sel:WORD_1
	v_add_f32_dpp v221, v221, v221 row_half_mirror row_mask:0xf bank_mask:0xf bound_ctrl:1
	v_pk_fma_f32 v[204:205], v[244:245], v[40:41], v[204:205]
	v_pk_fma_f32 v[206:207], v[202:203], v[42:43], v[206:207]
	s_add_i32 s0, s1, 21
	s_cmp_lt_i32 s0, s2
	s_cselect_b64 vcc, -1, 0
	v_cvt_pk_f32_fp8_e32 v[244:245], v163
	v_cvt_pk_f32_fp8_sdwa v[202:203], v163 src0_sel:WORD_1
	v_cndmask_b32_e32 v227, v220, v221, vcc
	v_pk_fma_f32 v[204:205], v[240:241], v[44:45], v[204:205]
	v_pk_fma_f32 v[206:207], v[242:243], v[46:47], v[206:207]
	v_pk_fma_f32 v[204:205], v[244:245], v[48:49], v[204:205]
	v_pk_fma_f32 v[206:207], v[202:203], v[50:51], v[206:207]
	v_readlane_b32 s0, v95, 22
	s_lshl_b32 s0, s0, 10
	s_add_u32 s4, s8, s0
	s_addc_u32 s5, s9, 0
	global_load_dwordx4 v[160:163], v16, s[4:5]
	v_pk_add_f32 v[204:205], v[204:205], v[206:207]
	s_nop 0
	v_add_f32_e32 v235, v204, v205
	s_waitcnt vmcnt(15)
	v_cvt_pk_f32_fp8_e32 v[240:241], v164
	v_cvt_pk_f32_fp8_sdwa v[242:243], v164 src0_sel:WORD_1
	v_cvt_pk_f32_fp8_e32 v[244:245], v165
	v_cvt_pk_f32_fp8_sdwa v[202:203], v165 src0_sel:WORD_1
	v_add_f32_dpp v235, v235, v235 quad_perm:[1,0,3,2] row_mask:0xf bank_mask:0xf bound_ctrl:1
	v_pk_mul_f32 v[204:205], v[240:241], v[36:37]
	v_pk_mul_f32 v[206:207], v[242:243], v[38:39]
	v_add_f32_dpp v235, v235, v235 quad_perm:[2,3,0,1] row_mask:0xf bank_mask:0xf bound_ctrl:1
	v_cvt_pk_f32_fp8_e32 v[240:241], v166
	v_cvt_pk_f32_fp8_sdwa v[242:243], v166 src0_sel:WORD_1
	v_add_f32_dpp v235, v235, v235 row_half_mirror row_mask:0xf bank_mask:0xf bound_ctrl:1
	v_pk_fma_f32 v[204:205], v[244:245], v[40:41], v[204:205]
	v_pk_fma_f32 v[206:207], v[202:203], v[42:43], v[206:207]
	s_add_i32 s0, s1, 22
	s_cmp_lt_i32 s0, s2
	s_cselect_b64 vcc, -1, 0
	v_cvt_pk_f32_fp8_e32 v[244:245], v167
	v_cvt_pk_f32_fp8_sdwa v[202:203], v167 src0_sel:WORD_1
	v_cndmask_b32_e32 v228, v220, v235, vcc
	v_pk_fma_f32 v[204:205], v[240:241], v[44:45], v[204:205]
	v_pk_fma_f32 v[206:207], v[242:243], v[46:47], v[206:207]
	v_pk_fma_f32 v[204:205], v[244:245], v[48:49], v[204:205]
	v_pk_fma_f32 v[206:207], v[202:203], v[50:51], v[206:207]
	v_readlane_b32 s0, v95, 23
	s_lshl_b32 s0, s0, 10
	s_add_u32 s4, s8, s0
	s_addc_u32 s5, s9, 0
	global_load_dwordx4 v[164:167], v16, s[4:5]
	v_pk_add_f32 v[204:205], v[204:205], v[206:207]
	s_nop 0
	v_add_f32_e32 v221, v204, v205
	s_waitcnt vmcnt(15)
	v_cvt_pk_f32_fp8_e32 v[240:241], v168
	v_cvt_pk_f32_fp8_sdwa v[242:243], v168 src0_sel:WORD_1
	v_cvt_pk_f32_fp8_e32 v[244:245], v169
	v_cvt_pk_f32_fp8_sdwa v[202:203], v169 src0_sel:WORD_1
	v_add_f32_dpp v221, v221, v221 quad_perm:[1,0,3,2] row_mask:0xf bank_mask:0xf bound_ctrl:1
	v_pk_mul_f32 v[204:205], v[240:241], v[36:37]
	v_pk_mul_f32 v[206:207], v[242:243], v[38:39]
	v_add_f32_dpp v221, v221, v221 quad_perm:[2,3,0,1] row_mask:0xf bank_mask:0xf bound_ctrl:1
	v_cvt_pk_f32_fp8_e32 v[240:241], v170
	v_cvt_pk_f32_fp8_sdwa v[242:243], v170 src0_sel:WORD_1
	v_add_f32_dpp v221, v221, v221 row_half_mirror row_mask:0xf bank_mask:0xf bound_ctrl:1
	v_pk_fma_f32 v[204:205], v[244:245], v[40:41], v[204:205]
	v_pk_fma_f32 v[206:207], v[202:203], v[42:43], v[206:207]
	s_add_i32 s0, s1, 23
	s_cmp_lt_i32 s0, s2
	s_cselect_b64 vcc, -1, 0
	v_cvt_pk_f32_fp8_e32 v[244:245], v171
	v_cvt_pk_f32_fp8_sdwa v[202:203], v171 src0_sel:WORD_1
	v_cndmask_b32_e32 v229, v220, v221, vcc
	v_pk_fma_f32 v[204:205], v[240:241], v[44:45], v[204:205]
	v_pk_fma_f32 v[206:207], v[242:243], v[46:47], v[206:207]
	v_pk_fma_f32 v[204:205], v[244:245], v[48:49], v[204:205]
	v_pk_fma_f32 v[206:207], v[202:203], v[50:51], v[206:207]
	v_readlane_b32 s0, v95, 24
	s_lshl_b32 s0, s0, 10
	s_add_u32 s4, s8, s0
	s_addc_u32 s5, s9, 0
	global_load_dwordx4 v[168:171], v16, s[4:5]
	v_pk_add_f32 v[204:205], v[204:205], v[206:207]
	s_nop 0
	v_add_f32_e32 v235, v204, v205
	s_waitcnt vmcnt(15)
; DI float sum8(float v) { v += DPPF(v, 0xB1); v += DPPF(v, 0x4E); v += DPPF(v, 0x141); return v; }
; DI void topk_phase(const bf16_t* PROJ, const unsigned char* K8, const unsigned char* V8, const unsigned short* SC, bf16_t* ODSA, int c, char* smem, int bid, int nb) {
;     ...
;         const size_t ro = (size_t)__builtin_amdgcn_readlane(mysel, jj) * 1024 + lane * 16;
;         const uint4 a = *(const uint4*)(K8 + ro), vv = *(const uint4*)(V8 + ro);
;         const unsigned w[4] = {a.x, a.y, a.z, a.w}, u[4] = {vv.x, vv.y, vv.z, vv.w};
;         float da = 0.f;
; #pragma unroll
;         for (int i = 0; i < 4; ++i) {
;           const f32x2v lo = __builtin_amdgcn_cvt_pk_f32_fp8((int)w[i], false), hi = __builtin_amdgcn_cvt_pk_f32_fp8((int)w[i], true);
;           da += qv[4 * i] * lo[0] + qv[4 * i + 1] * lo[1] + qv[4 * i + 2] * hi[0] + qv[4 * i + 3] * hi[1];
;         }
;         da = sum8(da);
;         da = j < count ? da : -3e30f;
	v_cvt_pk_f32_fp8_e32 v[240:241], v172
	v_cvt_pk_f32_fp8_sdwa v[242:243], v172 src0_sel:WORD_1
	v_cvt_pk_f32_fp8_e32 v[244:245], v173
	v_cvt_pk_f32_fp8_sdwa v[202:203], v173 src0_sel:WORD_1
	v_add_f32_dpp v235, v235, v235 quad_perm:[1,0,3,2] row_mask:0xf bank_mask:0xf bound_ctrl:1
	v_pk_mul_f32 v[204:205], v[240:241], v[36:37]
	v_pk_mul_f32 v[206:207], v[242:243], v[38:39]
	v_add_f32_dpp v235, v235, v235 quad_perm:[2,3,0,1] row_mask:0xf bank_mask:0xf bound_ctrl:1
	v_cvt_pk_f32_fp8_e32 v[240:241], v174
	v_cvt_pk_f32_fp8_sdwa v[242:243], v174 src0_sel:WORD_1
	v_add_f32_dpp v235, v235, v235 row_half_mirror row_mask:0xf bank_mask:0xf bound_ctrl:1
	v_pk_fma_f32 v[204:205], v[244:245], v[40:41], v[204:205]
	v_pk_fma_f32 v[206:207], v[202:203], v[42:43], v[206:207]
	s_add_i32 s0, s1, 24
	s_cmp_lt_i32 s0, s2
	s_cselect_b64 vcc, -1, 0
	v_cvt_pk_f32_fp8_e32 v[244:245], v175
	v_cvt_pk_f32_fp8_sdwa v[202:203], v175 src0_sel:WORD_1
	v_cndmask_b32_e32 v230, v220, v235, vcc
	v_pk_fma_f32 v[204:205], v[240:241], v[44:45], v[204:205]
	v_pk_fma_f32 v[206:207], v[242:243], v[46:47], v[206:207]
	v_pk_fma_f32 v[204:205], v[244:245], v[48:49], v[204:205]
	v_pk_fma_f32 v[206:207], v[202:203], v[50:51], v[206:207]
	v_readlane_b32 s0, v95, 25
	s_lshl_b32 s0, s0, 10
	s_add_u32 s4, s8, s0
	s_addc_u32 s5, s9, 0
	global_load_dwordx4 v[172:175], v16, s[4:5]
	v_pk_add_f32 v[204:205], v[204:205], v[206:207]
	s_nop 0
	v_add_f32_e32 v221, v204, v205
	s_waitcnt vmcnt(15)
	v_cvt_pk_f32_fp8_e32 v[240:241], v176
	v_cvt_pk_f32_fp8_sdwa v[242:243], v176 src0_sel:WORD_1
	v_cvt_pk_f32_fp8_e32 v[244:245], v177
	v_cvt_pk_f32_fp8_sdwa v[202:203], v177 src0_sel:WORD_1
	v_add_f32_dpp v221, v221, v221 quad_perm:[1,0,3,2] row_mask:0xf bank_mask:0xf bound_ctrl:1
	v_pk_mul_f32 v[204:205], v[240:241], v[36:37]
	v_pk_mul_f32 v[206:207], v[242:243], v[38:39]
	v_add_f32_dpp v221, v221, v221 quad_perm:[2,3,0,1] row_mask:0xf bank_mask:0xf bound_ctrl:1
	v_cvt_pk_f32_fp8_e32 v[240:241], v178
	v_cvt_pk_f32_fp8_sdwa v[242:243], v178 src0_sel:WORD_1
	v_add_f32_dpp v221, v221, v221 row_half_mirror row_mask:0xf bank_mask:0xf bound_ctrl:1
	v_pk_fma_f32 v[204:205], v[244:245], v[40:41], v[204:205]
	v_pk_fma_f32 v[206:207], v[202:203], v[42:43], v[206:207]
	s_add_i32 s0, s1, 25
	s_cmp_lt_i32 s0, s2
	s_cselect_b64 vcc, -1, 0
	v_cvt_pk_f32_fp8_e32 v[244:245], v179
	v_cvt_pk_f32_fp8_sdwa v[202:203], v179 src0_sel:WORD_1
	v_cndmask_b32_e32 v231, v220, v221, vcc
	v_pk_fma_f32 v[204:205], v[240:241], v[44:45], v[204:205]
	v_pk_fma_f32 v[206:207], v[242:243], v[46:47], v[206:207]
	v_pk_fma_f32 v[204:205], v[244:245], v[48:49], v[204:205]
	v_pk_fma_f32 v[206:207], v[202:203], v[50:51], v[206:207]
	v_readlane_b32 s0, v95, 26
	s_lshl_b32 s0, s0, 10
	s_add_u32 s4, s8, s0
	s_addc_u32 s5, s9, 0
	global_load_dwordx4 v[176:179], v16, s[4:5]
	v_pk_add_f32 v[204:205], v[204:205], v[206:207]
	s_nop 0
	v_add_f32_e32 v235, v204, v205
	s_waitcnt vmcnt(15)
	v_cvt_pk_f32_fp8_e32 v[240:241], v180
	v_cvt_pk_f32_fp8_sdwa v[242:243], v180 src0_sel:WORD_1
	v_cvt_pk_f32_fp8_e32 v[244:245], v181
	v_cvt_pk_f32_fp8_sdwa v[202:203], v181 src0_sel:WORD_1
	v_add_f32_dpp v235, v235, v235 quad_perm:[1,0,3,2] row_mask:0xf bank_mask:0xf bound_ctrl:1
	v_pk_mul_f32 v[204:205], v[240:241], v[36:37]
	v_pk_mul_f32 v[206:207], v[242:243], v[38:39]
	v_add_f32_dpp v235, v235, v235 quad_perm:[2,3,0,1] row_mask:0xf bank_mask:0xf bound_ctrl:1
	v_cvt_pk_f32_fp8_e32 v[240:241], v182
	v_cvt_pk_f32_fp8_sdwa v[242:243], v182 src0_sel:WORD_1
	v_add_f32_dpp v235, v235, v235 row_half_mirror row_mask:0xf bank_mask:0xf bound_ctrl:1
	v_pk_fma_f32 v[204:205], v[244:245], v[40:41], v[204:205]
	v_pk_fma_f32 v[206:207], v[202:203], v[42:43], v[206:207]
	s_add_i32 s0, s1, 26
	s_cmp_lt_i32 s0, s2
	s_cselect_b64 vcc, -1, 0
	v_cvt_pk_f32_fp8_e32 v[244:245], v183
	v_cvt_pk_f32_fp8_sdwa v[202:203], v183 src0_sel:WORD_1
	v_cndmask_b32_e32 v232, v220, v235, vcc
	v_pk_fma_f32 v[204:205], v[240:241], v[44:45], v[204:205]
	v_pk_fma_f32 v[206:207], v[242:243], v[46:47], v[206:207]
	v_pk_fma_f32 v[204:205], v[244:245], v[48:49], v[204:205]
	v_pk_fma_f32 v[206:207], v[202:203], v[50:51], v[206:207]
	v_readlane_b32 s0, v95, 27
	s_lshl_b32 s0, s0, 10
	s_add_u32 s4, s8, s0
	s_addc_u32 s5, s9, 0
	global_load_dwordx4 v[180:183], v16, s[4:5]
	v_pk_add_f32 v[204:205], v[204:205], v[206:207]
	s_nop 0
	v_add_f32_e32 v221, v204, v205
	s_waitcnt vmcnt(15)
	v_cvt_pk_f32_fp8_e32 v[240:241], v186
	v_cvt_pk_f32_fp8_sdwa v[242:243], v186 src0_sel:WORD_1
	v_cvt_pk_f32_fp8_e32 v[244:245], v187
	v_cvt_pk_f32_fp8_sdwa v[202:203], v187 src0_sel:WORD_1
	v_add_f32_dpp v221, v221, v221 quad_perm:[1,0,3,2] row_mask:0xf bank_mask:0xf bound_ctrl:1
	v_pk_mul_f32 v[204:205], v[240:241], v[36:37]
	v_pk_mul_f32 v[206:207], v[242:243], v[38:39]
	v_add_f32_dpp v221, v221, v221 quad_perm:[2,3,0,1] row_mask:0xf bank_mask:0xf bound_ctrl:1
	v_cvt_pk_f32_fp8_e32 v[240:241], v188
	v_cvt_pk_f32_fp8_sdwa v[242:243], v188 src0_sel:WORD_1
	v_add_f32_dpp v221, v221, v221 row_half_mirror row_mask:0xf bank_mask:0xf bound_ctrl:1
	v_pk_fma_f32 v[204:205], v[244:245], v[40:41], v[204:205]
	v_pk_fma_f32 v[206:207], v[202:203], v[42:43], v[206:207]
	s_add_i32 s0, s1, 27
	s_cmp_lt_i32 s0, s2
	s_cselect_b64 vcc, -1, 0
	v_cvt_pk_f32_fp8_e32 v[244:245], v189
	v_cvt_pk_f32_fp8_sdwa v[202:203], v189 src0_sel:WORD_1
	v_cndmask_b32_e32 v233, v220, v221, vcc
	v_pk_fma_f32 v[204:205], v[240:241], v[44:45], v[204:205]
	v_pk_fma_f32 v[206:207], v[242:243], v[46:47], v[206:207]
	v_pk_fma_f32 v[204:205], v[244:245], v[48:49], v[204:205]
	v_pk_fma_f32 v[206:207], v[202:203], v[50:51], v[206:207]
	v_readlane_b32 s0, v95, 28
	s_lshl_b32 s0, s0, 10
	s_add_u32 s4, s8, s0
	s_addc_u32 s5, s9, 0
	global_load_dwordx4 v[186:189], v16, s[4:5]
	v_pk_add_f32 v[204:205], v[204:205], v[206:207]
	s_nop 0
	v_add_f32_e32 v235, v204, v205
	s_waitcnt vmcnt(15)
; DI float sum8(float v) { v += DPPF(v, 0xB1); v += DPPF(v, 0x4E); v += DPPF(v, 0x141); return v; }
; DI void topk_phase(const bf16_t* PROJ, const unsigned char* K8, const unsigned char* V8, const unsigned short* SC, bf16_t* ODSA, int c, char* smem, int bid, int nb) {
;     ...
;         da = sum8(da);
;         da = j < count ? da : -3e30f;
;         const float mn = fmaxf(m_run, da), al = __builtin_amdgcn_exp2f(m_run - mn), pp = __builtin_amdgcn_exp2f(da - mn);
;         m_run = mn; l_run = l_run * al + pp;
; #pragma unroll
;         for (int i = 0; i < 4; ++i) {
;           const f32x2v lo = __builtin_amdgcn_cvt_pk_f32_fp8((int)u[i], false), hi = __builtin_amdgcn_cvt_pk_f32_fp8((int)u[i], true);
;           ov[4 * i] = ov[4 * i] * al + pp * lo[0]; ov[4 * i + 1] = ov[4 * i + 1] * al + pp * lo[1];
;           ov[4 * i + 2] = ov[4 * i + 2] * al + pp * hi[0]; ov[4 * i + 3] = ov[4 * i + 3] * al + pp * hi[1];
;         }
	v_cvt_pk_f32_fp8_e32 v[240:241], v190
	v_cvt_pk_f32_fp8_sdwa v[242:243], v190 src0_sel:WORD_1
	v_cvt_pk_f32_fp8_e32 v[244:245], v191
	v_cvt_pk_f32_fp8_sdwa v[202:203], v191 src0_sel:WORD_1
	v_add_f32_dpp v235, v235, v235 quad_perm:[1,0,3,2] row_mask:0xf bank_mask:0xf bound_ctrl:1
	v_pk_mul_f32 v[204:205], v[240:241], v[36:37]
	v_pk_mul_f32 v[206:207], v[242:243], v[38:39]
	v_add_f32_dpp v235, v235, v235 quad_perm:[2,3,0,1] row_mask:0xf bank_mask:0xf bound_ctrl:1
	v_cvt_pk_f32_fp8_e32 v[240:241], v192
	v_cvt_pk_f32_fp8_sdwa v[242:243], v192 src0_sel:WORD_1
	v_add_f32_dpp v235, v235, v235 row_half_mirror row_mask:0xf bank_mask:0xf bound_ctrl:1
	v_pk_fma_f32 v[204:205], v[244:245], v[40:41], v[204:205]
	v_pk_fma_f32 v[206:207], v[202:203], v[42:43], v[206:207]
	s_add_i32 s0, s1, 28
	s_cmp_lt_i32 s0, s2
	s_cselect_b64 vcc, -1, 0
	v_cvt_pk_f32_fp8_e32 v[244:245], v193
	v_cvt_pk_f32_fp8_sdwa v[202:203], v193 src0_sel:WORD_1
	v_cndmask_b32_e32 v236, v220, v235, vcc
	v_pk_fma_f32 v[204:205], v[240:241], v[44:45], v[204:205]
	v_pk_fma_f32 v[206:207], v[242:243], v[46:47], v[206:207]
	v_pk_fma_f32 v[204:205], v[244:245], v[48:49], v[204:205]
	v_pk_fma_f32 v[206:207], v[202:203], v[50:51], v[206:207]
	v_readlane_b32 s0, v95, 29
	s_lshl_b32 s0, s0, 10
	s_add_u32 s4, s8, s0
	s_addc_u32 s5, s9, 0
	global_load_dwordx4 v[190:193], v16, s[4:5]
	v_pk_add_f32 v[204:205], v[204:205], v[206:207]
	s_nop 0
	v_add_f32_e32 v221, v204, v205
	s_waitcnt vmcnt(15)
	v_cvt_pk_f32_fp8_e32 v[240:241], v194
	v_cvt_pk_f32_fp8_sdwa v[242:243], v194 src0_sel:WORD_1
	v_cvt_pk_f32_fp8_e32 v[244:245], v195
	v_cvt_pk_f32_fp8_sdwa v[202:203], v195 src0_sel:WORD_1
	v_add_f32_dpp v221, v221, v221 quad_perm:[1,0,3,2] row_mask:0xf bank_mask:0xf bound_ctrl:1
	v_pk_mul_f32 v[204:205], v[240:241], v[36:37]
	v_pk_mul_f32 v[206:207], v[242:243], v[38:39]
	v_add_f32_dpp v221, v221, v221 quad_perm:[2,3,0,1] row_mask:0xf bank_mask:0xf bound_ctrl:1
	v_cvt_pk_f32_fp8_e32 v[240:241], v196
	v_cvt_pk_f32_fp8_sdwa v[242:243], v196 src0_sel:WORD_1
	v_add_f32_dpp v221, v221, v221 row_half_mirror row_mask:0xf bank_mask:0xf bound_ctrl:1
	v_pk_fma_f32 v[204:205], v[244:245], v[40:41], v[204:205]
	v_pk_fma_f32 v[206:207], v[202:203], v[42:43], v[206:207]
	s_add_i32 s0, s1, 29
	s_cmp_lt_i32 s0, s2
	s_cselect_b64 vcc, -1, 0
	v_cvt_pk_f32_fp8_e32 v[244:245], v197
	v_cvt_pk_f32_fp8_sdwa v[202:203], v197 src0_sel:WORD_1
	v_cndmask_b32_e32 v237, v220, v221, vcc
	v_pk_fma_f32 v[204:205], v[240:241], v[44:45], v[204:205]
	v_pk_fma_f32 v[206:207], v[242:243], v[46:47], v[206:207]
	v_pk_fma_f32 v[204:205], v[244:245], v[48:49], v[204:205]
	v_pk_fma_f32 v[206:207], v[202:203], v[50:51], v[206:207]
	v_readlane_b32 s0, v95, 30
	s_lshl_b32 s0, s0, 10
	s_add_u32 s4, s8, s0
	s_addc_u32 s5, s9, 0
	global_load_dwordx4 v[194:197], v16, s[4:5]
	v_pk_add_f32 v[204:205], v[204:205], v[206:207]
	s_nop 0
	v_add_f32_e32 v235, v204, v205
	s_waitcnt vmcnt(15)
	v_cvt_pk_f32_fp8_e32 v[240:241], v198
	v_cvt_pk_f32_fp8_sdwa v[242:243], v198 src0_sel:WORD_1
	v_cvt_pk_f32_fp8_e32 v[244:245], v199
	v_cvt_pk_f32_fp8_sdwa v[202:203], v199 src0_sel:WORD_1
	v_add_f32_dpp v235, v235, v235 quad_perm:[1,0,3,2] row_mask:0xf bank_mask:0xf bound_ctrl:1
	v_pk_mul_f32 v[204:205], v[240:241], v[36:37]
	v_pk_mul_f32 v[206:207], v[242:243], v[38:39]
	v_add_f32_dpp v235, v235, v235 quad_perm:[2,3,0,1] row_mask:0xf bank_mask:0xf bound_ctrl:1
	v_cvt_pk_f32_fp8_e32 v[240:241], v200
	v_cvt_pk_f32_fp8_sdwa v[242:243], v200 src0_sel:WORD_1
	v_add_f32_dpp v235, v235, v235 row_half_mirror row_mask:0xf bank_mask:0xf bound_ctrl:1
	v_pk_fma_f32 v[204:205], v[244:245], v[40:41], v[204:205]
	v_pk_fma_f32 v[206:207], v[202:203], v[42:43], v[206:207]
	s_add_i32 s0, s1, 30
	s_cmp_lt_i32 s0, s2
	s_cselect_b64 vcc, -1, 0
	v_cvt_pk_f32_fp8_e32 v[244:245], v201
	v_cvt_pk_f32_fp8_sdwa v[202:203], v201 src0_sel:WORD_1
	v_cndmask_b32_e32 v238, v220, v235, vcc
	v_pk_fma_f32 v[204:205], v[240:241], v[44:45], v[204:205]
	v_pk_fma_f32 v[206:207], v[242:243], v[46:47], v[206:207]
	v_pk_fma_f32 v[204:205], v[244:245], v[48:49], v[204:205]
	v_pk_fma_f32 v[206:207], v[202:203], v[50:51], v[206:207]
	v_readlane_b32 s0, v95, 31
	s_lshl_b32 s0, s0, 10
	s_add_u32 s4, s8, s0
	s_addc_u32 s5, s9, 0
	global_load_dwordx4 v[198:201], v16, s[4:5]
	v_pk_add_f32 v[204:205], v[204:205], v[206:207]
	s_nop 0
	v_add_f32_e32 v221, v204, v205
	s_nop 1
	v_add_f32_dpp v221, v221, v221 quad_perm:[1,0,3,2] row_mask:0xf bank_mask:0xf bound_ctrl:1
	s_nop 1
	v_add_f32_dpp v221, v221, v221 quad_perm:[2,3,0,1] row_mask:0xf bank_mask:0xf bound_ctrl:1
	s_nop 1
	v_add_f32_dpp v221, v221, v221 row_half_mirror row_mask:0xf bank_mask:0xf bound_ctrl:1
	s_add_i32 s0, s1, 31
	s_cmp_lt_i32 s0, s2
	s_cselect_b64 vcc, -1, 0
	s_nop 1
	v_cndmask_b32_e32 v239, v220, v221, vcc
	v_max3_f32 v224, v210, v211, v212
	v_max3_f32 v224, v224, v213, v226
	v_max3_f32 v224, v224, v227, v228
	v_max3_f32 v224, v224, v229, v230
	v_max3_f32 v224, v224, v231, v232
	v_max3_f32 v224, v224, v233, v236
	v_max3_f32 v224, v224, v237, v238
	v_max_f32_e32 v224, v224, v239
	v_max_f32_e32 v221, v216, v224
	v_sub_f32_e32 v184, v216, v221
	v_exp_f32_e32 v184, v184
	v_mov_b32_e32 v216, v221
	s_nop 0
	v_pk_mul_f32 v[12:13], v[12:13], v[184:185] op_sel_hi:[1,0]
	v_pk_mul_f32 v[14:15], v[14:15], v[184:185] op_sel_hi:[1,0]
	v_pk_mul_f32 v[8:9], v[8:9], v[184:185] op_sel_hi:[1,0]
	v_pk_mul_f32 v[10:11], v[10:11], v[184:185] op_sel_hi:[1,0]
	v_pk_mul_f32 v[4:5], v[4:5], v[184:185] op_sel_hi:[1,0]
	v_pk_mul_f32 v[6:7], v[6:7], v[184:185] op_sel_hi:[1,0]
	v_pk_mul_f32 v[0:1], v[0:1], v[184:185] op_sel_hi:[1,0]
	v_pk_mul_f32 v[2:3], v[2:3], v[184:185] op_sel_hi:[1,0]
	v_mul_f32_e32 v215, v215, v184
	v_sub_f32_e32 v210, v210, v216
	v_exp_f32_e32 v210, v210
	s_waitcnt vmcnt(15)
; DI void topk_phase(const bf16_t* PROJ, const unsigned char* K8, const unsigned char* V8, const unsigned short* SC, bf16_t* ODSA, int c, char* smem, int bid, int nb) {
;     ...
;         const float mn = fmaxf(m_run, da), al = __builtin_amdgcn_exp2f(m_run - mn), pp = __builtin_amdgcn_exp2f(da - mn);
;         m_run = mn; l_run = l_run * al + pp;
; #pragma unroll
;         for (int i = 0; i < 4; ++i) {
;           const f32x2v lo = __builtin_amdgcn_cvt_pk_f32_fp8((int)u[i], false), hi = __builtin_amdgcn_cvt_pk_f32_fp8((int)u[i], true);
;           ov[4 * i] = ov[4 * i] * al + pp * lo[0]; ov[4 * i + 1] = ov[4 * i + 1] * al + pp * lo[1];
;           ov[4 * i + 2] = ov[4 * i + 2] * al + pp * hi[0]; ov[4 * i + 3] = ov[4 * i + 3] * al + pp * hi[1];
;         }
	v_cvt_pk_f32_fp8_e32 v[240:241], v136
	v_cvt_pk_f32_fp8_sdwa v[242:243], v136 src0_sel:WORD_1
	v_cvt_pk_f32_fp8_e32 v[244:245], v137
	v_pk_fma_f32 v[12:13], v[240:241], v[210:211], v[12:13] op_sel_hi:[1,0,1]
	v_cvt_pk_f32_fp8_sdwa v[240:241], v137 src0_sel:WORD_1
	v_pk_fma_f32 v[14:15], v[242:243], v[210:211], v[14:15] op_sel_hi:[1,0,1]
	v_cvt_pk_f32_fp8_e32 v[242:243], v138
	v_sub_f32_e32 v211, v211, v216
	v_pk_fma_f32 v[8:9], v[244:245], v[210:211], v[8:9] op_sel_hi:[1,0,1]
	v_cvt_pk_f32_fp8_sdwa v[244:245], v138 src0_sel:WORD_1
	v_pk_fma_f32 v[10:11], v[240:241], v[210:211], v[10:11] op_sel_hi:[1,0,1]
	v_cvt_pk_f32_fp8_e32 v[240:241], v139
	v_exp_f32_e32 v211, v211
	v_pk_fma_f32 v[4:5], v[242:243], v[210:211], v[4:5] op_sel_hi:[1,0,1]
	v_cvt_pk_f32_fp8_sdwa v[242:243], v139 src0_sel:WORD_1
	v_pk_fma_f32 v[6:7], v[244:245], v[210:211], v[6:7] op_sel_hi:[1,0,1]
	v_add_f32_e32 v215, v215, v210
	v_pk_fma_f32 v[0:1], v[240:241], v[210:211], v[0:1] op_sel_hi:[1,0,1]
	v_pk_fma_f32 v[2:3], v[242:243], v[210:211], v[2:3] op_sel_hi:[1,0,1]
	v_readlane_b32 s0, v95, 32
	s_lshl_b32 s0, s0, 10
	s_add_u32 s4, s6, s0
	s_addc_u32 s5, s7, 0
	global_load_dwordx4 v[136:139], v16, s[4:5]
	s_waitcnt vmcnt(15)
	v_cvt_pk_f32_fp8_e32 v[240:241], v140
	v_cvt_pk_f32_fp8_sdwa v[242:243], v140 src0_sel:WORD_1
	v_cvt_pk_f32_fp8_e32 v[244:245], v141
	v_pk_fma_f32 v[12:13], v[240:241], v[210:211], v[12:13] op_sel:[0,1,0]
	v_cvt_pk_f32_fp8_sdwa v[240:241], v141 src0_sel:WORD_1
	v_pk_fma_f32 v[14:15], v[242:243], v[210:211], v[14:15] op_sel:[0,1,0]
	v_cvt_pk_f32_fp8_e32 v[242:243], v142
	v_sub_f32_e32 v212, v212, v216
	v_pk_fma_f32 v[8:9], v[244:245], v[210:211], v[8:9] op_sel:[0,1,0]
	v_cvt_pk_f32_fp8_sdwa v[244:245], v142 src0_sel:WORD_1
	v_pk_fma_f32 v[10:11], v[240:241], v[210:211], v[10:11] op_sel:[0,1,0]
	v_cvt_pk_f32_fp8_e32 v[240:241], v143
	v_exp_f32_e32 v212, v212
	v_pk_fma_f32 v[4:5], v[242:243], v[210:211], v[4:5] op_sel:[0,1,0]
	v_cvt_pk_f32_fp8_sdwa v[242:243], v143 src0_sel:WORD_1
	v_pk_fma_f32 v[6:7], v[244:245], v[210:211], v[6:7] op_sel:[0,1,0]
	v_add_f32_e32 v215, v215, v211
	v_pk_fma_f32 v[0:1], v[240:241], v[210:211], v[0:1] op_sel:[0,1,0]
	v_pk_fma_f32 v[2:3], v[242:243], v[210:211], v[2:3] op_sel:[0,1,0]
	v_readlane_b32 s0, v95, 33
	s_lshl_b32 s0, s0, 10
	s_add_u32 s4, s6, s0
	s_addc_u32 s5, s7, 0
	global_load_dwordx4 v[140:143], v16, s[4:5]
	s_waitcnt vmcnt(15)
	v_cvt_pk_f32_fp8_e32 v[240:241], v144
	v_cvt_pk_f32_fp8_sdwa v[242:243], v144 src0_sel:WORD_1
	v_cvt_pk_f32_fp8_e32 v[244:245], v145
	v_pk_fma_f32 v[12:13], v[240:241], v[212:213], v[12:13] op_sel_hi:[1,0,1]
	v_cvt_pk_f32_fp8_sdwa v[240:241], v145 src0_sel:WORD_1
	v_pk_fma_f32 v[14:15], v[242:243], v[212:213], v[14:15] op_sel_hi:[1,0,1]
	v_cvt_pk_f32_fp8_e32 v[242:243], v146
	v_sub_f32_e32 v213, v213, v216
	v_pk_fma_f32 v[8:9], v[244:245], v[212:213], v[8:9] op_sel_hi:[1,0,1]
	v_cvt_pk_f32_fp8_sdwa v[244:245], v146 src0_sel:WORD_1
	v_pk_fma_f32 v[10:11], v[240:241], v[212:213], v[10:11] op_sel_hi:[1,0,1]
	v_cvt_pk_f32_fp8_e32 v[240:241], v147
	v_exp_f32_e32 v213, v213
	v_pk_fma_f32 v[4:5], v[242:243], v[212:213], v[4:5] op_sel_hi:[1,0,1]
	v_cvt_pk_f32_fp8_sdwa v[242:243], v147 src0_sel:WORD_1
	v_pk_fma_f32 v[6:7], v[244:245], v[212:213], v[6:7] op_sel_hi:[1,0,1]
	v_add_f32_e32 v215, v215, v212
	v_pk_fma_f32 v[0:1], v[240:241], v[212:213], v[0:1] op_sel_hi:[1,0,1]
	v_pk_fma_f32 v[2:3], v[242:243], v[212:213], v[2:3] op_sel_hi:[1,0,1]
	v_readlane_b32 s0, v95, 34
	s_lshl_b32 s0, s0, 10
	s_add_u32 s4, s6, s0
	s_addc_u32 s5, s7, 0
	global_load_dwordx4 v[144:147], v16, s[4:5]
	s_waitcnt vmcnt(15)
	v_cvt_pk_f32_fp8_e32 v[240:241], v148
	v_cvt_pk_f32_fp8_sdwa v[242:243], v148 src0_sel:WORD_1
	v_cvt_pk_f32_fp8_e32 v[244:245], v149
	v_pk_fma_f32 v[12:13], v[240:241], v[212:213], v[12:13] op_sel:[0,1,0]
	v_cvt_pk_f32_fp8_sdwa v[240:241], v149 src0_sel:WORD_1
	v_pk_fma_f32 v[14:15], v[242:243], v[212:213], v[14:15] op_sel:[0,1,0]
	v_cvt_pk_f32_fp8_e32 v[242:243], v150
	v_sub_f32_e32 v226, v226, v216
	v_pk_fma_f32 v[8:9], v[244:245], v[212:213], v[8:9] op_sel:[0,1,0]
	v_cvt_pk_f32_fp8_sdwa v[244:245], v150 src0_sel:WORD_1
	v_pk_fma_f32 v[10:11], v[240:241], v[212:213], v[10:11] op_sel:[0,1,0]
	v_cvt_pk_f32_fp8_e32 v[240:241], v151
	v_exp_f32_e32 v226, v226
	v_pk_fma_f32 v[4:5], v[242:243], v[212:213], v[4:5] op_sel:[0,1,0]
	v_cvt_pk_f32_fp8_sdwa v[242:243], v151 src0_sel:WORD_1
	v_pk_fma_f32 v[6:7], v[244:245], v[212:213], v[6:7] op_sel:[0,1,0]
	v_add_f32_e32 v215, v215, v213
	v_pk_fma_f32 v[0:1], v[240:241], v[212:213], v[0:1] op_sel:[0,1,0]
	v_pk_fma_f32 v[2:3], v[242:243], v[212:213], v[2:3] op_sel:[0,1,0]
	v_readlane_b32 s0, v95, 35
	s_lshl_b32 s0, s0, 10
	s_add_u32 s4, s6, s0
	s_addc_u32 s5, s7, 0
	global_load_dwordx4 v[148:151], v16, s[4:5]
	s_waitcnt vmcnt(15)
	v_cvt_pk_f32_fp8_e32 v[240:241], v152
	v_cvt_pk_f32_fp8_sdwa v[242:243], v152 src0_sel:WORD_1
	v_cvt_pk_f32_fp8_e32 v[244:245], v153
	v_pk_fma_f32 v[12:13], v[240:241], v[226:227], v[12:13] op_sel_hi:[1,0,1]
	v_cvt_pk_f32_fp8_sdwa v[240:241], v153 src0_sel:WORD_1
	v_pk_fma_f32 v[14:15], v[242:243], v[226:227], v[14:15] op_sel_hi:[1,0,1]
	v_cvt_pk_f32_fp8_e32 v[242:243], v154
	v_sub_f32_e32 v227, v227, v216
	v_pk_fma_f32 v[8:9], v[244:245], v[226:227], v[8:9] op_sel_hi:[1,0,1]
	v_cvt_pk_f32_fp8_sdwa v[244:245], v154 src0_sel:WORD_1
	v_pk_fma_f32 v[10:11], v[240:241], v[226:227], v[10:11] op_sel_hi:[1,0,1]
	v_cvt_pk_f32_fp8_e32 v[240:241], v155
	v_exp_f32_e32 v227, v227
	v_pk_fma_f32 v[4:5], v[242:243], v[226:227], v[4:5] op_sel_hi:[1,0,1]
	v_cvt_pk_f32_fp8_sdwa v[242:243], v155 src0_sel:WORD_1
	v_pk_fma_f32 v[6:7], v[244:245], v[226:227], v[6:7] op_sel_hi:[1,0,1]
	v_add_f32_e32 v215, v215, v226
	v_pk_fma_f32 v[0:1], v[240:241], v[226:227], v[0:1] op_sel_hi:[1,0,1]
	v_pk_fma_f32 v[2:3], v[242:243], v[226:227], v[2:3] op_sel_hi:[1,0,1]
	v_readlane_b32 s0, v95, 36
	s_lshl_b32 s0, s0, 10
	s_add_u32 s4, s6, s0
	s_addc_u32 s5, s7, 0
	global_load_dwordx4 v[152:155], v16, s[4:5]
	s_waitcnt vmcnt(15)
; DI void topk_phase(const bf16_t* PROJ, const unsigned char* K8, const unsigned char* V8, const unsigned short* SC, bf16_t* ODSA, int c, char* smem, int bid, int nb) {
;     ...
;         const float mn = fmaxf(m_run, da), al = __builtin_amdgcn_exp2f(m_run - mn), pp = __builtin_amdgcn_exp2f(da - mn);
;         m_run = mn; l_run = l_run * al + pp;
; #pragma unroll
;         for (int i = 0; i < 4; ++i) {
;           const f32x2v lo = __builtin_amdgcn_cvt_pk_f32_fp8((int)u[i], false), hi = __builtin_amdgcn_cvt_pk_f32_fp8((int)u[i], true);
;           ov[4 * i] = ov[4 * i] * al + pp * lo[0]; ov[4 * i + 1] = ov[4 * i + 1] * al + pp * lo[1];
;           ov[4 * i + 2] = ov[4 * i + 2] * al + pp * hi[0]; ov[4 * i + 3] = ov[4 * i + 3] * al + pp * hi[1];
;         }
	v_cvt_pk_f32_fp8_e32 v[240:241], v156
	v_cvt_pk_f32_fp8_sdwa v[242:243], v156 src0_sel:WORD_1
	v_cvt_pk_f32_fp8_e32 v[244:245], v157
	v_pk_fma_f32 v[12:13], v[240:241], v[226:227], v[12:13] op_sel:[0,1,0]
	v_cvt_pk_f32_fp8_sdwa v[240:241], v157 src0_sel:WORD_1
	v_pk_fma_f32 v[14:15], v[242:243], v[226:227], v[14:15] op_sel:[0,1,0]
	v_cvt_pk_f32_fp8_e32 v[242:243], v158
	v_sub_f32_e32 v228, v228, v216
	v_pk_fma_f32 v[8:9], v[244:245], v[226:227], v[8:9] op_sel:[0,1,0]
	v_cvt_pk_f32_fp8_sdwa v[244:245], v158 src0_sel:WORD_1
	v_pk_fma_f32 v[10:11], v[240:241], v[226:227], v[10:11] op_sel:[0,1,0]
	v_cvt_pk_f32_fp8_e32 v[240:241], v159
	v_exp_f32_e32 v228, v228
	v_pk_fma_f32 v[4:5], v[242:243], v[226:227], v[4:5] op_sel:[0,1,0]
	v_cvt_pk_f32_fp8_sdwa v[242:243], v159 src0_sel:WORD_1
	v_pk_fma_f32 v[6:7], v[244:245], v[226:227], v[6:7] op_sel:[0,1,0]
	v_add_f32_e32 v215, v215, v227
	v_pk_fma_f32 v[0:1], v[240:241], v[226:227], v[0:1] op_sel:[0,1,0]
	v_pk_fma_f32 v[2:3], v[242:243], v[226:227], v[2:3] op_sel:[0,1,0]
	v_readlane_b32 s0, v95, 37
	s_lshl_b32 s0, s0, 10
	s_add_u32 s4, s6, s0
	s_addc_u32 s5, s7, 0
	global_load_dwordx4 v[156:159], v16, s[4:5]
	s_waitcnt vmcnt(15)
	v_cvt_pk_f32_fp8_e32 v[240:241], v160
	v_cvt_pk_f32_fp8_sdwa v[242:243], v160 src0_sel:WORD_1
	v_cvt_pk_f32_fp8_e32 v[244:245], v161
	v_pk_fma_f32 v[12:13], v[240:241], v[228:229], v[12:13] op_sel_hi:[1,0,1]
	v_cvt_pk_f32_fp8_sdwa v[240:241], v161 src0_sel:WORD_1
	v_pk_fma_f32 v[14:15], v[242:243], v[228:229], v[14:15] op_sel_hi:[1,0,1]
	v_cvt_pk_f32_fp8_e32 v[242:243], v162
	v_sub_f32_e32 v229, v229, v216
	v_pk_fma_f32 v[8:9], v[244:245], v[228:229], v[8:9] op_sel_hi:[1,0,1]
	v_cvt_pk_f32_fp8_sdwa v[244:245], v162 src0_sel:WORD_1
	v_pk_fma_f32 v[10:11], v[240:241], v[228:229], v[10:11] op_sel_hi:[1,0,1]
	v_cvt_pk_f32_fp8_e32 v[240:241], v163
	v_exp_f32_e32 v229, v229
	v_pk_fma_f32 v[4:5], v[242:243], v[228:229], v[4:5] op_sel_hi:[1,0,1]
	v_cvt_pk_f32_fp8_sdwa v[242:243], v163 src0_sel:WORD_1
	v_pk_fma_f32 v[6:7], v[244:245], v[228:229], v[6:7] op_sel_hi:[1,0,1]
	v_add_f32_e32 v215, v215, v228
	v_pk_fma_f32 v[0:1], v[240:241], v[228:229], v[0:1] op_sel_hi:[1,0,1]
	v_pk_fma_f32 v[2:3], v[242:243], v[228:229], v[2:3] op_sel_hi:[1,0,1]
	v_readlane_b32 s0, v95, 38
	s_lshl_b32 s0, s0, 10
	s_add_u32 s4, s6, s0
	s_addc_u32 s5, s7, 0
	global_load_dwordx4 v[160:163], v16, s[4:5]
	s_waitcnt vmcnt(15)
	v_cvt_pk_f32_fp8_e32 v[240:241], v164
	v_cvt_pk_f32_fp8_sdwa v[242:243], v164 src0_sel:WORD_1
	v_cvt_pk_f32_fp8_e32 v[244:245], v165
	v_pk_fma_f32 v[12:13], v[240:241], v[228:229], v[12:13] op_sel:[0,1,0]
	v_cvt_pk_f32_fp8_sdwa v[240:241], v165 src0_sel:WORD_1
	v_pk_fma_f32 v[14:15], v[242:243], v[228:229], v[14:15] op_sel:[0,1,0]
	v_cvt_pk_f32_fp8_e32 v[242:243], v166
	v_sub_f32_e32 v230, v230, v216
	v_pk_fma_f32 v[8:9], v[244:245], v[228:229], v[8:9] op_sel:[0,1,0]
	v_cvt_pk_f32_fp8_sdwa v[244:245], v166 src0_sel:WORD_1
	v_pk_fma_f32 v[10:11], v[240:241], v[228:229], v[10:11] op_sel:[0,1,0]
	v_cvt_pk_f32_fp8_e32 v[240:241], v167
	v_exp_f32_e32 v230, v230
	v_pk_fma_f32 v[4:5], v[242:243], v[228:229], v[4:5] op_sel:[0,1,0]
	v_cvt_pk_f32_fp8_sdwa v[242:243], v167 src0_sel:WORD_1
	v_pk_fma_f32 v[6:7], v[244:245], v[228:229], v[6:7] op_sel:[0,1,0]
	v_add_f32_e32 v215, v215, v229
	v_pk_fma_f32 v[0:1], v[240:241], v[228:229], v[0:1] op_sel:[0,1,0]
	v_pk_fma_f32 v[2:3], v[242:243], v[228:229], v[2:3] op_sel:[0,1,0]
	v_readlane_b32 s0, v95, 39
	s_lshl_b32 s0, s0, 10
	s_add_u32 s4, s6, s0
	s_addc_u32 s5, s7, 0
	global_load_dwordx4 v[164:167], v16, s[4:5]
	s_waitcnt vmcnt(15)
	v_cvt_pk_f32_fp8_e32 v[240:241], v168
	v_cvt_pk_f32_fp8_sdwa v[242:243], v168 src0_sel:WORD_1
	v_cvt_pk_f32_fp8_e32 v[244:245], v169
	v_pk_fma_f32 v[12:13], v[240:241], v[230:231], v[12:13] op_sel_hi:[1,0,1]
	v_cvt_pk_f32_fp8_sdwa v[240:241], v169 src0_sel:WORD_1
	v_pk_fma_f32 v[14:15], v[242:243], v[230:231], v[14:15] op_sel_hi:[1,0,1]
	v_cvt_pk_f32_fp8_e32 v[242:243], v170
	v_sub_f32_e32 v231, v231, v216
	v_pk_fma_f32 v[8:9], v[244:245], v[230:231], v[8:9] op_sel_hi:[1,0,1]
	v_cvt_pk_f32_fp8_sdwa v[244:245], v170 src0_sel:WORD_1
	v_pk_fma_f32 v[10:11], v[240:241], v[230:231], v[10:11] op_sel_hi:[1,0,1]
	v_cvt_pk_f32_fp8_e32 v[240:241], v171
	v_exp_f32_e32 v231, v231
	v_pk_fma_f32 v[4:5], v[242:243], v[230:231], v[4:5] op_sel_hi:[1,0,1]
	v_cvt_pk_f32_fp8_sdwa v[242:243], v171 src0_sel:WORD_1
	v_pk_fma_f32 v[6:7], v[244:245], v[230:231], v[6:7] op_sel_hi:[1,0,1]
	v_add_f32_e32 v215, v215, v230
	v_pk_fma_f32 v[0:1], v[240:241], v[230:231], v[0:1] op_sel_hi:[1,0,1]
	v_pk_fma_f32 v[2:3], v[242:243], v[230:231], v[2:3] op_sel_hi:[1,0,1]
	v_readlane_b32 s0, v95, 40
	s_lshl_b32 s0, s0, 10
	s_add_u32 s4, s6, s0
	s_addc_u32 s5, s7, 0
	global_load_dwordx4 v[168:171], v16, s[4:5]
	s_waitcnt vmcnt(15)
	v_cvt_pk_f32_fp8_e32 v[240:241], v172
	v_cvt_pk_f32_fp8_sdwa v[242:243], v172 src0_sel:WORD_1
	v_cvt_pk_f32_fp8_e32 v[244:245], v173
	v_pk_fma_f32 v[12:13], v[240:241], v[230:231], v[12:13] op_sel:[0,1,0]
	v_cvt_pk_f32_fp8_sdwa v[240:241], v173 src0_sel:WORD_1
	v_pk_fma_f32 v[14:15], v[242:243], v[230:231], v[14:15] op_sel:[0,1,0]
	v_cvt_pk_f32_fp8_e32 v[242:243], v174
	v_sub_f32_e32 v232, v232, v216
	v_pk_fma_f32 v[8:9], v[244:245], v[230:231], v[8:9] op_sel:[0,1,0]
	v_cvt_pk_f32_fp8_sdwa v[244:245], v174 src0_sel:WORD_1
	v_pk_fma_f32 v[10:11], v[240:241], v[230:231], v[10:11] op_sel:[0,1,0]
	v_cvt_pk_f32_fp8_e32 v[240:241], v175
	v_exp_f32_e32 v232, v232
	v_pk_fma_f32 v[4:5], v[242:243], v[230:231], v[4:5] op_sel:[0,1,0]
	v_cvt_pk_f32_fp8_sdwa v[242:243], v175 src0_sel:WORD_1
	v_pk_fma_f32 v[6:7], v[244:245], v[230:231], v[6:7] op_sel:[0,1,0]
	v_add_f32_e32 v215, v215, v231
	v_pk_fma_f32 v[0:1], v[240:241], v[230:231], v[0:1] op_sel:[0,1,0]
	v_pk_fma_f32 v[2:3], v[242:243], v[230:231], v[2:3] op_sel:[0,1,0]
	v_readlane_b32 s0, v95, 41
	s_lshl_b32 s0, s0, 10
	s_add_u32 s4, s6, s0
	s_addc_u32 s5, s7, 0
	global_load_dwordx4 v[172:175], v16, s[4:5]
	s_waitcnt vmcnt(15)
; DI float sum8(float v) { v += DPPF(v, 0xB1); v += DPPF(v, 0x4E); v += DPPF(v, 0x141); return v; }
; DI void topk_phase(const bf16_t* PROJ, const unsigned char* K8, const unsigned char* V8, const unsigned short* SC, bf16_t* ODSA, int c, char* smem, int bid, int nb) {
;     ...
; #pragma unroll 4
;     for (int jj = 0; jj < 64; ++jj) {
;       const int j = wid * 64 + jj;
;       {
;         const size_t ro = (size_t)__builtin_amdgcn_readlane(mysel, jj) * 1024 + lane * 16;
;         const uint4 a = *(const uint4*)(K8 + ro), vv = *(const uint4*)(V8 + ro);
;         const unsigned w[4] = {a.x, a.y, a.z, a.w}, u[4] = {vv.x, vv.y, vv.z, vv.w};
;         float da = 0.f;
; #pragma unroll
;         for (int i = 0; i < 4; ++i) {
;           const f32x2v lo = __builtin_amdgcn_cvt_pk_f32_fp8((int)w[i], false), hi = __builtin_amdgcn_cvt_pk_f32_fp8((int)w[i], true);
;           da += qv[4 * i] * lo[0] + qv[4 * i + 1] * lo[1] + qv[4 * i + 2] * hi[0] + qv[4 * i + 3] * hi[1];
;         }
;         da = sum8(da);
;         da = j < count ? da : -3e30f;
;         const float mn = fmaxf(m_run, da), al = __builtin_amdgcn_exp2f(m_run - mn), pp = __builtin_amdgcn_exp2f(da - mn);
;         m_run = mn; l_run = l_run * al + pp;
; #pragma unroll
;         for (int i = 0; i < 4; ++i) {
;           const f32x2v lo = __builtin_amdgcn_cvt_pk_f32_fp8((int)u[i], false), hi = __builtin_amdgcn_cvt_pk_f32_fp8((int)u[i], true);
;           ov[4 * i] = ov[4 * i] * al + pp * lo[0]; ov[4 * i + 1] = ov[4 * i + 1] * al + pp * lo[1];
;           ov[4 * i + 2] = ov[4 * i + 2] * al + pp * hi[0]; ov[4 * i + 3] = ov[4 * i + 3] * al + pp * hi[1];
;         }
;       }
;     }
	v_cvt_pk_f32_fp8_e32 v[240:241], v176
	v_cvt_pk_f32_fp8_sdwa v[242:243], v176 src0_sel:WORD_1
	v_cvt_pk_f32_fp8_e32 v[244:245], v177
	v_pk_fma_f32 v[12:13], v[240:241], v[232:233], v[12:13] op_sel_hi:[1,0,1]
	v_cvt_pk_f32_fp8_sdwa v[240:241], v177 src0_sel:WORD_1
	v_pk_fma_f32 v[14:15], v[242:243], v[232:233], v[14:15] op_sel_hi:[1,0,1]
	v_cvt_pk_f32_fp8_e32 v[242:243], v178
	v_sub_f32_e32 v233, v233, v216
	v_pk_fma_f32 v[8:9], v[244:245], v[232:233], v[8:9] op_sel_hi:[1,0,1]
	v_cvt_pk_f32_fp8_sdwa v[244:245], v178 src0_sel:WORD_1
	v_pk_fma_f32 v[10:11], v[240:241], v[232:233], v[10:11] op_sel_hi:[1,0,1]
	v_cvt_pk_f32_fp8_e32 v[240:241], v179
	v_exp_f32_e32 v233, v233
	v_pk_fma_f32 v[4:5], v[242:243], v[232:233], v[4:5] op_sel_hi:[1,0,1]
	v_cvt_pk_f32_fp8_sdwa v[242:243], v179 src0_sel:WORD_1
	v_pk_fma_f32 v[6:7], v[244:245], v[232:233], v[6:7] op_sel_hi:[1,0,1]
	v_add_f32_e32 v215, v215, v232
	v_pk_fma_f32 v[0:1], v[240:241], v[232:233], v[0:1] op_sel_hi:[1,0,1]
	v_pk_fma_f32 v[2:3], v[242:243], v[232:233], v[2:3] op_sel_hi:[1,0,1]
	v_readlane_b32 s0, v95, 42
	s_lshl_b32 s0, s0, 10
	s_add_u32 s4, s6, s0
	s_addc_u32 s5, s7, 0
	global_load_dwordx4 v[176:179], v16, s[4:5]
	s_waitcnt vmcnt(15)
	v_cvt_pk_f32_fp8_e32 v[240:241], v180
	v_cvt_pk_f32_fp8_sdwa v[242:243], v180 src0_sel:WORD_1
	v_cvt_pk_f32_fp8_e32 v[244:245], v181
	v_pk_fma_f32 v[12:13], v[240:241], v[232:233], v[12:13] op_sel:[0,1,0]
	v_cvt_pk_f32_fp8_sdwa v[240:241], v181 src0_sel:WORD_1
	v_pk_fma_f32 v[14:15], v[242:243], v[232:233], v[14:15] op_sel:[0,1,0]
	v_cvt_pk_f32_fp8_e32 v[242:243], v182
	v_sub_f32_e32 v236, v236, v216
	v_pk_fma_f32 v[8:9], v[244:245], v[232:233], v[8:9] op_sel:[0,1,0]
	v_cvt_pk_f32_fp8_sdwa v[244:245], v182 src0_sel:WORD_1
	v_pk_fma_f32 v[10:11], v[240:241], v[232:233], v[10:11] op_sel:[0,1,0]
	v_cvt_pk_f32_fp8_e32 v[240:241], v183
	v_exp_f32_e32 v236, v236
	v_pk_fma_f32 v[4:5], v[242:243], v[232:233], v[4:5] op_sel:[0,1,0]
	v_cvt_pk_f32_fp8_sdwa v[242:243], v183 src0_sel:WORD_1
	v_pk_fma_f32 v[6:7], v[244:245], v[232:233], v[6:7] op_sel:[0,1,0]
	v_add_f32_e32 v215, v215, v233
	v_pk_fma_f32 v[0:1], v[240:241], v[232:233], v[0:1] op_sel:[0,1,0]
	v_pk_fma_f32 v[2:3], v[242:243], v[232:233], v[2:3] op_sel:[0,1,0]
	v_readlane_b32 s0, v95, 43
	s_lshl_b32 s0, s0, 10
	s_add_u32 s4, s6, s0
	s_addc_u32 s5, s7, 0
	global_load_dwordx4 v[180:183], v16, s[4:5]
	s_waitcnt vmcnt(15)
	v_cvt_pk_f32_fp8_e32 v[240:241], v186
	v_cvt_pk_f32_fp8_sdwa v[242:243], v186 src0_sel:WORD_1
	v_cvt_pk_f32_fp8_e32 v[244:245], v187
	v_pk_fma_f32 v[12:13], v[240:241], v[236:237], v[12:13] op_sel_hi:[1,0,1]
	v_cvt_pk_f32_fp8_sdwa v[240:241], v187 src0_sel:WORD_1
	v_pk_fma_f32 v[14:15], v[242:243], v[236:237], v[14:15] op_sel_hi:[1,0,1]
	v_cvt_pk_f32_fp8_e32 v[242:243], v188
	v_sub_f32_e32 v237, v237, v216
	v_pk_fma_f32 v[8:9], v[244:245], v[236:237], v[8:9] op_sel_hi:[1,0,1]
	v_cvt_pk_f32_fp8_sdwa v[244:245], v188 src0_sel:WORD_1
	v_pk_fma_f32 v[10:11], v[240:241], v[236:237], v[10:11] op_sel_hi:[1,0,1]
	v_cvt_pk_f32_fp8_e32 v[240:241], v189
	v_exp_f32_e32 v237, v237
	v_pk_fma_f32 v[4:5], v[242:243], v[236:237], v[4:5] op_sel_hi:[1,0,1]
	v_cvt_pk_f32_fp8_sdwa v[242:243], v189 src0_sel:WORD_1
	v_pk_fma_f32 v[6:7], v[244:245], v[236:237], v[6:7] op_sel_hi:[1,0,1]
	v_add_f32_e32 v215, v215, v236
	v_pk_fma_f32 v[0:1], v[240:241], v[236:237], v[0:1] op_sel_hi:[1,0,1]
	v_pk_fma_f32 v[2:3], v[242:243], v[236:237], v[2:3] op_sel_hi:[1,0,1]
	v_readlane_b32 s0, v95, 44
	s_lshl_b32 s0, s0, 10
	s_add_u32 s4, s6, s0
	s_addc_u32 s5, s7, 0
	global_load_dwordx4 v[186:189], v16, s[4:5]
	s_waitcnt vmcnt(15)
	v_cvt_pk_f32_fp8_e32 v[240:241], v190
	v_cvt_pk_f32_fp8_sdwa v[242:243], v190 src0_sel:WORD_1
	v_cvt_pk_f32_fp8_e32 v[244:245], v191
	v_pk_fma_f32 v[12:13], v[240:241], v[236:237], v[12:13] op_sel:[0,1,0]
	v_cvt_pk_f32_fp8_sdwa v[240:241], v191 src0_sel:WORD_1
	v_pk_fma_f32 v[14:15], v[242:243], v[236:237], v[14:15] op_sel:[0,1,0]
	v_cvt_pk_f32_fp8_e32 v[242:243], v192
	v_sub_f32_e32 v238, v238, v216
	v_pk_fma_f32 v[8:9], v[244:245], v[236:237], v[8:9] op_sel:[0,1,0]
	v_cvt_pk_f32_fp8_sdwa v[244:245], v192 src0_sel:WORD_1
	v_pk_fma_f32 v[10:11], v[240:241], v[236:237], v[10:11] op_sel:[0,1,0]
	v_cvt_pk_f32_fp8_e32 v[240:241], v193
	v_exp_f32_e32 v238, v238
	v_pk_fma_f32 v[4:5], v[242:243], v[236:237], v[4:5] op_sel:[0,1,0]
	v_cvt_pk_f32_fp8_sdwa v[242:243], v193 src0_sel:WORD_1
	v_pk_fma_f32 v[6:7], v[244:245], v[236:237], v[6:7] op_sel:[0,1,0]
	v_add_f32_e32 v215, v215, v237
	v_pk_fma_f32 v[0:1], v[240:241], v[236:237], v[0:1] op_sel:[0,1,0]
	v_pk_fma_f32 v[2:3], v[242:243], v[236:237], v[2:3] op_sel:[0,1,0]
	v_readlane_b32 s0, v95, 45
	s_lshl_b32 s0, s0, 10
	s_add_u32 s4, s6, s0
	s_addc_u32 s5, s7, 0
	global_load_dwordx4 v[190:193], v16, s[4:5]
	s_waitcnt vmcnt(15)
	v_cvt_pk_f32_fp8_e32 v[240:241], v194
	v_cvt_pk_f32_fp8_sdwa v[242:243], v194 src0_sel:WORD_1
	v_cvt_pk_f32_fp8_e32 v[244:245], v195
	v_pk_fma_f32 v[12:13], v[240:241], v[238:239], v[12:13] op_sel_hi:[1,0,1]
	v_cvt_pk_f32_fp8_sdwa v[240:241], v195 src0_sel:WORD_1
	v_pk_fma_f32 v[14:15], v[242:243], v[238:239], v[14:15] op_sel_hi:[1,0,1]
	v_cvt_pk_f32_fp8_e32 v[242:243], v196
	v_sub_f32_e32 v239, v239, v216
	v_pk_fma_f32 v[8:9], v[244:245], v[238:239], v[8:9] op_sel_hi:[1,0,1]
	v_cvt_pk_f32_fp8_sdwa v[244:245], v196 src0_sel:WORD_1
	v_pk_fma_f32 v[10:11], v[240:241], v[238:239], v[10:11] op_sel_hi:[1,0,1]
	v_cvt_pk_f32_fp8_e32 v[240:241], v197
	v_exp_f32_e32 v239, v239
	v_pk_fma_f32 v[4:5], v[242:243], v[238:239], v[4:5] op_sel_hi:[1,0,1]
	v_cvt_pk_f32_fp8_sdwa v[242:243], v197 src0_sel:WORD_1
	v_pk_fma_f32 v[6:7], v[244:245], v[238:239], v[6:7] op_sel_hi:[1,0,1]
	v_add_f32_e32 v215, v215, v238
	v_pk_fma_f32 v[0:1], v[240:241], v[238:239], v[0:1] op_sel_hi:[1,0,1]
	v_pk_fma_f32 v[2:3], v[242:243], v[238:239], v[2:3] op_sel_hi:[1,0,1]
	v_readlane_b32 s0, v95, 46
	s_lshl_b32 s0, s0, 10
	s_add_u32 s4, s6, s0
	s_addc_u32 s5, s7, 0
	global_load_dwordx4 v[194:197], v16, s[4:5]
	s_waitcnt vmcnt(15)
; DI float sum8(float v) { v += DPPF(v, 0xB1); v += DPPF(v, 0x4E); v += DPPF(v, 0x141); return v; }
; DI void topk_phase(const bf16_t* PROJ, const unsigned char* K8, const unsigned char* V8, const unsigned short* SC, bf16_t* ODSA, int c, char* smem, int bid, int nb) {
;     ...
; #pragma unroll 4
;     for (int jj = 0; jj < 64; ++jj) {
;       const int j = wid * 64 + jj;
;       {
;         const size_t ro = (size_t)__builtin_amdgcn_readlane(mysel, jj) * 1024 + lane * 16;
;         const uint4 a = *(const uint4*)(K8 + ro), vv = *(const uint4*)(V8 + ro);
;         const unsigned w[4] = {a.x, a.y, a.z, a.w}, u[4] = {vv.x, vv.y, vv.z, vv.w};
;         float da = 0.f;
; #pragma unroll
;         for (int i = 0; i < 4; ++i) {
;           const f32x2v lo = __builtin_amdgcn_cvt_pk_f32_fp8((int)w[i], false), hi = __builtin_amdgcn_cvt_pk_f32_fp8((int)w[i], true);
;           da += qv[4 * i] * lo[0] + qv[4 * i + 1] * lo[1] + qv[4 * i + 2] * hi[0] + qv[4 * i + 3] * hi[1];
;         }
;         da = sum8(da);
;         da = j < count ? da : -3e30f;
;         const float mn = fmaxf(m_run, da), al = __builtin_amdgcn_exp2f(m_run - mn), pp = __builtin_amdgcn_exp2f(da - mn);
	v_cvt_pk_f32_fp8_e32 v[240:241], v198
	v_cvt_pk_f32_fp8_sdwa v[242:243], v198 src0_sel:WORD_1
	v_cvt_pk_f32_fp8_e32 v[244:245], v199
	v_pk_fma_f32 v[12:13], v[240:241], v[238:239], v[12:13] op_sel:[0,1,0]
	v_cvt_pk_f32_fp8_sdwa v[240:241], v199 src0_sel:WORD_1
	v_pk_fma_f32 v[14:15], v[242:243], v[238:239], v[14:15] op_sel:[0,1,0]
	v_cvt_pk_f32_fp8_e32 v[242:243], v200
	v_add_f32_e32 v215, v215, v239
	v_pk_fma_f32 v[8:9], v[244:245], v[238:239], v[8:9] op_sel:[0,1,0]
	v_cvt_pk_f32_fp8_sdwa v[244:245], v200 src0_sel:WORD_1
	v_pk_fma_f32 v[10:11], v[240:241], v[238:239], v[10:11] op_sel:[0,1,0]
	v_cvt_pk_f32_fp8_e32 v[240:241], v201
	v_pk_fma_f32 v[4:5], v[242:243], v[238:239], v[4:5] op_sel:[0,1,0]
	v_cvt_pk_f32_fp8_sdwa v[242:243], v201 src0_sel:WORD_1
	v_pk_fma_f32 v[6:7], v[244:245], v[238:239], v[6:7] op_sel:[0,1,0]
	v_pk_fma_f32 v[0:1], v[240:241], v[238:239], v[0:1] op_sel:[0,1,0]
	v_pk_fma_f32 v[2:3], v[242:243], v[238:239], v[2:3] op_sel:[0,1,0]
	v_readlane_b32 s0, v95, 47
	s_lshl_b32 s0, s0, 10
	s_add_u32 s4, s6, s0
	s_addc_u32 s5, s7, 0
	global_load_dwordx4 v[198:201], v16, s[4:5]
	s_waitcnt vmcnt(15)
	v_cvt_pk_f32_fp8_e32 v[240:241], v136
	v_cvt_pk_f32_fp8_sdwa v[242:243], v136 src0_sel:WORD_1
	v_cvt_pk_f32_fp8_e32 v[244:245], v137
	v_cvt_pk_f32_fp8_sdwa v[202:203], v137 src0_sel:WORD_1
	v_pk_mul_f32 v[204:205], v[240:241], v[36:37]
	v_pk_mul_f32 v[206:207], v[242:243], v[38:39]
	v_cvt_pk_f32_fp8_e32 v[240:241], v138
	v_cvt_pk_f32_fp8_sdwa v[242:243], v138 src0_sel:WORD_1
	v_pk_fma_f32 v[204:205], v[244:245], v[40:41], v[204:205]
	v_pk_fma_f32 v[206:207], v[202:203], v[42:43], v[206:207]
	v_cvt_pk_f32_fp8_e32 v[244:245], v139
	v_cvt_pk_f32_fp8_sdwa v[202:203], v139 src0_sel:WORD_1
	v_pk_fma_f32 v[204:205], v[240:241], v[44:45], v[204:205]
	v_pk_fma_f32 v[206:207], v[242:243], v[46:47], v[206:207]
	v_pk_fma_f32 v[204:205], v[244:245], v[48:49], v[204:205]
	v_pk_fma_f32 v[206:207], v[202:203], v[50:51], v[206:207]
	v_readlane_b32 s0, v95, 32
	s_lshl_b32 s0, s0, 10
	s_add_u32 s4, s8, s0
	s_addc_u32 s5, s9, 0
	global_load_dwordx4 v[136:139], v16, s[4:5]
	v_pk_add_f32 v[204:205], v[204:205], v[206:207]
	s_nop 0
	v_add_f32_e32 v235, v204, v205
	s_waitcnt vmcnt(15)
	v_cvt_pk_f32_fp8_e32 v[240:241], v140
	v_cvt_pk_f32_fp8_sdwa v[242:243], v140 src0_sel:WORD_1
	v_cvt_pk_f32_fp8_e32 v[244:245], v141
	v_cvt_pk_f32_fp8_sdwa v[202:203], v141 src0_sel:WORD_1
	v_add_f32_dpp v235, v235, v235 quad_perm:[1,0,3,2] row_mask:0xf bank_mask:0xf bound_ctrl:1
	v_pk_mul_f32 v[204:205], v[240:241], v[36:37]
	v_pk_mul_f32 v[206:207], v[242:243], v[38:39]
	v_add_f32_dpp v235, v235, v235 quad_perm:[2,3,0,1] row_mask:0xf bank_mask:0xf bound_ctrl:1
	v_cvt_pk_f32_fp8_e32 v[240:241], v142
	v_cvt_pk_f32_fp8_sdwa v[242:243], v142 src0_sel:WORD_1
	v_add_f32_dpp v235, v235, v235 row_half_mirror row_mask:0xf bank_mask:0xf bound_ctrl:1
	v_pk_fma_f32 v[204:205], v[244:245], v[40:41], v[204:205]
	v_pk_fma_f32 v[206:207], v[202:203], v[42:43], v[206:207]
	s_add_i32 s0, s1, 32
	s_cmp_lt_i32 s0, s2
	s_cselect_b64 vcc, -1, 0
	v_cvt_pk_f32_fp8_e32 v[244:245], v143
	v_cvt_pk_f32_fp8_sdwa v[202:203], v143 src0_sel:WORD_1
	v_cndmask_b32_e32 v210, v220, v235, vcc
	v_pk_fma_f32 v[204:205], v[240:241], v[44:45], v[204:205]
	v_pk_fma_f32 v[206:207], v[242:243], v[46:47], v[206:207]
	v_pk_fma_f32 v[204:205], v[244:245], v[48:49], v[204:205]
	v_pk_fma_f32 v[206:207], v[202:203], v[50:51], v[206:207]
	v_readlane_b32 s0, v95, 33
	s_lshl_b32 s0, s0, 10
	s_add_u32 s4, s8, s0
	s_addc_u32 s5, s9, 0
	global_load_dwordx4 v[140:143], v16, s[4:5]
	v_pk_add_f32 v[204:205], v[204:205], v[206:207]
	s_nop 0
	v_add_f32_e32 v221, v204, v205
	s_waitcnt vmcnt(15)
	v_cvt_pk_f32_fp8_e32 v[240:241], v144
	v_cvt_pk_f32_fp8_sdwa v[242:243], v144 src0_sel:WORD_1
	v_cvt_pk_f32_fp8_e32 v[244:245], v145
	v_cvt_pk_f32_fp8_sdwa v[202:203], v145 src0_sel:WORD_1
	v_add_f32_dpp v221, v221, v221 quad_perm:[1,0,3,2] row_mask:0xf bank_mask:0xf bound_ctrl:1
	v_pk_mul_f32 v[204:205], v[240:241], v[36:37]
	v_pk_mul_f32 v[206:207], v[242:243], v[38:39]
	v_add_f32_dpp v221, v221, v221 quad_perm:[2,3,0,1] row_mask:0xf bank_mask:0xf bound_ctrl:1
	v_cvt_pk_f32_fp8_e32 v[240:241], v146
	v_cvt_pk_f32_fp8_sdwa v[242:243], v146 src0_sel:WORD_1
	v_add_f32_dpp v221, v221, v221 row_half_mirror row_mask:0xf bank_mask:0xf bound_ctrl:1
	v_pk_fma_f32 v[204:205], v[244:245], v[40:41], v[204:205]
	v_pk_fma_f32 v[206:207], v[202:203], v[42:43], v[206:207]
	s_add_i32 s0, s1, 33
	s_cmp_lt_i32 s0, s2
	s_cselect_b64 vcc, -1, 0
	v_cvt_pk_f32_fp8_e32 v[244:245], v147
	v_cvt_pk_f32_fp8_sdwa v[202:203], v147 src0_sel:WORD_1
	v_cndmask_b32_e32 v211, v220, v221, vcc
	v_pk_fma_f32 v[204:205], v[240:241], v[44:45], v[204:205]
	v_pk_fma_f32 v[206:207], v[242:243], v[46:47], v[206:207]
	v_pk_fma_f32 v[204:205], v[244:245], v[48:49], v[204:205]
	v_pk_fma_f32 v[206:207], v[202:203], v[50:51], v[206:207]
	v_readlane_b32 s0, v95, 34
	s_lshl_b32 s0, s0, 10
	s_add_u32 s4, s8, s0
	s_addc_u32 s5, s9, 0
	global_load_dwordx4 v[144:147], v16, s[4:5]
	v_pk_add_f32 v[204:205], v[204:205], v[206:207]
	s_nop 0
	v_add_f32_e32 v235, v204, v205
	s_waitcnt vmcnt(15)
; DI float sum8(float v) { v += DPPF(v, 0xB1); v += DPPF(v, 0x4E); v += DPPF(v, 0x141); return v; }
; DI void topk_phase(const bf16_t* PROJ, const unsigned char* K8, const unsigned char* V8, const unsigned short* SC, bf16_t* ODSA, int c, char* smem, int bid, int nb) {
;     ...
;     for (int jj = 0; jj < 64; ++jj) {
;       const int j = wid * 64 + jj;
;       {
;         const size_t ro = (size_t)__builtin_amdgcn_readlane(mysel, jj) * 1024 + lane * 16;
;         const uint4 a = *(const uint4*)(K8 + ro), vv = *(const uint4*)(V8 + ro);
;         const unsigned w[4] = {a.x, a.y, a.z, a.w}, u[4] = {vv.x, vv.y, vv.z, vv.w};
;         float da = 0.f;
; #pragma unroll
;         for (int i = 0; i < 4; ++i) {
;           const f32x2v lo = __builtin_amdgcn_cvt_pk_f32_fp8((int)w[i], false), hi = __builtin_amdgcn_cvt_pk_f32_fp8((int)w[i], true);
;           da += qv[4 * i] * lo[0] + qv[4 * i + 1] * lo[1] + qv[4 * i + 2] * hi[0] + qv[4 * i + 3] * hi[1];
;         }
;         da = sum8(da);
;         da = j < count ? da : -3e30f;
;         const float mn = fmaxf(m_run, da), al = __builtin_amdgcn_exp2f(m_run - mn), pp = __builtin_amdgcn_exp2f(da - mn);
	v_cvt_pk_f32_fp8_e32 v[240:241], v148
	v_cvt_pk_f32_fp8_sdwa v[242:243], v148 src0_sel:WORD_1
	v_cvt_pk_f32_fp8_e32 v[244:245], v149
	v_cvt_pk_f32_fp8_sdwa v[202:203], v149 src0_sel:WORD_1
	v_add_f32_dpp v235, v235, v235 quad_perm:[1,0,3,2] row_mask:0xf bank_mask:0xf bound_ctrl:1
	v_pk_mul_f32 v[204:205], v[240:241], v[36:37]
	v_pk_mul_f32 v[206:207], v[242:243], v[38:39]
	v_add_f32_dpp v235, v235, v235 quad_perm:[2,3,0,1] row_mask:0xf bank_mask:0xf bound_ctrl:1
	v_cvt_pk_f32_fp8_e32 v[240:241], v150
	v_cvt_pk_f32_fp8_sdwa v[242:243], v150 src0_sel:WORD_1
	v_add_f32_dpp v235, v235, v235 row_half_mirror row_mask:0xf bank_mask:0xf bound_ctrl:1
	v_pk_fma_f32 v[204:205], v[244:245], v[40:41], v[204:205]
	v_pk_fma_f32 v[206:207], v[202:203], v[42:43], v[206:207]
	s_add_i32 s0, s1, 34
	s_cmp_lt_i32 s0, s2
	s_cselect_b64 vcc, -1, 0
	v_cvt_pk_f32_fp8_e32 v[244:245], v151
	v_cvt_pk_f32_fp8_sdwa v[202:203], v151 src0_sel:WORD_1
	v_cndmask_b32_e32 v212, v220, v235, vcc
	v_pk_fma_f32 v[204:205], v[240:241], v[44:45], v[204:205]
	v_pk_fma_f32 v[206:207], v[242:243], v[46:47], v[206:207]
	v_pk_fma_f32 v[204:205], v[244:245], v[48:49], v[204:205]
	v_pk_fma_f32 v[206:207], v[202:203], v[50:51], v[206:207]
	v_readlane_b32 s0, v95, 35
	s_lshl_b32 s0, s0, 10
	s_add_u32 s4, s8, s0
	s_addc_u32 s5, s9, 0
	global_load_dwordx4 v[148:151], v16, s[4:5]
	v_pk_add_f32 v[204:205], v[204:205], v[206:207]
	s_nop 0
	v_add_f32_e32 v221, v204, v205
	s_waitcnt vmcnt(15)
	v_cvt_pk_f32_fp8_e32 v[240:241], v152
	v_cvt_pk_f32_fp8_sdwa v[242:243], v152 src0_sel:WORD_1
	v_cvt_pk_f32_fp8_e32 v[244:245], v153
	v_cvt_pk_f32_fp8_sdwa v[202:203], v153 src0_sel:WORD_1
	v_add_f32_dpp v221, v221, v221 quad_perm:[1,0,3,2] row_mask:0xf bank_mask:0xf bound_ctrl:1
	v_pk_mul_f32 v[204:205], v[240:241], v[36:37]
	v_pk_mul_f32 v[206:207], v[242:243], v[38:39]
	v_add_f32_dpp v221, v221, v221 quad_perm:[2,3,0,1] row_mask:0xf bank_mask:0xf bound_ctrl:1
	v_cvt_pk_f32_fp8_e32 v[240:241], v154
	v_cvt_pk_f32_fp8_sdwa v[242:243], v154 src0_sel:WORD_1
	v_add_f32_dpp v221, v221, v221 row_half_mirror row_mask:0xf bank_mask:0xf bound_ctrl:1
	v_pk_fma_f32 v[204:205], v[244:245], v[40:41], v[204:205]
	v_pk_fma_f32 v[206:207], v[202:203], v[42:43], v[206:207]
	s_add_i32 s0, s1, 35
	s_cmp_lt_i32 s0, s2
	s_cselect_b64 vcc, -1, 0
	v_cvt_pk_f32_fp8_e32 v[244:245], v155
	v_cvt_pk_f32_fp8_sdwa v[202:203], v155 src0_sel:WORD_1
	v_cndmask_b32_e32 v213, v220, v221, vcc
	v_pk_fma_f32 v[204:205], v[240:241], v[44:45], v[204:205]
	v_pk_fma_f32 v[206:207], v[242:243], v[46:47], v[206:207]
	v_pk_fma_f32 v[204:205], v[244:245], v[48:49], v[204:205]
	v_pk_fma_f32 v[206:207], v[202:203], v[50:51], v[206:207]
	v_readlane_b32 s0, v95, 36
	s_lshl_b32 s0, s0, 10
	s_add_u32 s4, s8, s0
	s_addc_u32 s5, s9, 0
	global_load_dwordx4 v[152:155], v16, s[4:5]
	v_pk_add_f32 v[204:205], v[204:205], v[206:207]
	s_nop 0
	v_add_f32_e32 v235, v204, v205
	s_waitcnt vmcnt(15)
	v_cvt_pk_f32_fp8_e32 v[240:241], v156
	v_cvt_pk_f32_fp8_sdwa v[242:243], v156 src0_sel:WORD_1
	v_cvt_pk_f32_fp8_e32 v[244:245], v157
	v_cvt_pk_f32_fp8_sdwa v[202:203], v157 src0_sel:WORD_1
	v_add_f32_dpp v235, v235, v235 quad_perm:[1,0,3,2] row_mask:0xf bank_mask:0xf bound_ctrl:1
	v_pk_mul_f32 v[204:205], v[240:241], v[36:37]
	v_pk_mul_f32 v[206:207], v[242:243], v[38:39]
	v_add_f32_dpp v235, v235, v235 quad_perm:[2,3,0,1] row_mask:0xf bank_mask:0xf bound_ctrl:1
	v_cvt_pk_f32_fp8_e32 v[240:241], v158
	v_cvt_pk_f32_fp8_sdwa v[242:243], v158 src0_sel:WORD_1
	v_add_f32_dpp v235, v235, v235 row_half_mirror row_mask:0xf bank_mask:0xf bound_ctrl:1
	v_pk_fma_f32 v[204:205], v[244:245], v[40:41], v[204:205]
	v_pk_fma_f32 v[206:207], v[202:203], v[42:43], v[206:207]
	s_add_i32 s0, s1, 36
	s_cmp_lt_i32 s0, s2
	s_cselect_b64 vcc, -1, 0
	v_cvt_pk_f32_fp8_e32 v[244:245], v159
	v_cvt_pk_f32_fp8_sdwa v[202:203], v159 src0_sel:WORD_1
	v_cndmask_b32_e32 v226, v220, v235, vcc
	v_pk_fma_f32 v[204:205], v[240:241], v[44:45], v[204:205]
	v_pk_fma_f32 v[206:207], v[242:243], v[46:47], v[206:207]
	v_pk_fma_f32 v[204:205], v[244:245], v[48:49], v[204:205]
	v_pk_fma_f32 v[206:207], v[202:203], v[50:51], v[206:207]
	v_readlane_b32 s0, v95, 37
	s_lshl_b32 s0, s0, 10
	s_add_u32 s4, s8, s0
	s_addc_u32 s5, s9, 0
	global_load_dwordx4 v[156:159], v16, s[4:5]
	v_pk_add_f32 v[204:205], v[204:205], v[206:207]
	s_nop 0
	v_add_f32_e32 v221, v204, v205
	s_waitcnt vmcnt(15)
	v_cvt_pk_f32_fp8_e32 v[240:241], v160
	v_cvt_pk_f32_fp8_sdwa v[242:243], v160 src0_sel:WORD_1
	v_cvt_pk_f32_fp8_e32 v[244:245], v161
	v_cvt_pk_f32_fp8_sdwa v[202:203], v161 src0_sel:WORD_1
	v_add_f32_dpp v221, v221, v221 quad_perm:[1,0,3,2] row_mask:0xf bank_mask:0xf bound_ctrl:1
	v_pk_mul_f32 v[204:205], v[240:241], v[36:37]
	v_pk_mul_f32 v[206:207], v[242:243], v[38:39]
	v_add_f32_dpp v221, v221, v221 quad_perm:[2,3,0,1] row_mask:0xf bank_mask:0xf bound_ctrl:1
	v_cvt_pk_f32_fp8_e32 v[240:241], v162
	v_cvt_pk_f32_fp8_sdwa v[242:243], v162 src0_sel:WORD_1
	v_add_f32_dpp v221, v221, v221 row_half_mirror row_mask:0xf bank_mask:0xf bound_ctrl:1
	v_pk_fma_f32 v[204:205], v[244:245], v[40:41], v[204:205]
	v_pk_fma_f32 v[206:207], v[202:203], v[42:43], v[206:207]
	s_add_i32 s0, s1, 37
	s_cmp_lt_i32 s0, s2
	s_cselect_b64 vcc, -1, 0
	v_cvt_pk_f32_fp8_e32 v[244:245], v163
	v_cvt_pk_f32_fp8_sdwa v[202:203], v163 src0_sel:WORD_1
	v_cndmask_b32_e32 v227, v220, v221, vcc
	v_pk_fma_f32 v[204:205], v[240:241], v[44:45], v[204:205]
	v_pk_fma_f32 v[206:207], v[242:243], v[46:47], v[206:207]
	v_pk_fma_f32 v[204:205], v[244:245], v[48:49], v[204:205]
	v_pk_fma_f32 v[206:207], v[202:203], v[50:51], v[206:207]
	v_readlane_b32 s0, v95, 38
	s_lshl_b32 s0, s0, 10
	s_add_u32 s4, s8, s0
	s_addc_u32 s5, s9, 0
	global_load_dwordx4 v[160:163], v16, s[4:5]
	v_pk_add_f32 v[204:205], v[204:205], v[206:207]
	s_nop 0
	v_add_f32_e32 v235, v204, v205
	s_waitcnt vmcnt(15)
; DI float sum8(float v) { v += DPPF(v, 0xB1); v += DPPF(v, 0x4E); v += DPPF(v, 0x141); return v; }
; DI void topk_phase(const bf16_t* PROJ, const unsigned char* K8, const unsigned char* V8, const unsigned short* SC, bf16_t* ODSA, int c, char* smem, int bid, int nb) {
;     ...
;     for (int jj = 0; jj < 64; ++jj) {
;       const int j = wid * 64 + jj;
;       {
;         const size_t ro = (size_t)__builtin_amdgcn_readlane(mysel, jj) * 1024 + lane * 16;
;         const uint4 a = *(const uint4*)(K8 + ro), vv = *(const uint4*)(V8 + ro);
;         const unsigned w[4] = {a.x, a.y, a.z, a.w}, u[4] = {vv.x, vv.y, vv.z, vv.w};
;         float da = 0.f;
; #pragma unroll
;         for (int i = 0; i < 4; ++i) {
;           const f32x2v lo = __builtin_amdgcn_cvt_pk_f32_fp8((int)w[i], false), hi = __builtin_amdgcn_cvt_pk_f32_fp8((int)w[i], true);
;           da += qv[4 * i] * lo[0] + qv[4 * i + 1] * lo[1] + qv[4 * i + 2] * hi[0] + qv[4 * i + 3] * hi[1];
;         }
;         da = sum8(da);
;         da = j < count ? da : -3e30f;
;         const float mn = fmaxf(m_run, da), al = __builtin_amdgcn_exp2f(m_run - mn), pp = __builtin_amdgcn_exp2f(da - mn);
	v_cvt_pk_f32_fp8_e32 v[240:241], v164
	v_cvt_pk_f32_fp8_sdwa v[242:243], v164 src0_sel:WORD_1
	v_cvt_pk_f32_fp8_e32 v[244:245], v165
	v_cvt_pk_f32_fp8_sdwa v[202:203], v165 src0_sel:WORD_1
	v_add_f32_dpp v235, v235, v235 quad_perm:[1,0,3,2] row_mask:0xf bank_mask:0xf bound_ctrl:1
	v_pk_mul_f32 v[204:205], v[240:241], v[36:37]
	v_pk_mul_f32 v[206:207], v[242:243], v[38:39]
	v_add_f32_dpp v235, v235, v235 quad_perm:[2,3,0,1] row_mask:0xf bank_mask:0xf bound_ctrl:1
	v_cvt_pk_f32_fp8_e32 v[240:241], v166
	v_cvt_pk_f32_fp8_sdwa v[242:243], v166 src0_sel:WORD_1
	v_add_f32_dpp v235, v235, v235 row_half_mirror row_mask:0xf bank_mask:0xf bound_ctrl:1
	v_pk_fma_f32 v[204:205], v[244:245], v[40:41], v[204:205]
	v_pk_fma_f32 v[206:207], v[202:203], v[42:43], v[206:207]
	s_add_i32 s0, s1, 38
	s_cmp_lt_i32 s0, s2
	s_cselect_b64 vcc, -1, 0
	v_cvt_pk_f32_fp8_e32 v[244:245], v167
	v_cvt_pk_f32_fp8_sdwa v[202:203], v167 src0_sel:WORD_1
	v_cndmask_b32_e32 v228, v220, v235, vcc
	v_pk_fma_f32 v[204:205], v[240:241], v[44:45], v[204:205]
	v_pk_fma_f32 v[206:207], v[242:243], v[46:47], v[206:207]
	v_pk_fma_f32 v[204:205], v[244:245], v[48:49], v[204:205]
	v_pk_fma_f32 v[206:207], v[202:203], v[50:51], v[206:207]
	v_readlane_b32 s0, v95, 39
	s_lshl_b32 s0, s0, 10
	s_add_u32 s4, s8, s0
	s_addc_u32 s5, s9, 0
	global_load_dwordx4 v[164:167], v16, s[4:5]
	v_pk_add_f32 v[204:205], v[204:205], v[206:207]
	s_nop 0
	v_add_f32_e32 v221, v204, v205
	s_waitcnt vmcnt(15)
	v_cvt_pk_f32_fp8_e32 v[240:241], v168
	v_cvt_pk_f32_fp8_sdwa v[242:243], v168 src0_sel:WORD_1
	v_cvt_pk_f32_fp8_e32 v[244:245], v169
	v_cvt_pk_f32_fp8_sdwa v[202:203], v169 src0_sel:WORD_1
	v_add_f32_dpp v221, v221, v221 quad_perm:[1,0,3,2] row_mask:0xf bank_mask:0xf bound_ctrl:1
	v_pk_mul_f32 v[204:205], v[240:241], v[36:37]
	v_pk_mul_f32 v[206:207], v[242:243], v[38:39]
	v_add_f32_dpp v221, v221, v221 quad_perm:[2,3,0,1] row_mask:0xf bank_mask:0xf bound_ctrl:1
	v_cvt_pk_f32_fp8_e32 v[240:241], v170
	v_cvt_pk_f32_fp8_sdwa v[242:243], v170 src0_sel:WORD_1
	v_add_f32_dpp v221, v221, v221 row_half_mirror row_mask:0xf bank_mask:0xf bound_ctrl:1
	v_pk_fma_f32 v[204:205], v[244:245], v[40:41], v[204:205]
	v_pk_fma_f32 v[206:207], v[202:203], v[42:43], v[206:207]
	s_add_i32 s0, s1, 39
	s_cmp_lt_i32 s0, s2
	s_cselect_b64 vcc, -1, 0
	v_cvt_pk_f32_fp8_e32 v[244:245], v171
	v_cvt_pk_f32_fp8_sdwa v[202:203], v171 src0_sel:WORD_1
	v_cndmask_b32_e32 v229, v220, v221, vcc
	v_pk_fma_f32 v[204:205], v[240:241], v[44:45], v[204:205]
	v_pk_fma_f32 v[206:207], v[242:243], v[46:47], v[206:207]
	v_pk_fma_f32 v[204:205], v[244:245], v[48:49], v[204:205]
	v_pk_fma_f32 v[206:207], v[202:203], v[50:51], v[206:207]
	v_readlane_b32 s0, v95, 40
	s_lshl_b32 s0, s0, 10
	s_add_u32 s4, s8, s0
	s_addc_u32 s5, s9, 0
	global_load_dwordx4 v[168:171], v16, s[4:5]
	v_pk_add_f32 v[204:205], v[204:205], v[206:207]
	s_nop 0
	v_add_f32_e32 v235, v204, v205
	s_waitcnt vmcnt(15)
	v_cvt_pk_f32_fp8_e32 v[240:241], v172
	v_cvt_pk_f32_fp8_sdwa v[242:243], v172 src0_sel:WORD_1
	v_cvt_pk_f32_fp8_e32 v[244:245], v173
	v_cvt_pk_f32_fp8_sdwa v[202:203], v173 src0_sel:WORD_1
	v_add_f32_dpp v235, v235, v235 quad_perm:[1,0,3,2] row_mask:0xf bank_mask:0xf bound_ctrl:1
	v_pk_mul_f32 v[204:205], v[240:241], v[36:37]
	v_pk_mul_f32 v[206:207], v[242:243], v[38:39]
	v_add_f32_dpp v235, v235, v235 quad_perm:[2,3,0,1] row_mask:0xf bank_mask:0xf bound_ctrl:1
	v_cvt_pk_f32_fp8_e32 v[240:241], v174
	v_cvt_pk_f32_fp8_sdwa v[242:243], v174 src0_sel:WORD_1
	v_add_f32_dpp v235, v235, v235 row_half_mirror row_mask:0xf bank_mask:0xf bound_ctrl:1
	v_pk_fma_f32 v[204:205], v[244:245], v[40:41], v[204:205]
	v_pk_fma_f32 v[206:207], v[202:203], v[42:43], v[206:207]
	s_add_i32 s0, s1, 40
	s_cmp_lt_i32 s0, s2
	s_cselect_b64 vcc, -1, 0
	v_cvt_pk_f32_fp8_e32 v[244:245], v175
	v_cvt_pk_f32_fp8_sdwa v[202:203], v175 src0_sel:WORD_1
	v_cndmask_b32_e32 v230, v220, v235, vcc
	v_pk_fma_f32 v[204:205], v[240:241], v[44:45], v[204:205]
	v_pk_fma_f32 v[206:207], v[242:243], v[46:47], v[206:207]
	v_pk_fma_f32 v[204:205], v[244:245], v[48:49], v[204:205]
	v_pk_fma_f32 v[206:207], v[202:203], v[50:51], v[206:207]
	v_readlane_b32 s0, v95, 41
	s_lshl_b32 s0, s0, 10
	s_add_u32 s4, s8, s0
	s_addc_u32 s5, s9, 0
	global_load_dwordx4 v[172:175], v16, s[4:5]
	v_pk_add_f32 v[204:205], v[204:205], v[206:207]
	s_nop 0
	v_add_f32_e32 v221, v204, v205
	s_waitcnt vmcnt(15)
	v_cvt_pk_f32_fp8_e32 v[240:241], v176
	v_cvt_pk_f32_fp8_sdwa v[242:243], v176 src0_sel:WORD_1
	v_cvt_pk_f32_fp8_e32 v[244:245], v177
	v_cvt_pk_f32_fp8_sdwa v[202:203], v177 src0_sel:WORD_1
	v_add_f32_dpp v221, v221, v221 quad_perm:[1,0,3,2] row_mask:0xf bank_mask:0xf bound_ctrl:1
	v_pk_mul_f32 v[204:205], v[240:241], v[36:37]
	v_pk_mul_f32 v[206:207], v[242:243], v[38:39]
	v_add_f32_dpp v221, v221, v221 quad_perm:[2,3,0,1] row_mask:0xf bank_mask:0xf bound_ctrl:1
	v_cvt_pk_f32_fp8_e32 v[240:241], v178
	v_cvt_pk_f32_fp8_sdwa v[242:243], v178 src0_sel:WORD_1
	v_add_f32_dpp v221, v221, v221 row_half_mirror row_mask:0xf bank_mask:0xf bound_ctrl:1
	v_pk_fma_f32 v[204:205], v[244:245], v[40:41], v[204:205]
	v_pk_fma_f32 v[206:207], v[202:203], v[42:43], v[206:207]
	s_add_i32 s0, s1, 41
	s_cmp_lt_i32 s0, s2
	s_cselect_b64 vcc, -1, 0
	v_cvt_pk_f32_fp8_e32 v[244:245], v179
	v_cvt_pk_f32_fp8_sdwa v[202:203], v179 src0_sel:WORD_1
	v_cndmask_b32_e32 v231, v220, v221, vcc
	v_pk_fma_f32 v[204:205], v[240:241], v[44:45], v[204:205]
	v_pk_fma_f32 v[206:207], v[242:243], v[46:47], v[206:207]
	v_pk_fma_f32 v[204:205], v[244:245], v[48:49], v[204:205]
	v_pk_fma_f32 v[206:207], v[202:203], v[50:51], v[206:207]
	v_readlane_b32 s0, v95, 42
	s_lshl_b32 s0, s0, 10
	s_add_u32 s4, s8, s0
	s_addc_u32 s5, s9, 0
	global_load_dwordx4 v[176:179], v16, s[4:5]
	v_pk_add_f32 v[204:205], v[204:205], v[206:207]
	s_nop 0
	v_add_f32_e32 v235, v204, v205
	s_waitcnt vmcnt(15)
; DI float sum8(float v) { v += DPPF(v, 0xB1); v += DPPF(v, 0x4E); v += DPPF(v, 0x141); return v; }
; DI void topk_phase(const bf16_t* PROJ, const unsigned char* K8, const unsigned char* V8, const unsigned short* SC, bf16_t* ODSA, int c, char* smem, int bid, int nb) {
;     ...
;     for (int jj = 0; jj < 64; ++jj) {
;       const int j = wid * 64 + jj;
;       {
;         const size_t ro = (size_t)__builtin_amdgcn_readlane(mysel, jj) * 1024 + lane * 16;
;         const uint4 a = *(const uint4*)(K8 + ro), vv = *(const uint4*)(V8 + ro);
;         const unsigned w[4] = {a.x, a.y, a.z, a.w}, u[4] = {vv.x, vv.y, vv.z, vv.w};
;         float da = 0.f;
; #pragma unroll
;         for (int i = 0; i < 4; ++i) {
;           const f32x2v lo = __builtin_amdgcn_cvt_pk_f32_fp8((int)w[i], false), hi = __builtin_amdgcn_cvt_pk_f32_fp8((int)w[i], true);
;           da += qv[4 * i] * lo[0] + qv[4 * i + 1] * lo[1] + qv[4 * i + 2] * hi[0] + qv[4 * i + 3] * hi[1];
;         }
;         da = sum8(da);
;         da = j < count ? da : -3e30f;
;         const float mn = fmaxf(m_run, da), al = __builtin_amdgcn_exp2f(m_run - mn), pp = __builtin_amdgcn_exp2f(da - mn);
	v_cvt_pk_f32_fp8_e32 v[240:241], v180
	v_cvt_pk_f32_fp8_sdwa v[242:243], v180 src0_sel:WORD_1
	v_cvt_pk_f32_fp8_e32 v[244:245], v181
	v_cvt_pk_f32_fp8_sdwa v[202:203], v181 src0_sel:WORD_1
	v_add_f32_dpp v235, v235, v235 quad_perm:[1,0,3,2] row_mask:0xf bank_mask:0xf bound_ctrl:1
	v_pk_mul_f32 v[204:205], v[240:241], v[36:37]
	v_pk_mul_f32 v[206:207], v[242:243], v[38:39]
	v_add_f32_dpp v235, v235, v235 quad_perm:[2,3,0,1] row_mask:0xf bank_mask:0xf bound_ctrl:1
	v_cvt_pk_f32_fp8_e32 v[240:241], v182
	v_cvt_pk_f32_fp8_sdwa v[242:243], v182 src0_sel:WORD_1
	v_add_f32_dpp v235, v235, v235 row_half_mirror row_mask:0xf bank_mask:0xf bound_ctrl:1
	v_pk_fma_f32 v[204:205], v[244:245], v[40:41], v[204:205]
	v_pk_fma_f32 v[206:207], v[202:203], v[42:43], v[206:207]
	s_add_i32 s0, s1, 42
	s_cmp_lt_i32 s0, s2
	s_cselect_b64 vcc, -1, 0
	v_cvt_pk_f32_fp8_e32 v[244:245], v183
	v_cvt_pk_f32_fp8_sdwa v[202:203], v183 src0_sel:WORD_1
	v_cndmask_b32_e32 v232, v220, v235, vcc
	v_pk_fma_f32 v[204:205], v[240:241], v[44:45], v[204:205]
	v_pk_fma_f32 v[206:207], v[242:243], v[46:47], v[206:207]
	v_pk_fma_f32 v[204:205], v[244:245], v[48:49], v[204:205]
	v_pk_fma_f32 v[206:207], v[202:203], v[50:51], v[206:207]
	v_readlane_b32 s0, v95, 43
	s_lshl_b32 s0, s0, 10
	s_add_u32 s4, s8, s0
	s_addc_u32 s5, s9, 0
	global_load_dwordx4 v[180:183], v16, s[4:5]
	v_pk_add_f32 v[204:205], v[204:205], v[206:207]
	s_nop 0
	v_add_f32_e32 v221, v204, v205
	s_waitcnt vmcnt(15)
	v_cvt_pk_f32_fp8_e32 v[240:241], v186
	v_cvt_pk_f32_fp8_sdwa v[242:243], v186 src0_sel:WORD_1
	v_cvt_pk_f32_fp8_e32 v[244:245], v187
	v_cvt_pk_f32_fp8_sdwa v[202:203], v187 src0_sel:WORD_1
	v_add_f32_dpp v221, v221, v221 quad_perm:[1,0,3,2] row_mask:0xf bank_mask:0xf bound_ctrl:1
	v_pk_mul_f32 v[204:205], v[240:241], v[36:37]
	v_pk_mul_f32 v[206:207], v[242:243], v[38:39]
	v_add_f32_dpp v221, v221, v221 quad_perm:[2,3,0,1] row_mask:0xf bank_mask:0xf bound_ctrl:1
	v_cvt_pk_f32_fp8_e32 v[240:241], v188
	v_cvt_pk_f32_fp8_sdwa v[242:243], v188 src0_sel:WORD_1
	v_add_f32_dpp v221, v221, v221 row_half_mirror row_mask:0xf bank_mask:0xf bound_ctrl:1
	v_pk_fma_f32 v[204:205], v[244:245], v[40:41], v[204:205]
	v_pk_fma_f32 v[206:207], v[202:203], v[42:43], v[206:207]
	s_add_i32 s0, s1, 43
	s_cmp_lt_i32 s0, s2
	s_cselect_b64 vcc, -1, 0
	v_cvt_pk_f32_fp8_e32 v[244:245], v189
	v_cvt_pk_f32_fp8_sdwa v[202:203], v189 src0_sel:WORD_1
	v_cndmask_b32_e32 v233, v220, v221, vcc
	v_pk_fma_f32 v[204:205], v[240:241], v[44:45], v[204:205]
	v_pk_fma_f32 v[206:207], v[242:243], v[46:47], v[206:207]
	v_pk_fma_f32 v[204:205], v[244:245], v[48:49], v[204:205]
	v_pk_fma_f32 v[206:207], v[202:203], v[50:51], v[206:207]
	v_readlane_b32 s0, v95, 44
	s_lshl_b32 s0, s0, 10
	s_add_u32 s4, s8, s0
	s_addc_u32 s5, s9, 0
	global_load_dwordx4 v[186:189], v16, s[4:5]
	v_pk_add_f32 v[204:205], v[204:205], v[206:207]
	s_nop 0
	v_add_f32_e32 v235, v204, v205
	s_waitcnt vmcnt(15)
	v_cvt_pk_f32_fp8_e32 v[240:241], v190
	v_cvt_pk_f32_fp8_sdwa v[242:243], v190 src0_sel:WORD_1
	v_cvt_pk_f32_fp8_e32 v[244:245], v191
	v_cvt_pk_f32_fp8_sdwa v[202:203], v191 src0_sel:WORD_1
	v_add_f32_dpp v235, v235, v235 quad_perm:[1,0,3,2] row_mask:0xf bank_mask:0xf bound_ctrl:1
	v_pk_mul_f32 v[204:205], v[240:241], v[36:37]
	v_pk_mul_f32 v[206:207], v[242:243], v[38:39]
	v_add_f32_dpp v235, v235, v235 quad_perm:[2,3,0,1] row_mask:0xf bank_mask:0xf bound_ctrl:1
	v_cvt_pk_f32_fp8_e32 v[240:241], v192
	v_cvt_pk_f32_fp8_sdwa v[242:243], v192 src0_sel:WORD_1
	v_add_f32_dpp v235, v235, v235 row_half_mirror row_mask:0xf bank_mask:0xf bound_ctrl:1
	v_pk_fma_f32 v[204:205], v[244:245], v[40:41], v[204:205]
	v_pk_fma_f32 v[206:207], v[202:203], v[42:43], v[206:207]
	s_add_i32 s0, s1, 44
	s_cmp_lt_i32 s0, s2
	s_cselect_b64 vcc, -1, 0
	v_cvt_pk_f32_fp8_e32 v[244:245], v193
	v_cvt_pk_f32_fp8_sdwa v[202:203], v193 src0_sel:WORD_1
	v_cndmask_b32_e32 v236, v220, v235, vcc
	v_pk_fma_f32 v[204:205], v[240:241], v[44:45], v[204:205]
	v_pk_fma_f32 v[206:207], v[242:243], v[46:47], v[206:207]
	v_pk_fma_f32 v[204:205], v[244:245], v[48:49], v[204:205]
	v_pk_fma_f32 v[206:207], v[202:203], v[50:51], v[206:207]
	v_readlane_b32 s0, v95, 45
	s_lshl_b32 s0, s0, 10
	s_add_u32 s4, s8, s0
	s_addc_u32 s5, s9, 0
	global_load_dwordx4 v[190:193], v16, s[4:5]
	v_pk_add_f32 v[204:205], v[204:205], v[206:207]
	s_nop 0
	v_add_f32_e32 v221, v204, v205
	s_waitcnt vmcnt(15)
	v_cvt_pk_f32_fp8_e32 v[240:241], v194
	v_cvt_pk_f32_fp8_sdwa v[242:243], v194 src0_sel:WORD_1
	v_cvt_pk_f32_fp8_e32 v[244:245], v195
	v_cvt_pk_f32_fp8_sdwa v[202:203], v195 src0_sel:WORD_1
	v_add_f32_dpp v221, v221, v221 quad_perm:[1,0,3,2] row_mask:0xf bank_mask:0xf bound_ctrl:1
	v_pk_mul_f32 v[204:205], v[240:241], v[36:37]
	v_pk_mul_f32 v[206:207], v[242:243], v[38:39]
	v_add_f32_dpp v221, v221, v221 quad_perm:[2,3,0,1] row_mask:0xf bank_mask:0xf bound_ctrl:1
	v_cvt_pk_f32_fp8_e32 v[240:241], v196
	v_cvt_pk_f32_fp8_sdwa v[242:243], v196 src0_sel:WORD_1
	v_add_f32_dpp v221, v221, v221 row_half_mirror row_mask:0xf bank_mask:0xf bound_ctrl:1
	v_pk_fma_f32 v[204:205], v[244:245], v[40:41], v[204:205]
	v_pk_fma_f32 v[206:207], v[202:203], v[42:43], v[206:207]
	s_add_i32 s0, s1, 45
	s_cmp_lt_i32 s0, s2
	s_cselect_b64 vcc, -1, 0
	v_cvt_pk_f32_fp8_e32 v[244:245], v197
	v_cvt_pk_f32_fp8_sdwa v[202:203], v197 src0_sel:WORD_1
	v_cndmask_b32_e32 v237, v220, v221, vcc
	v_pk_fma_f32 v[204:205], v[240:241], v[44:45], v[204:205]
	v_pk_fma_f32 v[206:207], v[242:243], v[46:47], v[206:207]
	v_pk_fma_f32 v[204:205], v[244:245], v[48:49], v[204:205]
	v_pk_fma_f32 v[206:207], v[202:203], v[50:51], v[206:207]
	v_readlane_b32 s0, v95, 46
	s_lshl_b32 s0, s0, 10
	s_add_u32 s4, s8, s0
	s_addc_u32 s5, s9, 0
	global_load_dwordx4 v[194:197], v16, s[4:5]
	v_pk_add_f32 v[204:205], v[204:205], v[206:207]
	s_nop 0
	v_add_f32_e32 v235, v204, v205
	s_waitcnt vmcnt(15)
; DI float sum8(float v) { v += DPPF(v, 0xB1); v += DPPF(v, 0x4E); v += DPPF(v, 0x141); return v; }
; DI void topk_phase(const bf16_t* PROJ, const unsigned char* K8, const unsigned char* V8, const unsigned short* SC, bf16_t* ODSA, int c, char* smem, int bid, int nb) {
;     ...
;         float da = 0.f;
; #pragma unroll
;         for (int i = 0; i < 4; ++i) {
;           const f32x2v lo = __builtin_amdgcn_cvt_pk_f32_fp8((int)w[i], false), hi = __builtin_amdgcn_cvt_pk_f32_fp8((int)w[i], true);
;           da += qv[4 * i] * lo[0] + qv[4 * i + 1] * lo[1] + qv[4 * i + 2] * hi[0] + qv[4 * i + 3] * hi[1];
;         }
;         da = sum8(da);
;         da = j < count ? da : -3e30f;
;         const float mn = fmaxf(m_run, da), al = __builtin_amdgcn_exp2f(m_run - mn), pp = __builtin_amdgcn_exp2f(da - mn);
;         m_run = mn; l_run = l_run * al + pp;
; #pragma unroll
;         for (int i = 0; i < 4; ++i) {
;           const f32x2v lo = __builtin_amdgcn_cvt_pk_f32_fp8((int)u[i], false), hi = __builtin_amdgcn_cvt_pk_f32_fp8((int)u[i], true);
;           ov[4 * i] = ov[4 * i] * al + pp * lo[0]; ov[4 * i + 1] = ov[4 * i + 1] * al + pp * lo[1];
;           ov[4 * i + 2] = ov[4 * i + 2] * al + pp * hi[0]; ov[4 * i + 3] = ov[4 * i + 3] * al + pp * hi[1];
;         }
	v_cvt_pk_f32_fp8_e32 v[240:241], v198
	v_cvt_pk_f32_fp8_sdwa v[242:243], v198 src0_sel:WORD_1
	v_cvt_pk_f32_fp8_e32 v[244:245], v199
	v_cvt_pk_f32_fp8_sdwa v[202:203], v199 src0_sel:WORD_1
	v_add_f32_dpp v235, v235, v235 quad_perm:[1,0,3,2] row_mask:0xf bank_mask:0xf bound_ctrl:1
	v_pk_mul_f32 v[204:205], v[240:241], v[36:37]
	v_pk_mul_f32 v[206:207], v[242:243], v[38:39]
	v_add_f32_dpp v235, v235, v235 quad_perm:[2,3,0,1] row_mask:0xf bank_mask:0xf bound_ctrl:1
	v_cvt_pk_f32_fp8_e32 v[240:241], v200
	v_cvt_pk_f32_fp8_sdwa v[242:243], v200 src0_sel:WORD_1
	v_add_f32_dpp v235, v235, v235 row_half_mirror row_mask:0xf bank_mask:0xf bound_ctrl:1
	v_pk_fma_f32 v[204:205], v[244:245], v[40:41], v[204:205]
	v_pk_fma_f32 v[206:207], v[202:203], v[42:43], v[206:207]
	s_add_i32 s0, s1, 46
	s_cmp_lt_i32 s0, s2
	s_cselect_b64 vcc, -1, 0
	v_cvt_pk_f32_fp8_e32 v[244:245], v201
	v_cvt_pk_f32_fp8_sdwa v[202:203], v201 src0_sel:WORD_1
	v_cndmask_b32_e32 v238, v220, v235, vcc
	v_pk_fma_f32 v[204:205], v[240:241], v[44:45], v[204:205]
	v_pk_fma_f32 v[206:207], v[242:243], v[46:47], v[206:207]
	v_pk_fma_f32 v[204:205], v[244:245], v[48:49], v[204:205]
	v_pk_fma_f32 v[206:207], v[202:203], v[50:51], v[206:207]
	v_readlane_b32 s0, v95, 47
	s_lshl_b32 s0, s0, 10
	s_add_u32 s4, s8, s0
	s_addc_u32 s5, s9, 0
	global_load_dwordx4 v[198:201], v16, s[4:5]
	v_pk_add_f32 v[204:205], v[204:205], v[206:207]
	s_nop 0
	v_add_f32_e32 v221, v204, v205
	s_nop 1
	v_add_f32_dpp v221, v221, v221 quad_perm:[1,0,3,2] row_mask:0xf bank_mask:0xf bound_ctrl:1
	s_nop 1
	v_add_f32_dpp v221, v221, v221 quad_perm:[2,3,0,1] row_mask:0xf bank_mask:0xf bound_ctrl:1
	s_nop 1
	v_add_f32_dpp v221, v221, v221 row_half_mirror row_mask:0xf bank_mask:0xf bound_ctrl:1
	s_add_i32 s0, s1, 47
	s_cmp_lt_i32 s0, s2
	s_cselect_b64 vcc, -1, 0
	s_nop 1
	v_cndmask_b32_e32 v239, v220, v221, vcc
	v_max3_f32 v224, v210, v211, v212
	v_max3_f32 v224, v224, v213, v226
	v_max3_f32 v224, v224, v227, v228
	v_max3_f32 v224, v224, v229, v230
	v_max3_f32 v224, v224, v231, v232
	v_max3_f32 v224, v224, v233, v236
	v_max3_f32 v224, v224, v237, v238
	v_max_f32_e32 v224, v224, v239
	v_max_f32_e32 v221, v216, v224
	v_sub_f32_e32 v184, v216, v221
	v_exp_f32_e32 v184, v184
	v_mov_b32_e32 v216, v221
	s_nop 0
	v_pk_mul_f32 v[12:13], v[12:13], v[184:185] op_sel_hi:[1,0]
	v_pk_mul_f32 v[14:15], v[14:15], v[184:185] op_sel_hi:[1,0]
	v_pk_mul_f32 v[8:9], v[8:9], v[184:185] op_sel_hi:[1,0]
	v_pk_mul_f32 v[10:11], v[10:11], v[184:185] op_sel_hi:[1,0]
	v_pk_mul_f32 v[4:5], v[4:5], v[184:185] op_sel_hi:[1,0]
	v_pk_mul_f32 v[6:7], v[6:7], v[184:185] op_sel_hi:[1,0]
	v_pk_mul_f32 v[0:1], v[0:1], v[184:185] op_sel_hi:[1,0]
	v_pk_mul_f32 v[2:3], v[2:3], v[184:185] op_sel_hi:[1,0]
	v_mul_f32_e32 v215, v215, v184
	v_sub_f32_e32 v210, v210, v216
	v_exp_f32_e32 v210, v210
	s_waitcnt vmcnt(15)
	v_cvt_pk_f32_fp8_e32 v[240:241], v136
	v_cvt_pk_f32_fp8_sdwa v[242:243], v136 src0_sel:WORD_1
	v_cvt_pk_f32_fp8_e32 v[244:245], v137
	v_pk_fma_f32 v[12:13], v[240:241], v[210:211], v[12:13] op_sel_hi:[1,0,1]
	v_cvt_pk_f32_fp8_sdwa v[240:241], v137 src0_sel:WORD_1
	v_pk_fma_f32 v[14:15], v[242:243], v[210:211], v[14:15] op_sel_hi:[1,0,1]
	v_cvt_pk_f32_fp8_e32 v[242:243], v138
	v_sub_f32_e32 v211, v211, v216
	v_pk_fma_f32 v[8:9], v[244:245], v[210:211], v[8:9] op_sel_hi:[1,0,1]
	v_cvt_pk_f32_fp8_sdwa v[244:245], v138 src0_sel:WORD_1
	v_pk_fma_f32 v[10:11], v[240:241], v[210:211], v[10:11] op_sel_hi:[1,0,1]
	v_cvt_pk_f32_fp8_e32 v[240:241], v139
	v_exp_f32_e32 v211, v211
	v_pk_fma_f32 v[4:5], v[242:243], v[210:211], v[4:5] op_sel_hi:[1,0,1]
	v_cvt_pk_f32_fp8_sdwa v[242:243], v139 src0_sel:WORD_1
	v_pk_fma_f32 v[6:7], v[244:245], v[210:211], v[6:7] op_sel_hi:[1,0,1]
	v_add_f32_e32 v215, v215, v210
	v_pk_fma_f32 v[0:1], v[240:241], v[210:211], v[0:1] op_sel_hi:[1,0,1]
	v_pk_fma_f32 v[2:3], v[242:243], v[210:211], v[2:3] op_sel_hi:[1,0,1]
	v_readlane_b32 s0, v95, 48
	s_lshl_b32 s0, s0, 10
	s_add_u32 s4, s6, s0
	s_addc_u32 s5, s7, 0
	global_load_dwordx4 v[136:139], v16, s[4:5]
	s_waitcnt vmcnt(15)
	v_cvt_pk_f32_fp8_e32 v[240:241], v140
	v_cvt_pk_f32_fp8_sdwa v[242:243], v140 src0_sel:WORD_1
	v_cvt_pk_f32_fp8_e32 v[244:245], v141
	v_pk_fma_f32 v[12:13], v[240:241], v[210:211], v[12:13] op_sel:[0,1,0]
	v_cvt_pk_f32_fp8_sdwa v[240:241], v141 src0_sel:WORD_1
	v_pk_fma_f32 v[14:15], v[242:243], v[210:211], v[14:15] op_sel:[0,1,0]
	v_cvt_pk_f32_fp8_e32 v[242:243], v142
	v_sub_f32_e32 v212, v212, v216
	v_pk_fma_f32 v[8:9], v[244:245], v[210:211], v[8:9] op_sel:[0,1,0]
	v_cvt_pk_f32_fp8_sdwa v[244:245], v142 src0_sel:WORD_1
	v_pk_fma_f32 v[10:11], v[240:241], v[210:211], v[10:11] op_sel:[0,1,0]
	v_cvt_pk_f32_fp8_e32 v[240:241], v143
	v_exp_f32_e32 v212, v212
	v_pk_fma_f32 v[4:5], v[242:243], v[210:211], v[4:5] op_sel:[0,1,0]
	v_cvt_pk_f32_fp8_sdwa v[242:243], v143 src0_sel:WORD_1
	v_pk_fma_f32 v[6:7], v[244:245], v[210:211], v[6:7] op_sel:[0,1,0]
	v_add_f32_e32 v215, v215, v211
	v_pk_fma_f32 v[0:1], v[240:241], v[210:211], v[0:1] op_sel:[0,1,0]
	v_pk_fma_f32 v[2:3], v[242:243], v[210:211], v[2:3] op_sel:[0,1,0]
	v_readlane_b32 s0, v95, 49
	s_lshl_b32 s0, s0, 10
	s_add_u32 s4, s6, s0
	s_addc_u32 s5, s7, 0
	global_load_dwordx4 v[140:143], v16, s[4:5]
	s_waitcnt vmcnt(15)
; DI void topk_phase(const bf16_t* PROJ, const unsigned char* K8, const unsigned char* V8, const unsigned short* SC, bf16_t* ODSA, int c, char* smem, int bid, int nb) {
;     ...
;         const float mn = fmaxf(m_run, da), al = __builtin_amdgcn_exp2f(m_run - mn), pp = __builtin_amdgcn_exp2f(da - mn);
;         m_run = mn; l_run = l_run * al + pp;
; #pragma unroll
;         for (int i = 0; i < 4; ++i) {
;           const f32x2v lo = __builtin_amdgcn_cvt_pk_f32_fp8((int)u[i], false), hi = __builtin_amdgcn_cvt_pk_f32_fp8((int)u[i], true);
;           ov[4 * i] = ov[4 * i] * al + pp * lo[0]; ov[4 * i + 1] = ov[4 * i + 1] * al + pp * lo[1];
;           ov[4 * i + 2] = ov[4 * i + 2] * al + pp * hi[0]; ov[4 * i + 3] = ov[4 * i + 3] * al + pp * hi[1];
;         }
	v_cvt_pk_f32_fp8_e32 v[240:241], v144
	v_cvt_pk_f32_fp8_sdwa v[242:243], v144 src0_sel:WORD_1
	v_cvt_pk_f32_fp8_e32 v[244:245], v145
	v_pk_fma_f32 v[12:13], v[240:241], v[212:213], v[12:13] op_sel_hi:[1,0,1]
	v_cvt_pk_f32_fp8_sdwa v[240:241], v145 src0_sel:WORD_1
	v_pk_fma_f32 v[14:15], v[242:243], v[212:213], v[14:15] op_sel_hi:[1,0,1]
	v_cvt_pk_f32_fp8_e32 v[242:243], v146
	v_sub_f32_e32 v213, v213, v216
	v_pk_fma_f32 v[8:9], v[244:245], v[212:213], v[8:9] op_sel_hi:[1,0,1]
	v_cvt_pk_f32_fp8_sdwa v[244:245], v146 src0_sel:WORD_1
	v_pk_fma_f32 v[10:11], v[240:241], v[212:213], v[10:11] op_sel_hi:[1,0,1]
	v_cvt_pk_f32_fp8_e32 v[240:241], v147
	v_exp_f32_e32 v213, v213
	v_pk_fma_f32 v[4:5], v[242:243], v[212:213], v[4:5] op_sel_hi:[1,0,1]
	v_cvt_pk_f32_fp8_sdwa v[242:243], v147 src0_sel:WORD_1
	v_pk_fma_f32 v[6:7], v[244:245], v[212:213], v[6:7] op_sel_hi:[1,0,1]
	v_add_f32_e32 v215, v215, v212
	v_pk_fma_f32 v[0:1], v[240:241], v[212:213], v[0:1] op_sel_hi:[1,0,1]
	v_pk_fma_f32 v[2:3], v[242:243], v[212:213], v[2:3] op_sel_hi:[1,0,1]
	v_readlane_b32 s0, v95, 50
	s_lshl_b32 s0, s0, 10
	s_add_u32 s4, s6, s0
	s_addc_u32 s5, s7, 0
	global_load_dwordx4 v[144:147], v16, s[4:5]
	s_waitcnt vmcnt(15)
	v_cvt_pk_f32_fp8_e32 v[240:241], v148
	v_cvt_pk_f32_fp8_sdwa v[242:243], v148 src0_sel:WORD_1
	v_cvt_pk_f32_fp8_e32 v[244:245], v149
	v_pk_fma_f32 v[12:13], v[240:241], v[212:213], v[12:13] op_sel:[0,1,0]
	v_cvt_pk_f32_fp8_sdwa v[240:241], v149 src0_sel:WORD_1
	v_pk_fma_f32 v[14:15], v[242:243], v[212:213], v[14:15] op_sel:[0,1,0]
	v_cvt_pk_f32_fp8_e32 v[242:243], v150
	v_sub_f32_e32 v226, v226, v216
	v_pk_fma_f32 v[8:9], v[244:245], v[212:213], v[8:9] op_sel:[0,1,0]
	v_cvt_pk_f32_fp8_sdwa v[244:245], v150 src0_sel:WORD_1
	v_pk_fma_f32 v[10:11], v[240:241], v[212:213], v[10:11] op_sel:[0,1,0]
	v_cvt_pk_f32_fp8_e32 v[240:241], v151
	v_exp_f32_e32 v226, v226
	v_pk_fma_f32 v[4:5], v[242:243], v[212:213], v[4:5] op_sel:[0,1,0]
	v_cvt_pk_f32_fp8_sdwa v[242:243], v151 src0_sel:WORD_1
	v_pk_fma_f32 v[6:7], v[244:245], v[212:213], v[6:7] op_sel:[0,1,0]
	v_add_f32_e32 v215, v215, v213
	v_pk_fma_f32 v[0:1], v[240:241], v[212:213], v[0:1] op_sel:[0,1,0]
	v_pk_fma_f32 v[2:3], v[242:243], v[212:213], v[2:3] op_sel:[0,1,0]
	v_readlane_b32 s0, v95, 51
	s_lshl_b32 s0, s0, 10
	s_add_u32 s4, s6, s0
	s_addc_u32 s5, s7, 0
	global_load_dwordx4 v[148:151], v16, s[4:5]
	s_waitcnt vmcnt(15)
	v_cvt_pk_f32_fp8_e32 v[240:241], v152
	v_cvt_pk_f32_fp8_sdwa v[242:243], v152 src0_sel:WORD_1
	v_cvt_pk_f32_fp8_e32 v[244:245], v153
	v_pk_fma_f32 v[12:13], v[240:241], v[226:227], v[12:13] op_sel_hi:[1,0,1]
	v_cvt_pk_f32_fp8_sdwa v[240:241], v153 src0_sel:WORD_1
	v_pk_fma_f32 v[14:15], v[242:243], v[226:227], v[14:15] op_sel_hi:[1,0,1]
	v_cvt_pk_f32_fp8_e32 v[242:243], v154
	v_sub_f32_e32 v227, v227, v216
	v_pk_fma_f32 v[8:9], v[244:245], v[226:227], v[8:9] op_sel_hi:[1,0,1]
	v_cvt_pk_f32_fp8_sdwa v[244:245], v154 src0_sel:WORD_1
	v_pk_fma_f32 v[10:11], v[240:241], v[226:227], v[10:11] op_sel_hi:[1,0,1]
	v_cvt_pk_f32_fp8_e32 v[240:241], v155
	v_exp_f32_e32 v227, v227
	v_pk_fma_f32 v[4:5], v[242:243], v[226:227], v[4:5] op_sel_hi:[1,0,1]
	v_cvt_pk_f32_fp8_sdwa v[242:243], v155 src0_sel:WORD_1
	v_pk_fma_f32 v[6:7], v[244:245], v[226:227], v[6:7] op_sel_hi:[1,0,1]
	v_add_f32_e32 v215, v215, v226
	v_pk_fma_f32 v[0:1], v[240:241], v[226:227], v[0:1] op_sel_hi:[1,0,1]
	v_pk_fma_f32 v[2:3], v[242:243], v[226:227], v[2:3] op_sel_hi:[1,0,1]
	v_readlane_b32 s0, v95, 52
	s_lshl_b32 s0, s0, 10
	s_add_u32 s4, s6, s0
	s_addc_u32 s5, s7, 0
	global_load_dwordx4 v[152:155], v16, s[4:5]
	s_waitcnt vmcnt(15)
	v_cvt_pk_f32_fp8_e32 v[240:241], v156
	v_cvt_pk_f32_fp8_sdwa v[242:243], v156 src0_sel:WORD_1
	v_cvt_pk_f32_fp8_e32 v[244:245], v157
	v_pk_fma_f32 v[12:13], v[240:241], v[226:227], v[12:13] op_sel:[0,1,0]
	v_cvt_pk_f32_fp8_sdwa v[240:241], v157 src0_sel:WORD_1
	v_pk_fma_f32 v[14:15], v[242:243], v[226:227], v[14:15] op_sel:[0,1,0]
	v_cvt_pk_f32_fp8_e32 v[242:243], v158
	v_sub_f32_e32 v228, v228, v216
	v_pk_fma_f32 v[8:9], v[244:245], v[226:227], v[8:9] op_sel:[0,1,0]
	v_cvt_pk_f32_fp8_sdwa v[244:245], v158 src0_sel:WORD_1
	v_pk_fma_f32 v[10:11], v[240:241], v[226:227], v[10:11] op_sel:[0,1,0]
	v_cvt_pk_f32_fp8_e32 v[240:241], v159
	v_exp_f32_e32 v228, v228
	v_pk_fma_f32 v[4:5], v[242:243], v[226:227], v[4:5] op_sel:[0,1,0]
	v_cvt_pk_f32_fp8_sdwa v[242:243], v159 src0_sel:WORD_1
	v_pk_fma_f32 v[6:7], v[244:245], v[226:227], v[6:7] op_sel:[0,1,0]
	v_add_f32_e32 v215, v215, v227
	v_pk_fma_f32 v[0:1], v[240:241], v[226:227], v[0:1] op_sel:[0,1,0]
	v_pk_fma_f32 v[2:3], v[242:243], v[226:227], v[2:3] op_sel:[0,1,0]
	v_readlane_b32 s0, v95, 53
	s_lshl_b32 s0, s0, 10
	s_add_u32 s4, s6, s0
	s_addc_u32 s5, s7, 0
	global_load_dwordx4 v[156:159], v16, s[4:5]
	s_waitcnt vmcnt(15)
	v_cvt_pk_f32_fp8_e32 v[240:241], v160
	v_cvt_pk_f32_fp8_sdwa v[242:243], v160 src0_sel:WORD_1
	v_cvt_pk_f32_fp8_e32 v[244:245], v161
	v_pk_fma_f32 v[12:13], v[240:241], v[228:229], v[12:13] op_sel_hi:[1,0,1]
	v_cvt_pk_f32_fp8_sdwa v[240:241], v161 src0_sel:WORD_1
	v_pk_fma_f32 v[14:15], v[242:243], v[228:229], v[14:15] op_sel_hi:[1,0,1]
	v_cvt_pk_f32_fp8_e32 v[242:243], v162
	v_sub_f32_e32 v229, v229, v216
	v_pk_fma_f32 v[8:9], v[244:245], v[228:229], v[8:9] op_sel_hi:[1,0,1]
	v_cvt_pk_f32_fp8_sdwa v[244:245], v162 src0_sel:WORD_1
	v_pk_fma_f32 v[10:11], v[240:241], v[228:229], v[10:11] op_sel_hi:[1,0,1]
	v_cvt_pk_f32_fp8_e32 v[240:241], v163
	v_exp_f32_e32 v229, v229
	v_pk_fma_f32 v[4:5], v[242:243], v[228:229], v[4:5] op_sel_hi:[1,0,1]
	v_cvt_pk_f32_fp8_sdwa v[242:243], v163 src0_sel:WORD_1
	v_pk_fma_f32 v[6:7], v[244:245], v[228:229], v[6:7] op_sel_hi:[1,0,1]
	v_add_f32_e32 v215, v215, v228
	v_pk_fma_f32 v[0:1], v[240:241], v[228:229], v[0:1] op_sel_hi:[1,0,1]
	v_pk_fma_f32 v[2:3], v[242:243], v[228:229], v[2:3] op_sel_hi:[1,0,1]
	v_readlane_b32 s0, v95, 54
	s_lshl_b32 s0, s0, 10
	s_add_u32 s4, s6, s0
	s_addc_u32 s5, s7, 0
	global_load_dwordx4 v[160:163], v16, s[4:5]
	s_waitcnt vmcnt(15)
; DI void topk_phase(const bf16_t* PROJ, const unsigned char* K8, const unsigned char* V8, const unsigned short* SC, bf16_t* ODSA, int c, char* smem, int bid, int nb) {
;     ...
;         const float mn = fmaxf(m_run, da), al = __builtin_amdgcn_exp2f(m_run - mn), pp = __builtin_amdgcn_exp2f(da - mn);
;         m_run = mn; l_run = l_run * al + pp;
; #pragma unroll
;         for (int i = 0; i < 4; ++i) {
;           const f32x2v lo = __builtin_amdgcn_cvt_pk_f32_fp8((int)u[i], false), hi = __builtin_amdgcn_cvt_pk_f32_fp8((int)u[i], true);
;           ov[4 * i] = ov[4 * i] * al + pp * lo[0]; ov[4 * i + 1] = ov[4 * i + 1] * al + pp * lo[1];
;           ov[4 * i + 2] = ov[4 * i + 2] * al + pp * hi[0]; ov[4 * i + 3] = ov[4 * i + 3] * al + pp * hi[1];
;         }
	v_cvt_pk_f32_fp8_e32 v[240:241], v164
	v_cvt_pk_f32_fp8_sdwa v[242:243], v164 src0_sel:WORD_1
	v_cvt_pk_f32_fp8_e32 v[244:245], v165
	v_pk_fma_f32 v[12:13], v[240:241], v[228:229], v[12:13] op_sel:[0,1,0]
	v_cvt_pk_f32_fp8_sdwa v[240:241], v165 src0_sel:WORD_1
	v_pk_fma_f32 v[14:15], v[242:243], v[228:229], v[14:15] op_sel:[0,1,0]
	v_cvt_pk_f32_fp8_e32 v[242:243], v166
	v_sub_f32_e32 v230, v230, v216
	v_pk_fma_f32 v[8:9], v[244:245], v[228:229], v[8:9] op_sel:[0,1,0]
	v_cvt_pk_f32_fp8_sdwa v[244:245], v166 src0_sel:WORD_1
	v_pk_fma_f32 v[10:11], v[240:241], v[228:229], v[10:11] op_sel:[0,1,0]
	v_cvt_pk_f32_fp8_e32 v[240:241], v167
	v_exp_f32_e32 v230, v230
	v_pk_fma_f32 v[4:5], v[242:243], v[228:229], v[4:5] op_sel:[0,1,0]
	v_cvt_pk_f32_fp8_sdwa v[242:243], v167 src0_sel:WORD_1
	v_pk_fma_f32 v[6:7], v[244:245], v[228:229], v[6:7] op_sel:[0,1,0]
	v_add_f32_e32 v215, v215, v229
	v_pk_fma_f32 v[0:1], v[240:241], v[228:229], v[0:1] op_sel:[0,1,0]
	v_pk_fma_f32 v[2:3], v[242:243], v[228:229], v[2:3] op_sel:[0,1,0]
	v_readlane_b32 s0, v95, 55
	s_lshl_b32 s0, s0, 10
	s_add_u32 s4, s6, s0
	s_addc_u32 s5, s7, 0
	global_load_dwordx4 v[164:167], v16, s[4:5]
	s_waitcnt vmcnt(15)
	v_cvt_pk_f32_fp8_e32 v[240:241], v168
	v_cvt_pk_f32_fp8_sdwa v[242:243], v168 src0_sel:WORD_1
	v_cvt_pk_f32_fp8_e32 v[244:245], v169
	v_pk_fma_f32 v[12:13], v[240:241], v[230:231], v[12:13] op_sel_hi:[1,0,1]
	v_cvt_pk_f32_fp8_sdwa v[240:241], v169 src0_sel:WORD_1
	v_pk_fma_f32 v[14:15], v[242:243], v[230:231], v[14:15] op_sel_hi:[1,0,1]
	v_cvt_pk_f32_fp8_e32 v[242:243], v170
	v_sub_f32_e32 v231, v231, v216
	v_pk_fma_f32 v[8:9], v[244:245], v[230:231], v[8:9] op_sel_hi:[1,0,1]
	v_cvt_pk_f32_fp8_sdwa v[244:245], v170 src0_sel:WORD_1
	v_pk_fma_f32 v[10:11], v[240:241], v[230:231], v[10:11] op_sel_hi:[1,0,1]
	v_cvt_pk_f32_fp8_e32 v[240:241], v171
	v_exp_f32_e32 v231, v231
	v_pk_fma_f32 v[4:5], v[242:243], v[230:231], v[4:5] op_sel_hi:[1,0,1]
	v_cvt_pk_f32_fp8_sdwa v[242:243], v171 src0_sel:WORD_1
	v_pk_fma_f32 v[6:7], v[244:245], v[230:231], v[6:7] op_sel_hi:[1,0,1]
	v_add_f32_e32 v215, v215, v230
	v_pk_fma_f32 v[0:1], v[240:241], v[230:231], v[0:1] op_sel_hi:[1,0,1]
	v_pk_fma_f32 v[2:3], v[242:243], v[230:231], v[2:3] op_sel_hi:[1,0,1]
	v_readlane_b32 s0, v95, 56
	s_lshl_b32 s0, s0, 10
	s_add_u32 s4, s6, s0
	s_addc_u32 s5, s7, 0
	global_load_dwordx4 v[168:171], v16, s[4:5]
	s_waitcnt vmcnt(15)
	v_cvt_pk_f32_fp8_e32 v[240:241], v172
	v_cvt_pk_f32_fp8_sdwa v[242:243], v172 src0_sel:WORD_1
	v_cvt_pk_f32_fp8_e32 v[244:245], v173
	v_pk_fma_f32 v[12:13], v[240:241], v[230:231], v[12:13] op_sel:[0,1,0]
	v_cvt_pk_f32_fp8_sdwa v[240:241], v173 src0_sel:WORD_1
	v_pk_fma_f32 v[14:15], v[242:243], v[230:231], v[14:15] op_sel:[0,1,0]
	v_cvt_pk_f32_fp8_e32 v[242:243], v174
	v_sub_f32_e32 v232, v232, v216
	v_pk_fma_f32 v[8:9], v[244:245], v[230:231], v[8:9] op_sel:[0,1,0]
	v_cvt_pk_f32_fp8_sdwa v[244:245], v174 src0_sel:WORD_1
	v_pk_fma_f32 v[10:11], v[240:241], v[230:231], v[10:11] op_sel:[0,1,0]
	v_cvt_pk_f32_fp8_e32 v[240:241], v175
	v_exp_f32_e32 v232, v232
	v_pk_fma_f32 v[4:5], v[242:243], v[230:231], v[4:5] op_sel:[0,1,0]
	v_cvt_pk_f32_fp8_sdwa v[242:243], v175 src0_sel:WORD_1
	v_pk_fma_f32 v[6:7], v[244:245], v[230:231], v[6:7] op_sel:[0,1,0]
	v_add_f32_e32 v215, v215, v231
	v_pk_fma_f32 v[0:1], v[240:241], v[230:231], v[0:1] op_sel:[0,1,0]
	v_pk_fma_f32 v[2:3], v[242:243], v[230:231], v[2:3] op_sel:[0,1,0]
	v_readlane_b32 s0, v95, 57
	s_lshl_b32 s0, s0, 10
	s_add_u32 s4, s6, s0
	s_addc_u32 s5, s7, 0
	global_load_dwordx4 v[172:175], v16, s[4:5]
	s_waitcnt vmcnt(15)
	v_cvt_pk_f32_fp8_e32 v[240:241], v176
	v_cvt_pk_f32_fp8_sdwa v[242:243], v176 src0_sel:WORD_1
	v_cvt_pk_f32_fp8_e32 v[244:245], v177
	v_pk_fma_f32 v[12:13], v[240:241], v[232:233], v[12:13] op_sel_hi:[1,0,1]
	v_cvt_pk_f32_fp8_sdwa v[240:241], v177 src0_sel:WORD_1
	v_pk_fma_f32 v[14:15], v[242:243], v[232:233], v[14:15] op_sel_hi:[1,0,1]
	v_cvt_pk_f32_fp8_e32 v[242:243], v178
	v_sub_f32_e32 v233, v233, v216
	v_pk_fma_f32 v[8:9], v[244:245], v[232:233], v[8:9] op_sel_hi:[1,0,1]
	v_cvt_pk_f32_fp8_sdwa v[244:245], v178 src0_sel:WORD_1
	v_pk_fma_f32 v[10:11], v[240:241], v[232:233], v[10:11] op_sel_hi:[1,0,1]
	v_cvt_pk_f32_fp8_e32 v[240:241], v179
	v_exp_f32_e32 v233, v233
	v_pk_fma_f32 v[4:5], v[242:243], v[232:233], v[4:5] op_sel_hi:[1,0,1]
	v_cvt_pk_f32_fp8_sdwa v[242:243], v179 src0_sel:WORD_1
	v_pk_fma_f32 v[6:7], v[244:245], v[232:233], v[6:7] op_sel_hi:[1,0,1]
	v_add_f32_e32 v215, v215, v232
	v_pk_fma_f32 v[0:1], v[240:241], v[232:233], v[0:1] op_sel_hi:[1,0,1]
	v_pk_fma_f32 v[2:3], v[242:243], v[232:233], v[2:3] op_sel_hi:[1,0,1]
	v_readlane_b32 s0, v95, 58
	s_lshl_b32 s0, s0, 10
	s_add_u32 s4, s6, s0
	s_addc_u32 s5, s7, 0
	global_load_dwordx4 v[176:179], v16, s[4:5]
	s_waitcnt vmcnt(15)
	v_cvt_pk_f32_fp8_e32 v[240:241], v180
	v_cvt_pk_f32_fp8_sdwa v[242:243], v180 src0_sel:WORD_1
	v_cvt_pk_f32_fp8_e32 v[244:245], v181
	v_pk_fma_f32 v[12:13], v[240:241], v[232:233], v[12:13] op_sel:[0,1,0]
	v_cvt_pk_f32_fp8_sdwa v[240:241], v181 src0_sel:WORD_1
	v_pk_fma_f32 v[14:15], v[242:243], v[232:233], v[14:15] op_sel:[0,1,0]
	v_cvt_pk_f32_fp8_e32 v[242:243], v182
	v_sub_f32_e32 v236, v236, v216
	v_pk_fma_f32 v[8:9], v[244:245], v[232:233], v[8:9] op_sel:[0,1,0]
	v_cvt_pk_f32_fp8_sdwa v[244:245], v182 src0_sel:WORD_1
	v_pk_fma_f32 v[10:11], v[240:241], v[232:233], v[10:11] op_sel:[0,1,0]
	v_cvt_pk_f32_fp8_e32 v[240:241], v183
	v_exp_f32_e32 v236, v236
	v_pk_fma_f32 v[4:5], v[242:243], v[232:233], v[4:5] op_sel:[0,1,0]
	v_cvt_pk_f32_fp8_sdwa v[242:243], v183 src0_sel:WORD_1
	v_pk_fma_f32 v[6:7], v[244:245], v[232:233], v[6:7] op_sel:[0,1,0]
	v_add_f32_e32 v215, v215, v233
	v_pk_fma_f32 v[0:1], v[240:241], v[232:233], v[0:1] op_sel:[0,1,0]
	v_pk_fma_f32 v[2:3], v[242:243], v[232:233], v[2:3] op_sel:[0,1,0]
	v_readlane_b32 s0, v95, 59
	s_lshl_b32 s0, s0, 10
	s_add_u32 s4, s6, s0
	s_addc_u32 s5, s7, 0
	global_load_dwordx4 v[180:183], v16, s[4:5]
	s_waitcnt vmcnt(15)
; DI float sum8(float v) { v += DPPF(v, 0xB1); v += DPPF(v, 0x4E); v += DPPF(v, 0x141); return v; }
; DI void topk_phase(const bf16_t* PROJ, const unsigned char* K8, const unsigned char* V8, const unsigned short* SC, bf16_t* ODSA, int c, char* smem, int bid, int nb) {
;     ...
; #pragma unroll 4
;     for (int jj = 0; jj < 64; ++jj) {
;       const int j = wid * 64 + jj;
;       {
;         const size_t ro = (size_t)__builtin_amdgcn_readlane(mysel, jj) * 1024 + lane * 16;
;         const uint4 a = *(const uint4*)(K8 + ro), vv = *(const uint4*)(V8 + ro);
;         const unsigned w[4] = {a.x, a.y, a.z, a.w}, u[4] = {vv.x, vv.y, vv.z, vv.w};
;         float da = 0.f;
; #pragma unroll
;         for (int i = 0; i < 4; ++i) {
;           const f32x2v lo = __builtin_amdgcn_cvt_pk_f32_fp8((int)w[i], false), hi = __builtin_amdgcn_cvt_pk_f32_fp8((int)w[i], true);
;           da += qv[4 * i] * lo[0] + qv[4 * i + 1] * lo[1] + qv[4 * i + 2] * hi[0] + qv[4 * i + 3] * hi[1];
;         }
;         da = sum8(da);
;         da = j < count ? da : -3e30f;
;         const float mn = fmaxf(m_run, da), al = __builtin_amdgcn_exp2f(m_run - mn), pp = __builtin_amdgcn_exp2f(da - mn);
	v_cvt_pk_f32_fp8_e32 v[240:241], v186
	v_cvt_pk_f32_fp8_sdwa v[242:243], v186 src0_sel:WORD_1
	v_cvt_pk_f32_fp8_e32 v[244:245], v187
	v_pk_fma_f32 v[12:13], v[240:241], v[236:237], v[12:13] op_sel_hi:[1,0,1]
	v_cvt_pk_f32_fp8_sdwa v[240:241], v187 src0_sel:WORD_1
	v_pk_fma_f32 v[14:15], v[242:243], v[236:237], v[14:15] op_sel_hi:[1,0,1]
	v_cvt_pk_f32_fp8_e32 v[242:243], v188
	v_sub_f32_e32 v237, v237, v216
	v_pk_fma_f32 v[8:9], v[244:245], v[236:237], v[8:9] op_sel_hi:[1,0,1]
	v_cvt_pk_f32_fp8_sdwa v[244:245], v188 src0_sel:WORD_1
	v_pk_fma_f32 v[10:11], v[240:241], v[236:237], v[10:11] op_sel_hi:[1,0,1]
	v_cvt_pk_f32_fp8_e32 v[240:241], v189
	v_exp_f32_e32 v237, v237
	v_pk_fma_f32 v[4:5], v[242:243], v[236:237], v[4:5] op_sel_hi:[1,0,1]
	v_cvt_pk_f32_fp8_sdwa v[242:243], v189 src0_sel:WORD_1
	v_pk_fma_f32 v[6:7], v[244:245], v[236:237], v[6:7] op_sel_hi:[1,0,1]
	v_add_f32_e32 v215, v215, v236
	v_pk_fma_f32 v[0:1], v[240:241], v[236:237], v[0:1] op_sel_hi:[1,0,1]
	v_pk_fma_f32 v[2:3], v[242:243], v[236:237], v[2:3] op_sel_hi:[1,0,1]
	v_readlane_b32 s0, v95, 60
	s_lshl_b32 s0, s0, 10
	s_add_u32 s4, s6, s0
	s_addc_u32 s5, s7, 0
	global_load_dwordx4 v[186:189], v16, s[4:5]
	s_waitcnt vmcnt(15)
	v_cvt_pk_f32_fp8_e32 v[240:241], v190
	v_cvt_pk_f32_fp8_sdwa v[242:243], v190 src0_sel:WORD_1
	v_cvt_pk_f32_fp8_e32 v[244:245], v191
	v_pk_fma_f32 v[12:13], v[240:241], v[236:237], v[12:13] op_sel:[0,1,0]
	v_cvt_pk_f32_fp8_sdwa v[240:241], v191 src0_sel:WORD_1
	v_pk_fma_f32 v[14:15], v[242:243], v[236:237], v[14:15] op_sel:[0,1,0]
	v_cvt_pk_f32_fp8_e32 v[242:243], v192
	v_sub_f32_e32 v238, v238, v216
	v_pk_fma_f32 v[8:9], v[244:245], v[236:237], v[8:9] op_sel:[0,1,0]
	v_cvt_pk_f32_fp8_sdwa v[244:245], v192 src0_sel:WORD_1
	v_pk_fma_f32 v[10:11], v[240:241], v[236:237], v[10:11] op_sel:[0,1,0]
	v_cvt_pk_f32_fp8_e32 v[240:241], v193
	v_exp_f32_e32 v238, v238
	v_pk_fma_f32 v[4:5], v[242:243], v[236:237], v[4:5] op_sel:[0,1,0]
	v_cvt_pk_f32_fp8_sdwa v[242:243], v193 src0_sel:WORD_1
	v_pk_fma_f32 v[6:7], v[244:245], v[236:237], v[6:7] op_sel:[0,1,0]
	v_add_f32_e32 v215, v215, v237
	v_pk_fma_f32 v[0:1], v[240:241], v[236:237], v[0:1] op_sel:[0,1,0]
	v_pk_fma_f32 v[2:3], v[242:243], v[236:237], v[2:3] op_sel:[0,1,0]
	v_readlane_b32 s0, v95, 61
	s_lshl_b32 s0, s0, 10
	s_add_u32 s4, s6, s0
	s_addc_u32 s5, s7, 0
	global_load_dwordx4 v[190:193], v16, s[4:5]
	s_waitcnt vmcnt(15)
	v_cvt_pk_f32_fp8_e32 v[240:241], v194
	v_cvt_pk_f32_fp8_sdwa v[242:243], v194 src0_sel:WORD_1
	v_cvt_pk_f32_fp8_e32 v[244:245], v195
	v_pk_fma_f32 v[12:13], v[240:241], v[238:239], v[12:13] op_sel_hi:[1,0,1]
	v_cvt_pk_f32_fp8_sdwa v[240:241], v195 src0_sel:WORD_1
	v_pk_fma_f32 v[14:15], v[242:243], v[238:239], v[14:15] op_sel_hi:[1,0,1]
	v_cvt_pk_f32_fp8_e32 v[242:243], v196
	v_sub_f32_e32 v239, v239, v216
	v_pk_fma_f32 v[8:9], v[244:245], v[238:239], v[8:9] op_sel_hi:[1,0,1]
	v_cvt_pk_f32_fp8_sdwa v[244:245], v196 src0_sel:WORD_1
	v_pk_fma_f32 v[10:11], v[240:241], v[238:239], v[10:11] op_sel_hi:[1,0,1]
	v_cvt_pk_f32_fp8_e32 v[240:241], v197
	v_exp_f32_e32 v239, v239
	v_pk_fma_f32 v[4:5], v[242:243], v[238:239], v[4:5] op_sel_hi:[1,0,1]
	v_cvt_pk_f32_fp8_sdwa v[242:243], v197 src0_sel:WORD_1
	v_pk_fma_f32 v[6:7], v[244:245], v[238:239], v[6:7] op_sel_hi:[1,0,1]
	v_add_f32_e32 v215, v215, v238
	v_pk_fma_f32 v[0:1], v[240:241], v[238:239], v[0:1] op_sel_hi:[1,0,1]
	v_pk_fma_f32 v[2:3], v[242:243], v[238:239], v[2:3] op_sel_hi:[1,0,1]
	v_readlane_b32 s0, v95, 62
	s_lshl_b32 s0, s0, 10
	s_add_u32 s4, s6, s0
	s_addc_u32 s5, s7, 0
	global_load_dwordx4 v[194:197], v16, s[4:5]
	s_waitcnt vmcnt(15)
	v_cvt_pk_f32_fp8_e32 v[240:241], v198
	v_cvt_pk_f32_fp8_sdwa v[242:243], v198 src0_sel:WORD_1
	v_cvt_pk_f32_fp8_e32 v[244:245], v199
	v_pk_fma_f32 v[12:13], v[240:241], v[238:239], v[12:13] op_sel:[0,1,0]
	v_cvt_pk_f32_fp8_sdwa v[240:241], v199 src0_sel:WORD_1
	v_pk_fma_f32 v[14:15], v[242:243], v[238:239], v[14:15] op_sel:[0,1,0]
	v_cvt_pk_f32_fp8_e32 v[242:243], v200
	v_add_f32_e32 v215, v215, v239
	v_pk_fma_f32 v[8:9], v[244:245], v[238:239], v[8:9] op_sel:[0,1,0]
	v_cvt_pk_f32_fp8_sdwa v[244:245], v200 src0_sel:WORD_1
	v_pk_fma_f32 v[10:11], v[240:241], v[238:239], v[10:11] op_sel:[0,1,0]
	v_cvt_pk_f32_fp8_e32 v[240:241], v201
	v_pk_fma_f32 v[4:5], v[242:243], v[238:239], v[4:5] op_sel:[0,1,0]
	v_cvt_pk_f32_fp8_sdwa v[242:243], v201 src0_sel:WORD_1
	v_pk_fma_f32 v[6:7], v[244:245], v[238:239], v[6:7] op_sel:[0,1,0]
	v_pk_fma_f32 v[0:1], v[240:241], v[238:239], v[0:1] op_sel:[0,1,0]
	v_pk_fma_f32 v[2:3], v[242:243], v[238:239], v[2:3] op_sel:[0,1,0]
	v_readlane_b32 s0, v95, 63
	s_lshl_b32 s0, s0, 10
	s_add_u32 s4, s6, s0
	s_addc_u32 s5, s7, 0
	global_load_dwordx4 v[198:201], v16, s[4:5]
	s_waitcnt vmcnt(15)
	v_cvt_pk_f32_fp8_e32 v[240:241], v136
	v_cvt_pk_f32_fp8_sdwa v[242:243], v136 src0_sel:WORD_1
	v_cvt_pk_f32_fp8_e32 v[244:245], v137
	v_cvt_pk_f32_fp8_sdwa v[202:203], v137 src0_sel:WORD_1
	v_pk_mul_f32 v[204:205], v[240:241], v[36:37]
	v_pk_mul_f32 v[206:207], v[242:243], v[38:39]
	v_cvt_pk_f32_fp8_e32 v[240:241], v138
	v_cvt_pk_f32_fp8_sdwa v[242:243], v138 src0_sel:WORD_1
	v_pk_fma_f32 v[204:205], v[244:245], v[40:41], v[204:205]
	v_pk_fma_f32 v[206:207], v[202:203], v[42:43], v[206:207]
	v_cvt_pk_f32_fp8_e32 v[244:245], v139
	v_cvt_pk_f32_fp8_sdwa v[202:203], v139 src0_sel:WORD_1
	v_pk_fma_f32 v[204:205], v[240:241], v[44:45], v[204:205]
	v_pk_fma_f32 v[206:207], v[242:243], v[46:47], v[206:207]
	v_pk_fma_f32 v[204:205], v[244:245], v[48:49], v[204:205]
	v_pk_fma_f32 v[206:207], v[202:203], v[50:51], v[206:207]
	v_readlane_b32 s0, v95, 48
	s_lshl_b32 s0, s0, 10
	s_add_u32 s4, s8, s0
	s_addc_u32 s5, s9, 0
	global_load_dwordx4 v[136:139], v16, s[4:5]
	v_pk_add_f32 v[204:205], v[204:205], v[206:207]
	s_nop 0
	v_add_f32_e32 v235, v204, v205
	s_waitcnt vmcnt(15)
; DI float sum8(float v) { v += DPPF(v, 0xB1); v += DPPF(v, 0x4E); v += DPPF(v, 0x141); return v; }
; DI void topk_phase(const bf16_t* PROJ, const unsigned char* K8, const unsigned char* V8, const unsigned short* SC, bf16_t* ODSA, int c, char* smem, int bid, int nb) {
;     ...
;     for (int jj = 0; jj < 64; ++jj) {
;       const int j = wid * 64 + jj;
;       {
;         const size_t ro = (size_t)__builtin_amdgcn_readlane(mysel, jj) * 1024 + lane * 16;
;         const uint4 a = *(const uint4*)(K8 + ro), vv = *(const uint4*)(V8 + ro);
;         const unsigned w[4] = {a.x, a.y, a.z, a.w}, u[4] = {vv.x, vv.y, vv.z, vv.w};
;         float da = 0.f;
; #pragma unroll
;         for (int i = 0; i < 4; ++i) {
;           const f32x2v lo = __builtin_amdgcn_cvt_pk_f32_fp8((int)w[i], false), hi = __builtin_amdgcn_cvt_pk_f32_fp8((int)w[i], true);
;           da += qv[4 * i] * lo[0] + qv[4 * i + 1] * lo[1] + qv[4 * i + 2] * hi[0] + qv[4 * i + 3] * hi[1];
;         }
;         da = sum8(da);
;         da = j < count ? da : -3e30f;
;         const float mn = fmaxf(m_run, da), al = __builtin_amdgcn_exp2f(m_run - mn), pp = __builtin_amdgcn_exp2f(da - mn);
	v_cvt_pk_f32_fp8_e32 v[240:241], v140
	v_cvt_pk_f32_fp8_sdwa v[242:243], v140 src0_sel:WORD_1
	v_cvt_pk_f32_fp8_e32 v[244:245], v141
	v_cvt_pk_f32_fp8_sdwa v[202:203], v141 src0_sel:WORD_1
	v_add_f32_dpp v235, v235, v235 quad_perm:[1,0,3,2] row_mask:0xf bank_mask:0xf bound_ctrl:1
	v_pk_mul_f32 v[204:205], v[240:241], v[36:37]
	v_pk_mul_f32 v[206:207], v[242:243], v[38:39]
	v_add_f32_dpp v235, v235, v235 quad_perm:[2,3,0,1] row_mask:0xf bank_mask:0xf bound_ctrl:1
	v_cvt_pk_f32_fp8_e32 v[240:241], v142
	v_cvt_pk_f32_fp8_sdwa v[242:243], v142 src0_sel:WORD_1
	v_add_f32_dpp v235, v235, v235 row_half_mirror row_mask:0xf bank_mask:0xf bound_ctrl:1
	v_pk_fma_f32 v[204:205], v[244:245], v[40:41], v[204:205]
	v_pk_fma_f32 v[206:207], v[202:203], v[42:43], v[206:207]
	s_add_i32 s0, s1, 48
	s_cmp_lt_i32 s0, s2
	s_cselect_b64 vcc, -1, 0
	v_cvt_pk_f32_fp8_e32 v[244:245], v143
	v_cvt_pk_f32_fp8_sdwa v[202:203], v143 src0_sel:WORD_1
	v_cndmask_b32_e32 v210, v220, v235, vcc
	v_pk_fma_f32 v[204:205], v[240:241], v[44:45], v[204:205]
	v_pk_fma_f32 v[206:207], v[242:243], v[46:47], v[206:207]
	v_pk_fma_f32 v[204:205], v[244:245], v[48:49], v[204:205]
	v_pk_fma_f32 v[206:207], v[202:203], v[50:51], v[206:207]
	v_readlane_b32 s0, v95, 49
	s_lshl_b32 s0, s0, 10
	s_add_u32 s4, s8, s0
	s_addc_u32 s5, s9, 0
	global_load_dwordx4 v[140:143], v16, s[4:5]
	v_pk_add_f32 v[204:205], v[204:205], v[206:207]
	s_nop 0
	v_add_f32_e32 v221, v204, v205
	s_waitcnt vmcnt(15)
	v_cvt_pk_f32_fp8_e32 v[240:241], v144
	v_cvt_pk_f32_fp8_sdwa v[242:243], v144 src0_sel:WORD_1
	v_cvt_pk_f32_fp8_e32 v[244:245], v145
	v_cvt_pk_f32_fp8_sdwa v[202:203], v145 src0_sel:WORD_1
	v_add_f32_dpp v221, v221, v221 quad_perm:[1,0,3,2] row_mask:0xf bank_mask:0xf bound_ctrl:1
	v_pk_mul_f32 v[204:205], v[240:241], v[36:37]
	v_pk_mul_f32 v[206:207], v[242:243], v[38:39]
	v_add_f32_dpp v221, v221, v221 quad_perm:[2,3,0,1] row_mask:0xf bank_mask:0xf bound_ctrl:1
	v_cvt_pk_f32_fp8_e32 v[240:241], v146
	v_cvt_pk_f32_fp8_sdwa v[242:243], v146 src0_sel:WORD_1
	v_add_f32_dpp v221, v221, v221 row_half_mirror row_mask:0xf bank_mask:0xf bound_ctrl:1
	v_pk_fma_f32 v[204:205], v[244:245], v[40:41], v[204:205]
	v_pk_fma_f32 v[206:207], v[202:203], v[42:43], v[206:207]
	s_add_i32 s0, s1, 49
	s_cmp_lt_i32 s0, s2
	s_cselect_b64 vcc, -1, 0
	v_cvt_pk_f32_fp8_e32 v[244:245], v147
	v_cvt_pk_f32_fp8_sdwa v[202:203], v147 src0_sel:WORD_1
	v_cndmask_b32_e32 v211, v220, v221, vcc
	v_pk_fma_f32 v[204:205], v[240:241], v[44:45], v[204:205]
	v_pk_fma_f32 v[206:207], v[242:243], v[46:47], v[206:207]
	v_pk_fma_f32 v[204:205], v[244:245], v[48:49], v[204:205]
	v_pk_fma_f32 v[206:207], v[202:203], v[50:51], v[206:207]
	v_readlane_b32 s0, v95, 50
	s_lshl_b32 s0, s0, 10
	s_add_u32 s4, s8, s0
	s_addc_u32 s5, s9, 0
	global_load_dwordx4 v[144:147], v16, s[4:5]
	v_pk_add_f32 v[204:205], v[204:205], v[206:207]
	s_nop 0
	v_add_f32_e32 v235, v204, v205
	s_waitcnt vmcnt(15)
	v_cvt_pk_f32_fp8_e32 v[240:241], v148
	v_cvt_pk_f32_fp8_sdwa v[242:243], v148 src0_sel:WORD_1
	v_cvt_pk_f32_fp8_e32 v[244:245], v149
	v_cvt_pk_f32_fp8_sdwa v[202:203], v149 src0_sel:WORD_1
	v_add_f32_dpp v235, v235, v235 quad_perm:[1,0,3,2] row_mask:0xf bank_mask:0xf bound_ctrl:1
	v_pk_mul_f32 v[204:205], v[240:241], v[36:37]
	v_pk_mul_f32 v[206:207], v[242:243], v[38:39]
	v_add_f32_dpp v235, v235, v235 quad_perm:[2,3,0,1] row_mask:0xf bank_mask:0xf bound_ctrl:1
	v_cvt_pk_f32_fp8_e32 v[240:241], v150
	v_cvt_pk_f32_fp8_sdwa v[242:243], v150 src0_sel:WORD_1
	v_add_f32_dpp v235, v235, v235 row_half_mirror row_mask:0xf bank_mask:0xf bound_ctrl:1
	v_pk_fma_f32 v[204:205], v[244:245], v[40:41], v[204:205]
	v_pk_fma_f32 v[206:207], v[202:203], v[42:43], v[206:207]
	s_add_i32 s0, s1, 50
	s_cmp_lt_i32 s0, s2
	s_cselect_b64 vcc, -1, 0
	v_cvt_pk_f32_fp8_e32 v[244:245], v151
	v_cvt_pk_f32_fp8_sdwa v[202:203], v151 src0_sel:WORD_1
	v_cndmask_b32_e32 v212, v220, v235, vcc
	v_pk_fma_f32 v[204:205], v[240:241], v[44:45], v[204:205]
	v_pk_fma_f32 v[206:207], v[242:243], v[46:47], v[206:207]
	v_pk_fma_f32 v[204:205], v[244:245], v[48:49], v[204:205]
	v_pk_fma_f32 v[206:207], v[202:203], v[50:51], v[206:207]
	v_readlane_b32 s0, v95, 51
	s_lshl_b32 s0, s0, 10
	s_add_u32 s4, s8, s0
	s_addc_u32 s5, s9, 0
	global_load_dwordx4 v[148:151], v16, s[4:5]
	v_pk_add_f32 v[204:205], v[204:205], v[206:207]
	s_nop 0
	v_add_f32_e32 v221, v204, v205
	s_waitcnt vmcnt(15)
	v_cvt_pk_f32_fp8_e32 v[240:241], v152
	v_cvt_pk_f32_fp8_sdwa v[242:243], v152 src0_sel:WORD_1
	v_cvt_pk_f32_fp8_e32 v[244:245], v153
	v_cvt_pk_f32_fp8_sdwa v[202:203], v153 src0_sel:WORD_1
	v_add_f32_dpp v221, v221, v221 quad_perm:[1,0,3,2] row_mask:0xf bank_mask:0xf bound_ctrl:1
	v_pk_mul_f32 v[204:205], v[240:241], v[36:37]
	v_pk_mul_f32 v[206:207], v[242:243], v[38:39]
	v_add_f32_dpp v221, v221, v221 quad_perm:[2,3,0,1] row_mask:0xf bank_mask:0xf bound_ctrl:1
	v_cvt_pk_f32_fp8_e32 v[240:241], v154
	v_cvt_pk_f32_fp8_sdwa v[242:243], v154 src0_sel:WORD_1
	v_add_f32_dpp v221, v221, v221 row_half_mirror row_mask:0xf bank_mask:0xf bound_ctrl:1
	v_pk_fma_f32 v[204:205], v[244:245], v[40:41], v[204:205]
	v_pk_fma_f32 v[206:207], v[202:203], v[42:43], v[206:207]
	s_add_i32 s0, s1, 51
	s_cmp_lt_i32 s0, s2
	s_cselect_b64 vcc, -1, 0
	v_cvt_pk_f32_fp8_e32 v[244:245], v155
	v_cvt_pk_f32_fp8_sdwa v[202:203], v155 src0_sel:WORD_1
	v_cndmask_b32_e32 v213, v220, v221, vcc
	v_pk_fma_f32 v[204:205], v[240:241], v[44:45], v[204:205]
	v_pk_fma_f32 v[206:207], v[242:243], v[46:47], v[206:207]
	v_pk_fma_f32 v[204:205], v[244:245], v[48:49], v[204:205]
	v_pk_fma_f32 v[206:207], v[202:203], v[50:51], v[206:207]
	v_readlane_b32 s0, v95, 52
	s_lshl_b32 s0, s0, 10
	s_add_u32 s4, s8, s0
	s_addc_u32 s5, s9, 0
	global_load_dwordx4 v[152:155], v16, s[4:5]
	v_pk_add_f32 v[204:205], v[204:205], v[206:207]
	s_nop 0
	v_add_f32_e32 v235, v204, v205
	s_waitcnt vmcnt(15)
; DI float sum8(float v) { v += DPPF(v, 0xB1); v += DPPF(v, 0x4E); v += DPPF(v, 0x141); return v; }
; DI void topk_phase(const bf16_t* PROJ, const unsigned char* K8, const unsigned char* V8, const unsigned short* SC, bf16_t* ODSA, int c, char* smem, int bid, int nb) {
;     ...
;     for (int jj = 0; jj < 64; ++jj) {
;       const int j = wid * 64 + jj;
;       {
;         const size_t ro = (size_t)__builtin_amdgcn_readlane(mysel, jj) * 1024 + lane * 16;
;         const uint4 a = *(const uint4*)(K8 + ro), vv = *(const uint4*)(V8 + ro);
;         const unsigned w[4] = {a.x, a.y, a.z, a.w}, u[4] = {vv.x, vv.y, vv.z, vv.w};
;         float da = 0.f;
; #pragma unroll
;         for (int i = 0; i < 4; ++i) {
;           const f32x2v lo = __builtin_amdgcn_cvt_pk_f32_fp8((int)w[i], false), hi = __builtin_amdgcn_cvt_pk_f32_fp8((int)w[i], true);
;           da += qv[4 * i] * lo[0] + qv[4 * i + 1] * lo[1] + qv[4 * i + 2] * hi[0] + qv[4 * i + 3] * hi[1];
;         }
;         da = sum8(da);
;         da = j < count ? da : -3e30f;
;         const float mn = fmaxf(m_run, da), al = __builtin_amdgcn_exp2f(m_run - mn), pp = __builtin_amdgcn_exp2f(da - mn);
	v_cvt_pk_f32_fp8_e32 v[240:241], v156
	v_cvt_pk_f32_fp8_sdwa v[242:243], v156 src0_sel:WORD_1
	v_cvt_pk_f32_fp8_e32 v[244:245], v157
	v_cvt_pk_f32_fp8_sdwa v[202:203], v157 src0_sel:WORD_1
	v_add_f32_dpp v235, v235, v235 quad_perm:[1,0,3,2] row_mask:0xf bank_mask:0xf bound_ctrl:1
	v_pk_mul_f32 v[204:205], v[240:241], v[36:37]
	v_pk_mul_f32 v[206:207], v[242:243], v[38:39]
	v_add_f32_dpp v235, v235, v235 quad_perm:[2,3,0,1] row_mask:0xf bank_mask:0xf bound_ctrl:1
	v_cvt_pk_f32_fp8_e32 v[240:241], v158
	v_cvt_pk_f32_fp8_sdwa v[242:243], v158 src0_sel:WORD_1
	v_add_f32_dpp v235, v235, v235 row_half_mirror row_mask:0xf bank_mask:0xf bound_ctrl:1
	v_pk_fma_f32 v[204:205], v[244:245], v[40:41], v[204:205]
	v_pk_fma_f32 v[206:207], v[202:203], v[42:43], v[206:207]
	s_add_i32 s0, s1, 52
	s_cmp_lt_i32 s0, s2
	s_cselect_b64 vcc, -1, 0
	v_cvt_pk_f32_fp8_e32 v[244:245], v159
	v_cvt_pk_f32_fp8_sdwa v[202:203], v159 src0_sel:WORD_1
	v_cndmask_b32_e32 v226, v220, v235, vcc
	v_pk_fma_f32 v[204:205], v[240:241], v[44:45], v[204:205]
	v_pk_fma_f32 v[206:207], v[242:243], v[46:47], v[206:207]
	v_pk_fma_f32 v[204:205], v[244:245], v[48:49], v[204:205]
	v_pk_fma_f32 v[206:207], v[202:203], v[50:51], v[206:207]
	v_readlane_b32 s0, v95, 53
	s_lshl_b32 s0, s0, 10
	s_add_u32 s4, s8, s0
	s_addc_u32 s5, s9, 0
	global_load_dwordx4 v[156:159], v16, s[4:5]
	v_pk_add_f32 v[204:205], v[204:205], v[206:207]
	s_nop 0
	v_add_f32_e32 v221, v204, v205
	s_waitcnt vmcnt(15)
	v_cvt_pk_f32_fp8_e32 v[240:241], v160
	v_cvt_pk_f32_fp8_sdwa v[242:243], v160 src0_sel:WORD_1
	v_cvt_pk_f32_fp8_e32 v[244:245], v161
	v_cvt_pk_f32_fp8_sdwa v[202:203], v161 src0_sel:WORD_1
	v_add_f32_dpp v221, v221, v221 quad_perm:[1,0,3,2] row_mask:0xf bank_mask:0xf bound_ctrl:1
	v_pk_mul_f32 v[204:205], v[240:241], v[36:37]
	v_pk_mul_f32 v[206:207], v[242:243], v[38:39]
	v_add_f32_dpp v221, v221, v221 quad_perm:[2,3,0,1] row_mask:0xf bank_mask:0xf bound_ctrl:1
	v_cvt_pk_f32_fp8_e32 v[240:241], v162
	v_cvt_pk_f32_fp8_sdwa v[242:243], v162 src0_sel:WORD_1
	v_add_f32_dpp v221, v221, v221 row_half_mirror row_mask:0xf bank_mask:0xf bound_ctrl:1
	v_pk_fma_f32 v[204:205], v[244:245], v[40:41], v[204:205]
	v_pk_fma_f32 v[206:207], v[202:203], v[42:43], v[206:207]
	s_add_i32 s0, s1, 53
	s_cmp_lt_i32 s0, s2
	s_cselect_b64 vcc, -1, 0
	v_cvt_pk_f32_fp8_e32 v[244:245], v163
	v_cvt_pk_f32_fp8_sdwa v[202:203], v163 src0_sel:WORD_1
	v_cndmask_b32_e32 v227, v220, v221, vcc
	v_pk_fma_f32 v[204:205], v[240:241], v[44:45], v[204:205]
	v_pk_fma_f32 v[206:207], v[242:243], v[46:47], v[206:207]
	v_pk_fma_f32 v[204:205], v[244:245], v[48:49], v[204:205]
	v_pk_fma_f32 v[206:207], v[202:203], v[50:51], v[206:207]
	v_readlane_b32 s0, v95, 54
	s_lshl_b32 s0, s0, 10
	s_add_u32 s4, s8, s0
	s_addc_u32 s5, s9, 0
	global_load_dwordx4 v[160:163], v16, s[4:5]
	v_pk_add_f32 v[204:205], v[204:205], v[206:207]
	s_nop 0
	v_add_f32_e32 v235, v204, v205
	s_waitcnt vmcnt(15)
	v_cvt_pk_f32_fp8_e32 v[240:241], v164
	v_cvt_pk_f32_fp8_sdwa v[242:243], v164 src0_sel:WORD_1
	v_cvt_pk_f32_fp8_e32 v[244:245], v165
	v_cvt_pk_f32_fp8_sdwa v[202:203], v165 src0_sel:WORD_1
	v_add_f32_dpp v235, v235, v235 quad_perm:[1,0,3,2] row_mask:0xf bank_mask:0xf bound_ctrl:1
	v_pk_mul_f32 v[204:205], v[240:241], v[36:37]
	v_pk_mul_f32 v[206:207], v[242:243], v[38:39]
	v_add_f32_dpp v235, v235, v235 quad_perm:[2,3,0,1] row_mask:0xf bank_mask:0xf bound_ctrl:1
	v_cvt_pk_f32_fp8_e32 v[240:241], v166
	v_cvt_pk_f32_fp8_sdwa v[242:243], v166 src0_sel:WORD_1
	v_add_f32_dpp v235, v235, v235 row_half_mirror row_mask:0xf bank_mask:0xf bound_ctrl:1
	v_pk_fma_f32 v[204:205], v[244:245], v[40:41], v[204:205]
	v_pk_fma_f32 v[206:207], v[202:203], v[42:43], v[206:207]
	s_add_i32 s0, s1, 54
	s_cmp_lt_i32 s0, s2
	s_cselect_b64 vcc, -1, 0
	v_cvt_pk_f32_fp8_e32 v[244:245], v167
	v_cvt_pk_f32_fp8_sdwa v[202:203], v167 src0_sel:WORD_1
	v_cndmask_b32_e32 v228, v220, v235, vcc
	v_pk_fma_f32 v[204:205], v[240:241], v[44:45], v[204:205]
	v_pk_fma_f32 v[206:207], v[242:243], v[46:47], v[206:207]
	v_pk_fma_f32 v[204:205], v[244:245], v[48:49], v[204:205]
	v_pk_fma_f32 v[206:207], v[202:203], v[50:51], v[206:207]
	v_readlane_b32 s0, v95, 55
	s_lshl_b32 s0, s0, 10
	s_add_u32 s4, s8, s0
	s_addc_u32 s5, s9, 0
	global_load_dwordx4 v[164:167], v16, s[4:5]
	v_pk_add_f32 v[204:205], v[204:205], v[206:207]
	s_nop 0
	v_add_f32_e32 v221, v204, v205
	s_waitcnt vmcnt(15)
	v_cvt_pk_f32_fp8_e32 v[240:241], v168
	v_cvt_pk_f32_fp8_sdwa v[242:243], v168 src0_sel:WORD_1
	v_cvt_pk_f32_fp8_e32 v[244:245], v169
	v_cvt_pk_f32_fp8_sdwa v[202:203], v169 src0_sel:WORD_1
	v_add_f32_dpp v221, v221, v221 quad_perm:[1,0,3,2] row_mask:0xf bank_mask:0xf bound_ctrl:1
	v_pk_mul_f32 v[204:205], v[240:241], v[36:37]
	v_pk_mul_f32 v[206:207], v[242:243], v[38:39]
	v_add_f32_dpp v221, v221, v221 quad_perm:[2,3,0,1] row_mask:0xf bank_mask:0xf bound_ctrl:1
	v_cvt_pk_f32_fp8_e32 v[240:241], v170
	v_cvt_pk_f32_fp8_sdwa v[242:243], v170 src0_sel:WORD_1
	v_add_f32_dpp v221, v221, v221 row_half_mirror row_mask:0xf bank_mask:0xf bound_ctrl:1
	v_pk_fma_f32 v[204:205], v[244:245], v[40:41], v[204:205]
	v_pk_fma_f32 v[206:207], v[202:203], v[42:43], v[206:207]
	s_add_i32 s0, s1, 55
	s_cmp_lt_i32 s0, s2
	s_cselect_b64 vcc, -1, 0
	v_cvt_pk_f32_fp8_e32 v[244:245], v171
	v_cvt_pk_f32_fp8_sdwa v[202:203], v171 src0_sel:WORD_1
	v_cndmask_b32_e32 v229, v220, v221, vcc
	v_pk_fma_f32 v[204:205], v[240:241], v[44:45], v[204:205]
	v_pk_fma_f32 v[206:207], v[242:243], v[46:47], v[206:207]
	v_pk_fma_f32 v[204:205], v[244:245], v[48:49], v[204:205]
	v_pk_fma_f32 v[206:207], v[202:203], v[50:51], v[206:207]
	v_readlane_b32 s0, v95, 56
	s_lshl_b32 s0, s0, 10
	s_add_u32 s4, s8, s0
	s_addc_u32 s5, s9, 0
	global_load_dwordx4 v[168:171], v16, s[4:5]
	v_pk_add_f32 v[204:205], v[204:205], v[206:207]
	s_nop 0
	v_add_f32_e32 v235, v204, v205
	s_waitcnt vmcnt(15)
; DI float sum8(float v) { v += DPPF(v, 0xB1); v += DPPF(v, 0x4E); v += DPPF(v, 0x141); return v; }
; DI void topk_phase(const bf16_t* PROJ, const unsigned char* K8, const unsigned char* V8, const unsigned short* SC, bf16_t* ODSA, int c, char* smem, int bid, int nb) {
;     ...
;     for (int jj = 0; jj < 64; ++jj) {
;       const int j = wid * 64 + jj;
;       {
;         const size_t ro = (size_t)__builtin_amdgcn_readlane(mysel, jj) * 1024 + lane * 16;
;         const uint4 a = *(const uint4*)(K8 + ro), vv = *(const uint4*)(V8 + ro);
;         const unsigned w[4] = {a.x, a.y, a.z, a.w}, u[4] = {vv.x, vv.y, vv.z, vv.w};
;         float da = 0.f;
; #pragma unroll
;         for (int i = 0; i < 4; ++i) {
;           const f32x2v lo = __builtin_amdgcn_cvt_pk_f32_fp8((int)w[i], false), hi = __builtin_amdgcn_cvt_pk_f32_fp8((int)w[i], true);
;           da += qv[4 * i] * lo[0] + qv[4 * i + 1] * lo[1] + qv[4 * i + 2] * hi[0] + qv[4 * i + 3] * hi[1];
;         }
;         da = sum8(da);
;         da = j < count ? da : -3e30f;
;         const float mn = fmaxf(m_run, da), al = __builtin_amdgcn_exp2f(m_run - mn), pp = __builtin_amdgcn_exp2f(da - mn);
	v_cvt_pk_f32_fp8_e32 v[240:241], v172
	v_cvt_pk_f32_fp8_sdwa v[242:243], v172 src0_sel:WORD_1
	v_cvt_pk_f32_fp8_e32 v[244:245], v173
	v_cvt_pk_f32_fp8_sdwa v[202:203], v173 src0_sel:WORD_1
	v_add_f32_dpp v235, v235, v235 quad_perm:[1,0,3,2] row_mask:0xf bank_mask:0xf bound_ctrl:1
	v_pk_mul_f32 v[204:205], v[240:241], v[36:37]
	v_pk_mul_f32 v[206:207], v[242:243], v[38:39]
	v_add_f32_dpp v235, v235, v235 quad_perm:[2,3,0,1] row_mask:0xf bank_mask:0xf bound_ctrl:1
	v_cvt_pk_f32_fp8_e32 v[240:241], v174
	v_cvt_pk_f32_fp8_sdwa v[242:243], v174 src0_sel:WORD_1
	v_add_f32_dpp v235, v235, v235 row_half_mirror row_mask:0xf bank_mask:0xf bound_ctrl:1
	v_pk_fma_f32 v[204:205], v[244:245], v[40:41], v[204:205]
	v_pk_fma_f32 v[206:207], v[202:203], v[42:43], v[206:207]
	s_add_i32 s0, s1, 56
	s_cmp_lt_i32 s0, s2
	s_cselect_b64 vcc, -1, 0
	v_cvt_pk_f32_fp8_e32 v[244:245], v175
	v_cvt_pk_f32_fp8_sdwa v[202:203], v175 src0_sel:WORD_1
	v_cndmask_b32_e32 v230, v220, v235, vcc
	v_pk_fma_f32 v[204:205], v[240:241], v[44:45], v[204:205]
	v_pk_fma_f32 v[206:207], v[242:243], v[46:47], v[206:207]
	v_pk_fma_f32 v[204:205], v[244:245], v[48:49], v[204:205]
	v_pk_fma_f32 v[206:207], v[202:203], v[50:51], v[206:207]
	v_readlane_b32 s0, v95, 57
	s_lshl_b32 s0, s0, 10
	s_add_u32 s4, s8, s0
	s_addc_u32 s5, s9, 0
	global_load_dwordx4 v[172:175], v16, s[4:5]
	v_pk_add_f32 v[204:205], v[204:205], v[206:207]
	s_nop 0
	v_add_f32_e32 v221, v204, v205
	s_waitcnt vmcnt(15)
	v_cvt_pk_f32_fp8_e32 v[240:241], v176
	v_cvt_pk_f32_fp8_sdwa v[242:243], v176 src0_sel:WORD_1
	v_cvt_pk_f32_fp8_e32 v[244:245], v177
	v_cvt_pk_f32_fp8_sdwa v[202:203], v177 src0_sel:WORD_1
	v_add_f32_dpp v221, v221, v221 quad_perm:[1,0,3,2] row_mask:0xf bank_mask:0xf bound_ctrl:1
	v_pk_mul_f32 v[204:205], v[240:241], v[36:37]
	v_pk_mul_f32 v[206:207], v[242:243], v[38:39]
	v_add_f32_dpp v221, v221, v221 quad_perm:[2,3,0,1] row_mask:0xf bank_mask:0xf bound_ctrl:1
	v_cvt_pk_f32_fp8_e32 v[240:241], v178
	v_cvt_pk_f32_fp8_sdwa v[242:243], v178 src0_sel:WORD_1
	v_add_f32_dpp v221, v221, v221 row_half_mirror row_mask:0xf bank_mask:0xf bound_ctrl:1
	v_pk_fma_f32 v[204:205], v[244:245], v[40:41], v[204:205]
	v_pk_fma_f32 v[206:207], v[202:203], v[42:43], v[206:207]
	s_add_i32 s0, s1, 57
	s_cmp_lt_i32 s0, s2
	s_cselect_b64 vcc, -1, 0
	v_cvt_pk_f32_fp8_e32 v[244:245], v179
	v_cvt_pk_f32_fp8_sdwa v[202:203], v179 src0_sel:WORD_1
	v_cndmask_b32_e32 v231, v220, v221, vcc
	v_pk_fma_f32 v[204:205], v[240:241], v[44:45], v[204:205]
	v_pk_fma_f32 v[206:207], v[242:243], v[46:47], v[206:207]
	v_pk_fma_f32 v[204:205], v[244:245], v[48:49], v[204:205]
	v_pk_fma_f32 v[206:207], v[202:203], v[50:51], v[206:207]
	v_readlane_b32 s0, v95, 58
	s_lshl_b32 s0, s0, 10
	s_add_u32 s4, s8, s0
	s_addc_u32 s5, s9, 0
	global_load_dwordx4 v[176:179], v16, s[4:5]
	v_pk_add_f32 v[204:205], v[204:205], v[206:207]
	s_nop 0
	v_add_f32_e32 v235, v204, v205
	s_waitcnt vmcnt(15)
	v_cvt_pk_f32_fp8_e32 v[240:241], v180
	v_cvt_pk_f32_fp8_sdwa v[242:243], v180 src0_sel:WORD_1
	v_cvt_pk_f32_fp8_e32 v[244:245], v181
	v_cvt_pk_f32_fp8_sdwa v[202:203], v181 src0_sel:WORD_1
	v_add_f32_dpp v235, v235, v235 quad_perm:[1,0,3,2] row_mask:0xf bank_mask:0xf bound_ctrl:1
	v_pk_mul_f32 v[204:205], v[240:241], v[36:37]
	v_pk_mul_f32 v[206:207], v[242:243], v[38:39]
	v_add_f32_dpp v235, v235, v235 quad_perm:[2,3,0,1] row_mask:0xf bank_mask:0xf bound_ctrl:1
	v_cvt_pk_f32_fp8_e32 v[240:241], v182
	v_cvt_pk_f32_fp8_sdwa v[242:243], v182 src0_sel:WORD_1
	v_add_f32_dpp v235, v235, v235 row_half_mirror row_mask:0xf bank_mask:0xf bound_ctrl:1
	v_pk_fma_f32 v[204:205], v[244:245], v[40:41], v[204:205]
	v_pk_fma_f32 v[206:207], v[202:203], v[42:43], v[206:207]
	s_add_i32 s0, s1, 58
	s_cmp_lt_i32 s0, s2
	s_cselect_b64 vcc, -1, 0
	v_cvt_pk_f32_fp8_e32 v[244:245], v183
	v_cvt_pk_f32_fp8_sdwa v[202:203], v183 src0_sel:WORD_1
	v_cndmask_b32_e32 v232, v220, v235, vcc
	v_pk_fma_f32 v[204:205], v[240:241], v[44:45], v[204:205]
	v_pk_fma_f32 v[206:207], v[242:243], v[46:47], v[206:207]
	v_pk_fma_f32 v[204:205], v[244:245], v[48:49], v[204:205]
	v_pk_fma_f32 v[206:207], v[202:203], v[50:51], v[206:207]
	v_readlane_b32 s0, v95, 59
	s_lshl_b32 s0, s0, 10
	s_add_u32 s4, s8, s0
	s_addc_u32 s5, s9, 0
	global_load_dwordx4 v[180:183], v16, s[4:5]
	v_pk_add_f32 v[204:205], v[204:205], v[206:207]
	s_nop 0
	v_add_f32_e32 v221, v204, v205
	s_waitcnt vmcnt(15)
	v_cvt_pk_f32_fp8_e32 v[240:241], v186
	v_cvt_pk_f32_fp8_sdwa v[242:243], v186 src0_sel:WORD_1
	v_cvt_pk_f32_fp8_e32 v[244:245], v187
	v_cvt_pk_f32_fp8_sdwa v[202:203], v187 src0_sel:WORD_1
	v_add_f32_dpp v221, v221, v221 quad_perm:[1,0,3,2] row_mask:0xf bank_mask:0xf bound_ctrl:1
	v_pk_mul_f32 v[204:205], v[240:241], v[36:37]
	v_pk_mul_f32 v[206:207], v[242:243], v[38:39]
	v_add_f32_dpp v221, v221, v221 quad_perm:[2,3,0,1] row_mask:0xf bank_mask:0xf bound_ctrl:1
	v_cvt_pk_f32_fp8_e32 v[240:241], v188
	v_cvt_pk_f32_fp8_sdwa v[242:243], v188 src0_sel:WORD_1
	v_add_f32_dpp v221, v221, v221 row_half_mirror row_mask:0xf bank_mask:0xf bound_ctrl:1
	v_pk_fma_f32 v[204:205], v[244:245], v[40:41], v[204:205]
	v_pk_fma_f32 v[206:207], v[202:203], v[42:43], v[206:207]
	s_add_i32 s0, s1, 59
	s_cmp_lt_i32 s0, s2
	s_cselect_b64 vcc, -1, 0
	v_cvt_pk_f32_fp8_e32 v[244:245], v189
	v_cvt_pk_f32_fp8_sdwa v[202:203], v189 src0_sel:WORD_1
	v_cndmask_b32_e32 v233, v220, v221, vcc
	v_pk_fma_f32 v[204:205], v[240:241], v[44:45], v[204:205]
	v_pk_fma_f32 v[206:207], v[242:243], v[46:47], v[206:207]
	v_pk_fma_f32 v[204:205], v[244:245], v[48:49], v[204:205]
	v_pk_fma_f32 v[206:207], v[202:203], v[50:51], v[206:207]
	v_readlane_b32 s0, v95, 60
	s_lshl_b32 s0, s0, 10
	s_add_u32 s4, s8, s0
	s_addc_u32 s5, s9, 0
	global_load_dwordx4 v[186:189], v16, s[4:5]
	v_pk_add_f32 v[204:205], v[204:205], v[206:207]
	s_nop 0
	v_add_f32_e32 v235, v204, v205
	s_waitcnt vmcnt(15)
; DI float sum8(float v) { v += DPPF(v, 0xB1); v += DPPF(v, 0x4E); v += DPPF(v, 0x141); return v; }
; DI void topk_phase(const bf16_t* PROJ, const unsigned char* K8, const unsigned char* V8, const unsigned short* SC, bf16_t* ODSA, int c, char* smem, int bid, int nb) {
;     ...
;         float da = 0.f;
; #pragma unroll
;         for (int i = 0; i < 4; ++i) {
;           const f32x2v lo = __builtin_amdgcn_cvt_pk_f32_fp8((int)w[i], false), hi = __builtin_amdgcn_cvt_pk_f32_fp8((int)w[i], true);
;           da += qv[4 * i] * lo[0] + qv[4 * i + 1] * lo[1] + qv[4 * i + 2] * hi[0] + qv[4 * i + 3] * hi[1];
;         }
;         da = sum8(da);
;         da = j < count ? da : -3e30f;
;         const float mn = fmaxf(m_run, da), al = __builtin_amdgcn_exp2f(m_run - mn), pp = __builtin_amdgcn_exp2f(da - mn);
;         m_run = mn; l_run = l_run * al + pp;
; #pragma unroll
;         for (int i = 0; i < 4; ++i) {
;           const f32x2v lo = __builtin_amdgcn_cvt_pk_f32_fp8((int)u[i], false), hi = __builtin_amdgcn_cvt_pk_f32_fp8((int)u[i], true);
;           ov[4 * i] = ov[4 * i] * al + pp * lo[0]; ov[4 * i + 1] = ov[4 * i + 1] * al + pp * lo[1];
;           ov[4 * i + 2] = ov[4 * i + 2] * al + pp * hi[0]; ov[4 * i + 3] = ov[4 * i + 3] * al + pp * hi[1];
;         }
	v_cvt_pk_f32_fp8_e32 v[240:241], v190
	v_cvt_pk_f32_fp8_sdwa v[242:243], v190 src0_sel:WORD_1
	v_cvt_pk_f32_fp8_e32 v[244:245], v191
	v_cvt_pk_f32_fp8_sdwa v[202:203], v191 src0_sel:WORD_1
	v_add_f32_dpp v235, v235, v235 quad_perm:[1,0,3,2] row_mask:0xf bank_mask:0xf bound_ctrl:1
	v_pk_mul_f32 v[204:205], v[240:241], v[36:37]
	v_pk_mul_f32 v[206:207], v[242:243], v[38:39]
	v_add_f32_dpp v235, v235, v235 quad_perm:[2,3,0,1] row_mask:0xf bank_mask:0xf bound_ctrl:1
	v_cvt_pk_f32_fp8_e32 v[240:241], v192
	v_cvt_pk_f32_fp8_sdwa v[242:243], v192 src0_sel:WORD_1
	v_add_f32_dpp v235, v235, v235 row_half_mirror row_mask:0xf bank_mask:0xf bound_ctrl:1
	v_pk_fma_f32 v[204:205], v[244:245], v[40:41], v[204:205]
	v_pk_fma_f32 v[206:207], v[202:203], v[42:43], v[206:207]
	s_add_i32 s0, s1, 60
	s_cmp_lt_i32 s0, s2
	s_cselect_b64 vcc, -1, 0
	v_cvt_pk_f32_fp8_e32 v[244:245], v193
	v_cvt_pk_f32_fp8_sdwa v[202:203], v193 src0_sel:WORD_1
	v_cndmask_b32_e32 v236, v220, v235, vcc
	v_pk_fma_f32 v[204:205], v[240:241], v[44:45], v[204:205]
	v_pk_fma_f32 v[206:207], v[242:243], v[46:47], v[206:207]
	v_pk_fma_f32 v[204:205], v[244:245], v[48:49], v[204:205]
	v_pk_fma_f32 v[206:207], v[202:203], v[50:51], v[206:207]
	v_readlane_b32 s0, v95, 61
	s_lshl_b32 s0, s0, 10
	s_add_u32 s4, s8, s0
	s_addc_u32 s5, s9, 0
	global_load_dwordx4 v[190:193], v16, s[4:5]
	v_pk_add_f32 v[204:205], v[204:205], v[206:207]
	s_nop 0
	v_add_f32_e32 v221, v204, v205
	s_waitcnt vmcnt(15)
	v_cvt_pk_f32_fp8_e32 v[240:241], v194
	v_cvt_pk_f32_fp8_sdwa v[242:243], v194 src0_sel:WORD_1
	v_cvt_pk_f32_fp8_e32 v[244:245], v195
	v_cvt_pk_f32_fp8_sdwa v[202:203], v195 src0_sel:WORD_1
	v_add_f32_dpp v221, v221, v221 quad_perm:[1,0,3,2] row_mask:0xf bank_mask:0xf bound_ctrl:1
	v_pk_mul_f32 v[204:205], v[240:241], v[36:37]
	v_pk_mul_f32 v[206:207], v[242:243], v[38:39]
	v_add_f32_dpp v221, v221, v221 quad_perm:[2,3,0,1] row_mask:0xf bank_mask:0xf bound_ctrl:1
	v_cvt_pk_f32_fp8_e32 v[240:241], v196
	v_cvt_pk_f32_fp8_sdwa v[242:243], v196 src0_sel:WORD_1
	v_add_f32_dpp v221, v221, v221 row_half_mirror row_mask:0xf bank_mask:0xf bound_ctrl:1
	v_pk_fma_f32 v[204:205], v[244:245], v[40:41], v[204:205]
	v_pk_fma_f32 v[206:207], v[202:203], v[42:43], v[206:207]
	s_add_i32 s0, s1, 61
	s_cmp_lt_i32 s0, s2
	s_cselect_b64 vcc, -1, 0
	v_cvt_pk_f32_fp8_e32 v[244:245], v197
	v_cvt_pk_f32_fp8_sdwa v[202:203], v197 src0_sel:WORD_1
	v_cndmask_b32_e32 v237, v220, v221, vcc
	v_pk_fma_f32 v[204:205], v[240:241], v[44:45], v[204:205]
	v_pk_fma_f32 v[206:207], v[242:243], v[46:47], v[206:207]
	v_pk_fma_f32 v[204:205], v[244:245], v[48:49], v[204:205]
	v_pk_fma_f32 v[206:207], v[202:203], v[50:51], v[206:207]
	v_readlane_b32 s0, v95, 62
	s_lshl_b32 s0, s0, 10
	s_add_u32 s4, s8, s0
	s_addc_u32 s5, s9, 0
	global_load_dwordx4 v[194:197], v16, s[4:5]
	v_pk_add_f32 v[204:205], v[204:205], v[206:207]
	s_nop 0
	v_add_f32_e32 v235, v204, v205
	s_waitcnt vmcnt(15)
	v_cvt_pk_f32_fp8_e32 v[240:241], v198
	v_cvt_pk_f32_fp8_sdwa v[242:243], v198 src0_sel:WORD_1
	v_cvt_pk_f32_fp8_e32 v[244:245], v199
	v_cvt_pk_f32_fp8_sdwa v[202:203], v199 src0_sel:WORD_1
	v_add_f32_dpp v235, v235, v235 quad_perm:[1,0,3,2] row_mask:0xf bank_mask:0xf bound_ctrl:1
	v_pk_mul_f32 v[204:205], v[240:241], v[36:37]
	v_pk_mul_f32 v[206:207], v[242:243], v[38:39]
	v_add_f32_dpp v235, v235, v235 quad_perm:[2,3,0,1] row_mask:0xf bank_mask:0xf bound_ctrl:1
	v_cvt_pk_f32_fp8_e32 v[240:241], v200
	v_cvt_pk_f32_fp8_sdwa v[242:243], v200 src0_sel:WORD_1
	v_add_f32_dpp v235, v235, v235 row_half_mirror row_mask:0xf bank_mask:0xf bound_ctrl:1
	v_pk_fma_f32 v[204:205], v[244:245], v[40:41], v[204:205]
	v_pk_fma_f32 v[206:207], v[202:203], v[42:43], v[206:207]
	s_add_i32 s0, s1, 62
	s_cmp_lt_i32 s0, s2
	s_cselect_b64 vcc, -1, 0
	v_cvt_pk_f32_fp8_e32 v[244:245], v201
	v_cvt_pk_f32_fp8_sdwa v[202:203], v201 src0_sel:WORD_1
	v_cndmask_b32_e32 v238, v220, v235, vcc
	v_pk_fma_f32 v[204:205], v[240:241], v[44:45], v[204:205]
	v_pk_fma_f32 v[206:207], v[242:243], v[46:47], v[206:207]
	v_pk_fma_f32 v[204:205], v[244:245], v[48:49], v[204:205]
	v_pk_fma_f32 v[206:207], v[202:203], v[50:51], v[206:207]
	v_readlane_b32 s0, v95, 63
	s_lshl_b32 s0, s0, 10
	s_add_u32 s4, s8, s0
	s_addc_u32 s5, s9, 0
	global_load_dwordx4 v[198:201], v16, s[4:5]
	v_pk_add_f32 v[204:205], v[204:205], v[206:207]
	s_nop 0
	v_add_f32_e32 v221, v204, v205
	s_nop 1
	v_add_f32_dpp v221, v221, v221 quad_perm:[1,0,3,2] row_mask:0xf bank_mask:0xf bound_ctrl:1
	s_nop 1
	v_add_f32_dpp v221, v221, v221 quad_perm:[2,3,0,1] row_mask:0xf bank_mask:0xf bound_ctrl:1
	s_nop 1
	v_add_f32_dpp v221, v221, v221 row_half_mirror row_mask:0xf bank_mask:0xf bound_ctrl:1
	s_add_i32 s0, s1, 63
	s_cmp_lt_i32 s0, s2
	s_cselect_b64 vcc, -1, 0
	s_nop 1
	v_cndmask_b32_e32 v239, v220, v221, vcc
	v_max3_f32 v224, v210, v211, v212
	v_max3_f32 v224, v224, v213, v226
	v_max3_f32 v224, v224, v227, v228
	v_max3_f32 v224, v224, v229, v230
	v_max3_f32 v224, v224, v231, v232
	v_max3_f32 v224, v224, v233, v236
	v_max3_f32 v224, v224, v237, v238
	v_max_f32_e32 v224, v224, v239
	v_max_f32_e32 v221, v216, v224
	v_sub_f32_e32 v184, v216, v221
	v_exp_f32_e32 v184, v184
	v_mov_b32_e32 v216, v221
	s_nop 0
	v_pk_mul_f32 v[12:13], v[12:13], v[184:185] op_sel_hi:[1,0]
	v_pk_mul_f32 v[14:15], v[14:15], v[184:185] op_sel_hi:[1,0]
	v_pk_mul_f32 v[8:9], v[8:9], v[184:185] op_sel_hi:[1,0]
	v_pk_mul_f32 v[10:11], v[10:11], v[184:185] op_sel_hi:[1,0]
	v_pk_mul_f32 v[4:5], v[4:5], v[184:185] op_sel_hi:[1,0]
	v_pk_mul_f32 v[6:7], v[6:7], v[184:185] op_sel_hi:[1,0]
	v_pk_mul_f32 v[0:1], v[0:1], v[184:185] op_sel_hi:[1,0]
	v_pk_mul_f32 v[2:3], v[2:3], v[184:185] op_sel_hi:[1,0]
	v_mul_f32_e32 v215, v215, v184
	v_sub_f32_e32 v210, v210, v216
	v_exp_f32_e32 v210, v210
	s_waitcnt vmcnt(15)
; DI void topk_phase(const bf16_t* PROJ, const unsigned char* K8, const unsigned char* V8, const unsigned short* SC, bf16_t* ODSA, int c, char* smem, int bid, int nb) {
;     ...
;         const float mn = fmaxf(m_run, da), al = __builtin_amdgcn_exp2f(m_run - mn), pp = __builtin_amdgcn_exp2f(da - mn);
;         m_run = mn; l_run = l_run * al + pp;
; #pragma unroll
;         for (int i = 0; i < 4; ++i) {
;           const f32x2v lo = __builtin_amdgcn_cvt_pk_f32_fp8((int)u[i], false), hi = __builtin_amdgcn_cvt_pk_f32_fp8((int)u[i], true);
;           ov[4 * i] = ov[4 * i] * al + pp * lo[0]; ov[4 * i + 1] = ov[4 * i + 1] * al + pp * lo[1];
;           ov[4 * i + 2] = ov[4 * i + 2] * al + pp * hi[0]; ov[4 * i + 3] = ov[4 * i + 3] * al + pp * hi[1];
;         }
	v_cvt_pk_f32_fp8_e32 v[240:241], v136
	v_cvt_pk_f32_fp8_sdwa v[242:243], v136 src0_sel:WORD_1
	v_cvt_pk_f32_fp8_e32 v[244:245], v137
	v_pk_fma_f32 v[12:13], v[240:241], v[210:211], v[12:13] op_sel_hi:[1,0,1]
	v_cvt_pk_f32_fp8_sdwa v[240:241], v137 src0_sel:WORD_1
	v_pk_fma_f32 v[14:15], v[242:243], v[210:211], v[14:15] op_sel_hi:[1,0,1]
	v_cvt_pk_f32_fp8_e32 v[242:243], v138
	v_sub_f32_e32 v211, v211, v216
	v_pk_fma_f32 v[8:9], v[244:245], v[210:211], v[8:9] op_sel_hi:[1,0,1]
	v_cvt_pk_f32_fp8_sdwa v[244:245], v138 src0_sel:WORD_1
	v_pk_fma_f32 v[10:11], v[240:241], v[210:211], v[10:11] op_sel_hi:[1,0,1]
	v_cvt_pk_f32_fp8_e32 v[240:241], v139
	v_exp_f32_e32 v211, v211
	v_pk_fma_f32 v[4:5], v[242:243], v[210:211], v[4:5] op_sel_hi:[1,0,1]
	v_cvt_pk_f32_fp8_sdwa v[242:243], v139 src0_sel:WORD_1
	v_pk_fma_f32 v[6:7], v[244:245], v[210:211], v[6:7] op_sel_hi:[1,0,1]
	v_add_f32_e32 v215, v215, v210
	v_pk_fma_f32 v[0:1], v[240:241], v[210:211], v[0:1] op_sel_hi:[1,0,1]
	v_pk_fma_f32 v[2:3], v[242:243], v[210:211], v[2:3] op_sel_hi:[1,0,1]
	s_waitcnt vmcnt(14)
	v_cvt_pk_f32_fp8_e32 v[240:241], v140
	v_cvt_pk_f32_fp8_sdwa v[242:243], v140 src0_sel:WORD_1
	v_cvt_pk_f32_fp8_e32 v[244:245], v141
	v_pk_fma_f32 v[12:13], v[240:241], v[210:211], v[12:13] op_sel:[0,1,0]
	v_cvt_pk_f32_fp8_sdwa v[240:241], v141 src0_sel:WORD_1
	v_pk_fma_f32 v[14:15], v[242:243], v[210:211], v[14:15] op_sel:[0,1,0]
	v_cvt_pk_f32_fp8_e32 v[242:243], v142
	v_sub_f32_e32 v212, v212, v216
	v_pk_fma_f32 v[8:9], v[244:245], v[210:211], v[8:9] op_sel:[0,1,0]
	v_cvt_pk_f32_fp8_sdwa v[244:245], v142 src0_sel:WORD_1
	v_pk_fma_f32 v[10:11], v[240:241], v[210:211], v[10:11] op_sel:[0,1,0]
	v_cvt_pk_f32_fp8_e32 v[240:241], v143
	v_exp_f32_e32 v212, v212
	v_pk_fma_f32 v[4:5], v[242:243], v[210:211], v[4:5] op_sel:[0,1,0]
	v_cvt_pk_f32_fp8_sdwa v[242:243], v143 src0_sel:WORD_1
	v_pk_fma_f32 v[6:7], v[244:245], v[210:211], v[6:7] op_sel:[0,1,0]
	v_add_f32_e32 v215, v215, v211
	v_pk_fma_f32 v[0:1], v[240:241], v[210:211], v[0:1] op_sel:[0,1,0]
	v_pk_fma_f32 v[2:3], v[242:243], v[210:211], v[2:3] op_sel:[0,1,0]
	s_waitcnt vmcnt(13)
	v_cvt_pk_f32_fp8_e32 v[240:241], v144
	v_cvt_pk_f32_fp8_sdwa v[242:243], v144 src0_sel:WORD_1
	v_cvt_pk_f32_fp8_e32 v[244:245], v145
	v_pk_fma_f32 v[12:13], v[240:241], v[212:213], v[12:13] op_sel_hi:[1,0,1]
	v_cvt_pk_f32_fp8_sdwa v[240:241], v145 src0_sel:WORD_1
	v_pk_fma_f32 v[14:15], v[242:243], v[212:213], v[14:15] op_sel_hi:[1,0,1]
	v_cvt_pk_f32_fp8_e32 v[242:243], v146
	v_sub_f32_e32 v213, v213, v216
	v_pk_fma_f32 v[8:9], v[244:245], v[212:213], v[8:9] op_sel_hi:[1,0,1]
	v_cvt_pk_f32_fp8_sdwa v[244:245], v146 src0_sel:WORD_1
	v_pk_fma_f32 v[10:11], v[240:241], v[212:213], v[10:11] op_sel_hi:[1,0,1]
	v_cvt_pk_f32_fp8_e32 v[240:241], v147
	v_exp_f32_e32 v213, v213
	v_pk_fma_f32 v[4:5], v[242:243], v[212:213], v[4:5] op_sel_hi:[1,0,1]
	v_cvt_pk_f32_fp8_sdwa v[242:243], v147 src0_sel:WORD_1
	v_pk_fma_f32 v[6:7], v[244:245], v[212:213], v[6:7] op_sel_hi:[1,0,1]
	v_add_f32_e32 v215, v215, v212
	v_pk_fma_f32 v[0:1], v[240:241], v[212:213], v[0:1] op_sel_hi:[1,0,1]
	v_pk_fma_f32 v[2:3], v[242:243], v[212:213], v[2:3] op_sel_hi:[1,0,1]
	s_waitcnt vmcnt(12)
	v_cvt_pk_f32_fp8_e32 v[240:241], v148
	v_cvt_pk_f32_fp8_sdwa v[242:243], v148 src0_sel:WORD_1
	v_cvt_pk_f32_fp8_e32 v[244:245], v149
	v_pk_fma_f32 v[12:13], v[240:241], v[212:213], v[12:13] op_sel:[0,1,0]
	v_cvt_pk_f32_fp8_sdwa v[240:241], v149 src0_sel:WORD_1
	v_pk_fma_f32 v[14:15], v[242:243], v[212:213], v[14:15] op_sel:[0,1,0]
	v_cvt_pk_f32_fp8_e32 v[242:243], v150
	v_sub_f32_e32 v226, v226, v216
	v_pk_fma_f32 v[8:9], v[244:245], v[212:213], v[8:9] op_sel:[0,1,0]
	v_cvt_pk_f32_fp8_sdwa v[244:245], v150 src0_sel:WORD_1
	v_pk_fma_f32 v[10:11], v[240:241], v[212:213], v[10:11] op_sel:[0,1,0]
	v_cvt_pk_f32_fp8_e32 v[240:241], v151
	v_exp_f32_e32 v226, v226
	v_pk_fma_f32 v[4:5], v[242:243], v[212:213], v[4:5] op_sel:[0,1,0]
	v_cvt_pk_f32_fp8_sdwa v[242:243], v151 src0_sel:WORD_1
	v_pk_fma_f32 v[6:7], v[244:245], v[212:213], v[6:7] op_sel:[0,1,0]
	v_add_f32_e32 v215, v215, v213
	v_pk_fma_f32 v[0:1], v[240:241], v[212:213], v[0:1] op_sel:[0,1,0]
	v_pk_fma_f32 v[2:3], v[242:243], v[212:213], v[2:3] op_sel:[0,1,0]
	s_waitcnt vmcnt(11)
	v_cvt_pk_f32_fp8_e32 v[240:241], v152
	v_cvt_pk_f32_fp8_sdwa v[242:243], v152 src0_sel:WORD_1
	v_cvt_pk_f32_fp8_e32 v[244:245], v153
	v_pk_fma_f32 v[12:13], v[240:241], v[226:227], v[12:13] op_sel_hi:[1,0,1]
	v_cvt_pk_f32_fp8_sdwa v[240:241], v153 src0_sel:WORD_1
	v_pk_fma_f32 v[14:15], v[242:243], v[226:227], v[14:15] op_sel_hi:[1,0,1]
	v_cvt_pk_f32_fp8_e32 v[242:243], v154
	v_sub_f32_e32 v227, v227, v216
	v_pk_fma_f32 v[8:9], v[244:245], v[226:227], v[8:9] op_sel_hi:[1,0,1]
	v_cvt_pk_f32_fp8_sdwa v[244:245], v154 src0_sel:WORD_1
	v_pk_fma_f32 v[10:11], v[240:241], v[226:227], v[10:11] op_sel_hi:[1,0,1]
	v_cvt_pk_f32_fp8_e32 v[240:241], v155
	v_exp_f32_e32 v227, v227
	v_pk_fma_f32 v[4:5], v[242:243], v[226:227], v[4:5] op_sel_hi:[1,0,1]
	v_cvt_pk_f32_fp8_sdwa v[242:243], v155 src0_sel:WORD_1
	v_pk_fma_f32 v[6:7], v[244:245], v[226:227], v[6:7] op_sel_hi:[1,0,1]
	v_add_f32_e32 v215, v215, v226
	v_pk_fma_f32 v[0:1], v[240:241], v[226:227], v[0:1] op_sel_hi:[1,0,1]
	v_pk_fma_f32 v[2:3], v[242:243], v[226:227], v[2:3] op_sel_hi:[1,0,1]
	s_waitcnt vmcnt(10)
; DI void topk_phase(const bf16_t* PROJ, const unsigned char* K8, const unsigned char* V8, const unsigned short* SC, bf16_t* ODSA, int c, char* smem, int bid, int nb) {
;     ...
;         const float mn = fmaxf(m_run, da), al = __builtin_amdgcn_exp2f(m_run - mn), pp = __builtin_amdgcn_exp2f(da - mn);
;         m_run = mn; l_run = l_run * al + pp;
; #pragma unroll
;         for (int i = 0; i < 4; ++i) {
;           const f32x2v lo = __builtin_amdgcn_cvt_pk_f32_fp8((int)u[i], false), hi = __builtin_amdgcn_cvt_pk_f32_fp8((int)u[i], true);
;           ov[4 * i] = ov[4 * i] * al + pp * lo[0]; ov[4 * i + 1] = ov[4 * i + 1] * al + pp * lo[1];
;           ov[4 * i + 2] = ov[4 * i + 2] * al + pp * hi[0]; ov[4 * i + 3] = ov[4 * i + 3] * al + pp * hi[1];
;         }
	v_cvt_pk_f32_fp8_e32 v[240:241], v156
	v_cvt_pk_f32_fp8_sdwa v[242:243], v156 src0_sel:WORD_1
	v_cvt_pk_f32_fp8_e32 v[244:245], v157
	v_pk_fma_f32 v[12:13], v[240:241], v[226:227], v[12:13] op_sel:[0,1,0]
	v_cvt_pk_f32_fp8_sdwa v[240:241], v157 src0_sel:WORD_1
	v_pk_fma_f32 v[14:15], v[242:243], v[226:227], v[14:15] op_sel:[0,1,0]
	v_cvt_pk_f32_fp8_e32 v[242:243], v158
	v_sub_f32_e32 v228, v228, v216
	v_pk_fma_f32 v[8:9], v[244:245], v[226:227], v[8:9] op_sel:[0,1,0]
	v_cvt_pk_f32_fp8_sdwa v[244:245], v158 src0_sel:WORD_1
	v_pk_fma_f32 v[10:11], v[240:241], v[226:227], v[10:11] op_sel:[0,1,0]
	v_cvt_pk_f32_fp8_e32 v[240:241], v159
	v_exp_f32_e32 v228, v228
	v_pk_fma_f32 v[4:5], v[242:243], v[226:227], v[4:5] op_sel:[0,1,0]
	v_cvt_pk_f32_fp8_sdwa v[242:243], v159 src0_sel:WORD_1
	v_pk_fma_f32 v[6:7], v[244:245], v[226:227], v[6:7] op_sel:[0,1,0]
	v_add_f32_e32 v215, v215, v227
	v_pk_fma_f32 v[0:1], v[240:241], v[226:227], v[0:1] op_sel:[0,1,0]
	v_pk_fma_f32 v[2:3], v[242:243], v[226:227], v[2:3] op_sel:[0,1,0]
	s_waitcnt vmcnt(9)
	v_cvt_pk_f32_fp8_e32 v[240:241], v160
	v_cvt_pk_f32_fp8_sdwa v[242:243], v160 src0_sel:WORD_1
	v_cvt_pk_f32_fp8_e32 v[244:245], v161
	v_pk_fma_f32 v[12:13], v[240:241], v[228:229], v[12:13] op_sel_hi:[1,0,1]
	v_cvt_pk_f32_fp8_sdwa v[240:241], v161 src0_sel:WORD_1
	v_pk_fma_f32 v[14:15], v[242:243], v[228:229], v[14:15] op_sel_hi:[1,0,1]
	v_cvt_pk_f32_fp8_e32 v[242:243], v162
	v_sub_f32_e32 v229, v229, v216
	v_pk_fma_f32 v[8:9], v[244:245], v[228:229], v[8:9] op_sel_hi:[1,0,1]
	v_cvt_pk_f32_fp8_sdwa v[244:245], v162 src0_sel:WORD_1
	v_pk_fma_f32 v[10:11], v[240:241], v[228:229], v[10:11] op_sel_hi:[1,0,1]
	v_cvt_pk_f32_fp8_e32 v[240:241], v163
	v_exp_f32_e32 v229, v229
	v_pk_fma_f32 v[4:5], v[242:243], v[228:229], v[4:5] op_sel_hi:[1,0,1]
	v_cvt_pk_f32_fp8_sdwa v[242:243], v163 src0_sel:WORD_1
	v_pk_fma_f32 v[6:7], v[244:245], v[228:229], v[6:7] op_sel_hi:[1,0,1]
	v_add_f32_e32 v215, v215, v228
	v_pk_fma_f32 v[0:1], v[240:241], v[228:229], v[0:1] op_sel_hi:[1,0,1]
	v_pk_fma_f32 v[2:3], v[242:243], v[228:229], v[2:3] op_sel_hi:[1,0,1]
	s_waitcnt vmcnt(8)
	v_cvt_pk_f32_fp8_e32 v[240:241], v164
	v_cvt_pk_f32_fp8_sdwa v[242:243], v164 src0_sel:WORD_1
	v_cvt_pk_f32_fp8_e32 v[244:245], v165
	v_pk_fma_f32 v[12:13], v[240:241], v[228:229], v[12:13] op_sel:[0,1,0]
	v_cvt_pk_f32_fp8_sdwa v[240:241], v165 src0_sel:WORD_1
	v_pk_fma_f32 v[14:15], v[242:243], v[228:229], v[14:15] op_sel:[0,1,0]
	v_cvt_pk_f32_fp8_e32 v[242:243], v166
	v_sub_f32_e32 v230, v230, v216
	v_pk_fma_f32 v[8:9], v[244:245], v[228:229], v[8:9] op_sel:[0,1,0]
	v_cvt_pk_f32_fp8_sdwa v[244:245], v166 src0_sel:WORD_1
	v_pk_fma_f32 v[10:11], v[240:241], v[228:229], v[10:11] op_sel:[0,1,0]
	v_cvt_pk_f32_fp8_e32 v[240:241], v167
	v_exp_f32_e32 v230, v230
	v_pk_fma_f32 v[4:5], v[242:243], v[228:229], v[4:5] op_sel:[0,1,0]
	v_cvt_pk_f32_fp8_sdwa v[242:243], v167 src0_sel:WORD_1
	v_pk_fma_f32 v[6:7], v[244:245], v[228:229], v[6:7] op_sel:[0,1,0]
	v_add_f32_e32 v215, v215, v229
	v_pk_fma_f32 v[0:1], v[240:241], v[228:229], v[0:1] op_sel:[0,1,0]
	v_pk_fma_f32 v[2:3], v[242:243], v[228:229], v[2:3] op_sel:[0,1,0]
	s_waitcnt vmcnt(7)
	v_cvt_pk_f32_fp8_e32 v[240:241], v168
	v_cvt_pk_f32_fp8_sdwa v[242:243], v168 src0_sel:WORD_1
	v_cvt_pk_f32_fp8_e32 v[244:245], v169
	v_pk_fma_f32 v[12:13], v[240:241], v[230:231], v[12:13] op_sel_hi:[1,0,1]
	v_cvt_pk_f32_fp8_sdwa v[240:241], v169 src0_sel:WORD_1
	v_pk_fma_f32 v[14:15], v[242:243], v[230:231], v[14:15] op_sel_hi:[1,0,1]
	v_cvt_pk_f32_fp8_e32 v[242:243], v170
	v_sub_f32_e32 v231, v231, v216
	v_pk_fma_f32 v[8:9], v[244:245], v[230:231], v[8:9] op_sel_hi:[1,0,1]
	v_cvt_pk_f32_fp8_sdwa v[244:245], v170 src0_sel:WORD_1
	v_pk_fma_f32 v[10:11], v[240:241], v[230:231], v[10:11] op_sel_hi:[1,0,1]
	v_cvt_pk_f32_fp8_e32 v[240:241], v171
	v_exp_f32_e32 v231, v231
	v_pk_fma_f32 v[4:5], v[242:243], v[230:231], v[4:5] op_sel_hi:[1,0,1]
	v_cvt_pk_f32_fp8_sdwa v[242:243], v171 src0_sel:WORD_1
	v_pk_fma_f32 v[6:7], v[244:245], v[230:231], v[6:7] op_sel_hi:[1,0,1]
	v_add_f32_e32 v215, v215, v230
	v_pk_fma_f32 v[0:1], v[240:241], v[230:231], v[0:1] op_sel_hi:[1,0,1]
	v_pk_fma_f32 v[2:3], v[242:243], v[230:231], v[2:3] op_sel_hi:[1,0,1]
	s_waitcnt vmcnt(6)
	v_cvt_pk_f32_fp8_e32 v[240:241], v172
	v_cvt_pk_f32_fp8_sdwa v[242:243], v172 src0_sel:WORD_1
	v_cvt_pk_f32_fp8_e32 v[244:245], v173
	v_pk_fma_f32 v[12:13], v[240:241], v[230:231], v[12:13] op_sel:[0,1,0]
	v_cvt_pk_f32_fp8_sdwa v[240:241], v173 src0_sel:WORD_1
	v_pk_fma_f32 v[14:15], v[242:243], v[230:231], v[14:15] op_sel:[0,1,0]
	v_cvt_pk_f32_fp8_e32 v[242:243], v174
	v_sub_f32_e32 v232, v232, v216
	v_pk_fma_f32 v[8:9], v[244:245], v[230:231], v[8:9] op_sel:[0,1,0]
	v_cvt_pk_f32_fp8_sdwa v[244:245], v174 src0_sel:WORD_1
	v_pk_fma_f32 v[10:11], v[240:241], v[230:231], v[10:11] op_sel:[0,1,0]
	v_cvt_pk_f32_fp8_e32 v[240:241], v175
	v_exp_f32_e32 v232, v232
	v_pk_fma_f32 v[4:5], v[242:243], v[230:231], v[4:5] op_sel:[0,1,0]
	v_cvt_pk_f32_fp8_sdwa v[242:243], v175 src0_sel:WORD_1
	v_pk_fma_f32 v[6:7], v[244:245], v[230:231], v[6:7] op_sel:[0,1,0]
	v_add_f32_e32 v215, v215, v231
	v_pk_fma_f32 v[0:1], v[240:241], v[230:231], v[0:1] op_sel:[0,1,0]
	v_pk_fma_f32 v[2:3], v[242:243], v[230:231], v[2:3] op_sel:[0,1,0]
	s_waitcnt vmcnt(5)
; DI void topk_phase(const bf16_t* PROJ, const unsigned char* K8, const unsigned char* V8, const unsigned short* SC, bf16_t* ODSA, int c, char* smem, int bid, int nb) {
;     ...
;         const float mn = fmaxf(m_run, da), al = __builtin_amdgcn_exp2f(m_run - mn), pp = __builtin_amdgcn_exp2f(da - mn);
;         m_run = mn; l_run = l_run * al + pp;
; #pragma unroll
;         for (int i = 0; i < 4; ++i) {
;           const f32x2v lo = __builtin_amdgcn_cvt_pk_f32_fp8((int)u[i], false), hi = __builtin_amdgcn_cvt_pk_f32_fp8((int)u[i], true);
;           ov[4 * i] = ov[4 * i] * al + pp * lo[0]; ov[4 * i + 1] = ov[4 * i + 1] * al + pp * lo[1];
;           ov[4 * i + 2] = ov[4 * i + 2] * al + pp * hi[0]; ov[4 * i + 3] = ov[4 * i + 3] * al + pp * hi[1];
;         }
;       }
;     }
;     if ((lane & 7) == 0) { sS[wid * 8 + hd] = m_run; sS[32 + wid * 8 + hd] = l_run; }
	v_cvt_pk_f32_fp8_e32 v[240:241], v176
	v_cvt_pk_f32_fp8_sdwa v[242:243], v176 src0_sel:WORD_1
	v_cvt_pk_f32_fp8_e32 v[244:245], v177
	v_pk_fma_f32 v[12:13], v[240:241], v[232:233], v[12:13] op_sel_hi:[1,0,1]
	v_cvt_pk_f32_fp8_sdwa v[240:241], v177 src0_sel:WORD_1
	v_pk_fma_f32 v[14:15], v[242:243], v[232:233], v[14:15] op_sel_hi:[1,0,1]
	v_cvt_pk_f32_fp8_e32 v[242:243], v178
	v_sub_f32_e32 v233, v233, v216
	v_pk_fma_f32 v[8:9], v[244:245], v[232:233], v[8:9] op_sel_hi:[1,0,1]
	v_cvt_pk_f32_fp8_sdwa v[244:245], v178 src0_sel:WORD_1
	v_pk_fma_f32 v[10:11], v[240:241], v[232:233], v[10:11] op_sel_hi:[1,0,1]
	v_cvt_pk_f32_fp8_e32 v[240:241], v179
	v_exp_f32_e32 v233, v233
	v_pk_fma_f32 v[4:5], v[242:243], v[232:233], v[4:5] op_sel_hi:[1,0,1]
	v_cvt_pk_f32_fp8_sdwa v[242:243], v179 src0_sel:WORD_1
	v_pk_fma_f32 v[6:7], v[244:245], v[232:233], v[6:7] op_sel_hi:[1,0,1]
	v_add_f32_e32 v215, v215, v232
	v_pk_fma_f32 v[0:1], v[240:241], v[232:233], v[0:1] op_sel_hi:[1,0,1]
	v_pk_fma_f32 v[2:3], v[242:243], v[232:233], v[2:3] op_sel_hi:[1,0,1]
	s_waitcnt vmcnt(4)
	v_cvt_pk_f32_fp8_e32 v[240:241], v180
	v_cvt_pk_f32_fp8_sdwa v[242:243], v180 src0_sel:WORD_1
	v_cvt_pk_f32_fp8_e32 v[244:245], v181
	v_pk_fma_f32 v[12:13], v[240:241], v[232:233], v[12:13] op_sel:[0,1,0]
	v_cvt_pk_f32_fp8_sdwa v[240:241], v181 src0_sel:WORD_1
	v_pk_fma_f32 v[14:15], v[242:243], v[232:233], v[14:15] op_sel:[0,1,0]
	v_cvt_pk_f32_fp8_e32 v[242:243], v182
	v_sub_f32_e32 v236, v236, v216
	v_pk_fma_f32 v[8:9], v[244:245], v[232:233], v[8:9] op_sel:[0,1,0]
	v_cvt_pk_f32_fp8_sdwa v[244:245], v182 src0_sel:WORD_1
	v_pk_fma_f32 v[10:11], v[240:241], v[232:233], v[10:11] op_sel:[0,1,0]
	v_cvt_pk_f32_fp8_e32 v[240:241], v183
	v_exp_f32_e32 v236, v236
	v_pk_fma_f32 v[4:5], v[242:243], v[232:233], v[4:5] op_sel:[0,1,0]
	v_cvt_pk_f32_fp8_sdwa v[242:243], v183 src0_sel:WORD_1
	v_pk_fma_f32 v[6:7], v[244:245], v[232:233], v[6:7] op_sel:[0,1,0]
	v_add_f32_e32 v215, v215, v233
	v_pk_fma_f32 v[0:1], v[240:241], v[232:233], v[0:1] op_sel:[0,1,0]
	v_pk_fma_f32 v[2:3], v[242:243], v[232:233], v[2:3] op_sel:[0,1,0]
	s_waitcnt vmcnt(3)
	v_cvt_pk_f32_fp8_e32 v[240:241], v186
	v_cvt_pk_f32_fp8_sdwa v[242:243], v186 src0_sel:WORD_1
	v_cvt_pk_f32_fp8_e32 v[244:245], v187
	v_pk_fma_f32 v[12:13], v[240:241], v[236:237], v[12:13] op_sel_hi:[1,0,1]
	v_cvt_pk_f32_fp8_sdwa v[240:241], v187 src0_sel:WORD_1
	v_pk_fma_f32 v[14:15], v[242:243], v[236:237], v[14:15] op_sel_hi:[1,0,1]
	v_cvt_pk_f32_fp8_e32 v[242:243], v188
	v_sub_f32_e32 v237, v237, v216
	v_pk_fma_f32 v[8:9], v[244:245], v[236:237], v[8:9] op_sel_hi:[1,0,1]
	v_cvt_pk_f32_fp8_sdwa v[244:245], v188 src0_sel:WORD_1
	v_pk_fma_f32 v[10:11], v[240:241], v[236:237], v[10:11] op_sel_hi:[1,0,1]
	v_cvt_pk_f32_fp8_e32 v[240:241], v189
	v_exp_f32_e32 v237, v237
	v_pk_fma_f32 v[4:5], v[242:243], v[236:237], v[4:5] op_sel_hi:[1,0,1]
	v_cvt_pk_f32_fp8_sdwa v[242:243], v189 src0_sel:WORD_1
	v_pk_fma_f32 v[6:7], v[244:245], v[236:237], v[6:7] op_sel_hi:[1,0,1]
	v_add_f32_e32 v215, v215, v236
	v_pk_fma_f32 v[0:1], v[240:241], v[236:237], v[0:1] op_sel_hi:[1,0,1]
	v_pk_fma_f32 v[2:3], v[242:243], v[236:237], v[2:3] op_sel_hi:[1,0,1]
	s_waitcnt vmcnt(2)
	v_cvt_pk_f32_fp8_e32 v[240:241], v190
	v_cvt_pk_f32_fp8_sdwa v[242:243], v190 src0_sel:WORD_1
	v_cvt_pk_f32_fp8_e32 v[244:245], v191
	v_pk_fma_f32 v[12:13], v[240:241], v[236:237], v[12:13] op_sel:[0,1,0]
	v_cvt_pk_f32_fp8_sdwa v[240:241], v191 src0_sel:WORD_1
	v_pk_fma_f32 v[14:15], v[242:243], v[236:237], v[14:15] op_sel:[0,1,0]
	v_cvt_pk_f32_fp8_e32 v[242:243], v192
	v_sub_f32_e32 v238, v238, v216
	v_pk_fma_f32 v[8:9], v[244:245], v[236:237], v[8:9] op_sel:[0,1,0]
	v_cvt_pk_f32_fp8_sdwa v[244:245], v192 src0_sel:WORD_1
	v_pk_fma_f32 v[10:11], v[240:241], v[236:237], v[10:11] op_sel:[0,1,0]
	v_cvt_pk_f32_fp8_e32 v[240:241], v193
	v_exp_f32_e32 v238, v238
	v_pk_fma_f32 v[4:5], v[242:243], v[236:237], v[4:5] op_sel:[0,1,0]
	v_cvt_pk_f32_fp8_sdwa v[242:243], v193 src0_sel:WORD_1
	v_pk_fma_f32 v[6:7], v[244:245], v[236:237], v[6:7] op_sel:[0,1,0]
	v_add_f32_e32 v215, v215, v237
	v_pk_fma_f32 v[0:1], v[240:241], v[236:237], v[0:1] op_sel:[0,1,0]
	v_pk_fma_f32 v[2:3], v[242:243], v[236:237], v[2:3] op_sel:[0,1,0]
	s_waitcnt vmcnt(1)
	v_cvt_pk_f32_fp8_e32 v[240:241], v194
	v_cvt_pk_f32_fp8_sdwa v[242:243], v194 src0_sel:WORD_1
	v_cvt_pk_f32_fp8_e32 v[244:245], v195
	v_pk_fma_f32 v[12:13], v[240:241], v[238:239], v[12:13] op_sel_hi:[1,0,1]
	v_cvt_pk_f32_fp8_sdwa v[240:241], v195 src0_sel:WORD_1
	v_pk_fma_f32 v[14:15], v[242:243], v[238:239], v[14:15] op_sel_hi:[1,0,1]
	v_cvt_pk_f32_fp8_e32 v[242:243], v196
	v_sub_f32_e32 v239, v239, v216
	v_pk_fma_f32 v[8:9], v[244:245], v[238:239], v[8:9] op_sel_hi:[1,0,1]
	v_cvt_pk_f32_fp8_sdwa v[244:245], v196 src0_sel:WORD_1
	v_pk_fma_f32 v[10:11], v[240:241], v[238:239], v[10:11] op_sel_hi:[1,0,1]
	v_cvt_pk_f32_fp8_e32 v[240:241], v197
	v_exp_f32_e32 v239, v239
	v_pk_fma_f32 v[4:5], v[242:243], v[238:239], v[4:5] op_sel_hi:[1,0,1]
	v_cvt_pk_f32_fp8_sdwa v[242:243], v197 src0_sel:WORD_1
	v_pk_fma_f32 v[6:7], v[244:245], v[238:239], v[6:7] op_sel_hi:[1,0,1]
	v_add_f32_e32 v215, v215, v238
	v_pk_fma_f32 v[0:1], v[240:241], v[238:239], v[0:1] op_sel_hi:[1,0,1]
	v_pk_fma_f32 v[2:3], v[242:243], v[238:239], v[2:3] op_sel_hi:[1,0,1]
	s_waitcnt vmcnt(0)
	v_cvt_pk_f32_fp8_e32 v[240:241], v198
	v_cvt_pk_f32_fp8_sdwa v[242:243], v198 src0_sel:WORD_1
	v_cvt_pk_f32_fp8_e32 v[244:245], v199
	v_pk_fma_f32 v[12:13], v[240:241], v[238:239], v[12:13] op_sel:[0,1,0]
	v_cvt_pk_f32_fp8_sdwa v[240:241], v199 src0_sel:WORD_1
	v_pk_fma_f32 v[14:15], v[242:243], v[238:239], v[14:15] op_sel:[0,1,0]
	v_cvt_pk_f32_fp8_e32 v[242:243], v200
	v_add_f32_e32 v215, v215, v239
	v_pk_fma_f32 v[8:9], v[244:245], v[238:239], v[8:9] op_sel:[0,1,0]
	v_cvt_pk_f32_fp8_sdwa v[244:245], v200 src0_sel:WORD_1
	v_pk_fma_f32 v[10:11], v[240:241], v[238:239], v[10:11] op_sel:[0,1,0]
	v_cvt_pk_f32_fp8_e32 v[240:241], v201
	v_pk_fma_f32 v[4:5], v[242:243], v[238:239], v[4:5] op_sel:[0,1,0]
	v_cvt_pk_f32_fp8_sdwa v[242:243], v201 src0_sel:WORD_1
	v_pk_fma_f32 v[6:7], v[244:245], v[238:239], v[6:7] op_sel:[0,1,0]
	v_pk_fma_f32 v[0:1], v[240:241], v[238:239], v[0:1] op_sel:[0,1,0]
	v_pk_fma_f32 v[2:3], v[242:243], v[238:239], v[2:3] op_sel:[0,1,0]
	v_mov_b32_e32 v52, v215
	v_mov_b32_e32 v53, v216
	s_mov_b64 s[0:1], exec
	v_readlane_b32 s2, v250, 43
	v_readlane_b32 s3, v250, 44
	s_and_b64 s[2:3], s[0:1], s[2:3]
	s_mov_b64 exec, s[2:3]
	s_cbranch_execz .LBB0_1066
	ds_write2_b32 v94, v53, v52 offset1:32
	s_branch .LBB0_1066

; DI void topk_phase(const bf16_t* PROJ, const unsigned char* K8, const unsigned char* V8, const unsigned short* SC, bf16_t* ODSA, int c, char* smem, int bid, int nb) {
;     ...
;       unsigned T = 0u;
;       for (int b = 15; b >= 0; --b) {
;         const unsigned cand = T | (1u << b);
;         int cc = 0;
; #pragma unroll
;         for (int i = 0; i < 64; ++i) if ((i >> 2) * 1024 < n) cc += key[i] >= cand ? 1 : 0;
;         if (block_count(cc, b & 1, red) >= 256) T = cand;
;       }
;       int cg_ = 0, ce_ = 0;
; #pragma unroll
;       for (int i = 0; i < 64; ++i) if ((i >> 2) * 1024 < n) { cg_ += key[i] > T ? 1 : 0; ce_ += key[i] == T ? 1 : 0; }
;       if (tid == 0) cnts[0] = 0;
;       const int cgt = block_count(cg_, 2, red);
;       const int ceq = block_count(ce_, 3, red);
;       const int need = 256 - cgt;
;       int X = 0x7fffffff;
;       if (ceq != need) {
;         X = 0;
;         for (int b = 13; b >= 0; --b) {
;           const int cand = X | (1 << b);
;           int cc = 0;
; #pragma unroll
;           for (int i = 0; i < 64; ++i) if ((i >> 2) * 1024 < n) cc += (key[i] == T && ((i >> 2) * 256 + tid) * 4 + (i & 3) < cand) ? 1 : 0;
;           if (block_count(cc, b & 1, red) < need) X = cand;
;         }
;       }
; #pragma unroll
;       for (int i = 0; i < 64; ++i)
;         if ((i >> 2) * 1024 < n) {
;           const int idx = ((i >> 2) * 256 + tid) * 4 + (i & 3);
;           if (key[i] > T || (key[i] == T && idx <= X)) { const int ps = atomicAdd(&cnts[0], 1); sel[ps] = idx; }
.LBB0_1364:
	s_or_b64 exec, exec, s[8:9]
	v_max3_u32 v8, v40, v39, v38
	v_max3_u32 v8, v8, v37, v36
	v_max3_u32 v8, v8, v35, v34
	v_max3_u32 v8, v8, v32, v33
	v_max3_u32 v8, v8, v31, v30
	v_max3_u32 v8, v8, v29, v28
	v_max3_u32 v8, v8, v15, v14
	v_max_u32_e32 v8, v8, v12
	v_not_b32_e32 v8, v8
	s_nop 1
	v_max_u32_dpp v8, v8, v8 row_shr:1 row_mask:0xf bank_mask:0xf bound_ctrl:1
	s_nop 1
	v_max_u32_dpp v8, v8, v8 row_shr:2 row_mask:0xf bank_mask:0xf bound_ctrl:1
	s_nop 1
	v_max_u32_dpp v8, v8, v8 row_shr:4 row_mask:0xf bank_mask:0xf bound_ctrl:1
	s_nop 1
	v_max_u32_dpp v8, v8, v8 row_shr:8 row_mask:0xf bank_mask:0xf bound_ctrl:1
	s_nop 1
	v_readlane_b32 s0, v8, 15
	v_readlane_b32 s1, v8, 31
	v_readlane_b32 s22, v8, 47
	v_readlane_b32 s23, v8, 63
	s_max_u32 s0, s0, s1
	s_max_u32 s22, s22, s23
	s_max_u32 s0, s0, s22
	v_lshrrev_b32_e32 v10, 6, v214
	v_lshlrev_b32_e32 v10, 2, v10
	v_mov_b32_e32 v9, s0
	ds_write_b32 v10, v9 offset:1024
	s_waitcnt lgkmcnt(0)
	s_barrier
	ds_read_b128 v[168:171], v185 offset:1024
	s_waitcnt lgkmcnt(0)
	v_max3_u32 v9, v168, v169, v170
	v_max_u32_e32 v9, v9, v171
	v_not_b32_e32 v9, v9
	s_nop 1
	v_readfirstlane_b32 s0, v9
	s_nop 1
	s_cmp_eq_u32 s0, 0
	s_cbranch_scc1 .Lsel_fb_C
	s_mov_b32 s1, 0
	v_cmp_le_u32_e64 s[22:23], s0, v40
	v_cmp_le_u32_e64 s[24:25], s0, v39
	s_bcnt1_i32_b64 s26, s[22:23]
	s_add_i32 s1, s1, s26
	v_cmp_le_u32_e64 s[22:23], s0, v38
	s_bcnt1_i32_b64 s26, s[24:25]
	s_add_i32 s1, s1, s26
	v_cmp_le_u32_e64 s[24:25], s0, v37
	s_bcnt1_i32_b64 s26, s[22:23]
	s_add_i32 s1, s1, s26
	v_cmp_le_u32_e64 s[22:23], s0, v36
	s_bcnt1_i32_b64 s26, s[24:25]
	s_add_i32 s1, s1, s26
	v_cmp_le_u32_e64 s[24:25], s0, v35
	s_bcnt1_i32_b64 s26, s[22:23]
	s_add_i32 s1, s1, s26
	v_cmp_le_u32_e64 s[22:23], s0, v34
	s_bcnt1_i32_b64 s26, s[24:25]
	s_add_i32 s1, s1, s26
	v_cmp_le_u32_e64 s[24:25], s0, v32
	s_bcnt1_i32_b64 s26, s[22:23]
	s_add_i32 s1, s1, s26
	v_cmp_le_u32_e64 s[22:23], s0, v33
	s_bcnt1_i32_b64 s26, s[24:25]
	s_add_i32 s1, s1, s26
	v_cmp_le_u32_e64 s[24:25], s0, v31
	s_bcnt1_i32_b64 s26, s[22:23]
	s_add_i32 s1, s1, s26
	v_cmp_le_u32_e64 s[22:23], s0, v30
	s_bcnt1_i32_b64 s26, s[24:25]
	s_add_i32 s1, s1, s26
	v_cmp_le_u32_e64 s[24:25], s0, v29
	s_bcnt1_i32_b64 s26, s[22:23]
	s_add_i32 s1, s1, s26
	v_cmp_le_u32_e64 s[22:23], s0, v28
	s_bcnt1_i32_b64 s26, s[24:25]
	s_add_i32 s1, s1, s26
	v_cmp_le_u32_e64 s[24:25], s0, v15
	s_bcnt1_i32_b64 s26, s[22:23]
	s_add_i32 s1, s1, s26
	v_cmp_le_u32_e64 s[22:23], s0, v14
	s_bcnt1_i32_b64 s26, s[24:25]
	s_add_i32 s1, s1, s26
	v_cmp_le_u32_e64 s[24:25], s0, v12
	s_bcnt1_i32_b64 s26, s[22:23]
	s_add_i32 s1, s1, s26
	s_bcnt1_i32_b64 s26, s[24:25]
	s_add_i32 s1, s1, s26
	v_mov_b32_e32 v9, s1
	ds_write_b32 v10, v9 offset:1040
	s_waitcnt lgkmcnt(0)
	s_barrier
	ds_read_b128 v[168:171], v185 offset:1040
	s_waitcnt lgkmcnt(0)
	v_readfirstlane_b32 s24, v168
	v_readfirstlane_b32 s25, v169
	v_readfirstlane_b32 s26, v170
	v_readfirstlane_b32 s27, v171
	s_add_i32 s28, s24, s25
	s_add_i32 s28, s28, s26
	s_add_i32 s28, s28, s27
	s_cmp_gt_u32 s28, 0x800
	s_cbranch_scc1 .Lsel_fb_C
	v_readfirstlane_b32 s29, v10
	s_mov_b32 s31, s28
	s_mov_b32 s1, 0
	s_cmp_ge_u32 s29, 4
	s_cselect_b32 s30, s24, 0
	s_add_i32 s1, s1, s30
	s_cmp_ge_u32 s29, 8
	s_cselect_b32 s30, s25, 0
	s_add_i32 s1, s1, s30
	s_cmp_ge_u32 s29, 12
	s_cselect_b32 s30, s26, 0
	s_add_i32 s1, s1, s30
	v_cmp_le_u32_e64 s[22:23], s0, v40
	v_cmp_le_u32_e64 s[24:25], s0, v39
	s_nop 0
	v_mbcnt_lo_u32_b32 v9, s22, 0
	v_mbcnt_hi_u32_b32 v9, s23, v9
	v_add_lshl_u32 v11, v9, s1, 2
	s_bcnt1_i32_b64 s26, s[22:23]
	s_add_i32 s1, s1, s26
	s_mov_b64 exec, s[22:23]
	ds_write2st64_b32 v11, v40, v18 offset0:36 offset1:68
	s_mov_b64 exec, -1
	v_cmp_le_u32_e64 s[22:23], s0, v38
	v_mbcnt_lo_u32_b32 v9, s24, 0
	v_mbcnt_hi_u32_b32 v9, s25, v9
	v_add_lshl_u32 v11, v9, s1, 2
	s_bcnt1_i32_b64 s26, s[24:25]
	s_add_i32 s1, s1, s26
	s_mov_b64 exec, s[24:25]
	ds_write2st64_b32 v11, v39, v70 offset0:36 offset1:68
	s_mov_b64 exec, -1
	v_cmp_le_u32_e64 s[24:25], s0, v37
	v_mbcnt_lo_u32_b32 v9, s22, 0
	v_mbcnt_hi_u32_b32 v9, s23, v9
	v_add_lshl_u32 v11, v9, s1, 2
	s_bcnt1_i32_b64 s26, s[22:23]
	s_add_i32 s1, s1, s26
	s_mov_b64 exec, s[22:23]
	ds_write2st64_b32 v11, v38, v61 offset0:36 offset1:68
	s_mov_b64 exec, -1
	v_cmp_le_u32_e64 s[22:23], s0, v36
	v_mbcnt_lo_u32_b32 v9, s24, 0
	v_mbcnt_hi_u32_b32 v9, s25, v9
	v_add_lshl_u32 v11, v9, s1, 2
	s_bcnt1_i32_b64 s26, s[24:25]
	s_add_i32 s1, s1, s26
	s_mov_b64 exec, s[24:25]
	ds_write2st64_b32 v11, v37, v62 offset0:36 offset1:68
	s_mov_b64 exec, -1
	v_cmp_le_u32_e64 s[24:25], s0, v35
	v_mbcnt_lo_u32_b32 v9, s22, 0
	v_mbcnt_hi_u32_b32 v9, s23, v9
	v_add_lshl_u32 v11, v9, s1, 2
	s_bcnt1_i32_b64 s26, s[22:23]
	s_add_i32 s1, s1, s26
	s_mov_b64 exec, s[22:23]
	ds_write2st64_b32 v11, v36, v63 offset0:36 offset1:68
	s_mov_b64 exec, -1
	v_cmp_le_u32_e64 s[22:23], s0, v34
	v_mbcnt_lo_u32_b32 v9, s24, 0
	v_mbcnt_hi_u32_b32 v9, s25, v9
	v_add_lshl_u32 v11, v9, s1, 2
	s_bcnt1_i32_b64 s26, s[24:25]
	s_add_i32 s1, s1, s26
	s_mov_b64 exec, s[24:25]
	ds_write2st64_b32 v11, v35, v71 offset0:36 offset1:68
	s_mov_b64 exec, -1
	v_cmp_le_u32_e64 s[24:25], s0, v32
	v_mbcnt_lo_u32_b32 v9, s22, 0
	v_mbcnt_hi_u32_b32 v9, s23, v9
	v_add_lshl_u32 v11, v9, s1, 2
	s_bcnt1_i32_b64 s26, s[22:23]
	s_add_i32 s1, s1, s26
	s_mov_b64 exec, s[22:23]
	ds_write2st64_b32 v11, v34, v64 offset0:36 offset1:68
	s_mov_b64 exec, -1
	v_cmp_le_u32_e64 s[22:23], s0, v33
	v_mbcnt_lo_u32_b32 v9, s24, 0
	v_mbcnt_hi_u32_b32 v9, s25, v9
	v_add_lshl_u32 v11, v9, s1, 2
	s_bcnt1_i32_b64 s26, s[24:25]
	s_add_i32 s1, s1, s26
	s_mov_b64 exec, s[24:25]
	ds_write2st64_b32 v11, v32, v65 offset0:36 offset1:68
; DI void topk_phase(const bf16_t* PROJ, const unsigned char* K8, const unsigned char* V8, const unsigned short* SC, bf16_t* ODSA, int c, char* smem, int bid, int nb) {
;     ...
; #pragma unroll
;       for (int i = 0; i < 64; ++i)
;         if ((i >> 2) * 1024 < n) {
;           const int idx = ((i >> 2) * 256 + tid) * 4 + (i & 3);
;           if (key[i] > T || (key[i] == T && idx <= X)) { const int ps = atomicAdd(&cnts[0], 1); sel[ps] = idx; }
;         }
;     }
	s_mov_b64 exec, -1
	v_cmp_le_u32_e64 s[24:25], s0, v31
	v_mbcnt_lo_u32_b32 v9, s22, 0
	v_mbcnt_hi_u32_b32 v9, s23, v9
	v_add_lshl_u32 v11, v9, s1, 2
	s_bcnt1_i32_b64 s26, s[22:23]
	s_add_i32 s1, s1, s26
	s_mov_b64 exec, s[22:23]
	ds_write2st64_b32 v11, v33, v22 offset0:36 offset1:68
	s_mov_b64 exec, -1
	v_cmp_le_u32_e64 s[22:23], s0, v30
	v_mbcnt_lo_u32_b32 v9, s24, 0
	v_mbcnt_hi_u32_b32 v9, s25, v9
	v_add_lshl_u32 v11, v9, s1, 2
	s_bcnt1_i32_b64 s26, s[24:25]
	s_add_i32 s1, s1, s26
	s_mov_b64 exec, s[24:25]
	ds_write2st64_b32 v11, v31, v72 offset0:36 offset1:68
	s_mov_b64 exec, -1
	v_cmp_le_u32_e64 s[24:25], s0, v29
	v_mbcnt_lo_u32_b32 v9, s22, 0
	v_mbcnt_hi_u32_b32 v9, s23, v9
	v_add_lshl_u32 v11, v9, s1, 2
	s_bcnt1_i32_b64 s26, s[22:23]
	s_add_i32 s1, s1, s26
	s_mov_b64 exec, s[22:23]
	ds_write2st64_b32 v11, v30, v66 offset0:36 offset1:68
	s_mov_b64 exec, -1
	v_cmp_le_u32_e64 s[22:23], s0, v28
	v_mbcnt_lo_u32_b32 v9, s24, 0
	v_mbcnt_hi_u32_b32 v9, s25, v9
	v_add_lshl_u32 v11, v9, s1, 2
	s_bcnt1_i32_b64 s26, s[24:25]
	s_add_i32 s1, s1, s26
	s_mov_b64 exec, s[24:25]
	ds_write2st64_b32 v11, v29, v67 offset0:36 offset1:68
	s_mov_b64 exec, -1
	v_cmp_le_u32_e64 s[24:25], s0, v15
	v_mbcnt_lo_u32_b32 v9, s22, 0
	v_mbcnt_hi_u32_b32 v9, s23, v9
	v_add_lshl_u32 v11, v9, s1, 2
	s_bcnt1_i32_b64 s26, s[22:23]
	s_add_i32 s1, s1, s26
	s_mov_b64 exec, s[22:23]
	ds_write2st64_b32 v11, v28, v24 offset0:36 offset1:68
	s_mov_b64 exec, -1
	v_cmp_le_u32_e64 s[22:23], s0, v14
	v_mbcnt_lo_u32_b32 v9, s24, 0
	v_mbcnt_hi_u32_b32 v9, s25, v9
	v_add_lshl_u32 v11, v9, s1, 2
	s_bcnt1_i32_b64 s26, s[24:25]
	s_add_i32 s1, s1, s26
	s_mov_b64 exec, s[24:25]
	ds_write2st64_b32 v11, v15, v73 offset0:36 offset1:68
	s_mov_b64 exec, -1
	v_cmp_le_u32_e64 s[24:25], s0, v12
	v_mbcnt_lo_u32_b32 v9, s22, 0
	v_mbcnt_hi_u32_b32 v9, s23, v9
	v_add_lshl_u32 v11, v9, s1, 2
	s_bcnt1_i32_b64 s26, s[22:23]
	s_add_i32 s1, s1, s26
	s_mov_b64 exec, s[22:23]
	ds_write2st64_b32 v11, v14, v68 offset0:36 offset1:68
	s_mov_b64 exec, -1
	v_mbcnt_lo_u32_b32 v9, s24, 0
	v_mbcnt_hi_u32_b32 v9, s25, v9
	v_add_lshl_u32 v11, v9, s1, 2
	s_bcnt1_i32_b64 s26, s[24:25]
	s_add_i32 s1, s1, s26
	s_mov_b64 exec, s[24:25]
	ds_write2st64_b32 v11, v12, v69 offset0:36 offset1:68
	s_mov_b64 exec, -1
	s_waitcnt lgkmcnt(0)
	s_barrier
	s_cmp_lg_u32 s29, 0
	s_cbranch_scc1 .LBB0_1485
; DI void topk_phase(const bf16_t* PROJ, const unsigned char* K8, const unsigned char* V8, const unsigned short* SC, bf16_t* ODSA, int c, char* smem, int bid, int nb) {
;     ...
;       unsigned T = 0u;
;       for (int b = 15; b >= 0; --b) {
;         const unsigned cand = T | (1u << b);
;         int cc = 0;
; #pragma unroll
;         for (int i = 0; i < 64; ++i) if ((i >> 2) * 1024 < n) cc += key[i] >= cand ? 1 : 0;
;         if (block_count(cc, b & 1, red) >= 256) T = cand;
;       }
;       int cg_ = 0, ce_ = 0;
; #pragma unroll
;       for (int i = 0; i < 64; ++i) if ((i >> 2) * 1024 < n) { cg_ += key[i] > T ? 1 : 0; ce_ += key[i] == T ? 1 : 0; }
;       if (tid == 0) cnts[0] = 0;
;       const int cgt = block_count(cg_, 2, red);
;       const int ceq = block_count(ce_, 3, red);
;       const int need = 256 - cgt;
;       int X = 0x7fffffff;
;       if (ceq != need) {
;         X = 0;
;         for (int b = 13; b >= 0; --b) {
;           const int cand = X | (1 << b);
;           int cc = 0;
; #pragma unroll
;           for (int i = 0; i < 64; ++i) if ((i >> 2) * 1024 < n) cc += (key[i] == T && ((i >> 2) * 256 + tid) * 4 + (i & 3) < cand) ? 1 : 0;
;           if (block_count(cc, b & 1, red) < need) X = cand;
	v_and_b32_e32 v10, 63, v214
	v_lshlrev_b32_e32 v11, 2, v10
	ds_read_b32 v186, v11 offset:9216
	ds_read_b32 v172, v11 offset:17408
	ds_read_b32 v187, v11 offset:9472
	ds_read_b32 v173, v11 offset:17664
	ds_read_b32 v188, v11 offset:9728
	ds_read_b32 v174, v11 offset:17920
	ds_read_b32 v189, v11 offset:9984
	ds_read_b32 v175, v11 offset:18176
	s_waitcnt lgkmcnt(0)
	ds_read_b32 v190, v11 offset:10240
	ds_read_b32 v176, v11 offset:18432
	ds_read_b32 v191, v11 offset:10496
	ds_read_b32 v177, v11 offset:18688
	ds_read_b32 v192, v11 offset:10752
	ds_read_b32 v178, v11 offset:18944
	ds_read_b32 v193, v11 offset:11008
	ds_read_b32 v179, v11 offset:19200
	s_waitcnt lgkmcnt(0)
	ds_read_b32 v194, v11 offset:11264
	ds_read_b32 v180, v11 offset:19456
	ds_read_b32 v195, v11 offset:11520
	ds_read_b32 v181, v11 offset:19712
	ds_read_b32 v196, v11 offset:11776
	ds_read_b32 v182, v11 offset:19968
	ds_read_b32 v197, v11 offset:12032
	ds_read_b32 v183, v11 offset:20224
	s_waitcnt lgkmcnt(0)
	ds_read_b32 v198, v11 offset:12288
	ds_read_b32 v184, v11 offset:20480
	ds_read_b32 v199, v11 offset:12544
	ds_read_b32 v230, v11 offset:20736
	ds_read_b32 v200, v11 offset:12800
	ds_read_b32 v231, v11 offset:20992
	ds_read_b32 v201, v11 offset:13056
	ds_read_b32 v232, v11 offset:21248
	s_waitcnt lgkmcnt(0)
	ds_read_b32 v202, v11 offset:13312
	ds_read_b32 v233, v11 offset:21504
	ds_read_b32 v203, v11 offset:13568
	ds_read_b32 v235, v11 offset:21760
	ds_read_b32 v204, v11 offset:13824
	ds_read_b32 v236, v11 offset:22016
	ds_read_b32 v205, v11 offset:14080
	ds_read_b32 v237, v11 offset:22272
	s_waitcnt lgkmcnt(0)
	ds_read_b32 v206, v11 offset:14336
	ds_read_b32 v238, v11 offset:22528
	ds_read_b32 v207, v11 offset:14592
	ds_read_b32 v239, v11 offset:22784
	ds_read_b32 v208, v11 offset:14848
	ds_read_b32 v240, v11 offset:23040
	ds_read_b32 v209, v11 offset:15104
	ds_read_b32 v241, v11 offset:23296
	s_waitcnt lgkmcnt(0)
	ds_read_b32 v210, v11 offset:15360
	ds_read_b32 v242, v11 offset:23552
	ds_read_b32 v211, v11 offset:15616
	ds_read_b32 v243, v11 offset:23808
	ds_read_b32 v212, v11 offset:15872
	ds_read_b32 v244, v11 offset:24064
	ds_read_b32 v213, v11 offset:16128
	ds_read_b32 v245, v11 offset:24320
	s_waitcnt lgkmcnt(0)
	ds_read_b32 v226, v11 offset:16384
	ds_read_b32 v215, v11 offset:24576
	ds_read_b32 v227, v11 offset:16640
	ds_read_b32 v216, v11 offset:24832
	ds_read_b32 v228, v11 offset:16896
	ds_read_b32 v221, v11 offset:25088
	ds_read_b32 v229, v11 offset:17152
	ds_read_b32 v224, v11 offset:25344
	s_waitcnt lgkmcnt(0)
	s_sub_i32 s26, s31, 0
	v_cmp_gt_i32_e64 s[22:23], s26, v10
	s_sub_i32 s27, s31, 64
	v_cmp_gt_i32_e64 s[24:25], s27, v10
	s_nop 0
	v_cndmask_b32_e64 v186, 0, v186, s[22:23]
	s_sub_i32 s26, s31, 128
	v_cmp_gt_i32_e64 s[22:23], s26, v10
	v_cndmask_b32_e64 v187, 0, v187, s[24:25]
	s_sub_i32 s27, s31, 192
	v_cmp_gt_i32_e64 s[24:25], s27, v10
	v_cndmask_b32_e64 v188, 0, v188, s[22:23]
	s_sub_i32 s26, s31, 256
	v_cmp_gt_i32_e64 s[22:23], s26, v10
	v_cndmask_b32_e64 v189, 0, v189, s[24:25]
	s_sub_i32 s27, s31, 320
	v_cmp_gt_i32_e64 s[24:25], s27, v10
	v_cndmask_b32_e64 v190, 0, v190, s[22:23]
	s_sub_i32 s26, s31, 384
	v_cmp_gt_i32_e64 s[22:23], s26, v10
	v_cndmask_b32_e64 v191, 0, v191, s[24:25]
	s_sub_i32 s27, s31, 448
	v_cmp_gt_i32_e64 s[24:25], s27, v10
	v_cndmask_b32_e64 v192, 0, v192, s[22:23]
	s_sub_i32 s26, s31, 512
	v_cmp_gt_i32_e64 s[22:23], s26, v10
	v_cndmask_b32_e64 v193, 0, v193, s[24:25]
	s_sub_i32 s27, s31, 576
	v_cmp_gt_i32_e64 s[24:25], s27, v10
	v_cndmask_b32_e64 v194, 0, v194, s[22:23]
	s_sub_i32 s26, s31, 640
	v_cmp_gt_i32_e64 s[22:23], s26, v10
	v_cndmask_b32_e64 v195, 0, v195, s[24:25]
	s_sub_i32 s27, s31, 704
	v_cmp_gt_i32_e64 s[24:25], s27, v10
	v_cndmask_b32_e64 v196, 0, v196, s[22:23]
	s_sub_i32 s26, s31, 768
	v_cmp_gt_i32_e64 s[22:23], s26, v10
	v_cndmask_b32_e64 v197, 0, v197, s[24:25]
	s_sub_i32 s27, s31, 832
	v_cmp_gt_i32_e64 s[24:25], s27, v10
	v_cndmask_b32_e64 v198, 0, v198, s[22:23]
	s_sub_i32 s26, s31, 896
	v_cmp_gt_i32_e64 s[22:23], s26, v10
	v_cndmask_b32_e64 v199, 0, v199, s[24:25]
	s_sub_i32 s27, s31, 960
	v_cmp_gt_i32_e64 s[24:25], s27, v10
	v_cndmask_b32_e64 v200, 0, v200, s[22:23]
	s_sub_i32 s26, s31, 1024
	v_cmp_gt_i32_e64 s[22:23], s26, v10
	v_cndmask_b32_e64 v201, 0, v201, s[24:25]
	s_sub_i32 s27, s31, 1088
	v_cmp_gt_i32_e64 s[24:25], s27, v10
	v_cndmask_b32_e64 v202, 0, v202, s[22:23]
	s_sub_i32 s26, s31, 1152
	v_cmp_gt_i32_e64 s[22:23], s26, v10
	v_cndmask_b32_e64 v203, 0, v203, s[24:25]
	s_sub_i32 s27, s31, 1216
	v_cmp_gt_i32_e64 s[24:25], s27, v10
	v_cndmask_b32_e64 v204, 0, v204, s[22:23]
	s_sub_i32 s26, s31, 1280
	v_cmp_gt_i32_e64 s[22:23], s26, v10
	v_cndmask_b32_e64 v205, 0, v205, s[24:25]
	s_sub_i32 s27, s31, 1344
	v_cmp_gt_i32_e64 s[24:25], s27, v10
	v_cndmask_b32_e64 v206, 0, v206, s[22:23]
	s_sub_i32 s26, s31, 1408
	v_cmp_gt_i32_e64 s[22:23], s26, v10
	v_cndmask_b32_e64 v207, 0, v207, s[24:25]
	s_sub_i32 s27, s31, 1472
	v_cmp_gt_i32_e64 s[24:25], s27, v10
	v_cndmask_b32_e64 v208, 0, v208, s[22:23]
	s_sub_i32 s26, s31, 1536
	v_cmp_gt_i32_e64 s[22:23], s26, v10
	v_cndmask_b32_e64 v209, 0, v209, s[24:25]
	s_sub_i32 s27, s31, 1600
	v_cmp_gt_i32_e64 s[24:25], s27, v10
	v_cndmask_b32_e64 v210, 0, v210, s[22:23]
	s_sub_i32 s26, s31, 1664
	v_cmp_gt_i32_e64 s[22:23], s26, v10
	v_cndmask_b32_e64 v211, 0, v211, s[24:25]
	s_sub_i32 s27, s31, 1728
	v_cmp_gt_i32_e64 s[24:25], s27, v10
	v_cndmask_b32_e64 v212, 0, v212, s[22:23]
	s_sub_i32 s26, s31, 1792
	v_cmp_gt_i32_e64 s[22:23], s26, v10
	v_cndmask_b32_e64 v213, 0, v213, s[24:25]
	s_sub_i32 s27, s31, 1856
	v_cmp_gt_i32_e64 s[24:25], s27, v10
	v_cndmask_b32_e64 v226, 0, v226, s[22:23]
	s_sub_i32 s26, s31, 1920
	v_cmp_gt_i32_e64 s[22:23], s26, v10
	v_cndmask_b32_e64 v227, 0, v227, s[24:25]
	s_sub_i32 s27, s31, 1984
	v_cmp_gt_i32_e64 s[24:25], s27, v10
	v_cndmask_b32_e64 v228, 0, v228, s[22:23]
	v_cndmask_b32_e64 v229, 0, v229, s[24:25]
	s_mov_b32 s1, 0
	s_mov_b32 s2, 15

; DI void topk_phase(const bf16_t* PROJ, const unsigned char* K8, const unsigned char* V8, const unsigned short* SC, bf16_t* ODSA, int c, char* smem, int bid, int nb) {
;     ...
;       unsigned T = 0u;
;       for (int b = 15; b >= 0; --b) {
;         const unsigned cand = T | (1u << b);
;         int cc = 0;
; #pragma unroll
;         for (int i = 0; i < 64; ++i) if ((i >> 2) * 1024 < n) cc += key[i] >= cand ? 1 : 0;
;         if (block_count(cc, b & 1, red) >= 256) T = cand;
;       }
.Lsel_fb_C:
	s_xor_b64 s[90:91], s[2:3], -1
	s_xor_b64 s[88:89], s[4:5], -1
	s_xor_b64 s[86:87], s[6:7], -1
	s_mov_b32 s2, 15
	v_mov_b32_e32 v13, 0
	s_branch .LBB0_1366

; DI float sum8(float v) { v += DPPF(v, 0xB1); v += DPPF(v, 0x4E); v += DPPF(v, 0x141); return v; }
; DI void topk_phase(const bf16_t* PROJ, const unsigned char* K8, const unsigned char* V8, const unsigned short* SC, bf16_t* ODSA, int c, char* smem, int bid, int nb) {
;     ...
;     const int mysel = sel[wid * 64 + lane];
; #pragma unroll 4
;     for (int jj = 0; jj < 64; ++jj) {
;       const int j = wid * 64 + jj;
;       {
;         const size_t ro = (size_t)__builtin_amdgcn_readlane(mysel, jj) * 1024 + lane * 16;
;         const uint4 a = *(const uint4*)(K8 + ro), vv = *(const uint4*)(V8 + ro);
;         const unsigned w[4] = {a.x, a.y, a.z, a.w}, u[4] = {vv.x, vv.y, vv.z, vv.w};
;         float da = 0.f;
; #pragma unroll
;         for (int i = 0; i < 4; ++i) {
;           const f32x2v lo = __builtin_amdgcn_cvt_pk_f32_fp8((int)w[i], false), hi = __builtin_amdgcn_cvt_pk_f32_fp8((int)w[i], true);
;           da += qv[4 * i] * lo[0] + qv[4 * i + 1] * lo[1] + qv[4 * i + 2] * hi[0] + qv[4 * i + 3] * hi[1];
;         }
;         da = sum8(da);
;         da = j < count ? da : -3e30f;
.LBB0_1489:
	s_waitcnt lgkmcnt(0)
	v_readfirstlane_b32 s1, v47
	v_readlane_b32 s0, v75, 0
	s_lshl_b32 s0, s0, 10
	s_add_u32 s4, s6, s0
	s_addc_u32 s5, s7, 0
	global_load_dwordx4 v[136:139], v16, s[4:5]
	v_readlane_b32 s0, v75, 1
	s_lshl_b32 s0, s0, 10
	s_add_u32 s4, s6, s0
	s_addc_u32 s5, s7, 0
	global_load_dwordx4 v[140:143], v16, s[4:5]
	v_readlane_b32 s0, v75, 2
	s_lshl_b32 s0, s0, 10
	s_add_u32 s4, s6, s0
	s_addc_u32 s5, s7, 0
	global_load_dwordx4 v[144:147], v16, s[4:5]
	v_readlane_b32 s0, v75, 3
	s_lshl_b32 s0, s0, 10
	s_add_u32 s4, s6, s0
	s_addc_u32 s5, s7, 0
	global_load_dwordx4 v[148:151], v16, s[4:5]
	v_readlane_b32 s0, v75, 4
	s_lshl_b32 s0, s0, 10
	s_add_u32 s4, s6, s0
	s_addc_u32 s5, s7, 0
	global_load_dwordx4 v[152:155], v16, s[4:5]
	v_readlane_b32 s0, v75, 5
	s_lshl_b32 s0, s0, 10
	s_add_u32 s4, s6, s0
	s_addc_u32 s5, s7, 0
	global_load_dwordx4 v[156:159], v16, s[4:5]
	v_readlane_b32 s0, v75, 6
	s_lshl_b32 s0, s0, 10
	s_add_u32 s4, s6, s0
	s_addc_u32 s5, s7, 0
	global_load_dwordx4 v[160:163], v16, s[4:5]
	v_readlane_b32 s0, v75, 7
	s_lshl_b32 s0, s0, 10
	s_add_u32 s4, s6, s0
	s_addc_u32 s5, s7, 0
	global_load_dwordx4 v[164:167], v16, s[4:5]
	v_readlane_b32 s0, v75, 8
	s_lshl_b32 s0, s0, 10
	s_add_u32 s4, s6, s0
	s_addc_u32 s5, s7, 0
	global_load_dwordx4 v[168:171], v16, s[4:5]
	v_readlane_b32 s0, v75, 9
	s_lshl_b32 s0, s0, 10
	s_add_u32 s4, s6, s0
	s_addc_u32 s5, s7, 0
	global_load_dwordx4 v[172:175], v16, s[4:5]
	v_readlane_b32 s0, v75, 10
	s_lshl_b32 s0, s0, 10
	s_add_u32 s4, s6, s0
	s_addc_u32 s5, s7, 0
	global_load_dwordx4 v[176:179], v16, s[4:5]
	v_readlane_b32 s0, v75, 11
	s_lshl_b32 s0, s0, 10
	s_add_u32 s4, s6, s0
	s_addc_u32 s5, s7, 0
	global_load_dwordx4 v[180:183], v16, s[4:5]
	v_readlane_b32 s0, v75, 12
	s_lshl_b32 s0, s0, 10
	s_add_u32 s4, s6, s0
	s_addc_u32 s5, s7, 0
	global_load_dwordx4 v[186:189], v16, s[4:5]
	v_readlane_b32 s0, v75, 13
	s_lshl_b32 s0, s0, 10
	s_add_u32 s4, s6, s0
	s_addc_u32 s5, s7, 0
	global_load_dwordx4 v[190:193], v16, s[4:5]
	v_readlane_b32 s0, v75, 14
	s_lshl_b32 s0, s0, 10
	s_add_u32 s4, s6, s0
	s_addc_u32 s5, s7, 0
	global_load_dwordx4 v[194:197], v16, s[4:5]
	v_readlane_b32 s0, v75, 15
	s_lshl_b32 s0, s0, 10
	s_add_u32 s4, s6, s0
	s_addc_u32 s5, s7, 0
	global_load_dwordx4 v[198:201], v16, s[4:5]
	v_mov_b32_e32 v240, v29
	v_mov_b32_e32 v241, v31
	v_mov_b32_e32 v29, v30
	v_mov_b32_e32 v31, v34
	v_mov_b32_e32 v30, v32
	v_mov_b32_e32 v34, v33
	v_mov_b32_e32 v32, v240
	v_mov_b32_e32 v33, v241
	v_mov_b32_e32 v240, v37
	v_mov_b32_e32 v241, v39
	v_mov_b32_e32 v37, v38
	v_mov_b32_e32 v39, v42
	v_mov_b32_e32 v38, v40
	v_mov_b32_e32 v42, v41
	v_mov_b32_e32 v40, v240
	v_mov_b32_e32 v41, v241
	v_mov_b32_e32 v0, 0
	v_mov_b32_e32 v1, 0
	v_mov_b32_e32 v2, 0
	v_mov_b32_e32 v3, 0
	v_mov_b32_e32 v4, 0
	v_mov_b32_e32 v5, 0
	v_mov_b32_e32 v6, 0
	v_mov_b32_e32 v7, 0
	v_mov_b32_e32 v8, 0
	v_mov_b32_e32 v9, 0
	v_mov_b32_e32 v10, 0
	v_mov_b32_e32 v11, 0
	v_mov_b32_e32 v12, 0
	v_mov_b32_e32 v13, 0
	v_mov_b32_e32 v14, 0
	v_mov_b32_e32 v15, 0
	v_mov_b32_e32 v215, 0
	v_mov_b32_e32 v216, 0xf149f2ca
	s_waitcnt vmcnt(15)
	v_cvt_pk_f32_fp8_e32 v[240:241], v136
	v_cvt_pk_f32_fp8_sdwa v[242:243], v136 src0_sel:WORD_1
	v_cvt_pk_f32_fp8_e32 v[244:245], v137
	v_cvt_pk_f32_fp8_sdwa v[202:203], v137 src0_sel:WORD_1
	v_pk_mul_f32 v[204:205], v[240:241], v[28:29]
	v_pk_mul_f32 v[206:207], v[242:243], v[30:31]
	v_cvt_pk_f32_fp8_e32 v[240:241], v138
	v_cvt_pk_f32_fp8_sdwa v[242:243], v138 src0_sel:WORD_1
	v_pk_fma_f32 v[204:205], v[244:245], v[32:33], v[204:205]
	v_pk_fma_f32 v[206:207], v[202:203], v[34:35], v[206:207]
	v_cvt_pk_f32_fp8_e32 v[244:245], v139
	v_cvt_pk_f32_fp8_sdwa v[202:203], v139 src0_sel:WORD_1
	v_pk_fma_f32 v[204:205], v[240:241], v[36:37], v[204:205]
	v_pk_fma_f32 v[206:207], v[242:243], v[38:39], v[206:207]
	v_pk_fma_f32 v[204:205], v[244:245], v[40:41], v[204:205]
	v_pk_fma_f32 v[206:207], v[202:203], v[42:43], v[206:207]
	v_readlane_b32 s0, v75, 0
	s_lshl_b32 s0, s0, 10
	s_add_u32 s4, s8, s0
	s_addc_u32 s5, s9, 0
	global_load_dwordx4 v[136:139], v16, s[4:5]
	v_pk_add_f32 v[204:205], v[204:205], v[206:207]
	s_nop 0
	v_add_f32_e32 v235, v204, v205
	s_waitcnt vmcnt(15)
	v_cvt_pk_f32_fp8_e32 v[240:241], v140
	v_cvt_pk_f32_fp8_sdwa v[242:243], v140 src0_sel:WORD_1
	v_cvt_pk_f32_fp8_e32 v[244:245], v141
	v_cvt_pk_f32_fp8_sdwa v[202:203], v141 src0_sel:WORD_1
	v_add_f32_dpp v235, v235, v235 quad_perm:[1,0,3,2] row_mask:0xf bank_mask:0xf bound_ctrl:1
	v_pk_mul_f32 v[204:205], v[240:241], v[28:29]
	v_pk_mul_f32 v[206:207], v[242:243], v[30:31]
	v_add_f32_dpp v235, v235, v235 quad_perm:[2,3,0,1] row_mask:0xf bank_mask:0xf bound_ctrl:1
	v_cvt_pk_f32_fp8_e32 v[240:241], v142
	v_cvt_pk_f32_fp8_sdwa v[242:243], v142 src0_sel:WORD_1
	v_add_f32_dpp v235, v235, v235 row_half_mirror row_mask:0xf bank_mask:0xf bound_ctrl:1
	v_pk_fma_f32 v[204:205], v[244:245], v[32:33], v[204:205]
	v_pk_fma_f32 v[206:207], v[202:203], v[34:35], v[206:207]
	s_add_i32 s0, s1, 0
	s_cmp_lt_i32 s0, s2
	s_cselect_b64 vcc, -1, 0
	v_cvt_pk_f32_fp8_e32 v[244:245], v143
	v_cvt_pk_f32_fp8_sdwa v[202:203], v143 src0_sel:WORD_1
	v_cndmask_b32_e32 v210, v220, v235, vcc
	v_pk_fma_f32 v[204:205], v[240:241], v[36:37], v[204:205]
	v_pk_fma_f32 v[206:207], v[242:243], v[38:39], v[206:207]
	v_pk_fma_f32 v[204:205], v[244:245], v[40:41], v[204:205]
	v_pk_fma_f32 v[206:207], v[202:203], v[42:43], v[206:207]
	v_readlane_b32 s0, v75, 1
	s_lshl_b32 s0, s0, 10
	s_add_u32 s4, s8, s0
	s_addc_u32 s5, s9, 0
	global_load_dwordx4 v[140:143], v16, s[4:5]
	v_pk_add_f32 v[204:205], v[204:205], v[206:207]
	s_nop 0
	v_add_f32_e32 v221, v204, v205
	s_waitcnt vmcnt(15)
; DI float sum8(float v) { v += DPPF(v, 0xB1); v += DPPF(v, 0x4E); v += DPPF(v, 0x141); return v; }
; DI void topk_phase(const bf16_t* PROJ, const unsigned char* K8, const unsigned char* V8, const unsigned short* SC, bf16_t* ODSA, int c, char* smem, int bid, int nb) {
;     ...
;         const size_t ro = (size_t)__builtin_amdgcn_readlane(mysel, jj) * 1024 + lane * 16;
;         const uint4 a = *(const uint4*)(K8 + ro), vv = *(const uint4*)(V8 + ro);
;         const unsigned w[4] = {a.x, a.y, a.z, a.w}, u[4] = {vv.x, vv.y, vv.z, vv.w};
;         float da = 0.f;
; #pragma unroll
;         for (int i = 0; i < 4; ++i) {
;           const f32x2v lo = __builtin_amdgcn_cvt_pk_f32_fp8((int)w[i], false), hi = __builtin_amdgcn_cvt_pk_f32_fp8((int)w[i], true);
;           da += qv[4 * i] * lo[0] + qv[4 * i + 1] * lo[1] + qv[4 * i + 2] * hi[0] + qv[4 * i + 3] * hi[1];
;         }
;         da = sum8(da);
;         da = j < count ? da : -3e30f;
	v_cvt_pk_f32_fp8_e32 v[240:241], v144
	v_cvt_pk_f32_fp8_sdwa v[242:243], v144 src0_sel:WORD_1
	v_cvt_pk_f32_fp8_e32 v[244:245], v145
	v_cvt_pk_f32_fp8_sdwa v[202:203], v145 src0_sel:WORD_1
	v_add_f32_dpp v221, v221, v221 quad_perm:[1,0,3,2] row_mask:0xf bank_mask:0xf bound_ctrl:1
	v_pk_mul_f32 v[204:205], v[240:241], v[28:29]
	v_pk_mul_f32 v[206:207], v[242:243], v[30:31]
	v_add_f32_dpp v221, v221, v221 quad_perm:[2,3,0,1] row_mask:0xf bank_mask:0xf bound_ctrl:1
	v_cvt_pk_f32_fp8_e32 v[240:241], v146
	v_cvt_pk_f32_fp8_sdwa v[242:243], v146 src0_sel:WORD_1
	v_add_f32_dpp v221, v221, v221 row_half_mirror row_mask:0xf bank_mask:0xf bound_ctrl:1
	v_pk_fma_f32 v[204:205], v[244:245], v[32:33], v[204:205]
	v_pk_fma_f32 v[206:207], v[202:203], v[34:35], v[206:207]
	s_add_i32 s0, s1, 1
	s_cmp_lt_i32 s0, s2
	s_cselect_b64 vcc, -1, 0
	v_cvt_pk_f32_fp8_e32 v[244:245], v147
	v_cvt_pk_f32_fp8_sdwa v[202:203], v147 src0_sel:WORD_1
	v_cndmask_b32_e32 v211, v220, v221, vcc
	v_pk_fma_f32 v[204:205], v[240:241], v[36:37], v[204:205]
	v_pk_fma_f32 v[206:207], v[242:243], v[38:39], v[206:207]
	v_pk_fma_f32 v[204:205], v[244:245], v[40:41], v[204:205]
	v_pk_fma_f32 v[206:207], v[202:203], v[42:43], v[206:207]
	v_readlane_b32 s0, v75, 2
	s_lshl_b32 s0, s0, 10
	s_add_u32 s4, s8, s0
	s_addc_u32 s5, s9, 0
	global_load_dwordx4 v[144:147], v16, s[4:5]
	v_pk_add_f32 v[204:205], v[204:205], v[206:207]
	s_nop 0
	v_add_f32_e32 v235, v204, v205
	s_waitcnt vmcnt(15)
	v_cvt_pk_f32_fp8_e32 v[240:241], v148
	v_cvt_pk_f32_fp8_sdwa v[242:243], v148 src0_sel:WORD_1
	v_cvt_pk_f32_fp8_e32 v[244:245], v149
	v_cvt_pk_f32_fp8_sdwa v[202:203], v149 src0_sel:WORD_1
	v_add_f32_dpp v235, v235, v235 quad_perm:[1,0,3,2] row_mask:0xf bank_mask:0xf bound_ctrl:1
	v_pk_mul_f32 v[204:205], v[240:241], v[28:29]
	v_pk_mul_f32 v[206:207], v[242:243], v[30:31]
	v_add_f32_dpp v235, v235, v235 quad_perm:[2,3,0,1] row_mask:0xf bank_mask:0xf bound_ctrl:1
	v_cvt_pk_f32_fp8_e32 v[240:241], v150
	v_cvt_pk_f32_fp8_sdwa v[242:243], v150 src0_sel:WORD_1
	v_add_f32_dpp v235, v235, v235 row_half_mirror row_mask:0xf bank_mask:0xf bound_ctrl:1
	v_pk_fma_f32 v[204:205], v[244:245], v[32:33], v[204:205]
	v_pk_fma_f32 v[206:207], v[202:203], v[34:35], v[206:207]
	s_add_i32 s0, s1, 2
	s_cmp_lt_i32 s0, s2
	s_cselect_b64 vcc, -1, 0
	v_cvt_pk_f32_fp8_e32 v[244:245], v151
	v_cvt_pk_f32_fp8_sdwa v[202:203], v151 src0_sel:WORD_1
	v_cndmask_b32_e32 v212, v220, v235, vcc
	v_pk_fma_f32 v[204:205], v[240:241], v[36:37], v[204:205]
	v_pk_fma_f32 v[206:207], v[242:243], v[38:39], v[206:207]
	v_pk_fma_f32 v[204:205], v[244:245], v[40:41], v[204:205]
	v_pk_fma_f32 v[206:207], v[202:203], v[42:43], v[206:207]
	v_readlane_b32 s0, v75, 3
	s_lshl_b32 s0, s0, 10
	s_add_u32 s4, s8, s0
	s_addc_u32 s5, s9, 0
	global_load_dwordx4 v[148:151], v16, s[4:5]
	v_pk_add_f32 v[204:205], v[204:205], v[206:207]
	s_nop 0
	v_add_f32_e32 v221, v204, v205
	s_waitcnt vmcnt(15)
	v_cvt_pk_f32_fp8_e32 v[240:241], v152
	v_cvt_pk_f32_fp8_sdwa v[242:243], v152 src0_sel:WORD_1
	v_cvt_pk_f32_fp8_e32 v[244:245], v153
	v_cvt_pk_f32_fp8_sdwa v[202:203], v153 src0_sel:WORD_1
	v_add_f32_dpp v221, v221, v221 quad_perm:[1,0,3,2] row_mask:0xf bank_mask:0xf bound_ctrl:1
	v_pk_mul_f32 v[204:205], v[240:241], v[28:29]
	v_pk_mul_f32 v[206:207], v[242:243], v[30:31]
	v_add_f32_dpp v221, v221, v221 quad_perm:[2,3,0,1] row_mask:0xf bank_mask:0xf bound_ctrl:1
	v_cvt_pk_f32_fp8_e32 v[240:241], v154
	v_cvt_pk_f32_fp8_sdwa v[242:243], v154 src0_sel:WORD_1
	v_add_f32_dpp v221, v221, v221 row_half_mirror row_mask:0xf bank_mask:0xf bound_ctrl:1
	v_pk_fma_f32 v[204:205], v[244:245], v[32:33], v[204:205]
	v_pk_fma_f32 v[206:207], v[202:203], v[34:35], v[206:207]
	s_add_i32 s0, s1, 3
	s_cmp_lt_i32 s0, s2
	s_cselect_b64 vcc, -1, 0
	v_cvt_pk_f32_fp8_e32 v[244:245], v155
	v_cvt_pk_f32_fp8_sdwa v[202:203], v155 src0_sel:WORD_1
	v_cndmask_b32_e32 v213, v220, v221, vcc
	v_pk_fma_f32 v[204:205], v[240:241], v[36:37], v[204:205]
	v_pk_fma_f32 v[206:207], v[242:243], v[38:39], v[206:207]
	v_pk_fma_f32 v[204:205], v[244:245], v[40:41], v[204:205]
	v_pk_fma_f32 v[206:207], v[202:203], v[42:43], v[206:207]
	v_readlane_b32 s0, v75, 4
	s_lshl_b32 s0, s0, 10
	s_add_u32 s4, s8, s0
	s_addc_u32 s5, s9, 0
	global_load_dwordx4 v[152:155], v16, s[4:5]
	v_pk_add_f32 v[204:205], v[204:205], v[206:207]
	s_nop 0
	v_add_f32_e32 v235, v204, v205
	s_waitcnt vmcnt(15)
	v_cvt_pk_f32_fp8_e32 v[240:241], v156
	v_cvt_pk_f32_fp8_sdwa v[242:243], v156 src0_sel:WORD_1
	v_cvt_pk_f32_fp8_e32 v[244:245], v157
	v_cvt_pk_f32_fp8_sdwa v[202:203], v157 src0_sel:WORD_1
	v_add_f32_dpp v235, v235, v235 quad_perm:[1,0,3,2] row_mask:0xf bank_mask:0xf bound_ctrl:1
	v_pk_mul_f32 v[204:205], v[240:241], v[28:29]
	v_pk_mul_f32 v[206:207], v[242:243], v[30:31]
	v_add_f32_dpp v235, v235, v235 quad_perm:[2,3,0,1] row_mask:0xf bank_mask:0xf bound_ctrl:1
	v_cvt_pk_f32_fp8_e32 v[240:241], v158
	v_cvt_pk_f32_fp8_sdwa v[242:243], v158 src0_sel:WORD_1
	v_add_f32_dpp v235, v235, v235 row_half_mirror row_mask:0xf bank_mask:0xf bound_ctrl:1
	v_pk_fma_f32 v[204:205], v[244:245], v[32:33], v[204:205]
	v_pk_fma_f32 v[206:207], v[202:203], v[34:35], v[206:207]
	s_add_i32 s0, s1, 4
	s_cmp_lt_i32 s0, s2
	s_cselect_b64 vcc, -1, 0
	v_cvt_pk_f32_fp8_e32 v[244:245], v159
	v_cvt_pk_f32_fp8_sdwa v[202:203], v159 src0_sel:WORD_1
	v_cndmask_b32_e32 v226, v220, v235, vcc
	v_pk_fma_f32 v[204:205], v[240:241], v[36:37], v[204:205]
	v_pk_fma_f32 v[206:207], v[242:243], v[38:39], v[206:207]
	v_pk_fma_f32 v[204:205], v[244:245], v[40:41], v[204:205]
	v_pk_fma_f32 v[206:207], v[202:203], v[42:43], v[206:207]
	v_readlane_b32 s0, v75, 5
	s_lshl_b32 s0, s0, 10
	s_add_u32 s4, s8, s0
	s_addc_u32 s5, s9, 0
	global_load_dwordx4 v[156:159], v16, s[4:5]
	v_pk_add_f32 v[204:205], v[204:205], v[206:207]
	s_nop 0
	v_add_f32_e32 v221, v204, v205
	s_waitcnt vmcnt(15)
; DI float sum8(float v) { v += DPPF(v, 0xB1); v += DPPF(v, 0x4E); v += DPPF(v, 0x141); return v; }
; DI void topk_phase(const bf16_t* PROJ, const unsigned char* K8, const unsigned char* V8, const unsigned short* SC, bf16_t* ODSA, int c, char* smem, int bid, int nb) {
;     ...
;         const size_t ro = (size_t)__builtin_amdgcn_readlane(mysel, jj) * 1024 + lane * 16;
;         const uint4 a = *(const uint4*)(K8 + ro), vv = *(const uint4*)(V8 + ro);
;         const unsigned w[4] = {a.x, a.y, a.z, a.w}, u[4] = {vv.x, vv.y, vv.z, vv.w};
;         float da = 0.f;
; #pragma unroll
;         for (int i = 0; i < 4; ++i) {
;           const f32x2v lo = __builtin_amdgcn_cvt_pk_f32_fp8((int)w[i], false), hi = __builtin_amdgcn_cvt_pk_f32_fp8((int)w[i], true);
;           da += qv[4 * i] * lo[0] + qv[4 * i + 1] * lo[1] + qv[4 * i + 2] * hi[0] + qv[4 * i + 3] * hi[1];
;         }
;         da = sum8(da);
;         da = j < count ? da : -3e30f;
	v_cvt_pk_f32_fp8_e32 v[240:241], v160
	v_cvt_pk_f32_fp8_sdwa v[242:243], v160 src0_sel:WORD_1
	v_cvt_pk_f32_fp8_e32 v[244:245], v161
	v_cvt_pk_f32_fp8_sdwa v[202:203], v161 src0_sel:WORD_1
	v_add_f32_dpp v221, v221, v221 quad_perm:[1,0,3,2] row_mask:0xf bank_mask:0xf bound_ctrl:1
	v_pk_mul_f32 v[204:205], v[240:241], v[28:29]
	v_pk_mul_f32 v[206:207], v[242:243], v[30:31]
	v_add_f32_dpp v221, v221, v221 quad_perm:[2,3,0,1] row_mask:0xf bank_mask:0xf bound_ctrl:1
	v_cvt_pk_f32_fp8_e32 v[240:241], v162
	v_cvt_pk_f32_fp8_sdwa v[242:243], v162 src0_sel:WORD_1
	v_add_f32_dpp v221, v221, v221 row_half_mirror row_mask:0xf bank_mask:0xf bound_ctrl:1
	v_pk_fma_f32 v[204:205], v[244:245], v[32:33], v[204:205]
	v_pk_fma_f32 v[206:207], v[202:203], v[34:35], v[206:207]
	s_add_i32 s0, s1, 5
	s_cmp_lt_i32 s0, s2
	s_cselect_b64 vcc, -1, 0
	v_cvt_pk_f32_fp8_e32 v[244:245], v163
	v_cvt_pk_f32_fp8_sdwa v[202:203], v163 src0_sel:WORD_1
	v_cndmask_b32_e32 v227, v220, v221, vcc
	v_pk_fma_f32 v[204:205], v[240:241], v[36:37], v[204:205]
	v_pk_fma_f32 v[206:207], v[242:243], v[38:39], v[206:207]
	v_pk_fma_f32 v[204:205], v[244:245], v[40:41], v[204:205]
	v_pk_fma_f32 v[206:207], v[202:203], v[42:43], v[206:207]
	v_readlane_b32 s0, v75, 6
	s_lshl_b32 s0, s0, 10
	s_add_u32 s4, s8, s0
	s_addc_u32 s5, s9, 0
	global_load_dwordx4 v[160:163], v16, s[4:5]
	v_pk_add_f32 v[204:205], v[204:205], v[206:207]
	s_nop 0
	v_add_f32_e32 v235, v204, v205
	s_waitcnt vmcnt(15)
	v_cvt_pk_f32_fp8_e32 v[240:241], v164
	v_cvt_pk_f32_fp8_sdwa v[242:243], v164 src0_sel:WORD_1
	v_cvt_pk_f32_fp8_e32 v[244:245], v165
	v_cvt_pk_f32_fp8_sdwa v[202:203], v165 src0_sel:WORD_1
	v_add_f32_dpp v235, v235, v235 quad_perm:[1,0,3,2] row_mask:0xf bank_mask:0xf bound_ctrl:1
	v_pk_mul_f32 v[204:205], v[240:241], v[28:29]
	v_pk_mul_f32 v[206:207], v[242:243], v[30:31]
	v_add_f32_dpp v235, v235, v235 quad_perm:[2,3,0,1] row_mask:0xf bank_mask:0xf bound_ctrl:1
	v_cvt_pk_f32_fp8_e32 v[240:241], v166
	v_cvt_pk_f32_fp8_sdwa v[242:243], v166 src0_sel:WORD_1
	v_add_f32_dpp v235, v235, v235 row_half_mirror row_mask:0xf bank_mask:0xf bound_ctrl:1
	v_pk_fma_f32 v[204:205], v[244:245], v[32:33], v[204:205]
	v_pk_fma_f32 v[206:207], v[202:203], v[34:35], v[206:207]
	s_add_i32 s0, s1, 6
	s_cmp_lt_i32 s0, s2
	s_cselect_b64 vcc, -1, 0
	v_cvt_pk_f32_fp8_e32 v[244:245], v167
	v_cvt_pk_f32_fp8_sdwa v[202:203], v167 src0_sel:WORD_1
	v_cndmask_b32_e32 v228, v220, v235, vcc
	v_pk_fma_f32 v[204:205], v[240:241], v[36:37], v[204:205]
	v_pk_fma_f32 v[206:207], v[242:243], v[38:39], v[206:207]
	v_pk_fma_f32 v[204:205], v[244:245], v[40:41], v[204:205]
	v_pk_fma_f32 v[206:207], v[202:203], v[42:43], v[206:207]
	v_readlane_b32 s0, v75, 7
	s_lshl_b32 s0, s0, 10
	s_add_u32 s4, s8, s0
	s_addc_u32 s5, s9, 0
	global_load_dwordx4 v[164:167], v16, s[4:5]
	v_pk_add_f32 v[204:205], v[204:205], v[206:207]
	s_nop 0
	v_add_f32_e32 v221, v204, v205
	s_waitcnt vmcnt(15)
	v_cvt_pk_f32_fp8_e32 v[240:241], v168
	v_cvt_pk_f32_fp8_sdwa v[242:243], v168 src0_sel:WORD_1
	v_cvt_pk_f32_fp8_e32 v[244:245], v169
	v_cvt_pk_f32_fp8_sdwa v[202:203], v169 src0_sel:WORD_1
	v_add_f32_dpp v221, v221, v221 quad_perm:[1,0,3,2] row_mask:0xf bank_mask:0xf bound_ctrl:1
	v_pk_mul_f32 v[204:205], v[240:241], v[28:29]
	v_pk_mul_f32 v[206:207], v[242:243], v[30:31]
	v_add_f32_dpp v221, v221, v221 quad_perm:[2,3,0,1] row_mask:0xf bank_mask:0xf bound_ctrl:1
	v_cvt_pk_f32_fp8_e32 v[240:241], v170
	v_cvt_pk_f32_fp8_sdwa v[242:243], v170 src0_sel:WORD_1
	v_add_f32_dpp v221, v221, v221 row_half_mirror row_mask:0xf bank_mask:0xf bound_ctrl:1
	v_pk_fma_f32 v[204:205], v[244:245], v[32:33], v[204:205]
	v_pk_fma_f32 v[206:207], v[202:203], v[34:35], v[206:207]
	s_add_i32 s0, s1, 7
	s_cmp_lt_i32 s0, s2
	s_cselect_b64 vcc, -1, 0
	v_cvt_pk_f32_fp8_e32 v[244:245], v171
	v_cvt_pk_f32_fp8_sdwa v[202:203], v171 src0_sel:WORD_1
	v_cndmask_b32_e32 v229, v220, v221, vcc
	v_pk_fma_f32 v[204:205], v[240:241], v[36:37], v[204:205]
	v_pk_fma_f32 v[206:207], v[242:243], v[38:39], v[206:207]
	v_pk_fma_f32 v[204:205], v[244:245], v[40:41], v[204:205]
	v_pk_fma_f32 v[206:207], v[202:203], v[42:43], v[206:207]
	v_readlane_b32 s0, v75, 8
	s_lshl_b32 s0, s0, 10
	s_add_u32 s4, s8, s0
	s_addc_u32 s5, s9, 0
	global_load_dwordx4 v[168:171], v16, s[4:5]
	v_pk_add_f32 v[204:205], v[204:205], v[206:207]
	s_nop 0
	v_add_f32_e32 v235, v204, v205
	s_waitcnt vmcnt(15)
	v_cvt_pk_f32_fp8_e32 v[240:241], v172
	v_cvt_pk_f32_fp8_sdwa v[242:243], v172 src0_sel:WORD_1
	v_cvt_pk_f32_fp8_e32 v[244:245], v173
	v_cvt_pk_f32_fp8_sdwa v[202:203], v173 src0_sel:WORD_1
	v_add_f32_dpp v235, v235, v235 quad_perm:[1,0,3,2] row_mask:0xf bank_mask:0xf bound_ctrl:1
	v_pk_mul_f32 v[204:205], v[240:241], v[28:29]
	v_pk_mul_f32 v[206:207], v[242:243], v[30:31]
	v_add_f32_dpp v235, v235, v235 quad_perm:[2,3,0,1] row_mask:0xf bank_mask:0xf bound_ctrl:1
	v_cvt_pk_f32_fp8_e32 v[240:241], v174
	v_cvt_pk_f32_fp8_sdwa v[242:243], v174 src0_sel:WORD_1
	v_add_f32_dpp v235, v235, v235 row_half_mirror row_mask:0xf bank_mask:0xf bound_ctrl:1
	v_pk_fma_f32 v[204:205], v[244:245], v[32:33], v[204:205]
	v_pk_fma_f32 v[206:207], v[202:203], v[34:35], v[206:207]
	s_add_i32 s0, s1, 8
	s_cmp_lt_i32 s0, s2
	s_cselect_b64 vcc, -1, 0
	v_cvt_pk_f32_fp8_e32 v[244:245], v175
	v_cvt_pk_f32_fp8_sdwa v[202:203], v175 src0_sel:WORD_1
	v_cndmask_b32_e32 v230, v220, v235, vcc
	v_pk_fma_f32 v[204:205], v[240:241], v[36:37], v[204:205]
	v_pk_fma_f32 v[206:207], v[242:243], v[38:39], v[206:207]
	v_pk_fma_f32 v[204:205], v[244:245], v[40:41], v[204:205]
	v_pk_fma_f32 v[206:207], v[202:203], v[42:43], v[206:207]
	v_readlane_b32 s0, v75, 9
	s_lshl_b32 s0, s0, 10
	s_add_u32 s4, s8, s0
	s_addc_u32 s5, s9, 0
	global_load_dwordx4 v[172:175], v16, s[4:5]
	v_pk_add_f32 v[204:205], v[204:205], v[206:207]
	s_nop 0
	v_add_f32_e32 v221, v204, v205
	s_waitcnt vmcnt(15)
; DI float sum8(float v) { v += DPPF(v, 0xB1); v += DPPF(v, 0x4E); v += DPPF(v, 0x141); return v; }
; DI void topk_phase(const bf16_t* PROJ, const unsigned char* K8, const unsigned char* V8, const unsigned short* SC, bf16_t* ODSA, int c, char* smem, int bid, int nb) {
;     ...
;         const size_t ro = (size_t)__builtin_amdgcn_readlane(mysel, jj) * 1024 + lane * 16;
;         const uint4 a = *(const uint4*)(K8 + ro), vv = *(const uint4*)(V8 + ro);
;         const unsigned w[4] = {a.x, a.y, a.z, a.w}, u[4] = {vv.x, vv.y, vv.z, vv.w};
;         float da = 0.f;
; #pragma unroll
;         for (int i = 0; i < 4; ++i) {
;           const f32x2v lo = __builtin_amdgcn_cvt_pk_f32_fp8((int)w[i], false), hi = __builtin_amdgcn_cvt_pk_f32_fp8((int)w[i], true);
;           da += qv[4 * i] * lo[0] + qv[4 * i + 1] * lo[1] + qv[4 * i + 2] * hi[0] + qv[4 * i + 3] * hi[1];
;         }
;         da = sum8(da);
;         da = j < count ? da : -3e30f;
	v_cvt_pk_f32_fp8_e32 v[240:241], v176
	v_cvt_pk_f32_fp8_sdwa v[242:243], v176 src0_sel:WORD_1
	v_cvt_pk_f32_fp8_e32 v[244:245], v177
	v_cvt_pk_f32_fp8_sdwa v[202:203], v177 src0_sel:WORD_1
	v_add_f32_dpp v221, v221, v221 quad_perm:[1,0,3,2] row_mask:0xf bank_mask:0xf bound_ctrl:1
	v_pk_mul_f32 v[204:205], v[240:241], v[28:29]
	v_pk_mul_f32 v[206:207], v[242:243], v[30:31]
	v_add_f32_dpp v221, v221, v221 quad_perm:[2,3,0,1] row_mask:0xf bank_mask:0xf bound_ctrl:1
	v_cvt_pk_f32_fp8_e32 v[240:241], v178
	v_cvt_pk_f32_fp8_sdwa v[242:243], v178 src0_sel:WORD_1
	v_add_f32_dpp v221, v221, v221 row_half_mirror row_mask:0xf bank_mask:0xf bound_ctrl:1
	v_pk_fma_f32 v[204:205], v[244:245], v[32:33], v[204:205]
	v_pk_fma_f32 v[206:207], v[202:203], v[34:35], v[206:207]
	s_add_i32 s0, s1, 9
	s_cmp_lt_i32 s0, s2
	s_cselect_b64 vcc, -1, 0
	v_cvt_pk_f32_fp8_e32 v[244:245], v179
	v_cvt_pk_f32_fp8_sdwa v[202:203], v179 src0_sel:WORD_1
	v_cndmask_b32_e32 v231, v220, v221, vcc
	v_pk_fma_f32 v[204:205], v[240:241], v[36:37], v[204:205]
	v_pk_fma_f32 v[206:207], v[242:243], v[38:39], v[206:207]
	v_pk_fma_f32 v[204:205], v[244:245], v[40:41], v[204:205]
	v_pk_fma_f32 v[206:207], v[202:203], v[42:43], v[206:207]
	v_readlane_b32 s0, v75, 10
	s_lshl_b32 s0, s0, 10
	s_add_u32 s4, s8, s0
	s_addc_u32 s5, s9, 0
	global_load_dwordx4 v[176:179], v16, s[4:5]
	v_pk_add_f32 v[204:205], v[204:205], v[206:207]
	s_nop 0
	v_add_f32_e32 v235, v204, v205
	s_waitcnt vmcnt(15)
	v_cvt_pk_f32_fp8_e32 v[240:241], v180
	v_cvt_pk_f32_fp8_sdwa v[242:243], v180 src0_sel:WORD_1
	v_cvt_pk_f32_fp8_e32 v[244:245], v181
	v_cvt_pk_f32_fp8_sdwa v[202:203], v181 src0_sel:WORD_1
	v_add_f32_dpp v235, v235, v235 quad_perm:[1,0,3,2] row_mask:0xf bank_mask:0xf bound_ctrl:1
	v_pk_mul_f32 v[204:205], v[240:241], v[28:29]
	v_pk_mul_f32 v[206:207], v[242:243], v[30:31]
	v_add_f32_dpp v235, v235, v235 quad_perm:[2,3,0,1] row_mask:0xf bank_mask:0xf bound_ctrl:1
	v_cvt_pk_f32_fp8_e32 v[240:241], v182
	v_cvt_pk_f32_fp8_sdwa v[242:243], v182 src0_sel:WORD_1
	v_add_f32_dpp v235, v235, v235 row_half_mirror row_mask:0xf bank_mask:0xf bound_ctrl:1
	v_pk_fma_f32 v[204:205], v[244:245], v[32:33], v[204:205]
	v_pk_fma_f32 v[206:207], v[202:203], v[34:35], v[206:207]
	s_add_i32 s0, s1, 10
	s_cmp_lt_i32 s0, s2
	s_cselect_b64 vcc, -1, 0
	v_cvt_pk_f32_fp8_e32 v[244:245], v183
	v_cvt_pk_f32_fp8_sdwa v[202:203], v183 src0_sel:WORD_1
	v_cndmask_b32_e32 v232, v220, v235, vcc
	v_pk_fma_f32 v[204:205], v[240:241], v[36:37], v[204:205]
	v_pk_fma_f32 v[206:207], v[242:243], v[38:39], v[206:207]
	v_pk_fma_f32 v[204:205], v[244:245], v[40:41], v[204:205]
	v_pk_fma_f32 v[206:207], v[202:203], v[42:43], v[206:207]
	v_readlane_b32 s0, v75, 11
	s_lshl_b32 s0, s0, 10
	s_add_u32 s4, s8, s0
	s_addc_u32 s5, s9, 0
	global_load_dwordx4 v[180:183], v16, s[4:5]
	v_pk_add_f32 v[204:205], v[204:205], v[206:207]
	s_nop 0
	v_add_f32_e32 v221, v204, v205
	s_waitcnt vmcnt(15)
	v_cvt_pk_f32_fp8_e32 v[240:241], v186
	v_cvt_pk_f32_fp8_sdwa v[242:243], v186 src0_sel:WORD_1
	v_cvt_pk_f32_fp8_e32 v[244:245], v187
	v_cvt_pk_f32_fp8_sdwa v[202:203], v187 src0_sel:WORD_1
	v_add_f32_dpp v221, v221, v221 quad_perm:[1,0,3,2] row_mask:0xf bank_mask:0xf bound_ctrl:1
	v_pk_mul_f32 v[204:205], v[240:241], v[28:29]
	v_pk_mul_f32 v[206:207], v[242:243], v[30:31]
	v_add_f32_dpp v221, v221, v221 quad_perm:[2,3,0,1] row_mask:0xf bank_mask:0xf bound_ctrl:1
	v_cvt_pk_f32_fp8_e32 v[240:241], v188
	v_cvt_pk_f32_fp8_sdwa v[242:243], v188 src0_sel:WORD_1
	v_add_f32_dpp v221, v221, v221 row_half_mirror row_mask:0xf bank_mask:0xf bound_ctrl:1
	v_pk_fma_f32 v[204:205], v[244:245], v[32:33], v[204:205]
	v_pk_fma_f32 v[206:207], v[202:203], v[34:35], v[206:207]
	s_add_i32 s0, s1, 11
	s_cmp_lt_i32 s0, s2
	s_cselect_b64 vcc, -1, 0
	v_cvt_pk_f32_fp8_e32 v[244:245], v189
	v_cvt_pk_f32_fp8_sdwa v[202:203], v189 src0_sel:WORD_1
	v_cndmask_b32_e32 v233, v220, v221, vcc
	v_pk_fma_f32 v[204:205], v[240:241], v[36:37], v[204:205]
	v_pk_fma_f32 v[206:207], v[242:243], v[38:39], v[206:207]
	v_pk_fma_f32 v[204:205], v[244:245], v[40:41], v[204:205]
	v_pk_fma_f32 v[206:207], v[202:203], v[42:43], v[206:207]
	v_readlane_b32 s0, v75, 12
	s_lshl_b32 s0, s0, 10
	s_add_u32 s4, s8, s0
	s_addc_u32 s5, s9, 0
	global_load_dwordx4 v[186:189], v16, s[4:5]
	v_pk_add_f32 v[204:205], v[204:205], v[206:207]
	s_nop 0
	v_add_f32_e32 v235, v204, v205
	s_waitcnt vmcnt(15)
	v_cvt_pk_f32_fp8_e32 v[240:241], v190
	v_cvt_pk_f32_fp8_sdwa v[242:243], v190 src0_sel:WORD_1
	v_cvt_pk_f32_fp8_e32 v[244:245], v191
	v_cvt_pk_f32_fp8_sdwa v[202:203], v191 src0_sel:WORD_1
	v_add_f32_dpp v235, v235, v235 quad_perm:[1,0,3,2] row_mask:0xf bank_mask:0xf bound_ctrl:1
	v_pk_mul_f32 v[204:205], v[240:241], v[28:29]
	v_pk_mul_f32 v[206:207], v[242:243], v[30:31]
	v_add_f32_dpp v235, v235, v235 quad_perm:[2,3,0,1] row_mask:0xf bank_mask:0xf bound_ctrl:1
	v_cvt_pk_f32_fp8_e32 v[240:241], v192
	v_cvt_pk_f32_fp8_sdwa v[242:243], v192 src0_sel:WORD_1
	v_add_f32_dpp v235, v235, v235 row_half_mirror row_mask:0xf bank_mask:0xf bound_ctrl:1
	v_pk_fma_f32 v[204:205], v[244:245], v[32:33], v[204:205]
	v_pk_fma_f32 v[206:207], v[202:203], v[34:35], v[206:207]
	s_add_i32 s0, s1, 12
	s_cmp_lt_i32 s0, s2
	s_cselect_b64 vcc, -1, 0
	v_cvt_pk_f32_fp8_e32 v[244:245], v193
	v_cvt_pk_f32_fp8_sdwa v[202:203], v193 src0_sel:WORD_1
	v_cndmask_b32_e32 v236, v220, v235, vcc
	v_pk_fma_f32 v[204:205], v[240:241], v[36:37], v[204:205]
	v_pk_fma_f32 v[206:207], v[242:243], v[38:39], v[206:207]
	v_pk_fma_f32 v[204:205], v[244:245], v[40:41], v[204:205]
	v_pk_fma_f32 v[206:207], v[202:203], v[42:43], v[206:207]
	v_readlane_b32 s0, v75, 13
	s_lshl_b32 s0, s0, 10
	s_add_u32 s4, s8, s0
	s_addc_u32 s5, s9, 0
	global_load_dwordx4 v[190:193], v16, s[4:5]
	v_pk_add_f32 v[204:205], v[204:205], v[206:207]
	s_nop 0
	v_add_f32_e32 v221, v204, v205
	s_waitcnt vmcnt(15)
; DI float sum8(float v) { v += DPPF(v, 0xB1); v += DPPF(v, 0x4E); v += DPPF(v, 0x141); return v; }
; DI void topk_phase(const bf16_t* PROJ, const unsigned char* K8, const unsigned char* V8, const unsigned short* SC, bf16_t* ODSA, int c, char* smem, int bid, int nb) {
;     ...
;         const size_t ro = (size_t)__builtin_amdgcn_readlane(mysel, jj) * 1024 + lane * 16;
;         const uint4 a = *(const uint4*)(K8 + ro), vv = *(const uint4*)(V8 + ro);
;         const unsigned w[4] = {a.x, a.y, a.z, a.w}, u[4] = {vv.x, vv.y, vv.z, vv.w};
;         float da = 0.f;
; #pragma unroll
;         for (int i = 0; i < 4; ++i) {
;           const f32x2v lo = __builtin_amdgcn_cvt_pk_f32_fp8((int)w[i], false), hi = __builtin_amdgcn_cvt_pk_f32_fp8((int)w[i], true);
;           da += qv[4 * i] * lo[0] + qv[4 * i + 1] * lo[1] + qv[4 * i + 2] * hi[0] + qv[4 * i + 3] * hi[1];
;         }
;         da = sum8(da);
;         da = j < count ? da : -3e30f;
;         const float mn = fmaxf(m_run, da), al = __builtin_amdgcn_exp2f(m_run - mn), pp = __builtin_amdgcn_exp2f(da - mn);
;         m_run = mn; l_run = l_run * al + pp;
; #pragma unroll
;         for (int i = 0; i < 4; ++i) {
;           const f32x2v lo = __builtin_amdgcn_cvt_pk_f32_fp8((int)u[i], false), hi = __builtin_amdgcn_cvt_pk_f32_fp8((int)u[i], true);
;           ov[4 * i] = ov[4 * i] * al + pp * lo[0]; ov[4 * i + 1] = ov[4 * i + 1] * al + pp * lo[1];
;           ov[4 * i + 2] = ov[4 * i + 2] * al + pp * hi[0]; ov[4 * i + 3] = ov[4 * i + 3] * al + pp * hi[1];
;         }
	v_cvt_pk_f32_fp8_e32 v[240:241], v194
	v_cvt_pk_f32_fp8_sdwa v[242:243], v194 src0_sel:WORD_1
	v_cvt_pk_f32_fp8_e32 v[244:245], v195
	v_cvt_pk_f32_fp8_sdwa v[202:203], v195 src0_sel:WORD_1
	v_add_f32_dpp v221, v221, v221 quad_perm:[1,0,3,2] row_mask:0xf bank_mask:0xf bound_ctrl:1
	v_pk_mul_f32 v[204:205], v[240:241], v[28:29]
	v_pk_mul_f32 v[206:207], v[242:243], v[30:31]
	v_add_f32_dpp v221, v221, v221 quad_perm:[2,3,0,1] row_mask:0xf bank_mask:0xf bound_ctrl:1
	v_cvt_pk_f32_fp8_e32 v[240:241], v196
	v_cvt_pk_f32_fp8_sdwa v[242:243], v196 src0_sel:WORD_1
	v_add_f32_dpp v221, v221, v221 row_half_mirror row_mask:0xf bank_mask:0xf bound_ctrl:1
	v_pk_fma_f32 v[204:205], v[244:245], v[32:33], v[204:205]
	v_pk_fma_f32 v[206:207], v[202:203], v[34:35], v[206:207]
	s_add_i32 s0, s1, 13
	s_cmp_lt_i32 s0, s2
	s_cselect_b64 vcc, -1, 0
	v_cvt_pk_f32_fp8_e32 v[244:245], v197
	v_cvt_pk_f32_fp8_sdwa v[202:203], v197 src0_sel:WORD_1
	v_cndmask_b32_e32 v237, v220, v221, vcc
	v_pk_fma_f32 v[204:205], v[240:241], v[36:37], v[204:205]
	v_pk_fma_f32 v[206:207], v[242:243], v[38:39], v[206:207]
	v_pk_fma_f32 v[204:205], v[244:245], v[40:41], v[204:205]
	v_pk_fma_f32 v[206:207], v[202:203], v[42:43], v[206:207]
	v_readlane_b32 s0, v75, 14
	s_lshl_b32 s0, s0, 10
	s_add_u32 s4, s8, s0
	s_addc_u32 s5, s9, 0
	global_load_dwordx4 v[194:197], v16, s[4:5]
	v_pk_add_f32 v[204:205], v[204:205], v[206:207]
	s_nop 0
	v_add_f32_e32 v235, v204, v205
	s_waitcnt vmcnt(15)
	v_cvt_pk_f32_fp8_e32 v[240:241], v198
	v_cvt_pk_f32_fp8_sdwa v[242:243], v198 src0_sel:WORD_1
	v_cvt_pk_f32_fp8_e32 v[244:245], v199
	v_cvt_pk_f32_fp8_sdwa v[202:203], v199 src0_sel:WORD_1
	v_add_f32_dpp v235, v235, v235 quad_perm:[1,0,3,2] row_mask:0xf bank_mask:0xf bound_ctrl:1
	v_pk_mul_f32 v[204:205], v[240:241], v[28:29]
	v_pk_mul_f32 v[206:207], v[242:243], v[30:31]
	v_add_f32_dpp v235, v235, v235 quad_perm:[2,3,0,1] row_mask:0xf bank_mask:0xf bound_ctrl:1
	v_cvt_pk_f32_fp8_e32 v[240:241], v200
	v_cvt_pk_f32_fp8_sdwa v[242:243], v200 src0_sel:WORD_1
	v_add_f32_dpp v235, v235, v235 row_half_mirror row_mask:0xf bank_mask:0xf bound_ctrl:1
	v_pk_fma_f32 v[204:205], v[244:245], v[32:33], v[204:205]
	v_pk_fma_f32 v[206:207], v[202:203], v[34:35], v[206:207]
	s_add_i32 s0, s1, 14
	s_cmp_lt_i32 s0, s2
	s_cselect_b64 vcc, -1, 0
	v_cvt_pk_f32_fp8_e32 v[244:245], v201
	v_cvt_pk_f32_fp8_sdwa v[202:203], v201 src0_sel:WORD_1
	v_cndmask_b32_e32 v238, v220, v235, vcc
	v_pk_fma_f32 v[204:205], v[240:241], v[36:37], v[204:205]
	v_pk_fma_f32 v[206:207], v[242:243], v[38:39], v[206:207]
	v_pk_fma_f32 v[204:205], v[244:245], v[40:41], v[204:205]
	v_pk_fma_f32 v[206:207], v[202:203], v[42:43], v[206:207]
	v_readlane_b32 s0, v75, 15
	s_lshl_b32 s0, s0, 10
	s_add_u32 s4, s8, s0
	s_addc_u32 s5, s9, 0
	global_load_dwordx4 v[198:201], v16, s[4:5]
	v_pk_add_f32 v[204:205], v[204:205], v[206:207]
	s_nop 0
	v_add_f32_e32 v221, v204, v205
	s_nop 1
	v_add_f32_dpp v221, v221, v221 quad_perm:[1,0,3,2] row_mask:0xf bank_mask:0xf bound_ctrl:1
	s_nop 1
	v_add_f32_dpp v221, v221, v221 quad_perm:[2,3,0,1] row_mask:0xf bank_mask:0xf bound_ctrl:1
	s_nop 1
	v_add_f32_dpp v221, v221, v221 row_half_mirror row_mask:0xf bank_mask:0xf bound_ctrl:1
	s_add_i32 s0, s1, 15
	s_cmp_lt_i32 s0, s2
	s_cselect_b64 vcc, -1, 0
	s_nop 1
	v_cndmask_b32_e32 v239, v220, v221, vcc
	v_max3_f32 v224, v210, v211, v212
	v_max3_f32 v224, v224, v213, v226
	v_max3_f32 v224, v224, v227, v228
	v_max3_f32 v224, v224, v229, v230
	v_max3_f32 v224, v224, v231, v232
	v_max3_f32 v224, v224, v233, v236
	v_max3_f32 v224, v224, v237, v238
	v_max_f32_e32 v224, v224, v239
	v_max_f32_e32 v216, v216, v224
	v_sub_f32_e32 v210, v210, v216
	v_exp_f32_e32 v210, v210
	s_waitcnt vmcnt(15)
	v_cvt_pk_f32_fp8_e32 v[240:241], v136
	v_cvt_pk_f32_fp8_sdwa v[242:243], v136 src0_sel:WORD_1
	v_cvt_pk_f32_fp8_e32 v[244:245], v137
	v_pk_fma_f32 v[12:13], v[240:241], v[210:211], v[12:13] op_sel_hi:[1,0,1]
	v_cvt_pk_f32_fp8_sdwa v[240:241], v137 src0_sel:WORD_1
	v_pk_fma_f32 v[14:15], v[242:243], v[210:211], v[14:15] op_sel_hi:[1,0,1]
	v_cvt_pk_f32_fp8_e32 v[242:243], v138
	v_sub_f32_e32 v211, v211, v216
	v_pk_fma_f32 v[8:9], v[244:245], v[210:211], v[8:9] op_sel_hi:[1,0,1]
	v_cvt_pk_f32_fp8_sdwa v[244:245], v138 src0_sel:WORD_1
	v_pk_fma_f32 v[10:11], v[240:241], v[210:211], v[10:11] op_sel_hi:[1,0,1]
	v_cvt_pk_f32_fp8_e32 v[240:241], v139
	v_exp_f32_e32 v211, v211
	v_pk_fma_f32 v[4:5], v[242:243], v[210:211], v[4:5] op_sel_hi:[1,0,1]
	v_cvt_pk_f32_fp8_sdwa v[242:243], v139 src0_sel:WORD_1
	v_pk_fma_f32 v[6:7], v[244:245], v[210:211], v[6:7] op_sel_hi:[1,0,1]
	v_add_f32_e32 v215, v215, v210
	v_pk_fma_f32 v[0:1], v[240:241], v[210:211], v[0:1] op_sel_hi:[1,0,1]
	v_pk_fma_f32 v[2:3], v[242:243], v[210:211], v[2:3] op_sel_hi:[1,0,1]
	v_readlane_b32 s0, v75, 16
	s_lshl_b32 s0, s0, 10
	s_add_u32 s4, s6, s0
	s_addc_u32 s5, s7, 0
	global_load_dwordx4 v[136:139], v16, s[4:5]
	s_waitcnt vmcnt(15)
	v_cvt_pk_f32_fp8_e32 v[240:241], v140
	v_cvt_pk_f32_fp8_sdwa v[242:243], v140 src0_sel:WORD_1
	v_cvt_pk_f32_fp8_e32 v[244:245], v141
	v_pk_fma_f32 v[12:13], v[240:241], v[210:211], v[12:13] op_sel:[0,1,0]
	v_cvt_pk_f32_fp8_sdwa v[240:241], v141 src0_sel:WORD_1
	v_pk_fma_f32 v[14:15], v[242:243], v[210:211], v[14:15] op_sel:[0,1,0]
	v_cvt_pk_f32_fp8_e32 v[242:243], v142
	v_sub_f32_e32 v212, v212, v216
	v_pk_fma_f32 v[8:9], v[244:245], v[210:211], v[8:9] op_sel:[0,1,0]
	v_cvt_pk_f32_fp8_sdwa v[244:245], v142 src0_sel:WORD_1
	v_pk_fma_f32 v[10:11], v[240:241], v[210:211], v[10:11] op_sel:[0,1,0]
	v_cvt_pk_f32_fp8_e32 v[240:241], v143
	v_exp_f32_e32 v212, v212
	v_pk_fma_f32 v[4:5], v[242:243], v[210:211], v[4:5] op_sel:[0,1,0]
	v_cvt_pk_f32_fp8_sdwa v[242:243], v143 src0_sel:WORD_1
	v_pk_fma_f32 v[6:7], v[244:245], v[210:211], v[6:7] op_sel:[0,1,0]
	v_add_f32_e32 v215, v215, v211
	v_pk_fma_f32 v[0:1], v[240:241], v[210:211], v[0:1] op_sel:[0,1,0]
	v_pk_fma_f32 v[2:3], v[242:243], v[210:211], v[2:3] op_sel:[0,1,0]
	v_readlane_b32 s0, v75, 17
	s_lshl_b32 s0, s0, 10
	s_add_u32 s4, s6, s0
	s_addc_u32 s5, s7, 0
	global_load_dwordx4 v[140:143], v16, s[4:5]
	s_waitcnt vmcnt(15)
; DI void topk_phase(const bf16_t* PROJ, const unsigned char* K8, const unsigned char* V8, const unsigned short* SC, bf16_t* ODSA, int c, char* smem, int bid, int nb) {
;     ...
;         const float mn = fmaxf(m_run, da), al = __builtin_amdgcn_exp2f(m_run - mn), pp = __builtin_amdgcn_exp2f(da - mn);
;         m_run = mn; l_run = l_run * al + pp;
; #pragma unroll
;         for (int i = 0; i < 4; ++i) {
;           const f32x2v lo = __builtin_amdgcn_cvt_pk_f32_fp8((int)u[i], false), hi = __builtin_amdgcn_cvt_pk_f32_fp8((int)u[i], true);
;           ov[4 * i] = ov[4 * i] * al + pp * lo[0]; ov[4 * i + 1] = ov[4 * i + 1] * al + pp * lo[1];
;           ov[4 * i + 2] = ov[4 * i + 2] * al + pp * hi[0]; ov[4 * i + 3] = ov[4 * i + 3] * al + pp * hi[1];
;         }
	v_cvt_pk_f32_fp8_e32 v[240:241], v144
	v_cvt_pk_f32_fp8_sdwa v[242:243], v144 src0_sel:WORD_1
	v_cvt_pk_f32_fp8_e32 v[244:245], v145
	v_pk_fma_f32 v[12:13], v[240:241], v[212:213], v[12:13] op_sel_hi:[1,0,1]
	v_cvt_pk_f32_fp8_sdwa v[240:241], v145 src0_sel:WORD_1
	v_pk_fma_f32 v[14:15], v[242:243], v[212:213], v[14:15] op_sel_hi:[1,0,1]
	v_cvt_pk_f32_fp8_e32 v[242:243], v146
	v_sub_f32_e32 v213, v213, v216
	v_pk_fma_f32 v[8:9], v[244:245], v[212:213], v[8:9] op_sel_hi:[1,0,1]
	v_cvt_pk_f32_fp8_sdwa v[244:245], v146 src0_sel:WORD_1
	v_pk_fma_f32 v[10:11], v[240:241], v[212:213], v[10:11] op_sel_hi:[1,0,1]
	v_cvt_pk_f32_fp8_e32 v[240:241], v147
	v_exp_f32_e32 v213, v213
	v_pk_fma_f32 v[4:5], v[242:243], v[212:213], v[4:5] op_sel_hi:[1,0,1]
	v_cvt_pk_f32_fp8_sdwa v[242:243], v147 src0_sel:WORD_1
	v_pk_fma_f32 v[6:7], v[244:245], v[212:213], v[6:7] op_sel_hi:[1,0,1]
	v_add_f32_e32 v215, v215, v212
	v_pk_fma_f32 v[0:1], v[240:241], v[212:213], v[0:1] op_sel_hi:[1,0,1]
	v_pk_fma_f32 v[2:3], v[242:243], v[212:213], v[2:3] op_sel_hi:[1,0,1]
	v_readlane_b32 s0, v75, 18
	s_lshl_b32 s0, s0, 10
	s_add_u32 s4, s6, s0
	s_addc_u32 s5, s7, 0
	global_load_dwordx4 v[144:147], v16, s[4:5]
	s_waitcnt vmcnt(15)
	v_cvt_pk_f32_fp8_e32 v[240:241], v148
	v_cvt_pk_f32_fp8_sdwa v[242:243], v148 src0_sel:WORD_1
	v_cvt_pk_f32_fp8_e32 v[244:245], v149
	v_pk_fma_f32 v[12:13], v[240:241], v[212:213], v[12:13] op_sel:[0,1,0]
	v_cvt_pk_f32_fp8_sdwa v[240:241], v149 src0_sel:WORD_1
	v_pk_fma_f32 v[14:15], v[242:243], v[212:213], v[14:15] op_sel:[0,1,0]
	v_cvt_pk_f32_fp8_e32 v[242:243], v150
	v_sub_f32_e32 v226, v226, v216
	v_pk_fma_f32 v[8:9], v[244:245], v[212:213], v[8:9] op_sel:[0,1,0]
	v_cvt_pk_f32_fp8_sdwa v[244:245], v150 src0_sel:WORD_1
	v_pk_fma_f32 v[10:11], v[240:241], v[212:213], v[10:11] op_sel:[0,1,0]
	v_cvt_pk_f32_fp8_e32 v[240:241], v151
	v_exp_f32_e32 v226, v226
	v_pk_fma_f32 v[4:5], v[242:243], v[212:213], v[4:5] op_sel:[0,1,0]
	v_cvt_pk_f32_fp8_sdwa v[242:243], v151 src0_sel:WORD_1
	v_pk_fma_f32 v[6:7], v[244:245], v[212:213], v[6:7] op_sel:[0,1,0]
	v_add_f32_e32 v215, v215, v213
	v_pk_fma_f32 v[0:1], v[240:241], v[212:213], v[0:1] op_sel:[0,1,0]
	v_pk_fma_f32 v[2:3], v[242:243], v[212:213], v[2:3] op_sel:[0,1,0]
	v_readlane_b32 s0, v75, 19
	s_lshl_b32 s0, s0, 10
	s_add_u32 s4, s6, s0
	s_addc_u32 s5, s7, 0
	global_load_dwordx4 v[148:151], v16, s[4:5]
	s_waitcnt vmcnt(15)
	v_cvt_pk_f32_fp8_e32 v[240:241], v152
	v_cvt_pk_f32_fp8_sdwa v[242:243], v152 src0_sel:WORD_1
	v_cvt_pk_f32_fp8_e32 v[244:245], v153
	v_pk_fma_f32 v[12:13], v[240:241], v[226:227], v[12:13] op_sel_hi:[1,0,1]
	v_cvt_pk_f32_fp8_sdwa v[240:241], v153 src0_sel:WORD_1
	v_pk_fma_f32 v[14:15], v[242:243], v[226:227], v[14:15] op_sel_hi:[1,0,1]
	v_cvt_pk_f32_fp8_e32 v[242:243], v154
	v_sub_f32_e32 v227, v227, v216
	v_pk_fma_f32 v[8:9], v[244:245], v[226:227], v[8:9] op_sel_hi:[1,0,1]
	v_cvt_pk_f32_fp8_sdwa v[244:245], v154 src0_sel:WORD_1
	v_pk_fma_f32 v[10:11], v[240:241], v[226:227], v[10:11] op_sel_hi:[1,0,1]
	v_cvt_pk_f32_fp8_e32 v[240:241], v155
	v_exp_f32_e32 v227, v227
	v_pk_fma_f32 v[4:5], v[242:243], v[226:227], v[4:5] op_sel_hi:[1,0,1]
	v_cvt_pk_f32_fp8_sdwa v[242:243], v155 src0_sel:WORD_1
	v_pk_fma_f32 v[6:7], v[244:245], v[226:227], v[6:7] op_sel_hi:[1,0,1]
	v_add_f32_e32 v215, v215, v226
	v_pk_fma_f32 v[0:1], v[240:241], v[226:227], v[0:1] op_sel_hi:[1,0,1]
	v_pk_fma_f32 v[2:3], v[242:243], v[226:227], v[2:3] op_sel_hi:[1,0,1]
	v_readlane_b32 s0, v75, 20
	s_lshl_b32 s0, s0, 10
	s_add_u32 s4, s6, s0
	s_addc_u32 s5, s7, 0
	global_load_dwordx4 v[152:155], v16, s[4:5]
	s_waitcnt vmcnt(15)
	v_cvt_pk_f32_fp8_e32 v[240:241], v156
	v_cvt_pk_f32_fp8_sdwa v[242:243], v156 src0_sel:WORD_1
	v_cvt_pk_f32_fp8_e32 v[244:245], v157
	v_pk_fma_f32 v[12:13], v[240:241], v[226:227], v[12:13] op_sel:[0,1,0]
	v_cvt_pk_f32_fp8_sdwa v[240:241], v157 src0_sel:WORD_1
	v_pk_fma_f32 v[14:15], v[242:243], v[226:227], v[14:15] op_sel:[0,1,0]
	v_cvt_pk_f32_fp8_e32 v[242:243], v158
	v_sub_f32_e32 v228, v228, v216
	v_pk_fma_f32 v[8:9], v[244:245], v[226:227], v[8:9] op_sel:[0,1,0]
	v_cvt_pk_f32_fp8_sdwa v[244:245], v158 src0_sel:WORD_1
	v_pk_fma_f32 v[10:11], v[240:241], v[226:227], v[10:11] op_sel:[0,1,0]
	v_cvt_pk_f32_fp8_e32 v[240:241], v159
	v_exp_f32_e32 v228, v228
	v_pk_fma_f32 v[4:5], v[242:243], v[226:227], v[4:5] op_sel:[0,1,0]
	v_cvt_pk_f32_fp8_sdwa v[242:243], v159 src0_sel:WORD_1
	v_pk_fma_f32 v[6:7], v[244:245], v[226:227], v[6:7] op_sel:[0,1,0]
	v_add_f32_e32 v215, v215, v227
	v_pk_fma_f32 v[0:1], v[240:241], v[226:227], v[0:1] op_sel:[0,1,0]
	v_pk_fma_f32 v[2:3], v[242:243], v[226:227], v[2:3] op_sel:[0,1,0]
	v_readlane_b32 s0, v75, 21
	s_lshl_b32 s0, s0, 10
	s_add_u32 s4, s6, s0
	s_addc_u32 s5, s7, 0
	global_load_dwordx4 v[156:159], v16, s[4:5]
	s_waitcnt vmcnt(15)
	v_cvt_pk_f32_fp8_e32 v[240:241], v160
	v_cvt_pk_f32_fp8_sdwa v[242:243], v160 src0_sel:WORD_1
	v_cvt_pk_f32_fp8_e32 v[244:245], v161
	v_pk_fma_f32 v[12:13], v[240:241], v[228:229], v[12:13] op_sel_hi:[1,0,1]
	v_cvt_pk_f32_fp8_sdwa v[240:241], v161 src0_sel:WORD_1
	v_pk_fma_f32 v[14:15], v[242:243], v[228:229], v[14:15] op_sel_hi:[1,0,1]
	v_cvt_pk_f32_fp8_e32 v[242:243], v162
	v_sub_f32_e32 v229, v229, v216
	v_pk_fma_f32 v[8:9], v[244:245], v[228:229], v[8:9] op_sel_hi:[1,0,1]
	v_cvt_pk_f32_fp8_sdwa v[244:245], v162 src0_sel:WORD_1
	v_pk_fma_f32 v[10:11], v[240:241], v[228:229], v[10:11] op_sel_hi:[1,0,1]
	v_cvt_pk_f32_fp8_e32 v[240:241], v163
	v_exp_f32_e32 v229, v229
	v_pk_fma_f32 v[4:5], v[242:243], v[228:229], v[4:5] op_sel_hi:[1,0,1]
	v_cvt_pk_f32_fp8_sdwa v[242:243], v163 src0_sel:WORD_1
	v_pk_fma_f32 v[6:7], v[244:245], v[228:229], v[6:7] op_sel_hi:[1,0,1]
	v_add_f32_e32 v215, v215, v228
	v_pk_fma_f32 v[0:1], v[240:241], v[228:229], v[0:1] op_sel_hi:[1,0,1]
	v_pk_fma_f32 v[2:3], v[242:243], v[228:229], v[2:3] op_sel_hi:[1,0,1]
	v_readlane_b32 s0, v75, 22
	s_lshl_b32 s0, s0, 10
	s_add_u32 s4, s6, s0
	s_addc_u32 s5, s7, 0
	global_load_dwordx4 v[160:163], v16, s[4:5]
	s_waitcnt vmcnt(15)
; DI void topk_phase(const bf16_t* PROJ, const unsigned char* K8, const unsigned char* V8, const unsigned short* SC, bf16_t* ODSA, int c, char* smem, int bid, int nb) {
;     ...
;         const float mn = fmaxf(m_run, da), al = __builtin_amdgcn_exp2f(m_run - mn), pp = __builtin_amdgcn_exp2f(da - mn);
;         m_run = mn; l_run = l_run * al + pp;
; #pragma unroll
;         for (int i = 0; i < 4; ++i) {
;           const f32x2v lo = __builtin_amdgcn_cvt_pk_f32_fp8((int)u[i], false), hi = __builtin_amdgcn_cvt_pk_f32_fp8((int)u[i], true);
;           ov[4 * i] = ov[4 * i] * al + pp * lo[0]; ov[4 * i + 1] = ov[4 * i + 1] * al + pp * lo[1];
;           ov[4 * i + 2] = ov[4 * i + 2] * al + pp * hi[0]; ov[4 * i + 3] = ov[4 * i + 3] * al + pp * hi[1];
;         }
	v_cvt_pk_f32_fp8_e32 v[240:241], v164
	v_cvt_pk_f32_fp8_sdwa v[242:243], v164 src0_sel:WORD_1
	v_cvt_pk_f32_fp8_e32 v[244:245], v165
	v_pk_fma_f32 v[12:13], v[240:241], v[228:229], v[12:13] op_sel:[0,1,0]
	v_cvt_pk_f32_fp8_sdwa v[240:241], v165 src0_sel:WORD_1
	v_pk_fma_f32 v[14:15], v[242:243], v[228:229], v[14:15] op_sel:[0,1,0]
	v_cvt_pk_f32_fp8_e32 v[242:243], v166
	v_sub_f32_e32 v230, v230, v216
	v_pk_fma_f32 v[8:9], v[244:245], v[228:229], v[8:9] op_sel:[0,1,0]
	v_cvt_pk_f32_fp8_sdwa v[244:245], v166 src0_sel:WORD_1
	v_pk_fma_f32 v[10:11], v[240:241], v[228:229], v[10:11] op_sel:[0,1,0]
	v_cvt_pk_f32_fp8_e32 v[240:241], v167
	v_exp_f32_e32 v230, v230
	v_pk_fma_f32 v[4:5], v[242:243], v[228:229], v[4:5] op_sel:[0,1,0]
	v_cvt_pk_f32_fp8_sdwa v[242:243], v167 src0_sel:WORD_1
	v_pk_fma_f32 v[6:7], v[244:245], v[228:229], v[6:7] op_sel:[0,1,0]
	v_add_f32_e32 v215, v215, v229
	v_pk_fma_f32 v[0:1], v[240:241], v[228:229], v[0:1] op_sel:[0,1,0]
	v_pk_fma_f32 v[2:3], v[242:243], v[228:229], v[2:3] op_sel:[0,1,0]
	v_readlane_b32 s0, v75, 23
	s_lshl_b32 s0, s0, 10
	s_add_u32 s4, s6, s0
	s_addc_u32 s5, s7, 0
	global_load_dwordx4 v[164:167], v16, s[4:5]
	s_waitcnt vmcnt(15)
	v_cvt_pk_f32_fp8_e32 v[240:241], v168
	v_cvt_pk_f32_fp8_sdwa v[242:243], v168 src0_sel:WORD_1
	v_cvt_pk_f32_fp8_e32 v[244:245], v169
	v_pk_fma_f32 v[12:13], v[240:241], v[230:231], v[12:13] op_sel_hi:[1,0,1]
	v_cvt_pk_f32_fp8_sdwa v[240:241], v169 src0_sel:WORD_1
	v_pk_fma_f32 v[14:15], v[242:243], v[230:231], v[14:15] op_sel_hi:[1,0,1]
	v_cvt_pk_f32_fp8_e32 v[242:243], v170
	v_sub_f32_e32 v231, v231, v216
	v_pk_fma_f32 v[8:9], v[244:245], v[230:231], v[8:9] op_sel_hi:[1,0,1]
	v_cvt_pk_f32_fp8_sdwa v[244:245], v170 src0_sel:WORD_1
	v_pk_fma_f32 v[10:11], v[240:241], v[230:231], v[10:11] op_sel_hi:[1,0,1]
	v_cvt_pk_f32_fp8_e32 v[240:241], v171
	v_exp_f32_e32 v231, v231
	v_pk_fma_f32 v[4:5], v[242:243], v[230:231], v[4:5] op_sel_hi:[1,0,1]
	v_cvt_pk_f32_fp8_sdwa v[242:243], v171 src0_sel:WORD_1
	v_pk_fma_f32 v[6:7], v[244:245], v[230:231], v[6:7] op_sel_hi:[1,0,1]
	v_add_f32_e32 v215, v215, v230
	v_pk_fma_f32 v[0:1], v[240:241], v[230:231], v[0:1] op_sel_hi:[1,0,1]
	v_pk_fma_f32 v[2:3], v[242:243], v[230:231], v[2:3] op_sel_hi:[1,0,1]
	v_readlane_b32 s0, v75, 24
	s_lshl_b32 s0, s0, 10
	s_add_u32 s4, s6, s0
	s_addc_u32 s5, s7, 0
	global_load_dwordx4 v[168:171], v16, s[4:5]
	s_waitcnt vmcnt(15)
	v_cvt_pk_f32_fp8_e32 v[240:241], v172
	v_cvt_pk_f32_fp8_sdwa v[242:243], v172 src0_sel:WORD_1
	v_cvt_pk_f32_fp8_e32 v[244:245], v173
	v_pk_fma_f32 v[12:13], v[240:241], v[230:231], v[12:13] op_sel:[0,1,0]
	v_cvt_pk_f32_fp8_sdwa v[240:241], v173 src0_sel:WORD_1
	v_pk_fma_f32 v[14:15], v[242:243], v[230:231], v[14:15] op_sel:[0,1,0]
	v_cvt_pk_f32_fp8_e32 v[242:243], v174
	v_sub_f32_e32 v232, v232, v216
	v_pk_fma_f32 v[8:9], v[244:245], v[230:231], v[8:9] op_sel:[0,1,0]
	v_cvt_pk_f32_fp8_sdwa v[244:245], v174 src0_sel:WORD_1
	v_pk_fma_f32 v[10:11], v[240:241], v[230:231], v[10:11] op_sel:[0,1,0]
	v_cvt_pk_f32_fp8_e32 v[240:241], v175
	v_exp_f32_e32 v232, v232
	v_pk_fma_f32 v[4:5], v[242:243], v[230:231], v[4:5] op_sel:[0,1,0]
	v_cvt_pk_f32_fp8_sdwa v[242:243], v175 src0_sel:WORD_1
	v_pk_fma_f32 v[6:7], v[244:245], v[230:231], v[6:7] op_sel:[0,1,0]
	v_add_f32_e32 v215, v215, v231
	v_pk_fma_f32 v[0:1], v[240:241], v[230:231], v[0:1] op_sel:[0,1,0]
	v_pk_fma_f32 v[2:3], v[242:243], v[230:231], v[2:3] op_sel:[0,1,0]
	v_readlane_b32 s0, v75, 25
	s_lshl_b32 s0, s0, 10
	s_add_u32 s4, s6, s0
	s_addc_u32 s5, s7, 0
	global_load_dwordx4 v[172:175], v16, s[4:5]
	s_waitcnt vmcnt(15)
	v_cvt_pk_f32_fp8_e32 v[240:241], v176
	v_cvt_pk_f32_fp8_sdwa v[242:243], v176 src0_sel:WORD_1
	v_cvt_pk_f32_fp8_e32 v[244:245], v177
	v_pk_fma_f32 v[12:13], v[240:241], v[232:233], v[12:13] op_sel_hi:[1,0,1]
	v_cvt_pk_f32_fp8_sdwa v[240:241], v177 src0_sel:WORD_1
	v_pk_fma_f32 v[14:15], v[242:243], v[232:233], v[14:15] op_sel_hi:[1,0,1]
	v_cvt_pk_f32_fp8_e32 v[242:243], v178
	v_sub_f32_e32 v233, v233, v216
	v_pk_fma_f32 v[8:9], v[244:245], v[232:233], v[8:9] op_sel_hi:[1,0,1]
	v_cvt_pk_f32_fp8_sdwa v[244:245], v178 src0_sel:WORD_1
	v_pk_fma_f32 v[10:11], v[240:241], v[232:233], v[10:11] op_sel_hi:[1,0,1]
	v_cvt_pk_f32_fp8_e32 v[240:241], v179
	v_exp_f32_e32 v233, v233
	v_pk_fma_f32 v[4:5], v[242:243], v[232:233], v[4:5] op_sel_hi:[1,0,1]
	v_cvt_pk_f32_fp8_sdwa v[242:243], v179 src0_sel:WORD_1
	v_pk_fma_f32 v[6:7], v[244:245], v[232:233], v[6:7] op_sel_hi:[1,0,1]
	v_add_f32_e32 v215, v215, v232
	v_pk_fma_f32 v[0:1], v[240:241], v[232:233], v[0:1] op_sel_hi:[1,0,1]
	v_pk_fma_f32 v[2:3], v[242:243], v[232:233], v[2:3] op_sel_hi:[1,0,1]
	v_readlane_b32 s0, v75, 26
	s_lshl_b32 s0, s0, 10
	s_add_u32 s4, s6, s0
	s_addc_u32 s5, s7, 0
	global_load_dwordx4 v[176:179], v16, s[4:5]
	s_waitcnt vmcnt(15)
	v_cvt_pk_f32_fp8_e32 v[240:241], v180
	v_cvt_pk_f32_fp8_sdwa v[242:243], v180 src0_sel:WORD_1
	v_cvt_pk_f32_fp8_e32 v[244:245], v181
	v_pk_fma_f32 v[12:13], v[240:241], v[232:233], v[12:13] op_sel:[0,1,0]
	v_cvt_pk_f32_fp8_sdwa v[240:241], v181 src0_sel:WORD_1
	v_pk_fma_f32 v[14:15], v[242:243], v[232:233], v[14:15] op_sel:[0,1,0]
	v_cvt_pk_f32_fp8_e32 v[242:243], v182
	v_sub_f32_e32 v236, v236, v216
	v_pk_fma_f32 v[8:9], v[244:245], v[232:233], v[8:9] op_sel:[0,1,0]
	v_cvt_pk_f32_fp8_sdwa v[244:245], v182 src0_sel:WORD_1
	v_pk_fma_f32 v[10:11], v[240:241], v[232:233], v[10:11] op_sel:[0,1,0]
	v_cvt_pk_f32_fp8_e32 v[240:241], v183
	v_exp_f32_e32 v236, v236
	v_pk_fma_f32 v[4:5], v[242:243], v[232:233], v[4:5] op_sel:[0,1,0]
	v_cvt_pk_f32_fp8_sdwa v[242:243], v183 src0_sel:WORD_1
	v_pk_fma_f32 v[6:7], v[244:245], v[232:233], v[6:7] op_sel:[0,1,0]
	v_add_f32_e32 v215, v215, v233
	v_pk_fma_f32 v[0:1], v[240:241], v[232:233], v[0:1] op_sel:[0,1,0]
	v_pk_fma_f32 v[2:3], v[242:243], v[232:233], v[2:3] op_sel:[0,1,0]
	v_readlane_b32 s0, v75, 27
	s_lshl_b32 s0, s0, 10
	s_add_u32 s4, s6, s0
	s_addc_u32 s5, s7, 0
	global_load_dwordx4 v[180:183], v16, s[4:5]
	s_waitcnt vmcnt(15)
; DI float sum8(float v) { v += DPPF(v, 0xB1); v += DPPF(v, 0x4E); v += DPPF(v, 0x141); return v; }
; DI void topk_phase(const bf16_t* PROJ, const unsigned char* K8, const unsigned char* V8, const unsigned short* SC, bf16_t* ODSA, int c, char* smem, int bid, int nb) {
;     ...
;         const size_t ro = (size_t)__builtin_amdgcn_readlane(mysel, jj) * 1024 + lane * 16;
;         const uint4 a = *(const uint4*)(K8 + ro), vv = *(const uint4*)(V8 + ro);
;         const unsigned w[4] = {a.x, a.y, a.z, a.w}, u[4] = {vv.x, vv.y, vv.z, vv.w};
;         float da = 0.f;
; #pragma unroll
;         for (int i = 0; i < 4; ++i) {
;           const f32x2v lo = __builtin_amdgcn_cvt_pk_f32_fp8((int)w[i], false), hi = __builtin_amdgcn_cvt_pk_f32_fp8((int)w[i], true);
;           da += qv[4 * i] * lo[0] + qv[4 * i + 1] * lo[1] + qv[4 * i + 2] * hi[0] + qv[4 * i + 3] * hi[1];
;         }
;         da = sum8(da);
;     ...
;         const float mn = fmaxf(m_run, da), al = __builtin_amdgcn_exp2f(m_run - mn), pp = __builtin_amdgcn_exp2f(da - mn);
;         m_run = mn; l_run = l_run * al + pp;
; #pragma unroll
;         for (int i = 0; i < 4; ++i) {
;           const f32x2v lo = __builtin_amdgcn_cvt_pk_f32_fp8((int)u[i], false), hi = __builtin_amdgcn_cvt_pk_f32_fp8((int)u[i], true);
;           ov[4 * i] = ov[4 * i] * al + pp * lo[0]; ov[4 * i + 1] = ov[4 * i + 1] * al + pp * lo[1];
;           ov[4 * i + 2] = ov[4 * i + 2] * al + pp * hi[0]; ov[4 * i + 3] = ov[4 * i + 3] * al + pp * hi[1];
;         }
	v_cvt_pk_f32_fp8_e32 v[240:241], v186
	v_cvt_pk_f32_fp8_sdwa v[242:243], v186 src0_sel:WORD_1
	v_cvt_pk_f32_fp8_e32 v[244:245], v187
	v_pk_fma_f32 v[12:13], v[240:241], v[236:237], v[12:13] op_sel_hi:[1,0,1]
	v_cvt_pk_f32_fp8_sdwa v[240:241], v187 src0_sel:WORD_1
	v_pk_fma_f32 v[14:15], v[242:243], v[236:237], v[14:15] op_sel_hi:[1,0,1]
	v_cvt_pk_f32_fp8_e32 v[242:243], v188
	v_sub_f32_e32 v237, v237, v216
	v_pk_fma_f32 v[8:9], v[244:245], v[236:237], v[8:9] op_sel_hi:[1,0,1]
	v_cvt_pk_f32_fp8_sdwa v[244:245], v188 src0_sel:WORD_1
	v_pk_fma_f32 v[10:11], v[240:241], v[236:237], v[10:11] op_sel_hi:[1,0,1]
	v_cvt_pk_f32_fp8_e32 v[240:241], v189
	v_exp_f32_e32 v237, v237
	v_pk_fma_f32 v[4:5], v[242:243], v[236:237], v[4:5] op_sel_hi:[1,0,1]
	v_cvt_pk_f32_fp8_sdwa v[242:243], v189 src0_sel:WORD_1
	v_pk_fma_f32 v[6:7], v[244:245], v[236:237], v[6:7] op_sel_hi:[1,0,1]
	v_add_f32_e32 v215, v215, v236
	v_pk_fma_f32 v[0:1], v[240:241], v[236:237], v[0:1] op_sel_hi:[1,0,1]
	v_pk_fma_f32 v[2:3], v[242:243], v[236:237], v[2:3] op_sel_hi:[1,0,1]
	v_readlane_b32 s0, v75, 28
	s_lshl_b32 s0, s0, 10
	s_add_u32 s4, s6, s0
	s_addc_u32 s5, s7, 0
	global_load_dwordx4 v[186:189], v16, s[4:5]
	s_waitcnt vmcnt(15)
	v_cvt_pk_f32_fp8_e32 v[240:241], v190
	v_cvt_pk_f32_fp8_sdwa v[242:243], v190 src0_sel:WORD_1
	v_cvt_pk_f32_fp8_e32 v[244:245], v191
	v_pk_fma_f32 v[12:13], v[240:241], v[236:237], v[12:13] op_sel:[0,1,0]
	v_cvt_pk_f32_fp8_sdwa v[240:241], v191 src0_sel:WORD_1
	v_pk_fma_f32 v[14:15], v[242:243], v[236:237], v[14:15] op_sel:[0,1,0]
	v_cvt_pk_f32_fp8_e32 v[242:243], v192
	v_sub_f32_e32 v238, v238, v216
	v_pk_fma_f32 v[8:9], v[244:245], v[236:237], v[8:9] op_sel:[0,1,0]
	v_cvt_pk_f32_fp8_sdwa v[244:245], v192 src0_sel:WORD_1
	v_pk_fma_f32 v[10:11], v[240:241], v[236:237], v[10:11] op_sel:[0,1,0]
	v_cvt_pk_f32_fp8_e32 v[240:241], v193
	v_exp_f32_e32 v238, v238
	v_pk_fma_f32 v[4:5], v[242:243], v[236:237], v[4:5] op_sel:[0,1,0]
	v_cvt_pk_f32_fp8_sdwa v[242:243], v193 src0_sel:WORD_1
	v_pk_fma_f32 v[6:7], v[244:245], v[236:237], v[6:7] op_sel:[0,1,0]
	v_add_f32_e32 v215, v215, v237
	v_pk_fma_f32 v[0:1], v[240:241], v[236:237], v[0:1] op_sel:[0,1,0]
	v_pk_fma_f32 v[2:3], v[242:243], v[236:237], v[2:3] op_sel:[0,1,0]
	v_readlane_b32 s0, v75, 29
	s_lshl_b32 s0, s0, 10
	s_add_u32 s4, s6, s0
	s_addc_u32 s5, s7, 0
	global_load_dwordx4 v[190:193], v16, s[4:5]
	s_waitcnt vmcnt(15)
	v_cvt_pk_f32_fp8_e32 v[240:241], v194
	v_cvt_pk_f32_fp8_sdwa v[242:243], v194 src0_sel:WORD_1
	v_cvt_pk_f32_fp8_e32 v[244:245], v195
	v_pk_fma_f32 v[12:13], v[240:241], v[238:239], v[12:13] op_sel_hi:[1,0,1]
	v_cvt_pk_f32_fp8_sdwa v[240:241], v195 src0_sel:WORD_1
	v_pk_fma_f32 v[14:15], v[242:243], v[238:239], v[14:15] op_sel_hi:[1,0,1]
	v_cvt_pk_f32_fp8_e32 v[242:243], v196
	v_sub_f32_e32 v239, v239, v216
	v_pk_fma_f32 v[8:9], v[244:245], v[238:239], v[8:9] op_sel_hi:[1,0,1]
	v_cvt_pk_f32_fp8_sdwa v[244:245], v196 src0_sel:WORD_1
	v_pk_fma_f32 v[10:11], v[240:241], v[238:239], v[10:11] op_sel_hi:[1,0,1]
	v_cvt_pk_f32_fp8_e32 v[240:241], v197
	v_exp_f32_e32 v239, v239
	v_pk_fma_f32 v[4:5], v[242:243], v[238:239], v[4:5] op_sel_hi:[1,0,1]
	v_cvt_pk_f32_fp8_sdwa v[242:243], v197 src0_sel:WORD_1
	v_pk_fma_f32 v[6:7], v[244:245], v[238:239], v[6:7] op_sel_hi:[1,0,1]
	v_add_f32_e32 v215, v215, v238
	v_pk_fma_f32 v[0:1], v[240:241], v[238:239], v[0:1] op_sel_hi:[1,0,1]
	v_pk_fma_f32 v[2:3], v[242:243], v[238:239], v[2:3] op_sel_hi:[1,0,1]
	v_readlane_b32 s0, v75, 30
	s_lshl_b32 s0, s0, 10
	s_add_u32 s4, s6, s0
	s_addc_u32 s5, s7, 0
	global_load_dwordx4 v[194:197], v16, s[4:5]
	s_waitcnt vmcnt(15)
	v_cvt_pk_f32_fp8_e32 v[240:241], v198
	v_cvt_pk_f32_fp8_sdwa v[242:243], v198 src0_sel:WORD_1
	v_cvt_pk_f32_fp8_e32 v[244:245], v199
	v_pk_fma_f32 v[12:13], v[240:241], v[238:239], v[12:13] op_sel:[0,1,0]
	v_cvt_pk_f32_fp8_sdwa v[240:241], v199 src0_sel:WORD_1
	v_pk_fma_f32 v[14:15], v[242:243], v[238:239], v[14:15] op_sel:[0,1,0]
	v_cvt_pk_f32_fp8_e32 v[242:243], v200
	v_add_f32_e32 v215, v215, v239
	v_pk_fma_f32 v[8:9], v[244:245], v[238:239], v[8:9] op_sel:[0,1,0]
	v_cvt_pk_f32_fp8_sdwa v[244:245], v200 src0_sel:WORD_1
	v_pk_fma_f32 v[10:11], v[240:241], v[238:239], v[10:11] op_sel:[0,1,0]
	v_cvt_pk_f32_fp8_e32 v[240:241], v201
	v_pk_fma_f32 v[4:5], v[242:243], v[238:239], v[4:5] op_sel:[0,1,0]
	v_cvt_pk_f32_fp8_sdwa v[242:243], v201 src0_sel:WORD_1
	v_pk_fma_f32 v[6:7], v[244:245], v[238:239], v[6:7] op_sel:[0,1,0]
	v_pk_fma_f32 v[0:1], v[240:241], v[238:239], v[0:1] op_sel:[0,1,0]
	v_pk_fma_f32 v[2:3], v[242:243], v[238:239], v[2:3] op_sel:[0,1,0]
	v_readlane_b32 s0, v75, 31
	s_lshl_b32 s0, s0, 10
	s_add_u32 s4, s6, s0
	s_addc_u32 s5, s7, 0
	global_load_dwordx4 v[198:201], v16, s[4:5]
	s_waitcnt vmcnt(15)
	v_cvt_pk_f32_fp8_e32 v[240:241], v136
	v_cvt_pk_f32_fp8_sdwa v[242:243], v136 src0_sel:WORD_1
	v_cvt_pk_f32_fp8_e32 v[244:245], v137
	v_cvt_pk_f32_fp8_sdwa v[202:203], v137 src0_sel:WORD_1
	v_pk_mul_f32 v[204:205], v[240:241], v[28:29]
	v_pk_mul_f32 v[206:207], v[242:243], v[30:31]
	v_cvt_pk_f32_fp8_e32 v[240:241], v138
	v_cvt_pk_f32_fp8_sdwa v[242:243], v138 src0_sel:WORD_1
	v_pk_fma_f32 v[204:205], v[244:245], v[32:33], v[204:205]
	v_pk_fma_f32 v[206:207], v[202:203], v[34:35], v[206:207]
	v_cvt_pk_f32_fp8_e32 v[244:245], v139
	v_cvt_pk_f32_fp8_sdwa v[202:203], v139 src0_sel:WORD_1
	v_pk_fma_f32 v[204:205], v[240:241], v[36:37], v[204:205]
	v_pk_fma_f32 v[206:207], v[242:243], v[38:39], v[206:207]
	v_pk_fma_f32 v[204:205], v[244:245], v[40:41], v[204:205]
	v_pk_fma_f32 v[206:207], v[202:203], v[42:43], v[206:207]
	v_readlane_b32 s0, v75, 16
	s_lshl_b32 s0, s0, 10
	s_add_u32 s4, s8, s0
	s_addc_u32 s5, s9, 0
	global_load_dwordx4 v[136:139], v16, s[4:5]
	v_pk_add_f32 v[204:205], v[204:205], v[206:207]
	s_nop 0
	v_add_f32_e32 v235, v204, v205
	s_waitcnt vmcnt(15)
; DI float sum8(float v) { v += DPPF(v, 0xB1); v += DPPF(v, 0x4E); v += DPPF(v, 0x141); return v; }
; DI void topk_phase(const bf16_t* PROJ, const unsigned char* K8, const unsigned char* V8, const unsigned short* SC, bf16_t* ODSA, int c, char* smem, int bid, int nb) {
;     ...
;         const size_t ro = (size_t)__builtin_amdgcn_readlane(mysel, jj) * 1024 + lane * 16;
;         const uint4 a = *(const uint4*)(K8 + ro), vv = *(const uint4*)(V8 + ro);
;         const unsigned w[4] = {a.x, a.y, a.z, a.w}, u[4] = {vv.x, vv.y, vv.z, vv.w};
;         float da = 0.f;
; #pragma unroll
;         for (int i = 0; i < 4; ++i) {
;           const f32x2v lo = __builtin_amdgcn_cvt_pk_f32_fp8((int)w[i], false), hi = __builtin_amdgcn_cvt_pk_f32_fp8((int)w[i], true);
;           da += qv[4 * i] * lo[0] + qv[4 * i + 1] * lo[1] + qv[4 * i + 2] * hi[0] + qv[4 * i + 3] * hi[1];
;         }
;         da = sum8(da);
;         da = j < count ? da : -3e30f;
	v_cvt_pk_f32_fp8_e32 v[240:241], v140
	v_cvt_pk_f32_fp8_sdwa v[242:243], v140 src0_sel:WORD_1
	v_cvt_pk_f32_fp8_e32 v[244:245], v141
	v_cvt_pk_f32_fp8_sdwa v[202:203], v141 src0_sel:WORD_1
	v_add_f32_dpp v235, v235, v235 quad_perm:[1,0,3,2] row_mask:0xf bank_mask:0xf bound_ctrl:1
	v_pk_mul_f32 v[204:205], v[240:241], v[28:29]
	v_pk_mul_f32 v[206:207], v[242:243], v[30:31]
	v_add_f32_dpp v235, v235, v235 quad_perm:[2,3,0,1] row_mask:0xf bank_mask:0xf bound_ctrl:1
	v_cvt_pk_f32_fp8_e32 v[240:241], v142
	v_cvt_pk_f32_fp8_sdwa v[242:243], v142 src0_sel:WORD_1
	v_add_f32_dpp v235, v235, v235 row_half_mirror row_mask:0xf bank_mask:0xf bound_ctrl:1
	v_pk_fma_f32 v[204:205], v[244:245], v[32:33], v[204:205]
	v_pk_fma_f32 v[206:207], v[202:203], v[34:35], v[206:207]
	s_add_i32 s0, s1, 16
	s_cmp_lt_i32 s0, s2
	s_cselect_b64 vcc, -1, 0
	v_cvt_pk_f32_fp8_e32 v[244:245], v143
	v_cvt_pk_f32_fp8_sdwa v[202:203], v143 src0_sel:WORD_1
	v_cndmask_b32_e32 v210, v220, v235, vcc
	v_pk_fma_f32 v[204:205], v[240:241], v[36:37], v[204:205]
	v_pk_fma_f32 v[206:207], v[242:243], v[38:39], v[206:207]
	v_pk_fma_f32 v[204:205], v[244:245], v[40:41], v[204:205]
	v_pk_fma_f32 v[206:207], v[202:203], v[42:43], v[206:207]
	v_readlane_b32 s0, v75, 17
	s_lshl_b32 s0, s0, 10
	s_add_u32 s4, s8, s0
	s_addc_u32 s5, s9, 0
	global_load_dwordx4 v[140:143], v16, s[4:5]
	v_pk_add_f32 v[204:205], v[204:205], v[206:207]
	s_nop 0
	v_add_f32_e32 v221, v204, v205
	s_waitcnt vmcnt(15)
	v_cvt_pk_f32_fp8_e32 v[240:241], v144
	v_cvt_pk_f32_fp8_sdwa v[242:243], v144 src0_sel:WORD_1
	v_cvt_pk_f32_fp8_e32 v[244:245], v145
	v_cvt_pk_f32_fp8_sdwa v[202:203], v145 src0_sel:WORD_1
	v_add_f32_dpp v221, v221, v221 quad_perm:[1,0,3,2] row_mask:0xf bank_mask:0xf bound_ctrl:1
	v_pk_mul_f32 v[204:205], v[240:241], v[28:29]
	v_pk_mul_f32 v[206:207], v[242:243], v[30:31]
	v_add_f32_dpp v221, v221, v221 quad_perm:[2,3,0,1] row_mask:0xf bank_mask:0xf bound_ctrl:1
	v_cvt_pk_f32_fp8_e32 v[240:241], v146
	v_cvt_pk_f32_fp8_sdwa v[242:243], v146 src0_sel:WORD_1
	v_add_f32_dpp v221, v221, v221 row_half_mirror row_mask:0xf bank_mask:0xf bound_ctrl:1
	v_pk_fma_f32 v[204:205], v[244:245], v[32:33], v[204:205]
	v_pk_fma_f32 v[206:207], v[202:203], v[34:35], v[206:207]
	s_add_i32 s0, s1, 17
	s_cmp_lt_i32 s0, s2
	s_cselect_b64 vcc, -1, 0
	v_cvt_pk_f32_fp8_e32 v[244:245], v147
	v_cvt_pk_f32_fp8_sdwa v[202:203], v147 src0_sel:WORD_1
	v_cndmask_b32_e32 v211, v220, v221, vcc
	v_pk_fma_f32 v[204:205], v[240:241], v[36:37], v[204:205]
	v_pk_fma_f32 v[206:207], v[242:243], v[38:39], v[206:207]
	v_pk_fma_f32 v[204:205], v[244:245], v[40:41], v[204:205]
	v_pk_fma_f32 v[206:207], v[202:203], v[42:43], v[206:207]
	v_readlane_b32 s0, v75, 18
	s_lshl_b32 s0, s0, 10
	s_add_u32 s4, s8, s0
	s_addc_u32 s5, s9, 0
	global_load_dwordx4 v[144:147], v16, s[4:5]
	v_pk_add_f32 v[204:205], v[204:205], v[206:207]
	s_nop 0
	v_add_f32_e32 v235, v204, v205
	s_waitcnt vmcnt(15)
	v_cvt_pk_f32_fp8_e32 v[240:241], v148
	v_cvt_pk_f32_fp8_sdwa v[242:243], v148 src0_sel:WORD_1
	v_cvt_pk_f32_fp8_e32 v[244:245], v149
	v_cvt_pk_f32_fp8_sdwa v[202:203], v149 src0_sel:WORD_1
	v_add_f32_dpp v235, v235, v235 quad_perm:[1,0,3,2] row_mask:0xf bank_mask:0xf bound_ctrl:1
	v_pk_mul_f32 v[204:205], v[240:241], v[28:29]
	v_pk_mul_f32 v[206:207], v[242:243], v[30:31]
	v_add_f32_dpp v235, v235, v235 quad_perm:[2,3,0,1] row_mask:0xf bank_mask:0xf bound_ctrl:1
	v_cvt_pk_f32_fp8_e32 v[240:241], v150
	v_cvt_pk_f32_fp8_sdwa v[242:243], v150 src0_sel:WORD_1
	v_add_f32_dpp v235, v235, v235 row_half_mirror row_mask:0xf bank_mask:0xf bound_ctrl:1
	v_pk_fma_f32 v[204:205], v[244:245], v[32:33], v[204:205]
	v_pk_fma_f32 v[206:207], v[202:203], v[34:35], v[206:207]
	s_add_i32 s0, s1, 18
	s_cmp_lt_i32 s0, s2
	s_cselect_b64 vcc, -1, 0
	v_cvt_pk_f32_fp8_e32 v[244:245], v151
	v_cvt_pk_f32_fp8_sdwa v[202:203], v151 src0_sel:WORD_1
	v_cndmask_b32_e32 v212, v220, v235, vcc
	v_pk_fma_f32 v[204:205], v[240:241], v[36:37], v[204:205]
	v_pk_fma_f32 v[206:207], v[242:243], v[38:39], v[206:207]
	v_pk_fma_f32 v[204:205], v[244:245], v[40:41], v[204:205]
	v_pk_fma_f32 v[206:207], v[202:203], v[42:43], v[206:207]
	v_readlane_b32 s0, v75, 19
	s_lshl_b32 s0, s0, 10
	s_add_u32 s4, s8, s0
	s_addc_u32 s5, s9, 0
	global_load_dwordx4 v[148:151], v16, s[4:5]
	v_pk_add_f32 v[204:205], v[204:205], v[206:207]
	s_nop 0
	v_add_f32_e32 v221, v204, v205
	s_waitcnt vmcnt(15)
	v_cvt_pk_f32_fp8_e32 v[240:241], v152
	v_cvt_pk_f32_fp8_sdwa v[242:243], v152 src0_sel:WORD_1
	v_cvt_pk_f32_fp8_e32 v[244:245], v153
	v_cvt_pk_f32_fp8_sdwa v[202:203], v153 src0_sel:WORD_1
	v_add_f32_dpp v221, v221, v221 quad_perm:[1,0,3,2] row_mask:0xf bank_mask:0xf bound_ctrl:1
	v_pk_mul_f32 v[204:205], v[240:241], v[28:29]
	v_pk_mul_f32 v[206:207], v[242:243], v[30:31]
	v_add_f32_dpp v221, v221, v221 quad_perm:[2,3,0,1] row_mask:0xf bank_mask:0xf bound_ctrl:1
	v_cvt_pk_f32_fp8_e32 v[240:241], v154
	v_cvt_pk_f32_fp8_sdwa v[242:243], v154 src0_sel:WORD_1
	v_add_f32_dpp v221, v221, v221 row_half_mirror row_mask:0xf bank_mask:0xf bound_ctrl:1
	v_pk_fma_f32 v[204:205], v[244:245], v[32:33], v[204:205]
	v_pk_fma_f32 v[206:207], v[202:203], v[34:35], v[206:207]
	s_add_i32 s0, s1, 19
	s_cmp_lt_i32 s0, s2
	s_cselect_b64 vcc, -1, 0
	v_cvt_pk_f32_fp8_e32 v[244:245], v155
	v_cvt_pk_f32_fp8_sdwa v[202:203], v155 src0_sel:WORD_1
	v_cndmask_b32_e32 v213, v220, v221, vcc
	v_pk_fma_f32 v[204:205], v[240:241], v[36:37], v[204:205]
	v_pk_fma_f32 v[206:207], v[242:243], v[38:39], v[206:207]
	v_pk_fma_f32 v[204:205], v[244:245], v[40:41], v[204:205]
	v_pk_fma_f32 v[206:207], v[202:203], v[42:43], v[206:207]
	v_readlane_b32 s0, v75, 20
	s_lshl_b32 s0, s0, 10
	s_add_u32 s4, s8, s0
	s_addc_u32 s5, s9, 0
	global_load_dwordx4 v[152:155], v16, s[4:5]
	v_pk_add_f32 v[204:205], v[204:205], v[206:207]
	s_nop 0
	v_add_f32_e32 v235, v204, v205
	s_waitcnt vmcnt(15)
; DI float sum8(float v) { v += DPPF(v, 0xB1); v += DPPF(v, 0x4E); v += DPPF(v, 0x141); return v; }
; DI void topk_phase(const bf16_t* PROJ, const unsigned char* K8, const unsigned char* V8, const unsigned short* SC, bf16_t* ODSA, int c, char* smem, int bid, int nb) {
;     ...
;         const size_t ro = (size_t)__builtin_amdgcn_readlane(mysel, jj) * 1024 + lane * 16;
;         const uint4 a = *(const uint4*)(K8 + ro), vv = *(const uint4*)(V8 + ro);
;         const unsigned w[4] = {a.x, a.y, a.z, a.w}, u[4] = {vv.x, vv.y, vv.z, vv.w};
;         float da = 0.f;
; #pragma unroll
;         for (int i = 0; i < 4; ++i) {
;           const f32x2v lo = __builtin_amdgcn_cvt_pk_f32_fp8((int)w[i], false), hi = __builtin_amdgcn_cvt_pk_f32_fp8((int)w[i], true);
;           da += qv[4 * i] * lo[0] + qv[4 * i + 1] * lo[1] + qv[4 * i + 2] * hi[0] + qv[4 * i + 3] * hi[1];
;         }
;         da = sum8(da);
;         da = j < count ? da : -3e30f;
	v_cvt_pk_f32_fp8_e32 v[240:241], v156
	v_cvt_pk_f32_fp8_sdwa v[242:243], v156 src0_sel:WORD_1
	v_cvt_pk_f32_fp8_e32 v[244:245], v157
	v_cvt_pk_f32_fp8_sdwa v[202:203], v157 src0_sel:WORD_1
	v_add_f32_dpp v235, v235, v235 quad_perm:[1,0,3,2] row_mask:0xf bank_mask:0xf bound_ctrl:1
	v_pk_mul_f32 v[204:205], v[240:241], v[28:29]
	v_pk_mul_f32 v[206:207], v[242:243], v[30:31]
	v_add_f32_dpp v235, v235, v235 quad_perm:[2,3,0,1] row_mask:0xf bank_mask:0xf bound_ctrl:1
	v_cvt_pk_f32_fp8_e32 v[240:241], v158
	v_cvt_pk_f32_fp8_sdwa v[242:243], v158 src0_sel:WORD_1
	v_add_f32_dpp v235, v235, v235 row_half_mirror row_mask:0xf bank_mask:0xf bound_ctrl:1
	v_pk_fma_f32 v[204:205], v[244:245], v[32:33], v[204:205]
	v_pk_fma_f32 v[206:207], v[202:203], v[34:35], v[206:207]
	s_add_i32 s0, s1, 20
	s_cmp_lt_i32 s0, s2
	s_cselect_b64 vcc, -1, 0
	v_cvt_pk_f32_fp8_e32 v[244:245], v159
	v_cvt_pk_f32_fp8_sdwa v[202:203], v159 src0_sel:WORD_1
	v_cndmask_b32_e32 v226, v220, v235, vcc
	v_pk_fma_f32 v[204:205], v[240:241], v[36:37], v[204:205]
	v_pk_fma_f32 v[206:207], v[242:243], v[38:39], v[206:207]
	v_pk_fma_f32 v[204:205], v[244:245], v[40:41], v[204:205]
	v_pk_fma_f32 v[206:207], v[202:203], v[42:43], v[206:207]
	v_readlane_b32 s0, v75, 21
	s_lshl_b32 s0, s0, 10
	s_add_u32 s4, s8, s0
	s_addc_u32 s5, s9, 0
	global_load_dwordx4 v[156:159], v16, s[4:5]
	v_pk_add_f32 v[204:205], v[204:205], v[206:207]
	s_nop 0
	v_add_f32_e32 v221, v204, v205
	s_waitcnt vmcnt(15)
	v_cvt_pk_f32_fp8_e32 v[240:241], v160
	v_cvt_pk_f32_fp8_sdwa v[242:243], v160 src0_sel:WORD_1
	v_cvt_pk_f32_fp8_e32 v[244:245], v161
	v_cvt_pk_f32_fp8_sdwa v[202:203], v161 src0_sel:WORD_1
	v_add_f32_dpp v221, v221, v221 quad_perm:[1,0,3,2] row_mask:0xf bank_mask:0xf bound_ctrl:1
	v_pk_mul_f32 v[204:205], v[240:241], v[28:29]
	v_pk_mul_f32 v[206:207], v[242:243], v[30:31]
	v_add_f32_dpp v221, v221, v221 quad_perm:[2,3,0,1] row_mask:0xf bank_mask:0xf bound_ctrl:1
	v_cvt_pk_f32_fp8_e32 v[240:241], v162
	v_cvt_pk_f32_fp8_sdwa v[242:243], v162 src0_sel:WORD_1
	v_add_f32_dpp v221, v221, v221 row_half_mirror row_mask:0xf bank_mask:0xf bound_ctrl:1
	v_pk_fma_f32 v[204:205], v[244:245], v[32:33], v[204:205]
	v_pk_fma_f32 v[206:207], v[202:203], v[34:35], v[206:207]
	s_add_i32 s0, s1, 21
	s_cmp_lt_i32 s0, s2
	s_cselect_b64 vcc, -1, 0
	v_cvt_pk_f32_fp8_e32 v[244:245], v163
	v_cvt_pk_f32_fp8_sdwa v[202:203], v163 src0_sel:WORD_1
	v_cndmask_b32_e32 v227, v220, v221, vcc
	v_pk_fma_f32 v[204:205], v[240:241], v[36:37], v[204:205]
	v_pk_fma_f32 v[206:207], v[242:243], v[38:39], v[206:207]
	v_pk_fma_f32 v[204:205], v[244:245], v[40:41], v[204:205]
	v_pk_fma_f32 v[206:207], v[202:203], v[42:43], v[206:207]
	v_readlane_b32 s0, v75, 22
	s_lshl_b32 s0, s0, 10
	s_add_u32 s4, s8, s0
	s_addc_u32 s5, s9, 0
	global_load_dwordx4 v[160:163], v16, s[4:5]
	v_pk_add_f32 v[204:205], v[204:205], v[206:207]
	s_nop 0
	v_add_f32_e32 v235, v204, v205
	s_waitcnt vmcnt(15)
	v_cvt_pk_f32_fp8_e32 v[240:241], v164
	v_cvt_pk_f32_fp8_sdwa v[242:243], v164 src0_sel:WORD_1
	v_cvt_pk_f32_fp8_e32 v[244:245], v165
	v_cvt_pk_f32_fp8_sdwa v[202:203], v165 src0_sel:WORD_1
	v_add_f32_dpp v235, v235, v235 quad_perm:[1,0,3,2] row_mask:0xf bank_mask:0xf bound_ctrl:1
	v_pk_mul_f32 v[204:205], v[240:241], v[28:29]
	v_pk_mul_f32 v[206:207], v[242:243], v[30:31]
	v_add_f32_dpp v235, v235, v235 quad_perm:[2,3,0,1] row_mask:0xf bank_mask:0xf bound_ctrl:1
	v_cvt_pk_f32_fp8_e32 v[240:241], v166
	v_cvt_pk_f32_fp8_sdwa v[242:243], v166 src0_sel:WORD_1
	v_add_f32_dpp v235, v235, v235 row_half_mirror row_mask:0xf bank_mask:0xf bound_ctrl:1
	v_pk_fma_f32 v[204:205], v[244:245], v[32:33], v[204:205]
	v_pk_fma_f32 v[206:207], v[202:203], v[34:35], v[206:207]
	s_add_i32 s0, s1, 22
	s_cmp_lt_i32 s0, s2
	s_cselect_b64 vcc, -1, 0
	v_cvt_pk_f32_fp8_e32 v[244:245], v167
	v_cvt_pk_f32_fp8_sdwa v[202:203], v167 src0_sel:WORD_1
	v_cndmask_b32_e32 v228, v220, v235, vcc
	v_pk_fma_f32 v[204:205], v[240:241], v[36:37], v[204:205]
	v_pk_fma_f32 v[206:207], v[242:243], v[38:39], v[206:207]
	v_pk_fma_f32 v[204:205], v[244:245], v[40:41], v[204:205]
	v_pk_fma_f32 v[206:207], v[202:203], v[42:43], v[206:207]
	v_readlane_b32 s0, v75, 23
	s_lshl_b32 s0, s0, 10
	s_add_u32 s4, s8, s0
	s_addc_u32 s5, s9, 0
	global_load_dwordx4 v[164:167], v16, s[4:5]
	v_pk_add_f32 v[204:205], v[204:205], v[206:207]
	s_nop 0
	v_add_f32_e32 v221, v204, v205
	s_waitcnt vmcnt(15)
	v_cvt_pk_f32_fp8_e32 v[240:241], v168
	v_cvt_pk_f32_fp8_sdwa v[242:243], v168 src0_sel:WORD_1
	v_cvt_pk_f32_fp8_e32 v[244:245], v169
	v_cvt_pk_f32_fp8_sdwa v[202:203], v169 src0_sel:WORD_1
	v_add_f32_dpp v221, v221, v221 quad_perm:[1,0,3,2] row_mask:0xf bank_mask:0xf bound_ctrl:1
	v_pk_mul_f32 v[204:205], v[240:241], v[28:29]
	v_pk_mul_f32 v[206:207], v[242:243], v[30:31]
	v_add_f32_dpp v221, v221, v221 quad_perm:[2,3,0,1] row_mask:0xf bank_mask:0xf bound_ctrl:1
	v_cvt_pk_f32_fp8_e32 v[240:241], v170
	v_cvt_pk_f32_fp8_sdwa v[242:243], v170 src0_sel:WORD_1
	v_add_f32_dpp v221, v221, v221 row_half_mirror row_mask:0xf bank_mask:0xf bound_ctrl:1
	v_pk_fma_f32 v[204:205], v[244:245], v[32:33], v[204:205]
	v_pk_fma_f32 v[206:207], v[202:203], v[34:35], v[206:207]
	s_add_i32 s0, s1, 23
	s_cmp_lt_i32 s0, s2
	s_cselect_b64 vcc, -1, 0
	v_cvt_pk_f32_fp8_e32 v[244:245], v171
	v_cvt_pk_f32_fp8_sdwa v[202:203], v171 src0_sel:WORD_1
	v_cndmask_b32_e32 v229, v220, v221, vcc
	v_pk_fma_f32 v[204:205], v[240:241], v[36:37], v[204:205]
	v_pk_fma_f32 v[206:207], v[242:243], v[38:39], v[206:207]
	v_pk_fma_f32 v[204:205], v[244:245], v[40:41], v[204:205]
	v_pk_fma_f32 v[206:207], v[202:203], v[42:43], v[206:207]
	v_readlane_b32 s0, v75, 24
	s_lshl_b32 s0, s0, 10
	s_add_u32 s4, s8, s0
	s_addc_u32 s5, s9, 0
	global_load_dwordx4 v[168:171], v16, s[4:5]
	v_pk_add_f32 v[204:205], v[204:205], v[206:207]
	s_nop 0
	v_add_f32_e32 v235, v204, v205
	s_waitcnt vmcnt(15)
; DI float sum8(float v) { v += DPPF(v, 0xB1); v += DPPF(v, 0x4E); v += DPPF(v, 0x141); return v; }
; DI void topk_phase(const bf16_t* PROJ, const unsigned char* K8, const unsigned char* V8, const unsigned short* SC, bf16_t* ODSA, int c, char* smem, int bid, int nb) {
;     ...
;         const size_t ro = (size_t)__builtin_amdgcn_readlane(mysel, jj) * 1024 + lane * 16;
;         const uint4 a = *(const uint4*)(K8 + ro), vv = *(const uint4*)(V8 + ro);
;         const unsigned w[4] = {a.x, a.y, a.z, a.w}, u[4] = {vv.x, vv.y, vv.z, vv.w};
;         float da = 0.f;
; #pragma unroll
;         for (int i = 0; i < 4; ++i) {
;           const f32x2v lo = __builtin_amdgcn_cvt_pk_f32_fp8((int)w[i], false), hi = __builtin_amdgcn_cvt_pk_f32_fp8((int)w[i], true);
;           da += qv[4 * i] * lo[0] + qv[4 * i + 1] * lo[1] + qv[4 * i + 2] * hi[0] + qv[4 * i + 3] * hi[1];
;         }
;         da = sum8(da);
;         da = j < count ? da : -3e30f;
	v_cvt_pk_f32_fp8_e32 v[240:241], v172
	v_cvt_pk_f32_fp8_sdwa v[242:243], v172 src0_sel:WORD_1
	v_cvt_pk_f32_fp8_e32 v[244:245], v173
	v_cvt_pk_f32_fp8_sdwa v[202:203], v173 src0_sel:WORD_1
	v_add_f32_dpp v235, v235, v235 quad_perm:[1,0,3,2] row_mask:0xf bank_mask:0xf bound_ctrl:1
	v_pk_mul_f32 v[204:205], v[240:241], v[28:29]
	v_pk_mul_f32 v[206:207], v[242:243], v[30:31]
	v_add_f32_dpp v235, v235, v235 quad_perm:[2,3,0,1] row_mask:0xf bank_mask:0xf bound_ctrl:1
	v_cvt_pk_f32_fp8_e32 v[240:241], v174
	v_cvt_pk_f32_fp8_sdwa v[242:243], v174 src0_sel:WORD_1
	v_add_f32_dpp v235, v235, v235 row_half_mirror row_mask:0xf bank_mask:0xf bound_ctrl:1
	v_pk_fma_f32 v[204:205], v[244:245], v[32:33], v[204:205]
	v_pk_fma_f32 v[206:207], v[202:203], v[34:35], v[206:207]
	s_add_i32 s0, s1, 24
	s_cmp_lt_i32 s0, s2
	s_cselect_b64 vcc, -1, 0
	v_cvt_pk_f32_fp8_e32 v[244:245], v175
	v_cvt_pk_f32_fp8_sdwa v[202:203], v175 src0_sel:WORD_1
	v_cndmask_b32_e32 v230, v220, v235, vcc
	v_pk_fma_f32 v[204:205], v[240:241], v[36:37], v[204:205]
	v_pk_fma_f32 v[206:207], v[242:243], v[38:39], v[206:207]
	v_pk_fma_f32 v[204:205], v[244:245], v[40:41], v[204:205]
	v_pk_fma_f32 v[206:207], v[202:203], v[42:43], v[206:207]
	v_readlane_b32 s0, v75, 25
	s_lshl_b32 s0, s0, 10
	s_add_u32 s4, s8, s0
	s_addc_u32 s5, s9, 0
	global_load_dwordx4 v[172:175], v16, s[4:5]
	v_pk_add_f32 v[204:205], v[204:205], v[206:207]
	s_nop 0
	v_add_f32_e32 v221, v204, v205
	s_waitcnt vmcnt(15)
	v_cvt_pk_f32_fp8_e32 v[240:241], v176
	v_cvt_pk_f32_fp8_sdwa v[242:243], v176 src0_sel:WORD_1
	v_cvt_pk_f32_fp8_e32 v[244:245], v177
	v_cvt_pk_f32_fp8_sdwa v[202:203], v177 src0_sel:WORD_1
	v_add_f32_dpp v221, v221, v221 quad_perm:[1,0,3,2] row_mask:0xf bank_mask:0xf bound_ctrl:1
	v_pk_mul_f32 v[204:205], v[240:241], v[28:29]
	v_pk_mul_f32 v[206:207], v[242:243], v[30:31]
	v_add_f32_dpp v221, v221, v221 quad_perm:[2,3,0,1] row_mask:0xf bank_mask:0xf bound_ctrl:1
	v_cvt_pk_f32_fp8_e32 v[240:241], v178
	v_cvt_pk_f32_fp8_sdwa v[242:243], v178 src0_sel:WORD_1
	v_add_f32_dpp v221, v221, v221 row_half_mirror row_mask:0xf bank_mask:0xf bound_ctrl:1
	v_pk_fma_f32 v[204:205], v[244:245], v[32:33], v[204:205]
	v_pk_fma_f32 v[206:207], v[202:203], v[34:35], v[206:207]
	s_add_i32 s0, s1, 25
	s_cmp_lt_i32 s0, s2
	s_cselect_b64 vcc, -1, 0
	v_cvt_pk_f32_fp8_e32 v[244:245], v179
	v_cvt_pk_f32_fp8_sdwa v[202:203], v179 src0_sel:WORD_1
	v_cndmask_b32_e32 v231, v220, v221, vcc
	v_pk_fma_f32 v[204:205], v[240:241], v[36:37], v[204:205]
	v_pk_fma_f32 v[206:207], v[242:243], v[38:39], v[206:207]
	v_pk_fma_f32 v[204:205], v[244:245], v[40:41], v[204:205]
	v_pk_fma_f32 v[206:207], v[202:203], v[42:43], v[206:207]
	v_readlane_b32 s0, v75, 26
	s_lshl_b32 s0, s0, 10
	s_add_u32 s4, s8, s0
	s_addc_u32 s5, s9, 0
	global_load_dwordx4 v[176:179], v16, s[4:5]
	v_pk_add_f32 v[204:205], v[204:205], v[206:207]
	s_nop 0
	v_add_f32_e32 v235, v204, v205
	s_waitcnt vmcnt(15)
	v_cvt_pk_f32_fp8_e32 v[240:241], v180
	v_cvt_pk_f32_fp8_sdwa v[242:243], v180 src0_sel:WORD_1
	v_cvt_pk_f32_fp8_e32 v[244:245], v181
	v_cvt_pk_f32_fp8_sdwa v[202:203], v181 src0_sel:WORD_1
	v_add_f32_dpp v235, v235, v235 quad_perm:[1,0,3,2] row_mask:0xf bank_mask:0xf bound_ctrl:1
	v_pk_mul_f32 v[204:205], v[240:241], v[28:29]
	v_pk_mul_f32 v[206:207], v[242:243], v[30:31]
	v_add_f32_dpp v235, v235, v235 quad_perm:[2,3,0,1] row_mask:0xf bank_mask:0xf bound_ctrl:1
	v_cvt_pk_f32_fp8_e32 v[240:241], v182
	v_cvt_pk_f32_fp8_sdwa v[242:243], v182 src0_sel:WORD_1
	v_add_f32_dpp v235, v235, v235 row_half_mirror row_mask:0xf bank_mask:0xf bound_ctrl:1
	v_pk_fma_f32 v[204:205], v[244:245], v[32:33], v[204:205]
	v_pk_fma_f32 v[206:207], v[202:203], v[34:35], v[206:207]
	s_add_i32 s0, s1, 26
	s_cmp_lt_i32 s0, s2
	s_cselect_b64 vcc, -1, 0
	v_cvt_pk_f32_fp8_e32 v[244:245], v183
	v_cvt_pk_f32_fp8_sdwa v[202:203], v183 src0_sel:WORD_1
	v_cndmask_b32_e32 v232, v220, v235, vcc
	v_pk_fma_f32 v[204:205], v[240:241], v[36:37], v[204:205]
	v_pk_fma_f32 v[206:207], v[242:243], v[38:39], v[206:207]
	v_pk_fma_f32 v[204:205], v[244:245], v[40:41], v[204:205]
	v_pk_fma_f32 v[206:207], v[202:203], v[42:43], v[206:207]
	v_readlane_b32 s0, v75, 27
	s_lshl_b32 s0, s0, 10
	s_add_u32 s4, s8, s0
	s_addc_u32 s5, s9, 0
	global_load_dwordx4 v[180:183], v16, s[4:5]
	v_pk_add_f32 v[204:205], v[204:205], v[206:207]
	s_nop 0
	v_add_f32_e32 v221, v204, v205
	s_waitcnt vmcnt(15)
	v_cvt_pk_f32_fp8_e32 v[240:241], v186
	v_cvt_pk_f32_fp8_sdwa v[242:243], v186 src0_sel:WORD_1
	v_cvt_pk_f32_fp8_e32 v[244:245], v187
	v_cvt_pk_f32_fp8_sdwa v[202:203], v187 src0_sel:WORD_1
	v_add_f32_dpp v221, v221, v221 quad_perm:[1,0,3,2] row_mask:0xf bank_mask:0xf bound_ctrl:1
	v_pk_mul_f32 v[204:205], v[240:241], v[28:29]
	v_pk_mul_f32 v[206:207], v[242:243], v[30:31]
	v_add_f32_dpp v221, v221, v221 quad_perm:[2,3,0,1] row_mask:0xf bank_mask:0xf bound_ctrl:1
	v_cvt_pk_f32_fp8_e32 v[240:241], v188
	v_cvt_pk_f32_fp8_sdwa v[242:243], v188 src0_sel:WORD_1
	v_add_f32_dpp v221, v221, v221 row_half_mirror row_mask:0xf bank_mask:0xf bound_ctrl:1
	v_pk_fma_f32 v[204:205], v[244:245], v[32:33], v[204:205]
	v_pk_fma_f32 v[206:207], v[202:203], v[34:35], v[206:207]
	s_add_i32 s0, s1, 27
	s_cmp_lt_i32 s0, s2
	s_cselect_b64 vcc, -1, 0
	v_cvt_pk_f32_fp8_e32 v[244:245], v189
	v_cvt_pk_f32_fp8_sdwa v[202:203], v189 src0_sel:WORD_1
	v_cndmask_b32_e32 v233, v220, v221, vcc
	v_pk_fma_f32 v[204:205], v[240:241], v[36:37], v[204:205]
	v_pk_fma_f32 v[206:207], v[242:243], v[38:39], v[206:207]
	v_pk_fma_f32 v[204:205], v[244:245], v[40:41], v[204:205]
	v_pk_fma_f32 v[206:207], v[202:203], v[42:43], v[206:207]
	v_readlane_b32 s0, v75, 28
	s_lshl_b32 s0, s0, 10
	s_add_u32 s4, s8, s0
	s_addc_u32 s5, s9, 0
	global_load_dwordx4 v[186:189], v16, s[4:5]
	v_pk_add_f32 v[204:205], v[204:205], v[206:207]
	s_nop 0
	v_add_f32_e32 v235, v204, v205
	s_waitcnt vmcnt(15)
; #define DPPF(v, ctrl) __builtin_bit_cast(float, __builtin_amdgcn_update_dpp(0, __builtin_bit_cast(int, (v)), (ctrl), 0xf, 0xf, true))
; DI float sum8(float v) { v += DPPF(v, 0xB1); v += DPPF(v, 0x4E); v += DPPF(v, 0x141); return v; }
; DI void topk_phase(const bf16_t* PROJ, const unsigned char* K8, const unsigned char* V8, const unsigned short* SC, bf16_t* ODSA, int c, char* smem, int bid, int nb) {
;     ...
;         const size_t ro = (size_t)__builtin_amdgcn_readlane(mysel, jj) * 1024 + lane * 16;
;         const uint4 a = *(const uint4*)(K8 + ro), vv = *(const uint4*)(V8 + ro);
;         const unsigned w[4] = {a.x, a.y, a.z, a.w}, u[4] = {vv.x, vv.y, vv.z, vv.w};
;         float da = 0.f;
; #pragma unroll
;         for (int i = 0; i < 4; ++i) {
;           const f32x2v lo = __builtin_amdgcn_cvt_pk_f32_fp8((int)w[i], false), hi = __builtin_amdgcn_cvt_pk_f32_fp8((int)w[i], true);
;           da += qv[4 * i] * lo[0] + qv[4 * i + 1] * lo[1] + qv[4 * i + 2] * hi[0] + qv[4 * i + 3] * hi[1];
;         }
;         da = sum8(da);
;         da = j < count ? da : -3e30f;
;         const float mn = fmaxf(m_run, da), al = __builtin_amdgcn_exp2f(m_run - mn), pp = __builtin_amdgcn_exp2f(da - mn);
;         m_run = mn; l_run = l_run * al + pp;
; #pragma unroll
;         for (int i = 0; i < 4; ++i) {
;           const f32x2v lo = __builtin_amdgcn_cvt_pk_f32_fp8((int)u[i], false), hi = __builtin_amdgcn_cvt_pk_f32_fp8((int)u[i], true);
;           ov[4 * i] = ov[4 * i] * al + pp * lo[0]; ov[4 * i + 1] = ov[4 * i + 1] * al + pp * lo[1];
;           ov[4 * i + 2] = ov[4 * i + 2] * al + pp * hi[0]; ov[4 * i + 3] = ov[4 * i + 3] * al + pp * hi[1];
;         }
	v_cvt_pk_f32_fp8_e32 v[240:241], v190
	v_cvt_pk_f32_fp8_sdwa v[242:243], v190 src0_sel:WORD_1
	v_cvt_pk_f32_fp8_e32 v[244:245], v191
	v_cvt_pk_f32_fp8_sdwa v[202:203], v191 src0_sel:WORD_1
	v_add_f32_dpp v235, v235, v235 quad_perm:[1,0,3,2] row_mask:0xf bank_mask:0xf bound_ctrl:1
	v_pk_mul_f32 v[204:205], v[240:241], v[28:29]
	v_pk_mul_f32 v[206:207], v[242:243], v[30:31]
	v_add_f32_dpp v235, v235, v235 quad_perm:[2,3,0,1] row_mask:0xf bank_mask:0xf bound_ctrl:1
	v_cvt_pk_f32_fp8_e32 v[240:241], v192
	v_cvt_pk_f32_fp8_sdwa v[242:243], v192 src0_sel:WORD_1
	v_add_f32_dpp v235, v235, v235 row_half_mirror row_mask:0xf bank_mask:0xf bound_ctrl:1
	v_pk_fma_f32 v[204:205], v[244:245], v[32:33], v[204:205]
	v_pk_fma_f32 v[206:207], v[202:203], v[34:35], v[206:207]
	s_add_i32 s0, s1, 28
	s_cmp_lt_i32 s0, s2
	s_cselect_b64 vcc, -1, 0
	v_cvt_pk_f32_fp8_e32 v[244:245], v193
	v_cvt_pk_f32_fp8_sdwa v[202:203], v193 src0_sel:WORD_1
	v_cndmask_b32_e32 v236, v220, v235, vcc
	v_pk_fma_f32 v[204:205], v[240:241], v[36:37], v[204:205]
	v_pk_fma_f32 v[206:207], v[242:243], v[38:39], v[206:207]
	v_pk_fma_f32 v[204:205], v[244:245], v[40:41], v[204:205]
	v_pk_fma_f32 v[206:207], v[202:203], v[42:43], v[206:207]
	v_readlane_b32 s0, v75, 29
	s_lshl_b32 s0, s0, 10
	s_add_u32 s4, s8, s0
	s_addc_u32 s5, s9, 0
	global_load_dwordx4 v[190:193], v16, s[4:5]
	v_pk_add_f32 v[204:205], v[204:205], v[206:207]
	s_nop 0
	v_add_f32_e32 v221, v204, v205
	s_waitcnt vmcnt(15)
	v_cvt_pk_f32_fp8_e32 v[240:241], v194
	v_cvt_pk_f32_fp8_sdwa v[242:243], v194 src0_sel:WORD_1
	v_cvt_pk_f32_fp8_e32 v[244:245], v195
	v_cvt_pk_f32_fp8_sdwa v[202:203], v195 src0_sel:WORD_1
	v_add_f32_dpp v221, v221, v221 quad_perm:[1,0,3,2] row_mask:0xf bank_mask:0xf bound_ctrl:1
	v_pk_mul_f32 v[204:205], v[240:241], v[28:29]
	v_pk_mul_f32 v[206:207], v[242:243], v[30:31]
	v_add_f32_dpp v221, v221, v221 quad_perm:[2,3,0,1] row_mask:0xf bank_mask:0xf bound_ctrl:1
	v_cvt_pk_f32_fp8_e32 v[240:241], v196
	v_cvt_pk_f32_fp8_sdwa v[242:243], v196 src0_sel:WORD_1
	v_add_f32_dpp v221, v221, v221 row_half_mirror row_mask:0xf bank_mask:0xf bound_ctrl:1
	v_pk_fma_f32 v[204:205], v[244:245], v[32:33], v[204:205]
	v_pk_fma_f32 v[206:207], v[202:203], v[34:35], v[206:207]
	s_add_i32 s0, s1, 29
	s_cmp_lt_i32 s0, s2
	s_cselect_b64 vcc, -1, 0
	v_cvt_pk_f32_fp8_e32 v[244:245], v197
	v_cvt_pk_f32_fp8_sdwa v[202:203], v197 src0_sel:WORD_1
	v_cndmask_b32_e32 v237, v220, v221, vcc
	v_pk_fma_f32 v[204:205], v[240:241], v[36:37], v[204:205]
	v_pk_fma_f32 v[206:207], v[242:243], v[38:39], v[206:207]
	v_pk_fma_f32 v[204:205], v[244:245], v[40:41], v[204:205]
	v_pk_fma_f32 v[206:207], v[202:203], v[42:43], v[206:207]
	v_readlane_b32 s0, v75, 30
	s_lshl_b32 s0, s0, 10
	s_add_u32 s4, s8, s0
	s_addc_u32 s5, s9, 0
	global_load_dwordx4 v[194:197], v16, s[4:5]
	v_pk_add_f32 v[204:205], v[204:205], v[206:207]
	s_nop 0
	v_add_f32_e32 v235, v204, v205
	s_waitcnt vmcnt(15)
	v_cvt_pk_f32_fp8_e32 v[240:241], v198
	v_cvt_pk_f32_fp8_sdwa v[242:243], v198 src0_sel:WORD_1
	v_cvt_pk_f32_fp8_e32 v[244:245], v199
	v_cvt_pk_f32_fp8_sdwa v[202:203], v199 src0_sel:WORD_1
	v_add_f32_dpp v235, v235, v235 quad_perm:[1,0,3,2] row_mask:0xf bank_mask:0xf bound_ctrl:1
	v_pk_mul_f32 v[204:205], v[240:241], v[28:29]
	v_pk_mul_f32 v[206:207], v[242:243], v[30:31]
	v_add_f32_dpp v235, v235, v235 quad_perm:[2,3,0,1] row_mask:0xf bank_mask:0xf bound_ctrl:1
	v_cvt_pk_f32_fp8_e32 v[240:241], v200
	v_cvt_pk_f32_fp8_sdwa v[242:243], v200 src0_sel:WORD_1
	v_add_f32_dpp v235, v235, v235 row_half_mirror row_mask:0xf bank_mask:0xf bound_ctrl:1
	v_pk_fma_f32 v[204:205], v[244:245], v[32:33], v[204:205]
	v_pk_fma_f32 v[206:207], v[202:203], v[34:35], v[206:207]
	s_add_i32 s0, s1, 30
	s_cmp_lt_i32 s0, s2
	s_cselect_b64 vcc, -1, 0
	v_cvt_pk_f32_fp8_e32 v[244:245], v201
	v_cvt_pk_f32_fp8_sdwa v[202:203], v201 src0_sel:WORD_1
	v_cndmask_b32_e32 v238, v220, v235, vcc
	v_pk_fma_f32 v[204:205], v[240:241], v[36:37], v[204:205]
	v_pk_fma_f32 v[206:207], v[242:243], v[38:39], v[206:207]
	v_pk_fma_f32 v[204:205], v[244:245], v[40:41], v[204:205]
	v_pk_fma_f32 v[206:207], v[202:203], v[42:43], v[206:207]
	v_readlane_b32 s0, v75, 31
	s_lshl_b32 s0, s0, 10
	s_add_u32 s4, s8, s0
	s_addc_u32 s5, s9, 0
	global_load_dwordx4 v[198:201], v16, s[4:5]
	v_pk_add_f32 v[204:205], v[204:205], v[206:207]
	s_nop 0
	v_add_f32_e32 v221, v204, v205
	s_nop 1
	v_add_f32_dpp v221, v221, v221 quad_perm:[1,0,3,2] row_mask:0xf bank_mask:0xf bound_ctrl:1
	s_nop 1
	v_add_f32_dpp v221, v221, v221 quad_perm:[2,3,0,1] row_mask:0xf bank_mask:0xf bound_ctrl:1
	s_nop 1
	v_add_f32_dpp v221, v221, v221 row_half_mirror row_mask:0xf bank_mask:0xf bound_ctrl:1
	s_add_i32 s0, s1, 31
	s_cmp_lt_i32 s0, s2
	s_cselect_b64 vcc, -1, 0
	s_nop 1
	v_cndmask_b32_e32 v239, v220, v221, vcc
	v_max3_f32 v224, v210, v211, v212
	v_max3_f32 v224, v224, v213, v226
	v_max3_f32 v224, v224, v227, v228
	v_max3_f32 v224, v224, v229, v230
	v_max3_f32 v224, v224, v231, v232
	v_max3_f32 v224, v224, v233, v236
	v_max3_f32 v224, v224, v237, v238
	v_max_f32_e32 v224, v224, v239
	v_max_f32_e32 v221, v216, v224
	v_sub_f32_e32 v184, v216, v221
	v_exp_f32_e32 v184, v184
	v_mov_b32_e32 v216, v221
	s_nop 0
	v_pk_mul_f32 v[12:13], v[12:13], v[184:185] op_sel_hi:[1,0]
	v_pk_mul_f32 v[14:15], v[14:15], v[184:185] op_sel_hi:[1,0]
	v_pk_mul_f32 v[8:9], v[8:9], v[184:185] op_sel_hi:[1,0]
	v_pk_mul_f32 v[10:11], v[10:11], v[184:185] op_sel_hi:[1,0]
	v_pk_mul_f32 v[4:5], v[4:5], v[184:185] op_sel_hi:[1,0]
	v_pk_mul_f32 v[6:7], v[6:7], v[184:185] op_sel_hi:[1,0]
	v_pk_mul_f32 v[0:1], v[0:1], v[184:185] op_sel_hi:[1,0]
	v_pk_mul_f32 v[2:3], v[2:3], v[184:185] op_sel_hi:[1,0]
	v_mul_f32_e32 v215, v215, v184
	v_sub_f32_e32 v210, v210, v216
	v_exp_f32_e32 v210, v210
	s_waitcnt vmcnt(15)
; DI void topk_phase(const bf16_t* PROJ, const unsigned char* K8, const unsigned char* V8, const unsigned short* SC, bf16_t* ODSA, int c, char* smem, int bid, int nb) {
;     ...
;         const float mn = fmaxf(m_run, da), al = __builtin_amdgcn_exp2f(m_run - mn), pp = __builtin_amdgcn_exp2f(da - mn);
;         m_run = mn; l_run = l_run * al + pp;
; #pragma unroll
;         for (int i = 0; i < 4; ++i) {
;           const f32x2v lo = __builtin_amdgcn_cvt_pk_f32_fp8((int)u[i], false), hi = __builtin_amdgcn_cvt_pk_f32_fp8((int)u[i], true);
;           ov[4 * i] = ov[4 * i] * al + pp * lo[0]; ov[4 * i + 1] = ov[4 * i + 1] * al + pp * lo[1];
;           ov[4 * i + 2] = ov[4 * i + 2] * al + pp * hi[0]; ov[4 * i + 3] = ov[4 * i + 3] * al + pp * hi[1];
;         }
	v_cvt_pk_f32_fp8_e32 v[240:241], v136
	v_cvt_pk_f32_fp8_sdwa v[242:243], v136 src0_sel:WORD_1
	v_cvt_pk_f32_fp8_e32 v[244:245], v137
	v_pk_fma_f32 v[12:13], v[240:241], v[210:211], v[12:13] op_sel_hi:[1,0,1]
	v_cvt_pk_f32_fp8_sdwa v[240:241], v137 src0_sel:WORD_1
	v_pk_fma_f32 v[14:15], v[242:243], v[210:211], v[14:15] op_sel_hi:[1,0,1]
	v_cvt_pk_f32_fp8_e32 v[242:243], v138
	v_sub_f32_e32 v211, v211, v216
	v_pk_fma_f32 v[8:9], v[244:245], v[210:211], v[8:9] op_sel_hi:[1,0,1]
	v_cvt_pk_f32_fp8_sdwa v[244:245], v138 src0_sel:WORD_1
	v_pk_fma_f32 v[10:11], v[240:241], v[210:211], v[10:11] op_sel_hi:[1,0,1]
	v_cvt_pk_f32_fp8_e32 v[240:241], v139
	v_exp_f32_e32 v211, v211
	v_pk_fma_f32 v[4:5], v[242:243], v[210:211], v[4:5] op_sel_hi:[1,0,1]
	v_cvt_pk_f32_fp8_sdwa v[242:243], v139 src0_sel:WORD_1
	v_pk_fma_f32 v[6:7], v[244:245], v[210:211], v[6:7] op_sel_hi:[1,0,1]
	v_add_f32_e32 v215, v215, v210
	v_pk_fma_f32 v[0:1], v[240:241], v[210:211], v[0:1] op_sel_hi:[1,0,1]
	v_pk_fma_f32 v[2:3], v[242:243], v[210:211], v[2:3] op_sel_hi:[1,0,1]
	v_readlane_b32 s0, v75, 32
	s_lshl_b32 s0, s0, 10
	s_add_u32 s4, s6, s0
	s_addc_u32 s5, s7, 0
	global_load_dwordx4 v[136:139], v16, s[4:5]
	s_waitcnt vmcnt(15)
	v_cvt_pk_f32_fp8_e32 v[240:241], v140
	v_cvt_pk_f32_fp8_sdwa v[242:243], v140 src0_sel:WORD_1
	v_cvt_pk_f32_fp8_e32 v[244:245], v141
	v_pk_fma_f32 v[12:13], v[240:241], v[210:211], v[12:13] op_sel:[0,1,0]
	v_cvt_pk_f32_fp8_sdwa v[240:241], v141 src0_sel:WORD_1
	v_pk_fma_f32 v[14:15], v[242:243], v[210:211], v[14:15] op_sel:[0,1,0]
	v_cvt_pk_f32_fp8_e32 v[242:243], v142
	v_sub_f32_e32 v212, v212, v216
	v_pk_fma_f32 v[8:9], v[244:245], v[210:211], v[8:9] op_sel:[0,1,0]
	v_cvt_pk_f32_fp8_sdwa v[244:245], v142 src0_sel:WORD_1
	v_pk_fma_f32 v[10:11], v[240:241], v[210:211], v[10:11] op_sel:[0,1,0]
	v_cvt_pk_f32_fp8_e32 v[240:241], v143
	v_exp_f32_e32 v212, v212
	v_pk_fma_f32 v[4:5], v[242:243], v[210:211], v[4:5] op_sel:[0,1,0]
	v_cvt_pk_f32_fp8_sdwa v[242:243], v143 src0_sel:WORD_1
	v_pk_fma_f32 v[6:7], v[244:245], v[210:211], v[6:7] op_sel:[0,1,0]
	v_add_f32_e32 v215, v215, v211
	v_pk_fma_f32 v[0:1], v[240:241], v[210:211], v[0:1] op_sel:[0,1,0]
	v_pk_fma_f32 v[2:3], v[242:243], v[210:211], v[2:3] op_sel:[0,1,0]
	v_readlane_b32 s0, v75, 33
	s_lshl_b32 s0, s0, 10
	s_add_u32 s4, s6, s0
	s_addc_u32 s5, s7, 0
	global_load_dwordx4 v[140:143], v16, s[4:5]
	s_waitcnt vmcnt(15)
	v_cvt_pk_f32_fp8_e32 v[240:241], v144
	v_cvt_pk_f32_fp8_sdwa v[242:243], v144 src0_sel:WORD_1
	v_cvt_pk_f32_fp8_e32 v[244:245], v145
	v_pk_fma_f32 v[12:13], v[240:241], v[212:213], v[12:13] op_sel_hi:[1,0,1]
	v_cvt_pk_f32_fp8_sdwa v[240:241], v145 src0_sel:WORD_1
	v_pk_fma_f32 v[14:15], v[242:243], v[212:213], v[14:15] op_sel_hi:[1,0,1]
	v_cvt_pk_f32_fp8_e32 v[242:243], v146
	v_sub_f32_e32 v213, v213, v216
	v_pk_fma_f32 v[8:9], v[244:245], v[212:213], v[8:9] op_sel_hi:[1,0,1]
	v_cvt_pk_f32_fp8_sdwa v[244:245], v146 src0_sel:WORD_1
	v_pk_fma_f32 v[10:11], v[240:241], v[212:213], v[10:11] op_sel_hi:[1,0,1]
	v_cvt_pk_f32_fp8_e32 v[240:241], v147
	v_exp_f32_e32 v213, v213
	v_pk_fma_f32 v[4:5], v[242:243], v[212:213], v[4:5] op_sel_hi:[1,0,1]
	v_cvt_pk_f32_fp8_sdwa v[242:243], v147 src0_sel:WORD_1
	v_pk_fma_f32 v[6:7], v[244:245], v[212:213], v[6:7] op_sel_hi:[1,0,1]
	v_add_f32_e32 v215, v215, v212
	v_pk_fma_f32 v[0:1], v[240:241], v[212:213], v[0:1] op_sel_hi:[1,0,1]
	v_pk_fma_f32 v[2:3], v[242:243], v[212:213], v[2:3] op_sel_hi:[1,0,1]
	v_readlane_b32 s0, v75, 34
	s_lshl_b32 s0, s0, 10
	s_add_u32 s4, s6, s0
	s_addc_u32 s5, s7, 0
	global_load_dwordx4 v[144:147], v16, s[4:5]
	s_waitcnt vmcnt(15)
	v_cvt_pk_f32_fp8_e32 v[240:241], v148
	v_cvt_pk_f32_fp8_sdwa v[242:243], v148 src0_sel:WORD_1
	v_cvt_pk_f32_fp8_e32 v[244:245], v149
	v_pk_fma_f32 v[12:13], v[240:241], v[212:213], v[12:13] op_sel:[0,1,0]
	v_cvt_pk_f32_fp8_sdwa v[240:241], v149 src0_sel:WORD_1
	v_pk_fma_f32 v[14:15], v[242:243], v[212:213], v[14:15] op_sel:[0,1,0]
	v_cvt_pk_f32_fp8_e32 v[242:243], v150
	v_sub_f32_e32 v226, v226, v216
	v_pk_fma_f32 v[8:9], v[244:245], v[212:213], v[8:9] op_sel:[0,1,0]
	v_cvt_pk_f32_fp8_sdwa v[244:245], v150 src0_sel:WORD_1
	v_pk_fma_f32 v[10:11], v[240:241], v[212:213], v[10:11] op_sel:[0,1,0]
	v_cvt_pk_f32_fp8_e32 v[240:241], v151
	v_exp_f32_e32 v226, v226
	v_pk_fma_f32 v[4:5], v[242:243], v[212:213], v[4:5] op_sel:[0,1,0]
	v_cvt_pk_f32_fp8_sdwa v[242:243], v151 src0_sel:WORD_1
	v_pk_fma_f32 v[6:7], v[244:245], v[212:213], v[6:7] op_sel:[0,1,0]
	v_add_f32_e32 v215, v215, v213
	v_pk_fma_f32 v[0:1], v[240:241], v[212:213], v[0:1] op_sel:[0,1,0]
	v_pk_fma_f32 v[2:3], v[242:243], v[212:213], v[2:3] op_sel:[0,1,0]
	v_readlane_b32 s0, v75, 35
	s_lshl_b32 s0, s0, 10
	s_add_u32 s4, s6, s0
	s_addc_u32 s5, s7, 0
	global_load_dwordx4 v[148:151], v16, s[4:5]
	s_waitcnt vmcnt(15)
	v_cvt_pk_f32_fp8_e32 v[240:241], v152
	v_cvt_pk_f32_fp8_sdwa v[242:243], v152 src0_sel:WORD_1
	v_cvt_pk_f32_fp8_e32 v[244:245], v153
	v_pk_fma_f32 v[12:13], v[240:241], v[226:227], v[12:13] op_sel_hi:[1,0,1]
	v_cvt_pk_f32_fp8_sdwa v[240:241], v153 src0_sel:WORD_1
	v_pk_fma_f32 v[14:15], v[242:243], v[226:227], v[14:15] op_sel_hi:[1,0,1]
	v_cvt_pk_f32_fp8_e32 v[242:243], v154
	v_sub_f32_e32 v227, v227, v216
	v_pk_fma_f32 v[8:9], v[244:245], v[226:227], v[8:9] op_sel_hi:[1,0,1]
	v_cvt_pk_f32_fp8_sdwa v[244:245], v154 src0_sel:WORD_1
	v_pk_fma_f32 v[10:11], v[240:241], v[226:227], v[10:11] op_sel_hi:[1,0,1]
	v_cvt_pk_f32_fp8_e32 v[240:241], v155
	v_exp_f32_e32 v227, v227
	v_pk_fma_f32 v[4:5], v[242:243], v[226:227], v[4:5] op_sel_hi:[1,0,1]
	v_cvt_pk_f32_fp8_sdwa v[242:243], v155 src0_sel:WORD_1
	v_pk_fma_f32 v[6:7], v[244:245], v[226:227], v[6:7] op_sel_hi:[1,0,1]
	v_add_f32_e32 v215, v215, v226
	v_pk_fma_f32 v[0:1], v[240:241], v[226:227], v[0:1] op_sel_hi:[1,0,1]
	v_pk_fma_f32 v[2:3], v[242:243], v[226:227], v[2:3] op_sel_hi:[1,0,1]
	v_readlane_b32 s0, v75, 36
	s_lshl_b32 s0, s0, 10
	s_add_u32 s4, s6, s0
	s_addc_u32 s5, s7, 0
	global_load_dwordx4 v[152:155], v16, s[4:5]
	s_waitcnt vmcnt(15)
; DI void topk_phase(const bf16_t* PROJ, const unsigned char* K8, const unsigned char* V8, const unsigned short* SC, bf16_t* ODSA, int c, char* smem, int bid, int nb) {
;     ...
;         const float mn = fmaxf(m_run, da), al = __builtin_amdgcn_exp2f(m_run - mn), pp = __builtin_amdgcn_exp2f(da - mn);
;         m_run = mn; l_run = l_run * al + pp;
; #pragma unroll
;         for (int i = 0; i < 4; ++i) {
;           const f32x2v lo = __builtin_amdgcn_cvt_pk_f32_fp8((int)u[i], false), hi = __builtin_amdgcn_cvt_pk_f32_fp8((int)u[i], true);
;           ov[4 * i] = ov[4 * i] * al + pp * lo[0]; ov[4 * i + 1] = ov[4 * i + 1] * al + pp * lo[1];
;           ov[4 * i + 2] = ov[4 * i + 2] * al + pp * hi[0]; ov[4 * i + 3] = ov[4 * i + 3] * al + pp * hi[1];
;         }
	v_cvt_pk_f32_fp8_e32 v[240:241], v156
	v_cvt_pk_f32_fp8_sdwa v[242:243], v156 src0_sel:WORD_1
	v_cvt_pk_f32_fp8_e32 v[244:245], v157
	v_pk_fma_f32 v[12:13], v[240:241], v[226:227], v[12:13] op_sel:[0,1,0]
	v_cvt_pk_f32_fp8_sdwa v[240:241], v157 src0_sel:WORD_1
	v_pk_fma_f32 v[14:15], v[242:243], v[226:227], v[14:15] op_sel:[0,1,0]
	v_cvt_pk_f32_fp8_e32 v[242:243], v158
	v_sub_f32_e32 v228, v228, v216
	v_pk_fma_f32 v[8:9], v[244:245], v[226:227], v[8:9] op_sel:[0,1,0]
	v_cvt_pk_f32_fp8_sdwa v[244:245], v158 src0_sel:WORD_1
	v_pk_fma_f32 v[10:11], v[240:241], v[226:227], v[10:11] op_sel:[0,1,0]
	v_cvt_pk_f32_fp8_e32 v[240:241], v159
	v_exp_f32_e32 v228, v228
	v_pk_fma_f32 v[4:5], v[242:243], v[226:227], v[4:5] op_sel:[0,1,0]
	v_cvt_pk_f32_fp8_sdwa v[242:243], v159 src0_sel:WORD_1
	v_pk_fma_f32 v[6:7], v[244:245], v[226:227], v[6:7] op_sel:[0,1,0]
	v_add_f32_e32 v215, v215, v227
	v_pk_fma_f32 v[0:1], v[240:241], v[226:227], v[0:1] op_sel:[0,1,0]
	v_pk_fma_f32 v[2:3], v[242:243], v[226:227], v[2:3] op_sel:[0,1,0]
	v_readlane_b32 s0, v75, 37
	s_lshl_b32 s0, s0, 10
	s_add_u32 s4, s6, s0
	s_addc_u32 s5, s7, 0
	global_load_dwordx4 v[156:159], v16, s[4:5]
	s_waitcnt vmcnt(15)
	v_cvt_pk_f32_fp8_e32 v[240:241], v160
	v_cvt_pk_f32_fp8_sdwa v[242:243], v160 src0_sel:WORD_1
	v_cvt_pk_f32_fp8_e32 v[244:245], v161
	v_pk_fma_f32 v[12:13], v[240:241], v[228:229], v[12:13] op_sel_hi:[1,0,1]
	v_cvt_pk_f32_fp8_sdwa v[240:241], v161 src0_sel:WORD_1
	v_pk_fma_f32 v[14:15], v[242:243], v[228:229], v[14:15] op_sel_hi:[1,0,1]
	v_cvt_pk_f32_fp8_e32 v[242:243], v162
	v_sub_f32_e32 v229, v229, v216
	v_pk_fma_f32 v[8:9], v[244:245], v[228:229], v[8:9] op_sel_hi:[1,0,1]
	v_cvt_pk_f32_fp8_sdwa v[244:245], v162 src0_sel:WORD_1
	v_pk_fma_f32 v[10:11], v[240:241], v[228:229], v[10:11] op_sel_hi:[1,0,1]
	v_cvt_pk_f32_fp8_e32 v[240:241], v163
	v_exp_f32_e32 v229, v229
	v_pk_fma_f32 v[4:5], v[242:243], v[228:229], v[4:5] op_sel_hi:[1,0,1]
	v_cvt_pk_f32_fp8_sdwa v[242:243], v163 src0_sel:WORD_1
	v_pk_fma_f32 v[6:7], v[244:245], v[228:229], v[6:7] op_sel_hi:[1,0,1]
	v_add_f32_e32 v215, v215, v228
	v_pk_fma_f32 v[0:1], v[240:241], v[228:229], v[0:1] op_sel_hi:[1,0,1]
	v_pk_fma_f32 v[2:3], v[242:243], v[228:229], v[2:3] op_sel_hi:[1,0,1]
	v_readlane_b32 s0, v75, 38
	s_lshl_b32 s0, s0, 10
	s_add_u32 s4, s6, s0
	s_addc_u32 s5, s7, 0
	global_load_dwordx4 v[160:163], v16, s[4:5]
	s_waitcnt vmcnt(15)
	v_cvt_pk_f32_fp8_e32 v[240:241], v164
	v_cvt_pk_f32_fp8_sdwa v[242:243], v164 src0_sel:WORD_1
	v_cvt_pk_f32_fp8_e32 v[244:245], v165
	v_pk_fma_f32 v[12:13], v[240:241], v[228:229], v[12:13] op_sel:[0,1,0]
	v_cvt_pk_f32_fp8_sdwa v[240:241], v165 src0_sel:WORD_1
	v_pk_fma_f32 v[14:15], v[242:243], v[228:229], v[14:15] op_sel:[0,1,0]
	v_cvt_pk_f32_fp8_e32 v[242:243], v166
	v_sub_f32_e32 v230, v230, v216
	v_pk_fma_f32 v[8:9], v[244:245], v[228:229], v[8:9] op_sel:[0,1,0]
	v_cvt_pk_f32_fp8_sdwa v[244:245], v166 src0_sel:WORD_1
	v_pk_fma_f32 v[10:11], v[240:241], v[228:229], v[10:11] op_sel:[0,1,0]
	v_cvt_pk_f32_fp8_e32 v[240:241], v167
	v_exp_f32_e32 v230, v230
	v_pk_fma_f32 v[4:5], v[242:243], v[228:229], v[4:5] op_sel:[0,1,0]
	v_cvt_pk_f32_fp8_sdwa v[242:243], v167 src0_sel:WORD_1
	v_pk_fma_f32 v[6:7], v[244:245], v[228:229], v[6:7] op_sel:[0,1,0]
	v_add_f32_e32 v215, v215, v229
	v_pk_fma_f32 v[0:1], v[240:241], v[228:229], v[0:1] op_sel:[0,1,0]
	v_pk_fma_f32 v[2:3], v[242:243], v[228:229], v[2:3] op_sel:[0,1,0]
	v_readlane_b32 s0, v75, 39
	s_lshl_b32 s0, s0, 10
	s_add_u32 s4, s6, s0
	s_addc_u32 s5, s7, 0
	global_load_dwordx4 v[164:167], v16, s[4:5]
	s_waitcnt vmcnt(15)
	v_cvt_pk_f32_fp8_e32 v[240:241], v168
	v_cvt_pk_f32_fp8_sdwa v[242:243], v168 src0_sel:WORD_1
	v_cvt_pk_f32_fp8_e32 v[244:245], v169
	v_pk_fma_f32 v[12:13], v[240:241], v[230:231], v[12:13] op_sel_hi:[1,0,1]
	v_cvt_pk_f32_fp8_sdwa v[240:241], v169 src0_sel:WORD_1
	v_pk_fma_f32 v[14:15], v[242:243], v[230:231], v[14:15] op_sel_hi:[1,0,1]
	v_cvt_pk_f32_fp8_e32 v[242:243], v170
	v_sub_f32_e32 v231, v231, v216
	v_pk_fma_f32 v[8:9], v[244:245], v[230:231], v[8:9] op_sel_hi:[1,0,1]
	v_cvt_pk_f32_fp8_sdwa v[244:245], v170 src0_sel:WORD_1
	v_pk_fma_f32 v[10:11], v[240:241], v[230:231], v[10:11] op_sel_hi:[1,0,1]
	v_cvt_pk_f32_fp8_e32 v[240:241], v171
	v_exp_f32_e32 v231, v231
	v_pk_fma_f32 v[4:5], v[242:243], v[230:231], v[4:5] op_sel_hi:[1,0,1]
	v_cvt_pk_f32_fp8_sdwa v[242:243], v171 src0_sel:WORD_1
	v_pk_fma_f32 v[6:7], v[244:245], v[230:231], v[6:7] op_sel_hi:[1,0,1]
	v_add_f32_e32 v215, v215, v230
	v_pk_fma_f32 v[0:1], v[240:241], v[230:231], v[0:1] op_sel_hi:[1,0,1]
	v_pk_fma_f32 v[2:3], v[242:243], v[230:231], v[2:3] op_sel_hi:[1,0,1]
	v_readlane_b32 s0, v75, 40
	s_lshl_b32 s0, s0, 10
	s_add_u32 s4, s6, s0
	s_addc_u32 s5, s7, 0
	global_load_dwordx4 v[168:171], v16, s[4:5]
	s_waitcnt vmcnt(15)
	v_cvt_pk_f32_fp8_e32 v[240:241], v172
	v_cvt_pk_f32_fp8_sdwa v[242:243], v172 src0_sel:WORD_1
	v_cvt_pk_f32_fp8_e32 v[244:245], v173
	v_pk_fma_f32 v[12:13], v[240:241], v[230:231], v[12:13] op_sel:[0,1,0]
	v_cvt_pk_f32_fp8_sdwa v[240:241], v173 src0_sel:WORD_1
	v_pk_fma_f32 v[14:15], v[242:243], v[230:231], v[14:15] op_sel:[0,1,0]
	v_cvt_pk_f32_fp8_e32 v[242:243], v174
	v_sub_f32_e32 v232, v232, v216
	v_pk_fma_f32 v[8:9], v[244:245], v[230:231], v[8:9] op_sel:[0,1,0]
	v_cvt_pk_f32_fp8_sdwa v[244:245], v174 src0_sel:WORD_1
	v_pk_fma_f32 v[10:11], v[240:241], v[230:231], v[10:11] op_sel:[0,1,0]
	v_cvt_pk_f32_fp8_e32 v[240:241], v175
	v_exp_f32_e32 v232, v232
	v_pk_fma_f32 v[4:5], v[242:243], v[230:231], v[4:5] op_sel:[0,1,0]
	v_cvt_pk_f32_fp8_sdwa v[242:243], v175 src0_sel:WORD_1
	v_pk_fma_f32 v[6:7], v[244:245], v[230:231], v[6:7] op_sel:[0,1,0]
	v_add_f32_e32 v215, v215, v231
	v_pk_fma_f32 v[0:1], v[240:241], v[230:231], v[0:1] op_sel:[0,1,0]
	v_pk_fma_f32 v[2:3], v[242:243], v[230:231], v[2:3] op_sel:[0,1,0]
	v_readlane_b32 s0, v75, 41
	s_lshl_b32 s0, s0, 10
	s_add_u32 s4, s6, s0
	s_addc_u32 s5, s7, 0
	global_load_dwordx4 v[172:175], v16, s[4:5]
	s_waitcnt vmcnt(15)
; DI void topk_phase(const bf16_t* PROJ, const unsigned char* K8, const unsigned char* V8, const unsigned short* SC, bf16_t* ODSA, int c, char* smem, int bid, int nb) {
;     ...
;         const float mn = fmaxf(m_run, da), al = __builtin_amdgcn_exp2f(m_run - mn), pp = __builtin_amdgcn_exp2f(da - mn);
;         m_run = mn; l_run = l_run * al + pp;
; #pragma unroll
;         for (int i = 0; i < 4; ++i) {
;           const f32x2v lo = __builtin_amdgcn_cvt_pk_f32_fp8((int)u[i], false), hi = __builtin_amdgcn_cvt_pk_f32_fp8((int)u[i], true);
;           ov[4 * i] = ov[4 * i] * al + pp * lo[0]; ov[4 * i + 1] = ov[4 * i + 1] * al + pp * lo[1];
;           ov[4 * i + 2] = ov[4 * i + 2] * al + pp * hi[0]; ov[4 * i + 3] = ov[4 * i + 3] * al + pp * hi[1];
;         }
	v_cvt_pk_f32_fp8_e32 v[240:241], v176
	v_cvt_pk_f32_fp8_sdwa v[242:243], v176 src0_sel:WORD_1
	v_cvt_pk_f32_fp8_e32 v[244:245], v177
	v_pk_fma_f32 v[12:13], v[240:241], v[232:233], v[12:13] op_sel_hi:[1,0,1]
	v_cvt_pk_f32_fp8_sdwa v[240:241], v177 src0_sel:WORD_1
	v_pk_fma_f32 v[14:15], v[242:243], v[232:233], v[14:15] op_sel_hi:[1,0,1]
	v_cvt_pk_f32_fp8_e32 v[242:243], v178
	v_sub_f32_e32 v233, v233, v216
	v_pk_fma_f32 v[8:9], v[244:245], v[232:233], v[8:9] op_sel_hi:[1,0,1]
	v_cvt_pk_f32_fp8_sdwa v[244:245], v178 src0_sel:WORD_1
	v_pk_fma_f32 v[10:11], v[240:241], v[232:233], v[10:11] op_sel_hi:[1,0,1]
	v_cvt_pk_f32_fp8_e32 v[240:241], v179
	v_exp_f32_e32 v233, v233
	v_pk_fma_f32 v[4:5], v[242:243], v[232:233], v[4:5] op_sel_hi:[1,0,1]
	v_cvt_pk_f32_fp8_sdwa v[242:243], v179 src0_sel:WORD_1
	v_pk_fma_f32 v[6:7], v[244:245], v[232:233], v[6:7] op_sel_hi:[1,0,1]
	v_add_f32_e32 v215, v215, v232
	v_pk_fma_f32 v[0:1], v[240:241], v[232:233], v[0:1] op_sel_hi:[1,0,1]
	v_pk_fma_f32 v[2:3], v[242:243], v[232:233], v[2:3] op_sel_hi:[1,0,1]
	v_readlane_b32 s0, v75, 42
	s_lshl_b32 s0, s0, 10
	s_add_u32 s4, s6, s0
	s_addc_u32 s5, s7, 0
	global_load_dwordx4 v[176:179], v16, s[4:5]
	s_waitcnt vmcnt(15)
	v_cvt_pk_f32_fp8_e32 v[240:241], v180
	v_cvt_pk_f32_fp8_sdwa v[242:243], v180 src0_sel:WORD_1
	v_cvt_pk_f32_fp8_e32 v[244:245], v181
	v_pk_fma_f32 v[12:13], v[240:241], v[232:233], v[12:13] op_sel:[0,1,0]
	v_cvt_pk_f32_fp8_sdwa v[240:241], v181 src0_sel:WORD_1
	v_pk_fma_f32 v[14:15], v[242:243], v[232:233], v[14:15] op_sel:[0,1,0]
	v_cvt_pk_f32_fp8_e32 v[242:243], v182
	v_sub_f32_e32 v236, v236, v216
	v_pk_fma_f32 v[8:9], v[244:245], v[232:233], v[8:9] op_sel:[0,1,0]
	v_cvt_pk_f32_fp8_sdwa v[244:245], v182 src0_sel:WORD_1
	v_pk_fma_f32 v[10:11], v[240:241], v[232:233], v[10:11] op_sel:[0,1,0]
	v_cvt_pk_f32_fp8_e32 v[240:241], v183
	v_exp_f32_e32 v236, v236
	v_pk_fma_f32 v[4:5], v[242:243], v[232:233], v[4:5] op_sel:[0,1,0]
	v_cvt_pk_f32_fp8_sdwa v[242:243], v183 src0_sel:WORD_1
	v_pk_fma_f32 v[6:7], v[244:245], v[232:233], v[6:7] op_sel:[0,1,0]
	v_add_f32_e32 v215, v215, v233
	v_pk_fma_f32 v[0:1], v[240:241], v[232:233], v[0:1] op_sel:[0,1,0]
	v_pk_fma_f32 v[2:3], v[242:243], v[232:233], v[2:3] op_sel:[0,1,0]
	v_readlane_b32 s0, v75, 43
	s_lshl_b32 s0, s0, 10
	s_add_u32 s4, s6, s0
	s_addc_u32 s5, s7, 0
	global_load_dwordx4 v[180:183], v16, s[4:5]
	s_waitcnt vmcnt(15)
	v_cvt_pk_f32_fp8_e32 v[240:241], v186
	v_cvt_pk_f32_fp8_sdwa v[242:243], v186 src0_sel:WORD_1
	v_cvt_pk_f32_fp8_e32 v[244:245], v187
	v_pk_fma_f32 v[12:13], v[240:241], v[236:237], v[12:13] op_sel_hi:[1,0,1]
	v_cvt_pk_f32_fp8_sdwa v[240:241], v187 src0_sel:WORD_1
	v_pk_fma_f32 v[14:15], v[242:243], v[236:237], v[14:15] op_sel_hi:[1,0,1]
	v_cvt_pk_f32_fp8_e32 v[242:243], v188
	v_sub_f32_e32 v237, v237, v216
	v_pk_fma_f32 v[8:9], v[244:245], v[236:237], v[8:9] op_sel_hi:[1,0,1]
	v_cvt_pk_f32_fp8_sdwa v[244:245], v188 src0_sel:WORD_1
	v_pk_fma_f32 v[10:11], v[240:241], v[236:237], v[10:11] op_sel_hi:[1,0,1]
	v_cvt_pk_f32_fp8_e32 v[240:241], v189
	v_exp_f32_e32 v237, v237
	v_pk_fma_f32 v[4:5], v[242:243], v[236:237], v[4:5] op_sel_hi:[1,0,1]
	v_cvt_pk_f32_fp8_sdwa v[242:243], v189 src0_sel:WORD_1
	v_pk_fma_f32 v[6:7], v[244:245], v[236:237], v[6:7] op_sel_hi:[1,0,1]
	v_add_f32_e32 v215, v215, v236
	v_pk_fma_f32 v[0:1], v[240:241], v[236:237], v[0:1] op_sel_hi:[1,0,1]
	v_pk_fma_f32 v[2:3], v[242:243], v[236:237], v[2:3] op_sel_hi:[1,0,1]
	v_readlane_b32 s0, v75, 44
	s_lshl_b32 s0, s0, 10
	s_add_u32 s4, s6, s0
	s_addc_u32 s5, s7, 0
	global_load_dwordx4 v[186:189], v16, s[4:5]
	s_waitcnt vmcnt(15)
	v_cvt_pk_f32_fp8_e32 v[240:241], v190
	v_cvt_pk_f32_fp8_sdwa v[242:243], v190 src0_sel:WORD_1
	v_cvt_pk_f32_fp8_e32 v[244:245], v191
	v_pk_fma_f32 v[12:13], v[240:241], v[236:237], v[12:13] op_sel:[0,1,0]
	v_cvt_pk_f32_fp8_sdwa v[240:241], v191 src0_sel:WORD_1
	v_pk_fma_f32 v[14:15], v[242:243], v[236:237], v[14:15] op_sel:[0,1,0]
	v_cvt_pk_f32_fp8_e32 v[242:243], v192
	v_sub_f32_e32 v238, v238, v216
	v_pk_fma_f32 v[8:9], v[244:245], v[236:237], v[8:9] op_sel:[0,1,0]
	v_cvt_pk_f32_fp8_sdwa v[244:245], v192 src0_sel:WORD_1
	v_pk_fma_f32 v[10:11], v[240:241], v[236:237], v[10:11] op_sel:[0,1,0]
	v_cvt_pk_f32_fp8_e32 v[240:241], v193
	v_exp_f32_e32 v238, v238
	v_pk_fma_f32 v[4:5], v[242:243], v[236:237], v[4:5] op_sel:[0,1,0]
	v_cvt_pk_f32_fp8_sdwa v[242:243], v193 src0_sel:WORD_1
	v_pk_fma_f32 v[6:7], v[244:245], v[236:237], v[6:7] op_sel:[0,1,0]
	v_add_f32_e32 v215, v215, v237
	v_pk_fma_f32 v[0:1], v[240:241], v[236:237], v[0:1] op_sel:[0,1,0]
	v_pk_fma_f32 v[2:3], v[242:243], v[236:237], v[2:3] op_sel:[0,1,0]
	v_readlane_b32 s0, v75, 45
	s_lshl_b32 s0, s0, 10
	s_add_u32 s4, s6, s0
	s_addc_u32 s5, s7, 0
	global_load_dwordx4 v[190:193], v16, s[4:5]
	s_waitcnt vmcnt(15)
	v_cvt_pk_f32_fp8_e32 v[240:241], v194
	v_cvt_pk_f32_fp8_sdwa v[242:243], v194 src0_sel:WORD_1
	v_cvt_pk_f32_fp8_e32 v[244:245], v195
	v_pk_fma_f32 v[12:13], v[240:241], v[238:239], v[12:13] op_sel_hi:[1,0,1]
	v_cvt_pk_f32_fp8_sdwa v[240:241], v195 src0_sel:WORD_1
	v_pk_fma_f32 v[14:15], v[242:243], v[238:239], v[14:15] op_sel_hi:[1,0,1]
	v_cvt_pk_f32_fp8_e32 v[242:243], v196
	v_sub_f32_e32 v239, v239, v216
	v_pk_fma_f32 v[8:9], v[244:245], v[238:239], v[8:9] op_sel_hi:[1,0,1]
	v_cvt_pk_f32_fp8_sdwa v[244:245], v196 src0_sel:WORD_1
	v_pk_fma_f32 v[10:11], v[240:241], v[238:239], v[10:11] op_sel_hi:[1,0,1]
	v_cvt_pk_f32_fp8_e32 v[240:241], v197
	v_exp_f32_e32 v239, v239
	v_pk_fma_f32 v[4:5], v[242:243], v[238:239], v[4:5] op_sel_hi:[1,0,1]
	v_cvt_pk_f32_fp8_sdwa v[242:243], v197 src0_sel:WORD_1
	v_pk_fma_f32 v[6:7], v[244:245], v[238:239], v[6:7] op_sel_hi:[1,0,1]
	v_add_f32_e32 v215, v215, v238
	v_pk_fma_f32 v[0:1], v[240:241], v[238:239], v[0:1] op_sel_hi:[1,0,1]
	v_pk_fma_f32 v[2:3], v[242:243], v[238:239], v[2:3] op_sel_hi:[1,0,1]
	v_readlane_b32 s0, v75, 46
	s_lshl_b32 s0, s0, 10
	s_add_u32 s4, s6, s0
	s_addc_u32 s5, s7, 0
	global_load_dwordx4 v[194:197], v16, s[4:5]
	s_waitcnt vmcnt(15)
; #define DPPF(v, ctrl) __builtin_bit_cast(float, __builtin_amdgcn_update_dpp(0, __builtin_bit_cast(int, (v)), (ctrl), 0xf, 0xf, true))
; DI float sum8(float v) { v += DPPF(v, 0xB1); v += DPPF(v, 0x4E); v += DPPF(v, 0x141); return v; }
; DI void topk_phase(const bf16_t* PROJ, const unsigned char* K8, const unsigned char* V8, const unsigned short* SC, bf16_t* ODSA, int c, char* smem, int bid, int nb) {
;     ...
;         const size_t ro = (size_t)__builtin_amdgcn_readlane(mysel, jj) * 1024 + lane * 16;
;         const uint4 a = *(const uint4*)(K8 + ro), vv = *(const uint4*)(V8 + ro);
;         const unsigned w[4] = {a.x, a.y, a.z, a.w}, u[4] = {vv.x, vv.y, vv.z, vv.w};
;         float da = 0.f;
; #pragma unroll
;         for (int i = 0; i < 4; ++i) {
;           const f32x2v lo = __builtin_amdgcn_cvt_pk_f32_fp8((int)w[i], false), hi = __builtin_amdgcn_cvt_pk_f32_fp8((int)w[i], true);
;           da += qv[4 * i] * lo[0] + qv[4 * i + 1] * lo[1] + qv[4 * i + 2] * hi[0] + qv[4 * i + 3] * hi[1];
;         }
;         da = sum8(da);
;         da = j < count ? da : -3e30f;
;         const float mn = fmaxf(m_run, da), al = __builtin_amdgcn_exp2f(m_run - mn), pp = __builtin_amdgcn_exp2f(da - mn);
;         m_run = mn; l_run = l_run * al + pp;
; #pragma unroll
;         for (int i = 0; i < 4; ++i) {
;           const f32x2v lo = __builtin_amdgcn_cvt_pk_f32_fp8((int)u[i], false), hi = __builtin_amdgcn_cvt_pk_f32_fp8((int)u[i], true);
;           ov[4 * i] = ov[4 * i] * al + pp * lo[0]; ov[4 * i + 1] = ov[4 * i + 1] * al + pp * lo[1];
;           ov[4 * i + 2] = ov[4 * i + 2] * al + pp * hi[0]; ov[4 * i + 3] = ov[4 * i + 3] * al + pp * hi[1];
;         }
	v_cvt_pk_f32_fp8_e32 v[240:241], v198
	v_cvt_pk_f32_fp8_sdwa v[242:243], v198 src0_sel:WORD_1
	v_cvt_pk_f32_fp8_e32 v[244:245], v199
	v_pk_fma_f32 v[12:13], v[240:241], v[238:239], v[12:13] op_sel:[0,1,0]
	v_cvt_pk_f32_fp8_sdwa v[240:241], v199 src0_sel:WORD_1
	v_pk_fma_f32 v[14:15], v[242:243], v[238:239], v[14:15] op_sel:[0,1,0]
	v_cvt_pk_f32_fp8_e32 v[242:243], v200
	v_add_f32_e32 v215, v215, v239
	v_pk_fma_f32 v[8:9], v[244:245], v[238:239], v[8:9] op_sel:[0,1,0]
	v_cvt_pk_f32_fp8_sdwa v[244:245], v200 src0_sel:WORD_1
	v_pk_fma_f32 v[10:11], v[240:241], v[238:239], v[10:11] op_sel:[0,1,0]
	v_cvt_pk_f32_fp8_e32 v[240:241], v201
	v_pk_fma_f32 v[4:5], v[242:243], v[238:239], v[4:5] op_sel:[0,1,0]
	v_cvt_pk_f32_fp8_sdwa v[242:243], v201 src0_sel:WORD_1
	v_pk_fma_f32 v[6:7], v[244:245], v[238:239], v[6:7] op_sel:[0,1,0]
	v_pk_fma_f32 v[0:1], v[240:241], v[238:239], v[0:1] op_sel:[0,1,0]
	v_pk_fma_f32 v[2:3], v[242:243], v[238:239], v[2:3] op_sel:[0,1,0]
	v_readlane_b32 s0, v75, 47
	s_lshl_b32 s0, s0, 10
	s_add_u32 s4, s6, s0
	s_addc_u32 s5, s7, 0
	global_load_dwordx4 v[198:201], v16, s[4:5]
	s_waitcnt vmcnt(15)
	v_cvt_pk_f32_fp8_e32 v[240:241], v136
	v_cvt_pk_f32_fp8_sdwa v[242:243], v136 src0_sel:WORD_1
	v_cvt_pk_f32_fp8_e32 v[244:245], v137
	v_cvt_pk_f32_fp8_sdwa v[202:203], v137 src0_sel:WORD_1
	v_pk_mul_f32 v[204:205], v[240:241], v[28:29]
	v_pk_mul_f32 v[206:207], v[242:243], v[30:31]
	v_cvt_pk_f32_fp8_e32 v[240:241], v138
	v_cvt_pk_f32_fp8_sdwa v[242:243], v138 src0_sel:WORD_1
	v_pk_fma_f32 v[204:205], v[244:245], v[32:33], v[204:205]
	v_pk_fma_f32 v[206:207], v[202:203], v[34:35], v[206:207]
	v_cvt_pk_f32_fp8_e32 v[244:245], v139
	v_cvt_pk_f32_fp8_sdwa v[202:203], v139 src0_sel:WORD_1
	v_pk_fma_f32 v[204:205], v[240:241], v[36:37], v[204:205]
	v_pk_fma_f32 v[206:207], v[242:243], v[38:39], v[206:207]
	v_pk_fma_f32 v[204:205], v[244:245], v[40:41], v[204:205]
	v_pk_fma_f32 v[206:207], v[202:203], v[42:43], v[206:207]
	v_readlane_b32 s0, v75, 32
	s_lshl_b32 s0, s0, 10
	s_add_u32 s4, s8, s0
	s_addc_u32 s5, s9, 0
	global_load_dwordx4 v[136:139], v16, s[4:5]
	v_pk_add_f32 v[204:205], v[204:205], v[206:207]
	s_nop 0
	v_add_f32_e32 v235, v204, v205
	s_waitcnt vmcnt(15)
	v_cvt_pk_f32_fp8_e32 v[240:241], v140
	v_cvt_pk_f32_fp8_sdwa v[242:243], v140 src0_sel:WORD_1
	v_cvt_pk_f32_fp8_e32 v[244:245], v141
	v_cvt_pk_f32_fp8_sdwa v[202:203], v141 src0_sel:WORD_1
	v_add_f32_dpp v235, v235, v235 quad_perm:[1,0,3,2] row_mask:0xf bank_mask:0xf bound_ctrl:1
	v_pk_mul_f32 v[204:205], v[240:241], v[28:29]
	v_pk_mul_f32 v[206:207], v[242:243], v[30:31]
	v_add_f32_dpp v235, v235, v235 quad_perm:[2,3,0,1] row_mask:0xf bank_mask:0xf bound_ctrl:1
	v_cvt_pk_f32_fp8_e32 v[240:241], v142
	v_cvt_pk_f32_fp8_sdwa v[242:243], v142 src0_sel:WORD_1
	v_add_f32_dpp v235, v235, v235 row_half_mirror row_mask:0xf bank_mask:0xf bound_ctrl:1
	v_pk_fma_f32 v[204:205], v[244:245], v[32:33], v[204:205]
	v_pk_fma_f32 v[206:207], v[202:203], v[34:35], v[206:207]
	s_add_i32 s0, s1, 32
	s_cmp_lt_i32 s0, s2
	s_cselect_b64 vcc, -1, 0
	v_cvt_pk_f32_fp8_e32 v[244:245], v143
	v_cvt_pk_f32_fp8_sdwa v[202:203], v143 src0_sel:WORD_1
	v_cndmask_b32_e32 v210, v220, v235, vcc
	v_pk_fma_f32 v[204:205], v[240:241], v[36:37], v[204:205]
	v_pk_fma_f32 v[206:207], v[242:243], v[38:39], v[206:207]
	v_pk_fma_f32 v[204:205], v[244:245], v[40:41], v[204:205]
	v_pk_fma_f32 v[206:207], v[202:203], v[42:43], v[206:207]
	v_readlane_b32 s0, v75, 33
	s_lshl_b32 s0, s0, 10
	s_add_u32 s4, s8, s0
	s_addc_u32 s5, s9, 0
	global_load_dwordx4 v[140:143], v16, s[4:5]
	v_pk_add_f32 v[204:205], v[204:205], v[206:207]
	s_nop 0
	v_add_f32_e32 v221, v204, v205
	s_waitcnt vmcnt(15)
	v_cvt_pk_f32_fp8_e32 v[240:241], v144
	v_cvt_pk_f32_fp8_sdwa v[242:243], v144 src0_sel:WORD_1
	v_cvt_pk_f32_fp8_e32 v[244:245], v145
	v_cvt_pk_f32_fp8_sdwa v[202:203], v145 src0_sel:WORD_1
	v_add_f32_dpp v221, v221, v221 quad_perm:[1,0,3,2] row_mask:0xf bank_mask:0xf bound_ctrl:1
	v_pk_mul_f32 v[204:205], v[240:241], v[28:29]
	v_pk_mul_f32 v[206:207], v[242:243], v[30:31]
	v_add_f32_dpp v221, v221, v221 quad_perm:[2,3,0,1] row_mask:0xf bank_mask:0xf bound_ctrl:1
	v_cvt_pk_f32_fp8_e32 v[240:241], v146
	v_cvt_pk_f32_fp8_sdwa v[242:243], v146 src0_sel:WORD_1
	v_add_f32_dpp v221, v221, v221 row_half_mirror row_mask:0xf bank_mask:0xf bound_ctrl:1
	v_pk_fma_f32 v[204:205], v[244:245], v[32:33], v[204:205]
	v_pk_fma_f32 v[206:207], v[202:203], v[34:35], v[206:207]
	s_add_i32 s0, s1, 33
	s_cmp_lt_i32 s0, s2
	s_cselect_b64 vcc, -1, 0
	v_cvt_pk_f32_fp8_e32 v[244:245], v147
	v_cvt_pk_f32_fp8_sdwa v[202:203], v147 src0_sel:WORD_1
	v_cndmask_b32_e32 v211, v220, v221, vcc
	v_pk_fma_f32 v[204:205], v[240:241], v[36:37], v[204:205]
	v_pk_fma_f32 v[206:207], v[242:243], v[38:39], v[206:207]
	v_pk_fma_f32 v[204:205], v[244:245], v[40:41], v[204:205]
	v_pk_fma_f32 v[206:207], v[202:203], v[42:43], v[206:207]
	v_readlane_b32 s0, v75, 34
	s_lshl_b32 s0, s0, 10
	s_add_u32 s4, s8, s0
	s_addc_u32 s5, s9, 0
	global_load_dwordx4 v[144:147], v16, s[4:5]
	v_pk_add_f32 v[204:205], v[204:205], v[206:207]
	s_nop 0
	v_add_f32_e32 v235, v204, v205
	s_waitcnt vmcnt(15)
; #define DPPF(v, ctrl) __builtin_bit_cast(float, __builtin_amdgcn_update_dpp(0, __builtin_bit_cast(int, (v)), (ctrl), 0xf, 0xf, true))
; DI float sum8(float v) { v += DPPF(v, 0xB1); v += DPPF(v, 0x4E); v += DPPF(v, 0x141); return v; }
; DI void topk_phase(const bf16_t* PROJ, const unsigned char* K8, const unsigned char* V8, const unsigned short* SC, bf16_t* ODSA, int c, char* smem, int bid, int nb) {
;     ...
;         const size_t ro = (size_t)__builtin_amdgcn_readlane(mysel, jj) * 1024 + lane * 16;
;         const uint4 a = *(const uint4*)(K8 + ro), vv = *(const uint4*)(V8 + ro);
;         const unsigned w[4] = {a.x, a.y, a.z, a.w}, u[4] = {vv.x, vv.y, vv.z, vv.w};
;         float da = 0.f;
; #pragma unroll
;         for (int i = 0; i < 4; ++i) {
;           const f32x2v lo = __builtin_amdgcn_cvt_pk_f32_fp8((int)w[i], false), hi = __builtin_amdgcn_cvt_pk_f32_fp8((int)w[i], true);
;           da += qv[4 * i] * lo[0] + qv[4 * i + 1] * lo[1] + qv[4 * i + 2] * hi[0] + qv[4 * i + 3] * hi[1];
;         }
;         da = sum8(da);
;         da = j < count ? da : -3e30f;
	v_cvt_pk_f32_fp8_e32 v[240:241], v148
	v_cvt_pk_f32_fp8_sdwa v[242:243], v148 src0_sel:WORD_1
	v_cvt_pk_f32_fp8_e32 v[244:245], v149
	v_cvt_pk_f32_fp8_sdwa v[202:203], v149 src0_sel:WORD_1
	v_add_f32_dpp v235, v235, v235 quad_perm:[1,0,3,2] row_mask:0xf bank_mask:0xf bound_ctrl:1
	v_pk_mul_f32 v[204:205], v[240:241], v[28:29]
	v_pk_mul_f32 v[206:207], v[242:243], v[30:31]
	v_add_f32_dpp v235, v235, v235 quad_perm:[2,3,0,1] row_mask:0xf bank_mask:0xf bound_ctrl:1
	v_cvt_pk_f32_fp8_e32 v[240:241], v150
	v_cvt_pk_f32_fp8_sdwa v[242:243], v150 src0_sel:WORD_1
	v_add_f32_dpp v235, v235, v235 row_half_mirror row_mask:0xf bank_mask:0xf bound_ctrl:1
	v_pk_fma_f32 v[204:205], v[244:245], v[32:33], v[204:205]
	v_pk_fma_f32 v[206:207], v[202:203], v[34:35], v[206:207]
	s_add_i32 s0, s1, 34
	s_cmp_lt_i32 s0, s2
	s_cselect_b64 vcc, -1, 0
	v_cvt_pk_f32_fp8_e32 v[244:245], v151
	v_cvt_pk_f32_fp8_sdwa v[202:203], v151 src0_sel:WORD_1
	v_cndmask_b32_e32 v212, v220, v235, vcc
	v_pk_fma_f32 v[204:205], v[240:241], v[36:37], v[204:205]
	v_pk_fma_f32 v[206:207], v[242:243], v[38:39], v[206:207]
	v_pk_fma_f32 v[204:205], v[244:245], v[40:41], v[204:205]
	v_pk_fma_f32 v[206:207], v[202:203], v[42:43], v[206:207]
	v_readlane_b32 s0, v75, 35
	s_lshl_b32 s0, s0, 10
	s_add_u32 s4, s8, s0
	s_addc_u32 s5, s9, 0
	global_load_dwordx4 v[148:151], v16, s[4:5]
	v_pk_add_f32 v[204:205], v[204:205], v[206:207]
	s_nop 0
	v_add_f32_e32 v221, v204, v205
	s_waitcnt vmcnt(15)
	v_cvt_pk_f32_fp8_e32 v[240:241], v152
	v_cvt_pk_f32_fp8_sdwa v[242:243], v152 src0_sel:WORD_1
	v_cvt_pk_f32_fp8_e32 v[244:245], v153
	v_cvt_pk_f32_fp8_sdwa v[202:203], v153 src0_sel:WORD_1
	v_add_f32_dpp v221, v221, v221 quad_perm:[1,0,3,2] row_mask:0xf bank_mask:0xf bound_ctrl:1
	v_pk_mul_f32 v[204:205], v[240:241], v[28:29]
	v_pk_mul_f32 v[206:207], v[242:243], v[30:31]
	v_add_f32_dpp v221, v221, v221 quad_perm:[2,3,0,1] row_mask:0xf bank_mask:0xf bound_ctrl:1
	v_cvt_pk_f32_fp8_e32 v[240:241], v154
	v_cvt_pk_f32_fp8_sdwa v[242:243], v154 src0_sel:WORD_1
	v_add_f32_dpp v221, v221, v221 row_half_mirror row_mask:0xf bank_mask:0xf bound_ctrl:1
	v_pk_fma_f32 v[204:205], v[244:245], v[32:33], v[204:205]
	v_pk_fma_f32 v[206:207], v[202:203], v[34:35], v[206:207]
	s_add_i32 s0, s1, 35
	s_cmp_lt_i32 s0, s2
	s_cselect_b64 vcc, -1, 0
	v_cvt_pk_f32_fp8_e32 v[244:245], v155
	v_cvt_pk_f32_fp8_sdwa v[202:203], v155 src0_sel:WORD_1
	v_cndmask_b32_e32 v213, v220, v221, vcc
	v_pk_fma_f32 v[204:205], v[240:241], v[36:37], v[204:205]
	v_pk_fma_f32 v[206:207], v[242:243], v[38:39], v[206:207]
	v_pk_fma_f32 v[204:205], v[244:245], v[40:41], v[204:205]
	v_pk_fma_f32 v[206:207], v[202:203], v[42:43], v[206:207]
	v_readlane_b32 s0, v75, 36
	s_lshl_b32 s0, s0, 10
	s_add_u32 s4, s8, s0
	s_addc_u32 s5, s9, 0
	global_load_dwordx4 v[152:155], v16, s[4:5]
	v_pk_add_f32 v[204:205], v[204:205], v[206:207]
	s_nop 0
	v_add_f32_e32 v235, v204, v205
	s_waitcnt vmcnt(15)
	v_cvt_pk_f32_fp8_e32 v[240:241], v156
	v_cvt_pk_f32_fp8_sdwa v[242:243], v156 src0_sel:WORD_1
	v_cvt_pk_f32_fp8_e32 v[244:245], v157
	v_cvt_pk_f32_fp8_sdwa v[202:203], v157 src0_sel:WORD_1
	v_add_f32_dpp v235, v235, v235 quad_perm:[1,0,3,2] row_mask:0xf bank_mask:0xf bound_ctrl:1
	v_pk_mul_f32 v[204:205], v[240:241], v[28:29]
	v_pk_mul_f32 v[206:207], v[242:243], v[30:31]
	v_add_f32_dpp v235, v235, v235 quad_perm:[2,3,0,1] row_mask:0xf bank_mask:0xf bound_ctrl:1
	v_cvt_pk_f32_fp8_e32 v[240:241], v158
	v_cvt_pk_f32_fp8_sdwa v[242:243], v158 src0_sel:WORD_1
	v_add_f32_dpp v235, v235, v235 row_half_mirror row_mask:0xf bank_mask:0xf bound_ctrl:1
	v_pk_fma_f32 v[204:205], v[244:245], v[32:33], v[204:205]
	v_pk_fma_f32 v[206:207], v[202:203], v[34:35], v[206:207]
	s_add_i32 s0, s1, 36
	s_cmp_lt_i32 s0, s2
	s_cselect_b64 vcc, -1, 0
	v_cvt_pk_f32_fp8_e32 v[244:245], v159
	v_cvt_pk_f32_fp8_sdwa v[202:203], v159 src0_sel:WORD_1
	v_cndmask_b32_e32 v226, v220, v235, vcc
	v_pk_fma_f32 v[204:205], v[240:241], v[36:37], v[204:205]
	v_pk_fma_f32 v[206:207], v[242:243], v[38:39], v[206:207]
	v_pk_fma_f32 v[204:205], v[244:245], v[40:41], v[204:205]
	v_pk_fma_f32 v[206:207], v[202:203], v[42:43], v[206:207]
	v_readlane_b32 s0, v75, 37
	s_lshl_b32 s0, s0, 10
	s_add_u32 s4, s8, s0
	s_addc_u32 s5, s9, 0
	global_load_dwordx4 v[156:159], v16, s[4:5]
	v_pk_add_f32 v[204:205], v[204:205], v[206:207]
	s_nop 0
	v_add_f32_e32 v221, v204, v205
	s_waitcnt vmcnt(15)
	v_cvt_pk_f32_fp8_e32 v[240:241], v160
	v_cvt_pk_f32_fp8_sdwa v[242:243], v160 src0_sel:WORD_1
	v_cvt_pk_f32_fp8_e32 v[244:245], v161
	v_cvt_pk_f32_fp8_sdwa v[202:203], v161 src0_sel:WORD_1
	v_add_f32_dpp v221, v221, v221 quad_perm:[1,0,3,2] row_mask:0xf bank_mask:0xf bound_ctrl:1
	v_pk_mul_f32 v[204:205], v[240:241], v[28:29]
	v_pk_mul_f32 v[206:207], v[242:243], v[30:31]
	v_add_f32_dpp v221, v221, v221 quad_perm:[2,3,0,1] row_mask:0xf bank_mask:0xf bound_ctrl:1
	v_cvt_pk_f32_fp8_e32 v[240:241], v162
	v_cvt_pk_f32_fp8_sdwa v[242:243], v162 src0_sel:WORD_1
	v_add_f32_dpp v221, v221, v221 row_half_mirror row_mask:0xf bank_mask:0xf bound_ctrl:1
	v_pk_fma_f32 v[204:205], v[244:245], v[32:33], v[204:205]
	v_pk_fma_f32 v[206:207], v[202:203], v[34:35], v[206:207]
	s_add_i32 s0, s1, 37
	s_cmp_lt_i32 s0, s2
	s_cselect_b64 vcc, -1, 0
	v_cvt_pk_f32_fp8_e32 v[244:245], v163
	v_cvt_pk_f32_fp8_sdwa v[202:203], v163 src0_sel:WORD_1
	v_cndmask_b32_e32 v227, v220, v221, vcc
	v_pk_fma_f32 v[204:205], v[240:241], v[36:37], v[204:205]
	v_pk_fma_f32 v[206:207], v[242:243], v[38:39], v[206:207]
	v_pk_fma_f32 v[204:205], v[244:245], v[40:41], v[204:205]
	v_pk_fma_f32 v[206:207], v[202:203], v[42:43], v[206:207]
	v_readlane_b32 s0, v75, 38
	s_lshl_b32 s0, s0, 10
	s_add_u32 s4, s8, s0
	s_addc_u32 s5, s9, 0
	global_load_dwordx4 v[160:163], v16, s[4:5]
	v_pk_add_f32 v[204:205], v[204:205], v[206:207]
	s_nop 0
	v_add_f32_e32 v235, v204, v205
	s_waitcnt vmcnt(15)
; #define DPPF(v, ctrl) __builtin_bit_cast(float, __builtin_amdgcn_update_dpp(0, __builtin_bit_cast(int, (v)), (ctrl), 0xf, 0xf, true))
; DI float sum8(float v) { v += DPPF(v, 0xB1); v += DPPF(v, 0x4E); v += DPPF(v, 0x141); return v; }
; DI void topk_phase(const bf16_t* PROJ, const unsigned char* K8, const unsigned char* V8, const unsigned short* SC, bf16_t* ODSA, int c, char* smem, int bid, int nb) {
;     ...
;         const size_t ro = (size_t)__builtin_amdgcn_readlane(mysel, jj) * 1024 + lane * 16;
;         const uint4 a = *(const uint4*)(K8 + ro), vv = *(const uint4*)(V8 + ro);
;         const unsigned w[4] = {a.x, a.y, a.z, a.w}, u[4] = {vv.x, vv.y, vv.z, vv.w};
;         float da = 0.f;
; #pragma unroll
;         for (int i = 0; i < 4; ++i) {
;           const f32x2v lo = __builtin_amdgcn_cvt_pk_f32_fp8((int)w[i], false), hi = __builtin_amdgcn_cvt_pk_f32_fp8((int)w[i], true);
;           da += qv[4 * i] * lo[0] + qv[4 * i + 1] * lo[1] + qv[4 * i + 2] * hi[0] + qv[4 * i + 3] * hi[1];
;         }
;         da = sum8(da);
;         da = j < count ? da : -3e30f;
	v_cvt_pk_f32_fp8_e32 v[240:241], v164
	v_cvt_pk_f32_fp8_sdwa v[242:243], v164 src0_sel:WORD_1
	v_cvt_pk_f32_fp8_e32 v[244:245], v165
	v_cvt_pk_f32_fp8_sdwa v[202:203], v165 src0_sel:WORD_1
	v_add_f32_dpp v235, v235, v235 quad_perm:[1,0,3,2] row_mask:0xf bank_mask:0xf bound_ctrl:1
	v_pk_mul_f32 v[204:205], v[240:241], v[28:29]
	v_pk_mul_f32 v[206:207], v[242:243], v[30:31]
	v_add_f32_dpp v235, v235, v235 quad_perm:[2,3,0,1] row_mask:0xf bank_mask:0xf bound_ctrl:1
	v_cvt_pk_f32_fp8_e32 v[240:241], v166
	v_cvt_pk_f32_fp8_sdwa v[242:243], v166 src0_sel:WORD_1
	v_add_f32_dpp v235, v235, v235 row_half_mirror row_mask:0xf bank_mask:0xf bound_ctrl:1
	v_pk_fma_f32 v[204:205], v[244:245], v[32:33], v[204:205]
	v_pk_fma_f32 v[206:207], v[202:203], v[34:35], v[206:207]
	s_add_i32 s0, s1, 38
	s_cmp_lt_i32 s0, s2
	s_cselect_b64 vcc, -1, 0
	v_cvt_pk_f32_fp8_e32 v[244:245], v167
	v_cvt_pk_f32_fp8_sdwa v[202:203], v167 src0_sel:WORD_1
	v_cndmask_b32_e32 v228, v220, v235, vcc
	v_pk_fma_f32 v[204:205], v[240:241], v[36:37], v[204:205]
	v_pk_fma_f32 v[206:207], v[242:243], v[38:39], v[206:207]
	v_pk_fma_f32 v[204:205], v[244:245], v[40:41], v[204:205]
	v_pk_fma_f32 v[206:207], v[202:203], v[42:43], v[206:207]
	v_readlane_b32 s0, v75, 39
	s_lshl_b32 s0, s0, 10
	s_add_u32 s4, s8, s0
	s_addc_u32 s5, s9, 0
	global_load_dwordx4 v[164:167], v16, s[4:5]
	v_pk_add_f32 v[204:205], v[204:205], v[206:207]
	s_nop 0
	v_add_f32_e32 v221, v204, v205
	s_waitcnt vmcnt(15)
	v_cvt_pk_f32_fp8_e32 v[240:241], v168
	v_cvt_pk_f32_fp8_sdwa v[242:243], v168 src0_sel:WORD_1
	v_cvt_pk_f32_fp8_e32 v[244:245], v169
	v_cvt_pk_f32_fp8_sdwa v[202:203], v169 src0_sel:WORD_1
	v_add_f32_dpp v221, v221, v221 quad_perm:[1,0,3,2] row_mask:0xf bank_mask:0xf bound_ctrl:1
	v_pk_mul_f32 v[204:205], v[240:241], v[28:29]
	v_pk_mul_f32 v[206:207], v[242:243], v[30:31]
	v_add_f32_dpp v221, v221, v221 quad_perm:[2,3,0,1] row_mask:0xf bank_mask:0xf bound_ctrl:1
	v_cvt_pk_f32_fp8_e32 v[240:241], v170
	v_cvt_pk_f32_fp8_sdwa v[242:243], v170 src0_sel:WORD_1
	v_add_f32_dpp v221, v221, v221 row_half_mirror row_mask:0xf bank_mask:0xf bound_ctrl:1
	v_pk_fma_f32 v[204:205], v[244:245], v[32:33], v[204:205]
	v_pk_fma_f32 v[206:207], v[202:203], v[34:35], v[206:207]
	s_add_i32 s0, s1, 39
	s_cmp_lt_i32 s0, s2
	s_cselect_b64 vcc, -1, 0
	v_cvt_pk_f32_fp8_e32 v[244:245], v171
	v_cvt_pk_f32_fp8_sdwa v[202:203], v171 src0_sel:WORD_1
	v_cndmask_b32_e32 v229, v220, v221, vcc
	v_pk_fma_f32 v[204:205], v[240:241], v[36:37], v[204:205]
	v_pk_fma_f32 v[206:207], v[242:243], v[38:39], v[206:207]
	v_pk_fma_f32 v[204:205], v[244:245], v[40:41], v[204:205]
	v_pk_fma_f32 v[206:207], v[202:203], v[42:43], v[206:207]
	v_readlane_b32 s0, v75, 40
	s_lshl_b32 s0, s0, 10
	s_add_u32 s4, s8, s0
	s_addc_u32 s5, s9, 0
	global_load_dwordx4 v[168:171], v16, s[4:5]
	v_pk_add_f32 v[204:205], v[204:205], v[206:207]
	s_nop 0
	v_add_f32_e32 v235, v204, v205
	s_waitcnt vmcnt(15)
	v_cvt_pk_f32_fp8_e32 v[240:241], v172
	v_cvt_pk_f32_fp8_sdwa v[242:243], v172 src0_sel:WORD_1
	v_cvt_pk_f32_fp8_e32 v[244:245], v173
	v_cvt_pk_f32_fp8_sdwa v[202:203], v173 src0_sel:WORD_1
	v_add_f32_dpp v235, v235, v235 quad_perm:[1,0,3,2] row_mask:0xf bank_mask:0xf bound_ctrl:1
	v_pk_mul_f32 v[204:205], v[240:241], v[28:29]
	v_pk_mul_f32 v[206:207], v[242:243], v[30:31]
	v_add_f32_dpp v235, v235, v235 quad_perm:[2,3,0,1] row_mask:0xf bank_mask:0xf bound_ctrl:1
	v_cvt_pk_f32_fp8_e32 v[240:241], v174
	v_cvt_pk_f32_fp8_sdwa v[242:243], v174 src0_sel:WORD_1
	v_add_f32_dpp v235, v235, v235 row_half_mirror row_mask:0xf bank_mask:0xf bound_ctrl:1
	v_pk_fma_f32 v[204:205], v[244:245], v[32:33], v[204:205]
	v_pk_fma_f32 v[206:207], v[202:203], v[34:35], v[206:207]
	s_add_i32 s0, s1, 40
	s_cmp_lt_i32 s0, s2
	s_cselect_b64 vcc, -1, 0
	v_cvt_pk_f32_fp8_e32 v[244:245], v175
	v_cvt_pk_f32_fp8_sdwa v[202:203], v175 src0_sel:WORD_1
	v_cndmask_b32_e32 v230, v220, v235, vcc
	v_pk_fma_f32 v[204:205], v[240:241], v[36:37], v[204:205]
	v_pk_fma_f32 v[206:207], v[242:243], v[38:39], v[206:207]
	v_pk_fma_f32 v[204:205], v[244:245], v[40:41], v[204:205]
	v_pk_fma_f32 v[206:207], v[202:203], v[42:43], v[206:207]
	v_readlane_b32 s0, v75, 41
	s_lshl_b32 s0, s0, 10
	s_add_u32 s4, s8, s0
	s_addc_u32 s5, s9, 0
	global_load_dwordx4 v[172:175], v16, s[4:5]
	v_pk_add_f32 v[204:205], v[204:205], v[206:207]
	s_nop 0
	v_add_f32_e32 v221, v204, v205
	s_waitcnt vmcnt(15)
	v_cvt_pk_f32_fp8_e32 v[240:241], v176
	v_cvt_pk_f32_fp8_sdwa v[242:243], v176 src0_sel:WORD_1
	v_cvt_pk_f32_fp8_e32 v[244:245], v177
	v_cvt_pk_f32_fp8_sdwa v[202:203], v177 src0_sel:WORD_1
	v_add_f32_dpp v221, v221, v221 quad_perm:[1,0,3,2] row_mask:0xf bank_mask:0xf bound_ctrl:1
	v_pk_mul_f32 v[204:205], v[240:241], v[28:29]
	v_pk_mul_f32 v[206:207], v[242:243], v[30:31]
	v_add_f32_dpp v221, v221, v221 quad_perm:[2,3,0,1] row_mask:0xf bank_mask:0xf bound_ctrl:1
	v_cvt_pk_f32_fp8_e32 v[240:241], v178
	v_cvt_pk_f32_fp8_sdwa v[242:243], v178 src0_sel:WORD_1
	v_add_f32_dpp v221, v221, v221 row_half_mirror row_mask:0xf bank_mask:0xf bound_ctrl:1
	v_pk_fma_f32 v[204:205], v[244:245], v[32:33], v[204:205]
	v_pk_fma_f32 v[206:207], v[202:203], v[34:35], v[206:207]
	s_add_i32 s0, s1, 41
	s_cmp_lt_i32 s0, s2
	s_cselect_b64 vcc, -1, 0
	v_cvt_pk_f32_fp8_e32 v[244:245], v179
	v_cvt_pk_f32_fp8_sdwa v[202:203], v179 src0_sel:WORD_1
	v_cndmask_b32_e32 v231, v220, v221, vcc
	v_pk_fma_f32 v[204:205], v[240:241], v[36:37], v[204:205]
	v_pk_fma_f32 v[206:207], v[242:243], v[38:39], v[206:207]
	v_pk_fma_f32 v[204:205], v[244:245], v[40:41], v[204:205]
	v_pk_fma_f32 v[206:207], v[202:203], v[42:43], v[206:207]
	v_readlane_b32 s0, v75, 42
	s_lshl_b32 s0, s0, 10
	s_add_u32 s4, s8, s0
	s_addc_u32 s5, s9, 0
	global_load_dwordx4 v[176:179], v16, s[4:5]
	v_pk_add_f32 v[204:205], v[204:205], v[206:207]
	s_nop 0
	v_add_f32_e32 v235, v204, v205
	s_waitcnt vmcnt(15)
; #define DPPF(v, ctrl) __builtin_bit_cast(float, __builtin_amdgcn_update_dpp(0, __builtin_bit_cast(int, (v)), (ctrl), 0xf, 0xf, true))
; DI float sum8(float v) { v += DPPF(v, 0xB1); v += DPPF(v, 0x4E); v += DPPF(v, 0x141); return v; }
; DI void topk_phase(const bf16_t* PROJ, const unsigned char* K8, const unsigned char* V8, const unsigned short* SC, bf16_t* ODSA, int c, char* smem, int bid, int nb) {
;     ...
;         const size_t ro = (size_t)__builtin_amdgcn_readlane(mysel, jj) * 1024 + lane * 16;
;         const uint4 a = *(const uint4*)(K8 + ro), vv = *(const uint4*)(V8 + ro);
;         const unsigned w[4] = {a.x, a.y, a.z, a.w}, u[4] = {vv.x, vv.y, vv.z, vv.w};
;         float da = 0.f;
; #pragma unroll
;         for (int i = 0; i < 4; ++i) {
;           const f32x2v lo = __builtin_amdgcn_cvt_pk_f32_fp8((int)w[i], false), hi = __builtin_amdgcn_cvt_pk_f32_fp8((int)w[i], true);
;           da += qv[4 * i] * lo[0] + qv[4 * i + 1] * lo[1] + qv[4 * i + 2] * hi[0] + qv[4 * i + 3] * hi[1];
;         }
;         da = sum8(da);
;         da = j < count ? da : -3e30f;
	v_cvt_pk_f32_fp8_e32 v[240:241], v180
	v_cvt_pk_f32_fp8_sdwa v[242:243], v180 src0_sel:WORD_1
	v_cvt_pk_f32_fp8_e32 v[244:245], v181
	v_cvt_pk_f32_fp8_sdwa v[202:203], v181 src0_sel:WORD_1
	v_add_f32_dpp v235, v235, v235 quad_perm:[1,0,3,2] row_mask:0xf bank_mask:0xf bound_ctrl:1
	v_pk_mul_f32 v[204:205], v[240:241], v[28:29]
	v_pk_mul_f32 v[206:207], v[242:243], v[30:31]
	v_add_f32_dpp v235, v235, v235 quad_perm:[2,3,0,1] row_mask:0xf bank_mask:0xf bound_ctrl:1
	v_cvt_pk_f32_fp8_e32 v[240:241], v182
	v_cvt_pk_f32_fp8_sdwa v[242:243], v182 src0_sel:WORD_1
	v_add_f32_dpp v235, v235, v235 row_half_mirror row_mask:0xf bank_mask:0xf bound_ctrl:1
	v_pk_fma_f32 v[204:205], v[244:245], v[32:33], v[204:205]
	v_pk_fma_f32 v[206:207], v[202:203], v[34:35], v[206:207]
	s_add_i32 s0, s1, 42
	s_cmp_lt_i32 s0, s2
	s_cselect_b64 vcc, -1, 0
	v_cvt_pk_f32_fp8_e32 v[244:245], v183
	v_cvt_pk_f32_fp8_sdwa v[202:203], v183 src0_sel:WORD_1
	v_cndmask_b32_e32 v232, v220, v235, vcc
	v_pk_fma_f32 v[204:205], v[240:241], v[36:37], v[204:205]
	v_pk_fma_f32 v[206:207], v[242:243], v[38:39], v[206:207]
	v_pk_fma_f32 v[204:205], v[244:245], v[40:41], v[204:205]
	v_pk_fma_f32 v[206:207], v[202:203], v[42:43], v[206:207]
	v_readlane_b32 s0, v75, 43
	s_lshl_b32 s0, s0, 10
	s_add_u32 s4, s8, s0
	s_addc_u32 s5, s9, 0
	global_load_dwordx4 v[180:183], v16, s[4:5]
	v_pk_add_f32 v[204:205], v[204:205], v[206:207]
	s_nop 0
	v_add_f32_e32 v221, v204, v205
	s_waitcnt vmcnt(15)
	v_cvt_pk_f32_fp8_e32 v[240:241], v186
	v_cvt_pk_f32_fp8_sdwa v[242:243], v186 src0_sel:WORD_1
	v_cvt_pk_f32_fp8_e32 v[244:245], v187
	v_cvt_pk_f32_fp8_sdwa v[202:203], v187 src0_sel:WORD_1
	v_add_f32_dpp v221, v221, v221 quad_perm:[1,0,3,2] row_mask:0xf bank_mask:0xf bound_ctrl:1
	v_pk_mul_f32 v[204:205], v[240:241], v[28:29]
	v_pk_mul_f32 v[206:207], v[242:243], v[30:31]
	v_add_f32_dpp v221, v221, v221 quad_perm:[2,3,0,1] row_mask:0xf bank_mask:0xf bound_ctrl:1
	v_cvt_pk_f32_fp8_e32 v[240:241], v188
	v_cvt_pk_f32_fp8_sdwa v[242:243], v188 src0_sel:WORD_1
	v_add_f32_dpp v221, v221, v221 row_half_mirror row_mask:0xf bank_mask:0xf bound_ctrl:1
	v_pk_fma_f32 v[204:205], v[244:245], v[32:33], v[204:205]
	v_pk_fma_f32 v[206:207], v[202:203], v[34:35], v[206:207]
	s_add_i32 s0, s1, 43
	s_cmp_lt_i32 s0, s2
	s_cselect_b64 vcc, -1, 0
	v_cvt_pk_f32_fp8_e32 v[244:245], v189
	v_cvt_pk_f32_fp8_sdwa v[202:203], v189 src0_sel:WORD_1
	v_cndmask_b32_e32 v233, v220, v221, vcc
	v_pk_fma_f32 v[204:205], v[240:241], v[36:37], v[204:205]
	v_pk_fma_f32 v[206:207], v[242:243], v[38:39], v[206:207]
	v_pk_fma_f32 v[204:205], v[244:245], v[40:41], v[204:205]
	v_pk_fma_f32 v[206:207], v[202:203], v[42:43], v[206:207]
	v_readlane_b32 s0, v75, 44
	s_lshl_b32 s0, s0, 10
	s_add_u32 s4, s8, s0
	s_addc_u32 s5, s9, 0
	global_load_dwordx4 v[186:189], v16, s[4:5]
	v_pk_add_f32 v[204:205], v[204:205], v[206:207]
	s_nop 0
	v_add_f32_e32 v235, v204, v205
	s_waitcnt vmcnt(15)
	v_cvt_pk_f32_fp8_e32 v[240:241], v190
	v_cvt_pk_f32_fp8_sdwa v[242:243], v190 src0_sel:WORD_1
	v_cvt_pk_f32_fp8_e32 v[244:245], v191
	v_cvt_pk_f32_fp8_sdwa v[202:203], v191 src0_sel:WORD_1
	v_add_f32_dpp v235, v235, v235 quad_perm:[1,0,3,2] row_mask:0xf bank_mask:0xf bound_ctrl:1
	v_pk_mul_f32 v[204:205], v[240:241], v[28:29]
	v_pk_mul_f32 v[206:207], v[242:243], v[30:31]
	v_add_f32_dpp v235, v235, v235 quad_perm:[2,3,0,1] row_mask:0xf bank_mask:0xf bound_ctrl:1
	v_cvt_pk_f32_fp8_e32 v[240:241], v192
	v_cvt_pk_f32_fp8_sdwa v[242:243], v192 src0_sel:WORD_1
	v_add_f32_dpp v235, v235, v235 row_half_mirror row_mask:0xf bank_mask:0xf bound_ctrl:1
	v_pk_fma_f32 v[204:205], v[244:245], v[32:33], v[204:205]
	v_pk_fma_f32 v[206:207], v[202:203], v[34:35], v[206:207]
	s_add_i32 s0, s1, 44
	s_cmp_lt_i32 s0, s2
	s_cselect_b64 vcc, -1, 0
	v_cvt_pk_f32_fp8_e32 v[244:245], v193
	v_cvt_pk_f32_fp8_sdwa v[202:203], v193 src0_sel:WORD_1
	v_cndmask_b32_e32 v236, v220, v235, vcc
	v_pk_fma_f32 v[204:205], v[240:241], v[36:37], v[204:205]
	v_pk_fma_f32 v[206:207], v[242:243], v[38:39], v[206:207]
	v_pk_fma_f32 v[204:205], v[244:245], v[40:41], v[204:205]
	v_pk_fma_f32 v[206:207], v[202:203], v[42:43], v[206:207]
	v_readlane_b32 s0, v75, 45
	s_lshl_b32 s0, s0, 10
	s_add_u32 s4, s8, s0
	s_addc_u32 s5, s9, 0
	global_load_dwordx4 v[190:193], v16, s[4:5]
	v_pk_add_f32 v[204:205], v[204:205], v[206:207]
	s_nop 0
	v_add_f32_e32 v221, v204, v205
	s_waitcnt vmcnt(15)
	v_cvt_pk_f32_fp8_e32 v[240:241], v194
	v_cvt_pk_f32_fp8_sdwa v[242:243], v194 src0_sel:WORD_1
	v_cvt_pk_f32_fp8_e32 v[244:245], v195
	v_cvt_pk_f32_fp8_sdwa v[202:203], v195 src0_sel:WORD_1
	v_add_f32_dpp v221, v221, v221 quad_perm:[1,0,3,2] row_mask:0xf bank_mask:0xf bound_ctrl:1
	v_pk_mul_f32 v[204:205], v[240:241], v[28:29]
	v_pk_mul_f32 v[206:207], v[242:243], v[30:31]
	v_add_f32_dpp v221, v221, v221 quad_perm:[2,3,0,1] row_mask:0xf bank_mask:0xf bound_ctrl:1
	v_cvt_pk_f32_fp8_e32 v[240:241], v196
	v_cvt_pk_f32_fp8_sdwa v[242:243], v196 src0_sel:WORD_1
	v_add_f32_dpp v221, v221, v221 row_half_mirror row_mask:0xf bank_mask:0xf bound_ctrl:1
	v_pk_fma_f32 v[204:205], v[244:245], v[32:33], v[204:205]
	v_pk_fma_f32 v[206:207], v[202:203], v[34:35], v[206:207]
	s_add_i32 s0, s1, 45
	s_cmp_lt_i32 s0, s2
	s_cselect_b64 vcc, -1, 0
	v_cvt_pk_f32_fp8_e32 v[244:245], v197
	v_cvt_pk_f32_fp8_sdwa v[202:203], v197 src0_sel:WORD_1
	v_cndmask_b32_e32 v237, v220, v221, vcc
	v_pk_fma_f32 v[204:205], v[240:241], v[36:37], v[204:205]
	v_pk_fma_f32 v[206:207], v[242:243], v[38:39], v[206:207]
	v_pk_fma_f32 v[204:205], v[244:245], v[40:41], v[204:205]
	v_pk_fma_f32 v[206:207], v[202:203], v[42:43], v[206:207]
	v_readlane_b32 s0, v75, 46
	s_lshl_b32 s0, s0, 10
	s_add_u32 s4, s8, s0
	s_addc_u32 s5, s9, 0
	global_load_dwordx4 v[194:197], v16, s[4:5]
	v_pk_add_f32 v[204:205], v[204:205], v[206:207]
	s_nop 0
	v_add_f32_e32 v235, v204, v205
	s_waitcnt vmcnt(15)
; #define DPPF(v, ctrl) __builtin_bit_cast(float, __builtin_amdgcn_update_dpp(0, __builtin_bit_cast(int, (v)), (ctrl), 0xf, 0xf, true))
; DI float sum8(float v) { v += DPPF(v, 0xB1); v += DPPF(v, 0x4E); v += DPPF(v, 0x141); return v; }
; DI void topk_phase(const bf16_t* PROJ, const unsigned char* K8, const unsigned char* V8, const unsigned short* SC, bf16_t* ODSA, int c, char* smem, int bid, int nb) {
;     ...
;         const size_t ro = (size_t)__builtin_amdgcn_readlane(mysel, jj) * 1024 + lane * 16;
;         const uint4 a = *(const uint4*)(K8 + ro), vv = *(const uint4*)(V8 + ro);
;         const unsigned w[4] = {a.x, a.y, a.z, a.w}, u[4] = {vv.x, vv.y, vv.z, vv.w};
;         float da = 0.f;
; #pragma unroll
;         for (int i = 0; i < 4; ++i) {
;           const f32x2v lo = __builtin_amdgcn_cvt_pk_f32_fp8((int)w[i], false), hi = __builtin_amdgcn_cvt_pk_f32_fp8((int)w[i], true);
;           da += qv[4 * i] * lo[0] + qv[4 * i + 1] * lo[1] + qv[4 * i + 2] * hi[0] + qv[4 * i + 3] * hi[1];
;         }
;         da = sum8(da);
;         da = j < count ? da : -3e30f;
;         const float mn = fmaxf(m_run, da), al = __builtin_amdgcn_exp2f(m_run - mn), pp = __builtin_amdgcn_exp2f(da - mn);
;         m_run = mn; l_run = l_run * al + pp;
; #pragma unroll
;         for (int i = 0; i < 4; ++i) {
;           const f32x2v lo = __builtin_amdgcn_cvt_pk_f32_fp8((int)u[i], false), hi = __builtin_amdgcn_cvt_pk_f32_fp8((int)u[i], true);
;           ov[4 * i] = ov[4 * i] * al + pp * lo[0]; ov[4 * i + 1] = ov[4 * i + 1] * al + pp * lo[1];
;           ov[4 * i + 2] = ov[4 * i + 2] * al + pp * hi[0]; ov[4 * i + 3] = ov[4 * i + 3] * al + pp * hi[1];
;         }
	v_cvt_pk_f32_fp8_e32 v[240:241], v198
	v_cvt_pk_f32_fp8_sdwa v[242:243], v198 src0_sel:WORD_1
	v_cvt_pk_f32_fp8_e32 v[244:245], v199
	v_cvt_pk_f32_fp8_sdwa v[202:203], v199 src0_sel:WORD_1
	v_add_f32_dpp v235, v235, v235 quad_perm:[1,0,3,2] row_mask:0xf bank_mask:0xf bound_ctrl:1
	v_pk_mul_f32 v[204:205], v[240:241], v[28:29]
	v_pk_mul_f32 v[206:207], v[242:243], v[30:31]
	v_add_f32_dpp v235, v235, v235 quad_perm:[2,3,0,1] row_mask:0xf bank_mask:0xf bound_ctrl:1
	v_cvt_pk_f32_fp8_e32 v[240:241], v200
	v_cvt_pk_f32_fp8_sdwa v[242:243], v200 src0_sel:WORD_1
	v_add_f32_dpp v235, v235, v235 row_half_mirror row_mask:0xf bank_mask:0xf bound_ctrl:1
	v_pk_fma_f32 v[204:205], v[244:245], v[32:33], v[204:205]
	v_pk_fma_f32 v[206:207], v[202:203], v[34:35], v[206:207]
	s_add_i32 s0, s1, 46
	s_cmp_lt_i32 s0, s2
	s_cselect_b64 vcc, -1, 0
	v_cvt_pk_f32_fp8_e32 v[244:245], v201
	v_cvt_pk_f32_fp8_sdwa v[202:203], v201 src0_sel:WORD_1
	v_cndmask_b32_e32 v238, v220, v235, vcc
	v_pk_fma_f32 v[204:205], v[240:241], v[36:37], v[204:205]
	v_pk_fma_f32 v[206:207], v[242:243], v[38:39], v[206:207]
	v_pk_fma_f32 v[204:205], v[244:245], v[40:41], v[204:205]
	v_pk_fma_f32 v[206:207], v[202:203], v[42:43], v[206:207]
	v_readlane_b32 s0, v75, 47
	s_lshl_b32 s0, s0, 10
	s_add_u32 s4, s8, s0
	s_addc_u32 s5, s9, 0
	global_load_dwordx4 v[198:201], v16, s[4:5]
	v_pk_add_f32 v[204:205], v[204:205], v[206:207]
	s_nop 0
	v_add_f32_e32 v221, v204, v205
	s_nop 1
	v_add_f32_dpp v221, v221, v221 quad_perm:[1,0,3,2] row_mask:0xf bank_mask:0xf bound_ctrl:1
	s_nop 1
	v_add_f32_dpp v221, v221, v221 quad_perm:[2,3,0,1] row_mask:0xf bank_mask:0xf bound_ctrl:1
	s_nop 1
	v_add_f32_dpp v221, v221, v221 row_half_mirror row_mask:0xf bank_mask:0xf bound_ctrl:1
	s_add_i32 s0, s1, 47
	s_cmp_lt_i32 s0, s2
	s_cselect_b64 vcc, -1, 0
	s_nop 1
	v_cndmask_b32_e32 v239, v220, v221, vcc
	v_max3_f32 v224, v210, v211, v212
	v_max3_f32 v224, v224, v213, v226
	v_max3_f32 v224, v224, v227, v228
	v_max3_f32 v224, v224, v229, v230
	v_max3_f32 v224, v224, v231, v232
	v_max3_f32 v224, v224, v233, v236
	v_max3_f32 v224, v224, v237, v238
	v_max_f32_e32 v224, v224, v239
	v_max_f32_e32 v221, v216, v224
	v_sub_f32_e32 v184, v216, v221
	v_exp_f32_e32 v184, v184
	v_mov_b32_e32 v216, v221
	s_nop 0
	v_pk_mul_f32 v[12:13], v[12:13], v[184:185] op_sel_hi:[1,0]
	v_pk_mul_f32 v[14:15], v[14:15], v[184:185] op_sel_hi:[1,0]
	v_pk_mul_f32 v[8:9], v[8:9], v[184:185] op_sel_hi:[1,0]
	v_pk_mul_f32 v[10:11], v[10:11], v[184:185] op_sel_hi:[1,0]
	v_pk_mul_f32 v[4:5], v[4:5], v[184:185] op_sel_hi:[1,0]
	v_pk_mul_f32 v[6:7], v[6:7], v[184:185] op_sel_hi:[1,0]
	v_pk_mul_f32 v[0:1], v[0:1], v[184:185] op_sel_hi:[1,0]
	v_pk_mul_f32 v[2:3], v[2:3], v[184:185] op_sel_hi:[1,0]
	v_mul_f32_e32 v215, v215, v184
	v_sub_f32_e32 v210, v210, v216
	v_exp_f32_e32 v210, v210
	s_waitcnt vmcnt(15)
	v_cvt_pk_f32_fp8_e32 v[240:241], v136
	v_cvt_pk_f32_fp8_sdwa v[242:243], v136 src0_sel:WORD_1
	v_cvt_pk_f32_fp8_e32 v[244:245], v137
	v_pk_fma_f32 v[12:13], v[240:241], v[210:211], v[12:13] op_sel_hi:[1,0,1]
	v_cvt_pk_f32_fp8_sdwa v[240:241], v137 src0_sel:WORD_1
	v_pk_fma_f32 v[14:15], v[242:243], v[210:211], v[14:15] op_sel_hi:[1,0,1]
	v_cvt_pk_f32_fp8_e32 v[242:243], v138
	v_sub_f32_e32 v211, v211, v216
	v_pk_fma_f32 v[8:9], v[244:245], v[210:211], v[8:9] op_sel_hi:[1,0,1]
	v_cvt_pk_f32_fp8_sdwa v[244:245], v138 src0_sel:WORD_1
	v_pk_fma_f32 v[10:11], v[240:241], v[210:211], v[10:11] op_sel_hi:[1,0,1]
	v_cvt_pk_f32_fp8_e32 v[240:241], v139
	v_exp_f32_e32 v211, v211
	v_pk_fma_f32 v[4:5], v[242:243], v[210:211], v[4:5] op_sel_hi:[1,0,1]
	v_cvt_pk_f32_fp8_sdwa v[242:243], v139 src0_sel:WORD_1
	v_pk_fma_f32 v[6:7], v[244:245], v[210:211], v[6:7] op_sel_hi:[1,0,1]
	v_add_f32_e32 v215, v215, v210
	v_pk_fma_f32 v[0:1], v[240:241], v[210:211], v[0:1] op_sel_hi:[1,0,1]
	v_pk_fma_f32 v[2:3], v[242:243], v[210:211], v[2:3] op_sel_hi:[1,0,1]
	v_readlane_b32 s0, v75, 48
	s_lshl_b32 s0, s0, 10
	s_add_u32 s4, s6, s0
	s_addc_u32 s5, s7, 0
	global_load_dwordx4 v[136:139], v16, s[4:5]
	s_waitcnt vmcnt(15)
	v_cvt_pk_f32_fp8_e32 v[240:241], v140
	v_cvt_pk_f32_fp8_sdwa v[242:243], v140 src0_sel:WORD_1
	v_cvt_pk_f32_fp8_e32 v[244:245], v141
	v_pk_fma_f32 v[12:13], v[240:241], v[210:211], v[12:13] op_sel:[0,1,0]
	v_cvt_pk_f32_fp8_sdwa v[240:241], v141 src0_sel:WORD_1
	v_pk_fma_f32 v[14:15], v[242:243], v[210:211], v[14:15] op_sel:[0,1,0]
	v_cvt_pk_f32_fp8_e32 v[242:243], v142
	v_sub_f32_e32 v212, v212, v216
	v_pk_fma_f32 v[8:9], v[244:245], v[210:211], v[8:9] op_sel:[0,1,0]
	v_cvt_pk_f32_fp8_sdwa v[244:245], v142 src0_sel:WORD_1
	v_pk_fma_f32 v[10:11], v[240:241], v[210:211], v[10:11] op_sel:[0,1,0]
	v_cvt_pk_f32_fp8_e32 v[240:241], v143
	v_exp_f32_e32 v212, v212
	v_pk_fma_f32 v[4:5], v[242:243], v[210:211], v[4:5] op_sel:[0,1,0]
	v_cvt_pk_f32_fp8_sdwa v[242:243], v143 src0_sel:WORD_1
	v_pk_fma_f32 v[6:7], v[244:245], v[210:211], v[6:7] op_sel:[0,1,0]
	v_add_f32_e32 v215, v215, v211
	v_pk_fma_f32 v[0:1], v[240:241], v[210:211], v[0:1] op_sel:[0,1,0]
	v_pk_fma_f32 v[2:3], v[242:243], v[210:211], v[2:3] op_sel:[0,1,0]
	v_readlane_b32 s0, v75, 49
	s_lshl_b32 s0, s0, 10
	s_add_u32 s4, s6, s0
	s_addc_u32 s5, s7, 0
	global_load_dwordx4 v[140:143], v16, s[4:5]
	s_waitcnt vmcnt(15)
; DI void topk_phase(const bf16_t* PROJ, const unsigned char* K8, const unsigned char* V8, const unsigned short* SC, bf16_t* ODSA, int c, char* smem, int bid, int nb) {
;     ...
;         const float mn = fmaxf(m_run, da), al = __builtin_amdgcn_exp2f(m_run - mn), pp = __builtin_amdgcn_exp2f(da - mn);
;         m_run = mn; l_run = l_run * al + pp;
; #pragma unroll
;         for (int i = 0; i < 4; ++i) {
;           const f32x2v lo = __builtin_amdgcn_cvt_pk_f32_fp8((int)u[i], false), hi = __builtin_amdgcn_cvt_pk_f32_fp8((int)u[i], true);
;           ov[4 * i] = ov[4 * i] * al + pp * lo[0]; ov[4 * i + 1] = ov[4 * i + 1] * al + pp * lo[1];
;           ov[4 * i + 2] = ov[4 * i + 2] * al + pp * hi[0]; ov[4 * i + 3] = ov[4 * i + 3] * al + pp * hi[1];
;         }
	v_cvt_pk_f32_fp8_e32 v[240:241], v144
	v_cvt_pk_f32_fp8_sdwa v[242:243], v144 src0_sel:WORD_1
	v_cvt_pk_f32_fp8_e32 v[244:245], v145
	v_pk_fma_f32 v[12:13], v[240:241], v[212:213], v[12:13] op_sel_hi:[1,0,1]
	v_cvt_pk_f32_fp8_sdwa v[240:241], v145 src0_sel:WORD_1
	v_pk_fma_f32 v[14:15], v[242:243], v[212:213], v[14:15] op_sel_hi:[1,0,1]
	v_cvt_pk_f32_fp8_e32 v[242:243], v146
	v_sub_f32_e32 v213, v213, v216
	v_pk_fma_f32 v[8:9], v[244:245], v[212:213], v[8:9] op_sel_hi:[1,0,1]
	v_cvt_pk_f32_fp8_sdwa v[244:245], v146 src0_sel:WORD_1
	v_pk_fma_f32 v[10:11], v[240:241], v[212:213], v[10:11] op_sel_hi:[1,0,1]
	v_cvt_pk_f32_fp8_e32 v[240:241], v147
	v_exp_f32_e32 v213, v213
	v_pk_fma_f32 v[4:5], v[242:243], v[212:213], v[4:5] op_sel_hi:[1,0,1]
	v_cvt_pk_f32_fp8_sdwa v[242:243], v147 src0_sel:WORD_1
	v_pk_fma_f32 v[6:7], v[244:245], v[212:213], v[6:7] op_sel_hi:[1,0,1]
	v_add_f32_e32 v215, v215, v212
	v_pk_fma_f32 v[0:1], v[240:241], v[212:213], v[0:1] op_sel_hi:[1,0,1]
	v_pk_fma_f32 v[2:3], v[242:243], v[212:213], v[2:3] op_sel_hi:[1,0,1]
	v_readlane_b32 s0, v75, 50
	s_lshl_b32 s0, s0, 10
	s_add_u32 s4, s6, s0
	s_addc_u32 s5, s7, 0
	global_load_dwordx4 v[144:147], v16, s[4:5]
	s_waitcnt vmcnt(15)
	v_cvt_pk_f32_fp8_e32 v[240:241], v148
	v_cvt_pk_f32_fp8_sdwa v[242:243], v148 src0_sel:WORD_1
	v_cvt_pk_f32_fp8_e32 v[244:245], v149
	v_pk_fma_f32 v[12:13], v[240:241], v[212:213], v[12:13] op_sel:[0,1,0]
	v_cvt_pk_f32_fp8_sdwa v[240:241], v149 src0_sel:WORD_1
	v_pk_fma_f32 v[14:15], v[242:243], v[212:213], v[14:15] op_sel:[0,1,0]
	v_cvt_pk_f32_fp8_e32 v[242:243], v150
	v_sub_f32_e32 v226, v226, v216
	v_pk_fma_f32 v[8:9], v[244:245], v[212:213], v[8:9] op_sel:[0,1,0]
	v_cvt_pk_f32_fp8_sdwa v[244:245], v150 src0_sel:WORD_1
	v_pk_fma_f32 v[10:11], v[240:241], v[212:213], v[10:11] op_sel:[0,1,0]
	v_cvt_pk_f32_fp8_e32 v[240:241], v151
	v_exp_f32_e32 v226, v226
	v_pk_fma_f32 v[4:5], v[242:243], v[212:213], v[4:5] op_sel:[0,1,0]
	v_cvt_pk_f32_fp8_sdwa v[242:243], v151 src0_sel:WORD_1
	v_pk_fma_f32 v[6:7], v[244:245], v[212:213], v[6:7] op_sel:[0,1,0]
	v_add_f32_e32 v215, v215, v213
	v_pk_fma_f32 v[0:1], v[240:241], v[212:213], v[0:1] op_sel:[0,1,0]
	v_pk_fma_f32 v[2:3], v[242:243], v[212:213], v[2:3] op_sel:[0,1,0]
	v_readlane_b32 s0, v75, 51
	s_lshl_b32 s0, s0, 10
	s_add_u32 s4, s6, s0
	s_addc_u32 s5, s7, 0
	global_load_dwordx4 v[148:151], v16, s[4:5]
	s_waitcnt vmcnt(15)
	v_cvt_pk_f32_fp8_e32 v[240:241], v152
	v_cvt_pk_f32_fp8_sdwa v[242:243], v152 src0_sel:WORD_1
	v_cvt_pk_f32_fp8_e32 v[244:245], v153
	v_pk_fma_f32 v[12:13], v[240:241], v[226:227], v[12:13] op_sel_hi:[1,0,1]
	v_cvt_pk_f32_fp8_sdwa v[240:241], v153 src0_sel:WORD_1
	v_pk_fma_f32 v[14:15], v[242:243], v[226:227], v[14:15] op_sel_hi:[1,0,1]
	v_cvt_pk_f32_fp8_e32 v[242:243], v154
	v_sub_f32_e32 v227, v227, v216
	v_pk_fma_f32 v[8:9], v[244:245], v[226:227], v[8:9] op_sel_hi:[1,0,1]
	v_cvt_pk_f32_fp8_sdwa v[244:245], v154 src0_sel:WORD_1
	v_pk_fma_f32 v[10:11], v[240:241], v[226:227], v[10:11] op_sel_hi:[1,0,1]
	v_cvt_pk_f32_fp8_e32 v[240:241], v155
	v_exp_f32_e32 v227, v227
	v_pk_fma_f32 v[4:5], v[242:243], v[226:227], v[4:5] op_sel_hi:[1,0,1]
	v_cvt_pk_f32_fp8_sdwa v[242:243], v155 src0_sel:WORD_1
	v_pk_fma_f32 v[6:7], v[244:245], v[226:227], v[6:7] op_sel_hi:[1,0,1]
	v_add_f32_e32 v215, v215, v226
	v_pk_fma_f32 v[0:1], v[240:241], v[226:227], v[0:1] op_sel_hi:[1,0,1]
	v_pk_fma_f32 v[2:3], v[242:243], v[226:227], v[2:3] op_sel_hi:[1,0,1]
	v_readlane_b32 s0, v75, 52
	s_lshl_b32 s0, s0, 10
	s_add_u32 s4, s6, s0
	s_addc_u32 s5, s7, 0
	global_load_dwordx4 v[152:155], v16, s[4:5]
	s_waitcnt vmcnt(15)
	v_cvt_pk_f32_fp8_e32 v[240:241], v156
	v_cvt_pk_f32_fp8_sdwa v[242:243], v156 src0_sel:WORD_1
	v_cvt_pk_f32_fp8_e32 v[244:245], v157
	v_pk_fma_f32 v[12:13], v[240:241], v[226:227], v[12:13] op_sel:[0,1,0]
	v_cvt_pk_f32_fp8_sdwa v[240:241], v157 src0_sel:WORD_1
	v_pk_fma_f32 v[14:15], v[242:243], v[226:227], v[14:15] op_sel:[0,1,0]
	v_cvt_pk_f32_fp8_e32 v[242:243], v158
	v_sub_f32_e32 v228, v228, v216
	v_pk_fma_f32 v[8:9], v[244:245], v[226:227], v[8:9] op_sel:[0,1,0]
	v_cvt_pk_f32_fp8_sdwa v[244:245], v158 src0_sel:WORD_1
	v_pk_fma_f32 v[10:11], v[240:241], v[226:227], v[10:11] op_sel:[0,1,0]
	v_cvt_pk_f32_fp8_e32 v[240:241], v159
	v_exp_f32_e32 v228, v228
	v_pk_fma_f32 v[4:5], v[242:243], v[226:227], v[4:5] op_sel:[0,1,0]
	v_cvt_pk_f32_fp8_sdwa v[242:243], v159 src0_sel:WORD_1
	v_pk_fma_f32 v[6:7], v[244:245], v[226:227], v[6:7] op_sel:[0,1,0]
	v_add_f32_e32 v215, v215, v227
	v_pk_fma_f32 v[0:1], v[240:241], v[226:227], v[0:1] op_sel:[0,1,0]
	v_pk_fma_f32 v[2:3], v[242:243], v[226:227], v[2:3] op_sel:[0,1,0]
	v_readlane_b32 s0, v75, 53
	s_lshl_b32 s0, s0, 10
	s_add_u32 s4, s6, s0
	s_addc_u32 s5, s7, 0
	global_load_dwordx4 v[156:159], v16, s[4:5]
	s_waitcnt vmcnt(15)
	v_cvt_pk_f32_fp8_e32 v[240:241], v160
	v_cvt_pk_f32_fp8_sdwa v[242:243], v160 src0_sel:WORD_1
	v_cvt_pk_f32_fp8_e32 v[244:245], v161
	v_pk_fma_f32 v[12:13], v[240:241], v[228:229], v[12:13] op_sel_hi:[1,0,1]
	v_cvt_pk_f32_fp8_sdwa v[240:241], v161 src0_sel:WORD_1
	v_pk_fma_f32 v[14:15], v[242:243], v[228:229], v[14:15] op_sel_hi:[1,0,1]
	v_cvt_pk_f32_fp8_e32 v[242:243], v162
	v_sub_f32_e32 v229, v229, v216
	v_pk_fma_f32 v[8:9], v[244:245], v[228:229], v[8:9] op_sel_hi:[1,0,1]
	v_cvt_pk_f32_fp8_sdwa v[244:245], v162 src0_sel:WORD_1
	v_pk_fma_f32 v[10:11], v[240:241], v[228:229], v[10:11] op_sel_hi:[1,0,1]
	v_cvt_pk_f32_fp8_e32 v[240:241], v163
	v_exp_f32_e32 v229, v229
	v_pk_fma_f32 v[4:5], v[242:243], v[228:229], v[4:5] op_sel_hi:[1,0,1]
	v_cvt_pk_f32_fp8_sdwa v[242:243], v163 src0_sel:WORD_1
	v_pk_fma_f32 v[6:7], v[244:245], v[228:229], v[6:7] op_sel_hi:[1,0,1]
	v_add_f32_e32 v215, v215, v228
	v_pk_fma_f32 v[0:1], v[240:241], v[228:229], v[0:1] op_sel_hi:[1,0,1]
	v_pk_fma_f32 v[2:3], v[242:243], v[228:229], v[2:3] op_sel_hi:[1,0,1]
	v_readlane_b32 s0, v75, 54
	s_lshl_b32 s0, s0, 10
	s_add_u32 s4, s6, s0
	s_addc_u32 s5, s7, 0
	global_load_dwordx4 v[160:163], v16, s[4:5]
	s_waitcnt vmcnt(15)
; DI void topk_phase(const bf16_t* PROJ, const unsigned char* K8, const unsigned char* V8, const unsigned short* SC, bf16_t* ODSA, int c, char* smem, int bid, int nb) {
;     ...
;         const float mn = fmaxf(m_run, da), al = __builtin_amdgcn_exp2f(m_run - mn), pp = __builtin_amdgcn_exp2f(da - mn);
;         m_run = mn; l_run = l_run * al + pp;
; #pragma unroll
;         for (int i = 0; i < 4; ++i) {
;           const f32x2v lo = __builtin_amdgcn_cvt_pk_f32_fp8((int)u[i], false), hi = __builtin_amdgcn_cvt_pk_f32_fp8((int)u[i], true);
;           ov[4 * i] = ov[4 * i] * al + pp * lo[0]; ov[4 * i + 1] = ov[4 * i + 1] * al + pp * lo[1];
;           ov[4 * i + 2] = ov[4 * i + 2] * al + pp * hi[0]; ov[4 * i + 3] = ov[4 * i + 3] * al + pp * hi[1];
;         }
	v_cvt_pk_f32_fp8_e32 v[240:241], v164
	v_cvt_pk_f32_fp8_sdwa v[242:243], v164 src0_sel:WORD_1
	v_cvt_pk_f32_fp8_e32 v[244:245], v165
	v_pk_fma_f32 v[12:13], v[240:241], v[228:229], v[12:13] op_sel:[0,1,0]
	v_cvt_pk_f32_fp8_sdwa v[240:241], v165 src0_sel:WORD_1
	v_pk_fma_f32 v[14:15], v[242:243], v[228:229], v[14:15] op_sel:[0,1,0]
	v_cvt_pk_f32_fp8_e32 v[242:243], v166
	v_sub_f32_e32 v230, v230, v216
	v_pk_fma_f32 v[8:9], v[244:245], v[228:229], v[8:9] op_sel:[0,1,0]
	v_cvt_pk_f32_fp8_sdwa v[244:245], v166 src0_sel:WORD_1
	v_pk_fma_f32 v[10:11], v[240:241], v[228:229], v[10:11] op_sel:[0,1,0]
	v_cvt_pk_f32_fp8_e32 v[240:241], v167
	v_exp_f32_e32 v230, v230
	v_pk_fma_f32 v[4:5], v[242:243], v[228:229], v[4:5] op_sel:[0,1,0]
	v_cvt_pk_f32_fp8_sdwa v[242:243], v167 src0_sel:WORD_1
	v_pk_fma_f32 v[6:7], v[244:245], v[228:229], v[6:7] op_sel:[0,1,0]
	v_add_f32_e32 v215, v215, v229
	v_pk_fma_f32 v[0:1], v[240:241], v[228:229], v[0:1] op_sel:[0,1,0]
	v_pk_fma_f32 v[2:3], v[242:243], v[228:229], v[2:3] op_sel:[0,1,0]
	v_readlane_b32 s0, v75, 55
	s_lshl_b32 s0, s0, 10
	s_add_u32 s4, s6, s0
	s_addc_u32 s5, s7, 0
	global_load_dwordx4 v[164:167], v16, s[4:5]
	s_waitcnt vmcnt(15)
	v_cvt_pk_f32_fp8_e32 v[240:241], v168
	v_cvt_pk_f32_fp8_sdwa v[242:243], v168 src0_sel:WORD_1
	v_cvt_pk_f32_fp8_e32 v[244:245], v169
	v_pk_fma_f32 v[12:13], v[240:241], v[230:231], v[12:13] op_sel_hi:[1,0,1]
	v_cvt_pk_f32_fp8_sdwa v[240:241], v169 src0_sel:WORD_1
	v_pk_fma_f32 v[14:15], v[242:243], v[230:231], v[14:15] op_sel_hi:[1,0,1]
	v_cvt_pk_f32_fp8_e32 v[242:243], v170
	v_sub_f32_e32 v231, v231, v216
	v_pk_fma_f32 v[8:9], v[244:245], v[230:231], v[8:9] op_sel_hi:[1,0,1]
	v_cvt_pk_f32_fp8_sdwa v[244:245], v170 src0_sel:WORD_1
	v_pk_fma_f32 v[10:11], v[240:241], v[230:231], v[10:11] op_sel_hi:[1,0,1]
	v_cvt_pk_f32_fp8_e32 v[240:241], v171
	v_exp_f32_e32 v231, v231
	v_pk_fma_f32 v[4:5], v[242:243], v[230:231], v[4:5] op_sel_hi:[1,0,1]
	v_cvt_pk_f32_fp8_sdwa v[242:243], v171 src0_sel:WORD_1
	v_pk_fma_f32 v[6:7], v[244:245], v[230:231], v[6:7] op_sel_hi:[1,0,1]
	v_add_f32_e32 v215, v215, v230
	v_pk_fma_f32 v[0:1], v[240:241], v[230:231], v[0:1] op_sel_hi:[1,0,1]
	v_pk_fma_f32 v[2:3], v[242:243], v[230:231], v[2:3] op_sel_hi:[1,0,1]
	v_readlane_b32 s0, v75, 56
	s_lshl_b32 s0, s0, 10
	s_add_u32 s4, s6, s0
	s_addc_u32 s5, s7, 0
	global_load_dwordx4 v[168:171], v16, s[4:5]
	s_waitcnt vmcnt(15)
	v_cvt_pk_f32_fp8_e32 v[240:241], v172
	v_cvt_pk_f32_fp8_sdwa v[242:243], v172 src0_sel:WORD_1
	v_cvt_pk_f32_fp8_e32 v[244:245], v173
	v_pk_fma_f32 v[12:13], v[240:241], v[230:231], v[12:13] op_sel:[0,1,0]
	v_cvt_pk_f32_fp8_sdwa v[240:241], v173 src0_sel:WORD_1
	v_pk_fma_f32 v[14:15], v[242:243], v[230:231], v[14:15] op_sel:[0,1,0]
	v_cvt_pk_f32_fp8_e32 v[242:243], v174
	v_sub_f32_e32 v232, v232, v216
	v_pk_fma_f32 v[8:9], v[244:245], v[230:231], v[8:9] op_sel:[0,1,0]
	v_cvt_pk_f32_fp8_sdwa v[244:245], v174 src0_sel:WORD_1
	v_pk_fma_f32 v[10:11], v[240:241], v[230:231], v[10:11] op_sel:[0,1,0]
	v_cvt_pk_f32_fp8_e32 v[240:241], v175
	v_exp_f32_e32 v232, v232
	v_pk_fma_f32 v[4:5], v[242:243], v[230:231], v[4:5] op_sel:[0,1,0]
	v_cvt_pk_f32_fp8_sdwa v[242:243], v175 src0_sel:WORD_1
	v_pk_fma_f32 v[6:7], v[244:245], v[230:231], v[6:7] op_sel:[0,1,0]
	v_add_f32_e32 v215, v215, v231
	v_pk_fma_f32 v[0:1], v[240:241], v[230:231], v[0:1] op_sel:[0,1,0]
	v_pk_fma_f32 v[2:3], v[242:243], v[230:231], v[2:3] op_sel:[0,1,0]
	v_readlane_b32 s0, v75, 57
	s_lshl_b32 s0, s0, 10
	s_add_u32 s4, s6, s0
	s_addc_u32 s5, s7, 0
	global_load_dwordx4 v[172:175], v16, s[4:5]
	s_waitcnt vmcnt(15)
	v_cvt_pk_f32_fp8_e32 v[240:241], v176
	v_cvt_pk_f32_fp8_sdwa v[242:243], v176 src0_sel:WORD_1
	v_cvt_pk_f32_fp8_e32 v[244:245], v177
	v_pk_fma_f32 v[12:13], v[240:241], v[232:233], v[12:13] op_sel_hi:[1,0,1]
	v_cvt_pk_f32_fp8_sdwa v[240:241], v177 src0_sel:WORD_1
	v_pk_fma_f32 v[14:15], v[242:243], v[232:233], v[14:15] op_sel_hi:[1,0,1]
	v_cvt_pk_f32_fp8_e32 v[242:243], v178
	v_sub_f32_e32 v233, v233, v216
	v_pk_fma_f32 v[8:9], v[244:245], v[232:233], v[8:9] op_sel_hi:[1,0,1]
	v_cvt_pk_f32_fp8_sdwa v[244:245], v178 src0_sel:WORD_1
	v_pk_fma_f32 v[10:11], v[240:241], v[232:233], v[10:11] op_sel_hi:[1,0,1]
	v_cvt_pk_f32_fp8_e32 v[240:241], v179
	v_exp_f32_e32 v233, v233
	v_pk_fma_f32 v[4:5], v[242:243], v[232:233], v[4:5] op_sel_hi:[1,0,1]
	v_cvt_pk_f32_fp8_sdwa v[242:243], v179 src0_sel:WORD_1
	v_pk_fma_f32 v[6:7], v[244:245], v[232:233], v[6:7] op_sel_hi:[1,0,1]
	v_add_f32_e32 v215, v215, v232
	v_pk_fma_f32 v[0:1], v[240:241], v[232:233], v[0:1] op_sel_hi:[1,0,1]
	v_pk_fma_f32 v[2:3], v[242:243], v[232:233], v[2:3] op_sel_hi:[1,0,1]
	v_readlane_b32 s0, v75, 58
	s_lshl_b32 s0, s0, 10
	s_add_u32 s4, s6, s0
	s_addc_u32 s5, s7, 0
	global_load_dwordx4 v[176:179], v16, s[4:5]
	s_waitcnt vmcnt(15)
	v_cvt_pk_f32_fp8_e32 v[240:241], v180
	v_cvt_pk_f32_fp8_sdwa v[242:243], v180 src0_sel:WORD_1
	v_cvt_pk_f32_fp8_e32 v[244:245], v181
	v_pk_fma_f32 v[12:13], v[240:241], v[232:233], v[12:13] op_sel:[0,1,0]
	v_cvt_pk_f32_fp8_sdwa v[240:241], v181 src0_sel:WORD_1
	v_pk_fma_f32 v[14:15], v[242:243], v[232:233], v[14:15] op_sel:[0,1,0]
	v_cvt_pk_f32_fp8_e32 v[242:243], v182
	v_sub_f32_e32 v236, v236, v216
	v_pk_fma_f32 v[8:9], v[244:245], v[232:233], v[8:9] op_sel:[0,1,0]
	v_cvt_pk_f32_fp8_sdwa v[244:245], v182 src0_sel:WORD_1
	v_pk_fma_f32 v[10:11], v[240:241], v[232:233], v[10:11] op_sel:[0,1,0]
	v_cvt_pk_f32_fp8_e32 v[240:241], v183
	v_exp_f32_e32 v236, v236
	v_pk_fma_f32 v[4:5], v[242:243], v[232:233], v[4:5] op_sel:[0,1,0]
	v_cvt_pk_f32_fp8_sdwa v[242:243], v183 src0_sel:WORD_1
	v_pk_fma_f32 v[6:7], v[244:245], v[232:233], v[6:7] op_sel:[0,1,0]
	v_add_f32_e32 v215, v215, v233
	v_pk_fma_f32 v[0:1], v[240:241], v[232:233], v[0:1] op_sel:[0,1,0]
	v_pk_fma_f32 v[2:3], v[242:243], v[232:233], v[2:3] op_sel:[0,1,0]
	v_readlane_b32 s0, v75, 59
	s_lshl_b32 s0, s0, 10
	s_add_u32 s4, s6, s0
	s_addc_u32 s5, s7, 0
	global_load_dwordx4 v[180:183], v16, s[4:5]
	s_waitcnt vmcnt(15)
; #define DPPF(v, ctrl) __builtin_bit_cast(float, __builtin_amdgcn_update_dpp(0, __builtin_bit_cast(int, (v)), (ctrl), 0xf, 0xf, true))
; DI float sum8(float v) { v += DPPF(v, 0xB1); v += DPPF(v, 0x4E); v += DPPF(v, 0x141); return v; }
; DI void topk_phase(const bf16_t* PROJ, const unsigned char* K8, const unsigned char* V8, const unsigned short* SC, bf16_t* ODSA, int c, char* smem, int bid, int nb) {
;     ...
;         const size_t ro = (size_t)__builtin_amdgcn_readlane(mysel, jj) * 1024 + lane * 16;
;         const uint4 a = *(const uint4*)(K8 + ro), vv = *(const uint4*)(V8 + ro);
;         const unsigned w[4] = {a.x, a.y, a.z, a.w}, u[4] = {vv.x, vv.y, vv.z, vv.w};
;         float da = 0.f;
; #pragma unroll
;         for (int i = 0; i < 4; ++i) {
;           const f32x2v lo = __builtin_amdgcn_cvt_pk_f32_fp8((int)w[i], false), hi = __builtin_amdgcn_cvt_pk_f32_fp8((int)w[i], true);
;           da += qv[4 * i] * lo[0] + qv[4 * i + 1] * lo[1] + qv[4 * i + 2] * hi[0] + qv[4 * i + 3] * hi[1];
;         }
;         da = sum8(da);
;         da = j < count ? da : -3e30f;
;         const float mn = fmaxf(m_run, da), al = __builtin_amdgcn_exp2f(m_run - mn), pp = __builtin_amdgcn_exp2f(da - mn);
;         m_run = mn; l_run = l_run * al + pp;
; #pragma unroll
;         for (int i = 0; i < 4; ++i) {
;           const f32x2v lo = __builtin_amdgcn_cvt_pk_f32_fp8((int)u[i], false), hi = __builtin_amdgcn_cvt_pk_f32_fp8((int)u[i], true);
;           ov[4 * i] = ov[4 * i] * al + pp * lo[0]; ov[4 * i + 1] = ov[4 * i + 1] * al + pp * lo[1];
;           ov[4 * i + 2] = ov[4 * i + 2] * al + pp * hi[0]; ov[4 * i + 3] = ov[4 * i + 3] * al + pp * hi[1];
;         }
	v_cvt_pk_f32_fp8_e32 v[240:241], v186
	v_cvt_pk_f32_fp8_sdwa v[242:243], v186 src0_sel:WORD_1
	v_cvt_pk_f32_fp8_e32 v[244:245], v187
	v_pk_fma_f32 v[12:13], v[240:241], v[236:237], v[12:13] op_sel_hi:[1,0,1]
	v_cvt_pk_f32_fp8_sdwa v[240:241], v187 src0_sel:WORD_1
	v_pk_fma_f32 v[14:15], v[242:243], v[236:237], v[14:15] op_sel_hi:[1,0,1]
	v_cvt_pk_f32_fp8_e32 v[242:243], v188
	v_sub_f32_e32 v237, v237, v216
	v_pk_fma_f32 v[8:9], v[244:245], v[236:237], v[8:9] op_sel_hi:[1,0,1]
	v_cvt_pk_f32_fp8_sdwa v[244:245], v188 src0_sel:WORD_1
	v_pk_fma_f32 v[10:11], v[240:241], v[236:237], v[10:11] op_sel_hi:[1,0,1]
	v_cvt_pk_f32_fp8_e32 v[240:241], v189
	v_exp_f32_e32 v237, v237
	v_pk_fma_f32 v[4:5], v[242:243], v[236:237], v[4:5] op_sel_hi:[1,0,1]
	v_cvt_pk_f32_fp8_sdwa v[242:243], v189 src0_sel:WORD_1
	v_pk_fma_f32 v[6:7], v[244:245], v[236:237], v[6:7] op_sel_hi:[1,0,1]
	v_add_f32_e32 v215, v215, v236
	v_pk_fma_f32 v[0:1], v[240:241], v[236:237], v[0:1] op_sel_hi:[1,0,1]
	v_pk_fma_f32 v[2:3], v[242:243], v[236:237], v[2:3] op_sel_hi:[1,0,1]
	v_readlane_b32 s0, v75, 60
	s_lshl_b32 s0, s0, 10
	s_add_u32 s4, s6, s0
	s_addc_u32 s5, s7, 0
	global_load_dwordx4 v[186:189], v16, s[4:5]
	s_waitcnt vmcnt(15)
	v_cvt_pk_f32_fp8_e32 v[240:241], v190
	v_cvt_pk_f32_fp8_sdwa v[242:243], v190 src0_sel:WORD_1
	v_cvt_pk_f32_fp8_e32 v[244:245], v191
	v_pk_fma_f32 v[12:13], v[240:241], v[236:237], v[12:13] op_sel:[0,1,0]
	v_cvt_pk_f32_fp8_sdwa v[240:241], v191 src0_sel:WORD_1
	v_pk_fma_f32 v[14:15], v[242:243], v[236:237], v[14:15] op_sel:[0,1,0]
	v_cvt_pk_f32_fp8_e32 v[242:243], v192
	v_sub_f32_e32 v238, v238, v216
	v_pk_fma_f32 v[8:9], v[244:245], v[236:237], v[8:9] op_sel:[0,1,0]
	v_cvt_pk_f32_fp8_sdwa v[244:245], v192 src0_sel:WORD_1
	v_pk_fma_f32 v[10:11], v[240:241], v[236:237], v[10:11] op_sel:[0,1,0]
	v_cvt_pk_f32_fp8_e32 v[240:241], v193
	v_exp_f32_e32 v238, v238
	v_pk_fma_f32 v[4:5], v[242:243], v[236:237], v[4:5] op_sel:[0,1,0]
	v_cvt_pk_f32_fp8_sdwa v[242:243], v193 src0_sel:WORD_1
	v_pk_fma_f32 v[6:7], v[244:245], v[236:237], v[6:7] op_sel:[0,1,0]
	v_add_f32_e32 v215, v215, v237
	v_pk_fma_f32 v[0:1], v[240:241], v[236:237], v[0:1] op_sel:[0,1,0]
	v_pk_fma_f32 v[2:3], v[242:243], v[236:237], v[2:3] op_sel:[0,1,0]
	v_readlane_b32 s0, v75, 61
	s_lshl_b32 s0, s0, 10
	s_add_u32 s4, s6, s0
	s_addc_u32 s5, s7, 0
	global_load_dwordx4 v[190:193], v16, s[4:5]
	s_waitcnt vmcnt(15)
	v_cvt_pk_f32_fp8_e32 v[240:241], v194
	v_cvt_pk_f32_fp8_sdwa v[242:243], v194 src0_sel:WORD_1
	v_cvt_pk_f32_fp8_e32 v[244:245], v195
	v_pk_fma_f32 v[12:13], v[240:241], v[238:239], v[12:13] op_sel_hi:[1,0,1]
	v_cvt_pk_f32_fp8_sdwa v[240:241], v195 src0_sel:WORD_1
	v_pk_fma_f32 v[14:15], v[242:243], v[238:239], v[14:15] op_sel_hi:[1,0,1]
	v_cvt_pk_f32_fp8_e32 v[242:243], v196
	v_sub_f32_e32 v239, v239, v216
	v_pk_fma_f32 v[8:9], v[244:245], v[238:239], v[8:9] op_sel_hi:[1,0,1]
	v_cvt_pk_f32_fp8_sdwa v[244:245], v196 src0_sel:WORD_1
	v_pk_fma_f32 v[10:11], v[240:241], v[238:239], v[10:11] op_sel_hi:[1,0,1]
	v_cvt_pk_f32_fp8_e32 v[240:241], v197
	v_exp_f32_e32 v239, v239
	v_pk_fma_f32 v[4:5], v[242:243], v[238:239], v[4:5] op_sel_hi:[1,0,1]
	v_cvt_pk_f32_fp8_sdwa v[242:243], v197 src0_sel:WORD_1
	v_pk_fma_f32 v[6:7], v[244:245], v[238:239], v[6:7] op_sel_hi:[1,0,1]
	v_add_f32_e32 v215, v215, v238
	v_pk_fma_f32 v[0:1], v[240:241], v[238:239], v[0:1] op_sel_hi:[1,0,1]
	v_pk_fma_f32 v[2:3], v[242:243], v[238:239], v[2:3] op_sel_hi:[1,0,1]
	v_readlane_b32 s0, v75, 62
	s_lshl_b32 s0, s0, 10
	s_add_u32 s4, s6, s0
	s_addc_u32 s5, s7, 0
	global_load_dwordx4 v[194:197], v16, s[4:5]
	s_waitcnt vmcnt(15)
	v_cvt_pk_f32_fp8_e32 v[240:241], v198
	v_cvt_pk_f32_fp8_sdwa v[242:243], v198 src0_sel:WORD_1
	v_cvt_pk_f32_fp8_e32 v[244:245], v199
	v_pk_fma_f32 v[12:13], v[240:241], v[238:239], v[12:13] op_sel:[0,1,0]
	v_cvt_pk_f32_fp8_sdwa v[240:241], v199 src0_sel:WORD_1
	v_pk_fma_f32 v[14:15], v[242:243], v[238:239], v[14:15] op_sel:[0,1,0]
	v_cvt_pk_f32_fp8_e32 v[242:243], v200
	v_add_f32_e32 v215, v215, v239
	v_pk_fma_f32 v[8:9], v[244:245], v[238:239], v[8:9] op_sel:[0,1,0]
	v_cvt_pk_f32_fp8_sdwa v[244:245], v200 src0_sel:WORD_1
	v_pk_fma_f32 v[10:11], v[240:241], v[238:239], v[10:11] op_sel:[0,1,0]
	v_cvt_pk_f32_fp8_e32 v[240:241], v201
	v_pk_fma_f32 v[4:5], v[242:243], v[238:239], v[4:5] op_sel:[0,1,0]
	v_cvt_pk_f32_fp8_sdwa v[242:243], v201 src0_sel:WORD_1
	v_pk_fma_f32 v[6:7], v[244:245], v[238:239], v[6:7] op_sel:[0,1,0]
	v_pk_fma_f32 v[0:1], v[240:241], v[238:239], v[0:1] op_sel:[0,1,0]
	v_pk_fma_f32 v[2:3], v[242:243], v[238:239], v[2:3] op_sel:[0,1,0]
	v_readlane_b32 s0, v75, 63
	s_lshl_b32 s0, s0, 10
	s_add_u32 s4, s6, s0
	s_addc_u32 s5, s7, 0
	global_load_dwordx4 v[198:201], v16, s[4:5]
	s_waitcnt vmcnt(15)
	v_cvt_pk_f32_fp8_e32 v[240:241], v136
	v_cvt_pk_f32_fp8_sdwa v[242:243], v136 src0_sel:WORD_1
	v_cvt_pk_f32_fp8_e32 v[244:245], v137
	v_cvt_pk_f32_fp8_sdwa v[202:203], v137 src0_sel:WORD_1
	v_pk_mul_f32 v[204:205], v[240:241], v[28:29]
	v_pk_mul_f32 v[206:207], v[242:243], v[30:31]
	v_cvt_pk_f32_fp8_e32 v[240:241], v138
	v_cvt_pk_f32_fp8_sdwa v[242:243], v138 src0_sel:WORD_1
	v_pk_fma_f32 v[204:205], v[244:245], v[32:33], v[204:205]
	v_pk_fma_f32 v[206:207], v[202:203], v[34:35], v[206:207]
	v_cvt_pk_f32_fp8_e32 v[244:245], v139
	v_cvt_pk_f32_fp8_sdwa v[202:203], v139 src0_sel:WORD_1
	v_pk_fma_f32 v[204:205], v[240:241], v[36:37], v[204:205]
	v_pk_fma_f32 v[206:207], v[242:243], v[38:39], v[206:207]
	v_pk_fma_f32 v[204:205], v[244:245], v[40:41], v[204:205]
	v_pk_fma_f32 v[206:207], v[202:203], v[42:43], v[206:207]
	v_readlane_b32 s0, v75, 48
	s_lshl_b32 s0, s0, 10
	s_add_u32 s4, s8, s0
	s_addc_u32 s5, s9, 0
	global_load_dwordx4 v[136:139], v16, s[4:5]
	v_pk_add_f32 v[204:205], v[204:205], v[206:207]
	s_nop 0
	v_add_f32_e32 v235, v204, v205
	s_waitcnt vmcnt(15)
; #define DPPF(v, ctrl) __builtin_bit_cast(float, __builtin_amdgcn_update_dpp(0, __builtin_bit_cast(int, (v)), (ctrl), 0xf, 0xf, true))
; DI float sum8(float v) { v += DPPF(v, 0xB1); v += DPPF(v, 0x4E); v += DPPF(v, 0x141); return v; }
; DI void topk_phase(const bf16_t* PROJ, const unsigned char* K8, const unsigned char* V8, const unsigned short* SC, bf16_t* ODSA, int c, char* smem, int bid, int nb) {
;     ...
;         const size_t ro = (size_t)__builtin_amdgcn_readlane(mysel, jj) * 1024 + lane * 16;
;         const uint4 a = *(const uint4*)(K8 + ro), vv = *(const uint4*)(V8 + ro);
;         const unsigned w[4] = {a.x, a.y, a.z, a.w}, u[4] = {vv.x, vv.y, vv.z, vv.w};
;         float da = 0.f;
; #pragma unroll
;         for (int i = 0; i < 4; ++i) {
;           const f32x2v lo = __builtin_amdgcn_cvt_pk_f32_fp8((int)w[i], false), hi = __builtin_amdgcn_cvt_pk_f32_fp8((int)w[i], true);
;           da += qv[4 * i] * lo[0] + qv[4 * i + 1] * lo[1] + qv[4 * i + 2] * hi[0] + qv[4 * i + 3] * hi[1];
;         }
;         da = sum8(da);
;         da = j < count ? da : -3e30f;
	v_cvt_pk_f32_fp8_e32 v[240:241], v140
	v_cvt_pk_f32_fp8_sdwa v[242:243], v140 src0_sel:WORD_1
	v_cvt_pk_f32_fp8_e32 v[244:245], v141
	v_cvt_pk_f32_fp8_sdwa v[202:203], v141 src0_sel:WORD_1
	v_add_f32_dpp v235, v235, v235 quad_perm:[1,0,3,2] row_mask:0xf bank_mask:0xf bound_ctrl:1
	v_pk_mul_f32 v[204:205], v[240:241], v[28:29]
	v_pk_mul_f32 v[206:207], v[242:243], v[30:31]
	v_add_f32_dpp v235, v235, v235 quad_perm:[2,3,0,1] row_mask:0xf bank_mask:0xf bound_ctrl:1
	v_cvt_pk_f32_fp8_e32 v[240:241], v142
	v_cvt_pk_f32_fp8_sdwa v[242:243], v142 src0_sel:WORD_1
	v_add_f32_dpp v235, v235, v235 row_half_mirror row_mask:0xf bank_mask:0xf bound_ctrl:1
	v_pk_fma_f32 v[204:205], v[244:245], v[32:33], v[204:205]
	v_pk_fma_f32 v[206:207], v[202:203], v[34:35], v[206:207]
	s_add_i32 s0, s1, 48
	s_cmp_lt_i32 s0, s2
	s_cselect_b64 vcc, -1, 0
	v_cvt_pk_f32_fp8_e32 v[244:245], v143
	v_cvt_pk_f32_fp8_sdwa v[202:203], v143 src0_sel:WORD_1
	v_cndmask_b32_e32 v210, v220, v235, vcc
	v_pk_fma_f32 v[204:205], v[240:241], v[36:37], v[204:205]
	v_pk_fma_f32 v[206:207], v[242:243], v[38:39], v[206:207]
	v_pk_fma_f32 v[204:205], v[244:245], v[40:41], v[204:205]
	v_pk_fma_f32 v[206:207], v[202:203], v[42:43], v[206:207]
	v_readlane_b32 s0, v75, 49
	s_lshl_b32 s0, s0, 10
	s_add_u32 s4, s8, s0
	s_addc_u32 s5, s9, 0
	global_load_dwordx4 v[140:143], v16, s[4:5]
	v_pk_add_f32 v[204:205], v[204:205], v[206:207]
	s_nop 0
	v_add_f32_e32 v221, v204, v205
	s_waitcnt vmcnt(15)
	v_cvt_pk_f32_fp8_e32 v[240:241], v144
	v_cvt_pk_f32_fp8_sdwa v[242:243], v144 src0_sel:WORD_1
	v_cvt_pk_f32_fp8_e32 v[244:245], v145
	v_cvt_pk_f32_fp8_sdwa v[202:203], v145 src0_sel:WORD_1
	v_add_f32_dpp v221, v221, v221 quad_perm:[1,0,3,2] row_mask:0xf bank_mask:0xf bound_ctrl:1
	v_pk_mul_f32 v[204:205], v[240:241], v[28:29]
	v_pk_mul_f32 v[206:207], v[242:243], v[30:31]
	v_add_f32_dpp v221, v221, v221 quad_perm:[2,3,0,1] row_mask:0xf bank_mask:0xf bound_ctrl:1
	v_cvt_pk_f32_fp8_e32 v[240:241], v146
	v_cvt_pk_f32_fp8_sdwa v[242:243], v146 src0_sel:WORD_1
	v_add_f32_dpp v221, v221, v221 row_half_mirror row_mask:0xf bank_mask:0xf bound_ctrl:1
	v_pk_fma_f32 v[204:205], v[244:245], v[32:33], v[204:205]
	v_pk_fma_f32 v[206:207], v[202:203], v[34:35], v[206:207]
	s_add_i32 s0, s1, 49
	s_cmp_lt_i32 s0, s2
	s_cselect_b64 vcc, -1, 0
	v_cvt_pk_f32_fp8_e32 v[244:245], v147
	v_cvt_pk_f32_fp8_sdwa v[202:203], v147 src0_sel:WORD_1
	v_cndmask_b32_e32 v211, v220, v221, vcc
	v_pk_fma_f32 v[204:205], v[240:241], v[36:37], v[204:205]
	v_pk_fma_f32 v[206:207], v[242:243], v[38:39], v[206:207]
	v_pk_fma_f32 v[204:205], v[244:245], v[40:41], v[204:205]
	v_pk_fma_f32 v[206:207], v[202:203], v[42:43], v[206:207]
	v_readlane_b32 s0, v75, 50
	s_lshl_b32 s0, s0, 10
	s_add_u32 s4, s8, s0
	s_addc_u32 s5, s9, 0
	global_load_dwordx4 v[144:147], v16, s[4:5]
	v_pk_add_f32 v[204:205], v[204:205], v[206:207]
	s_nop 0
	v_add_f32_e32 v235, v204, v205
	s_waitcnt vmcnt(15)
	v_cvt_pk_f32_fp8_e32 v[240:241], v148
	v_cvt_pk_f32_fp8_sdwa v[242:243], v148 src0_sel:WORD_1
	v_cvt_pk_f32_fp8_e32 v[244:245], v149
	v_cvt_pk_f32_fp8_sdwa v[202:203], v149 src0_sel:WORD_1
	v_add_f32_dpp v235, v235, v235 quad_perm:[1,0,3,2] row_mask:0xf bank_mask:0xf bound_ctrl:1
	v_pk_mul_f32 v[204:205], v[240:241], v[28:29]
	v_pk_mul_f32 v[206:207], v[242:243], v[30:31]
	v_add_f32_dpp v235, v235, v235 quad_perm:[2,3,0,1] row_mask:0xf bank_mask:0xf bound_ctrl:1
	v_cvt_pk_f32_fp8_e32 v[240:241], v150
	v_cvt_pk_f32_fp8_sdwa v[242:243], v150 src0_sel:WORD_1
	v_add_f32_dpp v235, v235, v235 row_half_mirror row_mask:0xf bank_mask:0xf bound_ctrl:1
	v_pk_fma_f32 v[204:205], v[244:245], v[32:33], v[204:205]
	v_pk_fma_f32 v[206:207], v[202:203], v[34:35], v[206:207]
	s_add_i32 s0, s1, 50
	s_cmp_lt_i32 s0, s2
	s_cselect_b64 vcc, -1, 0
	v_cvt_pk_f32_fp8_e32 v[244:245], v151
	v_cvt_pk_f32_fp8_sdwa v[202:203], v151 src0_sel:WORD_1
	v_cndmask_b32_e32 v212, v220, v235, vcc
	v_pk_fma_f32 v[204:205], v[240:241], v[36:37], v[204:205]
	v_pk_fma_f32 v[206:207], v[242:243], v[38:39], v[206:207]
	v_pk_fma_f32 v[204:205], v[244:245], v[40:41], v[204:205]
	v_pk_fma_f32 v[206:207], v[202:203], v[42:43], v[206:207]
	v_readlane_b32 s0, v75, 51
	s_lshl_b32 s0, s0, 10
	s_add_u32 s4, s8, s0
	s_addc_u32 s5, s9, 0
	global_load_dwordx4 v[148:151], v16, s[4:5]
	v_pk_add_f32 v[204:205], v[204:205], v[206:207]
	s_nop 0
	v_add_f32_e32 v221, v204, v205
	s_waitcnt vmcnt(15)
	v_cvt_pk_f32_fp8_e32 v[240:241], v152
	v_cvt_pk_f32_fp8_sdwa v[242:243], v152 src0_sel:WORD_1
	v_cvt_pk_f32_fp8_e32 v[244:245], v153
	v_cvt_pk_f32_fp8_sdwa v[202:203], v153 src0_sel:WORD_1
	v_add_f32_dpp v221, v221, v221 quad_perm:[1,0,3,2] row_mask:0xf bank_mask:0xf bound_ctrl:1
	v_pk_mul_f32 v[204:205], v[240:241], v[28:29]
	v_pk_mul_f32 v[206:207], v[242:243], v[30:31]
	v_add_f32_dpp v221, v221, v221 quad_perm:[2,3,0,1] row_mask:0xf bank_mask:0xf bound_ctrl:1
	v_cvt_pk_f32_fp8_e32 v[240:241], v154
	v_cvt_pk_f32_fp8_sdwa v[242:243], v154 src0_sel:WORD_1
	v_add_f32_dpp v221, v221, v221 row_half_mirror row_mask:0xf bank_mask:0xf bound_ctrl:1
	v_pk_fma_f32 v[204:205], v[244:245], v[32:33], v[204:205]
	v_pk_fma_f32 v[206:207], v[202:203], v[34:35], v[206:207]
	s_add_i32 s0, s1, 51
	s_cmp_lt_i32 s0, s2
	s_cselect_b64 vcc, -1, 0
	v_cvt_pk_f32_fp8_e32 v[244:245], v155
	v_cvt_pk_f32_fp8_sdwa v[202:203], v155 src0_sel:WORD_1
	v_cndmask_b32_e32 v213, v220, v221, vcc
	v_pk_fma_f32 v[204:205], v[240:241], v[36:37], v[204:205]
	v_pk_fma_f32 v[206:207], v[242:243], v[38:39], v[206:207]
	v_pk_fma_f32 v[204:205], v[244:245], v[40:41], v[204:205]
	v_pk_fma_f32 v[206:207], v[202:203], v[42:43], v[206:207]
	v_readlane_b32 s0, v75, 52
	s_lshl_b32 s0, s0, 10
	s_add_u32 s4, s8, s0
	s_addc_u32 s5, s9, 0
	global_load_dwordx4 v[152:155], v16, s[4:5]
	v_pk_add_f32 v[204:205], v[204:205], v[206:207]
	s_nop 0
	v_add_f32_e32 v235, v204, v205
	s_waitcnt vmcnt(15)
; #define DPPF(v, ctrl) __builtin_bit_cast(float, __builtin_amdgcn_update_dpp(0, __builtin_bit_cast(int, (v)), (ctrl), 0xf, 0xf, true))
; DI float sum8(float v) { v += DPPF(v, 0xB1); v += DPPF(v, 0x4E); v += DPPF(v, 0x141); return v; }
; DI void topk_phase(const bf16_t* PROJ, const unsigned char* K8, const unsigned char* V8, const unsigned short* SC, bf16_t* ODSA, int c, char* smem, int bid, int nb) {
;     ...
;         const size_t ro = (size_t)__builtin_amdgcn_readlane(mysel, jj) * 1024 + lane * 16;
;         const uint4 a = *(const uint4*)(K8 + ro), vv = *(const uint4*)(V8 + ro);
;         const unsigned w[4] = {a.x, a.y, a.z, a.w}, u[4] = {vv.x, vv.y, vv.z, vv.w};
;         float da = 0.f;
; #pragma unroll
;         for (int i = 0; i < 4; ++i) {
;           const f32x2v lo = __builtin_amdgcn_cvt_pk_f32_fp8((int)w[i], false), hi = __builtin_amdgcn_cvt_pk_f32_fp8((int)w[i], true);
;           da += qv[4 * i] * lo[0] + qv[4 * i + 1] * lo[1] + qv[4 * i + 2] * hi[0] + qv[4 * i + 3] * hi[1];
;         }
;         da = sum8(da);
;         da = j < count ? da : -3e30f;
	v_cvt_pk_f32_fp8_e32 v[240:241], v156
	v_cvt_pk_f32_fp8_sdwa v[242:243], v156 src0_sel:WORD_1
	v_cvt_pk_f32_fp8_e32 v[244:245], v157
	v_cvt_pk_f32_fp8_sdwa v[202:203], v157 src0_sel:WORD_1
	v_add_f32_dpp v235, v235, v235 quad_perm:[1,0,3,2] row_mask:0xf bank_mask:0xf bound_ctrl:1
	v_pk_mul_f32 v[204:205], v[240:241], v[28:29]
	v_pk_mul_f32 v[206:207], v[242:243], v[30:31]
	v_add_f32_dpp v235, v235, v235 quad_perm:[2,3,0,1] row_mask:0xf bank_mask:0xf bound_ctrl:1
	v_cvt_pk_f32_fp8_e32 v[240:241], v158
	v_cvt_pk_f32_fp8_sdwa v[242:243], v158 src0_sel:WORD_1
	v_add_f32_dpp v235, v235, v235 row_half_mirror row_mask:0xf bank_mask:0xf bound_ctrl:1
	v_pk_fma_f32 v[204:205], v[244:245], v[32:33], v[204:205]
	v_pk_fma_f32 v[206:207], v[202:203], v[34:35], v[206:207]
	s_add_i32 s0, s1, 52
	s_cmp_lt_i32 s0, s2
	s_cselect_b64 vcc, -1, 0
	v_cvt_pk_f32_fp8_e32 v[244:245], v159
	v_cvt_pk_f32_fp8_sdwa v[202:203], v159 src0_sel:WORD_1
	v_cndmask_b32_e32 v226, v220, v235, vcc
	v_pk_fma_f32 v[204:205], v[240:241], v[36:37], v[204:205]
	v_pk_fma_f32 v[206:207], v[242:243], v[38:39], v[206:207]
	v_pk_fma_f32 v[204:205], v[244:245], v[40:41], v[204:205]
	v_pk_fma_f32 v[206:207], v[202:203], v[42:43], v[206:207]
	v_readlane_b32 s0, v75, 53
	s_lshl_b32 s0, s0, 10
	s_add_u32 s4, s8, s0
	s_addc_u32 s5, s9, 0
	global_load_dwordx4 v[156:159], v16, s[4:5]
	v_pk_add_f32 v[204:205], v[204:205], v[206:207]
	s_nop 0
	v_add_f32_e32 v221, v204, v205
	s_waitcnt vmcnt(15)
	v_cvt_pk_f32_fp8_e32 v[240:241], v160
	v_cvt_pk_f32_fp8_sdwa v[242:243], v160 src0_sel:WORD_1
	v_cvt_pk_f32_fp8_e32 v[244:245], v161
	v_cvt_pk_f32_fp8_sdwa v[202:203], v161 src0_sel:WORD_1
	v_add_f32_dpp v221, v221, v221 quad_perm:[1,0,3,2] row_mask:0xf bank_mask:0xf bound_ctrl:1
	v_pk_mul_f32 v[204:205], v[240:241], v[28:29]
	v_pk_mul_f32 v[206:207], v[242:243], v[30:31]
	v_add_f32_dpp v221, v221, v221 quad_perm:[2,3,0,1] row_mask:0xf bank_mask:0xf bound_ctrl:1
	v_cvt_pk_f32_fp8_e32 v[240:241], v162
	v_cvt_pk_f32_fp8_sdwa v[242:243], v162 src0_sel:WORD_1
	v_add_f32_dpp v221, v221, v221 row_half_mirror row_mask:0xf bank_mask:0xf bound_ctrl:1
	v_pk_fma_f32 v[204:205], v[244:245], v[32:33], v[204:205]
	v_pk_fma_f32 v[206:207], v[202:203], v[34:35], v[206:207]
	s_add_i32 s0, s1, 53
	s_cmp_lt_i32 s0, s2
	s_cselect_b64 vcc, -1, 0
	v_cvt_pk_f32_fp8_e32 v[244:245], v163
	v_cvt_pk_f32_fp8_sdwa v[202:203], v163 src0_sel:WORD_1
	v_cndmask_b32_e32 v227, v220, v221, vcc
	v_pk_fma_f32 v[204:205], v[240:241], v[36:37], v[204:205]
	v_pk_fma_f32 v[206:207], v[242:243], v[38:39], v[206:207]
	v_pk_fma_f32 v[204:205], v[244:245], v[40:41], v[204:205]
	v_pk_fma_f32 v[206:207], v[202:203], v[42:43], v[206:207]
	v_readlane_b32 s0, v75, 54
	s_lshl_b32 s0, s0, 10
	s_add_u32 s4, s8, s0
	s_addc_u32 s5, s9, 0
	global_load_dwordx4 v[160:163], v16, s[4:5]
	v_pk_add_f32 v[204:205], v[204:205], v[206:207]
	s_nop 0
	v_add_f32_e32 v235, v204, v205
	s_waitcnt vmcnt(15)
	v_cvt_pk_f32_fp8_e32 v[240:241], v164
	v_cvt_pk_f32_fp8_sdwa v[242:243], v164 src0_sel:WORD_1
	v_cvt_pk_f32_fp8_e32 v[244:245], v165
	v_cvt_pk_f32_fp8_sdwa v[202:203], v165 src0_sel:WORD_1
	v_add_f32_dpp v235, v235, v235 quad_perm:[1,0,3,2] row_mask:0xf bank_mask:0xf bound_ctrl:1
	v_pk_mul_f32 v[204:205], v[240:241], v[28:29]
	v_pk_mul_f32 v[206:207], v[242:243], v[30:31]
	v_add_f32_dpp v235, v235, v235 quad_perm:[2,3,0,1] row_mask:0xf bank_mask:0xf bound_ctrl:1
	v_cvt_pk_f32_fp8_e32 v[240:241], v166
	v_cvt_pk_f32_fp8_sdwa v[242:243], v166 src0_sel:WORD_1
	v_add_f32_dpp v235, v235, v235 row_half_mirror row_mask:0xf bank_mask:0xf bound_ctrl:1
	v_pk_fma_f32 v[204:205], v[244:245], v[32:33], v[204:205]
	v_pk_fma_f32 v[206:207], v[202:203], v[34:35], v[206:207]
	s_add_i32 s0, s1, 54
	s_cmp_lt_i32 s0, s2
	s_cselect_b64 vcc, -1, 0
	v_cvt_pk_f32_fp8_e32 v[244:245], v167
	v_cvt_pk_f32_fp8_sdwa v[202:203], v167 src0_sel:WORD_1
	v_cndmask_b32_e32 v228, v220, v235, vcc
	v_pk_fma_f32 v[204:205], v[240:241], v[36:37], v[204:205]
	v_pk_fma_f32 v[206:207], v[242:243], v[38:39], v[206:207]
	v_pk_fma_f32 v[204:205], v[244:245], v[40:41], v[204:205]
	v_pk_fma_f32 v[206:207], v[202:203], v[42:43], v[206:207]
	v_readlane_b32 s0, v75, 55
	s_lshl_b32 s0, s0, 10
	s_add_u32 s4, s8, s0
	s_addc_u32 s5, s9, 0
	global_load_dwordx4 v[164:167], v16, s[4:5]
	v_pk_add_f32 v[204:205], v[204:205], v[206:207]
	s_nop 0
	v_add_f32_e32 v221, v204, v205
	s_waitcnt vmcnt(15)
	v_cvt_pk_f32_fp8_e32 v[240:241], v168
	v_cvt_pk_f32_fp8_sdwa v[242:243], v168 src0_sel:WORD_1
	v_cvt_pk_f32_fp8_e32 v[244:245], v169
	v_cvt_pk_f32_fp8_sdwa v[202:203], v169 src0_sel:WORD_1
	v_add_f32_dpp v221, v221, v221 quad_perm:[1,0,3,2] row_mask:0xf bank_mask:0xf bound_ctrl:1
	v_pk_mul_f32 v[204:205], v[240:241], v[28:29]
	v_pk_mul_f32 v[206:207], v[242:243], v[30:31]
	v_add_f32_dpp v221, v221, v221 quad_perm:[2,3,0,1] row_mask:0xf bank_mask:0xf bound_ctrl:1
	v_cvt_pk_f32_fp8_e32 v[240:241], v170
	v_cvt_pk_f32_fp8_sdwa v[242:243], v170 src0_sel:WORD_1
	v_add_f32_dpp v221, v221, v221 row_half_mirror row_mask:0xf bank_mask:0xf bound_ctrl:1
	v_pk_fma_f32 v[204:205], v[244:245], v[32:33], v[204:205]
	v_pk_fma_f32 v[206:207], v[202:203], v[34:35], v[206:207]
	s_add_i32 s0, s1, 55
	s_cmp_lt_i32 s0, s2
	s_cselect_b64 vcc, -1, 0
	v_cvt_pk_f32_fp8_e32 v[244:245], v171
	v_cvt_pk_f32_fp8_sdwa v[202:203], v171 src0_sel:WORD_1
	v_cndmask_b32_e32 v229, v220, v221, vcc
	v_pk_fma_f32 v[204:205], v[240:241], v[36:37], v[204:205]
	v_pk_fma_f32 v[206:207], v[242:243], v[38:39], v[206:207]
	v_pk_fma_f32 v[204:205], v[244:245], v[40:41], v[204:205]
	v_pk_fma_f32 v[206:207], v[202:203], v[42:43], v[206:207]
	v_readlane_b32 s0, v75, 56
	s_lshl_b32 s0, s0, 10
	s_add_u32 s4, s8, s0
	s_addc_u32 s5, s9, 0
	global_load_dwordx4 v[168:171], v16, s[4:5]
	v_pk_add_f32 v[204:205], v[204:205], v[206:207]
	s_nop 0
	v_add_f32_e32 v235, v204, v205
	s_waitcnt vmcnt(15)
; #define DPPF(v, ctrl) __builtin_bit_cast(float, __builtin_amdgcn_update_dpp(0, __builtin_bit_cast(int, (v)), (ctrl), 0xf, 0xf, true))
; DI float sum8(float v) { v += DPPF(v, 0xB1); v += DPPF(v, 0x4E); v += DPPF(v, 0x141); return v; }
; DI void topk_phase(const bf16_t* PROJ, const unsigned char* K8, const unsigned char* V8, const unsigned short* SC, bf16_t* ODSA, int c, char* smem, int bid, int nb) {
;     ...
;         const size_t ro = (size_t)__builtin_amdgcn_readlane(mysel, jj) * 1024 + lane * 16;
;         const uint4 a = *(const uint4*)(K8 + ro), vv = *(const uint4*)(V8 + ro);
;         const unsigned w[4] = {a.x, a.y, a.z, a.w}, u[4] = {vv.x, vv.y, vv.z, vv.w};
;         float da = 0.f;
; #pragma unroll
;         for (int i = 0; i < 4; ++i) {
;           const f32x2v lo = __builtin_amdgcn_cvt_pk_f32_fp8((int)w[i], false), hi = __builtin_amdgcn_cvt_pk_f32_fp8((int)w[i], true);
;           da += qv[4 * i] * lo[0] + qv[4 * i + 1] * lo[1] + qv[4 * i + 2] * hi[0] + qv[4 * i + 3] * hi[1];
;         }
;         da = sum8(da);
;         da = j < count ? da : -3e30f;
	v_cvt_pk_f32_fp8_e32 v[240:241], v172
	v_cvt_pk_f32_fp8_sdwa v[242:243], v172 src0_sel:WORD_1
	v_cvt_pk_f32_fp8_e32 v[244:245], v173
	v_cvt_pk_f32_fp8_sdwa v[202:203], v173 src0_sel:WORD_1
	v_add_f32_dpp v235, v235, v235 quad_perm:[1,0,3,2] row_mask:0xf bank_mask:0xf bound_ctrl:1
	v_pk_mul_f32 v[204:205], v[240:241], v[28:29]
	v_pk_mul_f32 v[206:207], v[242:243], v[30:31]
	v_add_f32_dpp v235, v235, v235 quad_perm:[2,3,0,1] row_mask:0xf bank_mask:0xf bound_ctrl:1
	v_cvt_pk_f32_fp8_e32 v[240:241], v174
	v_cvt_pk_f32_fp8_sdwa v[242:243], v174 src0_sel:WORD_1
	v_add_f32_dpp v235, v235, v235 row_half_mirror row_mask:0xf bank_mask:0xf bound_ctrl:1
	v_pk_fma_f32 v[204:205], v[244:245], v[32:33], v[204:205]
	v_pk_fma_f32 v[206:207], v[202:203], v[34:35], v[206:207]
	s_add_i32 s0, s1, 56
	s_cmp_lt_i32 s0, s2
	s_cselect_b64 vcc, -1, 0
	v_cvt_pk_f32_fp8_e32 v[244:245], v175
	v_cvt_pk_f32_fp8_sdwa v[202:203], v175 src0_sel:WORD_1
	v_cndmask_b32_e32 v230, v220, v235, vcc
	v_pk_fma_f32 v[204:205], v[240:241], v[36:37], v[204:205]
	v_pk_fma_f32 v[206:207], v[242:243], v[38:39], v[206:207]
	v_pk_fma_f32 v[204:205], v[244:245], v[40:41], v[204:205]
	v_pk_fma_f32 v[206:207], v[202:203], v[42:43], v[206:207]
	v_readlane_b32 s0, v75, 57
	s_lshl_b32 s0, s0, 10
	s_add_u32 s4, s8, s0
	s_addc_u32 s5, s9, 0
	global_load_dwordx4 v[172:175], v16, s[4:5]
	v_pk_add_f32 v[204:205], v[204:205], v[206:207]
	s_nop 0
	v_add_f32_e32 v221, v204, v205
	s_waitcnt vmcnt(15)
	v_cvt_pk_f32_fp8_e32 v[240:241], v176
	v_cvt_pk_f32_fp8_sdwa v[242:243], v176 src0_sel:WORD_1
	v_cvt_pk_f32_fp8_e32 v[244:245], v177
	v_cvt_pk_f32_fp8_sdwa v[202:203], v177 src0_sel:WORD_1
	v_add_f32_dpp v221, v221, v221 quad_perm:[1,0,3,2] row_mask:0xf bank_mask:0xf bound_ctrl:1
	v_pk_mul_f32 v[204:205], v[240:241], v[28:29]
	v_pk_mul_f32 v[206:207], v[242:243], v[30:31]
	v_add_f32_dpp v221, v221, v221 quad_perm:[2,3,0,1] row_mask:0xf bank_mask:0xf bound_ctrl:1
	v_cvt_pk_f32_fp8_e32 v[240:241], v178
	v_cvt_pk_f32_fp8_sdwa v[242:243], v178 src0_sel:WORD_1
	v_add_f32_dpp v221, v221, v221 row_half_mirror row_mask:0xf bank_mask:0xf bound_ctrl:1
	v_pk_fma_f32 v[204:205], v[244:245], v[32:33], v[204:205]
	v_pk_fma_f32 v[206:207], v[202:203], v[34:35], v[206:207]
	s_add_i32 s0, s1, 57
	s_cmp_lt_i32 s0, s2
	s_cselect_b64 vcc, -1, 0
	v_cvt_pk_f32_fp8_e32 v[244:245], v179
	v_cvt_pk_f32_fp8_sdwa v[202:203], v179 src0_sel:WORD_1
	v_cndmask_b32_e32 v231, v220, v221, vcc
	v_pk_fma_f32 v[204:205], v[240:241], v[36:37], v[204:205]
	v_pk_fma_f32 v[206:207], v[242:243], v[38:39], v[206:207]
	v_pk_fma_f32 v[204:205], v[244:245], v[40:41], v[204:205]
	v_pk_fma_f32 v[206:207], v[202:203], v[42:43], v[206:207]
	v_readlane_b32 s0, v75, 58
	s_lshl_b32 s0, s0, 10
	s_add_u32 s4, s8, s0
	s_addc_u32 s5, s9, 0
	global_load_dwordx4 v[176:179], v16, s[4:5]
	v_pk_add_f32 v[204:205], v[204:205], v[206:207]
	s_nop 0
	v_add_f32_e32 v235, v204, v205
	s_waitcnt vmcnt(15)
	v_cvt_pk_f32_fp8_e32 v[240:241], v180
	v_cvt_pk_f32_fp8_sdwa v[242:243], v180 src0_sel:WORD_1
	v_cvt_pk_f32_fp8_e32 v[244:245], v181
	v_cvt_pk_f32_fp8_sdwa v[202:203], v181 src0_sel:WORD_1
	v_add_f32_dpp v235, v235, v235 quad_perm:[1,0,3,2] row_mask:0xf bank_mask:0xf bound_ctrl:1
	v_pk_mul_f32 v[204:205], v[240:241], v[28:29]
	v_pk_mul_f32 v[206:207], v[242:243], v[30:31]
	v_add_f32_dpp v235, v235, v235 quad_perm:[2,3,0,1] row_mask:0xf bank_mask:0xf bound_ctrl:1
	v_cvt_pk_f32_fp8_e32 v[240:241], v182
	v_cvt_pk_f32_fp8_sdwa v[242:243], v182 src0_sel:WORD_1
	v_add_f32_dpp v235, v235, v235 row_half_mirror row_mask:0xf bank_mask:0xf bound_ctrl:1
	v_pk_fma_f32 v[204:205], v[244:245], v[32:33], v[204:205]
	v_pk_fma_f32 v[206:207], v[202:203], v[34:35], v[206:207]
	s_add_i32 s0, s1, 58
	s_cmp_lt_i32 s0, s2
	s_cselect_b64 vcc, -1, 0
	v_cvt_pk_f32_fp8_e32 v[244:245], v183
	v_cvt_pk_f32_fp8_sdwa v[202:203], v183 src0_sel:WORD_1
	v_cndmask_b32_e32 v232, v220, v235, vcc
	v_pk_fma_f32 v[204:205], v[240:241], v[36:37], v[204:205]
	v_pk_fma_f32 v[206:207], v[242:243], v[38:39], v[206:207]
	v_pk_fma_f32 v[204:205], v[244:245], v[40:41], v[204:205]
	v_pk_fma_f32 v[206:207], v[202:203], v[42:43], v[206:207]
	v_readlane_b32 s0, v75, 59
	s_lshl_b32 s0, s0, 10
	s_add_u32 s4, s8, s0
	s_addc_u32 s5, s9, 0
	global_load_dwordx4 v[180:183], v16, s[4:5]
	v_pk_add_f32 v[204:205], v[204:205], v[206:207]
	s_nop 0
	v_add_f32_e32 v221, v204, v205
	s_waitcnt vmcnt(15)
	v_cvt_pk_f32_fp8_e32 v[240:241], v186
	v_cvt_pk_f32_fp8_sdwa v[242:243], v186 src0_sel:WORD_1
	v_cvt_pk_f32_fp8_e32 v[244:245], v187
	v_cvt_pk_f32_fp8_sdwa v[202:203], v187 src0_sel:WORD_1
	v_add_f32_dpp v221, v221, v221 quad_perm:[1,0,3,2] row_mask:0xf bank_mask:0xf bound_ctrl:1
	v_pk_mul_f32 v[204:205], v[240:241], v[28:29]
	v_pk_mul_f32 v[206:207], v[242:243], v[30:31]
	v_add_f32_dpp v221, v221, v221 quad_perm:[2,3,0,1] row_mask:0xf bank_mask:0xf bound_ctrl:1
	v_cvt_pk_f32_fp8_e32 v[240:241], v188
	v_cvt_pk_f32_fp8_sdwa v[242:243], v188 src0_sel:WORD_1
	v_add_f32_dpp v221, v221, v221 row_half_mirror row_mask:0xf bank_mask:0xf bound_ctrl:1
	v_pk_fma_f32 v[204:205], v[244:245], v[32:33], v[204:205]
	v_pk_fma_f32 v[206:207], v[202:203], v[34:35], v[206:207]
	s_add_i32 s0, s1, 59
	s_cmp_lt_i32 s0, s2
	s_cselect_b64 vcc, -1, 0
	v_cvt_pk_f32_fp8_e32 v[244:245], v189
	v_cvt_pk_f32_fp8_sdwa v[202:203], v189 src0_sel:WORD_1
	v_cndmask_b32_e32 v233, v220, v221, vcc
	v_pk_fma_f32 v[204:205], v[240:241], v[36:37], v[204:205]
	v_pk_fma_f32 v[206:207], v[242:243], v[38:39], v[206:207]
	v_pk_fma_f32 v[204:205], v[244:245], v[40:41], v[204:205]
	v_pk_fma_f32 v[206:207], v[202:203], v[42:43], v[206:207]
	v_readlane_b32 s0, v75, 60
	s_lshl_b32 s0, s0, 10
	s_add_u32 s4, s8, s0
	s_addc_u32 s5, s9, 0
	global_load_dwordx4 v[186:189], v16, s[4:5]
	v_pk_add_f32 v[204:205], v[204:205], v[206:207]
	s_nop 0
	v_add_f32_e32 v235, v204, v205
	s_waitcnt vmcnt(15)
; DI float sum8(float v) { v += DPPF(v, 0xB1); v += DPPF(v, 0x4E); v += DPPF(v, 0x141); return v; }
; DI void topk_phase(const bf16_t* PROJ, const unsigned char* K8, const unsigned char* V8, const unsigned short* SC, bf16_t* ODSA, int c, char* smem, int bid, int nb) {
;     ...
; #pragma unroll 4
;     for (int jj = 0; jj < 64; ++jj) {
;       const int j = wid * 64 + jj;
;       {
;         const size_t ro = (size_t)__builtin_amdgcn_readlane(mysel, jj) * 1024 + lane * 16;
;         const uint4 a = *(const uint4*)(K8 + ro), vv = *(const uint4*)(V8 + ro);
;         const unsigned w[4] = {a.x, a.y, a.z, a.w}, u[4] = {vv.x, vv.y, vv.z, vv.w};
;         float da = 0.f;
; #pragma unroll
;         for (int i = 0; i < 4; ++i) {
;           const f32x2v lo = __builtin_amdgcn_cvt_pk_f32_fp8((int)w[i], false), hi = __builtin_amdgcn_cvt_pk_f32_fp8((int)w[i], true);
;           da += qv[4 * i] * lo[0] + qv[4 * i + 1] * lo[1] + qv[4 * i + 2] * hi[0] + qv[4 * i + 3] * hi[1];
;         }
;         da = sum8(da);
;         da = j < count ? da : -3e30f;
;         const float mn = fmaxf(m_run, da), al = __builtin_amdgcn_exp2f(m_run - mn), pp = __builtin_amdgcn_exp2f(da - mn);
;         m_run = mn; l_run = l_run * al + pp;
; #pragma unroll
;         for (int i = 0; i < 4; ++i) {
;           const f32x2v lo = __builtin_amdgcn_cvt_pk_f32_fp8((int)u[i], false), hi = __builtin_amdgcn_cvt_pk_f32_fp8((int)u[i], true);
;           ov[4 * i] = ov[4 * i] * al + pp * lo[0]; ov[4 * i + 1] = ov[4 * i + 1] * al + pp * lo[1];
;           ov[4 * i + 2] = ov[4 * i + 2] * al + pp * hi[0]; ov[4 * i + 3] = ov[4 * i + 3] * al + pp * hi[1];
;         }
;       }
;     }
	v_cvt_pk_f32_fp8_e32 v[240:241], v190
	v_cvt_pk_f32_fp8_sdwa v[242:243], v190 src0_sel:WORD_1
	v_cvt_pk_f32_fp8_e32 v[244:245], v191
	v_cvt_pk_f32_fp8_sdwa v[202:203], v191 src0_sel:WORD_1
	v_add_f32_dpp v235, v235, v235 quad_perm:[1,0,3,2] row_mask:0xf bank_mask:0xf bound_ctrl:1
	v_pk_mul_f32 v[204:205], v[240:241], v[28:29]
	v_pk_mul_f32 v[206:207], v[242:243], v[30:31]
	v_add_f32_dpp v235, v235, v235 quad_perm:[2,3,0,1] row_mask:0xf bank_mask:0xf bound_ctrl:1
	v_cvt_pk_f32_fp8_e32 v[240:241], v192
	v_cvt_pk_f32_fp8_sdwa v[242:243], v192 src0_sel:WORD_1
	v_add_f32_dpp v235, v235, v235 row_half_mirror row_mask:0xf bank_mask:0xf bound_ctrl:1
	v_pk_fma_f32 v[204:205], v[244:245], v[32:33], v[204:205]
	v_pk_fma_f32 v[206:207], v[202:203], v[34:35], v[206:207]
	s_add_i32 s0, s1, 60
	s_cmp_lt_i32 s0, s2
	s_cselect_b64 vcc, -1, 0
	v_cvt_pk_f32_fp8_e32 v[244:245], v193
	v_cvt_pk_f32_fp8_sdwa v[202:203], v193 src0_sel:WORD_1
	v_cndmask_b32_e32 v236, v220, v235, vcc
	v_pk_fma_f32 v[204:205], v[240:241], v[36:37], v[204:205]
	v_pk_fma_f32 v[206:207], v[242:243], v[38:39], v[206:207]
	v_pk_fma_f32 v[204:205], v[244:245], v[40:41], v[204:205]
	v_pk_fma_f32 v[206:207], v[202:203], v[42:43], v[206:207]
	v_readlane_b32 s0, v75, 61
	s_lshl_b32 s0, s0, 10
	s_add_u32 s4, s8, s0
	s_addc_u32 s5, s9, 0
	global_load_dwordx4 v[190:193], v16, s[4:5]
	v_pk_add_f32 v[204:205], v[204:205], v[206:207]
	s_nop 0
	v_add_f32_e32 v221, v204, v205
	s_waitcnt vmcnt(15)
	v_cvt_pk_f32_fp8_e32 v[240:241], v194
	v_cvt_pk_f32_fp8_sdwa v[242:243], v194 src0_sel:WORD_1
	v_cvt_pk_f32_fp8_e32 v[244:245], v195
	v_cvt_pk_f32_fp8_sdwa v[202:203], v195 src0_sel:WORD_1
	v_add_f32_dpp v221, v221, v221 quad_perm:[1,0,3,2] row_mask:0xf bank_mask:0xf bound_ctrl:1
	v_pk_mul_f32 v[204:205], v[240:241], v[28:29]
	v_pk_mul_f32 v[206:207], v[242:243], v[30:31]
	v_add_f32_dpp v221, v221, v221 quad_perm:[2,3,0,1] row_mask:0xf bank_mask:0xf bound_ctrl:1
	v_cvt_pk_f32_fp8_e32 v[240:241], v196
	v_cvt_pk_f32_fp8_sdwa v[242:243], v196 src0_sel:WORD_1
	v_add_f32_dpp v221, v221, v221 row_half_mirror row_mask:0xf bank_mask:0xf bound_ctrl:1
	v_pk_fma_f32 v[204:205], v[244:245], v[32:33], v[204:205]
	v_pk_fma_f32 v[206:207], v[202:203], v[34:35], v[206:207]
	s_add_i32 s0, s1, 61
	s_cmp_lt_i32 s0, s2
	s_cselect_b64 vcc, -1, 0
	v_cvt_pk_f32_fp8_e32 v[244:245], v197
	v_cvt_pk_f32_fp8_sdwa v[202:203], v197 src0_sel:WORD_1
	v_cndmask_b32_e32 v237, v220, v221, vcc
	v_pk_fma_f32 v[204:205], v[240:241], v[36:37], v[204:205]
	v_pk_fma_f32 v[206:207], v[242:243], v[38:39], v[206:207]
	v_pk_fma_f32 v[204:205], v[244:245], v[40:41], v[204:205]
	v_pk_fma_f32 v[206:207], v[202:203], v[42:43], v[206:207]
	v_readlane_b32 s0, v75, 62
	s_lshl_b32 s0, s0, 10
	s_add_u32 s4, s8, s0
	s_addc_u32 s5, s9, 0
	global_load_dwordx4 v[194:197], v16, s[4:5]
	v_pk_add_f32 v[204:205], v[204:205], v[206:207]
	s_nop 0
	v_add_f32_e32 v235, v204, v205
	s_waitcnt vmcnt(15)
	v_cvt_pk_f32_fp8_e32 v[240:241], v198
	v_cvt_pk_f32_fp8_sdwa v[242:243], v198 src0_sel:WORD_1
	v_cvt_pk_f32_fp8_e32 v[244:245], v199
	v_cvt_pk_f32_fp8_sdwa v[202:203], v199 src0_sel:WORD_1
	v_add_f32_dpp v235, v235, v235 quad_perm:[1,0,3,2] row_mask:0xf bank_mask:0xf bound_ctrl:1
	v_pk_mul_f32 v[204:205], v[240:241], v[28:29]
	v_pk_mul_f32 v[206:207], v[242:243], v[30:31]
	v_add_f32_dpp v235, v235, v235 quad_perm:[2,3,0,1] row_mask:0xf bank_mask:0xf bound_ctrl:1
	v_cvt_pk_f32_fp8_e32 v[240:241], v200
	v_cvt_pk_f32_fp8_sdwa v[242:243], v200 src0_sel:WORD_1
	v_add_f32_dpp v235, v235, v235 row_half_mirror row_mask:0xf bank_mask:0xf bound_ctrl:1
	v_pk_fma_f32 v[204:205], v[244:245], v[32:33], v[204:205]
	v_pk_fma_f32 v[206:207], v[202:203], v[34:35], v[206:207]
	s_add_i32 s0, s1, 62
	s_cmp_lt_i32 s0, s2
	s_cselect_b64 vcc, -1, 0
	v_cvt_pk_f32_fp8_e32 v[244:245], v201
	v_cvt_pk_f32_fp8_sdwa v[202:203], v201 src0_sel:WORD_1
	v_cndmask_b32_e32 v238, v220, v235, vcc
	v_pk_fma_f32 v[204:205], v[240:241], v[36:37], v[204:205]
	v_pk_fma_f32 v[206:207], v[242:243], v[38:39], v[206:207]
	v_pk_fma_f32 v[204:205], v[244:245], v[40:41], v[204:205]
	v_pk_fma_f32 v[206:207], v[202:203], v[42:43], v[206:207]
	v_readlane_b32 s0, v75, 63
	s_lshl_b32 s0, s0, 10
	s_add_u32 s4, s8, s0
	s_addc_u32 s5, s9, 0
	global_load_dwordx4 v[198:201], v16, s[4:5]
	v_pk_add_f32 v[204:205], v[204:205], v[206:207]
	s_nop 0
	v_add_f32_e32 v221, v204, v205
	s_nop 1
	v_add_f32_dpp v221, v221, v221 quad_perm:[1,0,3,2] row_mask:0xf bank_mask:0xf bound_ctrl:1
	s_nop 1
	v_add_f32_dpp v221, v221, v221 quad_perm:[2,3,0,1] row_mask:0xf bank_mask:0xf bound_ctrl:1
	s_nop 1
	v_add_f32_dpp v221, v221, v221 row_half_mirror row_mask:0xf bank_mask:0xf bound_ctrl:1
	s_add_i32 s0, s1, 63
	s_cmp_lt_i32 s0, s2
	s_cselect_b64 vcc, -1, 0
	s_nop 1
	v_cndmask_b32_e32 v239, v220, v221, vcc
	v_max3_f32 v224, v210, v211, v212
	v_max3_f32 v224, v224, v213, v226
	v_max3_f32 v224, v224, v227, v228
	v_max3_f32 v224, v224, v229, v230
	v_max3_f32 v224, v224, v231, v232
	v_max3_f32 v224, v224, v233, v236
	v_max3_f32 v224, v224, v237, v238
	v_max_f32_e32 v224, v224, v239
	v_max_f32_e32 v221, v216, v224
	v_sub_f32_e32 v184, v216, v221
	v_exp_f32_e32 v184, v184
	v_mov_b32_e32 v216, v221
	s_nop 0
	v_pk_mul_f32 v[12:13], v[12:13], v[184:185] op_sel_hi:[1,0]
	v_pk_mul_f32 v[14:15], v[14:15], v[184:185] op_sel_hi:[1,0]
	v_pk_mul_f32 v[8:9], v[8:9], v[184:185] op_sel_hi:[1,0]
	v_pk_mul_f32 v[10:11], v[10:11], v[184:185] op_sel_hi:[1,0]
	v_pk_mul_f32 v[4:5], v[4:5], v[184:185] op_sel_hi:[1,0]
	v_pk_mul_f32 v[6:7], v[6:7], v[184:185] op_sel_hi:[1,0]
	v_pk_mul_f32 v[0:1], v[0:1], v[184:185] op_sel_hi:[1,0]
	v_pk_mul_f32 v[2:3], v[2:3], v[184:185] op_sel_hi:[1,0]
	v_mul_f32_e32 v215, v215, v184
	v_sub_f32_e32 v210, v210, v216
	v_exp_f32_e32 v210, v210
	s_waitcnt vmcnt(15)
; DI void topk_phase(const bf16_t* PROJ, const unsigned char* K8, const unsigned char* V8, const unsigned short* SC, bf16_t* ODSA, int c, char* smem, int bid, int nb) {
;     ...
;         const float mn = fmaxf(m_run, da), al = __builtin_amdgcn_exp2f(m_run - mn), pp = __builtin_amdgcn_exp2f(da - mn);
;         m_run = mn; l_run = l_run * al + pp;
; #pragma unroll
;         for (int i = 0; i < 4; ++i) {
;           const f32x2v lo = __builtin_amdgcn_cvt_pk_f32_fp8((int)u[i], false), hi = __builtin_amdgcn_cvt_pk_f32_fp8((int)u[i], true);
;           ov[4 * i] = ov[4 * i] * al + pp * lo[0]; ov[4 * i + 1] = ov[4 * i + 1] * al + pp * lo[1];
;           ov[4 * i + 2] = ov[4 * i + 2] * al + pp * hi[0]; ov[4 * i + 3] = ov[4 * i + 3] * al + pp * hi[1];
;         }
	v_cvt_pk_f32_fp8_e32 v[240:241], v136
	v_cvt_pk_f32_fp8_sdwa v[242:243], v136 src0_sel:WORD_1
	v_cvt_pk_f32_fp8_e32 v[244:245], v137
	v_pk_fma_f32 v[12:13], v[240:241], v[210:211], v[12:13] op_sel_hi:[1,0,1]
	v_cvt_pk_f32_fp8_sdwa v[240:241], v137 src0_sel:WORD_1
	v_pk_fma_f32 v[14:15], v[242:243], v[210:211], v[14:15] op_sel_hi:[1,0,1]
	v_cvt_pk_f32_fp8_e32 v[242:243], v138
	v_sub_f32_e32 v211, v211, v216
	v_pk_fma_f32 v[8:9], v[244:245], v[210:211], v[8:9] op_sel_hi:[1,0,1]
	v_cvt_pk_f32_fp8_sdwa v[244:245], v138 src0_sel:WORD_1
	v_pk_fma_f32 v[10:11], v[240:241], v[210:211], v[10:11] op_sel_hi:[1,0,1]
	v_cvt_pk_f32_fp8_e32 v[240:241], v139
	v_exp_f32_e32 v211, v211
	v_pk_fma_f32 v[4:5], v[242:243], v[210:211], v[4:5] op_sel_hi:[1,0,1]
	v_cvt_pk_f32_fp8_sdwa v[242:243], v139 src0_sel:WORD_1
	v_pk_fma_f32 v[6:7], v[244:245], v[210:211], v[6:7] op_sel_hi:[1,0,1]
	v_add_f32_e32 v215, v215, v210
	v_pk_fma_f32 v[0:1], v[240:241], v[210:211], v[0:1] op_sel_hi:[1,0,1]
	v_pk_fma_f32 v[2:3], v[242:243], v[210:211], v[2:3] op_sel_hi:[1,0,1]
	s_waitcnt vmcnt(14)
	v_cvt_pk_f32_fp8_e32 v[240:241], v140
	v_cvt_pk_f32_fp8_sdwa v[242:243], v140 src0_sel:WORD_1
	v_cvt_pk_f32_fp8_e32 v[244:245], v141
	v_pk_fma_f32 v[12:13], v[240:241], v[210:211], v[12:13] op_sel:[0,1,0]
	v_cvt_pk_f32_fp8_sdwa v[240:241], v141 src0_sel:WORD_1
	v_pk_fma_f32 v[14:15], v[242:243], v[210:211], v[14:15] op_sel:[0,1,0]
	v_cvt_pk_f32_fp8_e32 v[242:243], v142
	v_sub_f32_e32 v212, v212, v216
	v_pk_fma_f32 v[8:9], v[244:245], v[210:211], v[8:9] op_sel:[0,1,0]
	v_cvt_pk_f32_fp8_sdwa v[244:245], v142 src0_sel:WORD_1
	v_pk_fma_f32 v[10:11], v[240:241], v[210:211], v[10:11] op_sel:[0,1,0]
	v_cvt_pk_f32_fp8_e32 v[240:241], v143
	v_exp_f32_e32 v212, v212
	v_pk_fma_f32 v[4:5], v[242:243], v[210:211], v[4:5] op_sel:[0,1,0]
	v_cvt_pk_f32_fp8_sdwa v[242:243], v143 src0_sel:WORD_1
	v_pk_fma_f32 v[6:7], v[244:245], v[210:211], v[6:7] op_sel:[0,1,0]
	v_add_f32_e32 v215, v215, v211
	v_pk_fma_f32 v[0:1], v[240:241], v[210:211], v[0:1] op_sel:[0,1,0]
	v_pk_fma_f32 v[2:3], v[242:243], v[210:211], v[2:3] op_sel:[0,1,0]
	s_waitcnt vmcnt(13)
	v_cvt_pk_f32_fp8_e32 v[240:241], v144
	v_cvt_pk_f32_fp8_sdwa v[242:243], v144 src0_sel:WORD_1
	v_cvt_pk_f32_fp8_e32 v[244:245], v145
	v_pk_fma_f32 v[12:13], v[240:241], v[212:213], v[12:13] op_sel_hi:[1,0,1]
	v_cvt_pk_f32_fp8_sdwa v[240:241], v145 src0_sel:WORD_1
	v_pk_fma_f32 v[14:15], v[242:243], v[212:213], v[14:15] op_sel_hi:[1,0,1]
	v_cvt_pk_f32_fp8_e32 v[242:243], v146
	v_sub_f32_e32 v213, v213, v216
	v_pk_fma_f32 v[8:9], v[244:245], v[212:213], v[8:9] op_sel_hi:[1,0,1]
	v_cvt_pk_f32_fp8_sdwa v[244:245], v146 src0_sel:WORD_1
	v_pk_fma_f32 v[10:11], v[240:241], v[212:213], v[10:11] op_sel_hi:[1,0,1]
	v_cvt_pk_f32_fp8_e32 v[240:241], v147
	v_exp_f32_e32 v213, v213
	v_pk_fma_f32 v[4:5], v[242:243], v[212:213], v[4:5] op_sel_hi:[1,0,1]
	v_cvt_pk_f32_fp8_sdwa v[242:243], v147 src0_sel:WORD_1
	v_pk_fma_f32 v[6:7], v[244:245], v[212:213], v[6:7] op_sel_hi:[1,0,1]
	v_add_f32_e32 v215, v215, v212
	v_pk_fma_f32 v[0:1], v[240:241], v[212:213], v[0:1] op_sel_hi:[1,0,1]
	v_pk_fma_f32 v[2:3], v[242:243], v[212:213], v[2:3] op_sel_hi:[1,0,1]
	s_waitcnt vmcnt(12)
	v_cvt_pk_f32_fp8_e32 v[240:241], v148
	v_cvt_pk_f32_fp8_sdwa v[242:243], v148 src0_sel:WORD_1
	v_cvt_pk_f32_fp8_e32 v[244:245], v149
	v_pk_fma_f32 v[12:13], v[240:241], v[212:213], v[12:13] op_sel:[0,1,0]
	v_cvt_pk_f32_fp8_sdwa v[240:241], v149 src0_sel:WORD_1
	v_pk_fma_f32 v[14:15], v[242:243], v[212:213], v[14:15] op_sel:[0,1,0]
	v_cvt_pk_f32_fp8_e32 v[242:243], v150
	v_sub_f32_e32 v226, v226, v216
	v_pk_fma_f32 v[8:9], v[244:245], v[212:213], v[8:9] op_sel:[0,1,0]
	v_cvt_pk_f32_fp8_sdwa v[244:245], v150 src0_sel:WORD_1
	v_pk_fma_f32 v[10:11], v[240:241], v[212:213], v[10:11] op_sel:[0,1,0]
	v_cvt_pk_f32_fp8_e32 v[240:241], v151
	v_exp_f32_e32 v226, v226
	v_pk_fma_f32 v[4:5], v[242:243], v[212:213], v[4:5] op_sel:[0,1,0]
	v_cvt_pk_f32_fp8_sdwa v[242:243], v151 src0_sel:WORD_1
	v_pk_fma_f32 v[6:7], v[244:245], v[212:213], v[6:7] op_sel:[0,1,0]
	v_add_f32_e32 v215, v215, v213
	v_pk_fma_f32 v[0:1], v[240:241], v[212:213], v[0:1] op_sel:[0,1,0]
	v_pk_fma_f32 v[2:3], v[242:243], v[212:213], v[2:3] op_sel:[0,1,0]
	s_waitcnt vmcnt(11)
	v_cvt_pk_f32_fp8_e32 v[240:241], v152
	v_cvt_pk_f32_fp8_sdwa v[242:243], v152 src0_sel:WORD_1
	v_cvt_pk_f32_fp8_e32 v[244:245], v153
	v_pk_fma_f32 v[12:13], v[240:241], v[226:227], v[12:13] op_sel_hi:[1,0,1]
	v_cvt_pk_f32_fp8_sdwa v[240:241], v153 src0_sel:WORD_1
	v_pk_fma_f32 v[14:15], v[242:243], v[226:227], v[14:15] op_sel_hi:[1,0,1]
	v_cvt_pk_f32_fp8_e32 v[242:243], v154
	v_sub_f32_e32 v227, v227, v216
	v_pk_fma_f32 v[8:9], v[244:245], v[226:227], v[8:9] op_sel_hi:[1,0,1]
	v_cvt_pk_f32_fp8_sdwa v[244:245], v154 src0_sel:WORD_1
	v_pk_fma_f32 v[10:11], v[240:241], v[226:227], v[10:11] op_sel_hi:[1,0,1]
	v_cvt_pk_f32_fp8_e32 v[240:241], v155
	v_exp_f32_e32 v227, v227
	v_pk_fma_f32 v[4:5], v[242:243], v[226:227], v[4:5] op_sel_hi:[1,0,1]
	v_cvt_pk_f32_fp8_sdwa v[242:243], v155 src0_sel:WORD_1
	v_pk_fma_f32 v[6:7], v[244:245], v[226:227], v[6:7] op_sel_hi:[1,0,1]
	v_add_f32_e32 v215, v215, v226
	v_pk_fma_f32 v[0:1], v[240:241], v[226:227], v[0:1] op_sel_hi:[1,0,1]
	v_pk_fma_f32 v[2:3], v[242:243], v[226:227], v[2:3] op_sel_hi:[1,0,1]
	s_waitcnt vmcnt(10)
; DI void topk_phase(const bf16_t* PROJ, const unsigned char* K8, const unsigned char* V8, const unsigned short* SC, bf16_t* ODSA, int c, char* smem, int bid, int nb) {
;     ...
;         const float mn = fmaxf(m_run, da), al = __builtin_amdgcn_exp2f(m_run - mn), pp = __builtin_amdgcn_exp2f(da - mn);
;         m_run = mn; l_run = l_run * al + pp;
; #pragma unroll
;         for (int i = 0; i < 4; ++i) {
;           const f32x2v lo = __builtin_amdgcn_cvt_pk_f32_fp8((int)u[i], false), hi = __builtin_amdgcn_cvt_pk_f32_fp8((int)u[i], true);
;           ov[4 * i] = ov[4 * i] * al + pp * lo[0]; ov[4 * i + 1] = ov[4 * i + 1] * al + pp * lo[1];
;           ov[4 * i + 2] = ov[4 * i + 2] * al + pp * hi[0]; ov[4 * i + 3] = ov[4 * i + 3] * al + pp * hi[1];
;         }
	v_cvt_pk_f32_fp8_e32 v[240:241], v156
	v_cvt_pk_f32_fp8_sdwa v[242:243], v156 src0_sel:WORD_1
	v_cvt_pk_f32_fp8_e32 v[244:245], v157
	v_pk_fma_f32 v[12:13], v[240:241], v[226:227], v[12:13] op_sel:[0,1,0]
	v_cvt_pk_f32_fp8_sdwa v[240:241], v157 src0_sel:WORD_1
	v_pk_fma_f32 v[14:15], v[242:243], v[226:227], v[14:15] op_sel:[0,1,0]
	v_cvt_pk_f32_fp8_e32 v[242:243], v158
	v_sub_f32_e32 v228, v228, v216
	v_pk_fma_f32 v[8:9], v[244:245], v[226:227], v[8:9] op_sel:[0,1,0]
	v_cvt_pk_f32_fp8_sdwa v[244:245], v158 src0_sel:WORD_1
	v_pk_fma_f32 v[10:11], v[240:241], v[226:227], v[10:11] op_sel:[0,1,0]
	v_cvt_pk_f32_fp8_e32 v[240:241], v159
	v_exp_f32_e32 v228, v228
	v_pk_fma_f32 v[4:5], v[242:243], v[226:227], v[4:5] op_sel:[0,1,0]
	v_cvt_pk_f32_fp8_sdwa v[242:243], v159 src0_sel:WORD_1
	v_pk_fma_f32 v[6:7], v[244:245], v[226:227], v[6:7] op_sel:[0,1,0]
	v_add_f32_e32 v215, v215, v227
	v_pk_fma_f32 v[0:1], v[240:241], v[226:227], v[0:1] op_sel:[0,1,0]
	v_pk_fma_f32 v[2:3], v[242:243], v[226:227], v[2:3] op_sel:[0,1,0]
	s_waitcnt vmcnt(9)
	v_cvt_pk_f32_fp8_e32 v[240:241], v160
	v_cvt_pk_f32_fp8_sdwa v[242:243], v160 src0_sel:WORD_1
	v_cvt_pk_f32_fp8_e32 v[244:245], v161
	v_pk_fma_f32 v[12:13], v[240:241], v[228:229], v[12:13] op_sel_hi:[1,0,1]
	v_cvt_pk_f32_fp8_sdwa v[240:241], v161 src0_sel:WORD_1
	v_pk_fma_f32 v[14:15], v[242:243], v[228:229], v[14:15] op_sel_hi:[1,0,1]
	v_cvt_pk_f32_fp8_e32 v[242:243], v162
	v_sub_f32_e32 v229, v229, v216
	v_pk_fma_f32 v[8:9], v[244:245], v[228:229], v[8:9] op_sel_hi:[1,0,1]
	v_cvt_pk_f32_fp8_sdwa v[244:245], v162 src0_sel:WORD_1
	v_pk_fma_f32 v[10:11], v[240:241], v[228:229], v[10:11] op_sel_hi:[1,0,1]
	v_cvt_pk_f32_fp8_e32 v[240:241], v163
	v_exp_f32_e32 v229, v229
	v_pk_fma_f32 v[4:5], v[242:243], v[228:229], v[4:5] op_sel_hi:[1,0,1]
	v_cvt_pk_f32_fp8_sdwa v[242:243], v163 src0_sel:WORD_1
	v_pk_fma_f32 v[6:7], v[244:245], v[228:229], v[6:7] op_sel_hi:[1,0,1]
	v_add_f32_e32 v215, v215, v228
	v_pk_fma_f32 v[0:1], v[240:241], v[228:229], v[0:1] op_sel_hi:[1,0,1]
	v_pk_fma_f32 v[2:3], v[242:243], v[228:229], v[2:3] op_sel_hi:[1,0,1]
	s_waitcnt vmcnt(8)
	v_cvt_pk_f32_fp8_e32 v[240:241], v164
	v_cvt_pk_f32_fp8_sdwa v[242:243], v164 src0_sel:WORD_1
	v_cvt_pk_f32_fp8_e32 v[244:245], v165
	v_pk_fma_f32 v[12:13], v[240:241], v[228:229], v[12:13] op_sel:[0,1,0]
	v_cvt_pk_f32_fp8_sdwa v[240:241], v165 src0_sel:WORD_1
	v_pk_fma_f32 v[14:15], v[242:243], v[228:229], v[14:15] op_sel:[0,1,0]
	v_cvt_pk_f32_fp8_e32 v[242:243], v166
	v_sub_f32_e32 v230, v230, v216
	v_pk_fma_f32 v[8:9], v[244:245], v[228:229], v[8:9] op_sel:[0,1,0]
	v_cvt_pk_f32_fp8_sdwa v[244:245], v166 src0_sel:WORD_1
	v_pk_fma_f32 v[10:11], v[240:241], v[228:229], v[10:11] op_sel:[0,1,0]
	v_cvt_pk_f32_fp8_e32 v[240:241], v167
	v_exp_f32_e32 v230, v230
	v_pk_fma_f32 v[4:5], v[242:243], v[228:229], v[4:5] op_sel:[0,1,0]
	v_cvt_pk_f32_fp8_sdwa v[242:243], v167 src0_sel:WORD_1
	v_pk_fma_f32 v[6:7], v[244:245], v[228:229], v[6:7] op_sel:[0,1,0]
	v_add_f32_e32 v215, v215, v229
	v_pk_fma_f32 v[0:1], v[240:241], v[228:229], v[0:1] op_sel:[0,1,0]
	v_pk_fma_f32 v[2:3], v[242:243], v[228:229], v[2:3] op_sel:[0,1,0]
	s_waitcnt vmcnt(7)
	v_cvt_pk_f32_fp8_e32 v[240:241], v168
	v_cvt_pk_f32_fp8_sdwa v[242:243], v168 src0_sel:WORD_1
	v_cvt_pk_f32_fp8_e32 v[244:245], v169
	v_pk_fma_f32 v[12:13], v[240:241], v[230:231], v[12:13] op_sel_hi:[1,0,1]
	v_cvt_pk_f32_fp8_sdwa v[240:241], v169 src0_sel:WORD_1
	v_pk_fma_f32 v[14:15], v[242:243], v[230:231], v[14:15] op_sel_hi:[1,0,1]
	v_cvt_pk_f32_fp8_e32 v[242:243], v170
	v_sub_f32_e32 v231, v231, v216
	v_pk_fma_f32 v[8:9], v[244:245], v[230:231], v[8:9] op_sel_hi:[1,0,1]
	v_cvt_pk_f32_fp8_sdwa v[244:245], v170 src0_sel:WORD_1
	v_pk_fma_f32 v[10:11], v[240:241], v[230:231], v[10:11] op_sel_hi:[1,0,1]
	v_cvt_pk_f32_fp8_e32 v[240:241], v171
	v_exp_f32_e32 v231, v231
	v_pk_fma_f32 v[4:5], v[242:243], v[230:231], v[4:5] op_sel_hi:[1,0,1]
	v_cvt_pk_f32_fp8_sdwa v[242:243], v171 src0_sel:WORD_1
	v_pk_fma_f32 v[6:7], v[244:245], v[230:231], v[6:7] op_sel_hi:[1,0,1]
	v_add_f32_e32 v215, v215, v230
	v_pk_fma_f32 v[0:1], v[240:241], v[230:231], v[0:1] op_sel_hi:[1,0,1]
	v_pk_fma_f32 v[2:3], v[242:243], v[230:231], v[2:3] op_sel_hi:[1,0,1]
	s_waitcnt vmcnt(6)
	v_cvt_pk_f32_fp8_e32 v[240:241], v172
	v_cvt_pk_f32_fp8_sdwa v[242:243], v172 src0_sel:WORD_1
	v_cvt_pk_f32_fp8_e32 v[244:245], v173
	v_pk_fma_f32 v[12:13], v[240:241], v[230:231], v[12:13] op_sel:[0,1,0]
	v_cvt_pk_f32_fp8_sdwa v[240:241], v173 src0_sel:WORD_1
	v_pk_fma_f32 v[14:15], v[242:243], v[230:231], v[14:15] op_sel:[0,1,0]
	v_cvt_pk_f32_fp8_e32 v[242:243], v174
	v_sub_f32_e32 v232, v232, v216
	v_pk_fma_f32 v[8:9], v[244:245], v[230:231], v[8:9] op_sel:[0,1,0]
	v_cvt_pk_f32_fp8_sdwa v[244:245], v174 src0_sel:WORD_1
	v_pk_fma_f32 v[10:11], v[240:241], v[230:231], v[10:11] op_sel:[0,1,0]
	v_cvt_pk_f32_fp8_e32 v[240:241], v175
	v_exp_f32_e32 v232, v232
	v_pk_fma_f32 v[4:5], v[242:243], v[230:231], v[4:5] op_sel:[0,1,0]
	v_cvt_pk_f32_fp8_sdwa v[242:243], v175 src0_sel:WORD_1
	v_pk_fma_f32 v[6:7], v[244:245], v[230:231], v[6:7] op_sel:[0,1,0]
	v_add_f32_e32 v215, v215, v231
	v_pk_fma_f32 v[0:1], v[240:241], v[230:231], v[0:1] op_sel:[0,1,0]
	v_pk_fma_f32 v[2:3], v[242:243], v[230:231], v[2:3] op_sel:[0,1,0]
	s_waitcnt vmcnt(5)
; DI void topk_phase(const bf16_t* PROJ, const unsigned char* K8, const unsigned char* V8, const unsigned short* SC, bf16_t* ODSA, int c, char* smem, int bid, int nb) {
;     ...
;         const float mn = fmaxf(m_run, da), al = __builtin_amdgcn_exp2f(m_run - mn), pp = __builtin_amdgcn_exp2f(da - mn);
;         m_run = mn; l_run = l_run * al + pp;
; #pragma unroll
;         for (int i = 0; i < 4; ++i) {
;           const f32x2v lo = __builtin_amdgcn_cvt_pk_f32_fp8((int)u[i], false), hi = __builtin_amdgcn_cvt_pk_f32_fp8((int)u[i], true);
;           ov[4 * i] = ov[4 * i] * al + pp * lo[0]; ov[4 * i + 1] = ov[4 * i + 1] * al + pp * lo[1];
;           ov[4 * i + 2] = ov[4 * i + 2] * al + pp * hi[0]; ov[4 * i + 3] = ov[4 * i + 3] * al + pp * hi[1];
;         }
;       }
;     }
;     if ((lane & 7) == 0) { sS[wid * 8 + hd] = m_run; sS[32 + wid * 8 + hd] = l_run; }
	v_cvt_pk_f32_fp8_e32 v[240:241], v176
	v_cvt_pk_f32_fp8_sdwa v[242:243], v176 src0_sel:WORD_1
	v_cvt_pk_f32_fp8_e32 v[244:245], v177
	v_pk_fma_f32 v[12:13], v[240:241], v[232:233], v[12:13] op_sel_hi:[1,0,1]
	v_cvt_pk_f32_fp8_sdwa v[240:241], v177 src0_sel:WORD_1
	v_pk_fma_f32 v[14:15], v[242:243], v[232:233], v[14:15] op_sel_hi:[1,0,1]
	v_cvt_pk_f32_fp8_e32 v[242:243], v178
	v_sub_f32_e32 v233, v233, v216
	v_pk_fma_f32 v[8:9], v[244:245], v[232:233], v[8:9] op_sel_hi:[1,0,1]
	v_cvt_pk_f32_fp8_sdwa v[244:245], v178 src0_sel:WORD_1
	v_pk_fma_f32 v[10:11], v[240:241], v[232:233], v[10:11] op_sel_hi:[1,0,1]
	v_cvt_pk_f32_fp8_e32 v[240:241], v179
	v_exp_f32_e32 v233, v233
	v_pk_fma_f32 v[4:5], v[242:243], v[232:233], v[4:5] op_sel_hi:[1,0,1]
	v_cvt_pk_f32_fp8_sdwa v[242:243], v179 src0_sel:WORD_1
	v_pk_fma_f32 v[6:7], v[244:245], v[232:233], v[6:7] op_sel_hi:[1,0,1]
	v_add_f32_e32 v215, v215, v232
	v_pk_fma_f32 v[0:1], v[240:241], v[232:233], v[0:1] op_sel_hi:[1,0,1]
	v_pk_fma_f32 v[2:3], v[242:243], v[232:233], v[2:3] op_sel_hi:[1,0,1]
	s_waitcnt vmcnt(4)
	v_cvt_pk_f32_fp8_e32 v[240:241], v180
	v_cvt_pk_f32_fp8_sdwa v[242:243], v180 src0_sel:WORD_1
	v_cvt_pk_f32_fp8_e32 v[244:245], v181
	v_pk_fma_f32 v[12:13], v[240:241], v[232:233], v[12:13] op_sel:[0,1,0]
	v_cvt_pk_f32_fp8_sdwa v[240:241], v181 src0_sel:WORD_1
	v_pk_fma_f32 v[14:15], v[242:243], v[232:233], v[14:15] op_sel:[0,1,0]
	v_cvt_pk_f32_fp8_e32 v[242:243], v182
	v_sub_f32_e32 v236, v236, v216
	v_pk_fma_f32 v[8:9], v[244:245], v[232:233], v[8:9] op_sel:[0,1,0]
	v_cvt_pk_f32_fp8_sdwa v[244:245], v182 src0_sel:WORD_1
	v_pk_fma_f32 v[10:11], v[240:241], v[232:233], v[10:11] op_sel:[0,1,0]
	v_cvt_pk_f32_fp8_e32 v[240:241], v183
	v_exp_f32_e32 v236, v236
	v_pk_fma_f32 v[4:5], v[242:243], v[232:233], v[4:5] op_sel:[0,1,0]
	v_cvt_pk_f32_fp8_sdwa v[242:243], v183 src0_sel:WORD_1
	v_pk_fma_f32 v[6:7], v[244:245], v[232:233], v[6:7] op_sel:[0,1,0]
	v_add_f32_e32 v215, v215, v233
	v_pk_fma_f32 v[0:1], v[240:241], v[232:233], v[0:1] op_sel:[0,1,0]
	v_pk_fma_f32 v[2:3], v[242:243], v[232:233], v[2:3] op_sel:[0,1,0]
	s_waitcnt vmcnt(3)
	v_cvt_pk_f32_fp8_e32 v[240:241], v186
	v_cvt_pk_f32_fp8_sdwa v[242:243], v186 src0_sel:WORD_1
	v_cvt_pk_f32_fp8_e32 v[244:245], v187
	v_pk_fma_f32 v[12:13], v[240:241], v[236:237], v[12:13] op_sel_hi:[1,0,1]
	v_cvt_pk_f32_fp8_sdwa v[240:241], v187 src0_sel:WORD_1
	v_pk_fma_f32 v[14:15], v[242:243], v[236:237], v[14:15] op_sel_hi:[1,0,1]
	v_cvt_pk_f32_fp8_e32 v[242:243], v188
	v_sub_f32_e32 v237, v237, v216
	v_pk_fma_f32 v[8:9], v[244:245], v[236:237], v[8:9] op_sel_hi:[1,0,1]
	v_cvt_pk_f32_fp8_sdwa v[244:245], v188 src0_sel:WORD_1
	v_pk_fma_f32 v[10:11], v[240:241], v[236:237], v[10:11] op_sel_hi:[1,0,1]
	v_cvt_pk_f32_fp8_e32 v[240:241], v189
	v_exp_f32_e32 v237, v237
	v_pk_fma_f32 v[4:5], v[242:243], v[236:237], v[4:5] op_sel_hi:[1,0,1]
	v_cvt_pk_f32_fp8_sdwa v[242:243], v189 src0_sel:WORD_1
	v_pk_fma_f32 v[6:7], v[244:245], v[236:237], v[6:7] op_sel_hi:[1,0,1]
	v_add_f32_e32 v215, v215, v236
	v_pk_fma_f32 v[0:1], v[240:241], v[236:237], v[0:1] op_sel_hi:[1,0,1]
	v_pk_fma_f32 v[2:3], v[242:243], v[236:237], v[2:3] op_sel_hi:[1,0,1]
	s_waitcnt vmcnt(2)
	v_cvt_pk_f32_fp8_e32 v[240:241], v190
	v_cvt_pk_f32_fp8_sdwa v[242:243], v190 src0_sel:WORD_1
	v_cvt_pk_f32_fp8_e32 v[244:245], v191
	v_pk_fma_f32 v[12:13], v[240:241], v[236:237], v[12:13] op_sel:[0,1,0]
	v_cvt_pk_f32_fp8_sdwa v[240:241], v191 src0_sel:WORD_1
	v_pk_fma_f32 v[14:15], v[242:243], v[236:237], v[14:15] op_sel:[0,1,0]
	v_cvt_pk_f32_fp8_e32 v[242:243], v192
	v_sub_f32_e32 v238, v238, v216
	v_pk_fma_f32 v[8:9], v[244:245], v[236:237], v[8:9] op_sel:[0,1,0]
	v_cvt_pk_f32_fp8_sdwa v[244:245], v192 src0_sel:WORD_1
	v_pk_fma_f32 v[10:11], v[240:241], v[236:237], v[10:11] op_sel:[0,1,0]
	v_cvt_pk_f32_fp8_e32 v[240:241], v193
	v_exp_f32_e32 v238, v238
	v_pk_fma_f32 v[4:5], v[242:243], v[236:237], v[4:5] op_sel:[0,1,0]
	v_cvt_pk_f32_fp8_sdwa v[242:243], v193 src0_sel:WORD_1
	v_pk_fma_f32 v[6:7], v[244:245], v[236:237], v[6:7] op_sel:[0,1,0]
	v_add_f32_e32 v215, v215, v237
	v_pk_fma_f32 v[0:1], v[240:241], v[236:237], v[0:1] op_sel:[0,1,0]
	v_pk_fma_f32 v[2:3], v[242:243], v[236:237], v[2:3] op_sel:[0,1,0]
	s_waitcnt vmcnt(1)
	v_cvt_pk_f32_fp8_e32 v[240:241], v194
	v_cvt_pk_f32_fp8_sdwa v[242:243], v194 src0_sel:WORD_1
	v_cvt_pk_f32_fp8_e32 v[244:245], v195
	v_pk_fma_f32 v[12:13], v[240:241], v[238:239], v[12:13] op_sel_hi:[1,0,1]
	v_cvt_pk_f32_fp8_sdwa v[240:241], v195 src0_sel:WORD_1
	v_pk_fma_f32 v[14:15], v[242:243], v[238:239], v[14:15] op_sel_hi:[1,0,1]
	v_cvt_pk_f32_fp8_e32 v[242:243], v196
	v_sub_f32_e32 v239, v239, v216
	v_pk_fma_f32 v[8:9], v[244:245], v[238:239], v[8:9] op_sel_hi:[1,0,1]
	v_cvt_pk_f32_fp8_sdwa v[244:245], v196 src0_sel:WORD_1
	v_pk_fma_f32 v[10:11], v[240:241], v[238:239], v[10:11] op_sel_hi:[1,0,1]
	v_cvt_pk_f32_fp8_e32 v[240:241], v197
	v_exp_f32_e32 v239, v239
	v_pk_fma_f32 v[4:5], v[242:243], v[238:239], v[4:5] op_sel_hi:[1,0,1]
	v_cvt_pk_f32_fp8_sdwa v[242:243], v197 src0_sel:WORD_1
	v_pk_fma_f32 v[6:7], v[244:245], v[238:239], v[6:7] op_sel_hi:[1,0,1]
	v_add_f32_e32 v215, v215, v238
	v_pk_fma_f32 v[0:1], v[240:241], v[238:239], v[0:1] op_sel_hi:[1,0,1]
	v_pk_fma_f32 v[2:3], v[242:243], v[238:239], v[2:3] op_sel_hi:[1,0,1]
	s_waitcnt vmcnt(0)
	v_cvt_pk_f32_fp8_e32 v[240:241], v198
	v_cvt_pk_f32_fp8_sdwa v[242:243], v198 src0_sel:WORD_1
	v_cvt_pk_f32_fp8_e32 v[244:245], v199
	v_pk_fma_f32 v[12:13], v[240:241], v[238:239], v[12:13] op_sel:[0,1,0]
	v_cvt_pk_f32_fp8_sdwa v[240:241], v199 src0_sel:WORD_1
	v_pk_fma_f32 v[14:15], v[242:243], v[238:239], v[14:15] op_sel:[0,1,0]
	v_cvt_pk_f32_fp8_e32 v[242:243], v200
	v_add_f32_e32 v215, v215, v239
	v_pk_fma_f32 v[8:9], v[244:245], v[238:239], v[8:9] op_sel:[0,1,0]
	v_cvt_pk_f32_fp8_sdwa v[244:245], v200 src0_sel:WORD_1
	v_pk_fma_f32 v[10:11], v[240:241], v[238:239], v[10:11] op_sel:[0,1,0]
	v_cvt_pk_f32_fp8_e32 v[240:241], v201
	v_pk_fma_f32 v[4:5], v[242:243], v[238:239], v[4:5] op_sel:[0,1,0]
	v_cvt_pk_f32_fp8_sdwa v[242:243], v201 src0_sel:WORD_1
	v_pk_fma_f32 v[6:7], v[244:245], v[238:239], v[6:7] op_sel:[0,1,0]
	v_pk_fma_f32 v[0:1], v[240:241], v[238:239], v[0:1] op_sel:[0,1,0]
	v_pk_fma_f32 v[2:3], v[242:243], v[238:239], v[2:3] op_sel:[0,1,0]
	v_mov_b32_e32 v44, v215
	v_mov_b32_e32 v45, v216
	s_mov_b64 s[0:1], exec
	v_readlane_b32 s2, v250, 43
	v_readlane_b32 s3, v250, 44
	s_and_b64 s[2:3], s[0:1], s[2:3]
	s_mov_b64 exec, s[2:3]
	s_cbranch_execz .LBB0_1354
	ds_write2_b32 v74, v45, v44 offset1:32
	s_branch .LBB0_1354

; #define MFMA16(a, b, c) __builtin_amdgcn_mfma_f32_16x16x32_bf16((a), (b), (c), 0, 0, 0)
; DI void gld(u32x4v& r, const void* p) { asm volatile("global_load_dwordx4 %0, %1, off" : "=v"(r) : "v"(p) : "memory"); }
; template <int DQK>
; DI void attn_phase(const bf16_t* Q, int ldq, const bf16_t* K1, int ldk1, const bf16_t* K2, int ldk2, const bf16_t* VT, int ldvt,
;                    bf16_t* O, int ldo, int nheads, int nq, int nkeys, bool causal, float scale, char* smem, int bid, int nb) {
;     ...
;         const int s1 = (kt + 1 < ntiles ? kt + 1 : kt) * 64;
; #pragma unroll
;         for (int j = 0; j < CPR / 4; ++j) {
;           const int c = tl + 256 * j, row = c / CPR, ch = c % CPR;
;           gld(kr[j], ch < 16 ? K1 + (size_t)(s1 + row) * ldk1 + h * 128 + ch * 8 : K2 + (size_t)(s1 + row) * ldk2 + (ch - 16) * 8);
;         }
; #pragma unroll
;         for (int j = 0; j < 4; ++j) { const int c = tl + 256 * j, d = c >> 3, ch = c & 7; gld(vr[j], VT + (size_t)(h * 128 + d) * ldvt + s1 + ch * 8); }
;       }
;       __syncthreads();
;       if (causal && s0 > qw + 31) continue;
;       f32x4 st[2][4];
; #pragma unroll
;       for (int mi = 0; mi < 2; ++mi)
; #pragma unroll
;         for (int nj = 0; nj < 4; ++nj) st[mi][nj] = (f32x4){0.f, 0.f, 0.f, 0.f};
;       asm volatile("" ::: "memory");
; #pragma unroll
;       for (int ks = 0; ks < NKS; ++ks) {
;         bf16x8 kf[4];
; #pragma unroll
;         for (int nj = 0; nj < 4; ++nj) kf[nj] = *(const bf16x8*)(Ks + (nj * 16 + fr) * LK * 2 + ((((ks * 4) & ~7) | (((ks * 4 + fq) ^ (fr >> 1)) & 7)) * 16));
;         bf16x8 qq[2];
; #pragma unroll
;         for (int mi = 0; mi < 2; ++mi) {
;           if (ks < NKH) qq[mi] = qf[mi][ks < NKH ? ks : 0];
;           else qq[mi] = *(const bf16x8*)(Q + (size_t)(qw + mi * 16 + fr) * ldq + h * DQK + ks * 32 + fq * 8);
;         }
; #pragma unroll
;         for (int mi = 0; mi < 2; ++mi)
; #pragma unroll
;           for (int nj = 0; nj < 4; ++nj) st[mi][nj] = MFMA16(kf[nj], qq[mi], st[mi][nj]);
.LBB0_1562:
	s_andn2_saveexec_b64 s[0:1], s[0:1]
	v_lshlrev_b64 v[68:69], 11, v[68:69]
	v_lshl_add_u64 v[68:69], s[10:11], 0, v[68:69]
	v_ashrrev_i32_e32 v71, 31, v184
	v_mov_b32_e32 v70, v184
	v_lshl_add_u64 v[70:71], v[70:71], 1, v[68:69]
	s_or_b64 exec, exec, s[0:1]
	v_readlane_b32 s0, v247, 47
	v_readlane_b32 s1, v247, 48
	s_lshl_b64 s[0:1], s[0:1], 1
	v_readlane_b32 s4, v249, 3
	v_readlane_b32 s5, v249, 4
	s_add_u32 s0, s4, s0
	v_add_u32_e32 v72, s8, v156
	s_addc_u32 s1, s5, s1
	v_lshlrev_b32_e32 v184, 1, v157
	v_ashrrev_i32_e32 v73, 31, v72
	v_add_u32_e32 v76, s8, v155
	v_lshl_add_u64 v[84:85], s[0:1], 0, v[184:185]
	v_lshlrev_b64 v[72:73], 15, v[72:73]
	v_ashrrev_i32_e32 v77, 31, v76
	v_add_u32_e32 v80, s8, v154
	global_load_dwordx4 v[68:71], v[70:71], off
	v_lshl_add_u64 v[72:73], v[84:85], 0, v[72:73]
	v_lshlrev_b64 v[76:77], 15, v[76:77]
	v_ashrrev_i32_e32 v81, 31, v80
	v_add_u32_e32 v86, s8, v153
	global_load_dwordx4 v[72:75], v[72:73], off
	v_lshl_add_u64 v[76:77], v[84:85], 0, v[76:77]
	v_lshlrev_b64 v[80:81], 15, v[80:81]
	v_ashrrev_i32_e32 v87, 31, v86
	global_load_dwordx4 v[76:79], v[76:77], off
	v_lshl_add_u64 v[80:81], v[84:85], 0, v[80:81]
	v_lshlrev_b64 v[86:87], 15, v[86:87]
	global_load_dwordx4 v[80:83], v[80:81], off
	v_lshl_add_u64 v[84:85], v[84:85], 0, v[86:87]
	global_load_dwordx4 v[84:87], v[84:85], off
	s_sub_i32 s0, s9, 63
	v_cmp_le_i32_e32 vcc, s0, v237
	s_waitcnt lgkmcnt(0)
	s_barrier
	s_and_saveexec_b64 s[12:13], vcc
	s_cbranch_execz .LBB0_1539
	ds_read_b128 v[154:157], v231
	ds_read_b128 v[158:161], v231 offset:6144
	ds_read_b128 v[162:165], v231 offset:12288
	ds_read_b128 v[166:169], v231 offset:18432
	ds_read_b128 v[198:201], v232
	ds_read_b128 v[202:205], v232 offset:6144
	ds_read_b128 v[206:209], v232 offset:12288
	ds_read_b128 v[210:213], v232 offset:18432
	s_waitcnt lgkmcnt(7)
	v_mfma_f32_16x16x32_bf16 v[170:173], v[154:157], v[4:7], 0
	v_add_u32_e32 v153, s9, v230
	v_subrev_u32_e32 v182, 63, v153
	v_cmp_gt_i32_e32 vcc, s9, v234
	s_waitcnt lgkmcnt(6)
	v_mfma_f32_16x16x32_bf16 v[186:189], v[158:161], v[4:7], 0
	v_cmp_ge_i32_e64 s[4:5], v182, v235
	s_and_b64 s[4:5], vcc, s[4:5]
	v_cmp_gt_i32_e64 s[0:1], v182, v235
	s_waitcnt lgkmcnt(5)
	v_mfma_f32_16x16x32_bf16 v[190:193], v[162:165], v[4:7], 0
	s_and_b64 s[0:1], vcc, s[0:1]
	s_mov_b32 s17, 0xf149f2ca
	s_movk_i32 s16, 0x7fff
	s_waitcnt lgkmcnt(4)
	v_mfma_f32_16x16x32_bf16 v[194:197], v[166:169], v[4:7], 0
	s_mov_b32 s15, 0xffff0000
	v_add_u32_e32 v244, 0x6800, v233
	v_add_u32_e32 v245, 0x7000, v233
	s_nop 0
	v_mfma_f32_16x16x32_bf16 v[154:157], v[154:157], v[28:31], 0
	v_add_u32_e32 v221, 0x7800, v233
	v_add_u32_e32 v215, 0x8000, v233
	v_add_u32_e32 v216, 0x8800, v233
	v_mfma_f32_16x16x32_bf16 v[158:161], v[158:161], v[28:31], 0
	v_add_u32_e32 v224, 0x9000, v233
	v_add_u32_e32 v225, 0x9800, v233
	v_mfma_f32_16x16x32_bf16 v[162:165], v[162:165], v[28:31], 0
	v_mfma_f32_16x16x32_bf16 v[166:169], v[166:169], v[28:31], 0
	s_waitcnt lgkmcnt(3)
	v_mfma_f32_16x16x32_bf16 v[170:173], v[198:201], v[8:11], v[170:173]
	s_waitcnt lgkmcnt(2)
	v_mfma_f32_16x16x32_bf16 v[186:189], v[202:205], v[8:11], v[186:189]
	s_waitcnt lgkmcnt(1)
	v_mfma_f32_16x16x32_bf16 v[190:193], v[206:209], v[8:11], v[190:193]
	s_waitcnt lgkmcnt(0)
	v_mfma_f32_16x16x32_bf16 v[194:197], v[210:213], v[8:11], v[194:197]
	s_nop 0
	v_mfma_f32_16x16x32_bf16 v[154:157], v[198:201], v[32:35], v[154:157]
	v_mfma_f32_16x16x32_bf16 v[158:161], v[202:205], v[32:35], v[158:161]
	v_mfma_f32_16x16x32_bf16 v[162:165], v[206:209], v[32:35], v[162:165]
	v_mfma_f32_16x16x32_bf16 v[166:169], v[210:213], v[32:35], v[166:169]
	ds_read_b128 v[198:201], v231 offset:128
	ds_read_b128 v[202:205], v231 offset:6272
	ds_read_b128 v[206:209], v231 offset:12416
	ds_read_b128 v[210:213], v231 offset:18560
	s_waitcnt lgkmcnt(3)
	v_mfma_f32_16x16x32_bf16 v[170:173], v[198:201], v[12:15], v[170:173]
	s_waitcnt lgkmcnt(2)
	v_mfma_f32_16x16x32_bf16 v[186:189], v[202:205], v[12:15], v[186:189]
	s_waitcnt lgkmcnt(1)
	v_mfma_f32_16x16x32_bf16 v[190:193], v[206:209], v[12:15], v[190:193]
	s_waitcnt lgkmcnt(0)
	v_mfma_f32_16x16x32_bf16 v[194:197], v[210:213], v[12:15], v[194:197]
	s_nop 0
	v_mfma_f32_16x16x32_bf16 v[154:157], v[198:201], v[36:39], v[154:157]
	v_mfma_f32_16x16x32_bf16 v[158:161], v[202:205], v[36:39], v[158:161]
	v_mfma_f32_16x16x32_bf16 v[162:165], v[206:209], v[36:39], v[162:165]
	v_mfma_f32_16x16x32_bf16 v[166:169], v[210:213], v[36:39], v[166:169]
	ds_read_b128 v[198:201], v232 offset:128
	ds_read_b128 v[202:205], v232 offset:6272
	ds_read_b128 v[206:209], v232 offset:12416
	ds_read_b128 v[210:213], v232 offset:18560
	s_waitcnt lgkmcnt(3)
	v_mfma_f32_16x16x32_bf16 v[170:173], v[198:201], v[16:19], v[170:173]
	s_waitcnt lgkmcnt(2)
	v_mfma_f32_16x16x32_bf16 v[186:189], v[202:205], v[16:19], v[186:189]
	s_waitcnt lgkmcnt(1)
	v_mfma_f32_16x16x32_bf16 v[190:193], v[206:209], v[16:19], v[190:193]
	s_waitcnt lgkmcnt(0)
	v_mfma_f32_16x16x32_bf16 v[194:197], v[210:213], v[16:19], v[194:197]
	s_nop 0
	v_mfma_f32_16x16x32_bf16 v[154:157], v[198:201], v[40:43], v[154:157]
	v_mfma_f32_16x16x32_bf16 v[158:161], v[202:205], v[40:43], v[158:161]
	v_mfma_f32_16x16x32_bf16 v[162:165], v[206:209], v[40:43], v[162:165]
	v_mfma_f32_16x16x32_bf16 v[166:169], v[210:213], v[40:43], v[166:169]
	ds_read_b128 v[198:201], v231 offset:256
	ds_read_b128 v[202:205], v231 offset:6400
	ds_read_b128 v[206:209], v231 offset:12544
	ds_read_b128 v[210:213], v231 offset:18688
	s_waitcnt lgkmcnt(3)
	v_mfma_f32_16x16x32_bf16 v[170:173], v[198:201], v[20:23], v[170:173]
	s_waitcnt lgkmcnt(2)
	v_mfma_f32_16x16x32_bf16 v[186:189], v[202:205], v[20:23], v[186:189]
	s_waitcnt lgkmcnt(1)
; #define MFMA16(a, b, c) __builtin_amdgcn_mfma_f32_16x16x32_bf16((a), (b), (c), 0, 0, 0)
; template <int DQK>
; DI void attn_phase(const bf16_t* Q, int ldq, const bf16_t* K1, int ldk1, const bf16_t* K2, int ldk2, const bf16_t* VT, int ldvt,
;                    bf16_t* O, int ldo, int nheads, int nq, int nkeys, bool causal, float scale, char* smem, int bid, int nb) {
;     ...
;           for (int nj = 0; nj < 4; ++nj) st[mi][nj] = MFMA16(kf[nj], qq[mi], st[mi][nj]);
;       }
;       const bool diag = causal && (s0 + 63 > qw);
;       bf16x8 pf[2][2];
; #pragma unroll
;       for (int mi = 0; mi < 2; ++mi) {
;         const int qi = qw + mi * 16 + fr;
;         float mx = -1e30f;
; #pragma unroll
;         for (int nj = 0; nj < 4; ++nj)
; #pragma unroll
;           for (int r = 0; r < 4; ++r) {
;             float v = st[mi][nj][r] * sc2;
;             if (diag && (s0 + nj * 16 + fq * 4 + r > qi)) v = -1e30f;
;             st[mi][nj][r] = v; mx = fmaxf(mx, v);
;           }
;         mx = rows4_max(mx);
;         const float mn = fmaxf(mrow[mi], mx), al = __builtin_amdgcn_exp2f(mrow[mi] - mn);
	v_mfma_f32_16x16x32_bf16 v[190:193], v[206:209], v[20:23], v[190:193]
	s_waitcnt lgkmcnt(0)
	v_mfma_f32_16x16x32_bf16 v[194:197], v[210:213], v[20:23], v[194:197]
	s_nop 0
	v_mfma_f32_16x16x32_bf16 v[154:157], v[198:201], v[44:47], v[154:157]
	v_mfma_f32_16x16x32_bf16 v[158:161], v[202:205], v[44:47], v[158:161]
	v_mfma_f32_16x16x32_bf16 v[162:165], v[206:209], v[44:47], v[162:165]
	v_mfma_f32_16x16x32_bf16 v[198:201], v[210:213], v[44:47], v[166:169]
	s_nop 2
	ds_read_b128 v[166:169], v232 offset:256
	ds_read_b128 v[202:205], v232 offset:6400
	ds_read_b128 v[206:209], v232 offset:12544
	ds_read_b128 v[210:213], v232 offset:18688
	s_waitcnt lgkmcnt(3)
	v_mfma_f32_16x16x32_bf16 v[238:241], v[166:169], v[24:27], v[170:173]
	s_nop 0
	v_mfma_f32_16x16x32_bf16 v[172:175], v[166:169], v[48:51], v[154:157]
	s_waitcnt lgkmcnt(2)
	v_mfma_f32_16x16x32_bf16 v[168:171], v[202:205], v[48:51], v[158:161]
	s_nop 3
	v_mul_f32_e32 v155, 0x3dd53b94, v239
	v_cndmask_b32_e64 v155, v155, v223, s[4:5]
	v_mul_f32_e32 v157, 0x3dd53b94, v240
	s_waitcnt lgkmcnt(1)
	v_mfma_f32_16x16x32_bf16 v[164:167], v[206:209], v[48:51], v[162:165]
	v_mul_f32_e32 v158, 0x3dd53b94, v241
	v_subrev_u32_e32 v159, 47, v153
	v_mul_f32_e32 v154, 0x3dd53b94, v238
	s_waitcnt lgkmcnt(0)
	v_mfma_f32_16x16x32_bf16 v[160:163], v[210:213], v[48:51], v[198:201]
	v_cndmask_b32_e64 v154, v154, v223, s[0:1]
	v_max3_f32 v156, v154, s17, v155
	v_add_u32_e32 v240, -12, v153
	v_subrev_u32_e32 v198, 61, v153
	v_cmp_gt_i32_e64 s[4:5], v198, v235
	v_mfma_f32_16x16x32_bf16 v[186:189], v[202:205], v[24:27], v[186:189]
	s_and_b64 s[4:5], vcc, s[4:5]
	v_subrev_u32_e32 v200, 60, v153
	v_cndmask_b32_e64 v157, v157, v223, s[4:5]
	v_cmp_gt_i32_e64 s[4:5], v200, v235
	s_and_b64 s[4:5], vcc, s[4:5]
	s_nop 2
	v_mul_f32_e32 v181, 0x3dd53b94, v186
	v_cndmask_b32_e64 v158, v158, v223, s[4:5]
	v_cmp_gt_i32_e64 s[4:5], v159, v235
	s_and_b64 s[4:5], vcc, s[4:5]
	v_subrev_u32_e32 v186, 46, v153
	v_cndmask_b32_e64 v159, v181, v223, s[4:5]
	v_cmp_gt_i32_e64 s[4:5], v186, v235
	v_mul_f32_e32 v181, 0x3dd53b94, v187
	s_and_b64 s[4:5], vcc, s[4:5]
	v_cndmask_b32_e64 v183, v181, v223, s[4:5]
	v_mul_f32_e32 v181, 0x3dd53b94, v188
	v_subrev_u32_e32 v188, 45, v153
	v_cmp_gt_i32_e64 s[4:5], v188, v235
	v_mfma_f32_16x16x32_bf16 v[190:193], v[206:209], v[24:27], v[190:193]
	s_and_b64 s[4:5], vcc, s[4:5]
	v_subrev_u32_e32 v202, 44, v153
	v_cndmask_b32_e64 v184, v181, v223, s[4:5]
	v_cmp_gt_i32_e64 s[4:5], v202, v235
	v_mul_f32_e32 v181, 0x3dd53b94, v189
	s_and_b64 s[4:5], vcc, s[4:5]
	v_subrev_u32_e32 v204, 31, v153
	v_cndmask_b32_e64 v201, v181, v223, s[4:5]
	v_cmp_gt_i32_e64 s[4:5], v204, v235
	v_mul_f32_e32 v181, 0x3dd53b94, v190
	s_and_b64 s[4:5], vcc, s[4:5]
	v_subrev_u32_e32 v206, 30, v153
	v_cndmask_b32_e64 v190, v181, v223, s[4:5]
	v_cmp_gt_i32_e64 s[4:5], v206, v235
	v_mul_f32_e32 v181, 0x3dd53b94, v191
	s_and_b64 s[4:5], vcc, s[4:5]
	v_cndmask_b32_e64 v191, v181, v223, s[4:5]
	v_mul_f32_e32 v181, 0x3dd53b94, v192
	v_subrev_u32_e32 v192, 29, v153
	v_cmp_gt_i32_e64 s[4:5], v192, v235
	v_mfma_f32_16x16x32_bf16 v[194:197], v[210:213], v[24:27], v[194:197]
	s_and_b64 s[4:5], vcc, s[4:5]
	v_subrev_u32_e32 v208, 28, v153
	v_cndmask_b32_e64 v203, v181, v223, s[4:5]
	v_cmp_gt_i32_e64 s[4:5], v208, v235
	v_mul_f32_e32 v181, 0x3dd53b94, v193
	s_and_b64 s[4:5], vcc, s[4:5]
	v_add_u32_e32 v210, -15, v153
	v_cndmask_b32_e64 v209, v181, v223, s[4:5]
	v_cmp_gt_i32_e64 s[4:5], v210, v235
	v_mul_f32_e32 v181, 0x3dd53b94, v194
	s_and_b64 s[4:5], vcc, s[4:5]
	v_add_u32_e32 v212, -14, v153
	v_cndmask_b32_e64 v194, v181, v223, s[4:5]
	v_cmp_gt_i32_e64 s[4:5], v212, v235
	v_mul_f32_e32 v181, 0x3dd53b94, v195
	s_and_b64 s[4:5], vcc, s[4:5]
	v_max3_f32 v156, v156, v157, v158
	v_cndmask_b32_e64 v211, v181, v223, s[4:5]
	v_mul_f32_e32 v181, 0x3dd53b94, v196
	v_add_u32_e32 v196, -13, v153
	v_max3_f32 v156, v156, v159, v183
	v_cmp_gt_i32_e64 s[4:5], v196, v235
	v_max3_f32 v156, v156, v184, v201
	s_and_b64 s[4:5], vcc, s[4:5]
	v_max3_f32 v156, v156, v190, v191
	v_cndmask_b32_e64 v239, v181, v223, s[4:5]
	v_cmp_gt_i32_e64 s[4:5], v240, v235
	v_max3_f32 v156, v156, v203, v209
	v_mul_f32_e32 v181, 0x3dd53b94, v197
	s_and_b64 s[4:5], vcc, s[4:5]
	v_max3_f32 v156, v156, v194, v211
	v_cndmask_b32_e64 v153, v181, v223, s[4:5]
	v_max3_f32 v156, v156, v239, v153
	v_mov_b32_e32 v181, v156
	s_nop 1
	v_permlane32_swap_b32_e32 v156, v181
	v_max_f32_e32 v181, v181, v181
	v_max_f32_e32 v156, v156, v156
	v_max_f32_e32 v156, v156, v181
	v_mov_b32_e32 v181, v156
	s_nop 1
	v_permlane16_swap_b32_e32 v156, v181
	v_max3_f32 v238, v152, v156, v181
	v_sub_f32_e32 v154, v154, v238
	v_exp_f32_e32 v181, v154
	v_sub_f32_e32 v154, v155, v238
	v_exp_f32_e32 v189, v154
	v_sub_f32_e32 v154, v157, v238
	v_exp_f32_e32 v187, v154
	v_sub_f32_e32 v154, v158, v238
	v_exp_f32_e32 v199, v154
	v_sub_f32_e32 v154, v159, v238
	v_mul_f32_e32 v168, 0x3dd53b94, v168
	v_exp_f32_e32 v193, v154
	v_sub_f32_e32 v154, v183, v238
	v_cndmask_b32_e64 v168, v168, v223, s[0:1]
	v_cmp_gt_i32_e64 s[0:1], v186, v236
	v_exp_f32_e32 v207, v154
	v_sub_f32_e32 v154, v184, v238
	v_mul_f32_e32 v169, 0x3dd53b94, v169
	s_and_b64 s[0:1], vcc, s[0:1]
	v_exp_f32_e32 v205, v154
	v_sub_f32_e32 v154, v201, v238
	v_cndmask_b32_e64 v169, v169, v223, s[0:1]
	v_cmp_gt_i32_e64 s[0:1], v188, v236
	v_exp_f32_e32 v213, v154
	v_sub_f32_e32 v154, v190, v238
	v_mul_f32_e32 v170, 0x3dd53b94, v170
	s_and_b64 s[0:1], vcc, s[0:1]
	v_sub_f32_e32 v152, v152, v238
	v_exp_f32_e32 v183, v154
	v_sub_f32_e32 v154, v191, v238
	v_cndmask_b32_e64 v170, v170, v223, s[0:1]
	v_cmp_gt_i32_e64 s[0:1], v202, v236
	v_exp_f32_e32 v197, v154
; DI unsigned pack2(float a, float b) { return (unsigned)f2bf(a) | ((unsigned)f2bf(b) << 16); }
; template <int DQK>
; DI void attn_phase(const bf16_t* Q, int ldq, const bf16_t* K1, int ldk1, const bf16_t* K2, int ldk2, const bf16_t* VT, int ldvt,
;                    bf16_t* O, int ldo, int nheads, int nq, int nkeys, bool causal, float scale, char* smem, int bid, int nb) {
;     ...
;             if (diag && (s0 + nj * 16 + fq * 4 + r > qi)) v = -1e30f;
;             st[mi][nj][r] = v; mx = fmaxf(mx, v);
;           }
;         mx = rows4_max(mx);
;         const float mn = fmaxf(mrow[mi], mx), al = __builtin_amdgcn_exp2f(mrow[mi] - mn);
;         mrow[mi] = mn;
;         float ps = 0.f;
; #pragma unroll
;         for (int nj = 0; nj < 4; ++nj)
; #pragma unroll
;           for (int r = 0; r < 4; ++r) { const float pv = __builtin_amdgcn_exp2f(st[mi][nj][r] - mn); st[mi][nj][r] = pv; ps += pv; }
;         lrow[mi] = lrow[mi] * al + ps;
; #pragma unroll
;         for (int dj = 0; dj < 8; ++dj) ot[mi][dj] *= al;
; #pragma unroll
;         for (int s = 0; s < 2; ++s) {
;           uint4 w;
;           w.x = pack2(st[mi][2 * s][0], st[mi][2 * s][1]); w.y = pack2(st[mi][2 * s][2], st[mi][2 * s][3]);
;           w.z = pack2(st[mi][2 * s + 1][0], st[mi][2 * s + 1][1]); w.w = pack2(st[mi][2 * s + 1][2], st[mi][2 * s + 1][3]);
;           pf[mi][s] = __builtin_bit_cast(bf16x8, w);
;         }
;       }
	v_sub_f32_e32 v154, v203, v238
	v_exp_f32_e32 v184, v152
	v_mul_f32_e32 v171, 0x3dd53b94, v171
	s_and_b64 s[0:1], vcc, s[0:1]
	v_exp_f32_e32 v191, v154
	v_sub_f32_e32 v154, v209, v238
	v_cndmask_b32_e64 v171, v171, v223, s[0:1]
	v_cmp_gt_i32_e64 s[0:1], v204, v236
	v_exp_f32_e32 v203, v154
	v_sub_f32_e32 v154, v194, v238
	v_mul_f32_e32 v164, 0x3dd53b94, v164
	s_and_b64 s[0:1], vcc, s[0:1]
	v_exp_f32_e32 v195, v154
	v_sub_f32_e32 v154, v211, v238
	v_cmp_gt_i32_e64 s[4:5], v182, v236
	v_cndmask_b32_e64 v164, v164, v223, s[0:1]
	v_cmp_gt_i32_e64 s[0:1], v206, v236
	v_exp_f32_e32 v209, v154
	v_sub_f32_e32 v154, v239, v238
	v_sub_f32_e32 v153, v153, v238
	v_pk_mul_f32 v[158:159], v[150:151], v[184:185] op_sel_hi:[1,0]
	v_pk_mul_f32 v[150:151], v[142:143], v[184:185] op_sel_hi:[1,0]
	v_pk_mul_f32 v[142:143], v[130:131], v[184:185] op_sel_hi:[1,0]
	v_bfe_u32 v130, v199, 16, 1
	v_bfe_u32 v131, v189, 16, 1
	v_mul_f32_e32 v172, 0x3dd53b94, v172
	s_and_b64 s[4:5], vcc, s[4:5]
	v_mul_f32_e32 v165, 0x3dd53b94, v165
	s_and_b64 s[0:1], vcc, s[0:1]
	v_exp_f32_e32 v201, v154
	v_exp_f32_e32 v211, v153
	v_pk_mul_f32 v[154:155], v[146:147], v[184:185] op_sel_hi:[1,0]
	v_pk_mul_f32 v[152:153], v[144:145], v[184:185] op_sel_hi:[1,0]
	v_pk_mul_f32 v[146:147], v[138:139], v[184:185] op_sel_hi:[1,0]
	v_pk_mul_f32 v[144:145], v[136:137], v[184:185] op_sel_hi:[1,0]
	v_pk_mul_f32 v[138:139], v[126:127], v[184:185] op_sel_hi:[1,0]
	v_pk_mul_f32 v[136:137], v[124:125], v[184:185] op_sel_hi:[1,0]
	v_pk_mul_f32 v[126:127], v[122:123], v[184:185] op_sel_hi:[1,0]
	v_pk_mul_f32 v[124:125], v[120:121], v[184:185] op_sel_hi:[1,0]
	v_pk_mul_f32 v[122:123], v[134:135], v[184:185] op_sel_hi:[1,0]
	v_pk_mul_f32 v[120:121], v[132:133], v[184:185] op_sel_hi:[1,0]
	v_add3_u32 v132, v189, v131, s16
	v_add3_u32 v133, v199, v130, s16
	v_bfe_u32 v130, v181, 16, 1
	v_bfe_u32 v131, v187, 16, 1
	v_bfe_u32 v134, v193, 16, 1
	v_bfe_u32 v135, v205, 16, 1
	v_cndmask_b32_e64 v172, v172, v223, s[4:5]
	v_cmp_ge_i32_e64 s[4:5], v182, v236
	v_cndmask_b32_e64 v165, v165, v223, s[0:1]
	v_cmp_gt_i32_e64 s[0:1], v192, v236
	v_pk_mul_f32 v[156:157], v[148:149], v[184:185] op_sel_hi:[1,0]
	v_pk_mul_f32 v[148:149], v[140:141], v[184:185] op_sel_hi:[1,0]
	v_pk_mul_f32 v[140:141], v[128:129], v[184:185] op_sel_hi:[1,0]
	v_bfe_u32 v128, v213, 16, 1
	v_bfe_u32 v129, v207, 16, 1
	v_add3_u32 v135, v205, v135, s16
	v_add3_u32 v134, v193, v134, s16
	v_add3_u32 v131, v187, v131, s16
	v_add3_u32 v130, v181, v130, s16
	v_mul_f32_e32 v173, 0x3dd53b94, v173
	s_and_b64 s[4:5], vcc, s[4:5]
	v_mul_f32_e32 v166, 0x3dd53b94, v166
	s_and_b64 s[0:1], vcc, s[0:1]
	v_add3_u32 v129, v207, v129, s16
	v_add3_u32 v128, v213, v128, s16
	v_lshrrev_b32_e32 v190, 16, v130
	v_lshrrev_b32_e32 v194, 16, v131
	v_lshrrev_b32_e32 v130, 16, v134
	v_lshrrev_b32_e32 v131, 16, v135
	v_bfe_u32 v134, v203, 16, 1
	v_bfe_u32 v135, v197, 16, 1
	v_cndmask_b32_e64 v173, v173, v223, s[4:5]
	v_cmp_gt_i32_e64 s[4:5], v198, v236
	v_cndmask_b32_e64 v166, v166, v223, s[0:1]
	v_cmp_gt_i32_e64 s[0:1], v208, v236
	v_and_or_b32 v131, v128, s15, v131
	v_and_or_b32 v130, v129, s15, v130
	v_and_or_b32 v129, v133, s15, v194
	v_and_or_b32 v128, v132, s15, v190
	v_add3_u32 v190, v197, v135, s16
	v_add3_u32 v194, v203, v134, s16
	v_bfe_u32 v134, v183, 16, 1
	v_bfe_u32 v135, v191, 16, 1
	v_bfe_u32 v239, v195, 16, 1
	v_mul_f32_e32 v174, 0x3dd53b94, v174
	s_and_b64 s[4:5], vcc, s[4:5]
	v_mul_f32_e32 v167, 0x3dd53b94, v167
	s_and_b64 s[0:1], vcc, s[0:1]
	v_bfe_u32 v133, v209, 16, 1
	v_add3_u32 v239, v195, v239, s16
	v_add3_u32 v135, v191, v135, s16
	v_add3_u32 v134, v183, v134, s16
	v_cndmask_b32_e64 v174, v174, v223, s[4:5]
	v_cmp_gt_i32_e64 s[4:5], v200, v236
	v_cndmask_b32_e64 v167, v167, v223, s[0:1]
	v_cmp_gt_i32_e64 s[0:1], v210, v236
	v_add3_u32 v133, v209, v133, s16
	v_lshrrev_b32_e32 v242, 16, v134
	v_lshrrev_b32_e32 v243, 16, v135
	v_lshrrev_b32_e32 v134, 16, v239
	v_mul_f32_e32 v175, 0x3dd53b94, v175
	s_and_b64 s[4:5], vcc, s[4:5]
	v_mul_f32_e32 v160, 0x3dd53b94, v160
	s_and_b64 s[0:1], vcc, s[0:1]
	v_and_or_b32 v134, v133, s15, v134
	v_and_or_b32 v133, v194, s15, v243
	v_max3_f32 v182, v172, s17, v173
	v_cndmask_b32_e64 v175, v175, v223, s[4:5]
	v_cndmask_b32_e64 v194, v160, v223, s[0:1]
	v_cmp_gt_i32_e64 s[0:1], v212, v236
	v_max3_f32 v182, v182, v174, v175
	v_mul_f32_e32 v160, 0x3dd53b94, v161
	s_and_b64 s[0:1], vcc, s[0:1]
	v_max3_f32 v182, v182, v168, v169
	v_cndmask_b32_e64 v200, v160, v223, s[0:1]
	v_cmp_gt_i32_e64 s[0:1], v196, v236
	v_max3_f32 v182, v182, v170, v171
	v_mul_f32_e32 v161, 0x3dd53b94, v162
	s_and_b64 s[0:1], vcc, s[0:1]
	v_max3_f32 v182, v182, v164, v165
	v_cndmask_b32_e64 v162, v161, v223, s[0:1]
	v_cmp_gt_i32_e64 s[0:1], v240, v236
	v_max3_f32 v182, v182, v166, v167
	v_mul_f32_e32 v161, 0x3dd53b94, v163
	s_and_b64 vcc, vcc, s[0:1]
	v_max3_f32 v160, v182, v194, v200
	v_cndmask_b32_e32 v163, v161, v223, vcc
	v_max3_f32 v160, v160, v162, v163
	v_mov_b32_e32 v161, v160
	s_nop 1
	v_permlane32_swap_b32_e32 v160, v161
	v_max_f32_e32 v161, v161, v161
	v_max_f32_e32 v160, v160, v160
	v_max_f32_e32 v160, v160, v161
	v_mov_b32_e32 v161, v160
	s_nop 1
	v_permlane16_swap_b32_e32 v160, v161
	v_max3_f32 v239, v180, v160, v161
	v_sub_f32_e32 v160, v172, v239
	v_sub_f32_e32 v240, v180, v239
	v_exp_f32_e32 v180, v160
	v_sub_f32_e32 v160, v173, v239
	v_exp_f32_e32 v188, v160
	v_sub_f32_e32 v160, v174, v239
	v_exp_f32_e32 v186, v160
	v_sub_f32_e32 v160, v175, v239
	v_exp_f32_e32 v198, v160
	v_sub_f32_e32 v160, v168, v239
	v_exp_f32_e32 v192, v160
	v_sub_f32_e32 v160, v169, v239
	v_exp_f32_e32 v206, v160
	v_sub_f32_e32 v160, v170, v239
	v_exp_f32_e32 v204, v160
; DI unsigned pack2(float a, float b) { return (unsigned)f2bf(a) | ((unsigned)f2bf(b) << 16); }
; template <int DQK>
; DI void attn_phase(const bf16_t* Q, int ldq, const bf16_t* K1, int ldk1, const bf16_t* K2, int ldk2, const bf16_t* VT, int ldvt,
;                    bf16_t* O, int ldo, int nheads, int nq, int nkeys, bool causal, float scale, char* smem, int bid, int nb) {
;     ...
;         float ps = 0.f;
; #pragma unroll
;         for (int nj = 0; nj < 4; ++nj)
; #pragma unroll
;           for (int r = 0; r < 4; ++r) { const float pv = __builtin_amdgcn_exp2f(st[mi][nj][r] - mn); st[mi][nj][r] = pv; ps += pv; }
;         lrow[mi] = lrow[mi] * al + ps;
; #pragma unroll
;         for (int dj = 0; dj < 8; ++dj) ot[mi][dj] *= al;
; #pragma unroll
;         for (int s = 0; s < 2; ++s) {
;           uint4 w;
;           w.x = pack2(st[mi][2 * s][0], st[mi][2 * s][1]); w.y = pack2(st[mi][2 * s][2], st[mi][2 * s][3]);
;           w.z = pack2(st[mi][2 * s + 1][0], st[mi][2 * s + 1][1]); w.w = pack2(st[mi][2 * s + 1][2], st[mi][2 * s + 1][3]);
;           pf[mi][s] = __builtin_bit_cast(bf16x8, w);
;         }
;       }
; #pragma unroll
;       for (int s = 0; s < 2; ++s)
; #pragma unroll
;         for (int dj = 0; dj < 8; ++dj) {
;           const char* vp = Vs + ((dj * 16 + fr) * LDT + 32 * s + fq * 4) * 2;
	v_sub_f32_e32 v160, v171, v239
	v_exp_f32_e32 v212, v160
	v_pk_add_f32 v[160:161], v[180:181], 0 op_sel_hi:[1,0]
	v_bfe_u32 v241, v201, 16, 1
	v_pk_add_f32 v[160:161], v[188:189], v[160:161]
	v_sub_f32_e32 v164, v164, v239
	v_pk_add_f32 v[160:161], v[186:187], v[160:161]
	v_bfe_u32 v132, v211, 16, 1
	v_pk_add_f32 v[160:161], v[198:199], v[160:161]
	v_add3_u32 v241, v201, v241, s16
	v_pk_add_f32 v[160:161], v[192:193], v[160:161]
	v_exp_f32_e32 v182, v164
	v_sub_f32_e32 v164, v165, v239
	v_add3_u32 v132, v211, v132, s16
	v_lshrrev_b32_e32 v135, 16, v241
	v_pk_add_f32 v[160:161], v[206:207], v[160:161]
	v_exp_f32_e32 v196, v164
	v_sub_f32_e32 v164, v166, v239
	v_and_or_b32 v135, v132, s15, v135
	v_and_or_b32 v132, v190, s15, v242
	v_pk_add_f32 v[160:161], v[204:205], v[160:161]
	v_exp_f32_e32 v190, v164
	v_sub_f32_e32 v164, v167, v239
	v_pk_add_f32 v[160:161], v[212:213], v[160:161]
	v_exp_f32_e32 v202, v164
	v_sub_f32_e32 v164, v194, v239
	v_exp_f32_e32 v194, v164
	v_sub_f32_e32 v164, v200, v239
	v_sub_f32_e32 v162, v162, v239
	v_pk_add_f32 v[160:161], v[182:183], v[160:161]
	v_exp_f32_e32 v208, v164
	v_exp_f32_e32 v200, v162
	v_sub_f32_e32 v162, v163, v239
	v_pk_add_f32 v[160:161], v[196:197], v[160:161]
	v_exp_f32_e32 v210, v162
	v_exp_f32_e32 v162, v240
	v_pk_add_f32 v[160:161], v[190:191], v[160:161]
	v_mov_b32_e32 v163, v184
	v_pk_add_f32 v[160:161], v[202:203], v[160:161]
	v_pk_mul_f32 v[170:171], v[118:119], v[162:163] op_sel_hi:[1,0]
	v_pk_add_f32 v[160:161], v[194:195], v[160:161]
	v_pk_mul_f32 v[168:169], v[116:117], v[162:163] op_sel_hi:[1,0]
	v_pk_add_f32 v[160:161], v[208:209], v[160:161]
	v_pk_mul_f32 v[118:119], v[110:111], v[162:163] op_sel_hi:[1,0]
	v_pk_add_f32 v[160:161], v[200:201], v[160:161]
	v_pk_mul_f32 v[116:117], v[108:109], v[162:163] op_sel_hi:[1,0]
	v_bfe_u32 v108, v186, 16, 1
	v_bfe_u32 v109, v204, 16, 1
	v_bfe_u32 v110, v180, 16, 1
	v_pk_add_f32 v[160:161], v[210:211], v[160:161]
	v_pk_mul_f32 v[166:167], v[114:115], v[162:163] op_sel_hi:[1,0]
	v_pk_mul_f32 v[164:165], v[112:113], v[162:163] op_sel_hi:[1,0]
	v_pk_mul_f32 v[114:115], v[102:103], v[162:163] op_sel_hi:[1,0]
	v_pk_mul_f32 v[112:113], v[100:101], v[162:163] op_sel_hi:[1,0]
	v_pk_mul_f32 v[102:103], v[98:99], v[162:163] op_sel_hi:[1,0]
	v_pk_mul_f32 v[100:101], v[96:97], v[162:163] op_sel_hi:[1,0]
	v_pk_mul_f32 v[98:99], v[90:91], v[162:163] op_sel_hi:[1,0]
	v_pk_mul_f32 v[96:97], v[88:89], v[162:163] op_sel_hi:[1,0]
	v_pk_mul_f32 v[90:91], v[106:107], v[162:163] op_sel_hi:[1,0]
	v_pk_mul_f32 v[88:89], v[104:105], v[162:163] op_sel_hi:[1,0]
	v_bfe_u32 v104, v212, 16, 1
	v_bfe_u32 v105, v198, 16, 1
	v_bfe_u32 v107, v188, 16, 1
	v_bfe_u32 v111, v192, 16, 1
	v_add3_u32 v109, v204, v109, s16
	v_add3_u32 v108, v186, v108, s16
	v_add3_u32 v110, v180, v110, s16
	v_pk_fma_f32 v[178:179], v[178:179], v[162:163], v[160:161]
	v_add3_u32 v105, v198, v105, s16
	v_add3_u32 v104, v212, v104, s16
	v_add3_u32 v107, v188, v107, s16
	v_add3_u32 v111, v192, v111, s16
	v_lshrrev_b32_e32 v108, 16, v108
	v_lshrrev_b32_e32 v109, 16, v109
	v_lshrrev_b32_e32 v160, 16, v110
	v_lshrrev_b32_e32 v110, 16, v111
	v_and_or_b32 v111, v104, s15, v109
	v_and_or_b32 v109, v105, s15, v108
	v_and_or_b32 v108, v107, s15, v160
	v_bfe_u32 v107, v196, 16, 1
	v_add3_u32 v160, v196, v107, s16
	v_bfe_u32 v107, v190, 16, 1
	v_bfe_u32 v105, v202, 16, 1
	v_add3_u32 v107, v190, v107, s16
	v_add3_u32 v105, v202, v105, s16
	v_lshrrev_b32_e32 v172, 16, v107
	v_add_u32_e32 v184, 0x6000, v233
	v_and_or_b32 v105, v105, s15, v172
	ds_read2_b64 v[172:175], v184 offset1:4
	v_bfe_u32 v106, v206, 16, 1
	v_pk_mul_f32 v[94:95], v[94:95], v[162:163] op_sel_hi:[1,0]
	v_pk_mul_f32 v[92:93], v[92:93], v[162:163] op_sel_hi:[1,0]
	v_add3_u32 v106, v206, v106, s16
	v_bfe_u32 v161, v200, 16, 1
	v_bfe_u32 v162, v182, 16, 1
	v_bfe_u32 v163, v194, 16, 1
	v_and_or_b32 v110, v106, s15, v110
	v_bfe_u32 v104, v210, 16, 1
	v_bfe_u32 v106, v208, 16, 1
	v_add3_u32 v161, v200, v161, s16
	v_add3_u32 v163, v194, v163, s16
	v_add3_u32 v162, v182, v162, s16
	v_add3_u32 v104, v210, v104, s16
	v_add3_u32 v106, v208, v106, s16
	v_lshrrev_b32_e32 v107, 16, v161
	v_lshrrev_b32_e32 v161, 16, v162
	v_lshrrev_b32_e32 v162, 16, v163
	v_and_or_b32 v107, v104, s15, v107
	v_and_or_b32 v106, v106, s15, v162
	v_and_or_b32 v104, v160, s15, v161
	s_waitcnt lgkmcnt(0)
; #define MFMA16(a, b, c) __builtin_amdgcn_mfma_f32_16x16x32_bf16((a), (b), (c), 0, 0, 0)
; template <int DQK>
; DI void attn_phase(const bf16_t* Q, int ldq, const bf16_t* K1, int ldk1, const bf16_t* K2, int ldk2, const bf16_t* VT, int ldvt,
;                    bf16_t* O, int ldo, int nheads, int nq, int nkeys, bool causal, float scale, char* smem, int bid, int nb) {
;     ...
; #pragma unroll
;       for (int s = 0; s < 2; ++s)
; #pragma unroll
;         for (int dj = 0; dj < 8; ++dj) {
;           const char* vp = Vs + ((dj * 16 + fr) * LDT + 32 * s + fq * 4) * 2;
;           const s16x4 lo = *(const s16x4*)vp, hi = *(const s16x4*)(vp + 32);
;           const bf16x8 vf = __builtin_shufflevector(lo, hi, 0, 1, 2, 3, 4, 5, 6, 7);
; #pragma unroll
;           for (int mi = 0; mi < 2; ++mi) ot[mi][dj] = MFMA16(vf, pf[mi][s], ot[mi][dj]);
;         }
	v_mfma_f32_16x16x32_bf16 v[160:163], v[172:175], v[128:131], v[156:159]
	v_mfma_f32_16x16x32_bf16 v[156:159], v[172:175], v[108:111], v[168:171]
	ds_read2_b64 v[172:175], v245 offset0:64 offset1:68
	s_nop 1
	ds_read2_b64 v[168:171], v244 offset0:32 offset1:36
	s_waitcnt lgkmcnt(0)
	v_mfma_f32_16x16x32_bf16 v[152:155], v[168:171], v[128:131], v[152:155]
	v_mfma_f32_16x16x32_bf16 v[164:167], v[168:171], v[108:111], v[164:167]
	v_mfma_f32_16x16x32_bf16 v[168:171], v[172:175], v[128:131], v[148:151]
	v_mfma_f32_16x16x32_bf16 v[172:175], v[172:175], v[108:111], v[116:119]
	s_nop 2
	ds_read2_b64 v[116:119], v221 offset0:96 offset1:100
	s_waitcnt lgkmcnt(0)
	v_mfma_f32_16x16x32_bf16 v[186:189], v[116:119], v[108:111], v[112:115]
	s_nop 2
	ds_read2_b64 v[112:115], v215 offset0:128 offset1:132
	s_waitcnt lgkmcnt(0)
	v_mfma_f32_16x16x32_bf16 v[194:197], v[112:115], v[108:111], v[100:103]
	s_nop 2
	ds_read2_b64 v[100:103], v216 offset0:160 offset1:164
	s_waitcnt lgkmcnt(0)
	v_mfma_f32_16x16x32_bf16 v[202:205], v[100:103], v[108:111], v[96:99]
	s_nop 2
	ds_read2_b64 v[96:99], v224 offset0:192 offset1:196
	s_waitcnt lgkmcnt(0)
	v_mfma_f32_16x16x32_bf16 v[206:209], v[96:99], v[128:131], v[124:127]
	v_mfma_f32_16x16x32_bf16 v[92:95], v[96:99], v[108:111], v[92:95]
	ds_read2_b64 v[96:99], v225 offset0:224 offset1:228
	s_waitcnt lgkmcnt(0)
	v_mfma_f32_16x16x32_bf16 v[240:243], v[96:99], v[108:111], v[88:91]
	s_nop 2
	ds_read2_b64 v[88:91], v184 offset0:8 offset1:12
	v_mfma_f32_16x16x32_bf16 v[180:183], v[116:119], v[128:131], v[144:147]
	s_waitcnt lgkmcnt(0)
	v_mfma_f32_16x16x32_bf16 v[148:151], v[88:91], v[132:135], v[160:163]
	v_mfma_f32_16x16x32_bf16 v[116:119], v[88:91], v[104:107], v[156:159]
	ds_read2_b64 v[88:91], v244 offset0:40 offset1:44
	v_mfma_f32_16x16x32_bf16 v[190:193], v[112:115], v[128:131], v[140:143]
	s_waitcnt lgkmcnt(0)
	v_mfma_f32_16x16x32_bf16 v[144:147], v[88:91], v[132:135], v[152:155]
	s_nop 2
	ds_read2_b64 v[152:155], v224 offset0:200 offset1:204
	v_mfma_f32_16x16x32_bf16 v[112:115], v[88:91], v[104:107], v[164:167]
	ds_read2_b64 v[88:91], v245 offset0:72 offset1:76
	s_waitcnt lgkmcnt(0)
	v_mfma_f32_16x16x32_bf16 v[140:143], v[88:91], v[132:135], v[168:171]
	v_mfma_f32_16x16x32_bf16 v[108:111], v[88:91], v[104:107], v[172:175]
	ds_read2_b64 v[88:91], v221 offset0:104 offset1:108
	v_mfma_f32_16x16x32_bf16 v[198:201], v[100:103], v[128:131], v[136:139]
	s_waitcnt lgkmcnt(0)
	v_mfma_f32_16x16x32_bf16 v[136:139], v[88:91], v[132:135], v[180:183]
	s_nop 2
	v_mov_b32_e32 v180, v239
	v_mfma_f32_16x16x32_bf16 v[100:103], v[88:91], v[104:107], v[186:189]
	ds_read2_b64 v[88:91], v215 offset0:136 offset1:140
	v_mfma_f32_16x16x32_bf16 v[210:213], v[96:99], v[128:131], v[120:123]
	s_waitcnt lgkmcnt(0)
	v_mfma_f32_16x16x32_bf16 v[128:131], v[88:91], v[132:135], v[190:193]
	v_mfma_f32_16x16x32_bf16 v[96:99], v[88:91], v[104:107], v[194:197]
	ds_read2_b64 v[88:91], v216 offset0:168 offset1:172
	v_mfma_f32_16x16x32_bf16 v[120:123], v[152:155], v[132:135], v[206:209]
	v_mfma_f32_16x16x32_bf16 v[92:95], v[152:155], v[104:107], v[92:95]
	ds_read2_b64 v[152:155], v225 offset0:232 offset1:236
	s_waitcnt lgkmcnt(1)
	v_mfma_f32_16x16x32_bf16 v[124:127], v[88:91], v[132:135], v[198:201]
	v_mfma_f32_16x16x32_bf16 v[88:91], v[88:91], v[104:107], v[202:205]
	s_waitcnt lgkmcnt(0)
	v_mfma_f32_16x16x32_bf16 v[132:135], v[152:155], v[132:135], v[210:213]
	v_mfma_f32_16x16x32_bf16 v[104:107], v[152:155], v[104:107], v[240:243]
	v_mov_b32_e32 v152, v238
	s_branch .LBB0_1539
